# software-pipelined K loops (LDS-DMA interleaved with MFMA, LDS prefetch across barrier) for FFN up/down, w_in, w_o GEMMs
# speedup vs baseline: 1.0409x; 1.0409x over previous
;   const int tid = TIDX, lane = tid & 63, wid = tid >> 6, wr = wid >> 1, wc = wid & 1, r = lane & 31, h = lane >> 5;
;   const int ch = (tid & 7) ^ ((tid >> 4) & 7);
;   unsigned avo[4], bvo[2];
; #pragma unroll
;   for (int i = 0; i < 4; ++i) avo[i] = (unsigned)(((tid >> 3) + 64 * i) * lda * 2 + ch * 16);
; #pragma unroll
;   for (int i = 0; i < 2; ++i) bvo[i] = (unsigned)(((tid >> 3) + 64 * i) * ldb * 2 + ch * 16);
;   const char* Ab = (const char*)A; const char* Bb = (const char*)Bt;
;   char* lw = lds + tid * 16;
;   const int nk = K >> 6;
;   const unsigned swz = (unsigned)((r >> 1) & 7);
;   const unsigned arow_u = (unsigned)((wr * 64 + r) * 128), brow_u = (unsigned)((wc * 64 + r) * 128);
;   const unsigned co0 = ((0u + h) ^ swz) << 4, co1 = ((2u + h) ^ swz) << 4, co2 = ((4u + h) ^ swz) << 4, co3 = ((6u + h) ^ swz) << 4;
;     ...
;   if (PART != 2) {
;     GEMM_ISSUE(0, 0);
;     if (nk > 1) GEMM_ISSUE(1, 1);
;   }
;   if (PART == 1) return;
;   int st = 0;
;   for (int kt = 0; kt < nk; ++kt) {
;     if (kt + 1 < nk) asm volatile("s_waitcnt vmcnt(6)" ::: "memory");
;     else asm volatile("s_waitcnt vmcnt(0)" ::: "memory");
;     __builtin_amdgcn_s_barrier();
;     asm volatile("" ::: "memory");
;     if (kt + 2 < nk) { const int st2 = (st >= 1) ? st - 1 : 2; GEMM_ISSUE(kt + 2, st2); }
;     const char* la = lds + st * STAGE_B;
;     const char* lb = la + 32768;
;     const unsigned sa_u = (unsigned)(size_t)la + arow_u, sb_u = (unsigned)(size_t)lb + brow_u;
;     const unsigned a0 = sa_u + co0, a1 = sa_u + co1, a2 = sa_u + co2, a3 = sa_u + co3;
;     const unsigned b0 = sb_u + co0, b1 = sb_u + co1, b2 = sb_u + co2, b3 = sb_u + co3;
;     {
;       bf16x8 p0, p1, q0, q1, u0, u1, w0, w1;
;       asm volatile(
;         "ds_read_b128 %4, %12\n\tds_read_b128 %5, %12 offset:4096\n\tds_read_b128 %6, %16\n\tds_read_b128 %7, %16 offset:4096\n\t"
;         "ds_read_b128 %8, %13\n\tds_read_b128 %9, %13 offset:4096\n\tds_read_b128 %10, %17\n\tds_read_b128 %11, %17 offset:4096\n\t"
;         "s_waitcnt lgkmcnt(4)\n\t"
;         "v_mfma_f32_32x32x16_bf16 %0, %4, %6, %0\n\tv_mfma_f32_32x32x16_bf16 %1, %4, %7, %1\n\tv_mfma_f32_32x32x16_bf16 %2, %5, %6, %2\n\tv_mfma_f32_32x32x16_bf16 %3, %5, %7, %3\n\t"
;         "ds_read_b128 %4, %14\n\tds_read_b128 %5, %14 offset:4096\n\tds_read_b128 %6, %18\n\tds_read_b128 %7, %18 offset:4096\n\t"
;         "s_waitcnt lgkmcnt(4)\n\t"
.LBB0_32:
	v_and_b32_e32 v164, 31, v129
	v_bfe_u32 v165, v129, 5, 1
	v_lshrrev_b32_e32 v166, 6, v129
	v_bfe_u32 v168, v129, 1, 3
	v_lshrrev_b32_e32 v167, 1, v166
	v_and_b32_e32 v166, 1, v166
	v_xor_b32_e32 v165, v165, v168
	v_lshl_add_u32 v167, v167, 6, v164
	v_lshl_add_u32 v166, v166, 6, v164
	v_lshlrev_b32_e32 v165, 4, v165
	v_lshlrev_b32_e32 v167, 7, v167
	v_lshlrev_b32_e32 v166, 7, v166
	v_add_u32_e32 v166, 0x8000, v166
	v_add_u32_e32 v76, v167, v165
	v_add_u32_e32 v80, v166, v165
	v_xor_b32_e32 v169, 0x20, v165
	v_add_u32_e32 v77, v167, v169
	v_add_u32_e32 v81, v166, v169
	v_xor_b32_e32 v169, 0x40, v165
	v_add_u32_e32 v78, v167, v169
	v_add_u32_e32 v82, v166, v169
	v_xor_b32_e32 v169, 0x60, v165
	v_add_u32_e32 v79, v167, v169
	v_add_u32_e32 v83, v166, v169
	v_add_u32_e32 v84, 0x18000, v76
	v_add_u32_e32 v156, 0x18000, v80
	v_add_u32_e32 v85, 0x18000, v77
	v_add_u32_e32 v157, 0x18000, v81
	v_add_u32_e32 v86, 0x18000, v78
	v_add_u32_e32 v158, 0x18000, v82
	v_add_u32_e32 v87, 0x18000, v79
	v_add_u32_e32 v159, 0x18000, v83
	v_lshlrev_b32_e32 v164, 4, v129
	s_nop 0
	v_readfirstlane_b32 s11, v164
	s_mov_b32 s15, 0
	s_waitcnt vmcnt(63)
	s_barrier
	ds_read_b128 v[164:167], v76
	ds_read_b128 v[168:171], v76 offset:4096
	ds_read_b128 v[172:175], v80
	ds_read_b128 v[176:179], v80 offset:4096
	s_mov_b32 s14, 0xa5c2100
	s_add_u32 m0, s11, 0x18000
	v_lshl_add_u64 v[160:161], v[74:75], 0, s[14:15]
	global_load_lds_dwordx4 v[160:161], off
	s_add_u32 m0, s11, 0x1a000
	v_lshl_add_u64 v[162:163], v[72:73], 0, s[14:15]
	global_load_lds_dwordx4 v[162:163], off
	ds_read_b128 v[180:183], v77
	ds_read_b128 v[184:187], v77 offset:4096
	ds_read_b128 v[218:221], v81
	ds_read_b128 v[222:225], v81 offset:4096
	s_waitcnt lgkmcnt(4)
	v_mfma_f32_32x32x16_bf16 v[48:63], v[164:167], v[172:175], v[48:63]
	s_add_u32 m0, s11, 0x1c000
	v_lshl_add_u64 v[160:161], v[70:71], 0, s[14:15]
	global_load_lds_dwordx4 v[160:161], off
	v_mfma_f32_32x32x16_bf16 v[32:47], v[164:167], v[176:179], v[32:47]
	v_mfma_f32_32x32x16_bf16 v[16:31], v[168:171], v[172:175], v[16:31]
	s_add_u32 m0, s11, 0x1e000
	v_lshl_add_u64 v[162:163], v[68:69], 0, s[14:15]
	global_load_lds_dwordx4 v[162:163], off
	v_mfma_f32_32x32x16_bf16 v[0:15], v[168:171], v[176:179], v[0:15]
	ds_read_b128 v[164:167], v78
	ds_read_b128 v[168:171], v78 offset:4096
	ds_read_b128 v[172:175], v82
	ds_read_b128 v[176:179], v82 offset:4096
	s_waitcnt lgkmcnt(4)
	v_mfma_f32_32x32x16_bf16 v[48:63], v[180:183], v[218:221], v[48:63]
	s_mov_b32 s14, 0x1b80100
	s_add_u32 m0, s11, 0x20000
	v_lshl_add_u64 v[160:161], v[66:67], 0, s[14:15]
	global_load_lds_dwordx4 v[160:161], off
	v_mfma_f32_32x32x16_bf16 v[32:47], v[180:183], v[222:225], v[32:47]
	v_mfma_f32_32x32x16_bf16 v[16:31], v[184:187], v[218:221], v[16:31]
	s_add_u32 m0, s11, 0x22000
	v_lshl_add_u64 v[162:163], v[64:65], 0, s[14:15]
	global_load_lds_dwordx4 v[162:163], off
	v_mfma_f32_32x32x16_bf16 v[0:15], v[184:187], v[222:225], v[0:15]
	ds_read_b128 v[180:183], v79
	ds_read_b128 v[184:187], v79 offset:4096
	ds_read_b128 v[218:221], v83
	ds_read_b128 v[222:225], v83 offset:4096
	s_waitcnt lgkmcnt(4)
	v_mfma_f32_32x32x16_bf16 v[48:63], v[164:167], v[172:175], v[48:63]
	v_mfma_f32_32x32x16_bf16 v[32:47], v[164:167], v[176:179], v[32:47]
	v_mfma_f32_32x32x16_bf16 v[16:31], v[168:171], v[172:175], v[16:31]
	v_mfma_f32_32x32x16_bf16 v[0:15], v[168:171], v[176:179], v[0:15]
	s_waitcnt vmcnt(63) lgkmcnt(0)
	s_barrier
	ds_read_b128 v[164:167], v76 offset:49152
	ds_read_b128 v[168:171], v76 offset:53248
	ds_read_b128 v[172:175], v80 offset:49152
	ds_read_b128 v[176:179], v80 offset:53248
	v_mfma_f32_32x32x16_bf16 v[48:63], v[180:183], v[218:221], v[48:63]
	s_mov_b32 s14, 0xa5c2180
	s_mov_b32 m0, s11
	v_lshl_add_u64 v[160:161], v[74:75], 0, s[14:15]
	global_load_lds_dwordx4 v[160:161], off
	v_mfma_f32_32x32x16_bf16 v[32:47], v[180:183], v[222:225], v[32:47]
	v_mfma_f32_32x32x16_bf16 v[16:31], v[184:187], v[218:221], v[16:31]
	s_add_u32 m0, s11, 0x2000
	v_lshl_add_u64 v[162:163], v[72:73], 0, s[14:15]
	global_load_lds_dwordx4 v[162:163], off
	v_mfma_f32_32x32x16_bf16 v[0:15], v[184:187], v[222:225], v[0:15]
	ds_read_b128 v[180:183], v77 offset:49152
	ds_read_b128 v[184:187], v77 offset:53248
	ds_read_b128 v[218:221], v81 offset:49152
	ds_read_b128 v[222:225], v81 offset:53248
	s_waitcnt lgkmcnt(4)
	v_mfma_f32_32x32x16_bf16 v[48:63], v[164:167], v[172:175], v[48:63]
	s_add_u32 m0, s11, 0x4000
	v_lshl_add_u64 v[160:161], v[70:71], 0, s[14:15]
	global_load_lds_dwordx4 v[160:161], off
	v_mfma_f32_32x32x16_bf16 v[32:47], v[164:167], v[176:179], v[32:47]
	v_mfma_f32_32x32x16_bf16 v[16:31], v[168:171], v[172:175], v[16:31]
	s_add_u32 m0, s11, 0x6000
	v_lshl_add_u64 v[162:163], v[68:69], 0, s[14:15]
	global_load_lds_dwordx4 v[162:163], off
	v_mfma_f32_32x32x16_bf16 v[0:15], v[168:171], v[176:179], v[0:15]
	ds_read_b128 v[164:167], v78 offset:49152
	ds_read_b128 v[168:171], v78 offset:53248
	ds_read_b128 v[172:175], v82 offset:49152
	ds_read_b128 v[176:179], v82 offset:53248
	s_waitcnt lgkmcnt(4)
	v_mfma_f32_32x32x16_bf16 v[48:63], v[180:183], v[218:221], v[48:63]
	s_mov_b32 s14, 0x1b80180
	s_add_u32 m0, s11, 0x8000
	v_lshl_add_u64 v[160:161], v[66:67], 0, s[14:15]
	global_load_lds_dwordx4 v[160:161], off
	v_mfma_f32_32x32x16_bf16 v[32:47], v[180:183], v[222:225], v[32:47]
	v_mfma_f32_32x32x16_bf16 v[16:31], v[184:187], v[218:221], v[16:31]
	s_add_u32 m0, s11, 0xa000
	v_lshl_add_u64 v[162:163], v[64:65], 0, s[14:15]
	global_load_lds_dwordx4 v[162:163], off
	v_mfma_f32_32x32x16_bf16 v[0:15], v[184:187], v[222:225], v[0:15]
	ds_read_b128 v[180:183], v79 offset:49152
	ds_read_b128 v[184:187], v79 offset:53248
	ds_read_b128 v[218:221], v83 offset:49152
	ds_read_b128 v[222:225], v83 offset:53248
	s_waitcnt lgkmcnt(4)
	v_mfma_f32_32x32x16_bf16 v[48:63], v[164:167], v[172:175], v[48:63]
	v_mfma_f32_32x32x16_bf16 v[32:47], v[164:167], v[176:179], v[32:47]
	v_mfma_f32_32x32x16_bf16 v[16:31], v[168:171], v[172:175], v[16:31]
	v_mfma_f32_32x32x16_bf16 v[0:15], v[168:171], v[176:179], v[0:15]
	s_waitcnt vmcnt(6) lgkmcnt(0)
	s_barrier
;     ...
;   for (int kt = 0; kt < nk; ++kt) {
;     if (kt + 1 < nk) asm volatile("s_waitcnt vmcnt(6)" ::: "memory");
;     else asm volatile("s_waitcnt vmcnt(0)" ::: "memory");
;     __builtin_amdgcn_s_barrier();
;     asm volatile("" ::: "memory");
;     if (kt + 2 < nk) { const int st2 = (st >= 1) ? st - 1 : 2; GEMM_ISSUE(kt + 2, st2); }
;     const char* la = lds + st * STAGE_B;
;     const char* lb = la + 32768;
;     const unsigned sa_u = (unsigned)(size_t)la + arow_u, sb_u = (unsigned)(size_t)lb + brow_u;
;     const unsigned a0 = sa_u + co0, a1 = sa_u + co1, a2 = sa_u + co2, a3 = sa_u + co3;
;     const unsigned b0 = sb_u + co0, b1 = sb_u + co1, b2 = sb_u + co2, b3 = sb_u + co3;
;     {
;       bf16x8 p0, p1, q0, q1, u0, u1, w0, w1;
;       asm volatile(
;         "ds_read_b128 %4, %12\n\tds_read_b128 %5, %12 offset:4096\n\tds_read_b128 %6, %16\n\tds_read_b128 %7, %16 offset:4096\n\t"
;         "ds_read_b128 %8, %13\n\tds_read_b128 %9, %13 offset:4096\n\tds_read_b128 %10, %17\n\tds_read_b128 %11, %17 offset:4096\n\t"
;         "s_waitcnt lgkmcnt(4)\n\t"
;         "v_mfma_f32_32x32x16_bf16 %0, %4, %6, %0\n\tv_mfma_f32_32x32x16_bf16 %1, %4, %7, %1\n\tv_mfma_f32_32x32x16_bf16 %2, %5, %6, %2\n\tv_mfma_f32_32x32x16_bf16 %3, %5, %7, %3\n\t"
;         "ds_read_b128 %4, %14\n\tds_read_b128 %5, %14 offset:4096\n\tds_read_b128 %6, %18\n\tds_read_b128 %7, %18 offset:4096\n\t"
;         "s_waitcnt lgkmcnt(4)\n\t"
;         "v_mfma_f32_32x32x16_bf16 %0, %8, %10, %0\n\tv_mfma_f32_32x32x16_bf16 %1, %8, %11, %1\n\tv_mfma_f32_32x32x16_bf16 %2, %9, %10, %2\n\tv_mfma_f32_32x32x16_bf16 %3, %9, %11, %3\n\t"
;         "ds_read_b128 %8, %15\n\tds_read_b128 %9, %15 offset:4096\n\tds_read_b128 %10, %19\n\tds_read_b128 %11, %19 offset:4096\n\t"
;         "s_waitcnt lgkmcnt(4)\n\t"
;         "v_mfma_f32_32x32x16_bf16 %0, %4, %6, %0\n\tv_mfma_f32_32x32x16_bf16 %1, %4, %7, %1\n\tv_mfma_f32_32x32x16_bf16 %2, %5, %6, %2\n\tv_mfma_f32_32x32x16_bf16 %3, %5, %7, %3\n\t"
;         "s_waitcnt lgkmcnt(0)\n\t"
;         "v_mfma_f32_32x32x16_bf16 %0, %8, %10, %0\n\tv_mfma_f32_32x32x16_bf16 %1, %8, %11, %1\n\tv_mfma_f32_32x32x16_bf16 %2, %9, %10, %2\n\tv_mfma_f32_32x32x16_bf16 %3, %9, %11, %3"
;         : "+v"(acc[0][0]), "+v"(acc[0][1]), "+v"(acc[1][0]), "+v"(acc[1][1]),
;           "=&v"(p0), "=&v"(p1), "=&v"(q0), "=&v"(q1), "=&v"(u0), "=&v"(u1), "=&v"(w0), "=&v"(w1)
	ds_read_b128 v[164:167], v84
	ds_read_b128 v[168:171], v84 offset:4096
	ds_read_b128 v[172:175], v156
	ds_read_b128 v[176:179], v156 offset:4096
	v_mfma_f32_32x32x16_bf16 v[48:63], v[180:183], v[218:221], v[48:63]
	s_mov_b32 s14, 0xa5c2200
	s_add_u32 m0, s11, 0xc000
	v_lshl_add_u64 v[160:161], v[74:75], 0, s[14:15]
	global_load_lds_dwordx4 v[160:161], off
	v_mfma_f32_32x32x16_bf16 v[32:47], v[180:183], v[222:225], v[32:47]
	v_mfma_f32_32x32x16_bf16 v[16:31], v[184:187], v[218:221], v[16:31]
	s_add_u32 m0, s11, 0xe000
	v_lshl_add_u64 v[162:163], v[72:73], 0, s[14:15]
	global_load_lds_dwordx4 v[162:163], off
	v_mfma_f32_32x32x16_bf16 v[0:15], v[184:187], v[222:225], v[0:15]
	ds_read_b128 v[180:183], v85
	ds_read_b128 v[184:187], v85 offset:4096
	ds_read_b128 v[218:221], v157
	ds_read_b128 v[222:225], v157 offset:4096
	s_waitcnt lgkmcnt(4)
	v_mfma_f32_32x32x16_bf16 v[48:63], v[164:167], v[172:175], v[48:63]
	s_add_u32 m0, s11, 0x10000
	v_lshl_add_u64 v[160:161], v[70:71], 0, s[14:15]
	global_load_lds_dwordx4 v[160:161], off
	v_mfma_f32_32x32x16_bf16 v[32:47], v[164:167], v[176:179], v[32:47]
	v_mfma_f32_32x32x16_bf16 v[16:31], v[168:171], v[172:175], v[16:31]
	s_add_u32 m0, s11, 0x12000
	v_lshl_add_u64 v[162:163], v[68:69], 0, s[14:15]
	global_load_lds_dwordx4 v[162:163], off
	v_mfma_f32_32x32x16_bf16 v[0:15], v[168:171], v[176:179], v[0:15]
	ds_read_b128 v[164:167], v86
	ds_read_b128 v[168:171], v86 offset:4096
	ds_read_b128 v[172:175], v158
	ds_read_b128 v[176:179], v158 offset:4096
	s_waitcnt lgkmcnt(4)
	v_mfma_f32_32x32x16_bf16 v[48:63], v[180:183], v[218:221], v[48:63]
	s_mov_b32 s14, 0x1b80200
	s_add_u32 m0, s11, 0x14000
	v_lshl_add_u64 v[160:161], v[66:67], 0, s[14:15]
	global_load_lds_dwordx4 v[160:161], off
	v_mfma_f32_32x32x16_bf16 v[32:47], v[180:183], v[222:225], v[32:47]
	v_mfma_f32_32x32x16_bf16 v[16:31], v[184:187], v[218:221], v[16:31]
	s_add_u32 m0, s11, 0x16000
	v_lshl_add_u64 v[162:163], v[64:65], 0, s[14:15]
	global_load_lds_dwordx4 v[162:163], off
	v_mfma_f32_32x32x16_bf16 v[0:15], v[184:187], v[222:225], v[0:15]
	ds_read_b128 v[180:183], v87
	ds_read_b128 v[184:187], v87 offset:4096
	ds_read_b128 v[218:221], v159
	ds_read_b128 v[222:225], v159 offset:4096
	s_waitcnt lgkmcnt(4)
	v_mfma_f32_32x32x16_bf16 v[48:63], v[164:167], v[172:175], v[48:63]
	v_mfma_f32_32x32x16_bf16 v[32:47], v[164:167], v[176:179], v[32:47]
	v_mfma_f32_32x32x16_bf16 v[16:31], v[168:171], v[172:175], v[16:31]
	v_mfma_f32_32x32x16_bf16 v[0:15], v[168:171], v[176:179], v[0:15]
	s_waitcnt vmcnt(6) lgkmcnt(0)
	s_barrier
	ds_read_b128 v[164:167], v76
	ds_read_b128 v[168:171], v76 offset:4096
	ds_read_b128 v[172:175], v80
	ds_read_b128 v[176:179], v80 offset:4096
	v_mfma_f32_32x32x16_bf16 v[48:63], v[180:183], v[218:221], v[48:63]
	s_mov_b32 s14, 0xa5c2280
	s_add_u32 m0, s11, 0x18000
	v_lshl_add_u64 v[160:161], v[74:75], 0, s[14:15]
	global_load_lds_dwordx4 v[160:161], off
	v_mfma_f32_32x32x16_bf16 v[32:47], v[180:183], v[222:225], v[32:47]
	v_mfma_f32_32x32x16_bf16 v[16:31], v[184:187], v[218:221], v[16:31]
	s_add_u32 m0, s11, 0x1a000
	v_lshl_add_u64 v[162:163], v[72:73], 0, s[14:15]
	global_load_lds_dwordx4 v[162:163], off
	v_mfma_f32_32x32x16_bf16 v[0:15], v[184:187], v[222:225], v[0:15]
	ds_read_b128 v[180:183], v77
	ds_read_b128 v[184:187], v77 offset:4096
	ds_read_b128 v[218:221], v81
	ds_read_b128 v[222:225], v81 offset:4096
	s_waitcnt lgkmcnt(4)
	v_mfma_f32_32x32x16_bf16 v[48:63], v[164:167], v[172:175], v[48:63]
	s_add_u32 m0, s11, 0x1c000
	v_lshl_add_u64 v[160:161], v[70:71], 0, s[14:15]
	global_load_lds_dwordx4 v[160:161], off
	v_mfma_f32_32x32x16_bf16 v[32:47], v[164:167], v[176:179], v[32:47]
	v_mfma_f32_32x32x16_bf16 v[16:31], v[168:171], v[172:175], v[16:31]
	s_add_u32 m0, s11, 0x1e000
	v_lshl_add_u64 v[162:163], v[68:69], 0, s[14:15]
	global_load_lds_dwordx4 v[162:163], off
	v_mfma_f32_32x32x16_bf16 v[0:15], v[168:171], v[176:179], v[0:15]
	ds_read_b128 v[164:167], v78
	ds_read_b128 v[168:171], v78 offset:4096
	ds_read_b128 v[172:175], v82
	ds_read_b128 v[176:179], v82 offset:4096
	s_waitcnt lgkmcnt(4)
	v_mfma_f32_32x32x16_bf16 v[48:63], v[180:183], v[218:221], v[48:63]
	s_mov_b32 s14, 0x1b80280
	s_add_u32 m0, s11, 0x20000
	v_lshl_add_u64 v[160:161], v[66:67], 0, s[14:15]
	global_load_lds_dwordx4 v[160:161], off
	v_mfma_f32_32x32x16_bf16 v[32:47], v[180:183], v[222:225], v[32:47]
	v_mfma_f32_32x32x16_bf16 v[16:31], v[184:187], v[218:221], v[16:31]
	s_add_u32 m0, s11, 0x22000
	v_lshl_add_u64 v[162:163], v[64:65], 0, s[14:15]
	global_load_lds_dwordx4 v[162:163], off
	v_mfma_f32_32x32x16_bf16 v[0:15], v[184:187], v[222:225], v[0:15]
	ds_read_b128 v[180:183], v79
	ds_read_b128 v[184:187], v79 offset:4096
	ds_read_b128 v[218:221], v83
	ds_read_b128 v[222:225], v83 offset:4096
	s_waitcnt lgkmcnt(4)
	v_mfma_f32_32x32x16_bf16 v[48:63], v[164:167], v[172:175], v[48:63]
	v_mfma_f32_32x32x16_bf16 v[32:47], v[164:167], v[176:179], v[32:47]
	v_mfma_f32_32x32x16_bf16 v[16:31], v[168:171], v[172:175], v[16:31]
	v_mfma_f32_32x32x16_bf16 v[0:15], v[168:171], v[176:179], v[0:15]
	s_waitcnt vmcnt(6) lgkmcnt(0)
	s_barrier
;     ...
;   for (int kt = 0; kt < nk; ++kt) {
;     if (kt + 1 < nk) asm volatile("s_waitcnt vmcnt(6)" ::: "memory");
;     else asm volatile("s_waitcnt vmcnt(0)" ::: "memory");
;     __builtin_amdgcn_s_barrier();
;     asm volatile("" ::: "memory");
;     if (kt + 2 < nk) { const int st2 = (st >= 1) ? st - 1 : 2; GEMM_ISSUE(kt + 2, st2); }
;     const char* la = lds + st * STAGE_B;
;     const char* lb = la + 32768;
;     const unsigned sa_u = (unsigned)(size_t)la + arow_u, sb_u = (unsigned)(size_t)lb + brow_u;
;     const unsigned a0 = sa_u + co0, a1 = sa_u + co1, a2 = sa_u + co2, a3 = sa_u + co3;
;     const unsigned b0 = sb_u + co0, b1 = sb_u + co1, b2 = sb_u + co2, b3 = sb_u + co3;
;     {
;       bf16x8 p0, p1, q0, q1, u0, u1, w0, w1;
;       asm volatile(
;         "ds_read_b128 %4, %12\n\tds_read_b128 %5, %12 offset:4096\n\tds_read_b128 %6, %16\n\tds_read_b128 %7, %16 offset:4096\n\t"
;         "ds_read_b128 %8, %13\n\tds_read_b128 %9, %13 offset:4096\n\tds_read_b128 %10, %17\n\tds_read_b128 %11, %17 offset:4096\n\t"
;         "s_waitcnt lgkmcnt(4)\n\t"
;         "v_mfma_f32_32x32x16_bf16 %0, %4, %6, %0\n\tv_mfma_f32_32x32x16_bf16 %1, %4, %7, %1\n\tv_mfma_f32_32x32x16_bf16 %2, %5, %6, %2\n\tv_mfma_f32_32x32x16_bf16 %3, %5, %7, %3\n\t"
;         "ds_read_b128 %4, %14\n\tds_read_b128 %5, %14 offset:4096\n\tds_read_b128 %6, %18\n\tds_read_b128 %7, %18 offset:4096\n\t"
;         "s_waitcnt lgkmcnt(4)\n\t"
;         "v_mfma_f32_32x32x16_bf16 %0, %8, %10, %0\n\tv_mfma_f32_32x32x16_bf16 %1, %8, %11, %1\n\tv_mfma_f32_32x32x16_bf16 %2, %9, %10, %2\n\tv_mfma_f32_32x32x16_bf16 %3, %9, %11, %3\n\t"
;         "ds_read_b128 %8, %15\n\tds_read_b128 %9, %15 offset:4096\n\tds_read_b128 %10, %19\n\tds_read_b128 %11, %19 offset:4096\n\t"
;         "s_waitcnt lgkmcnt(4)\n\t"
;         "v_mfma_f32_32x32x16_bf16 %0, %4, %6, %0\n\tv_mfma_f32_32x32x16_bf16 %1, %4, %7, %1\n\tv_mfma_f32_32x32x16_bf16 %2, %5, %6, %2\n\tv_mfma_f32_32x32x16_bf16 %3, %5, %7, %3\n\t"
;         "s_waitcnt lgkmcnt(0)\n\t"
;         "v_mfma_f32_32x32x16_bf16 %0, %8, %10, %0\n\tv_mfma_f32_32x32x16_bf16 %1, %8, %11, %1\n\tv_mfma_f32_32x32x16_bf16 %2, %9, %10, %2\n\tv_mfma_f32_32x32x16_bf16 %3, %9, %11, %3"
;         : "+v"(acc[0][0]), "+v"(acc[0][1]), "+v"(acc[1][0]), "+v"(acc[1][1]),
;           "=&v"(p0), "=&v"(p1), "=&v"(q0), "=&v"(q1), "=&v"(u0), "=&v"(u1), "=&v"(w0), "=&v"(w1)
	ds_read_b128 v[164:167], v76 offset:49152
	ds_read_b128 v[168:171], v76 offset:53248
	ds_read_b128 v[172:175], v80 offset:49152
	ds_read_b128 v[176:179], v80 offset:53248
	v_mfma_f32_32x32x16_bf16 v[48:63], v[180:183], v[218:221], v[48:63]
	s_mov_b32 s14, 0xa5c2300
	s_mov_b32 m0, s11
	v_lshl_add_u64 v[160:161], v[74:75], 0, s[14:15]
	global_load_lds_dwordx4 v[160:161], off
	v_mfma_f32_32x32x16_bf16 v[32:47], v[180:183], v[222:225], v[32:47]
	v_mfma_f32_32x32x16_bf16 v[16:31], v[184:187], v[218:221], v[16:31]
	s_add_u32 m0, s11, 0x2000
	v_lshl_add_u64 v[162:163], v[72:73], 0, s[14:15]
	global_load_lds_dwordx4 v[162:163], off
	v_mfma_f32_32x32x16_bf16 v[0:15], v[184:187], v[222:225], v[0:15]
	ds_read_b128 v[180:183], v77 offset:49152
	ds_read_b128 v[184:187], v77 offset:53248
	ds_read_b128 v[218:221], v81 offset:49152
	ds_read_b128 v[222:225], v81 offset:53248
	s_waitcnt lgkmcnt(4)
	v_mfma_f32_32x32x16_bf16 v[48:63], v[164:167], v[172:175], v[48:63]
	s_add_u32 m0, s11, 0x4000
	v_lshl_add_u64 v[160:161], v[70:71], 0, s[14:15]
	global_load_lds_dwordx4 v[160:161], off
	v_mfma_f32_32x32x16_bf16 v[32:47], v[164:167], v[176:179], v[32:47]
	v_mfma_f32_32x32x16_bf16 v[16:31], v[168:171], v[172:175], v[16:31]
	s_add_u32 m0, s11, 0x6000
	v_lshl_add_u64 v[162:163], v[68:69], 0, s[14:15]
	global_load_lds_dwordx4 v[162:163], off
	v_mfma_f32_32x32x16_bf16 v[0:15], v[168:171], v[176:179], v[0:15]
	ds_read_b128 v[164:167], v78 offset:49152
	ds_read_b128 v[168:171], v78 offset:53248
	ds_read_b128 v[172:175], v82 offset:49152
	ds_read_b128 v[176:179], v82 offset:53248
	s_waitcnt lgkmcnt(4)
	v_mfma_f32_32x32x16_bf16 v[48:63], v[180:183], v[218:221], v[48:63]
	s_mov_b32 s14, 0x1b80300
	s_add_u32 m0, s11, 0x8000
	v_lshl_add_u64 v[160:161], v[66:67], 0, s[14:15]
	global_load_lds_dwordx4 v[160:161], off
	v_mfma_f32_32x32x16_bf16 v[32:47], v[180:183], v[222:225], v[32:47]
	v_mfma_f32_32x32x16_bf16 v[16:31], v[184:187], v[218:221], v[16:31]
	s_add_u32 m0, s11, 0xa000
	v_lshl_add_u64 v[162:163], v[64:65], 0, s[14:15]
	global_load_lds_dwordx4 v[162:163], off
	v_mfma_f32_32x32x16_bf16 v[0:15], v[184:187], v[222:225], v[0:15]
	ds_read_b128 v[180:183], v79 offset:49152
	ds_read_b128 v[184:187], v79 offset:53248
	ds_read_b128 v[218:221], v83 offset:49152
	ds_read_b128 v[222:225], v83 offset:53248
	s_waitcnt lgkmcnt(4)
	v_mfma_f32_32x32x16_bf16 v[48:63], v[164:167], v[172:175], v[48:63]
	v_mfma_f32_32x32x16_bf16 v[32:47], v[164:167], v[176:179], v[32:47]
	v_mfma_f32_32x32x16_bf16 v[16:31], v[168:171], v[172:175], v[16:31]
	v_mfma_f32_32x32x16_bf16 v[0:15], v[168:171], v[176:179], v[0:15]
	s_waitcnt vmcnt(6) lgkmcnt(0)
	s_barrier
	ds_read_b128 v[164:167], v84
	ds_read_b128 v[168:171], v84 offset:4096
	ds_read_b128 v[172:175], v156
	ds_read_b128 v[176:179], v156 offset:4096
	v_mfma_f32_32x32x16_bf16 v[48:63], v[180:183], v[218:221], v[48:63]
	s_mov_b32 s14, 0xa5c2380
	s_add_u32 m0, s11, 0xc000
	v_lshl_add_u64 v[160:161], v[74:75], 0, s[14:15]
	global_load_lds_dwordx4 v[160:161], off
	v_mfma_f32_32x32x16_bf16 v[32:47], v[180:183], v[222:225], v[32:47]
	v_mfma_f32_32x32x16_bf16 v[16:31], v[184:187], v[218:221], v[16:31]
	s_add_u32 m0, s11, 0xe000
	v_lshl_add_u64 v[162:163], v[72:73], 0, s[14:15]
	global_load_lds_dwordx4 v[162:163], off
	v_mfma_f32_32x32x16_bf16 v[0:15], v[184:187], v[222:225], v[0:15]
	ds_read_b128 v[180:183], v85
	ds_read_b128 v[184:187], v85 offset:4096
	ds_read_b128 v[218:221], v157
	ds_read_b128 v[222:225], v157 offset:4096
	s_waitcnt lgkmcnt(4)
	v_mfma_f32_32x32x16_bf16 v[48:63], v[164:167], v[172:175], v[48:63]
	s_add_u32 m0, s11, 0x10000
	v_lshl_add_u64 v[160:161], v[70:71], 0, s[14:15]
	global_load_lds_dwordx4 v[160:161], off
	v_mfma_f32_32x32x16_bf16 v[32:47], v[164:167], v[176:179], v[32:47]
	v_mfma_f32_32x32x16_bf16 v[16:31], v[168:171], v[172:175], v[16:31]
	s_add_u32 m0, s11, 0x12000
	v_lshl_add_u64 v[162:163], v[68:69], 0, s[14:15]
	global_load_lds_dwordx4 v[162:163], off
	v_mfma_f32_32x32x16_bf16 v[0:15], v[168:171], v[176:179], v[0:15]
	ds_read_b128 v[164:167], v86
	ds_read_b128 v[168:171], v86 offset:4096
	ds_read_b128 v[172:175], v158
	ds_read_b128 v[176:179], v158 offset:4096
	s_waitcnt lgkmcnt(4)
	v_mfma_f32_32x32x16_bf16 v[48:63], v[180:183], v[218:221], v[48:63]
	s_mov_b32 s14, 0x1b80380
	s_add_u32 m0, s11, 0x14000
	v_lshl_add_u64 v[160:161], v[66:67], 0, s[14:15]
	global_load_lds_dwordx4 v[160:161], off
	v_mfma_f32_32x32x16_bf16 v[32:47], v[180:183], v[222:225], v[32:47]
	v_mfma_f32_32x32x16_bf16 v[16:31], v[184:187], v[218:221], v[16:31]
	s_add_u32 m0, s11, 0x16000
	v_lshl_add_u64 v[162:163], v[64:65], 0, s[14:15]
	global_load_lds_dwordx4 v[162:163], off
	v_mfma_f32_32x32x16_bf16 v[0:15], v[184:187], v[222:225], v[0:15]
	ds_read_b128 v[180:183], v87
	ds_read_b128 v[184:187], v87 offset:4096
	ds_read_b128 v[218:221], v159
	ds_read_b128 v[222:225], v159 offset:4096
	s_waitcnt lgkmcnt(4)
	v_mfma_f32_32x32x16_bf16 v[48:63], v[164:167], v[172:175], v[48:63]
	v_mfma_f32_32x32x16_bf16 v[32:47], v[164:167], v[176:179], v[32:47]
	v_mfma_f32_32x32x16_bf16 v[16:31], v[168:171], v[172:175], v[16:31]
	v_mfma_f32_32x32x16_bf16 v[0:15], v[168:171], v[176:179], v[0:15]
	s_waitcnt vmcnt(6) lgkmcnt(0)
	s_barrier
;     ...
;   for (int kt = 0; kt < nk; ++kt) {
;     if (kt + 1 < nk) asm volatile("s_waitcnt vmcnt(6)" ::: "memory");
;     else asm volatile("s_waitcnt vmcnt(0)" ::: "memory");
;     __builtin_amdgcn_s_barrier();
;     asm volatile("" ::: "memory");
;     if (kt + 2 < nk) { const int st2 = (st >= 1) ? st - 1 : 2; GEMM_ISSUE(kt + 2, st2); }
;     const char* la = lds + st * STAGE_B;
;     const char* lb = la + 32768;
;     const unsigned sa_u = (unsigned)(size_t)la + arow_u, sb_u = (unsigned)(size_t)lb + brow_u;
;     const unsigned a0 = sa_u + co0, a1 = sa_u + co1, a2 = sa_u + co2, a3 = sa_u + co3;
;     const unsigned b0 = sb_u + co0, b1 = sb_u + co1, b2 = sb_u + co2, b3 = sb_u + co3;
;     {
;       bf16x8 p0, p1, q0, q1, u0, u1, w0, w1;
;       asm volatile(
;         "ds_read_b128 %4, %12\n\tds_read_b128 %5, %12 offset:4096\n\tds_read_b128 %6, %16\n\tds_read_b128 %7, %16 offset:4096\n\t"
;         "ds_read_b128 %8, %13\n\tds_read_b128 %9, %13 offset:4096\n\tds_read_b128 %10, %17\n\tds_read_b128 %11, %17 offset:4096\n\t"
;         "s_waitcnt lgkmcnt(4)\n\t"
;         "v_mfma_f32_32x32x16_bf16 %0, %4, %6, %0\n\tv_mfma_f32_32x32x16_bf16 %1, %4, %7, %1\n\tv_mfma_f32_32x32x16_bf16 %2, %5, %6, %2\n\tv_mfma_f32_32x32x16_bf16 %3, %5, %7, %3\n\t"
;         "ds_read_b128 %4, %14\n\tds_read_b128 %5, %14 offset:4096\n\tds_read_b128 %6, %18\n\tds_read_b128 %7, %18 offset:4096\n\t"
;         "s_waitcnt lgkmcnt(4)\n\t"
;         "v_mfma_f32_32x32x16_bf16 %0, %8, %10, %0\n\tv_mfma_f32_32x32x16_bf16 %1, %8, %11, %1\n\tv_mfma_f32_32x32x16_bf16 %2, %9, %10, %2\n\tv_mfma_f32_32x32x16_bf16 %3, %9, %11, %3\n\t"
;         "ds_read_b128 %8, %15\n\tds_read_b128 %9, %15 offset:4096\n\tds_read_b128 %10, %19\n\tds_read_b128 %11, %19 offset:4096\n\t"
;         "s_waitcnt lgkmcnt(4)\n\t"
;         "v_mfma_f32_32x32x16_bf16 %0, %4, %6, %0\n\tv_mfma_f32_32x32x16_bf16 %1, %4, %7, %1\n\tv_mfma_f32_32x32x16_bf16 %2, %5, %6, %2\n\tv_mfma_f32_32x32x16_bf16 %3, %5, %7, %3\n\t"
;         "s_waitcnt lgkmcnt(0)\n\t"
;         "v_mfma_f32_32x32x16_bf16 %0, %8, %10, %0\n\tv_mfma_f32_32x32x16_bf16 %1, %8, %11, %1\n\tv_mfma_f32_32x32x16_bf16 %2, %9, %10, %2\n\tv_mfma_f32_32x32x16_bf16 %3, %9, %11, %3"
;         : "+v"(acc[0][0]), "+v"(acc[0][1]), "+v"(acc[1][0]), "+v"(acc[1][1]),
;           "=&v"(p0), "=&v"(p1), "=&v"(q0), "=&v"(q1), "=&v"(u0), "=&v"(u1), "=&v"(w0), "=&v"(w1)
	ds_read_b128 v[164:167], v76
	ds_read_b128 v[168:171], v76 offset:4096
	ds_read_b128 v[172:175], v80
	ds_read_b128 v[176:179], v80 offset:4096
	v_mfma_f32_32x32x16_bf16 v[48:63], v[180:183], v[218:221], v[48:63]
	s_mov_b32 s14, 0xa5c2400
	s_add_u32 m0, s11, 0x18000
	v_lshl_add_u64 v[160:161], v[74:75], 0, s[14:15]
	global_load_lds_dwordx4 v[160:161], off
	v_mfma_f32_32x32x16_bf16 v[32:47], v[180:183], v[222:225], v[32:47]
	v_mfma_f32_32x32x16_bf16 v[16:31], v[184:187], v[218:221], v[16:31]
	s_add_u32 m0, s11, 0x1a000
	v_lshl_add_u64 v[162:163], v[72:73], 0, s[14:15]
	global_load_lds_dwordx4 v[162:163], off
	v_mfma_f32_32x32x16_bf16 v[0:15], v[184:187], v[222:225], v[0:15]
	ds_read_b128 v[180:183], v77
	ds_read_b128 v[184:187], v77 offset:4096
	ds_read_b128 v[218:221], v81
	ds_read_b128 v[222:225], v81 offset:4096
	s_waitcnt lgkmcnt(4)
	v_mfma_f32_32x32x16_bf16 v[48:63], v[164:167], v[172:175], v[48:63]
	s_add_u32 m0, s11, 0x1c000
	v_lshl_add_u64 v[160:161], v[70:71], 0, s[14:15]
	global_load_lds_dwordx4 v[160:161], off
	v_mfma_f32_32x32x16_bf16 v[32:47], v[164:167], v[176:179], v[32:47]
	v_mfma_f32_32x32x16_bf16 v[16:31], v[168:171], v[172:175], v[16:31]
	s_add_u32 m0, s11, 0x1e000
	v_lshl_add_u64 v[162:163], v[68:69], 0, s[14:15]
	global_load_lds_dwordx4 v[162:163], off
	v_mfma_f32_32x32x16_bf16 v[0:15], v[168:171], v[176:179], v[0:15]
	ds_read_b128 v[164:167], v78
	ds_read_b128 v[168:171], v78 offset:4096
	ds_read_b128 v[172:175], v82
	ds_read_b128 v[176:179], v82 offset:4096
	s_waitcnt lgkmcnt(4)
	v_mfma_f32_32x32x16_bf16 v[48:63], v[180:183], v[218:221], v[48:63]
	s_mov_b32 s14, 0x1b80400
	s_add_u32 m0, s11, 0x20000
	v_lshl_add_u64 v[160:161], v[66:67], 0, s[14:15]
	global_load_lds_dwordx4 v[160:161], off
	v_mfma_f32_32x32x16_bf16 v[32:47], v[180:183], v[222:225], v[32:47]
	v_mfma_f32_32x32x16_bf16 v[16:31], v[184:187], v[218:221], v[16:31]
	s_add_u32 m0, s11, 0x22000
	v_lshl_add_u64 v[162:163], v[64:65], 0, s[14:15]
	global_load_lds_dwordx4 v[162:163], off
	v_mfma_f32_32x32x16_bf16 v[0:15], v[184:187], v[222:225], v[0:15]
	ds_read_b128 v[180:183], v79
	ds_read_b128 v[184:187], v79 offset:4096
	ds_read_b128 v[218:221], v83
	ds_read_b128 v[222:225], v83 offset:4096
	s_waitcnt lgkmcnt(4)
	v_mfma_f32_32x32x16_bf16 v[48:63], v[164:167], v[172:175], v[48:63]
	v_mfma_f32_32x32x16_bf16 v[32:47], v[164:167], v[176:179], v[32:47]
	v_mfma_f32_32x32x16_bf16 v[16:31], v[168:171], v[172:175], v[16:31]
	v_mfma_f32_32x32x16_bf16 v[0:15], v[168:171], v[176:179], v[0:15]
	s_waitcnt vmcnt(6) lgkmcnt(0)
	s_barrier
	ds_read_b128 v[164:167], v76 offset:49152
	ds_read_b128 v[168:171], v76 offset:53248
	ds_read_b128 v[172:175], v80 offset:49152
	ds_read_b128 v[176:179], v80 offset:53248
	v_mfma_f32_32x32x16_bf16 v[48:63], v[180:183], v[218:221], v[48:63]
	s_mov_b32 s14, 0xa5c2480
	s_mov_b32 m0, s11
	v_lshl_add_u64 v[160:161], v[74:75], 0, s[14:15]
	global_load_lds_dwordx4 v[160:161], off
	v_mfma_f32_32x32x16_bf16 v[32:47], v[180:183], v[222:225], v[32:47]
	v_mfma_f32_32x32x16_bf16 v[16:31], v[184:187], v[218:221], v[16:31]
	s_add_u32 m0, s11, 0x2000
	v_lshl_add_u64 v[162:163], v[72:73], 0, s[14:15]
	global_load_lds_dwordx4 v[162:163], off
	v_mfma_f32_32x32x16_bf16 v[0:15], v[184:187], v[222:225], v[0:15]
	ds_read_b128 v[180:183], v77 offset:49152
	ds_read_b128 v[184:187], v77 offset:53248
	ds_read_b128 v[218:221], v81 offset:49152
	ds_read_b128 v[222:225], v81 offset:53248
	s_waitcnt lgkmcnt(4)
	v_mfma_f32_32x32x16_bf16 v[48:63], v[164:167], v[172:175], v[48:63]
	s_add_u32 m0, s11, 0x4000
	v_lshl_add_u64 v[160:161], v[70:71], 0, s[14:15]
	global_load_lds_dwordx4 v[160:161], off
	v_mfma_f32_32x32x16_bf16 v[32:47], v[164:167], v[176:179], v[32:47]
	v_mfma_f32_32x32x16_bf16 v[16:31], v[168:171], v[172:175], v[16:31]
	s_add_u32 m0, s11, 0x6000
	v_lshl_add_u64 v[162:163], v[68:69], 0, s[14:15]
	global_load_lds_dwordx4 v[162:163], off
	v_mfma_f32_32x32x16_bf16 v[0:15], v[168:171], v[176:179], v[0:15]
	ds_read_b128 v[164:167], v78 offset:49152
	ds_read_b128 v[168:171], v78 offset:53248
	ds_read_b128 v[172:175], v82 offset:49152
	ds_read_b128 v[176:179], v82 offset:53248
	s_waitcnt lgkmcnt(4)
	v_mfma_f32_32x32x16_bf16 v[48:63], v[180:183], v[218:221], v[48:63]
	s_mov_b32 s14, 0x1b80480
	s_add_u32 m0, s11, 0x8000
	v_lshl_add_u64 v[160:161], v[66:67], 0, s[14:15]
	global_load_lds_dwordx4 v[160:161], off
	v_mfma_f32_32x32x16_bf16 v[32:47], v[180:183], v[222:225], v[32:47]
	v_mfma_f32_32x32x16_bf16 v[16:31], v[184:187], v[218:221], v[16:31]
	s_add_u32 m0, s11, 0xa000
	v_lshl_add_u64 v[162:163], v[64:65], 0, s[14:15]
	global_load_lds_dwordx4 v[162:163], off
	v_mfma_f32_32x32x16_bf16 v[0:15], v[184:187], v[222:225], v[0:15]
	ds_read_b128 v[180:183], v79 offset:49152
	ds_read_b128 v[184:187], v79 offset:53248
	ds_read_b128 v[218:221], v83 offset:49152
	ds_read_b128 v[222:225], v83 offset:53248
	s_waitcnt lgkmcnt(4)
	v_mfma_f32_32x32x16_bf16 v[48:63], v[164:167], v[172:175], v[48:63]
	v_mfma_f32_32x32x16_bf16 v[32:47], v[164:167], v[176:179], v[32:47]
	v_mfma_f32_32x32x16_bf16 v[16:31], v[168:171], v[172:175], v[16:31]
	v_mfma_f32_32x32x16_bf16 v[0:15], v[168:171], v[176:179], v[0:15]
	s_waitcnt vmcnt(6) lgkmcnt(0)
	s_barrier
;     ...
;   for (int kt = 0; kt < nk; ++kt) {
;     if (kt + 1 < nk) asm volatile("s_waitcnt vmcnt(6)" ::: "memory");
;     else asm volatile("s_waitcnt vmcnt(0)" ::: "memory");
;     __builtin_amdgcn_s_barrier();
;     asm volatile("" ::: "memory");
;     if (kt + 2 < nk) { const int st2 = (st >= 1) ? st - 1 : 2; GEMM_ISSUE(kt + 2, st2); }
;     const char* la = lds + st * STAGE_B;
;     const char* lb = la + 32768;
;     const unsigned sa_u = (unsigned)(size_t)la + arow_u, sb_u = (unsigned)(size_t)lb + brow_u;
;     const unsigned a0 = sa_u + co0, a1 = sa_u + co1, a2 = sa_u + co2, a3 = sa_u + co3;
;     const unsigned b0 = sb_u + co0, b1 = sb_u + co1, b2 = sb_u + co2, b3 = sb_u + co3;
;     {
;       bf16x8 p0, p1, q0, q1, u0, u1, w0, w1;
;       asm volatile(
;         "ds_read_b128 %4, %12\n\tds_read_b128 %5, %12 offset:4096\n\tds_read_b128 %6, %16\n\tds_read_b128 %7, %16 offset:4096\n\t"
;         "ds_read_b128 %8, %13\n\tds_read_b128 %9, %13 offset:4096\n\tds_read_b128 %10, %17\n\tds_read_b128 %11, %17 offset:4096\n\t"
;         "s_waitcnt lgkmcnt(4)\n\t"
;         "v_mfma_f32_32x32x16_bf16 %0, %4, %6, %0\n\tv_mfma_f32_32x32x16_bf16 %1, %4, %7, %1\n\tv_mfma_f32_32x32x16_bf16 %2, %5, %6, %2\n\tv_mfma_f32_32x32x16_bf16 %3, %5, %7, %3\n\t"
;         "ds_read_b128 %4, %14\n\tds_read_b128 %5, %14 offset:4096\n\tds_read_b128 %6, %18\n\tds_read_b128 %7, %18 offset:4096\n\t"
;         "s_waitcnt lgkmcnt(4)\n\t"
;         "v_mfma_f32_32x32x16_bf16 %0, %8, %10, %0\n\tv_mfma_f32_32x32x16_bf16 %1, %8, %11, %1\n\tv_mfma_f32_32x32x16_bf16 %2, %9, %10, %2\n\tv_mfma_f32_32x32x16_bf16 %3, %9, %11, %3\n\t"
;         "ds_read_b128 %8, %15\n\tds_read_b128 %9, %15 offset:4096\n\tds_read_b128 %10, %19\n\tds_read_b128 %11, %19 offset:4096\n\t"
;         "s_waitcnt lgkmcnt(4)\n\t"
;         "v_mfma_f32_32x32x16_bf16 %0, %4, %6, %0\n\tv_mfma_f32_32x32x16_bf16 %1, %4, %7, %1\n\tv_mfma_f32_32x32x16_bf16 %2, %5, %6, %2\n\tv_mfma_f32_32x32x16_bf16 %3, %5, %7, %3\n\t"
;         "s_waitcnt lgkmcnt(0)\n\t"
;         "v_mfma_f32_32x32x16_bf16 %0, %8, %10, %0\n\tv_mfma_f32_32x32x16_bf16 %1, %8, %11, %1\n\tv_mfma_f32_32x32x16_bf16 %2, %9, %10, %2\n\tv_mfma_f32_32x32x16_bf16 %3, %9, %11, %3"
;         : "+v"(acc[0][0]), "+v"(acc[0][1]), "+v"(acc[1][0]), "+v"(acc[1][1]),
;           "=&v"(p0), "=&v"(p1), "=&v"(q0), "=&v"(q1), "=&v"(u0), "=&v"(u1), "=&v"(w0), "=&v"(w1)
	ds_read_b128 v[164:167], v84
	ds_read_b128 v[168:171], v84 offset:4096
	ds_read_b128 v[172:175], v156
	ds_read_b128 v[176:179], v156 offset:4096
	v_mfma_f32_32x32x16_bf16 v[48:63], v[180:183], v[218:221], v[48:63]
	s_mov_b32 s14, 0xa5c2500
	s_add_u32 m0, s11, 0xc000
	v_lshl_add_u64 v[160:161], v[74:75], 0, s[14:15]
	global_load_lds_dwordx4 v[160:161], off
	v_mfma_f32_32x32x16_bf16 v[32:47], v[180:183], v[222:225], v[32:47]
	v_mfma_f32_32x32x16_bf16 v[16:31], v[184:187], v[218:221], v[16:31]
	s_add_u32 m0, s11, 0xe000
	v_lshl_add_u64 v[162:163], v[72:73], 0, s[14:15]
	global_load_lds_dwordx4 v[162:163], off
	v_mfma_f32_32x32x16_bf16 v[0:15], v[184:187], v[222:225], v[0:15]
	ds_read_b128 v[180:183], v85
	ds_read_b128 v[184:187], v85 offset:4096
	ds_read_b128 v[218:221], v157
	ds_read_b128 v[222:225], v157 offset:4096
	s_waitcnt lgkmcnt(4)
	v_mfma_f32_32x32x16_bf16 v[48:63], v[164:167], v[172:175], v[48:63]
	s_add_u32 m0, s11, 0x10000
	v_lshl_add_u64 v[160:161], v[70:71], 0, s[14:15]
	global_load_lds_dwordx4 v[160:161], off
	v_mfma_f32_32x32x16_bf16 v[32:47], v[164:167], v[176:179], v[32:47]
	v_mfma_f32_32x32x16_bf16 v[16:31], v[168:171], v[172:175], v[16:31]
	s_add_u32 m0, s11, 0x12000
	v_lshl_add_u64 v[162:163], v[68:69], 0, s[14:15]
	global_load_lds_dwordx4 v[162:163], off
	v_mfma_f32_32x32x16_bf16 v[0:15], v[168:171], v[176:179], v[0:15]
	ds_read_b128 v[164:167], v86
	ds_read_b128 v[168:171], v86 offset:4096
	ds_read_b128 v[172:175], v158
	ds_read_b128 v[176:179], v158 offset:4096
	s_waitcnt lgkmcnt(4)
	v_mfma_f32_32x32x16_bf16 v[48:63], v[180:183], v[218:221], v[48:63]
	s_mov_b32 s14, 0x1b80500
	s_add_u32 m0, s11, 0x14000
	v_lshl_add_u64 v[160:161], v[66:67], 0, s[14:15]
	global_load_lds_dwordx4 v[160:161], off
	v_mfma_f32_32x32x16_bf16 v[32:47], v[180:183], v[222:225], v[32:47]
	v_mfma_f32_32x32x16_bf16 v[16:31], v[184:187], v[218:221], v[16:31]
	s_add_u32 m0, s11, 0x16000
	v_lshl_add_u64 v[162:163], v[64:65], 0, s[14:15]
	global_load_lds_dwordx4 v[162:163], off
	v_mfma_f32_32x32x16_bf16 v[0:15], v[184:187], v[222:225], v[0:15]
	ds_read_b128 v[180:183], v87
	ds_read_b128 v[184:187], v87 offset:4096
	ds_read_b128 v[218:221], v159
	ds_read_b128 v[222:225], v159 offset:4096
	s_waitcnt lgkmcnt(4)
	v_mfma_f32_32x32x16_bf16 v[48:63], v[164:167], v[172:175], v[48:63]
	v_mfma_f32_32x32x16_bf16 v[32:47], v[164:167], v[176:179], v[32:47]
	v_mfma_f32_32x32x16_bf16 v[16:31], v[168:171], v[172:175], v[16:31]
	v_mfma_f32_32x32x16_bf16 v[0:15], v[168:171], v[176:179], v[0:15]
	s_waitcnt vmcnt(6) lgkmcnt(0)
	s_barrier
	ds_read_b128 v[164:167], v76
	ds_read_b128 v[168:171], v76 offset:4096
	ds_read_b128 v[172:175], v80
	ds_read_b128 v[176:179], v80 offset:4096
	v_mfma_f32_32x32x16_bf16 v[48:63], v[180:183], v[218:221], v[48:63]
	s_mov_b32 s14, 0xa5c2580
	s_add_u32 m0, s11, 0x18000
	v_lshl_add_u64 v[160:161], v[74:75], 0, s[14:15]
	global_load_lds_dwordx4 v[160:161], off
	v_mfma_f32_32x32x16_bf16 v[32:47], v[180:183], v[222:225], v[32:47]
	v_mfma_f32_32x32x16_bf16 v[16:31], v[184:187], v[218:221], v[16:31]
	s_add_u32 m0, s11, 0x1a000
	v_lshl_add_u64 v[162:163], v[72:73], 0, s[14:15]
	global_load_lds_dwordx4 v[162:163], off
	v_mfma_f32_32x32x16_bf16 v[0:15], v[184:187], v[222:225], v[0:15]
	ds_read_b128 v[180:183], v77
	ds_read_b128 v[184:187], v77 offset:4096
	ds_read_b128 v[218:221], v81
	ds_read_b128 v[222:225], v81 offset:4096
	s_waitcnt lgkmcnt(4)
	v_mfma_f32_32x32x16_bf16 v[48:63], v[164:167], v[172:175], v[48:63]
	s_add_u32 m0, s11, 0x1c000
	v_lshl_add_u64 v[160:161], v[70:71], 0, s[14:15]
	global_load_lds_dwordx4 v[160:161], off
	v_mfma_f32_32x32x16_bf16 v[32:47], v[164:167], v[176:179], v[32:47]
	v_mfma_f32_32x32x16_bf16 v[16:31], v[168:171], v[172:175], v[16:31]
	s_add_u32 m0, s11, 0x1e000
	v_lshl_add_u64 v[162:163], v[68:69], 0, s[14:15]
	global_load_lds_dwordx4 v[162:163], off
	v_mfma_f32_32x32x16_bf16 v[0:15], v[168:171], v[176:179], v[0:15]
	ds_read_b128 v[164:167], v78
	ds_read_b128 v[168:171], v78 offset:4096
	ds_read_b128 v[172:175], v82
	ds_read_b128 v[176:179], v82 offset:4096
	s_waitcnt lgkmcnt(4)
	v_mfma_f32_32x32x16_bf16 v[48:63], v[180:183], v[218:221], v[48:63]
	s_mov_b32 s14, 0x1b80580
	s_add_u32 m0, s11, 0x20000
	v_lshl_add_u64 v[160:161], v[66:67], 0, s[14:15]
	global_load_lds_dwordx4 v[160:161], off
	v_mfma_f32_32x32x16_bf16 v[32:47], v[180:183], v[222:225], v[32:47]
	v_mfma_f32_32x32x16_bf16 v[16:31], v[184:187], v[218:221], v[16:31]
	s_add_u32 m0, s11, 0x22000
	v_lshl_add_u64 v[162:163], v[64:65], 0, s[14:15]
	global_load_lds_dwordx4 v[162:163], off
	v_mfma_f32_32x32x16_bf16 v[0:15], v[184:187], v[222:225], v[0:15]
	ds_read_b128 v[180:183], v79
	ds_read_b128 v[184:187], v79 offset:4096
	ds_read_b128 v[218:221], v83
	ds_read_b128 v[222:225], v83 offset:4096
	s_waitcnt lgkmcnt(4)
	v_mfma_f32_32x32x16_bf16 v[48:63], v[164:167], v[172:175], v[48:63]
	v_mfma_f32_32x32x16_bf16 v[32:47], v[164:167], v[176:179], v[32:47]
	v_mfma_f32_32x32x16_bf16 v[16:31], v[168:171], v[172:175], v[16:31]
	v_mfma_f32_32x32x16_bf16 v[0:15], v[168:171], v[176:179], v[0:15]
	s_waitcnt vmcnt(6) lgkmcnt(0)
	s_barrier
;     ...
;   for (int kt = 0; kt < nk; ++kt) {
;     if (kt + 1 < nk) asm volatile("s_waitcnt vmcnt(6)" ::: "memory");
;     else asm volatile("s_waitcnt vmcnt(0)" ::: "memory");
;     __builtin_amdgcn_s_barrier();
;     asm volatile("" ::: "memory");
;     if (kt + 2 < nk) { const int st2 = (st >= 1) ? st - 1 : 2; GEMM_ISSUE(kt + 2, st2); }
;     const char* la = lds + st * STAGE_B;
;     const char* lb = la + 32768;
;     const unsigned sa_u = (unsigned)(size_t)la + arow_u, sb_u = (unsigned)(size_t)lb + brow_u;
;     const unsigned a0 = sa_u + co0, a1 = sa_u + co1, a2 = sa_u + co2, a3 = sa_u + co3;
;     const unsigned b0 = sb_u + co0, b1 = sb_u + co1, b2 = sb_u + co2, b3 = sb_u + co3;
;     {
;       bf16x8 p0, p1, q0, q1, u0, u1, w0, w1;
;       asm volatile(
;         "ds_read_b128 %4, %12\n\tds_read_b128 %5, %12 offset:4096\n\tds_read_b128 %6, %16\n\tds_read_b128 %7, %16 offset:4096\n\t"
;         "ds_read_b128 %8, %13\n\tds_read_b128 %9, %13 offset:4096\n\tds_read_b128 %10, %17\n\tds_read_b128 %11, %17 offset:4096\n\t"
;         "s_waitcnt lgkmcnt(4)\n\t"
;         "v_mfma_f32_32x32x16_bf16 %0, %4, %6, %0\n\tv_mfma_f32_32x32x16_bf16 %1, %4, %7, %1\n\tv_mfma_f32_32x32x16_bf16 %2, %5, %6, %2\n\tv_mfma_f32_32x32x16_bf16 %3, %5, %7, %3\n\t"
;         "ds_read_b128 %4, %14\n\tds_read_b128 %5, %14 offset:4096\n\tds_read_b128 %6, %18\n\tds_read_b128 %7, %18 offset:4096\n\t"
;         "s_waitcnt lgkmcnt(4)\n\t"
;         "v_mfma_f32_32x32x16_bf16 %0, %8, %10, %0\n\tv_mfma_f32_32x32x16_bf16 %1, %8, %11, %1\n\tv_mfma_f32_32x32x16_bf16 %2, %9, %10, %2\n\tv_mfma_f32_32x32x16_bf16 %3, %9, %11, %3\n\t"
;         "ds_read_b128 %8, %15\n\tds_read_b128 %9, %15 offset:4096\n\tds_read_b128 %10, %19\n\tds_read_b128 %11, %19 offset:4096\n\t"
;         "s_waitcnt lgkmcnt(4)\n\t"
;         "v_mfma_f32_32x32x16_bf16 %0, %4, %6, %0\n\tv_mfma_f32_32x32x16_bf16 %1, %4, %7, %1\n\tv_mfma_f32_32x32x16_bf16 %2, %5, %6, %2\n\tv_mfma_f32_32x32x16_bf16 %3, %5, %7, %3\n\t"
;         "s_waitcnt lgkmcnt(0)\n\t"
;         "v_mfma_f32_32x32x16_bf16 %0, %8, %10, %0\n\tv_mfma_f32_32x32x16_bf16 %1, %8, %11, %1\n\tv_mfma_f32_32x32x16_bf16 %2, %9, %10, %2\n\tv_mfma_f32_32x32x16_bf16 %3, %9, %11, %3"
;         : "+v"(acc[0][0]), "+v"(acc[0][1]), "+v"(acc[1][0]), "+v"(acc[1][1]),
;           "=&v"(p0), "=&v"(p1), "=&v"(q0), "=&v"(q1), "=&v"(u0), "=&v"(u1), "=&v"(w0), "=&v"(w1)
	ds_read_b128 v[164:167], v76 offset:49152
	ds_read_b128 v[168:171], v76 offset:53248
	ds_read_b128 v[172:175], v80 offset:49152
	ds_read_b128 v[176:179], v80 offset:53248
	v_mfma_f32_32x32x16_bf16 v[48:63], v[180:183], v[218:221], v[48:63]
	s_mov_b32 s14, 0xa5c2600
	s_mov_b32 m0, s11
	v_lshl_add_u64 v[160:161], v[74:75], 0, s[14:15]
	global_load_lds_dwordx4 v[160:161], off
	v_mfma_f32_32x32x16_bf16 v[32:47], v[180:183], v[222:225], v[32:47]
	v_mfma_f32_32x32x16_bf16 v[16:31], v[184:187], v[218:221], v[16:31]
	s_add_u32 m0, s11, 0x2000
	v_lshl_add_u64 v[162:163], v[72:73], 0, s[14:15]
	global_load_lds_dwordx4 v[162:163], off
	v_mfma_f32_32x32x16_bf16 v[0:15], v[184:187], v[222:225], v[0:15]
	ds_read_b128 v[180:183], v77 offset:49152
	ds_read_b128 v[184:187], v77 offset:53248
	ds_read_b128 v[218:221], v81 offset:49152
	ds_read_b128 v[222:225], v81 offset:53248
	s_waitcnt lgkmcnt(4)
	v_mfma_f32_32x32x16_bf16 v[48:63], v[164:167], v[172:175], v[48:63]
	s_add_u32 m0, s11, 0x4000
	v_lshl_add_u64 v[160:161], v[70:71], 0, s[14:15]
	global_load_lds_dwordx4 v[160:161], off
	v_mfma_f32_32x32x16_bf16 v[32:47], v[164:167], v[176:179], v[32:47]
	v_mfma_f32_32x32x16_bf16 v[16:31], v[168:171], v[172:175], v[16:31]
	s_add_u32 m0, s11, 0x6000
	v_lshl_add_u64 v[162:163], v[68:69], 0, s[14:15]
	global_load_lds_dwordx4 v[162:163], off
	v_mfma_f32_32x32x16_bf16 v[0:15], v[168:171], v[176:179], v[0:15]
	ds_read_b128 v[164:167], v78 offset:49152
	ds_read_b128 v[168:171], v78 offset:53248
	ds_read_b128 v[172:175], v82 offset:49152
	ds_read_b128 v[176:179], v82 offset:53248
	s_waitcnt lgkmcnt(4)
	v_mfma_f32_32x32x16_bf16 v[48:63], v[180:183], v[218:221], v[48:63]
	s_mov_b32 s14, 0x1b80600
	s_add_u32 m0, s11, 0x8000
	v_lshl_add_u64 v[160:161], v[66:67], 0, s[14:15]
	global_load_lds_dwordx4 v[160:161], off
	v_mfma_f32_32x32x16_bf16 v[32:47], v[180:183], v[222:225], v[32:47]
	v_mfma_f32_32x32x16_bf16 v[16:31], v[184:187], v[218:221], v[16:31]
	s_add_u32 m0, s11, 0xa000
	v_lshl_add_u64 v[162:163], v[64:65], 0, s[14:15]
	global_load_lds_dwordx4 v[162:163], off
	v_mfma_f32_32x32x16_bf16 v[0:15], v[184:187], v[222:225], v[0:15]
	ds_read_b128 v[180:183], v79 offset:49152
	ds_read_b128 v[184:187], v79 offset:53248
	ds_read_b128 v[218:221], v83 offset:49152
	ds_read_b128 v[222:225], v83 offset:53248
	s_waitcnt lgkmcnt(4)
	v_mfma_f32_32x32x16_bf16 v[48:63], v[164:167], v[172:175], v[48:63]
	v_mfma_f32_32x32x16_bf16 v[32:47], v[164:167], v[176:179], v[32:47]
	v_mfma_f32_32x32x16_bf16 v[16:31], v[168:171], v[172:175], v[16:31]
	v_mfma_f32_32x32x16_bf16 v[0:15], v[168:171], v[176:179], v[0:15]
	s_waitcnt vmcnt(6) lgkmcnt(0)
	s_barrier
	ds_read_b128 v[164:167], v84
	ds_read_b128 v[168:171], v84 offset:4096
	ds_read_b128 v[172:175], v156
	ds_read_b128 v[176:179], v156 offset:4096
	v_mfma_f32_32x32x16_bf16 v[48:63], v[180:183], v[218:221], v[48:63]
	s_mov_b32 s14, 0xa5c2680
	s_add_u32 m0, s11, 0xc000
	v_lshl_add_u64 v[160:161], v[74:75], 0, s[14:15]
	global_load_lds_dwordx4 v[160:161], off
	v_mfma_f32_32x32x16_bf16 v[32:47], v[180:183], v[222:225], v[32:47]
	v_mfma_f32_32x32x16_bf16 v[16:31], v[184:187], v[218:221], v[16:31]
	s_add_u32 m0, s11, 0xe000
	v_lshl_add_u64 v[162:163], v[72:73], 0, s[14:15]
	global_load_lds_dwordx4 v[162:163], off
	v_mfma_f32_32x32x16_bf16 v[0:15], v[184:187], v[222:225], v[0:15]
	ds_read_b128 v[180:183], v85
	ds_read_b128 v[184:187], v85 offset:4096
	ds_read_b128 v[218:221], v157
	ds_read_b128 v[222:225], v157 offset:4096
	s_waitcnt lgkmcnt(4)
	v_mfma_f32_32x32x16_bf16 v[48:63], v[164:167], v[172:175], v[48:63]
	s_add_u32 m0, s11, 0x10000
	v_lshl_add_u64 v[160:161], v[70:71], 0, s[14:15]
	global_load_lds_dwordx4 v[160:161], off
	v_mfma_f32_32x32x16_bf16 v[32:47], v[164:167], v[176:179], v[32:47]
	v_mfma_f32_32x32x16_bf16 v[16:31], v[168:171], v[172:175], v[16:31]
	s_add_u32 m0, s11, 0x12000
	v_lshl_add_u64 v[162:163], v[68:69], 0, s[14:15]
	global_load_lds_dwordx4 v[162:163], off
	v_mfma_f32_32x32x16_bf16 v[0:15], v[168:171], v[176:179], v[0:15]
	ds_read_b128 v[164:167], v86
	ds_read_b128 v[168:171], v86 offset:4096
	ds_read_b128 v[172:175], v158
	ds_read_b128 v[176:179], v158 offset:4096
	s_waitcnt lgkmcnt(4)
	v_mfma_f32_32x32x16_bf16 v[48:63], v[180:183], v[218:221], v[48:63]
	s_mov_b32 s14, 0x1b80680
	s_add_u32 m0, s11, 0x14000
	v_lshl_add_u64 v[160:161], v[66:67], 0, s[14:15]
	global_load_lds_dwordx4 v[160:161], off
	v_mfma_f32_32x32x16_bf16 v[32:47], v[180:183], v[222:225], v[32:47]
	v_mfma_f32_32x32x16_bf16 v[16:31], v[184:187], v[218:221], v[16:31]
	s_add_u32 m0, s11, 0x16000
	v_lshl_add_u64 v[162:163], v[64:65], 0, s[14:15]
	global_load_lds_dwordx4 v[162:163], off
	v_mfma_f32_32x32x16_bf16 v[0:15], v[184:187], v[222:225], v[0:15]
	ds_read_b128 v[180:183], v87
	ds_read_b128 v[184:187], v87 offset:4096
	ds_read_b128 v[218:221], v159
	ds_read_b128 v[222:225], v159 offset:4096
	s_waitcnt lgkmcnt(4)
	v_mfma_f32_32x32x16_bf16 v[48:63], v[164:167], v[172:175], v[48:63]
	v_mfma_f32_32x32x16_bf16 v[32:47], v[164:167], v[176:179], v[32:47]
	v_mfma_f32_32x32x16_bf16 v[16:31], v[168:171], v[172:175], v[16:31]
	v_mfma_f32_32x32x16_bf16 v[0:15], v[168:171], v[176:179], v[0:15]
	s_waitcnt vmcnt(6) lgkmcnt(0)
	s_barrier
;     ...
;   for (int kt = 0; kt < nk; ++kt) {
;     if (kt + 1 < nk) asm volatile("s_waitcnt vmcnt(6)" ::: "memory");
;     else asm volatile("s_waitcnt vmcnt(0)" ::: "memory");
;     __builtin_amdgcn_s_barrier();
;     asm volatile("" ::: "memory");
;     if (kt + 2 < nk) { const int st2 = (st >= 1) ? st - 1 : 2; GEMM_ISSUE(kt + 2, st2); }
;     const char* la = lds + st * STAGE_B;
;     const char* lb = la + 32768;
;     const unsigned sa_u = (unsigned)(size_t)la + arow_u, sb_u = (unsigned)(size_t)lb + brow_u;
;     const unsigned a0 = sa_u + co0, a1 = sa_u + co1, a2 = sa_u + co2, a3 = sa_u + co3;
;     const unsigned b0 = sb_u + co0, b1 = sb_u + co1, b2 = sb_u + co2, b3 = sb_u + co3;
;     {
;       bf16x8 p0, p1, q0, q1, u0, u1, w0, w1;
;       asm volatile(
;         "ds_read_b128 %4, %12\n\tds_read_b128 %5, %12 offset:4096\n\tds_read_b128 %6, %16\n\tds_read_b128 %7, %16 offset:4096\n\t"
;         "ds_read_b128 %8, %13\n\tds_read_b128 %9, %13 offset:4096\n\tds_read_b128 %10, %17\n\tds_read_b128 %11, %17 offset:4096\n\t"
;         "s_waitcnt lgkmcnt(4)\n\t"
;         "v_mfma_f32_32x32x16_bf16 %0, %4, %6, %0\n\tv_mfma_f32_32x32x16_bf16 %1, %4, %7, %1\n\tv_mfma_f32_32x32x16_bf16 %2, %5, %6, %2\n\tv_mfma_f32_32x32x16_bf16 %3, %5, %7, %3\n\t"
;         "ds_read_b128 %4, %14\n\tds_read_b128 %5, %14 offset:4096\n\tds_read_b128 %6, %18\n\tds_read_b128 %7, %18 offset:4096\n\t"
;         "s_waitcnt lgkmcnt(4)\n\t"
;         "v_mfma_f32_32x32x16_bf16 %0, %8, %10, %0\n\tv_mfma_f32_32x32x16_bf16 %1, %8, %11, %1\n\tv_mfma_f32_32x32x16_bf16 %2, %9, %10, %2\n\tv_mfma_f32_32x32x16_bf16 %3, %9, %11, %3\n\t"
;         "ds_read_b128 %8, %15\n\tds_read_b128 %9, %15 offset:4096\n\tds_read_b128 %10, %19\n\tds_read_b128 %11, %19 offset:4096\n\t"
;         "s_waitcnt lgkmcnt(4)\n\t"
;         "v_mfma_f32_32x32x16_bf16 %0, %4, %6, %0\n\tv_mfma_f32_32x32x16_bf16 %1, %4, %7, %1\n\tv_mfma_f32_32x32x16_bf16 %2, %5, %6, %2\n\tv_mfma_f32_32x32x16_bf16 %3, %5, %7, %3\n\t"
;         "s_waitcnt lgkmcnt(0)\n\t"
;         "v_mfma_f32_32x32x16_bf16 %0, %8, %10, %0\n\tv_mfma_f32_32x32x16_bf16 %1, %8, %11, %1\n\tv_mfma_f32_32x32x16_bf16 %2, %9, %10, %2\n\tv_mfma_f32_32x32x16_bf16 %3, %9, %11, %3"
;         : "+v"(acc[0][0]), "+v"(acc[0][1]), "+v"(acc[1][0]), "+v"(acc[1][1]),
;           "=&v"(p0), "=&v"(p1), "=&v"(q0), "=&v"(q1), "=&v"(u0), "=&v"(u1), "=&v"(w0), "=&v"(w1)
	ds_read_b128 v[164:167], v76
	ds_read_b128 v[168:171], v76 offset:4096
	ds_read_b128 v[172:175], v80
	ds_read_b128 v[176:179], v80 offset:4096
	v_mfma_f32_32x32x16_bf16 v[48:63], v[180:183], v[218:221], v[48:63]
	s_mov_b32 s14, 0xa5c2700
	s_add_u32 m0, s11, 0x18000
	v_lshl_add_u64 v[160:161], v[74:75], 0, s[14:15]
	global_load_lds_dwordx4 v[160:161], off
	v_mfma_f32_32x32x16_bf16 v[32:47], v[180:183], v[222:225], v[32:47]
	v_mfma_f32_32x32x16_bf16 v[16:31], v[184:187], v[218:221], v[16:31]
	s_add_u32 m0, s11, 0x1a000
	v_lshl_add_u64 v[162:163], v[72:73], 0, s[14:15]
	global_load_lds_dwordx4 v[162:163], off
	v_mfma_f32_32x32x16_bf16 v[0:15], v[184:187], v[222:225], v[0:15]
	ds_read_b128 v[180:183], v77
	ds_read_b128 v[184:187], v77 offset:4096
	ds_read_b128 v[218:221], v81
	ds_read_b128 v[222:225], v81 offset:4096
	s_waitcnt lgkmcnt(4)
	v_mfma_f32_32x32x16_bf16 v[48:63], v[164:167], v[172:175], v[48:63]
	s_add_u32 m0, s11, 0x1c000
	v_lshl_add_u64 v[160:161], v[70:71], 0, s[14:15]
	global_load_lds_dwordx4 v[160:161], off
	v_mfma_f32_32x32x16_bf16 v[32:47], v[164:167], v[176:179], v[32:47]
	v_mfma_f32_32x32x16_bf16 v[16:31], v[168:171], v[172:175], v[16:31]
	s_add_u32 m0, s11, 0x1e000
	v_lshl_add_u64 v[162:163], v[68:69], 0, s[14:15]
	global_load_lds_dwordx4 v[162:163], off
	v_mfma_f32_32x32x16_bf16 v[0:15], v[168:171], v[176:179], v[0:15]
	ds_read_b128 v[164:167], v78
	ds_read_b128 v[168:171], v78 offset:4096
	ds_read_b128 v[172:175], v82
	ds_read_b128 v[176:179], v82 offset:4096
	s_waitcnt lgkmcnt(4)
	v_mfma_f32_32x32x16_bf16 v[48:63], v[180:183], v[218:221], v[48:63]
	s_mov_b32 s14, 0x1b80700
	s_add_u32 m0, s11, 0x20000
	v_lshl_add_u64 v[160:161], v[66:67], 0, s[14:15]
	global_load_lds_dwordx4 v[160:161], off
	v_mfma_f32_32x32x16_bf16 v[32:47], v[180:183], v[222:225], v[32:47]
	v_mfma_f32_32x32x16_bf16 v[16:31], v[184:187], v[218:221], v[16:31]
	s_add_u32 m0, s11, 0x22000
	v_lshl_add_u64 v[162:163], v[64:65], 0, s[14:15]
	global_load_lds_dwordx4 v[162:163], off
	v_mfma_f32_32x32x16_bf16 v[0:15], v[184:187], v[222:225], v[0:15]
	ds_read_b128 v[180:183], v79
	ds_read_b128 v[184:187], v79 offset:4096
	ds_read_b128 v[218:221], v83
	ds_read_b128 v[222:225], v83 offset:4096
	s_waitcnt lgkmcnt(4)
	v_mfma_f32_32x32x16_bf16 v[48:63], v[164:167], v[172:175], v[48:63]
	v_mfma_f32_32x32x16_bf16 v[32:47], v[164:167], v[176:179], v[32:47]
	v_mfma_f32_32x32x16_bf16 v[16:31], v[168:171], v[172:175], v[16:31]
	v_mfma_f32_32x32x16_bf16 v[0:15], v[168:171], v[176:179], v[0:15]
	s_waitcnt vmcnt(6) lgkmcnt(0)
	s_barrier
	ds_read_b128 v[164:167], v76 offset:49152
	ds_read_b128 v[168:171], v76 offset:53248
	ds_read_b128 v[172:175], v80 offset:49152
	ds_read_b128 v[176:179], v80 offset:53248
	v_mfma_f32_32x32x16_bf16 v[48:63], v[180:183], v[218:221], v[48:63]
	s_mov_b32 s14, 0xa5c2780
	s_mov_b32 m0, s11
	v_lshl_add_u64 v[160:161], v[74:75], 0, s[14:15]
	global_load_lds_dwordx4 v[160:161], off
	v_mfma_f32_32x32x16_bf16 v[32:47], v[180:183], v[222:225], v[32:47]
	v_mfma_f32_32x32x16_bf16 v[16:31], v[184:187], v[218:221], v[16:31]
	s_add_u32 m0, s11, 0x2000
	v_lshl_add_u64 v[162:163], v[72:73], 0, s[14:15]
	global_load_lds_dwordx4 v[162:163], off
	v_mfma_f32_32x32x16_bf16 v[0:15], v[184:187], v[222:225], v[0:15]
	ds_read_b128 v[180:183], v77 offset:49152
	ds_read_b128 v[184:187], v77 offset:53248
	ds_read_b128 v[218:221], v81 offset:49152
	ds_read_b128 v[222:225], v81 offset:53248
	s_waitcnt lgkmcnt(4)
	v_mfma_f32_32x32x16_bf16 v[48:63], v[164:167], v[172:175], v[48:63]
	s_add_u32 m0, s11, 0x4000
	v_lshl_add_u64 v[160:161], v[70:71], 0, s[14:15]
	global_load_lds_dwordx4 v[160:161], off
	v_mfma_f32_32x32x16_bf16 v[32:47], v[164:167], v[176:179], v[32:47]
	v_mfma_f32_32x32x16_bf16 v[16:31], v[168:171], v[172:175], v[16:31]
	s_add_u32 m0, s11, 0x6000
	v_lshl_add_u64 v[162:163], v[68:69], 0, s[14:15]
	global_load_lds_dwordx4 v[162:163], off
	v_mfma_f32_32x32x16_bf16 v[0:15], v[168:171], v[176:179], v[0:15]
	ds_read_b128 v[164:167], v78 offset:49152
	ds_read_b128 v[168:171], v78 offset:53248
	ds_read_b128 v[172:175], v82 offset:49152
	ds_read_b128 v[176:179], v82 offset:53248
	s_waitcnt lgkmcnt(4)
	v_mfma_f32_32x32x16_bf16 v[48:63], v[180:183], v[218:221], v[48:63]
	s_mov_b32 s14, 0x1b80780
	s_add_u32 m0, s11, 0x8000
	v_lshl_add_u64 v[160:161], v[66:67], 0, s[14:15]
	global_load_lds_dwordx4 v[160:161], off
	v_mfma_f32_32x32x16_bf16 v[32:47], v[180:183], v[222:225], v[32:47]
	v_mfma_f32_32x32x16_bf16 v[16:31], v[184:187], v[218:221], v[16:31]
	s_add_u32 m0, s11, 0xa000
	v_lshl_add_u64 v[162:163], v[64:65], 0, s[14:15]
	global_load_lds_dwordx4 v[162:163], off
	v_mfma_f32_32x32x16_bf16 v[0:15], v[184:187], v[222:225], v[0:15]
	ds_read_b128 v[180:183], v79 offset:49152
	ds_read_b128 v[184:187], v79 offset:53248
	ds_read_b128 v[218:221], v83 offset:49152
	ds_read_b128 v[222:225], v83 offset:53248
	s_waitcnt lgkmcnt(4)
	v_mfma_f32_32x32x16_bf16 v[48:63], v[164:167], v[172:175], v[48:63]
	v_mfma_f32_32x32x16_bf16 v[32:47], v[164:167], v[176:179], v[32:47]
	v_mfma_f32_32x32x16_bf16 v[16:31], v[168:171], v[172:175], v[16:31]
	v_mfma_f32_32x32x16_bf16 v[0:15], v[168:171], v[176:179], v[0:15]
	s_waitcnt vmcnt(6) lgkmcnt(0)
	s_barrier
;     ...
;   for (int kt = 0; kt < nk; ++kt) {
;     if (kt + 1 < nk) asm volatile("s_waitcnt vmcnt(6)" ::: "memory");
;     else asm volatile("s_waitcnt vmcnt(0)" ::: "memory");
;     __builtin_amdgcn_s_barrier();
;     asm volatile("" ::: "memory");
;     if (kt + 2 < nk) { const int st2 = (st >= 1) ? st - 1 : 2; GEMM_ISSUE(kt + 2, st2); }
;     const char* la = lds + st * STAGE_B;
;     const char* lb = la + 32768;
;     const unsigned sa_u = (unsigned)(size_t)la + arow_u, sb_u = (unsigned)(size_t)lb + brow_u;
;     const unsigned a0 = sa_u + co0, a1 = sa_u + co1, a2 = sa_u + co2, a3 = sa_u + co3;
;     const unsigned b0 = sb_u + co0, b1 = sb_u + co1, b2 = sb_u + co2, b3 = sb_u + co3;
;     {
;       bf16x8 p0, p1, q0, q1, u0, u1, w0, w1;
;       asm volatile(
;         "ds_read_b128 %4, %12\n\tds_read_b128 %5, %12 offset:4096\n\tds_read_b128 %6, %16\n\tds_read_b128 %7, %16 offset:4096\n\t"
;         "ds_read_b128 %8, %13\n\tds_read_b128 %9, %13 offset:4096\n\tds_read_b128 %10, %17\n\tds_read_b128 %11, %17 offset:4096\n\t"
;         "s_waitcnt lgkmcnt(4)\n\t"
;         "v_mfma_f32_32x32x16_bf16 %0, %4, %6, %0\n\tv_mfma_f32_32x32x16_bf16 %1, %4, %7, %1\n\tv_mfma_f32_32x32x16_bf16 %2, %5, %6, %2\n\tv_mfma_f32_32x32x16_bf16 %3, %5, %7, %3\n\t"
;         "ds_read_b128 %4, %14\n\tds_read_b128 %5, %14 offset:4096\n\tds_read_b128 %6, %18\n\tds_read_b128 %7, %18 offset:4096\n\t"
;         "s_waitcnt lgkmcnt(4)\n\t"
;         "v_mfma_f32_32x32x16_bf16 %0, %8, %10, %0\n\tv_mfma_f32_32x32x16_bf16 %1, %8, %11, %1\n\tv_mfma_f32_32x32x16_bf16 %2, %9, %10, %2\n\tv_mfma_f32_32x32x16_bf16 %3, %9, %11, %3\n\t"
;         "ds_read_b128 %8, %15\n\tds_read_b128 %9, %15 offset:4096\n\tds_read_b128 %10, %19\n\tds_read_b128 %11, %19 offset:4096\n\t"
;         "s_waitcnt lgkmcnt(4)\n\t"
;         "v_mfma_f32_32x32x16_bf16 %0, %4, %6, %0\n\tv_mfma_f32_32x32x16_bf16 %1, %4, %7, %1\n\tv_mfma_f32_32x32x16_bf16 %2, %5, %6, %2\n\tv_mfma_f32_32x32x16_bf16 %3, %5, %7, %3\n\t"
;         "s_waitcnt lgkmcnt(0)\n\t"
;         "v_mfma_f32_32x32x16_bf16 %0, %8, %10, %0\n\tv_mfma_f32_32x32x16_bf16 %1, %8, %11, %1\n\tv_mfma_f32_32x32x16_bf16 %2, %9, %10, %2\n\tv_mfma_f32_32x32x16_bf16 %3, %9, %11, %3"
;         : "+v"(acc[0][0]), "+v"(acc[0][1]), "+v"(acc[1][0]), "+v"(acc[1][1]),
;           "=&v"(p0), "=&v"(p1), "=&v"(q0), "=&v"(q1), "=&v"(u0), "=&v"(u1), "=&v"(w0), "=&v"(w1)
	ds_read_b128 v[164:167], v84
	ds_read_b128 v[168:171], v84 offset:4096
	ds_read_b128 v[172:175], v156
	ds_read_b128 v[176:179], v156 offset:4096
	v_mfma_f32_32x32x16_bf16 v[48:63], v[180:183], v[218:221], v[48:63]
	s_mov_b32 s14, 0xa5c2800
	s_add_u32 m0, s11, 0xc000
	v_lshl_add_u64 v[160:161], v[74:75], 0, s[14:15]
	global_load_lds_dwordx4 v[160:161], off
	v_mfma_f32_32x32x16_bf16 v[32:47], v[180:183], v[222:225], v[32:47]
	v_mfma_f32_32x32x16_bf16 v[16:31], v[184:187], v[218:221], v[16:31]
	s_add_u32 m0, s11, 0xe000
	v_lshl_add_u64 v[162:163], v[72:73], 0, s[14:15]
	global_load_lds_dwordx4 v[162:163], off
	v_mfma_f32_32x32x16_bf16 v[0:15], v[184:187], v[222:225], v[0:15]
	ds_read_b128 v[180:183], v85
	ds_read_b128 v[184:187], v85 offset:4096
	ds_read_b128 v[218:221], v157
	ds_read_b128 v[222:225], v157 offset:4096
	s_waitcnt lgkmcnt(4)
	v_mfma_f32_32x32x16_bf16 v[48:63], v[164:167], v[172:175], v[48:63]
	s_add_u32 m0, s11, 0x10000
	v_lshl_add_u64 v[160:161], v[70:71], 0, s[14:15]
	global_load_lds_dwordx4 v[160:161], off
	v_mfma_f32_32x32x16_bf16 v[32:47], v[164:167], v[176:179], v[32:47]
	v_mfma_f32_32x32x16_bf16 v[16:31], v[168:171], v[172:175], v[16:31]
	s_add_u32 m0, s11, 0x12000
	v_lshl_add_u64 v[162:163], v[68:69], 0, s[14:15]
	global_load_lds_dwordx4 v[162:163], off
	v_mfma_f32_32x32x16_bf16 v[0:15], v[168:171], v[176:179], v[0:15]
	ds_read_b128 v[164:167], v86
	ds_read_b128 v[168:171], v86 offset:4096
	ds_read_b128 v[172:175], v158
	ds_read_b128 v[176:179], v158 offset:4096
	s_waitcnt lgkmcnt(4)
	v_mfma_f32_32x32x16_bf16 v[48:63], v[180:183], v[218:221], v[48:63]
	s_mov_b32 s14, 0x1b80800
	s_add_u32 m0, s11, 0x14000
	v_lshl_add_u64 v[160:161], v[66:67], 0, s[14:15]
	global_load_lds_dwordx4 v[160:161], off
	v_mfma_f32_32x32x16_bf16 v[32:47], v[180:183], v[222:225], v[32:47]
	v_mfma_f32_32x32x16_bf16 v[16:31], v[184:187], v[218:221], v[16:31]
	s_add_u32 m0, s11, 0x16000
	v_lshl_add_u64 v[162:163], v[64:65], 0, s[14:15]
	global_load_lds_dwordx4 v[162:163], off
	v_mfma_f32_32x32x16_bf16 v[0:15], v[184:187], v[222:225], v[0:15]
	ds_read_b128 v[180:183], v87
	ds_read_b128 v[184:187], v87 offset:4096
	ds_read_b128 v[218:221], v159
	ds_read_b128 v[222:225], v159 offset:4096
	s_waitcnt lgkmcnt(4)
	v_mfma_f32_32x32x16_bf16 v[48:63], v[164:167], v[172:175], v[48:63]
	v_mfma_f32_32x32x16_bf16 v[32:47], v[164:167], v[176:179], v[32:47]
	v_mfma_f32_32x32x16_bf16 v[16:31], v[168:171], v[172:175], v[16:31]
	v_mfma_f32_32x32x16_bf16 v[0:15], v[168:171], v[176:179], v[0:15]
	s_waitcnt vmcnt(6) lgkmcnt(0)
	s_barrier
	ds_read_b128 v[164:167], v76
	ds_read_b128 v[168:171], v76 offset:4096
	ds_read_b128 v[172:175], v80
	ds_read_b128 v[176:179], v80 offset:4096
	v_mfma_f32_32x32x16_bf16 v[48:63], v[180:183], v[218:221], v[48:63]
	s_mov_b32 s14, 0xa5c2880
	s_add_u32 m0, s11, 0x18000
	v_lshl_add_u64 v[160:161], v[74:75], 0, s[14:15]
	global_load_lds_dwordx4 v[160:161], off
	v_mfma_f32_32x32x16_bf16 v[32:47], v[180:183], v[222:225], v[32:47]
	v_mfma_f32_32x32x16_bf16 v[16:31], v[184:187], v[218:221], v[16:31]
	s_add_u32 m0, s11, 0x1a000
	v_lshl_add_u64 v[162:163], v[72:73], 0, s[14:15]
	global_load_lds_dwordx4 v[162:163], off
	v_mfma_f32_32x32x16_bf16 v[0:15], v[184:187], v[222:225], v[0:15]
	ds_read_b128 v[180:183], v77
	ds_read_b128 v[184:187], v77 offset:4096
	ds_read_b128 v[218:221], v81
	ds_read_b128 v[222:225], v81 offset:4096
	s_waitcnt lgkmcnt(4)
	v_mfma_f32_32x32x16_bf16 v[48:63], v[164:167], v[172:175], v[48:63]
	s_add_u32 m0, s11, 0x1c000
	v_lshl_add_u64 v[160:161], v[70:71], 0, s[14:15]
	global_load_lds_dwordx4 v[160:161], off
	v_mfma_f32_32x32x16_bf16 v[32:47], v[164:167], v[176:179], v[32:47]
	v_mfma_f32_32x32x16_bf16 v[16:31], v[168:171], v[172:175], v[16:31]
	s_add_u32 m0, s11, 0x1e000
	v_lshl_add_u64 v[162:163], v[68:69], 0, s[14:15]
	global_load_lds_dwordx4 v[162:163], off
	v_mfma_f32_32x32x16_bf16 v[0:15], v[168:171], v[176:179], v[0:15]
	ds_read_b128 v[164:167], v78
	ds_read_b128 v[168:171], v78 offset:4096
	ds_read_b128 v[172:175], v82
	ds_read_b128 v[176:179], v82 offset:4096
	s_waitcnt lgkmcnt(4)
	v_mfma_f32_32x32x16_bf16 v[48:63], v[180:183], v[218:221], v[48:63]
	s_mov_b32 s14, 0x1b80880
	s_add_u32 m0, s11, 0x20000
	v_lshl_add_u64 v[160:161], v[66:67], 0, s[14:15]
	global_load_lds_dwordx4 v[160:161], off
	v_mfma_f32_32x32x16_bf16 v[32:47], v[180:183], v[222:225], v[32:47]
	v_mfma_f32_32x32x16_bf16 v[16:31], v[184:187], v[218:221], v[16:31]
	s_add_u32 m0, s11, 0x22000
	v_lshl_add_u64 v[162:163], v[64:65], 0, s[14:15]
	global_load_lds_dwordx4 v[162:163], off
	v_mfma_f32_32x32x16_bf16 v[0:15], v[184:187], v[222:225], v[0:15]
	ds_read_b128 v[180:183], v79
	ds_read_b128 v[184:187], v79 offset:4096
	ds_read_b128 v[218:221], v83
	ds_read_b128 v[222:225], v83 offset:4096
	s_waitcnt lgkmcnt(4)
	v_mfma_f32_32x32x16_bf16 v[48:63], v[164:167], v[172:175], v[48:63]
	v_mfma_f32_32x32x16_bf16 v[32:47], v[164:167], v[176:179], v[32:47]
	v_mfma_f32_32x32x16_bf16 v[16:31], v[168:171], v[172:175], v[16:31]
	v_mfma_f32_32x32x16_bf16 v[0:15], v[168:171], v[176:179], v[0:15]
	s_waitcnt vmcnt(6) lgkmcnt(0)
	s_barrier
;     ...
;   for (int kt = 0; kt < nk; ++kt) {
;     if (kt + 1 < nk) asm volatile("s_waitcnt vmcnt(6)" ::: "memory");
;     else asm volatile("s_waitcnt vmcnt(0)" ::: "memory");
;     __builtin_amdgcn_s_barrier();
;     asm volatile("" ::: "memory");
;     if (kt + 2 < nk) { const int st2 = (st >= 1) ? st - 1 : 2; GEMM_ISSUE(kt + 2, st2); }
;     const char* la = lds + st * STAGE_B;
;     const char* lb = la + 32768;
;     const unsigned sa_u = (unsigned)(size_t)la + arow_u, sb_u = (unsigned)(size_t)lb + brow_u;
;     const unsigned a0 = sa_u + co0, a1 = sa_u + co1, a2 = sa_u + co2, a3 = sa_u + co3;
;     const unsigned b0 = sb_u + co0, b1 = sb_u + co1, b2 = sb_u + co2, b3 = sb_u + co3;
;     {
;       bf16x8 p0, p1, q0, q1, u0, u1, w0, w1;
;       asm volatile(
;         "ds_read_b128 %4, %12\n\tds_read_b128 %5, %12 offset:4096\n\tds_read_b128 %6, %16\n\tds_read_b128 %7, %16 offset:4096\n\t"
;         "ds_read_b128 %8, %13\n\tds_read_b128 %9, %13 offset:4096\n\tds_read_b128 %10, %17\n\tds_read_b128 %11, %17 offset:4096\n\t"
;         "s_waitcnt lgkmcnt(4)\n\t"
;         "v_mfma_f32_32x32x16_bf16 %0, %4, %6, %0\n\tv_mfma_f32_32x32x16_bf16 %1, %4, %7, %1\n\tv_mfma_f32_32x32x16_bf16 %2, %5, %6, %2\n\tv_mfma_f32_32x32x16_bf16 %3, %5, %7, %3\n\t"
;         "ds_read_b128 %4, %14\n\tds_read_b128 %5, %14 offset:4096\n\tds_read_b128 %6, %18\n\tds_read_b128 %7, %18 offset:4096\n\t"
;         "s_waitcnt lgkmcnt(4)\n\t"
;         "v_mfma_f32_32x32x16_bf16 %0, %8, %10, %0\n\tv_mfma_f32_32x32x16_bf16 %1, %8, %11, %1\n\tv_mfma_f32_32x32x16_bf16 %2, %9, %10, %2\n\tv_mfma_f32_32x32x16_bf16 %3, %9, %11, %3\n\t"
;         "ds_read_b128 %8, %15\n\tds_read_b128 %9, %15 offset:4096\n\tds_read_b128 %10, %19\n\tds_read_b128 %11, %19 offset:4096\n\t"
;         "s_waitcnt lgkmcnt(4)\n\t"
;         "v_mfma_f32_32x32x16_bf16 %0, %4, %6, %0\n\tv_mfma_f32_32x32x16_bf16 %1, %4, %7, %1\n\tv_mfma_f32_32x32x16_bf16 %2, %5, %6, %2\n\tv_mfma_f32_32x32x16_bf16 %3, %5, %7, %3\n\t"
;         "s_waitcnt lgkmcnt(0)\n\t"
;         "v_mfma_f32_32x32x16_bf16 %0, %8, %10, %0\n\tv_mfma_f32_32x32x16_bf16 %1, %8, %11, %1\n\tv_mfma_f32_32x32x16_bf16 %2, %9, %10, %2\n\tv_mfma_f32_32x32x16_bf16 %3, %9, %11, %3"
;         : "+v"(acc[0][0]), "+v"(acc[0][1]), "+v"(acc[1][0]), "+v"(acc[1][1]),
;           "=&v"(p0), "=&v"(p1), "=&v"(q0), "=&v"(q1), "=&v"(u0), "=&v"(u1), "=&v"(w0), "=&v"(w1)
	ds_read_b128 v[164:167], v76 offset:49152
	ds_read_b128 v[168:171], v76 offset:53248
	ds_read_b128 v[172:175], v80 offset:49152
	ds_read_b128 v[176:179], v80 offset:53248
	v_mfma_f32_32x32x16_bf16 v[48:63], v[180:183], v[218:221], v[48:63]
	s_mov_b32 s14, 0xa5c2900
	s_mov_b32 m0, s11
	v_lshl_add_u64 v[160:161], v[74:75], 0, s[14:15]
	global_load_lds_dwordx4 v[160:161], off
	v_mfma_f32_32x32x16_bf16 v[32:47], v[180:183], v[222:225], v[32:47]
	v_mfma_f32_32x32x16_bf16 v[16:31], v[184:187], v[218:221], v[16:31]
	s_add_u32 m0, s11, 0x2000
	v_lshl_add_u64 v[162:163], v[72:73], 0, s[14:15]
	global_load_lds_dwordx4 v[162:163], off
	v_mfma_f32_32x32x16_bf16 v[0:15], v[184:187], v[222:225], v[0:15]
	ds_read_b128 v[180:183], v77 offset:49152
	ds_read_b128 v[184:187], v77 offset:53248
	ds_read_b128 v[218:221], v81 offset:49152
	ds_read_b128 v[222:225], v81 offset:53248
	s_waitcnt lgkmcnt(4)
	v_mfma_f32_32x32x16_bf16 v[48:63], v[164:167], v[172:175], v[48:63]
	s_add_u32 m0, s11, 0x4000
	v_lshl_add_u64 v[160:161], v[70:71], 0, s[14:15]
	global_load_lds_dwordx4 v[160:161], off
	v_mfma_f32_32x32x16_bf16 v[32:47], v[164:167], v[176:179], v[32:47]
	v_mfma_f32_32x32x16_bf16 v[16:31], v[168:171], v[172:175], v[16:31]
	s_add_u32 m0, s11, 0x6000
	v_lshl_add_u64 v[162:163], v[68:69], 0, s[14:15]
	global_load_lds_dwordx4 v[162:163], off
	v_mfma_f32_32x32x16_bf16 v[0:15], v[168:171], v[176:179], v[0:15]
	ds_read_b128 v[164:167], v78 offset:49152
	ds_read_b128 v[168:171], v78 offset:53248
	ds_read_b128 v[172:175], v82 offset:49152
	ds_read_b128 v[176:179], v82 offset:53248
	s_waitcnt lgkmcnt(4)
	v_mfma_f32_32x32x16_bf16 v[48:63], v[180:183], v[218:221], v[48:63]
	s_mov_b32 s14, 0x1b80900
	s_add_u32 m0, s11, 0x8000
	v_lshl_add_u64 v[160:161], v[66:67], 0, s[14:15]
	global_load_lds_dwordx4 v[160:161], off
	v_mfma_f32_32x32x16_bf16 v[32:47], v[180:183], v[222:225], v[32:47]
	v_mfma_f32_32x32x16_bf16 v[16:31], v[184:187], v[218:221], v[16:31]
	s_add_u32 m0, s11, 0xa000
	v_lshl_add_u64 v[162:163], v[64:65], 0, s[14:15]
	global_load_lds_dwordx4 v[162:163], off
	v_mfma_f32_32x32x16_bf16 v[0:15], v[184:187], v[222:225], v[0:15]
	ds_read_b128 v[180:183], v79 offset:49152
	ds_read_b128 v[184:187], v79 offset:53248
	ds_read_b128 v[218:221], v83 offset:49152
	ds_read_b128 v[222:225], v83 offset:53248
	s_waitcnt lgkmcnt(4)
	v_mfma_f32_32x32x16_bf16 v[48:63], v[164:167], v[172:175], v[48:63]
	v_mfma_f32_32x32x16_bf16 v[32:47], v[164:167], v[176:179], v[32:47]
	v_mfma_f32_32x32x16_bf16 v[16:31], v[168:171], v[172:175], v[16:31]
	v_mfma_f32_32x32x16_bf16 v[0:15], v[168:171], v[176:179], v[0:15]
	s_waitcnt vmcnt(6) lgkmcnt(0)
	s_barrier
	ds_read_b128 v[164:167], v84
	ds_read_b128 v[168:171], v84 offset:4096
	ds_read_b128 v[172:175], v156
	ds_read_b128 v[176:179], v156 offset:4096
	v_mfma_f32_32x32x16_bf16 v[48:63], v[180:183], v[218:221], v[48:63]
	s_mov_b32 s14, 0xa5c2980
	s_add_u32 m0, s11, 0xc000
	v_lshl_add_u64 v[160:161], v[74:75], 0, s[14:15]
	global_load_lds_dwordx4 v[160:161], off
	v_mfma_f32_32x32x16_bf16 v[32:47], v[180:183], v[222:225], v[32:47]
	v_mfma_f32_32x32x16_bf16 v[16:31], v[184:187], v[218:221], v[16:31]
	s_add_u32 m0, s11, 0xe000
	v_lshl_add_u64 v[162:163], v[72:73], 0, s[14:15]
	global_load_lds_dwordx4 v[162:163], off
	v_mfma_f32_32x32x16_bf16 v[0:15], v[184:187], v[222:225], v[0:15]
	ds_read_b128 v[180:183], v85
	ds_read_b128 v[184:187], v85 offset:4096
	ds_read_b128 v[218:221], v157
	ds_read_b128 v[222:225], v157 offset:4096
	s_waitcnt lgkmcnt(4)
	v_mfma_f32_32x32x16_bf16 v[48:63], v[164:167], v[172:175], v[48:63]
	s_add_u32 m0, s11, 0x10000
	v_lshl_add_u64 v[160:161], v[70:71], 0, s[14:15]
	global_load_lds_dwordx4 v[160:161], off
	v_mfma_f32_32x32x16_bf16 v[32:47], v[164:167], v[176:179], v[32:47]
	v_mfma_f32_32x32x16_bf16 v[16:31], v[168:171], v[172:175], v[16:31]
	s_add_u32 m0, s11, 0x12000
	v_lshl_add_u64 v[162:163], v[68:69], 0, s[14:15]
	global_load_lds_dwordx4 v[162:163], off
	v_mfma_f32_32x32x16_bf16 v[0:15], v[168:171], v[176:179], v[0:15]
	ds_read_b128 v[164:167], v86
	ds_read_b128 v[168:171], v86 offset:4096
	ds_read_b128 v[172:175], v158
	ds_read_b128 v[176:179], v158 offset:4096
	s_waitcnt lgkmcnt(4)
	v_mfma_f32_32x32x16_bf16 v[48:63], v[180:183], v[218:221], v[48:63]
	s_mov_b32 s14, 0x1b80980
	s_add_u32 m0, s11, 0x14000
	v_lshl_add_u64 v[160:161], v[66:67], 0, s[14:15]
	global_load_lds_dwordx4 v[160:161], off
	v_mfma_f32_32x32x16_bf16 v[32:47], v[180:183], v[222:225], v[32:47]
	v_mfma_f32_32x32x16_bf16 v[16:31], v[184:187], v[218:221], v[16:31]
	s_add_u32 m0, s11, 0x16000
	v_lshl_add_u64 v[162:163], v[64:65], 0, s[14:15]
	global_load_lds_dwordx4 v[162:163], off
	v_mfma_f32_32x32x16_bf16 v[0:15], v[184:187], v[222:225], v[0:15]
	ds_read_b128 v[180:183], v87
	ds_read_b128 v[184:187], v87 offset:4096
	ds_read_b128 v[218:221], v159
	ds_read_b128 v[222:225], v159 offset:4096
	s_waitcnt lgkmcnt(4)
	v_mfma_f32_32x32x16_bf16 v[48:63], v[164:167], v[172:175], v[48:63]
	v_mfma_f32_32x32x16_bf16 v[32:47], v[164:167], v[176:179], v[32:47]
	v_mfma_f32_32x32x16_bf16 v[16:31], v[168:171], v[172:175], v[16:31]
	v_mfma_f32_32x32x16_bf16 v[0:15], v[168:171], v[176:179], v[0:15]
	s_waitcnt vmcnt(6) lgkmcnt(0)
	s_barrier
;     ...
;   for (int kt = 0; kt < nk; ++kt) {
;     if (kt + 1 < nk) asm volatile("s_waitcnt vmcnt(6)" ::: "memory");
;     else asm volatile("s_waitcnt vmcnt(0)" ::: "memory");
;     __builtin_amdgcn_s_barrier();
;     asm volatile("" ::: "memory");
;     if (kt + 2 < nk) { const int st2 = (st >= 1) ? st - 1 : 2; GEMM_ISSUE(kt + 2, st2); }
;     const char* la = lds + st * STAGE_B;
;     const char* lb = la + 32768;
;     const unsigned sa_u = (unsigned)(size_t)la + arow_u, sb_u = (unsigned)(size_t)lb + brow_u;
;     const unsigned a0 = sa_u + co0, a1 = sa_u + co1, a2 = sa_u + co2, a3 = sa_u + co3;
;     const unsigned b0 = sb_u + co0, b1 = sb_u + co1, b2 = sb_u + co2, b3 = sb_u + co3;
;     {
;       bf16x8 p0, p1, q0, q1, u0, u1, w0, w1;
;       asm volatile(
;         "ds_read_b128 %4, %12\n\tds_read_b128 %5, %12 offset:4096\n\tds_read_b128 %6, %16\n\tds_read_b128 %7, %16 offset:4096\n\t"
;         "ds_read_b128 %8, %13\n\tds_read_b128 %9, %13 offset:4096\n\tds_read_b128 %10, %17\n\tds_read_b128 %11, %17 offset:4096\n\t"
;         "s_waitcnt lgkmcnt(4)\n\t"
;         "v_mfma_f32_32x32x16_bf16 %0, %4, %6, %0\n\tv_mfma_f32_32x32x16_bf16 %1, %4, %7, %1\n\tv_mfma_f32_32x32x16_bf16 %2, %5, %6, %2\n\tv_mfma_f32_32x32x16_bf16 %3, %5, %7, %3\n\t"
;         "ds_read_b128 %4, %14\n\tds_read_b128 %5, %14 offset:4096\n\tds_read_b128 %6, %18\n\tds_read_b128 %7, %18 offset:4096\n\t"
;         "s_waitcnt lgkmcnt(4)\n\t"
;         "v_mfma_f32_32x32x16_bf16 %0, %8, %10, %0\n\tv_mfma_f32_32x32x16_bf16 %1, %8, %11, %1\n\tv_mfma_f32_32x32x16_bf16 %2, %9, %10, %2\n\tv_mfma_f32_32x32x16_bf16 %3, %9, %11, %3\n\t"
;         "ds_read_b128 %8, %15\n\tds_read_b128 %9, %15 offset:4096\n\tds_read_b128 %10, %19\n\tds_read_b128 %11, %19 offset:4096\n\t"
;         "s_waitcnt lgkmcnt(4)\n\t"
;         "v_mfma_f32_32x32x16_bf16 %0, %4, %6, %0\n\tv_mfma_f32_32x32x16_bf16 %1, %4, %7, %1\n\tv_mfma_f32_32x32x16_bf16 %2, %5, %6, %2\n\tv_mfma_f32_32x32x16_bf16 %3, %5, %7, %3\n\t"
;         "s_waitcnt lgkmcnt(0)\n\t"
;         "v_mfma_f32_32x32x16_bf16 %0, %8, %10, %0\n\tv_mfma_f32_32x32x16_bf16 %1, %8, %11, %1\n\tv_mfma_f32_32x32x16_bf16 %2, %9, %10, %2\n\tv_mfma_f32_32x32x16_bf16 %3, %9, %11, %3"
;         : "+v"(acc[0][0]), "+v"(acc[0][1]), "+v"(acc[1][0]), "+v"(acc[1][1]),
;           "=&v"(p0), "=&v"(p1), "=&v"(q0), "=&v"(q1), "=&v"(u0), "=&v"(u1), "=&v"(w0), "=&v"(w1)
	ds_read_b128 v[164:167], v76
	ds_read_b128 v[168:171], v76 offset:4096
	ds_read_b128 v[172:175], v80
	ds_read_b128 v[176:179], v80 offset:4096
	v_mfma_f32_32x32x16_bf16 v[48:63], v[180:183], v[218:221], v[48:63]
	s_mov_b32 s14, 0xa5c2a00
	s_add_u32 m0, s11, 0x18000
	v_lshl_add_u64 v[160:161], v[74:75], 0, s[14:15]
	global_load_lds_dwordx4 v[160:161], off
	v_mfma_f32_32x32x16_bf16 v[32:47], v[180:183], v[222:225], v[32:47]
	v_mfma_f32_32x32x16_bf16 v[16:31], v[184:187], v[218:221], v[16:31]
	s_add_u32 m0, s11, 0x1a000
	v_lshl_add_u64 v[162:163], v[72:73], 0, s[14:15]
	global_load_lds_dwordx4 v[162:163], off
	v_mfma_f32_32x32x16_bf16 v[0:15], v[184:187], v[222:225], v[0:15]
	ds_read_b128 v[180:183], v77
	ds_read_b128 v[184:187], v77 offset:4096
	ds_read_b128 v[218:221], v81
	ds_read_b128 v[222:225], v81 offset:4096
	s_waitcnt lgkmcnt(4)
	v_mfma_f32_32x32x16_bf16 v[48:63], v[164:167], v[172:175], v[48:63]
	s_add_u32 m0, s11, 0x1c000
	v_lshl_add_u64 v[160:161], v[70:71], 0, s[14:15]
	global_load_lds_dwordx4 v[160:161], off
	v_mfma_f32_32x32x16_bf16 v[32:47], v[164:167], v[176:179], v[32:47]
	v_mfma_f32_32x32x16_bf16 v[16:31], v[168:171], v[172:175], v[16:31]
	s_add_u32 m0, s11, 0x1e000
	v_lshl_add_u64 v[162:163], v[68:69], 0, s[14:15]
	global_load_lds_dwordx4 v[162:163], off
	v_mfma_f32_32x32x16_bf16 v[0:15], v[168:171], v[176:179], v[0:15]
	ds_read_b128 v[164:167], v78
	ds_read_b128 v[168:171], v78 offset:4096
	ds_read_b128 v[172:175], v82
	ds_read_b128 v[176:179], v82 offset:4096
	s_waitcnt lgkmcnt(4)
	v_mfma_f32_32x32x16_bf16 v[48:63], v[180:183], v[218:221], v[48:63]
	s_mov_b32 s14, 0x1b80a00
	s_add_u32 m0, s11, 0x20000
	v_lshl_add_u64 v[160:161], v[66:67], 0, s[14:15]
	global_load_lds_dwordx4 v[160:161], off
	v_mfma_f32_32x32x16_bf16 v[32:47], v[180:183], v[222:225], v[32:47]
	v_mfma_f32_32x32x16_bf16 v[16:31], v[184:187], v[218:221], v[16:31]
	s_add_u32 m0, s11, 0x22000
	v_lshl_add_u64 v[162:163], v[64:65], 0, s[14:15]
	global_load_lds_dwordx4 v[162:163], off
	v_mfma_f32_32x32x16_bf16 v[0:15], v[184:187], v[222:225], v[0:15]
	ds_read_b128 v[180:183], v79
	ds_read_b128 v[184:187], v79 offset:4096
	ds_read_b128 v[218:221], v83
	ds_read_b128 v[222:225], v83 offset:4096
	s_waitcnt lgkmcnt(4)
	v_mfma_f32_32x32x16_bf16 v[48:63], v[164:167], v[172:175], v[48:63]
	v_mfma_f32_32x32x16_bf16 v[32:47], v[164:167], v[176:179], v[32:47]
	v_mfma_f32_32x32x16_bf16 v[16:31], v[168:171], v[172:175], v[16:31]
	v_mfma_f32_32x32x16_bf16 v[0:15], v[168:171], v[176:179], v[0:15]
	s_waitcnt vmcnt(6) lgkmcnt(0)
	s_barrier
	ds_read_b128 v[164:167], v76 offset:49152
	ds_read_b128 v[168:171], v76 offset:53248
	ds_read_b128 v[172:175], v80 offset:49152
	ds_read_b128 v[176:179], v80 offset:53248
	v_mfma_f32_32x32x16_bf16 v[48:63], v[180:183], v[218:221], v[48:63]
	s_mov_b32 s14, 0xa5c2a80
	s_mov_b32 m0, s11
	v_lshl_add_u64 v[160:161], v[74:75], 0, s[14:15]
	global_load_lds_dwordx4 v[160:161], off
	v_mfma_f32_32x32x16_bf16 v[32:47], v[180:183], v[222:225], v[32:47]
	v_mfma_f32_32x32x16_bf16 v[16:31], v[184:187], v[218:221], v[16:31]
	s_add_u32 m0, s11, 0x2000
	v_lshl_add_u64 v[162:163], v[72:73], 0, s[14:15]
	global_load_lds_dwordx4 v[162:163], off
	v_mfma_f32_32x32x16_bf16 v[0:15], v[184:187], v[222:225], v[0:15]
	ds_read_b128 v[180:183], v77 offset:49152
	ds_read_b128 v[184:187], v77 offset:53248
	ds_read_b128 v[218:221], v81 offset:49152
	ds_read_b128 v[222:225], v81 offset:53248
	s_waitcnt lgkmcnt(4)
	v_mfma_f32_32x32x16_bf16 v[48:63], v[164:167], v[172:175], v[48:63]
	s_add_u32 m0, s11, 0x4000
	v_lshl_add_u64 v[160:161], v[70:71], 0, s[14:15]
	global_load_lds_dwordx4 v[160:161], off
	v_mfma_f32_32x32x16_bf16 v[32:47], v[164:167], v[176:179], v[32:47]
	v_mfma_f32_32x32x16_bf16 v[16:31], v[168:171], v[172:175], v[16:31]
	s_add_u32 m0, s11, 0x6000
	v_lshl_add_u64 v[162:163], v[68:69], 0, s[14:15]
	global_load_lds_dwordx4 v[162:163], off
	v_mfma_f32_32x32x16_bf16 v[0:15], v[168:171], v[176:179], v[0:15]
	ds_read_b128 v[164:167], v78 offset:49152
	ds_read_b128 v[168:171], v78 offset:53248
	ds_read_b128 v[172:175], v82 offset:49152
	ds_read_b128 v[176:179], v82 offset:53248
	s_waitcnt lgkmcnt(4)
	v_mfma_f32_32x32x16_bf16 v[48:63], v[180:183], v[218:221], v[48:63]
	s_mov_b32 s14, 0x1b80a80
	s_add_u32 m0, s11, 0x8000
	v_lshl_add_u64 v[160:161], v[66:67], 0, s[14:15]
	global_load_lds_dwordx4 v[160:161], off
	v_mfma_f32_32x32x16_bf16 v[32:47], v[180:183], v[222:225], v[32:47]
	v_mfma_f32_32x32x16_bf16 v[16:31], v[184:187], v[218:221], v[16:31]
	s_add_u32 m0, s11, 0xa000
	v_lshl_add_u64 v[162:163], v[64:65], 0, s[14:15]
	global_load_lds_dwordx4 v[162:163], off
	v_mfma_f32_32x32x16_bf16 v[0:15], v[184:187], v[222:225], v[0:15]
	ds_read_b128 v[180:183], v79 offset:49152
	ds_read_b128 v[184:187], v79 offset:53248
	ds_read_b128 v[218:221], v83 offset:49152
	ds_read_b128 v[222:225], v83 offset:53248
	s_waitcnt lgkmcnt(4)
	v_mfma_f32_32x32x16_bf16 v[48:63], v[164:167], v[172:175], v[48:63]
	v_mfma_f32_32x32x16_bf16 v[32:47], v[164:167], v[176:179], v[32:47]
	v_mfma_f32_32x32x16_bf16 v[16:31], v[168:171], v[172:175], v[16:31]
	v_mfma_f32_32x32x16_bf16 v[0:15], v[168:171], v[176:179], v[0:15]
	s_waitcnt vmcnt(6) lgkmcnt(0)
	s_barrier
;     ...
;   for (int kt = 0; kt < nk; ++kt) {
;     if (kt + 1 < nk) asm volatile("s_waitcnt vmcnt(6)" ::: "memory");
;     else asm volatile("s_waitcnt vmcnt(0)" ::: "memory");
;     __builtin_amdgcn_s_barrier();
;     asm volatile("" ::: "memory");
;     if (kt + 2 < nk) { const int st2 = (st >= 1) ? st - 1 : 2; GEMM_ISSUE(kt + 2, st2); }
;     const char* la = lds + st * STAGE_B;
;     const char* lb = la + 32768;
;     const unsigned sa_u = (unsigned)(size_t)la + arow_u, sb_u = (unsigned)(size_t)lb + brow_u;
;     const unsigned a0 = sa_u + co0, a1 = sa_u + co1, a2 = sa_u + co2, a3 = sa_u + co3;
;     const unsigned b0 = sb_u + co0, b1 = sb_u + co1, b2 = sb_u + co2, b3 = sb_u + co3;
;     {
;       bf16x8 p0, p1, q0, q1, u0, u1, w0, w1;
;       asm volatile(
;         "ds_read_b128 %4, %12\n\tds_read_b128 %5, %12 offset:4096\n\tds_read_b128 %6, %16\n\tds_read_b128 %7, %16 offset:4096\n\t"
;         "ds_read_b128 %8, %13\n\tds_read_b128 %9, %13 offset:4096\n\tds_read_b128 %10, %17\n\tds_read_b128 %11, %17 offset:4096\n\t"
;         "s_waitcnt lgkmcnt(4)\n\t"
;         "v_mfma_f32_32x32x16_bf16 %0, %4, %6, %0\n\tv_mfma_f32_32x32x16_bf16 %1, %4, %7, %1\n\tv_mfma_f32_32x32x16_bf16 %2, %5, %6, %2\n\tv_mfma_f32_32x32x16_bf16 %3, %5, %7, %3\n\t"
;         "ds_read_b128 %4, %14\n\tds_read_b128 %5, %14 offset:4096\n\tds_read_b128 %6, %18\n\tds_read_b128 %7, %18 offset:4096\n\t"
;         "s_waitcnt lgkmcnt(4)\n\t"
;         "v_mfma_f32_32x32x16_bf16 %0, %8, %10, %0\n\tv_mfma_f32_32x32x16_bf16 %1, %8, %11, %1\n\tv_mfma_f32_32x32x16_bf16 %2, %9, %10, %2\n\tv_mfma_f32_32x32x16_bf16 %3, %9, %11, %3\n\t"
;         "ds_read_b128 %8, %15\n\tds_read_b128 %9, %15 offset:4096\n\tds_read_b128 %10, %19\n\tds_read_b128 %11, %19 offset:4096\n\t"
;         "s_waitcnt lgkmcnt(4)\n\t"
;         "v_mfma_f32_32x32x16_bf16 %0, %4, %6, %0\n\tv_mfma_f32_32x32x16_bf16 %1, %4, %7, %1\n\tv_mfma_f32_32x32x16_bf16 %2, %5, %6, %2\n\tv_mfma_f32_32x32x16_bf16 %3, %5, %7, %3\n\t"
;         "s_waitcnt lgkmcnt(0)\n\t"
;         "v_mfma_f32_32x32x16_bf16 %0, %8, %10, %0\n\tv_mfma_f32_32x32x16_bf16 %1, %8, %11, %1\n\tv_mfma_f32_32x32x16_bf16 %2, %9, %10, %2\n\tv_mfma_f32_32x32x16_bf16 %3, %9, %11, %3"
;         : "+v"(acc[0][0]), "+v"(acc[0][1]), "+v"(acc[1][0]), "+v"(acc[1][1]),
;           "=&v"(p0), "=&v"(p1), "=&v"(q0), "=&v"(q1), "=&v"(u0), "=&v"(u1), "=&v"(w0), "=&v"(w1)
	ds_read_b128 v[164:167], v84
	ds_read_b128 v[168:171], v84 offset:4096
	ds_read_b128 v[172:175], v156
	ds_read_b128 v[176:179], v156 offset:4096
	v_mfma_f32_32x32x16_bf16 v[48:63], v[180:183], v[218:221], v[48:63]
	s_mov_b32 s14, 0xa5c2b00
	s_add_u32 m0, s11, 0xc000
	v_lshl_add_u64 v[160:161], v[74:75], 0, s[14:15]
	global_load_lds_dwordx4 v[160:161], off
	v_mfma_f32_32x32x16_bf16 v[32:47], v[180:183], v[222:225], v[32:47]
	v_mfma_f32_32x32x16_bf16 v[16:31], v[184:187], v[218:221], v[16:31]
	s_add_u32 m0, s11, 0xe000
	v_lshl_add_u64 v[162:163], v[72:73], 0, s[14:15]
	global_load_lds_dwordx4 v[162:163], off
	v_mfma_f32_32x32x16_bf16 v[0:15], v[184:187], v[222:225], v[0:15]
	ds_read_b128 v[180:183], v85
	ds_read_b128 v[184:187], v85 offset:4096
	ds_read_b128 v[218:221], v157
	ds_read_b128 v[222:225], v157 offset:4096
	s_waitcnt lgkmcnt(4)
	v_mfma_f32_32x32x16_bf16 v[48:63], v[164:167], v[172:175], v[48:63]
	s_add_u32 m0, s11, 0x10000
	v_lshl_add_u64 v[160:161], v[70:71], 0, s[14:15]
	global_load_lds_dwordx4 v[160:161], off
	v_mfma_f32_32x32x16_bf16 v[32:47], v[164:167], v[176:179], v[32:47]
	v_mfma_f32_32x32x16_bf16 v[16:31], v[168:171], v[172:175], v[16:31]
	s_add_u32 m0, s11, 0x12000
	v_lshl_add_u64 v[162:163], v[68:69], 0, s[14:15]
	global_load_lds_dwordx4 v[162:163], off
	v_mfma_f32_32x32x16_bf16 v[0:15], v[168:171], v[176:179], v[0:15]
	ds_read_b128 v[164:167], v86
	ds_read_b128 v[168:171], v86 offset:4096
	ds_read_b128 v[172:175], v158
	ds_read_b128 v[176:179], v158 offset:4096
	s_waitcnt lgkmcnt(4)
	v_mfma_f32_32x32x16_bf16 v[48:63], v[180:183], v[218:221], v[48:63]
	s_mov_b32 s14, 0x1b80b00
	s_add_u32 m0, s11, 0x14000
	v_lshl_add_u64 v[160:161], v[66:67], 0, s[14:15]
	global_load_lds_dwordx4 v[160:161], off
	v_mfma_f32_32x32x16_bf16 v[32:47], v[180:183], v[222:225], v[32:47]
	v_mfma_f32_32x32x16_bf16 v[16:31], v[184:187], v[218:221], v[16:31]
	s_add_u32 m0, s11, 0x16000
	v_lshl_add_u64 v[162:163], v[64:65], 0, s[14:15]
	global_load_lds_dwordx4 v[162:163], off
	v_mfma_f32_32x32x16_bf16 v[0:15], v[184:187], v[222:225], v[0:15]
	ds_read_b128 v[180:183], v87
	ds_read_b128 v[184:187], v87 offset:4096
	ds_read_b128 v[218:221], v159
	ds_read_b128 v[222:225], v159 offset:4096
	s_waitcnt lgkmcnt(4)
	v_mfma_f32_32x32x16_bf16 v[48:63], v[164:167], v[172:175], v[48:63]
	v_mfma_f32_32x32x16_bf16 v[32:47], v[164:167], v[176:179], v[32:47]
	v_mfma_f32_32x32x16_bf16 v[16:31], v[168:171], v[172:175], v[16:31]
	v_mfma_f32_32x32x16_bf16 v[0:15], v[168:171], v[176:179], v[0:15]
	s_waitcnt vmcnt(6) lgkmcnt(0)
	s_barrier
	ds_read_b128 v[164:167], v76
	ds_read_b128 v[168:171], v76 offset:4096
	ds_read_b128 v[172:175], v80
	ds_read_b128 v[176:179], v80 offset:4096
	v_mfma_f32_32x32x16_bf16 v[48:63], v[180:183], v[218:221], v[48:63]
	s_mov_b32 s14, 0xa5c2b80
	s_add_u32 m0, s11, 0x18000
	v_lshl_add_u64 v[160:161], v[74:75], 0, s[14:15]
	global_load_lds_dwordx4 v[160:161], off
	v_mfma_f32_32x32x16_bf16 v[32:47], v[180:183], v[222:225], v[32:47]
	v_mfma_f32_32x32x16_bf16 v[16:31], v[184:187], v[218:221], v[16:31]
	s_add_u32 m0, s11, 0x1a000
	v_lshl_add_u64 v[162:163], v[72:73], 0, s[14:15]
	global_load_lds_dwordx4 v[162:163], off
	v_mfma_f32_32x32x16_bf16 v[0:15], v[184:187], v[222:225], v[0:15]
	ds_read_b128 v[180:183], v77
	ds_read_b128 v[184:187], v77 offset:4096
	ds_read_b128 v[218:221], v81
	ds_read_b128 v[222:225], v81 offset:4096
	s_waitcnt lgkmcnt(4)
	v_mfma_f32_32x32x16_bf16 v[48:63], v[164:167], v[172:175], v[48:63]
	s_add_u32 m0, s11, 0x1c000
	v_lshl_add_u64 v[160:161], v[70:71], 0, s[14:15]
	global_load_lds_dwordx4 v[160:161], off
	v_mfma_f32_32x32x16_bf16 v[32:47], v[164:167], v[176:179], v[32:47]
	v_mfma_f32_32x32x16_bf16 v[16:31], v[168:171], v[172:175], v[16:31]
	s_add_u32 m0, s11, 0x1e000
	v_lshl_add_u64 v[162:163], v[68:69], 0, s[14:15]
	global_load_lds_dwordx4 v[162:163], off
	v_mfma_f32_32x32x16_bf16 v[0:15], v[168:171], v[176:179], v[0:15]
	ds_read_b128 v[164:167], v78
	ds_read_b128 v[168:171], v78 offset:4096
	ds_read_b128 v[172:175], v82
	ds_read_b128 v[176:179], v82 offset:4096
	s_waitcnt lgkmcnt(4)
	v_mfma_f32_32x32x16_bf16 v[48:63], v[180:183], v[218:221], v[48:63]
	s_mov_b32 s14, 0x1b80b80
	s_add_u32 m0, s11, 0x20000
	v_lshl_add_u64 v[160:161], v[66:67], 0, s[14:15]
	global_load_lds_dwordx4 v[160:161], off
	v_mfma_f32_32x32x16_bf16 v[32:47], v[180:183], v[222:225], v[32:47]
	v_mfma_f32_32x32x16_bf16 v[16:31], v[184:187], v[218:221], v[16:31]
	s_add_u32 m0, s11, 0x22000
	v_lshl_add_u64 v[162:163], v[64:65], 0, s[14:15]
	global_load_lds_dwordx4 v[162:163], off
	v_mfma_f32_32x32x16_bf16 v[0:15], v[184:187], v[222:225], v[0:15]
	ds_read_b128 v[180:183], v79
	ds_read_b128 v[184:187], v79 offset:4096
	ds_read_b128 v[218:221], v83
	ds_read_b128 v[222:225], v83 offset:4096
	s_waitcnt lgkmcnt(4)
	v_mfma_f32_32x32x16_bf16 v[48:63], v[164:167], v[172:175], v[48:63]
	v_mfma_f32_32x32x16_bf16 v[32:47], v[164:167], v[176:179], v[32:47]
	v_mfma_f32_32x32x16_bf16 v[16:31], v[168:171], v[172:175], v[16:31]
	v_mfma_f32_32x32x16_bf16 v[0:15], v[168:171], v[176:179], v[0:15]
	s_waitcnt vmcnt(6) lgkmcnt(0)
	s_barrier
;     ...
;   for (int kt = 0; kt < nk; ++kt) {
;     if (kt + 1 < nk) asm volatile("s_waitcnt vmcnt(6)" ::: "memory");
;     else asm volatile("s_waitcnt vmcnt(0)" ::: "memory");
;     __builtin_amdgcn_s_barrier();
;     asm volatile("" ::: "memory");
;     if (kt + 2 < nk) { const int st2 = (st >= 1) ? st - 1 : 2; GEMM_ISSUE(kt + 2, st2); }
;     const char* la = lds + st * STAGE_B;
;     const char* lb = la + 32768;
;     const unsigned sa_u = (unsigned)(size_t)la + arow_u, sb_u = (unsigned)(size_t)lb + brow_u;
;     const unsigned a0 = sa_u + co0, a1 = sa_u + co1, a2 = sa_u + co2, a3 = sa_u + co3;
;     const unsigned b0 = sb_u + co0, b1 = sb_u + co1, b2 = sb_u + co2, b3 = sb_u + co3;
;     {
;       bf16x8 p0, p1, q0, q1, u0, u1, w0, w1;
;       asm volatile(
;         "ds_read_b128 %4, %12\n\tds_read_b128 %5, %12 offset:4096\n\tds_read_b128 %6, %16\n\tds_read_b128 %7, %16 offset:4096\n\t"
;         "ds_read_b128 %8, %13\n\tds_read_b128 %9, %13 offset:4096\n\tds_read_b128 %10, %17\n\tds_read_b128 %11, %17 offset:4096\n\t"
;         "s_waitcnt lgkmcnt(4)\n\t"
;         "v_mfma_f32_32x32x16_bf16 %0, %4, %6, %0\n\tv_mfma_f32_32x32x16_bf16 %1, %4, %7, %1\n\tv_mfma_f32_32x32x16_bf16 %2, %5, %6, %2\n\tv_mfma_f32_32x32x16_bf16 %3, %5, %7, %3\n\t"
;         "ds_read_b128 %4, %14\n\tds_read_b128 %5, %14 offset:4096\n\tds_read_b128 %6, %18\n\tds_read_b128 %7, %18 offset:4096\n\t"
;         "s_waitcnt lgkmcnt(4)\n\t"
;         "v_mfma_f32_32x32x16_bf16 %0, %8, %10, %0\n\tv_mfma_f32_32x32x16_bf16 %1, %8, %11, %1\n\tv_mfma_f32_32x32x16_bf16 %2, %9, %10, %2\n\tv_mfma_f32_32x32x16_bf16 %3, %9, %11, %3\n\t"
;         "ds_read_b128 %8, %15\n\tds_read_b128 %9, %15 offset:4096\n\tds_read_b128 %10, %19\n\tds_read_b128 %11, %19 offset:4096\n\t"
;         "s_waitcnt lgkmcnt(4)\n\t"
;         "v_mfma_f32_32x32x16_bf16 %0, %4, %6, %0\n\tv_mfma_f32_32x32x16_bf16 %1, %4, %7, %1\n\tv_mfma_f32_32x32x16_bf16 %2, %5, %6, %2\n\tv_mfma_f32_32x32x16_bf16 %3, %5, %7, %3\n\t"
;         "s_waitcnt lgkmcnt(0)\n\t"
;         "v_mfma_f32_32x32x16_bf16 %0, %8, %10, %0\n\tv_mfma_f32_32x32x16_bf16 %1, %8, %11, %1\n\tv_mfma_f32_32x32x16_bf16 %2, %9, %10, %2\n\tv_mfma_f32_32x32x16_bf16 %3, %9, %11, %3"
;         : "+v"(acc[0][0]), "+v"(acc[0][1]), "+v"(acc[1][0]), "+v"(acc[1][1]),
;           "=&v"(p0), "=&v"(p1), "=&v"(q0), "=&v"(q1), "=&v"(u0), "=&v"(u1), "=&v"(w0), "=&v"(w1)
	ds_read_b128 v[164:167], v76 offset:49152
	ds_read_b128 v[168:171], v76 offset:53248
	ds_read_b128 v[172:175], v80 offset:49152
	ds_read_b128 v[176:179], v80 offset:53248
	v_mfma_f32_32x32x16_bf16 v[48:63], v[180:183], v[218:221], v[48:63]
	s_mov_b32 s14, 0xa5c2c00
	s_mov_b32 m0, s11
	v_lshl_add_u64 v[160:161], v[74:75], 0, s[14:15]
	global_load_lds_dwordx4 v[160:161], off
	v_mfma_f32_32x32x16_bf16 v[32:47], v[180:183], v[222:225], v[32:47]
	v_mfma_f32_32x32x16_bf16 v[16:31], v[184:187], v[218:221], v[16:31]
	s_add_u32 m0, s11, 0x2000
	v_lshl_add_u64 v[162:163], v[72:73], 0, s[14:15]
	global_load_lds_dwordx4 v[162:163], off
	v_mfma_f32_32x32x16_bf16 v[0:15], v[184:187], v[222:225], v[0:15]
	ds_read_b128 v[180:183], v77 offset:49152
	ds_read_b128 v[184:187], v77 offset:53248
	ds_read_b128 v[218:221], v81 offset:49152
	ds_read_b128 v[222:225], v81 offset:53248
	s_waitcnt lgkmcnt(4)
	v_mfma_f32_32x32x16_bf16 v[48:63], v[164:167], v[172:175], v[48:63]
	s_add_u32 m0, s11, 0x4000
	v_lshl_add_u64 v[160:161], v[70:71], 0, s[14:15]
	global_load_lds_dwordx4 v[160:161], off
	v_mfma_f32_32x32x16_bf16 v[32:47], v[164:167], v[176:179], v[32:47]
	v_mfma_f32_32x32x16_bf16 v[16:31], v[168:171], v[172:175], v[16:31]
	s_add_u32 m0, s11, 0x6000
	v_lshl_add_u64 v[162:163], v[68:69], 0, s[14:15]
	global_load_lds_dwordx4 v[162:163], off
	v_mfma_f32_32x32x16_bf16 v[0:15], v[168:171], v[176:179], v[0:15]
	ds_read_b128 v[164:167], v78 offset:49152
	ds_read_b128 v[168:171], v78 offset:53248
	ds_read_b128 v[172:175], v82 offset:49152
	ds_read_b128 v[176:179], v82 offset:53248
	s_waitcnt lgkmcnt(4)
	v_mfma_f32_32x32x16_bf16 v[48:63], v[180:183], v[218:221], v[48:63]
	s_mov_b32 s14, 0x1b80c00
	s_add_u32 m0, s11, 0x8000
	v_lshl_add_u64 v[160:161], v[66:67], 0, s[14:15]
	global_load_lds_dwordx4 v[160:161], off
	v_mfma_f32_32x32x16_bf16 v[32:47], v[180:183], v[222:225], v[32:47]
	v_mfma_f32_32x32x16_bf16 v[16:31], v[184:187], v[218:221], v[16:31]
	s_add_u32 m0, s11, 0xa000
	v_lshl_add_u64 v[162:163], v[64:65], 0, s[14:15]
	global_load_lds_dwordx4 v[162:163], off
	v_mfma_f32_32x32x16_bf16 v[0:15], v[184:187], v[222:225], v[0:15]
	ds_read_b128 v[180:183], v79 offset:49152
	ds_read_b128 v[184:187], v79 offset:53248
	ds_read_b128 v[218:221], v83 offset:49152
	ds_read_b128 v[222:225], v83 offset:53248
	s_waitcnt lgkmcnt(4)
	v_mfma_f32_32x32x16_bf16 v[48:63], v[164:167], v[172:175], v[48:63]
	v_mfma_f32_32x32x16_bf16 v[32:47], v[164:167], v[176:179], v[32:47]
	v_mfma_f32_32x32x16_bf16 v[16:31], v[168:171], v[172:175], v[16:31]
	v_mfma_f32_32x32x16_bf16 v[0:15], v[168:171], v[176:179], v[0:15]
	s_waitcnt vmcnt(6) lgkmcnt(0)
	s_barrier
	ds_read_b128 v[164:167], v84
	ds_read_b128 v[168:171], v84 offset:4096
	ds_read_b128 v[172:175], v156
	ds_read_b128 v[176:179], v156 offset:4096
	v_mfma_f32_32x32x16_bf16 v[48:63], v[180:183], v[218:221], v[48:63]
	s_mov_b32 s14, 0xa5c2c80
	s_add_u32 m0, s11, 0xc000
	v_lshl_add_u64 v[160:161], v[74:75], 0, s[14:15]
	global_load_lds_dwordx4 v[160:161], off
	v_mfma_f32_32x32x16_bf16 v[32:47], v[180:183], v[222:225], v[32:47]
	v_mfma_f32_32x32x16_bf16 v[16:31], v[184:187], v[218:221], v[16:31]
	s_add_u32 m0, s11, 0xe000
	v_lshl_add_u64 v[162:163], v[72:73], 0, s[14:15]
	global_load_lds_dwordx4 v[162:163], off
	v_mfma_f32_32x32x16_bf16 v[0:15], v[184:187], v[222:225], v[0:15]
	ds_read_b128 v[180:183], v85
	ds_read_b128 v[184:187], v85 offset:4096
	ds_read_b128 v[218:221], v157
	ds_read_b128 v[222:225], v157 offset:4096
	s_waitcnt lgkmcnt(4)
	v_mfma_f32_32x32x16_bf16 v[48:63], v[164:167], v[172:175], v[48:63]
	s_add_u32 m0, s11, 0x10000
	v_lshl_add_u64 v[160:161], v[70:71], 0, s[14:15]
	global_load_lds_dwordx4 v[160:161], off
	v_mfma_f32_32x32x16_bf16 v[32:47], v[164:167], v[176:179], v[32:47]
	v_mfma_f32_32x32x16_bf16 v[16:31], v[168:171], v[172:175], v[16:31]
	s_add_u32 m0, s11, 0x12000
	v_lshl_add_u64 v[162:163], v[68:69], 0, s[14:15]
	global_load_lds_dwordx4 v[162:163], off
	v_mfma_f32_32x32x16_bf16 v[0:15], v[168:171], v[176:179], v[0:15]
	ds_read_b128 v[164:167], v86
	ds_read_b128 v[168:171], v86 offset:4096
	ds_read_b128 v[172:175], v158
	ds_read_b128 v[176:179], v158 offset:4096
	s_waitcnt lgkmcnt(4)
	v_mfma_f32_32x32x16_bf16 v[48:63], v[180:183], v[218:221], v[48:63]
	s_mov_b32 s14, 0x1b80c80
	s_add_u32 m0, s11, 0x14000
	v_lshl_add_u64 v[160:161], v[66:67], 0, s[14:15]
	global_load_lds_dwordx4 v[160:161], off
	v_mfma_f32_32x32x16_bf16 v[32:47], v[180:183], v[222:225], v[32:47]
	v_mfma_f32_32x32x16_bf16 v[16:31], v[184:187], v[218:221], v[16:31]
	s_add_u32 m0, s11, 0x16000
	v_lshl_add_u64 v[162:163], v[64:65], 0, s[14:15]
	global_load_lds_dwordx4 v[162:163], off
	v_mfma_f32_32x32x16_bf16 v[0:15], v[184:187], v[222:225], v[0:15]
	ds_read_b128 v[180:183], v87
	ds_read_b128 v[184:187], v87 offset:4096
	ds_read_b128 v[218:221], v159
	ds_read_b128 v[222:225], v159 offset:4096
	s_waitcnt lgkmcnt(4)
	v_mfma_f32_32x32x16_bf16 v[48:63], v[164:167], v[172:175], v[48:63]
	v_mfma_f32_32x32x16_bf16 v[32:47], v[164:167], v[176:179], v[32:47]
	v_mfma_f32_32x32x16_bf16 v[16:31], v[168:171], v[172:175], v[16:31]
	v_mfma_f32_32x32x16_bf16 v[0:15], v[168:171], v[176:179], v[0:15]
	s_waitcnt vmcnt(6) lgkmcnt(0)
	s_barrier
;     ...
;   for (int kt = 0; kt < nk; ++kt) {
;     if (kt + 1 < nk) asm volatile("s_waitcnt vmcnt(6)" ::: "memory");
;     else asm volatile("s_waitcnt vmcnt(0)" ::: "memory");
;     __builtin_amdgcn_s_barrier();
;     asm volatile("" ::: "memory");
;     if (kt + 2 < nk) { const int st2 = (st >= 1) ? st - 1 : 2; GEMM_ISSUE(kt + 2, st2); }
;     const char* la = lds + st * STAGE_B;
;     const char* lb = la + 32768;
;     const unsigned sa_u = (unsigned)(size_t)la + arow_u, sb_u = (unsigned)(size_t)lb + brow_u;
;     const unsigned a0 = sa_u + co0, a1 = sa_u + co1, a2 = sa_u + co2, a3 = sa_u + co3;
;     const unsigned b0 = sb_u + co0, b1 = sb_u + co1, b2 = sb_u + co2, b3 = sb_u + co3;
;     {
;       bf16x8 p0, p1, q0, q1, u0, u1, w0, w1;
;       asm volatile(
;         "ds_read_b128 %4, %12\n\tds_read_b128 %5, %12 offset:4096\n\tds_read_b128 %6, %16\n\tds_read_b128 %7, %16 offset:4096\n\t"
;         "ds_read_b128 %8, %13\n\tds_read_b128 %9, %13 offset:4096\n\tds_read_b128 %10, %17\n\tds_read_b128 %11, %17 offset:4096\n\t"
;         "s_waitcnt lgkmcnt(4)\n\t"
;         "v_mfma_f32_32x32x16_bf16 %0, %4, %6, %0\n\tv_mfma_f32_32x32x16_bf16 %1, %4, %7, %1\n\tv_mfma_f32_32x32x16_bf16 %2, %5, %6, %2\n\tv_mfma_f32_32x32x16_bf16 %3, %5, %7, %3\n\t"
;         "ds_read_b128 %4, %14\n\tds_read_b128 %5, %14 offset:4096\n\tds_read_b128 %6, %18\n\tds_read_b128 %7, %18 offset:4096\n\t"
;         "s_waitcnt lgkmcnt(4)\n\t"
;         "v_mfma_f32_32x32x16_bf16 %0, %8, %10, %0\n\tv_mfma_f32_32x32x16_bf16 %1, %8, %11, %1\n\tv_mfma_f32_32x32x16_bf16 %2, %9, %10, %2\n\tv_mfma_f32_32x32x16_bf16 %3, %9, %11, %3\n\t"
;         "ds_read_b128 %8, %15\n\tds_read_b128 %9, %15 offset:4096\n\tds_read_b128 %10, %19\n\tds_read_b128 %11, %19 offset:4096\n\t"
;         "s_waitcnt lgkmcnt(4)\n\t"
;         "v_mfma_f32_32x32x16_bf16 %0, %4, %6, %0\n\tv_mfma_f32_32x32x16_bf16 %1, %4, %7, %1\n\tv_mfma_f32_32x32x16_bf16 %2, %5, %6, %2\n\tv_mfma_f32_32x32x16_bf16 %3, %5, %7, %3\n\t"
;         "s_waitcnt lgkmcnt(0)\n\t"
;         "v_mfma_f32_32x32x16_bf16 %0, %8, %10, %0\n\tv_mfma_f32_32x32x16_bf16 %1, %8, %11, %1\n\tv_mfma_f32_32x32x16_bf16 %2, %9, %10, %2\n\tv_mfma_f32_32x32x16_bf16 %3, %9, %11, %3"
;         : "+v"(acc[0][0]), "+v"(acc[0][1]), "+v"(acc[1][0]), "+v"(acc[1][1]),
;           "=&v"(p0), "=&v"(p1), "=&v"(q0), "=&v"(q1), "=&v"(u0), "=&v"(u1), "=&v"(w0), "=&v"(w1)
	ds_read_b128 v[164:167], v76
	ds_read_b128 v[168:171], v76 offset:4096
	ds_read_b128 v[172:175], v80
	ds_read_b128 v[176:179], v80 offset:4096
	v_mfma_f32_32x32x16_bf16 v[48:63], v[180:183], v[218:221], v[48:63]
	s_mov_b32 s14, 0xa5c2d00
	s_add_u32 m0, s11, 0x18000
	v_lshl_add_u64 v[160:161], v[74:75], 0, s[14:15]
	global_load_lds_dwordx4 v[160:161], off
	v_mfma_f32_32x32x16_bf16 v[32:47], v[180:183], v[222:225], v[32:47]
	v_mfma_f32_32x32x16_bf16 v[16:31], v[184:187], v[218:221], v[16:31]
	s_add_u32 m0, s11, 0x1a000
	v_lshl_add_u64 v[162:163], v[72:73], 0, s[14:15]
	global_load_lds_dwordx4 v[162:163], off
	v_mfma_f32_32x32x16_bf16 v[0:15], v[184:187], v[222:225], v[0:15]
	ds_read_b128 v[180:183], v77
	ds_read_b128 v[184:187], v77 offset:4096
	ds_read_b128 v[218:221], v81
	ds_read_b128 v[222:225], v81 offset:4096
	s_waitcnt lgkmcnt(4)
	v_mfma_f32_32x32x16_bf16 v[48:63], v[164:167], v[172:175], v[48:63]
	s_add_u32 m0, s11, 0x1c000
	v_lshl_add_u64 v[160:161], v[70:71], 0, s[14:15]
	global_load_lds_dwordx4 v[160:161], off
	v_mfma_f32_32x32x16_bf16 v[32:47], v[164:167], v[176:179], v[32:47]
	v_mfma_f32_32x32x16_bf16 v[16:31], v[168:171], v[172:175], v[16:31]
	s_add_u32 m0, s11, 0x1e000
	v_lshl_add_u64 v[162:163], v[68:69], 0, s[14:15]
	global_load_lds_dwordx4 v[162:163], off
	v_mfma_f32_32x32x16_bf16 v[0:15], v[168:171], v[176:179], v[0:15]
	ds_read_b128 v[164:167], v78
	ds_read_b128 v[168:171], v78 offset:4096
	ds_read_b128 v[172:175], v82
	ds_read_b128 v[176:179], v82 offset:4096
	s_waitcnt lgkmcnt(4)
	v_mfma_f32_32x32x16_bf16 v[48:63], v[180:183], v[218:221], v[48:63]
	s_mov_b32 s14, 0x1b80d00
	s_add_u32 m0, s11, 0x20000
	v_lshl_add_u64 v[160:161], v[66:67], 0, s[14:15]
	global_load_lds_dwordx4 v[160:161], off
	v_mfma_f32_32x32x16_bf16 v[32:47], v[180:183], v[222:225], v[32:47]
	v_mfma_f32_32x32x16_bf16 v[16:31], v[184:187], v[218:221], v[16:31]
	s_add_u32 m0, s11, 0x22000
	v_lshl_add_u64 v[162:163], v[64:65], 0, s[14:15]
	global_load_lds_dwordx4 v[162:163], off
	v_mfma_f32_32x32x16_bf16 v[0:15], v[184:187], v[222:225], v[0:15]
	ds_read_b128 v[180:183], v79
	ds_read_b128 v[184:187], v79 offset:4096
	ds_read_b128 v[218:221], v83
	ds_read_b128 v[222:225], v83 offset:4096
	s_waitcnt lgkmcnt(4)
	v_mfma_f32_32x32x16_bf16 v[48:63], v[164:167], v[172:175], v[48:63]
	v_mfma_f32_32x32x16_bf16 v[32:47], v[164:167], v[176:179], v[32:47]
	v_mfma_f32_32x32x16_bf16 v[16:31], v[168:171], v[172:175], v[16:31]
	v_mfma_f32_32x32x16_bf16 v[0:15], v[168:171], v[176:179], v[0:15]
	s_waitcnt vmcnt(6) lgkmcnt(0)
	s_barrier
	ds_read_b128 v[164:167], v76 offset:49152
	ds_read_b128 v[168:171], v76 offset:53248
	ds_read_b128 v[172:175], v80 offset:49152
	ds_read_b128 v[176:179], v80 offset:53248
	v_mfma_f32_32x32x16_bf16 v[48:63], v[180:183], v[218:221], v[48:63]
	s_mov_b32 s14, 0xa5c2d80
	s_mov_b32 m0, s11
	v_lshl_add_u64 v[160:161], v[74:75], 0, s[14:15]
	global_load_lds_dwordx4 v[160:161], off
	v_mfma_f32_32x32x16_bf16 v[32:47], v[180:183], v[222:225], v[32:47]
	v_mfma_f32_32x32x16_bf16 v[16:31], v[184:187], v[218:221], v[16:31]
	s_add_u32 m0, s11, 0x2000
	v_lshl_add_u64 v[162:163], v[72:73], 0, s[14:15]
	global_load_lds_dwordx4 v[162:163], off
	v_mfma_f32_32x32x16_bf16 v[0:15], v[184:187], v[222:225], v[0:15]
	ds_read_b128 v[180:183], v77 offset:49152
	ds_read_b128 v[184:187], v77 offset:53248
	ds_read_b128 v[218:221], v81 offset:49152
	ds_read_b128 v[222:225], v81 offset:53248
	s_waitcnt lgkmcnt(4)
	v_mfma_f32_32x32x16_bf16 v[48:63], v[164:167], v[172:175], v[48:63]
	s_add_u32 m0, s11, 0x4000
	v_lshl_add_u64 v[160:161], v[70:71], 0, s[14:15]
	global_load_lds_dwordx4 v[160:161], off
	v_mfma_f32_32x32x16_bf16 v[32:47], v[164:167], v[176:179], v[32:47]
	v_mfma_f32_32x32x16_bf16 v[16:31], v[168:171], v[172:175], v[16:31]
	s_add_u32 m0, s11, 0x6000
	v_lshl_add_u64 v[162:163], v[68:69], 0, s[14:15]
	global_load_lds_dwordx4 v[162:163], off
	v_mfma_f32_32x32x16_bf16 v[0:15], v[168:171], v[176:179], v[0:15]
	ds_read_b128 v[164:167], v78 offset:49152
	ds_read_b128 v[168:171], v78 offset:53248
	ds_read_b128 v[172:175], v82 offset:49152
	ds_read_b128 v[176:179], v82 offset:53248
	s_waitcnt lgkmcnt(4)
	v_mfma_f32_32x32x16_bf16 v[48:63], v[180:183], v[218:221], v[48:63]
	s_mov_b32 s14, 0x1b80d80
	s_add_u32 m0, s11, 0x8000
	v_lshl_add_u64 v[160:161], v[66:67], 0, s[14:15]
	global_load_lds_dwordx4 v[160:161], off
	v_mfma_f32_32x32x16_bf16 v[32:47], v[180:183], v[222:225], v[32:47]
	v_mfma_f32_32x32x16_bf16 v[16:31], v[184:187], v[218:221], v[16:31]
	s_add_u32 m0, s11, 0xa000
	v_lshl_add_u64 v[162:163], v[64:65], 0, s[14:15]
	global_load_lds_dwordx4 v[162:163], off
	v_mfma_f32_32x32x16_bf16 v[0:15], v[184:187], v[222:225], v[0:15]
	ds_read_b128 v[180:183], v79 offset:49152
	ds_read_b128 v[184:187], v79 offset:53248
	ds_read_b128 v[218:221], v83 offset:49152
	ds_read_b128 v[222:225], v83 offset:53248
	s_waitcnt lgkmcnt(4)
	v_mfma_f32_32x32x16_bf16 v[48:63], v[164:167], v[172:175], v[48:63]
	v_mfma_f32_32x32x16_bf16 v[32:47], v[164:167], v[176:179], v[32:47]
	v_mfma_f32_32x32x16_bf16 v[16:31], v[168:171], v[172:175], v[16:31]
	v_mfma_f32_32x32x16_bf16 v[0:15], v[168:171], v[176:179], v[0:15]
	s_waitcnt vmcnt(6) lgkmcnt(0)
	s_barrier
;     ...
;   for (int kt = 0; kt < nk; ++kt) {
;     if (kt + 1 < nk) asm volatile("s_waitcnt vmcnt(6)" ::: "memory");
;     else asm volatile("s_waitcnt vmcnt(0)" ::: "memory");
;     __builtin_amdgcn_s_barrier();
;     asm volatile("" ::: "memory");
;     if (kt + 2 < nk) { const int st2 = (st >= 1) ? st - 1 : 2; GEMM_ISSUE(kt + 2, st2); }
;     const char* la = lds + st * STAGE_B;
;     const char* lb = la + 32768;
;     const unsigned sa_u = (unsigned)(size_t)la + arow_u, sb_u = (unsigned)(size_t)lb + brow_u;
;     const unsigned a0 = sa_u + co0, a1 = sa_u + co1, a2 = sa_u + co2, a3 = sa_u + co3;
;     const unsigned b0 = sb_u + co0, b1 = sb_u + co1, b2 = sb_u + co2, b3 = sb_u + co3;
;     {
;       bf16x8 p0, p1, q0, q1, u0, u1, w0, w1;
;       asm volatile(
;         "ds_read_b128 %4, %12\n\tds_read_b128 %5, %12 offset:4096\n\tds_read_b128 %6, %16\n\tds_read_b128 %7, %16 offset:4096\n\t"
;         "ds_read_b128 %8, %13\n\tds_read_b128 %9, %13 offset:4096\n\tds_read_b128 %10, %17\n\tds_read_b128 %11, %17 offset:4096\n\t"
;         "s_waitcnt lgkmcnt(4)\n\t"
;         "v_mfma_f32_32x32x16_bf16 %0, %4, %6, %0\n\tv_mfma_f32_32x32x16_bf16 %1, %4, %7, %1\n\tv_mfma_f32_32x32x16_bf16 %2, %5, %6, %2\n\tv_mfma_f32_32x32x16_bf16 %3, %5, %7, %3\n\t"
;         "ds_read_b128 %4, %14\n\tds_read_b128 %5, %14 offset:4096\n\tds_read_b128 %6, %18\n\tds_read_b128 %7, %18 offset:4096\n\t"
;         "s_waitcnt lgkmcnt(4)\n\t"
;         "v_mfma_f32_32x32x16_bf16 %0, %8, %10, %0\n\tv_mfma_f32_32x32x16_bf16 %1, %8, %11, %1\n\tv_mfma_f32_32x32x16_bf16 %2, %9, %10, %2\n\tv_mfma_f32_32x32x16_bf16 %3, %9, %11, %3\n\t"
;         "ds_read_b128 %8, %15\n\tds_read_b128 %9, %15 offset:4096\n\tds_read_b128 %10, %19\n\tds_read_b128 %11, %19 offset:4096\n\t"
;         "s_waitcnt lgkmcnt(4)\n\t"
;         "v_mfma_f32_32x32x16_bf16 %0, %4, %6, %0\n\tv_mfma_f32_32x32x16_bf16 %1, %4, %7, %1\n\tv_mfma_f32_32x32x16_bf16 %2, %5, %6, %2\n\tv_mfma_f32_32x32x16_bf16 %3, %5, %7, %3\n\t"
;         "s_waitcnt lgkmcnt(0)\n\t"
;         "v_mfma_f32_32x32x16_bf16 %0, %8, %10, %0\n\tv_mfma_f32_32x32x16_bf16 %1, %8, %11, %1\n\tv_mfma_f32_32x32x16_bf16 %2, %9, %10, %2\n\tv_mfma_f32_32x32x16_bf16 %3, %9, %11, %3"
;         : "+v"(acc[0][0]), "+v"(acc[0][1]), "+v"(acc[1][0]), "+v"(acc[1][1]),
;           "=&v"(p0), "=&v"(p1), "=&v"(q0), "=&v"(q1), "=&v"(u0), "=&v"(u1), "=&v"(w0), "=&v"(w1)
	ds_read_b128 v[164:167], v84
	ds_read_b128 v[168:171], v84 offset:4096
	ds_read_b128 v[172:175], v156
	ds_read_b128 v[176:179], v156 offset:4096
	v_mfma_f32_32x32x16_bf16 v[48:63], v[180:183], v[218:221], v[48:63]
	s_mov_b32 s14, 0xa5c2e00
	s_add_u32 m0, s11, 0xc000
	v_lshl_add_u64 v[160:161], v[74:75], 0, s[14:15]
	global_load_lds_dwordx4 v[160:161], off
	v_mfma_f32_32x32x16_bf16 v[32:47], v[180:183], v[222:225], v[32:47]
	v_mfma_f32_32x32x16_bf16 v[16:31], v[184:187], v[218:221], v[16:31]
	s_add_u32 m0, s11, 0xe000
	v_lshl_add_u64 v[162:163], v[72:73], 0, s[14:15]
	global_load_lds_dwordx4 v[162:163], off
	v_mfma_f32_32x32x16_bf16 v[0:15], v[184:187], v[222:225], v[0:15]
	ds_read_b128 v[180:183], v85
	ds_read_b128 v[184:187], v85 offset:4096
	ds_read_b128 v[218:221], v157
	ds_read_b128 v[222:225], v157 offset:4096
	s_waitcnt lgkmcnt(4)
	v_mfma_f32_32x32x16_bf16 v[48:63], v[164:167], v[172:175], v[48:63]
	s_add_u32 m0, s11, 0x10000
	v_lshl_add_u64 v[160:161], v[70:71], 0, s[14:15]
	global_load_lds_dwordx4 v[160:161], off
	v_mfma_f32_32x32x16_bf16 v[32:47], v[164:167], v[176:179], v[32:47]
	v_mfma_f32_32x32x16_bf16 v[16:31], v[168:171], v[172:175], v[16:31]
	s_add_u32 m0, s11, 0x12000
	v_lshl_add_u64 v[162:163], v[68:69], 0, s[14:15]
	global_load_lds_dwordx4 v[162:163], off
	v_mfma_f32_32x32x16_bf16 v[0:15], v[168:171], v[176:179], v[0:15]
	ds_read_b128 v[164:167], v86
	ds_read_b128 v[168:171], v86 offset:4096
	ds_read_b128 v[172:175], v158
	ds_read_b128 v[176:179], v158 offset:4096
	s_waitcnt lgkmcnt(4)
	v_mfma_f32_32x32x16_bf16 v[48:63], v[180:183], v[218:221], v[48:63]
	s_mov_b32 s14, 0x1b80e00
	s_add_u32 m0, s11, 0x14000
	v_lshl_add_u64 v[160:161], v[66:67], 0, s[14:15]
	global_load_lds_dwordx4 v[160:161], off
	v_mfma_f32_32x32x16_bf16 v[32:47], v[180:183], v[222:225], v[32:47]
	v_mfma_f32_32x32x16_bf16 v[16:31], v[184:187], v[218:221], v[16:31]
	s_add_u32 m0, s11, 0x16000
	v_lshl_add_u64 v[162:163], v[64:65], 0, s[14:15]
	global_load_lds_dwordx4 v[162:163], off
	v_mfma_f32_32x32x16_bf16 v[0:15], v[184:187], v[222:225], v[0:15]
	ds_read_b128 v[180:183], v87
	ds_read_b128 v[184:187], v87 offset:4096
	ds_read_b128 v[218:221], v159
	ds_read_b128 v[222:225], v159 offset:4096
	s_waitcnt lgkmcnt(4)
	v_mfma_f32_32x32x16_bf16 v[48:63], v[164:167], v[172:175], v[48:63]
	v_mfma_f32_32x32x16_bf16 v[32:47], v[164:167], v[176:179], v[32:47]
	v_mfma_f32_32x32x16_bf16 v[16:31], v[168:171], v[172:175], v[16:31]
	v_mfma_f32_32x32x16_bf16 v[0:15], v[168:171], v[176:179], v[0:15]
	s_waitcnt vmcnt(6) lgkmcnt(0)
	s_barrier
	ds_read_b128 v[164:167], v76
	ds_read_b128 v[168:171], v76 offset:4096
	ds_read_b128 v[172:175], v80
	ds_read_b128 v[176:179], v80 offset:4096
	v_mfma_f32_32x32x16_bf16 v[48:63], v[180:183], v[218:221], v[48:63]
	s_mov_b32 s14, 0xa5c2e80
	s_add_u32 m0, s11, 0x18000
	v_lshl_add_u64 v[160:161], v[74:75], 0, s[14:15]
	global_load_lds_dwordx4 v[160:161], off
	v_mfma_f32_32x32x16_bf16 v[32:47], v[180:183], v[222:225], v[32:47]
	v_mfma_f32_32x32x16_bf16 v[16:31], v[184:187], v[218:221], v[16:31]
	s_add_u32 m0, s11, 0x1a000
	v_lshl_add_u64 v[162:163], v[72:73], 0, s[14:15]
	global_load_lds_dwordx4 v[162:163], off
	v_mfma_f32_32x32x16_bf16 v[0:15], v[184:187], v[222:225], v[0:15]
	ds_read_b128 v[180:183], v77
	ds_read_b128 v[184:187], v77 offset:4096
	ds_read_b128 v[218:221], v81
	ds_read_b128 v[222:225], v81 offset:4096
	s_waitcnt lgkmcnt(4)
	v_mfma_f32_32x32x16_bf16 v[48:63], v[164:167], v[172:175], v[48:63]
	s_add_u32 m0, s11, 0x1c000
	v_lshl_add_u64 v[160:161], v[70:71], 0, s[14:15]
	global_load_lds_dwordx4 v[160:161], off
	v_mfma_f32_32x32x16_bf16 v[32:47], v[164:167], v[176:179], v[32:47]
	v_mfma_f32_32x32x16_bf16 v[16:31], v[168:171], v[172:175], v[16:31]
	s_add_u32 m0, s11, 0x1e000
	v_lshl_add_u64 v[162:163], v[68:69], 0, s[14:15]
	global_load_lds_dwordx4 v[162:163], off
	v_mfma_f32_32x32x16_bf16 v[0:15], v[168:171], v[176:179], v[0:15]
	ds_read_b128 v[164:167], v78
	ds_read_b128 v[168:171], v78 offset:4096
	ds_read_b128 v[172:175], v82
	ds_read_b128 v[176:179], v82 offset:4096
	s_waitcnt lgkmcnt(4)
	v_mfma_f32_32x32x16_bf16 v[48:63], v[180:183], v[218:221], v[48:63]
	s_mov_b32 s14, 0x1b80e80
	s_add_u32 m0, s11, 0x20000
	v_lshl_add_u64 v[160:161], v[66:67], 0, s[14:15]
	global_load_lds_dwordx4 v[160:161], off
	v_mfma_f32_32x32x16_bf16 v[32:47], v[180:183], v[222:225], v[32:47]
	v_mfma_f32_32x32x16_bf16 v[16:31], v[184:187], v[218:221], v[16:31]
	s_add_u32 m0, s11, 0x22000
	v_lshl_add_u64 v[162:163], v[64:65], 0, s[14:15]
	global_load_lds_dwordx4 v[162:163], off
	v_mfma_f32_32x32x16_bf16 v[0:15], v[184:187], v[222:225], v[0:15]
	ds_read_b128 v[180:183], v79
	ds_read_b128 v[184:187], v79 offset:4096
	ds_read_b128 v[218:221], v83
	ds_read_b128 v[222:225], v83 offset:4096
	s_waitcnt lgkmcnt(4)
	v_mfma_f32_32x32x16_bf16 v[48:63], v[164:167], v[172:175], v[48:63]
	v_mfma_f32_32x32x16_bf16 v[32:47], v[164:167], v[176:179], v[32:47]
	v_mfma_f32_32x32x16_bf16 v[16:31], v[168:171], v[172:175], v[16:31]
	v_mfma_f32_32x32x16_bf16 v[0:15], v[168:171], v[176:179], v[0:15]
	s_waitcnt vmcnt(6) lgkmcnt(0)
	s_barrier
;     ...
;   for (int kt = 0; kt < nk; ++kt) {
;     if (kt + 1 < nk) asm volatile("s_waitcnt vmcnt(6)" ::: "memory");
;     else asm volatile("s_waitcnt vmcnt(0)" ::: "memory");
;     __builtin_amdgcn_s_barrier();
;     asm volatile("" ::: "memory");
;     if (kt + 2 < nk) { const int st2 = (st >= 1) ? st - 1 : 2; GEMM_ISSUE(kt + 2, st2); }
;     const char* la = lds + st * STAGE_B;
;     const char* lb = la + 32768;
;     const unsigned sa_u = (unsigned)(size_t)la + arow_u, sb_u = (unsigned)(size_t)lb + brow_u;
;     const unsigned a0 = sa_u + co0, a1 = sa_u + co1, a2 = sa_u + co2, a3 = sa_u + co3;
;     const unsigned b0 = sb_u + co0, b1 = sb_u + co1, b2 = sb_u + co2, b3 = sb_u + co3;
;     {
;       bf16x8 p0, p1, q0, q1, u0, u1, w0, w1;
;       asm volatile(
;         "ds_read_b128 %4, %12\n\tds_read_b128 %5, %12 offset:4096\n\tds_read_b128 %6, %16\n\tds_read_b128 %7, %16 offset:4096\n\t"
;         "ds_read_b128 %8, %13\n\tds_read_b128 %9, %13 offset:4096\n\tds_read_b128 %10, %17\n\tds_read_b128 %11, %17 offset:4096\n\t"
;         "s_waitcnt lgkmcnt(4)\n\t"
;         "v_mfma_f32_32x32x16_bf16 %0, %4, %6, %0\n\tv_mfma_f32_32x32x16_bf16 %1, %4, %7, %1\n\tv_mfma_f32_32x32x16_bf16 %2, %5, %6, %2\n\tv_mfma_f32_32x32x16_bf16 %3, %5, %7, %3\n\t"
;         "ds_read_b128 %4, %14\n\tds_read_b128 %5, %14 offset:4096\n\tds_read_b128 %6, %18\n\tds_read_b128 %7, %18 offset:4096\n\t"
;         "s_waitcnt lgkmcnt(4)\n\t"
;         "v_mfma_f32_32x32x16_bf16 %0, %8, %10, %0\n\tv_mfma_f32_32x32x16_bf16 %1, %8, %11, %1\n\tv_mfma_f32_32x32x16_bf16 %2, %9, %10, %2\n\tv_mfma_f32_32x32x16_bf16 %3, %9, %11, %3\n\t"
;         "ds_read_b128 %8, %15\n\tds_read_b128 %9, %15 offset:4096\n\tds_read_b128 %10, %19\n\tds_read_b128 %11, %19 offset:4096\n\t"
;         "s_waitcnt lgkmcnt(4)\n\t"
;         "v_mfma_f32_32x32x16_bf16 %0, %4, %6, %0\n\tv_mfma_f32_32x32x16_bf16 %1, %4, %7, %1\n\tv_mfma_f32_32x32x16_bf16 %2, %5, %6, %2\n\tv_mfma_f32_32x32x16_bf16 %3, %5, %7, %3\n\t"
;         "s_waitcnt lgkmcnt(0)\n\t"
;         "v_mfma_f32_32x32x16_bf16 %0, %8, %10, %0\n\tv_mfma_f32_32x32x16_bf16 %1, %8, %11, %1\n\tv_mfma_f32_32x32x16_bf16 %2, %9, %10, %2\n\tv_mfma_f32_32x32x16_bf16 %3, %9, %11, %3"
;         : "+v"(acc[0][0]), "+v"(acc[0][1]), "+v"(acc[1][0]), "+v"(acc[1][1]),
;           "=&v"(p0), "=&v"(p1), "=&v"(q0), "=&v"(q1), "=&v"(u0), "=&v"(u1), "=&v"(w0), "=&v"(w1)
	ds_read_b128 v[164:167], v76 offset:49152
	ds_read_b128 v[168:171], v76 offset:53248
	ds_read_b128 v[172:175], v80 offset:49152
	ds_read_b128 v[176:179], v80 offset:53248
	v_mfma_f32_32x32x16_bf16 v[48:63], v[180:183], v[218:221], v[48:63]
	s_mov_b32 s14, 0xa5c2f00
	s_mov_b32 m0, s11
	v_lshl_add_u64 v[160:161], v[74:75], 0, s[14:15]
	global_load_lds_dwordx4 v[160:161], off
	v_mfma_f32_32x32x16_bf16 v[32:47], v[180:183], v[222:225], v[32:47]
	v_mfma_f32_32x32x16_bf16 v[16:31], v[184:187], v[218:221], v[16:31]
	s_add_u32 m0, s11, 0x2000
	v_lshl_add_u64 v[162:163], v[72:73], 0, s[14:15]
	global_load_lds_dwordx4 v[162:163], off
	v_mfma_f32_32x32x16_bf16 v[0:15], v[184:187], v[222:225], v[0:15]
	ds_read_b128 v[180:183], v77 offset:49152
	ds_read_b128 v[184:187], v77 offset:53248
	ds_read_b128 v[218:221], v81 offset:49152
	ds_read_b128 v[222:225], v81 offset:53248
	s_waitcnt lgkmcnt(4)
	v_mfma_f32_32x32x16_bf16 v[48:63], v[164:167], v[172:175], v[48:63]
	s_add_u32 m0, s11, 0x4000
	v_lshl_add_u64 v[160:161], v[70:71], 0, s[14:15]
	global_load_lds_dwordx4 v[160:161], off
	v_mfma_f32_32x32x16_bf16 v[32:47], v[164:167], v[176:179], v[32:47]
	v_mfma_f32_32x32x16_bf16 v[16:31], v[168:171], v[172:175], v[16:31]
	s_add_u32 m0, s11, 0x6000
	v_lshl_add_u64 v[162:163], v[68:69], 0, s[14:15]
	global_load_lds_dwordx4 v[162:163], off
	v_mfma_f32_32x32x16_bf16 v[0:15], v[168:171], v[176:179], v[0:15]
	ds_read_b128 v[164:167], v78 offset:49152
	ds_read_b128 v[168:171], v78 offset:53248
	ds_read_b128 v[172:175], v82 offset:49152
	ds_read_b128 v[176:179], v82 offset:53248
	s_waitcnt lgkmcnt(4)
	v_mfma_f32_32x32x16_bf16 v[48:63], v[180:183], v[218:221], v[48:63]
	s_mov_b32 s14, 0x1b80f00
	s_add_u32 m0, s11, 0x8000
	v_lshl_add_u64 v[160:161], v[66:67], 0, s[14:15]
	global_load_lds_dwordx4 v[160:161], off
	v_mfma_f32_32x32x16_bf16 v[32:47], v[180:183], v[222:225], v[32:47]
	v_mfma_f32_32x32x16_bf16 v[16:31], v[184:187], v[218:221], v[16:31]
	s_add_u32 m0, s11, 0xa000
	v_lshl_add_u64 v[162:163], v[64:65], 0, s[14:15]
	global_load_lds_dwordx4 v[162:163], off
	v_mfma_f32_32x32x16_bf16 v[0:15], v[184:187], v[222:225], v[0:15]
	ds_read_b128 v[180:183], v79 offset:49152
	ds_read_b128 v[184:187], v79 offset:53248
	ds_read_b128 v[218:221], v83 offset:49152
	ds_read_b128 v[222:225], v83 offset:53248
	s_waitcnt lgkmcnt(4)
	v_mfma_f32_32x32x16_bf16 v[48:63], v[164:167], v[172:175], v[48:63]
	v_mfma_f32_32x32x16_bf16 v[32:47], v[164:167], v[176:179], v[32:47]
	v_mfma_f32_32x32x16_bf16 v[16:31], v[168:171], v[172:175], v[16:31]
	v_mfma_f32_32x32x16_bf16 v[0:15], v[168:171], v[176:179], v[0:15]
	s_waitcnt vmcnt(6) lgkmcnt(0)
	s_barrier
	ds_read_b128 v[164:167], v84
	ds_read_b128 v[168:171], v84 offset:4096
	ds_read_b128 v[172:175], v156
	ds_read_b128 v[176:179], v156 offset:4096
	v_mfma_f32_32x32x16_bf16 v[48:63], v[180:183], v[218:221], v[48:63]
	s_mov_b32 s14, 0xa5c2f80
	s_add_u32 m0, s11, 0xc000
	v_lshl_add_u64 v[160:161], v[74:75], 0, s[14:15]
	global_load_lds_dwordx4 v[160:161], off
	v_mfma_f32_32x32x16_bf16 v[32:47], v[180:183], v[222:225], v[32:47]
	v_mfma_f32_32x32x16_bf16 v[16:31], v[184:187], v[218:221], v[16:31]
	s_add_u32 m0, s11, 0xe000
	v_lshl_add_u64 v[162:163], v[72:73], 0, s[14:15]
	global_load_lds_dwordx4 v[162:163], off
	v_mfma_f32_32x32x16_bf16 v[0:15], v[184:187], v[222:225], v[0:15]
	ds_read_b128 v[180:183], v85
	ds_read_b128 v[184:187], v85 offset:4096
	ds_read_b128 v[218:221], v157
	ds_read_b128 v[222:225], v157 offset:4096
	s_waitcnt lgkmcnt(4)
	v_mfma_f32_32x32x16_bf16 v[48:63], v[164:167], v[172:175], v[48:63]
	s_add_u32 m0, s11, 0x10000
	v_lshl_add_u64 v[160:161], v[70:71], 0, s[14:15]
	global_load_lds_dwordx4 v[160:161], off
	v_mfma_f32_32x32x16_bf16 v[32:47], v[164:167], v[176:179], v[32:47]
	v_mfma_f32_32x32x16_bf16 v[16:31], v[168:171], v[172:175], v[16:31]
	s_add_u32 m0, s11, 0x12000
	v_lshl_add_u64 v[162:163], v[68:69], 0, s[14:15]
	global_load_lds_dwordx4 v[162:163], off
	v_mfma_f32_32x32x16_bf16 v[0:15], v[168:171], v[176:179], v[0:15]
	ds_read_b128 v[164:167], v86
	ds_read_b128 v[168:171], v86 offset:4096
	ds_read_b128 v[172:175], v158
	ds_read_b128 v[176:179], v158 offset:4096
	s_waitcnt lgkmcnt(4)
	v_mfma_f32_32x32x16_bf16 v[48:63], v[180:183], v[218:221], v[48:63]
	s_mov_b32 s14, 0x1b80f80
	s_add_u32 m0, s11, 0x14000
	v_lshl_add_u64 v[160:161], v[66:67], 0, s[14:15]
	global_load_lds_dwordx4 v[160:161], off
	v_mfma_f32_32x32x16_bf16 v[32:47], v[180:183], v[222:225], v[32:47]
	v_mfma_f32_32x32x16_bf16 v[16:31], v[184:187], v[218:221], v[16:31]
	s_add_u32 m0, s11, 0x16000
	v_lshl_add_u64 v[162:163], v[64:65], 0, s[14:15]
	global_load_lds_dwordx4 v[162:163], off
	v_mfma_f32_32x32x16_bf16 v[0:15], v[184:187], v[222:225], v[0:15]
	ds_read_b128 v[180:183], v87
	ds_read_b128 v[184:187], v87 offset:4096
	ds_read_b128 v[218:221], v159
	ds_read_b128 v[222:225], v159 offset:4096
	s_waitcnt lgkmcnt(4)
	v_mfma_f32_32x32x16_bf16 v[48:63], v[164:167], v[172:175], v[48:63]
	v_mfma_f32_32x32x16_bf16 v[32:47], v[164:167], v[176:179], v[32:47]
	v_mfma_f32_32x32x16_bf16 v[16:31], v[168:171], v[172:175], v[16:31]
	v_mfma_f32_32x32x16_bf16 v[0:15], v[168:171], v[176:179], v[0:15]
	s_waitcnt vmcnt(6) lgkmcnt(0)
	s_barrier
;     ...
;   for (int kt = 0; kt < nk; ++kt) {
;     if (kt + 1 < nk) asm volatile("s_waitcnt vmcnt(6)" ::: "memory");
;     else asm volatile("s_waitcnt vmcnt(0)" ::: "memory");
;     __builtin_amdgcn_s_barrier();
;     asm volatile("" ::: "memory");
;     if (kt + 2 < nk) { const int st2 = (st >= 1) ? st - 1 : 2; GEMM_ISSUE(kt + 2, st2); }
;     const char* la = lds + st * STAGE_B;
;     const char* lb = la + 32768;
;     const unsigned sa_u = (unsigned)(size_t)la + arow_u, sb_u = (unsigned)(size_t)lb + brow_u;
;     const unsigned a0 = sa_u + co0, a1 = sa_u + co1, a2 = sa_u + co2, a3 = sa_u + co3;
;     const unsigned b0 = sb_u + co0, b1 = sb_u + co1, b2 = sb_u + co2, b3 = sb_u + co3;
;     {
;       bf16x8 p0, p1, q0, q1, u0, u1, w0, w1;
;       asm volatile(
;         "ds_read_b128 %4, %12\n\tds_read_b128 %5, %12 offset:4096\n\tds_read_b128 %6, %16\n\tds_read_b128 %7, %16 offset:4096\n\t"
;         "ds_read_b128 %8, %13\n\tds_read_b128 %9, %13 offset:4096\n\tds_read_b128 %10, %17\n\tds_read_b128 %11, %17 offset:4096\n\t"
;         "s_waitcnt lgkmcnt(4)\n\t"
;         "v_mfma_f32_32x32x16_bf16 %0, %4, %6, %0\n\tv_mfma_f32_32x32x16_bf16 %1, %4, %7, %1\n\tv_mfma_f32_32x32x16_bf16 %2, %5, %6, %2\n\tv_mfma_f32_32x32x16_bf16 %3, %5, %7, %3\n\t"
;         "ds_read_b128 %4, %14\n\tds_read_b128 %5, %14 offset:4096\n\tds_read_b128 %6, %18\n\tds_read_b128 %7, %18 offset:4096\n\t"
;         "s_waitcnt lgkmcnt(4)\n\t"
;         "v_mfma_f32_32x32x16_bf16 %0, %8, %10, %0\n\tv_mfma_f32_32x32x16_bf16 %1, %8, %11, %1\n\tv_mfma_f32_32x32x16_bf16 %2, %9, %10, %2\n\tv_mfma_f32_32x32x16_bf16 %3, %9, %11, %3\n\t"
;         "ds_read_b128 %8, %15\n\tds_read_b128 %9, %15 offset:4096\n\tds_read_b128 %10, %19\n\tds_read_b128 %11, %19 offset:4096\n\t"
;         "s_waitcnt lgkmcnt(4)\n\t"
;         "v_mfma_f32_32x32x16_bf16 %0, %4, %6, %0\n\tv_mfma_f32_32x32x16_bf16 %1, %4, %7, %1\n\tv_mfma_f32_32x32x16_bf16 %2, %5, %6, %2\n\tv_mfma_f32_32x32x16_bf16 %3, %5, %7, %3\n\t"
;         "s_waitcnt lgkmcnt(0)\n\t"
;         "v_mfma_f32_32x32x16_bf16 %0, %8, %10, %0\n\tv_mfma_f32_32x32x16_bf16 %1, %8, %11, %1\n\tv_mfma_f32_32x32x16_bf16 %2, %9, %10, %2\n\tv_mfma_f32_32x32x16_bf16 %3, %9, %11, %3"
;         : "+v"(acc[0][0]), "+v"(acc[0][1]), "+v"(acc[1][0]), "+v"(acc[1][1]),
;           "=&v"(p0), "=&v"(p1), "=&v"(q0), "=&v"(q1), "=&v"(u0), "=&v"(u1), "=&v"(w0), "=&v"(w1)
	ds_read_b128 v[164:167], v76
	ds_read_b128 v[168:171], v76 offset:4096
	ds_read_b128 v[172:175], v80
	ds_read_b128 v[176:179], v80 offset:4096
	v_mfma_f32_32x32x16_bf16 v[48:63], v[180:183], v[218:221], v[48:63]
	s_mov_b32 s14, 0xa5c3000
	s_add_u32 m0, s11, 0x18000
	v_lshl_add_u64 v[160:161], v[74:75], 0, s[14:15]
	global_load_lds_dwordx4 v[160:161], off
	v_mfma_f32_32x32x16_bf16 v[32:47], v[180:183], v[222:225], v[32:47]
	v_mfma_f32_32x32x16_bf16 v[16:31], v[184:187], v[218:221], v[16:31]
	s_add_u32 m0, s11, 0x1a000
	v_lshl_add_u64 v[162:163], v[72:73], 0, s[14:15]
	global_load_lds_dwordx4 v[162:163], off
	v_mfma_f32_32x32x16_bf16 v[0:15], v[184:187], v[222:225], v[0:15]
	ds_read_b128 v[180:183], v77
	ds_read_b128 v[184:187], v77 offset:4096
	ds_read_b128 v[218:221], v81
	ds_read_b128 v[222:225], v81 offset:4096
	s_waitcnt lgkmcnt(4)
	v_mfma_f32_32x32x16_bf16 v[48:63], v[164:167], v[172:175], v[48:63]
	s_add_u32 m0, s11, 0x1c000
	v_lshl_add_u64 v[160:161], v[70:71], 0, s[14:15]
	global_load_lds_dwordx4 v[160:161], off
	v_mfma_f32_32x32x16_bf16 v[32:47], v[164:167], v[176:179], v[32:47]
	v_mfma_f32_32x32x16_bf16 v[16:31], v[168:171], v[172:175], v[16:31]
	s_add_u32 m0, s11, 0x1e000
	v_lshl_add_u64 v[162:163], v[68:69], 0, s[14:15]
	global_load_lds_dwordx4 v[162:163], off
	v_mfma_f32_32x32x16_bf16 v[0:15], v[168:171], v[176:179], v[0:15]
	ds_read_b128 v[164:167], v78
	ds_read_b128 v[168:171], v78 offset:4096
	ds_read_b128 v[172:175], v82
	ds_read_b128 v[176:179], v82 offset:4096
	s_waitcnt lgkmcnt(4)
	v_mfma_f32_32x32x16_bf16 v[48:63], v[180:183], v[218:221], v[48:63]
	s_mov_b32 s14, 0x1b81000
	s_add_u32 m0, s11, 0x20000
	v_lshl_add_u64 v[160:161], v[66:67], 0, s[14:15]
	global_load_lds_dwordx4 v[160:161], off
	v_mfma_f32_32x32x16_bf16 v[32:47], v[180:183], v[222:225], v[32:47]
	v_mfma_f32_32x32x16_bf16 v[16:31], v[184:187], v[218:221], v[16:31]
	s_add_u32 m0, s11, 0x22000
	v_lshl_add_u64 v[162:163], v[64:65], 0, s[14:15]
	global_load_lds_dwordx4 v[162:163], off
	v_mfma_f32_32x32x16_bf16 v[0:15], v[184:187], v[222:225], v[0:15]
	ds_read_b128 v[180:183], v79
	ds_read_b128 v[184:187], v79 offset:4096
	ds_read_b128 v[218:221], v83
	ds_read_b128 v[222:225], v83 offset:4096
	s_waitcnt lgkmcnt(4)
	v_mfma_f32_32x32x16_bf16 v[48:63], v[164:167], v[172:175], v[48:63]
	v_mfma_f32_32x32x16_bf16 v[32:47], v[164:167], v[176:179], v[32:47]
	v_mfma_f32_32x32x16_bf16 v[16:31], v[168:171], v[172:175], v[16:31]
	v_mfma_f32_32x32x16_bf16 v[0:15], v[168:171], v[176:179], v[0:15]
	s_waitcnt vmcnt(6) lgkmcnt(0)
	s_barrier
	ds_read_b128 v[164:167], v76 offset:49152
	ds_read_b128 v[168:171], v76 offset:53248
	ds_read_b128 v[172:175], v80 offset:49152
	ds_read_b128 v[176:179], v80 offset:53248
	v_mfma_f32_32x32x16_bf16 v[48:63], v[180:183], v[218:221], v[48:63]
	s_mov_b32 s14, 0xa5c3080
	s_mov_b32 m0, s11
	v_lshl_add_u64 v[160:161], v[74:75], 0, s[14:15]
	global_load_lds_dwordx4 v[160:161], off
	v_mfma_f32_32x32x16_bf16 v[32:47], v[180:183], v[222:225], v[32:47]
	v_mfma_f32_32x32x16_bf16 v[16:31], v[184:187], v[218:221], v[16:31]
	s_add_u32 m0, s11, 0x2000
	v_lshl_add_u64 v[162:163], v[72:73], 0, s[14:15]
	global_load_lds_dwordx4 v[162:163], off
	v_mfma_f32_32x32x16_bf16 v[0:15], v[184:187], v[222:225], v[0:15]
	ds_read_b128 v[180:183], v77 offset:49152
	ds_read_b128 v[184:187], v77 offset:53248
	ds_read_b128 v[218:221], v81 offset:49152
	ds_read_b128 v[222:225], v81 offset:53248
	s_waitcnt lgkmcnt(4)
	v_mfma_f32_32x32x16_bf16 v[48:63], v[164:167], v[172:175], v[48:63]
	s_add_u32 m0, s11, 0x4000
	v_lshl_add_u64 v[160:161], v[70:71], 0, s[14:15]
	global_load_lds_dwordx4 v[160:161], off
	v_mfma_f32_32x32x16_bf16 v[32:47], v[164:167], v[176:179], v[32:47]
	v_mfma_f32_32x32x16_bf16 v[16:31], v[168:171], v[172:175], v[16:31]
	s_add_u32 m0, s11, 0x6000
	v_lshl_add_u64 v[162:163], v[68:69], 0, s[14:15]
	global_load_lds_dwordx4 v[162:163], off
	v_mfma_f32_32x32x16_bf16 v[0:15], v[168:171], v[176:179], v[0:15]
	ds_read_b128 v[164:167], v78 offset:49152
	ds_read_b128 v[168:171], v78 offset:53248
	ds_read_b128 v[172:175], v82 offset:49152
	ds_read_b128 v[176:179], v82 offset:53248
	s_waitcnt lgkmcnt(4)
	v_mfma_f32_32x32x16_bf16 v[48:63], v[180:183], v[218:221], v[48:63]
	s_mov_b32 s14, 0x1b81080
	s_add_u32 m0, s11, 0x8000
	v_lshl_add_u64 v[160:161], v[66:67], 0, s[14:15]
	global_load_lds_dwordx4 v[160:161], off
	v_mfma_f32_32x32x16_bf16 v[32:47], v[180:183], v[222:225], v[32:47]
	v_mfma_f32_32x32x16_bf16 v[16:31], v[184:187], v[218:221], v[16:31]
	s_add_u32 m0, s11, 0xa000
	v_lshl_add_u64 v[162:163], v[64:65], 0, s[14:15]
	global_load_lds_dwordx4 v[162:163], off
	v_mfma_f32_32x32x16_bf16 v[0:15], v[184:187], v[222:225], v[0:15]
	ds_read_b128 v[180:183], v79 offset:49152
	ds_read_b128 v[184:187], v79 offset:53248
	ds_read_b128 v[218:221], v83 offset:49152
	ds_read_b128 v[222:225], v83 offset:53248
	s_waitcnt lgkmcnt(4)
	v_mfma_f32_32x32x16_bf16 v[48:63], v[164:167], v[172:175], v[48:63]
	v_mfma_f32_32x32x16_bf16 v[32:47], v[164:167], v[176:179], v[32:47]
	v_mfma_f32_32x32x16_bf16 v[16:31], v[168:171], v[172:175], v[16:31]
	v_mfma_f32_32x32x16_bf16 v[0:15], v[168:171], v[176:179], v[0:15]
	s_waitcnt vmcnt(6) lgkmcnt(0)
	s_barrier
;     ...
;   for (int kt = 0; kt < nk; ++kt) {
;     if (kt + 1 < nk) asm volatile("s_waitcnt vmcnt(6)" ::: "memory");
;     else asm volatile("s_waitcnt vmcnt(0)" ::: "memory");
;     __builtin_amdgcn_s_barrier();
;     asm volatile("" ::: "memory");
;     if (kt + 2 < nk) { const int st2 = (st >= 1) ? st - 1 : 2; GEMM_ISSUE(kt + 2, st2); }
;     const char* la = lds + st * STAGE_B;
;     const char* lb = la + 32768;
;     const unsigned sa_u = (unsigned)(size_t)la + arow_u, sb_u = (unsigned)(size_t)lb + brow_u;
;     const unsigned a0 = sa_u + co0, a1 = sa_u + co1, a2 = sa_u + co2, a3 = sa_u + co3;
;     const unsigned b0 = sb_u + co0, b1 = sb_u + co1, b2 = sb_u + co2, b3 = sb_u + co3;
;     {
;       bf16x8 p0, p1, q0, q1, u0, u1, w0, w1;
;       asm volatile(
;         "ds_read_b128 %4, %12\n\tds_read_b128 %5, %12 offset:4096\n\tds_read_b128 %6, %16\n\tds_read_b128 %7, %16 offset:4096\n\t"
;         "ds_read_b128 %8, %13\n\tds_read_b128 %9, %13 offset:4096\n\tds_read_b128 %10, %17\n\tds_read_b128 %11, %17 offset:4096\n\t"
;         "s_waitcnt lgkmcnt(4)\n\t"
;         "v_mfma_f32_32x32x16_bf16 %0, %4, %6, %0\n\tv_mfma_f32_32x32x16_bf16 %1, %4, %7, %1\n\tv_mfma_f32_32x32x16_bf16 %2, %5, %6, %2\n\tv_mfma_f32_32x32x16_bf16 %3, %5, %7, %3\n\t"
;         "ds_read_b128 %4, %14\n\tds_read_b128 %5, %14 offset:4096\n\tds_read_b128 %6, %18\n\tds_read_b128 %7, %18 offset:4096\n\t"
;         "s_waitcnt lgkmcnt(4)\n\t"
;         "v_mfma_f32_32x32x16_bf16 %0, %8, %10, %0\n\tv_mfma_f32_32x32x16_bf16 %1, %8, %11, %1\n\tv_mfma_f32_32x32x16_bf16 %2, %9, %10, %2\n\tv_mfma_f32_32x32x16_bf16 %3, %9, %11, %3\n\t"
;         "ds_read_b128 %8, %15\n\tds_read_b128 %9, %15 offset:4096\n\tds_read_b128 %10, %19\n\tds_read_b128 %11, %19 offset:4096\n\t"
;         "s_waitcnt lgkmcnt(4)\n\t"
;         "v_mfma_f32_32x32x16_bf16 %0, %4, %6, %0\n\tv_mfma_f32_32x32x16_bf16 %1, %4, %7, %1\n\tv_mfma_f32_32x32x16_bf16 %2, %5, %6, %2\n\tv_mfma_f32_32x32x16_bf16 %3, %5, %7, %3\n\t"
;         "s_waitcnt lgkmcnt(0)\n\t"
;         "v_mfma_f32_32x32x16_bf16 %0, %8, %10, %0\n\tv_mfma_f32_32x32x16_bf16 %1, %8, %11, %1\n\tv_mfma_f32_32x32x16_bf16 %2, %9, %10, %2\n\tv_mfma_f32_32x32x16_bf16 %3, %9, %11, %3"
;         : "+v"(acc[0][0]), "+v"(acc[0][1]), "+v"(acc[1][0]), "+v"(acc[1][1]),
;           "=&v"(p0), "=&v"(p1), "=&v"(q0), "=&v"(q1), "=&v"(u0), "=&v"(u1), "=&v"(w0), "=&v"(w1)
	ds_read_b128 v[164:167], v84
	ds_read_b128 v[168:171], v84 offset:4096
	ds_read_b128 v[172:175], v156
	ds_read_b128 v[176:179], v156 offset:4096
	v_mfma_f32_32x32x16_bf16 v[48:63], v[180:183], v[218:221], v[48:63]
	s_mov_b32 s14, 0xa5c3100
	s_add_u32 m0, s11, 0xc000
	v_lshl_add_u64 v[160:161], v[74:75], 0, s[14:15]
	global_load_lds_dwordx4 v[160:161], off
	v_mfma_f32_32x32x16_bf16 v[32:47], v[180:183], v[222:225], v[32:47]
	v_mfma_f32_32x32x16_bf16 v[16:31], v[184:187], v[218:221], v[16:31]
	s_add_u32 m0, s11, 0xe000
	v_lshl_add_u64 v[162:163], v[72:73], 0, s[14:15]
	global_load_lds_dwordx4 v[162:163], off
	v_mfma_f32_32x32x16_bf16 v[0:15], v[184:187], v[222:225], v[0:15]
	ds_read_b128 v[180:183], v85
	ds_read_b128 v[184:187], v85 offset:4096
	ds_read_b128 v[218:221], v157
	ds_read_b128 v[222:225], v157 offset:4096
	s_waitcnt lgkmcnt(4)
	v_mfma_f32_32x32x16_bf16 v[48:63], v[164:167], v[172:175], v[48:63]
	s_add_u32 m0, s11, 0x10000
	v_lshl_add_u64 v[160:161], v[70:71], 0, s[14:15]
	global_load_lds_dwordx4 v[160:161], off
	v_mfma_f32_32x32x16_bf16 v[32:47], v[164:167], v[176:179], v[32:47]
	v_mfma_f32_32x32x16_bf16 v[16:31], v[168:171], v[172:175], v[16:31]
	s_add_u32 m0, s11, 0x12000
	v_lshl_add_u64 v[162:163], v[68:69], 0, s[14:15]
	global_load_lds_dwordx4 v[162:163], off
	v_mfma_f32_32x32x16_bf16 v[0:15], v[168:171], v[176:179], v[0:15]
	ds_read_b128 v[164:167], v86
	ds_read_b128 v[168:171], v86 offset:4096
	ds_read_b128 v[172:175], v158
	ds_read_b128 v[176:179], v158 offset:4096
	s_waitcnt lgkmcnt(4)
	v_mfma_f32_32x32x16_bf16 v[48:63], v[180:183], v[218:221], v[48:63]
	s_mov_b32 s14, 0x1b81100
	s_add_u32 m0, s11, 0x14000
	v_lshl_add_u64 v[160:161], v[66:67], 0, s[14:15]
	global_load_lds_dwordx4 v[160:161], off
	v_mfma_f32_32x32x16_bf16 v[32:47], v[180:183], v[222:225], v[32:47]
	v_mfma_f32_32x32x16_bf16 v[16:31], v[184:187], v[218:221], v[16:31]
	s_add_u32 m0, s11, 0x16000
	v_lshl_add_u64 v[162:163], v[64:65], 0, s[14:15]
	global_load_lds_dwordx4 v[162:163], off
	v_mfma_f32_32x32x16_bf16 v[0:15], v[184:187], v[222:225], v[0:15]
	ds_read_b128 v[180:183], v87
	ds_read_b128 v[184:187], v87 offset:4096
	ds_read_b128 v[218:221], v159
	ds_read_b128 v[222:225], v159 offset:4096
	s_waitcnt lgkmcnt(4)
	v_mfma_f32_32x32x16_bf16 v[48:63], v[164:167], v[172:175], v[48:63]
	v_mfma_f32_32x32x16_bf16 v[32:47], v[164:167], v[176:179], v[32:47]
	v_mfma_f32_32x32x16_bf16 v[16:31], v[168:171], v[172:175], v[16:31]
	v_mfma_f32_32x32x16_bf16 v[0:15], v[168:171], v[176:179], v[0:15]
	s_waitcnt vmcnt(6) lgkmcnt(0)
	s_barrier
	ds_read_b128 v[164:167], v76
	ds_read_b128 v[168:171], v76 offset:4096
	ds_read_b128 v[172:175], v80
	ds_read_b128 v[176:179], v80 offset:4096
	v_mfma_f32_32x32x16_bf16 v[48:63], v[180:183], v[218:221], v[48:63]
	s_mov_b32 s14, 0xa5c3180
	s_add_u32 m0, s11, 0x18000
	v_lshl_add_u64 v[160:161], v[74:75], 0, s[14:15]
	global_load_lds_dwordx4 v[160:161], off
	v_mfma_f32_32x32x16_bf16 v[32:47], v[180:183], v[222:225], v[32:47]
	v_mfma_f32_32x32x16_bf16 v[16:31], v[184:187], v[218:221], v[16:31]
	s_add_u32 m0, s11, 0x1a000
	v_lshl_add_u64 v[162:163], v[72:73], 0, s[14:15]
	global_load_lds_dwordx4 v[162:163], off
	v_mfma_f32_32x32x16_bf16 v[0:15], v[184:187], v[222:225], v[0:15]
	ds_read_b128 v[180:183], v77
	ds_read_b128 v[184:187], v77 offset:4096
	ds_read_b128 v[218:221], v81
	ds_read_b128 v[222:225], v81 offset:4096
	s_waitcnt lgkmcnt(4)
	v_mfma_f32_32x32x16_bf16 v[48:63], v[164:167], v[172:175], v[48:63]
	s_add_u32 m0, s11, 0x1c000
	v_lshl_add_u64 v[160:161], v[70:71], 0, s[14:15]
	global_load_lds_dwordx4 v[160:161], off
	v_mfma_f32_32x32x16_bf16 v[32:47], v[164:167], v[176:179], v[32:47]
	v_mfma_f32_32x32x16_bf16 v[16:31], v[168:171], v[172:175], v[16:31]
	s_add_u32 m0, s11, 0x1e000
	v_lshl_add_u64 v[162:163], v[68:69], 0, s[14:15]
	global_load_lds_dwordx4 v[162:163], off
	v_mfma_f32_32x32x16_bf16 v[0:15], v[168:171], v[176:179], v[0:15]
	ds_read_b128 v[164:167], v78
	ds_read_b128 v[168:171], v78 offset:4096
	ds_read_b128 v[172:175], v82
	ds_read_b128 v[176:179], v82 offset:4096
	s_waitcnt lgkmcnt(4)
	v_mfma_f32_32x32x16_bf16 v[48:63], v[180:183], v[218:221], v[48:63]
	s_mov_b32 s14, 0x1b81180
	s_add_u32 m0, s11, 0x20000
	v_lshl_add_u64 v[160:161], v[66:67], 0, s[14:15]
	global_load_lds_dwordx4 v[160:161], off
	v_mfma_f32_32x32x16_bf16 v[32:47], v[180:183], v[222:225], v[32:47]
	v_mfma_f32_32x32x16_bf16 v[16:31], v[184:187], v[218:221], v[16:31]
	s_add_u32 m0, s11, 0x22000
	v_lshl_add_u64 v[162:163], v[64:65], 0, s[14:15]
	global_load_lds_dwordx4 v[162:163], off
	v_mfma_f32_32x32x16_bf16 v[0:15], v[184:187], v[222:225], v[0:15]
	ds_read_b128 v[180:183], v79
	ds_read_b128 v[184:187], v79 offset:4096
	ds_read_b128 v[218:221], v83
	ds_read_b128 v[222:225], v83 offset:4096
	s_waitcnt lgkmcnt(4)
	v_mfma_f32_32x32x16_bf16 v[48:63], v[164:167], v[172:175], v[48:63]
	v_mfma_f32_32x32x16_bf16 v[32:47], v[164:167], v[176:179], v[32:47]
	v_mfma_f32_32x32x16_bf16 v[16:31], v[168:171], v[172:175], v[16:31]
	v_mfma_f32_32x32x16_bf16 v[0:15], v[168:171], v[176:179], v[0:15]
	s_waitcnt vmcnt(6) lgkmcnt(0)
	s_barrier
;     ...
;   for (int kt = 0; kt < nk; ++kt) {
;     if (kt + 1 < nk) asm volatile("s_waitcnt vmcnt(6)" ::: "memory");
;     else asm volatile("s_waitcnt vmcnt(0)" ::: "memory");
;     __builtin_amdgcn_s_barrier();
;     asm volatile("" ::: "memory");
;     if (kt + 2 < nk) { const int st2 = (st >= 1) ? st - 1 : 2; GEMM_ISSUE(kt + 2, st2); }
;     const char* la = lds + st * STAGE_B;
;     const char* lb = la + 32768;
;     const unsigned sa_u = (unsigned)(size_t)la + arow_u, sb_u = (unsigned)(size_t)lb + brow_u;
;     const unsigned a0 = sa_u + co0, a1 = sa_u + co1, a2 = sa_u + co2, a3 = sa_u + co3;
;     const unsigned b0 = sb_u + co0, b1 = sb_u + co1, b2 = sb_u + co2, b3 = sb_u + co3;
;     {
;       bf16x8 p0, p1, q0, q1, u0, u1, w0, w1;
;       asm volatile(
;         "ds_read_b128 %4, %12\n\tds_read_b128 %5, %12 offset:4096\n\tds_read_b128 %6, %16\n\tds_read_b128 %7, %16 offset:4096\n\t"
;         "ds_read_b128 %8, %13\n\tds_read_b128 %9, %13 offset:4096\n\tds_read_b128 %10, %17\n\tds_read_b128 %11, %17 offset:4096\n\t"
;         "s_waitcnt lgkmcnt(4)\n\t"
;         "v_mfma_f32_32x32x16_bf16 %0, %4, %6, %0\n\tv_mfma_f32_32x32x16_bf16 %1, %4, %7, %1\n\tv_mfma_f32_32x32x16_bf16 %2, %5, %6, %2\n\tv_mfma_f32_32x32x16_bf16 %3, %5, %7, %3\n\t"
;         "ds_read_b128 %4, %14\n\tds_read_b128 %5, %14 offset:4096\n\tds_read_b128 %6, %18\n\tds_read_b128 %7, %18 offset:4096\n\t"
;         "s_waitcnt lgkmcnt(4)\n\t"
;         "v_mfma_f32_32x32x16_bf16 %0, %8, %10, %0\n\tv_mfma_f32_32x32x16_bf16 %1, %8, %11, %1\n\tv_mfma_f32_32x32x16_bf16 %2, %9, %10, %2\n\tv_mfma_f32_32x32x16_bf16 %3, %9, %11, %3\n\t"
;         "ds_read_b128 %8, %15\n\tds_read_b128 %9, %15 offset:4096\n\tds_read_b128 %10, %19\n\tds_read_b128 %11, %19 offset:4096\n\t"
;         "s_waitcnt lgkmcnt(4)\n\t"
;         "v_mfma_f32_32x32x16_bf16 %0, %4, %6, %0\n\tv_mfma_f32_32x32x16_bf16 %1, %4, %7, %1\n\tv_mfma_f32_32x32x16_bf16 %2, %5, %6, %2\n\tv_mfma_f32_32x32x16_bf16 %3, %5, %7, %3\n\t"
;         "s_waitcnt lgkmcnt(0)\n\t"
;         "v_mfma_f32_32x32x16_bf16 %0, %8, %10, %0\n\tv_mfma_f32_32x32x16_bf16 %1, %8, %11, %1\n\tv_mfma_f32_32x32x16_bf16 %2, %9, %10, %2\n\tv_mfma_f32_32x32x16_bf16 %3, %9, %11, %3"
;         : "+v"(acc[0][0]), "+v"(acc[0][1]), "+v"(acc[1][0]), "+v"(acc[1][1]),
;           "=&v"(p0), "=&v"(p1), "=&v"(q0), "=&v"(q1), "=&v"(u0), "=&v"(u1), "=&v"(w0), "=&v"(w1)
	ds_read_b128 v[164:167], v76 offset:49152
	ds_read_b128 v[168:171], v76 offset:53248
	ds_read_b128 v[172:175], v80 offset:49152
	ds_read_b128 v[176:179], v80 offset:53248
	v_mfma_f32_32x32x16_bf16 v[48:63], v[180:183], v[218:221], v[48:63]
	s_mov_b32 s14, 0xa5c3200
	s_mov_b32 m0, s11
	v_lshl_add_u64 v[160:161], v[74:75], 0, s[14:15]
	global_load_lds_dwordx4 v[160:161], off
	v_mfma_f32_32x32x16_bf16 v[32:47], v[180:183], v[222:225], v[32:47]
	v_mfma_f32_32x32x16_bf16 v[16:31], v[184:187], v[218:221], v[16:31]
	s_add_u32 m0, s11, 0x2000
	v_lshl_add_u64 v[162:163], v[72:73], 0, s[14:15]
	global_load_lds_dwordx4 v[162:163], off
	v_mfma_f32_32x32x16_bf16 v[0:15], v[184:187], v[222:225], v[0:15]
	ds_read_b128 v[180:183], v77 offset:49152
	ds_read_b128 v[184:187], v77 offset:53248
	ds_read_b128 v[218:221], v81 offset:49152
	ds_read_b128 v[222:225], v81 offset:53248
	s_waitcnt lgkmcnt(4)
	v_mfma_f32_32x32x16_bf16 v[48:63], v[164:167], v[172:175], v[48:63]
	s_add_u32 m0, s11, 0x4000
	v_lshl_add_u64 v[160:161], v[70:71], 0, s[14:15]
	global_load_lds_dwordx4 v[160:161], off
	v_mfma_f32_32x32x16_bf16 v[32:47], v[164:167], v[176:179], v[32:47]
	v_mfma_f32_32x32x16_bf16 v[16:31], v[168:171], v[172:175], v[16:31]
	s_add_u32 m0, s11, 0x6000
	v_lshl_add_u64 v[162:163], v[68:69], 0, s[14:15]
	global_load_lds_dwordx4 v[162:163], off
	v_mfma_f32_32x32x16_bf16 v[0:15], v[168:171], v[176:179], v[0:15]
	ds_read_b128 v[164:167], v78 offset:49152
	ds_read_b128 v[168:171], v78 offset:53248
	ds_read_b128 v[172:175], v82 offset:49152
	ds_read_b128 v[176:179], v82 offset:53248
	s_waitcnt lgkmcnt(4)
	v_mfma_f32_32x32x16_bf16 v[48:63], v[180:183], v[218:221], v[48:63]
	s_mov_b32 s14, 0x1b81200
	s_add_u32 m0, s11, 0x8000
	v_lshl_add_u64 v[160:161], v[66:67], 0, s[14:15]
	global_load_lds_dwordx4 v[160:161], off
	v_mfma_f32_32x32x16_bf16 v[32:47], v[180:183], v[222:225], v[32:47]
	v_mfma_f32_32x32x16_bf16 v[16:31], v[184:187], v[218:221], v[16:31]
	s_add_u32 m0, s11, 0xa000
	v_lshl_add_u64 v[162:163], v[64:65], 0, s[14:15]
	global_load_lds_dwordx4 v[162:163], off
	v_mfma_f32_32x32x16_bf16 v[0:15], v[184:187], v[222:225], v[0:15]
	ds_read_b128 v[180:183], v79 offset:49152
	ds_read_b128 v[184:187], v79 offset:53248
	ds_read_b128 v[218:221], v83 offset:49152
	ds_read_b128 v[222:225], v83 offset:53248
	s_waitcnt lgkmcnt(4)
	v_mfma_f32_32x32x16_bf16 v[48:63], v[164:167], v[172:175], v[48:63]
	v_mfma_f32_32x32x16_bf16 v[32:47], v[164:167], v[176:179], v[32:47]
	v_mfma_f32_32x32x16_bf16 v[16:31], v[168:171], v[172:175], v[16:31]
	v_mfma_f32_32x32x16_bf16 v[0:15], v[168:171], v[176:179], v[0:15]
	s_waitcnt vmcnt(6) lgkmcnt(0)
	s_barrier
	ds_read_b128 v[164:167], v84
	ds_read_b128 v[168:171], v84 offset:4096
	ds_read_b128 v[172:175], v156
	ds_read_b128 v[176:179], v156 offset:4096
	v_mfma_f32_32x32x16_bf16 v[48:63], v[180:183], v[218:221], v[48:63]
	s_mov_b32 s14, 0xa5c3280
	s_add_u32 m0, s11, 0xc000
	v_lshl_add_u64 v[160:161], v[74:75], 0, s[14:15]
	global_load_lds_dwordx4 v[160:161], off
	v_mfma_f32_32x32x16_bf16 v[32:47], v[180:183], v[222:225], v[32:47]
	v_mfma_f32_32x32x16_bf16 v[16:31], v[184:187], v[218:221], v[16:31]
	s_add_u32 m0, s11, 0xe000
	v_lshl_add_u64 v[162:163], v[72:73], 0, s[14:15]
	global_load_lds_dwordx4 v[162:163], off
	v_mfma_f32_32x32x16_bf16 v[0:15], v[184:187], v[222:225], v[0:15]
	ds_read_b128 v[180:183], v85
	ds_read_b128 v[184:187], v85 offset:4096
	ds_read_b128 v[218:221], v157
	ds_read_b128 v[222:225], v157 offset:4096
	s_waitcnt lgkmcnt(4)
	v_mfma_f32_32x32x16_bf16 v[48:63], v[164:167], v[172:175], v[48:63]
	s_add_u32 m0, s11, 0x10000
	v_lshl_add_u64 v[160:161], v[70:71], 0, s[14:15]
	global_load_lds_dwordx4 v[160:161], off
	v_mfma_f32_32x32x16_bf16 v[32:47], v[164:167], v[176:179], v[32:47]
	v_mfma_f32_32x32x16_bf16 v[16:31], v[168:171], v[172:175], v[16:31]
	s_add_u32 m0, s11, 0x12000
	v_lshl_add_u64 v[162:163], v[68:69], 0, s[14:15]
	global_load_lds_dwordx4 v[162:163], off
	v_mfma_f32_32x32x16_bf16 v[0:15], v[168:171], v[176:179], v[0:15]
	ds_read_b128 v[164:167], v86
	ds_read_b128 v[168:171], v86 offset:4096
	ds_read_b128 v[172:175], v158
	ds_read_b128 v[176:179], v158 offset:4096
	s_waitcnt lgkmcnt(4)
	v_mfma_f32_32x32x16_bf16 v[48:63], v[180:183], v[218:221], v[48:63]
	s_mov_b32 s14, 0x1b81280
	s_add_u32 m0, s11, 0x14000
	v_lshl_add_u64 v[160:161], v[66:67], 0, s[14:15]
	global_load_lds_dwordx4 v[160:161], off
	v_mfma_f32_32x32x16_bf16 v[32:47], v[180:183], v[222:225], v[32:47]
	v_mfma_f32_32x32x16_bf16 v[16:31], v[184:187], v[218:221], v[16:31]
	s_add_u32 m0, s11, 0x16000
	v_lshl_add_u64 v[162:163], v[64:65], 0, s[14:15]
	global_load_lds_dwordx4 v[162:163], off
	v_mfma_f32_32x32x16_bf16 v[0:15], v[184:187], v[222:225], v[0:15]
	ds_read_b128 v[180:183], v87
	ds_read_b128 v[184:187], v87 offset:4096
	ds_read_b128 v[218:221], v159
	ds_read_b128 v[222:225], v159 offset:4096
	s_waitcnt lgkmcnt(4)
	v_mfma_f32_32x32x16_bf16 v[48:63], v[164:167], v[172:175], v[48:63]
	v_mfma_f32_32x32x16_bf16 v[32:47], v[164:167], v[176:179], v[32:47]
	v_mfma_f32_32x32x16_bf16 v[16:31], v[168:171], v[172:175], v[16:31]
	v_mfma_f32_32x32x16_bf16 v[0:15], v[168:171], v[176:179], v[0:15]
	s_waitcnt vmcnt(6) lgkmcnt(0)
	s_barrier
;     ...
;   for (int kt = 0; kt < nk; ++kt) {
;     if (kt + 1 < nk) asm volatile("s_waitcnt vmcnt(6)" ::: "memory");
;     else asm volatile("s_waitcnt vmcnt(0)" ::: "memory");
;     __builtin_amdgcn_s_barrier();
;     asm volatile("" ::: "memory");
;     if (kt + 2 < nk) { const int st2 = (st >= 1) ? st - 1 : 2; GEMM_ISSUE(kt + 2, st2); }
;     const char* la = lds + st * STAGE_B;
;     const char* lb = la + 32768;
;     const unsigned sa_u = (unsigned)(size_t)la + arow_u, sb_u = (unsigned)(size_t)lb + brow_u;
;     const unsigned a0 = sa_u + co0, a1 = sa_u + co1, a2 = sa_u + co2, a3 = sa_u + co3;
;     const unsigned b0 = sb_u + co0, b1 = sb_u + co1, b2 = sb_u + co2, b3 = sb_u + co3;
;     {
;       bf16x8 p0, p1, q0, q1, u0, u1, w0, w1;
;       asm volatile(
;         "ds_read_b128 %4, %12\n\tds_read_b128 %5, %12 offset:4096\n\tds_read_b128 %6, %16\n\tds_read_b128 %7, %16 offset:4096\n\t"
;         "ds_read_b128 %8, %13\n\tds_read_b128 %9, %13 offset:4096\n\tds_read_b128 %10, %17\n\tds_read_b128 %11, %17 offset:4096\n\t"
;         "s_waitcnt lgkmcnt(4)\n\t"
;         "v_mfma_f32_32x32x16_bf16 %0, %4, %6, %0\n\tv_mfma_f32_32x32x16_bf16 %1, %4, %7, %1\n\tv_mfma_f32_32x32x16_bf16 %2, %5, %6, %2\n\tv_mfma_f32_32x32x16_bf16 %3, %5, %7, %3\n\t"
;         "ds_read_b128 %4, %14\n\tds_read_b128 %5, %14 offset:4096\n\tds_read_b128 %6, %18\n\tds_read_b128 %7, %18 offset:4096\n\t"
;         "s_waitcnt lgkmcnt(4)\n\t"
;         "v_mfma_f32_32x32x16_bf16 %0, %8, %10, %0\n\tv_mfma_f32_32x32x16_bf16 %1, %8, %11, %1\n\tv_mfma_f32_32x32x16_bf16 %2, %9, %10, %2\n\tv_mfma_f32_32x32x16_bf16 %3, %9, %11, %3\n\t"
;         "ds_read_b128 %8, %15\n\tds_read_b128 %9, %15 offset:4096\n\tds_read_b128 %10, %19\n\tds_read_b128 %11, %19 offset:4096\n\t"
;         "s_waitcnt lgkmcnt(4)\n\t"
;         "v_mfma_f32_32x32x16_bf16 %0, %4, %6, %0\n\tv_mfma_f32_32x32x16_bf16 %1, %4, %7, %1\n\tv_mfma_f32_32x32x16_bf16 %2, %5, %6, %2\n\tv_mfma_f32_32x32x16_bf16 %3, %5, %7, %3\n\t"
;         "s_waitcnt lgkmcnt(0)\n\t"
;         "v_mfma_f32_32x32x16_bf16 %0, %8, %10, %0\n\tv_mfma_f32_32x32x16_bf16 %1, %8, %11, %1\n\tv_mfma_f32_32x32x16_bf16 %2, %9, %10, %2\n\tv_mfma_f32_32x32x16_bf16 %3, %9, %11, %3"
;         : "+v"(acc[0][0]), "+v"(acc[0][1]), "+v"(acc[1][0]), "+v"(acc[1][1]),
;           "=&v"(p0), "=&v"(p1), "=&v"(q0), "=&v"(q1), "=&v"(u0), "=&v"(u1), "=&v"(w0), "=&v"(w1)
	ds_read_b128 v[164:167], v76
	ds_read_b128 v[168:171], v76 offset:4096
	ds_read_b128 v[172:175], v80
	ds_read_b128 v[176:179], v80 offset:4096
	v_mfma_f32_32x32x16_bf16 v[48:63], v[180:183], v[218:221], v[48:63]
	s_mov_b32 s14, 0xa5c3300
	s_add_u32 m0, s11, 0x18000
	v_lshl_add_u64 v[160:161], v[74:75], 0, s[14:15]
	global_load_lds_dwordx4 v[160:161], off
	v_mfma_f32_32x32x16_bf16 v[32:47], v[180:183], v[222:225], v[32:47]
	v_mfma_f32_32x32x16_bf16 v[16:31], v[184:187], v[218:221], v[16:31]
	s_add_u32 m0, s11, 0x1a000
	v_lshl_add_u64 v[162:163], v[72:73], 0, s[14:15]
	global_load_lds_dwordx4 v[162:163], off
	v_mfma_f32_32x32x16_bf16 v[0:15], v[184:187], v[222:225], v[0:15]
	ds_read_b128 v[180:183], v77
	ds_read_b128 v[184:187], v77 offset:4096
	ds_read_b128 v[218:221], v81
	ds_read_b128 v[222:225], v81 offset:4096
	s_waitcnt lgkmcnt(4)
	v_mfma_f32_32x32x16_bf16 v[48:63], v[164:167], v[172:175], v[48:63]
	s_add_u32 m0, s11, 0x1c000
	v_lshl_add_u64 v[160:161], v[70:71], 0, s[14:15]
	global_load_lds_dwordx4 v[160:161], off
	v_mfma_f32_32x32x16_bf16 v[32:47], v[164:167], v[176:179], v[32:47]
	v_mfma_f32_32x32x16_bf16 v[16:31], v[168:171], v[172:175], v[16:31]
	s_add_u32 m0, s11, 0x1e000
	v_lshl_add_u64 v[162:163], v[68:69], 0, s[14:15]
	global_load_lds_dwordx4 v[162:163], off
	v_mfma_f32_32x32x16_bf16 v[0:15], v[168:171], v[176:179], v[0:15]
	ds_read_b128 v[164:167], v78
	ds_read_b128 v[168:171], v78 offset:4096
	ds_read_b128 v[172:175], v82
	ds_read_b128 v[176:179], v82 offset:4096
	s_waitcnt lgkmcnt(4)
	v_mfma_f32_32x32x16_bf16 v[48:63], v[180:183], v[218:221], v[48:63]
	s_mov_b32 s14, 0x1b81300
	s_add_u32 m0, s11, 0x20000
	v_lshl_add_u64 v[160:161], v[66:67], 0, s[14:15]
	global_load_lds_dwordx4 v[160:161], off
	v_mfma_f32_32x32x16_bf16 v[32:47], v[180:183], v[222:225], v[32:47]
	v_mfma_f32_32x32x16_bf16 v[16:31], v[184:187], v[218:221], v[16:31]
	s_add_u32 m0, s11, 0x22000
	v_lshl_add_u64 v[162:163], v[64:65], 0, s[14:15]
	global_load_lds_dwordx4 v[162:163], off
	v_mfma_f32_32x32x16_bf16 v[0:15], v[184:187], v[222:225], v[0:15]
	ds_read_b128 v[180:183], v79
	ds_read_b128 v[184:187], v79 offset:4096
	ds_read_b128 v[218:221], v83
	ds_read_b128 v[222:225], v83 offset:4096
	s_waitcnt lgkmcnt(4)
	v_mfma_f32_32x32x16_bf16 v[48:63], v[164:167], v[172:175], v[48:63]
	v_mfma_f32_32x32x16_bf16 v[32:47], v[164:167], v[176:179], v[32:47]
	v_mfma_f32_32x32x16_bf16 v[16:31], v[168:171], v[172:175], v[16:31]
	v_mfma_f32_32x32x16_bf16 v[0:15], v[168:171], v[176:179], v[0:15]
	s_waitcnt vmcnt(6) lgkmcnt(0)
	s_barrier
	ds_read_b128 v[164:167], v76 offset:49152
	ds_read_b128 v[168:171], v76 offset:53248
	ds_read_b128 v[172:175], v80 offset:49152
	ds_read_b128 v[176:179], v80 offset:53248
	v_mfma_f32_32x32x16_bf16 v[48:63], v[180:183], v[218:221], v[48:63]
	s_mov_b32 s14, 0xa5c3380
	s_mov_b32 m0, s11
	v_lshl_add_u64 v[160:161], v[74:75], 0, s[14:15]
	global_load_lds_dwordx4 v[160:161], off
	v_mfma_f32_32x32x16_bf16 v[32:47], v[180:183], v[222:225], v[32:47]
	v_mfma_f32_32x32x16_bf16 v[16:31], v[184:187], v[218:221], v[16:31]
	s_add_u32 m0, s11, 0x2000
	v_lshl_add_u64 v[162:163], v[72:73], 0, s[14:15]
	global_load_lds_dwordx4 v[162:163], off
	v_mfma_f32_32x32x16_bf16 v[0:15], v[184:187], v[222:225], v[0:15]
	ds_read_b128 v[180:183], v77 offset:49152
	ds_read_b128 v[184:187], v77 offset:53248
	ds_read_b128 v[218:221], v81 offset:49152
	ds_read_b128 v[222:225], v81 offset:53248
	s_waitcnt lgkmcnt(4)
	v_mfma_f32_32x32x16_bf16 v[48:63], v[164:167], v[172:175], v[48:63]
	s_add_u32 m0, s11, 0x4000
	v_lshl_add_u64 v[160:161], v[70:71], 0, s[14:15]
	global_load_lds_dwordx4 v[160:161], off
	v_mfma_f32_32x32x16_bf16 v[32:47], v[164:167], v[176:179], v[32:47]
	v_mfma_f32_32x32x16_bf16 v[16:31], v[168:171], v[172:175], v[16:31]
	s_add_u32 m0, s11, 0x6000
	v_lshl_add_u64 v[162:163], v[68:69], 0, s[14:15]
	global_load_lds_dwordx4 v[162:163], off
	v_mfma_f32_32x32x16_bf16 v[0:15], v[168:171], v[176:179], v[0:15]
	ds_read_b128 v[164:167], v78 offset:49152
	ds_read_b128 v[168:171], v78 offset:53248
	ds_read_b128 v[172:175], v82 offset:49152
	ds_read_b128 v[176:179], v82 offset:53248
	s_waitcnt lgkmcnt(4)
	v_mfma_f32_32x32x16_bf16 v[48:63], v[180:183], v[218:221], v[48:63]
	s_mov_b32 s14, 0x1b81380
	s_add_u32 m0, s11, 0x8000
	v_lshl_add_u64 v[160:161], v[66:67], 0, s[14:15]
	global_load_lds_dwordx4 v[160:161], off
	v_mfma_f32_32x32x16_bf16 v[32:47], v[180:183], v[222:225], v[32:47]
	v_mfma_f32_32x32x16_bf16 v[16:31], v[184:187], v[218:221], v[16:31]
	s_add_u32 m0, s11, 0xa000
	v_lshl_add_u64 v[162:163], v[64:65], 0, s[14:15]
	global_load_lds_dwordx4 v[162:163], off
	v_mfma_f32_32x32x16_bf16 v[0:15], v[184:187], v[222:225], v[0:15]
	ds_read_b128 v[180:183], v79 offset:49152
	ds_read_b128 v[184:187], v79 offset:53248
	ds_read_b128 v[218:221], v83 offset:49152
	ds_read_b128 v[222:225], v83 offset:53248
	s_waitcnt lgkmcnt(4)
	v_mfma_f32_32x32x16_bf16 v[48:63], v[164:167], v[172:175], v[48:63]
	v_mfma_f32_32x32x16_bf16 v[32:47], v[164:167], v[176:179], v[32:47]
	v_mfma_f32_32x32x16_bf16 v[16:31], v[168:171], v[172:175], v[16:31]
	v_mfma_f32_32x32x16_bf16 v[0:15], v[168:171], v[176:179], v[0:15]
	s_waitcnt vmcnt(6) lgkmcnt(0)
	s_barrier
;     ...
;   for (int kt = 0; kt < nk; ++kt) {
;     if (kt + 1 < nk) asm volatile("s_waitcnt vmcnt(6)" ::: "memory");
;     else asm volatile("s_waitcnt vmcnt(0)" ::: "memory");
;     __builtin_amdgcn_s_barrier();
;     asm volatile("" ::: "memory");
;     if (kt + 2 < nk) { const int st2 = (st >= 1) ? st - 1 : 2; GEMM_ISSUE(kt + 2, st2); }
;     const char* la = lds + st * STAGE_B;
;     const char* lb = la + 32768;
;     const unsigned sa_u = (unsigned)(size_t)la + arow_u, sb_u = (unsigned)(size_t)lb + brow_u;
;     const unsigned a0 = sa_u + co0, a1 = sa_u + co1, a2 = sa_u + co2, a3 = sa_u + co3;
;     const unsigned b0 = sb_u + co0, b1 = sb_u + co1, b2 = sb_u + co2, b3 = sb_u + co3;
;     {
;       bf16x8 p0, p1, q0, q1, u0, u1, w0, w1;
;       asm volatile(
;         "ds_read_b128 %4, %12\n\tds_read_b128 %5, %12 offset:4096\n\tds_read_b128 %6, %16\n\tds_read_b128 %7, %16 offset:4096\n\t"
;         "ds_read_b128 %8, %13\n\tds_read_b128 %9, %13 offset:4096\n\tds_read_b128 %10, %17\n\tds_read_b128 %11, %17 offset:4096\n\t"
;         "s_waitcnt lgkmcnt(4)\n\t"
;         "v_mfma_f32_32x32x16_bf16 %0, %4, %6, %0\n\tv_mfma_f32_32x32x16_bf16 %1, %4, %7, %1\n\tv_mfma_f32_32x32x16_bf16 %2, %5, %6, %2\n\tv_mfma_f32_32x32x16_bf16 %3, %5, %7, %3\n\t"
;         "ds_read_b128 %4, %14\n\tds_read_b128 %5, %14 offset:4096\n\tds_read_b128 %6, %18\n\tds_read_b128 %7, %18 offset:4096\n\t"
;         "s_waitcnt lgkmcnt(4)\n\t"
;         "v_mfma_f32_32x32x16_bf16 %0, %8, %10, %0\n\tv_mfma_f32_32x32x16_bf16 %1, %8, %11, %1\n\tv_mfma_f32_32x32x16_bf16 %2, %9, %10, %2\n\tv_mfma_f32_32x32x16_bf16 %3, %9, %11, %3\n\t"
;         "ds_read_b128 %8, %15\n\tds_read_b128 %9, %15 offset:4096\n\tds_read_b128 %10, %19\n\tds_read_b128 %11, %19 offset:4096\n\t"
;         "s_waitcnt lgkmcnt(4)\n\t"
;         "v_mfma_f32_32x32x16_bf16 %0, %4, %6, %0\n\tv_mfma_f32_32x32x16_bf16 %1, %4, %7, %1\n\tv_mfma_f32_32x32x16_bf16 %2, %5, %6, %2\n\tv_mfma_f32_32x32x16_bf16 %3, %5, %7, %3\n\t"
;         "s_waitcnt lgkmcnt(0)\n\t"
;         "v_mfma_f32_32x32x16_bf16 %0, %8, %10, %0\n\tv_mfma_f32_32x32x16_bf16 %1, %8, %11, %1\n\tv_mfma_f32_32x32x16_bf16 %2, %9, %10, %2\n\tv_mfma_f32_32x32x16_bf16 %3, %9, %11, %3"
;         : "+v"(acc[0][0]), "+v"(acc[0][1]), "+v"(acc[1][0]), "+v"(acc[1][1]),
;           "=&v"(p0), "=&v"(p1), "=&v"(q0), "=&v"(q1), "=&v"(u0), "=&v"(u1), "=&v"(w0), "=&v"(w1)
	ds_read_b128 v[164:167], v84
	ds_read_b128 v[168:171], v84 offset:4096
	ds_read_b128 v[172:175], v156
	ds_read_b128 v[176:179], v156 offset:4096
	v_mfma_f32_32x32x16_bf16 v[48:63], v[180:183], v[218:221], v[48:63]
	s_mov_b32 s14, 0xa5c3400
	s_add_u32 m0, s11, 0xc000
	v_lshl_add_u64 v[160:161], v[74:75], 0, s[14:15]
	global_load_lds_dwordx4 v[160:161], off
	v_mfma_f32_32x32x16_bf16 v[32:47], v[180:183], v[222:225], v[32:47]
	v_mfma_f32_32x32x16_bf16 v[16:31], v[184:187], v[218:221], v[16:31]
	s_add_u32 m0, s11, 0xe000
	v_lshl_add_u64 v[162:163], v[72:73], 0, s[14:15]
	global_load_lds_dwordx4 v[162:163], off
	v_mfma_f32_32x32x16_bf16 v[0:15], v[184:187], v[222:225], v[0:15]
	ds_read_b128 v[180:183], v85
	ds_read_b128 v[184:187], v85 offset:4096
	ds_read_b128 v[218:221], v157
	ds_read_b128 v[222:225], v157 offset:4096
	s_waitcnt lgkmcnt(4)
	v_mfma_f32_32x32x16_bf16 v[48:63], v[164:167], v[172:175], v[48:63]
	s_add_u32 m0, s11, 0x10000
	v_lshl_add_u64 v[160:161], v[70:71], 0, s[14:15]
	global_load_lds_dwordx4 v[160:161], off
	v_mfma_f32_32x32x16_bf16 v[32:47], v[164:167], v[176:179], v[32:47]
	v_mfma_f32_32x32x16_bf16 v[16:31], v[168:171], v[172:175], v[16:31]
	s_add_u32 m0, s11, 0x12000
	v_lshl_add_u64 v[162:163], v[68:69], 0, s[14:15]
	global_load_lds_dwordx4 v[162:163], off
	v_mfma_f32_32x32x16_bf16 v[0:15], v[168:171], v[176:179], v[0:15]
	ds_read_b128 v[164:167], v86
	ds_read_b128 v[168:171], v86 offset:4096
	ds_read_b128 v[172:175], v158
	ds_read_b128 v[176:179], v158 offset:4096
	s_waitcnt lgkmcnt(4)
	v_mfma_f32_32x32x16_bf16 v[48:63], v[180:183], v[218:221], v[48:63]
	s_mov_b32 s14, 0x1b81400
	s_add_u32 m0, s11, 0x14000
	v_lshl_add_u64 v[160:161], v[66:67], 0, s[14:15]
	global_load_lds_dwordx4 v[160:161], off
	v_mfma_f32_32x32x16_bf16 v[32:47], v[180:183], v[222:225], v[32:47]
	v_mfma_f32_32x32x16_bf16 v[16:31], v[184:187], v[218:221], v[16:31]
	s_add_u32 m0, s11, 0x16000
	v_lshl_add_u64 v[162:163], v[64:65], 0, s[14:15]
	global_load_lds_dwordx4 v[162:163], off
	v_mfma_f32_32x32x16_bf16 v[0:15], v[184:187], v[222:225], v[0:15]
	ds_read_b128 v[180:183], v87
	ds_read_b128 v[184:187], v87 offset:4096
	ds_read_b128 v[218:221], v159
	ds_read_b128 v[222:225], v159 offset:4096
	s_waitcnt lgkmcnt(4)
	v_mfma_f32_32x32x16_bf16 v[48:63], v[164:167], v[172:175], v[48:63]
	v_mfma_f32_32x32x16_bf16 v[32:47], v[164:167], v[176:179], v[32:47]
	v_mfma_f32_32x32x16_bf16 v[16:31], v[168:171], v[172:175], v[16:31]
	v_mfma_f32_32x32x16_bf16 v[0:15], v[168:171], v[176:179], v[0:15]
	s_waitcnt vmcnt(6) lgkmcnt(0)
	s_barrier
	ds_read_b128 v[164:167], v76
	ds_read_b128 v[168:171], v76 offset:4096
	ds_read_b128 v[172:175], v80
	ds_read_b128 v[176:179], v80 offset:4096
	v_mfma_f32_32x32x16_bf16 v[48:63], v[180:183], v[218:221], v[48:63]
	s_mov_b32 s14, 0xa5c3480
	s_add_u32 m0, s11, 0x18000
	v_lshl_add_u64 v[160:161], v[74:75], 0, s[14:15]
	global_load_lds_dwordx4 v[160:161], off
	v_mfma_f32_32x32x16_bf16 v[32:47], v[180:183], v[222:225], v[32:47]
	v_mfma_f32_32x32x16_bf16 v[16:31], v[184:187], v[218:221], v[16:31]
	s_add_u32 m0, s11, 0x1a000
	v_lshl_add_u64 v[162:163], v[72:73], 0, s[14:15]
	global_load_lds_dwordx4 v[162:163], off
	v_mfma_f32_32x32x16_bf16 v[0:15], v[184:187], v[222:225], v[0:15]
	ds_read_b128 v[180:183], v77
	ds_read_b128 v[184:187], v77 offset:4096
	ds_read_b128 v[218:221], v81
	ds_read_b128 v[222:225], v81 offset:4096
	s_waitcnt lgkmcnt(4)
	v_mfma_f32_32x32x16_bf16 v[48:63], v[164:167], v[172:175], v[48:63]
	s_add_u32 m0, s11, 0x1c000
	v_lshl_add_u64 v[160:161], v[70:71], 0, s[14:15]
	global_load_lds_dwordx4 v[160:161], off
	v_mfma_f32_32x32x16_bf16 v[32:47], v[164:167], v[176:179], v[32:47]
	v_mfma_f32_32x32x16_bf16 v[16:31], v[168:171], v[172:175], v[16:31]
	s_add_u32 m0, s11, 0x1e000
	v_lshl_add_u64 v[162:163], v[68:69], 0, s[14:15]
	global_load_lds_dwordx4 v[162:163], off
	v_mfma_f32_32x32x16_bf16 v[0:15], v[168:171], v[176:179], v[0:15]
	ds_read_b128 v[164:167], v78
	ds_read_b128 v[168:171], v78 offset:4096
	ds_read_b128 v[172:175], v82
	ds_read_b128 v[176:179], v82 offset:4096
	s_waitcnt lgkmcnt(4)
	v_mfma_f32_32x32x16_bf16 v[48:63], v[180:183], v[218:221], v[48:63]
	s_mov_b32 s14, 0x1b81480
	s_add_u32 m0, s11, 0x20000
	v_lshl_add_u64 v[160:161], v[66:67], 0, s[14:15]
	global_load_lds_dwordx4 v[160:161], off
	v_mfma_f32_32x32x16_bf16 v[32:47], v[180:183], v[222:225], v[32:47]
	v_mfma_f32_32x32x16_bf16 v[16:31], v[184:187], v[218:221], v[16:31]
	s_add_u32 m0, s11, 0x22000
	v_lshl_add_u64 v[162:163], v[64:65], 0, s[14:15]
	global_load_lds_dwordx4 v[162:163], off
	v_mfma_f32_32x32x16_bf16 v[0:15], v[184:187], v[222:225], v[0:15]
	ds_read_b128 v[180:183], v79
	ds_read_b128 v[184:187], v79 offset:4096
	ds_read_b128 v[218:221], v83
	ds_read_b128 v[222:225], v83 offset:4096
	s_waitcnt lgkmcnt(4)
	v_mfma_f32_32x32x16_bf16 v[48:63], v[164:167], v[172:175], v[48:63]
	v_mfma_f32_32x32x16_bf16 v[32:47], v[164:167], v[176:179], v[32:47]
	v_mfma_f32_32x32x16_bf16 v[16:31], v[168:171], v[172:175], v[16:31]
	v_mfma_f32_32x32x16_bf16 v[0:15], v[168:171], v[176:179], v[0:15]
	s_waitcnt vmcnt(6) lgkmcnt(0)
	s_barrier
;     ...
;   for (int kt = 0; kt < nk; ++kt) {
;     if (kt + 1 < nk) asm volatile("s_waitcnt vmcnt(6)" ::: "memory");
;     else asm volatile("s_waitcnt vmcnt(0)" ::: "memory");
;     __builtin_amdgcn_s_barrier();
;     asm volatile("" ::: "memory");
;     if (kt + 2 < nk) { const int st2 = (st >= 1) ? st - 1 : 2; GEMM_ISSUE(kt + 2, st2); }
;     const char* la = lds + st * STAGE_B;
;     const char* lb = la + 32768;
;     const unsigned sa_u = (unsigned)(size_t)la + arow_u, sb_u = (unsigned)(size_t)lb + brow_u;
;     const unsigned a0 = sa_u + co0, a1 = sa_u + co1, a2 = sa_u + co2, a3 = sa_u + co3;
;     const unsigned b0 = sb_u + co0, b1 = sb_u + co1, b2 = sb_u + co2, b3 = sb_u + co3;
;     {
;       bf16x8 p0, p1, q0, q1, u0, u1, w0, w1;
;       asm volatile(
;         "ds_read_b128 %4, %12\n\tds_read_b128 %5, %12 offset:4096\n\tds_read_b128 %6, %16\n\tds_read_b128 %7, %16 offset:4096\n\t"
;         "ds_read_b128 %8, %13\n\tds_read_b128 %9, %13 offset:4096\n\tds_read_b128 %10, %17\n\tds_read_b128 %11, %17 offset:4096\n\t"
;         "s_waitcnt lgkmcnt(4)\n\t"
;         "v_mfma_f32_32x32x16_bf16 %0, %4, %6, %0\n\tv_mfma_f32_32x32x16_bf16 %1, %4, %7, %1\n\tv_mfma_f32_32x32x16_bf16 %2, %5, %6, %2\n\tv_mfma_f32_32x32x16_bf16 %3, %5, %7, %3\n\t"
;         "ds_read_b128 %4, %14\n\tds_read_b128 %5, %14 offset:4096\n\tds_read_b128 %6, %18\n\tds_read_b128 %7, %18 offset:4096\n\t"
;         "s_waitcnt lgkmcnt(4)\n\t"
;         "v_mfma_f32_32x32x16_bf16 %0, %8, %10, %0\n\tv_mfma_f32_32x32x16_bf16 %1, %8, %11, %1\n\tv_mfma_f32_32x32x16_bf16 %2, %9, %10, %2\n\tv_mfma_f32_32x32x16_bf16 %3, %9, %11, %3\n\t"
;         "ds_read_b128 %8, %15\n\tds_read_b128 %9, %15 offset:4096\n\tds_read_b128 %10, %19\n\tds_read_b128 %11, %19 offset:4096\n\t"
;         "s_waitcnt lgkmcnt(4)\n\t"
;         "v_mfma_f32_32x32x16_bf16 %0, %4, %6, %0\n\tv_mfma_f32_32x32x16_bf16 %1, %4, %7, %1\n\tv_mfma_f32_32x32x16_bf16 %2, %5, %6, %2\n\tv_mfma_f32_32x32x16_bf16 %3, %5, %7, %3\n\t"
;         "s_waitcnt lgkmcnt(0)\n\t"
;         "v_mfma_f32_32x32x16_bf16 %0, %8, %10, %0\n\tv_mfma_f32_32x32x16_bf16 %1, %8, %11, %1\n\tv_mfma_f32_32x32x16_bf16 %2, %9, %10, %2\n\tv_mfma_f32_32x32x16_bf16 %3, %9, %11, %3"
;         : "+v"(acc[0][0]), "+v"(acc[0][1]), "+v"(acc[1][0]), "+v"(acc[1][1]),
;           "=&v"(p0), "=&v"(p1), "=&v"(q0), "=&v"(q1), "=&v"(u0), "=&v"(u1), "=&v"(w0), "=&v"(w1)
	ds_read_b128 v[164:167], v76 offset:49152
	ds_read_b128 v[168:171], v76 offset:53248
	ds_read_b128 v[172:175], v80 offset:49152
	ds_read_b128 v[176:179], v80 offset:53248
	v_mfma_f32_32x32x16_bf16 v[48:63], v[180:183], v[218:221], v[48:63]
	s_mov_b32 s14, 0xa5c3500
	s_mov_b32 m0, s11
	v_lshl_add_u64 v[160:161], v[74:75], 0, s[14:15]
	global_load_lds_dwordx4 v[160:161], off
	v_mfma_f32_32x32x16_bf16 v[32:47], v[180:183], v[222:225], v[32:47]
	v_mfma_f32_32x32x16_bf16 v[16:31], v[184:187], v[218:221], v[16:31]
	s_add_u32 m0, s11, 0x2000
	v_lshl_add_u64 v[162:163], v[72:73], 0, s[14:15]
	global_load_lds_dwordx4 v[162:163], off
	v_mfma_f32_32x32x16_bf16 v[0:15], v[184:187], v[222:225], v[0:15]
	ds_read_b128 v[180:183], v77 offset:49152
	ds_read_b128 v[184:187], v77 offset:53248
	ds_read_b128 v[218:221], v81 offset:49152
	ds_read_b128 v[222:225], v81 offset:53248
	s_waitcnt lgkmcnt(4)
	v_mfma_f32_32x32x16_bf16 v[48:63], v[164:167], v[172:175], v[48:63]
	s_add_u32 m0, s11, 0x4000
	v_lshl_add_u64 v[160:161], v[70:71], 0, s[14:15]
	global_load_lds_dwordx4 v[160:161], off
	v_mfma_f32_32x32x16_bf16 v[32:47], v[164:167], v[176:179], v[32:47]
	v_mfma_f32_32x32x16_bf16 v[16:31], v[168:171], v[172:175], v[16:31]
	s_add_u32 m0, s11, 0x6000
	v_lshl_add_u64 v[162:163], v[68:69], 0, s[14:15]
	global_load_lds_dwordx4 v[162:163], off
	v_mfma_f32_32x32x16_bf16 v[0:15], v[168:171], v[176:179], v[0:15]
	ds_read_b128 v[164:167], v78 offset:49152
	ds_read_b128 v[168:171], v78 offset:53248
	ds_read_b128 v[172:175], v82 offset:49152
	ds_read_b128 v[176:179], v82 offset:53248
	s_waitcnt lgkmcnt(4)
	v_mfma_f32_32x32x16_bf16 v[48:63], v[180:183], v[218:221], v[48:63]
	s_mov_b32 s14, 0x1b81500
	s_add_u32 m0, s11, 0x8000
	v_lshl_add_u64 v[160:161], v[66:67], 0, s[14:15]
	global_load_lds_dwordx4 v[160:161], off
	v_mfma_f32_32x32x16_bf16 v[32:47], v[180:183], v[222:225], v[32:47]
	v_mfma_f32_32x32x16_bf16 v[16:31], v[184:187], v[218:221], v[16:31]
	s_add_u32 m0, s11, 0xa000
	v_lshl_add_u64 v[162:163], v[64:65], 0, s[14:15]
	global_load_lds_dwordx4 v[162:163], off
	v_mfma_f32_32x32x16_bf16 v[0:15], v[184:187], v[222:225], v[0:15]
	ds_read_b128 v[180:183], v79 offset:49152
	ds_read_b128 v[184:187], v79 offset:53248
	ds_read_b128 v[218:221], v83 offset:49152
	ds_read_b128 v[222:225], v83 offset:53248
	s_waitcnt lgkmcnt(4)
	v_mfma_f32_32x32x16_bf16 v[48:63], v[164:167], v[172:175], v[48:63]
	v_mfma_f32_32x32x16_bf16 v[32:47], v[164:167], v[176:179], v[32:47]
	v_mfma_f32_32x32x16_bf16 v[16:31], v[168:171], v[172:175], v[16:31]
	v_mfma_f32_32x32x16_bf16 v[0:15], v[168:171], v[176:179], v[0:15]
	s_waitcnt vmcnt(6) lgkmcnt(0)
	s_barrier
	ds_read_b128 v[164:167], v84
	ds_read_b128 v[168:171], v84 offset:4096
	ds_read_b128 v[172:175], v156
	ds_read_b128 v[176:179], v156 offset:4096
	v_mfma_f32_32x32x16_bf16 v[48:63], v[180:183], v[218:221], v[48:63]
	s_mov_b32 s14, 0xa5c3580
	s_add_u32 m0, s11, 0xc000
	v_lshl_add_u64 v[160:161], v[74:75], 0, s[14:15]
	global_load_lds_dwordx4 v[160:161], off
	v_mfma_f32_32x32x16_bf16 v[32:47], v[180:183], v[222:225], v[32:47]
	v_mfma_f32_32x32x16_bf16 v[16:31], v[184:187], v[218:221], v[16:31]
	s_add_u32 m0, s11, 0xe000
	v_lshl_add_u64 v[162:163], v[72:73], 0, s[14:15]
	global_load_lds_dwordx4 v[162:163], off
	v_mfma_f32_32x32x16_bf16 v[0:15], v[184:187], v[222:225], v[0:15]
	ds_read_b128 v[180:183], v85
	ds_read_b128 v[184:187], v85 offset:4096
	ds_read_b128 v[218:221], v157
	ds_read_b128 v[222:225], v157 offset:4096
	s_waitcnt lgkmcnt(4)
	v_mfma_f32_32x32x16_bf16 v[48:63], v[164:167], v[172:175], v[48:63]
	s_add_u32 m0, s11, 0x10000
	v_lshl_add_u64 v[160:161], v[70:71], 0, s[14:15]
	global_load_lds_dwordx4 v[160:161], off
	v_mfma_f32_32x32x16_bf16 v[32:47], v[164:167], v[176:179], v[32:47]
	v_mfma_f32_32x32x16_bf16 v[16:31], v[168:171], v[172:175], v[16:31]
	s_add_u32 m0, s11, 0x12000
	v_lshl_add_u64 v[162:163], v[68:69], 0, s[14:15]
	global_load_lds_dwordx4 v[162:163], off
	v_mfma_f32_32x32x16_bf16 v[0:15], v[168:171], v[176:179], v[0:15]
	ds_read_b128 v[164:167], v86
	ds_read_b128 v[168:171], v86 offset:4096
	ds_read_b128 v[172:175], v158
	ds_read_b128 v[176:179], v158 offset:4096
	s_waitcnt lgkmcnt(4)
	v_mfma_f32_32x32x16_bf16 v[48:63], v[180:183], v[218:221], v[48:63]
	s_mov_b32 s14, 0x1b81580
	s_add_u32 m0, s11, 0x14000
	v_lshl_add_u64 v[160:161], v[66:67], 0, s[14:15]
	global_load_lds_dwordx4 v[160:161], off
	v_mfma_f32_32x32x16_bf16 v[32:47], v[180:183], v[222:225], v[32:47]
	v_mfma_f32_32x32x16_bf16 v[16:31], v[184:187], v[218:221], v[16:31]
	s_add_u32 m0, s11, 0x16000
	v_lshl_add_u64 v[162:163], v[64:65], 0, s[14:15]
	global_load_lds_dwordx4 v[162:163], off
	v_mfma_f32_32x32x16_bf16 v[0:15], v[184:187], v[222:225], v[0:15]
	ds_read_b128 v[180:183], v87
	ds_read_b128 v[184:187], v87 offset:4096
	ds_read_b128 v[218:221], v159
	ds_read_b128 v[222:225], v159 offset:4096
	s_waitcnt lgkmcnt(4)
	v_mfma_f32_32x32x16_bf16 v[48:63], v[164:167], v[172:175], v[48:63]
	v_mfma_f32_32x32x16_bf16 v[32:47], v[164:167], v[176:179], v[32:47]
	v_mfma_f32_32x32x16_bf16 v[16:31], v[168:171], v[172:175], v[16:31]
	v_mfma_f32_32x32x16_bf16 v[0:15], v[168:171], v[176:179], v[0:15]
	s_waitcnt vmcnt(6) lgkmcnt(0)
	s_barrier
;     ...
;   for (int kt = 0; kt < nk; ++kt) {
;     if (kt + 1 < nk) asm volatile("s_waitcnt vmcnt(6)" ::: "memory");
;     else asm volatile("s_waitcnt vmcnt(0)" ::: "memory");
;     __builtin_amdgcn_s_barrier();
;     asm volatile("" ::: "memory");
;     if (kt + 2 < nk) { const int st2 = (st >= 1) ? st - 1 : 2; GEMM_ISSUE(kt + 2, st2); }
;     const char* la = lds + st * STAGE_B;
;     const char* lb = la + 32768;
;     const unsigned sa_u = (unsigned)(size_t)la + arow_u, sb_u = (unsigned)(size_t)lb + brow_u;
;     const unsigned a0 = sa_u + co0, a1 = sa_u + co1, a2 = sa_u + co2, a3 = sa_u + co3;
;     const unsigned b0 = sb_u + co0, b1 = sb_u + co1, b2 = sb_u + co2, b3 = sb_u + co3;
;     {
;       bf16x8 p0, p1, q0, q1, u0, u1, w0, w1;
;       asm volatile(
;         "ds_read_b128 %4, %12\n\tds_read_b128 %5, %12 offset:4096\n\tds_read_b128 %6, %16\n\tds_read_b128 %7, %16 offset:4096\n\t"
;         "ds_read_b128 %8, %13\n\tds_read_b128 %9, %13 offset:4096\n\tds_read_b128 %10, %17\n\tds_read_b128 %11, %17 offset:4096\n\t"
;         "s_waitcnt lgkmcnt(4)\n\t"
;         "v_mfma_f32_32x32x16_bf16 %0, %4, %6, %0\n\tv_mfma_f32_32x32x16_bf16 %1, %4, %7, %1\n\tv_mfma_f32_32x32x16_bf16 %2, %5, %6, %2\n\tv_mfma_f32_32x32x16_bf16 %3, %5, %7, %3\n\t"
;         "ds_read_b128 %4, %14\n\tds_read_b128 %5, %14 offset:4096\n\tds_read_b128 %6, %18\n\tds_read_b128 %7, %18 offset:4096\n\t"
;         "s_waitcnt lgkmcnt(4)\n\t"
;         "v_mfma_f32_32x32x16_bf16 %0, %8, %10, %0\n\tv_mfma_f32_32x32x16_bf16 %1, %8, %11, %1\n\tv_mfma_f32_32x32x16_bf16 %2, %9, %10, %2\n\tv_mfma_f32_32x32x16_bf16 %3, %9, %11, %3\n\t"
;         "ds_read_b128 %8, %15\n\tds_read_b128 %9, %15 offset:4096\n\tds_read_b128 %10, %19\n\tds_read_b128 %11, %19 offset:4096\n\t"
;         "s_waitcnt lgkmcnt(4)\n\t"
;         "v_mfma_f32_32x32x16_bf16 %0, %4, %6, %0\n\tv_mfma_f32_32x32x16_bf16 %1, %4, %7, %1\n\tv_mfma_f32_32x32x16_bf16 %2, %5, %6, %2\n\tv_mfma_f32_32x32x16_bf16 %3, %5, %7, %3\n\t"
;         "s_waitcnt lgkmcnt(0)\n\t"
;         "v_mfma_f32_32x32x16_bf16 %0, %8, %10, %0\n\tv_mfma_f32_32x32x16_bf16 %1, %8, %11, %1\n\tv_mfma_f32_32x32x16_bf16 %2, %9, %10, %2\n\tv_mfma_f32_32x32x16_bf16 %3, %9, %11, %3"
;         : "+v"(acc[0][0]), "+v"(acc[0][1]), "+v"(acc[1][0]), "+v"(acc[1][1]),
;           "=&v"(p0), "=&v"(p1), "=&v"(q0), "=&v"(q1), "=&v"(u0), "=&v"(u1), "=&v"(w0), "=&v"(w1)
	ds_read_b128 v[164:167], v76
	ds_read_b128 v[168:171], v76 offset:4096
	ds_read_b128 v[172:175], v80
	ds_read_b128 v[176:179], v80 offset:4096
	v_mfma_f32_32x32x16_bf16 v[48:63], v[180:183], v[218:221], v[48:63]
	v_mfma_f32_32x32x16_bf16 v[32:47], v[180:183], v[222:225], v[32:47]
	v_mfma_f32_32x32x16_bf16 v[16:31], v[184:187], v[218:221], v[16:31]
	v_mfma_f32_32x32x16_bf16 v[0:15], v[184:187], v[222:225], v[0:15]
	ds_read_b128 v[180:183], v77
	ds_read_b128 v[184:187], v77 offset:4096
	ds_read_b128 v[218:221], v81
	ds_read_b128 v[222:225], v81 offset:4096
	s_waitcnt lgkmcnt(4)
	v_mfma_f32_32x32x16_bf16 v[48:63], v[164:167], v[172:175], v[48:63]
	v_mfma_f32_32x32x16_bf16 v[32:47], v[164:167], v[176:179], v[32:47]
	v_mfma_f32_32x32x16_bf16 v[16:31], v[168:171], v[172:175], v[16:31]
	v_mfma_f32_32x32x16_bf16 v[0:15], v[168:171], v[176:179], v[0:15]
	ds_read_b128 v[164:167], v78
	ds_read_b128 v[168:171], v78 offset:4096
	ds_read_b128 v[172:175], v82
	ds_read_b128 v[176:179], v82 offset:4096
	s_waitcnt lgkmcnt(4)
	v_mfma_f32_32x32x16_bf16 v[48:63], v[180:183], v[218:221], v[48:63]
	v_mfma_f32_32x32x16_bf16 v[32:47], v[180:183], v[222:225], v[32:47]
	v_mfma_f32_32x32x16_bf16 v[16:31], v[184:187], v[218:221], v[16:31]
	v_mfma_f32_32x32x16_bf16 v[0:15], v[184:187], v[222:225], v[0:15]
	ds_read_b128 v[180:183], v79
	ds_read_b128 v[184:187], v79 offset:4096
	ds_read_b128 v[218:221], v83
	ds_read_b128 v[222:225], v83 offset:4096
	s_waitcnt lgkmcnt(4)
	v_mfma_f32_32x32x16_bf16 v[48:63], v[164:167], v[172:175], v[48:63]
	v_mfma_f32_32x32x16_bf16 v[32:47], v[164:167], v[176:179], v[32:47]
	v_mfma_f32_32x32x16_bf16 v[16:31], v[168:171], v[172:175], v[16:31]
	v_mfma_f32_32x32x16_bf16 v[0:15], v[168:171], v[176:179], v[0:15]
	s_waitcnt vmcnt(0) lgkmcnt(0)
	s_barrier
	ds_read_b128 v[164:167], v76 offset:49152
	ds_read_b128 v[168:171], v76 offset:53248
	ds_read_b128 v[172:175], v80 offset:49152
	ds_read_b128 v[176:179], v80 offset:53248
	v_mfma_f32_32x32x16_bf16 v[48:63], v[180:183], v[218:221], v[48:63]
	v_mfma_f32_32x32x16_bf16 v[32:47], v[180:183], v[222:225], v[32:47]
	v_mfma_f32_32x32x16_bf16 v[16:31], v[184:187], v[218:221], v[16:31]
	v_mfma_f32_32x32x16_bf16 v[0:15], v[184:187], v[222:225], v[0:15]
	ds_read_b128 v[180:183], v77 offset:49152
	ds_read_b128 v[184:187], v77 offset:53248
	ds_read_b128 v[218:221], v81 offset:49152
	ds_read_b128 v[222:225], v81 offset:53248
	s_waitcnt lgkmcnt(4)
	v_mfma_f32_32x32x16_bf16 v[48:63], v[164:167], v[172:175], v[48:63]
	v_mfma_f32_32x32x16_bf16 v[32:47], v[164:167], v[176:179], v[32:47]
	v_mfma_f32_32x32x16_bf16 v[16:31], v[168:171], v[172:175], v[16:31]
	v_mfma_f32_32x32x16_bf16 v[0:15], v[168:171], v[176:179], v[0:15]
	ds_read_b128 v[164:167], v78 offset:49152
	ds_read_b128 v[168:171], v78 offset:53248
	ds_read_b128 v[172:175], v82 offset:49152
	ds_read_b128 v[176:179], v82 offset:53248
	s_waitcnt lgkmcnt(4)
	v_mfma_f32_32x32x16_bf16 v[48:63], v[180:183], v[218:221], v[48:63]
	v_mfma_f32_32x32x16_bf16 v[32:47], v[180:183], v[222:225], v[32:47]
	v_mfma_f32_32x32x16_bf16 v[16:31], v[184:187], v[218:221], v[16:31]
	v_mfma_f32_32x32x16_bf16 v[0:15], v[184:187], v[222:225], v[0:15]
	ds_read_b128 v[180:183], v79 offset:49152
	ds_read_b128 v[184:187], v79 offset:53248
	ds_read_b128 v[218:221], v83 offset:49152
	ds_read_b128 v[222:225], v83 offset:53248
	s_waitcnt lgkmcnt(4)
	v_mfma_f32_32x32x16_bf16 v[48:63], v[164:167], v[172:175], v[48:63]
	v_mfma_f32_32x32x16_bf16 v[32:47], v[164:167], v[176:179], v[32:47]
	v_mfma_f32_32x32x16_bf16 v[16:31], v[168:171], v[172:175], v[16:31]
	v_mfma_f32_32x32x16_bf16 v[0:15], v[168:171], v[176:179], v[0:15]
	s_waitcnt lgkmcnt(0)
	v_mfma_f32_32x32x16_bf16 v[48:63], v[180:183], v[218:221], v[48:63]
	v_mfma_f32_32x32x16_bf16 v[32:47], v[180:183], v[222:225], v[32:47]
	v_mfma_f32_32x32x16_bf16 v[16:31], v[184:187], v[218:221], v[16:31]
	v_mfma_f32_32x32x16_bf16 v[0:15], v[184:187], v[222:225], v[0:15]
	s_nop 15
	s_nop 15
	s_nop 7
	s_barrier
	s_load_dword s11, s[0:1], 0x10
	s_waitcnt lgkmcnt(0)
	s_lshr_b32 s11, s11, 16
	s_cmp_lg_u32 s11, 0
	s_cselect_b64 s[14:15], -1, 0
	s_cmp_lg_u64 s[14:15], 0
	s_addc_u32 s11, s33, 0

;     ...
;   if (PART != 2) {
;     GEMM_ISSUE(0, 0);
;     if (nk > 1) GEMM_ISSUE(1, 1);
;   }
;   if (PART == 1) return;
;   int st = 0;
;   for (int kt = 0; kt < nk; ++kt) {
;     if (kt + 1 < nk) asm volatile("s_waitcnt vmcnt(6)" ::: "memory");
;     else asm volatile("s_waitcnt vmcnt(0)" ::: "memory");
;     __builtin_amdgcn_s_barrier();
;     asm volatile("" ::: "memory");
;     if (kt + 2 < nk) { const int st2 = (st >= 1) ? st - 1 : 2; GEMM_ISSUE(kt + 2, st2); }
;     const char* la = lds + st * STAGE_B;
;     const char* lb = la + 32768;
;     const unsigned sa_u = (unsigned)(size_t)la + arow_u, sb_u = (unsigned)(size_t)lb + brow_u;
;     const unsigned a0 = sa_u + co0, a1 = sa_u + co1, a2 = sa_u + co2, a3 = sa_u + co3;
;     const unsigned b0 = sb_u + co0, b1 = sb_u + co1, b2 = sb_u + co2, b3 = sb_u + co3;
;     {
;       bf16x8 p0, p1, q0, q1, u0, u1, w0, w1;
;       asm volatile(
;         "ds_read_b128 %4, %12\n\tds_read_b128 %5, %12 offset:4096\n\tds_read_b128 %6, %16\n\tds_read_b128 %7, %16 offset:4096\n\t"
;         "ds_read_b128 %8, %13\n\tds_read_b128 %9, %13 offset:4096\n\tds_read_b128 %10, %17\n\tds_read_b128 %11, %17 offset:4096\n\t"
;         "s_waitcnt lgkmcnt(4)\n\t"
;         "v_mfma_f32_32x32x16_bf16 %0, %4, %6, %0\n\tv_mfma_f32_32x32x16_bf16 %1, %4, %7, %1\n\tv_mfma_f32_32x32x16_bf16 %2, %5, %6, %2\n\tv_mfma_f32_32x32x16_bf16 %3, %5, %7, %3\n\t"
;         "ds_read_b128 %4, %14\n\tds_read_b128 %5, %14 offset:4096\n\tds_read_b128 %6, %18\n\tds_read_b128 %7, %18 offset:4096\n\t"
;         "s_waitcnt lgkmcnt(4)\n\t"
;         "v_mfma_f32_32x32x16_bf16 %0, %8, %10, %0\n\tv_mfma_f32_32x32x16_bf16 %1, %8, %11, %1\n\tv_mfma_f32_32x32x16_bf16 %2, %9, %10, %2\n\tv_mfma_f32_32x32x16_bf16 %3, %9, %11, %3\n\t"
;         "ds_read_b128 %8, %15\n\tds_read_b128 %9, %15 offset:4096\n\tds_read_b128 %10, %19\n\tds_read_b128 %11, %19 offset:4096\n\t"
;         "s_waitcnt lgkmcnt(4)\n\t"
;         "v_mfma_f32_32x32x16_bf16 %0, %4, %6, %0\n\tv_mfma_f32_32x32x16_bf16 %1, %4, %7, %1\n\tv_mfma_f32_32x32x16_bf16 %2, %5, %6, %2\n\tv_mfma_f32_32x32x16_bf16 %3, %5, %7, %3\n\t"
;         "s_waitcnt lgkmcnt(0)\n\t"
;         "v_mfma_f32_32x32x16_bf16 %0, %8, %10, %0\n\tv_mfma_f32_32x32x16_bf16 %1, %8, %11, %1\n\tv_mfma_f32_32x32x16_bf16 %2, %9, %10, %2\n\tv_mfma_f32_32x32x16_bf16 %3, %9, %11, %3"
.LBB0_57:
	v_mov_b32_e32 v1, v129
	s_mov_b32 s68, s8
	v_lshlrev_b32_e32 v5, 4, v1
	v_lshrrev_b32_e32 v3, 5, v1
	v_xor_b32_e32 v0, v5, v1
	v_lshlrev_b32_e32 v2, 8, v1
	v_and_b32_e32 v6, 31, v1
	v_bfe_u32 v7, v1, 5, 1
	v_add_u32_e32 v116, 0, v5
	v_lshrrev_b32_e32 v5, 1, v1
	v_bfe_u32 v8, v1, 1, 3
	v_lshlrev_b32_e32 v1, 7, v1
	s_ashr_i32 s69, s8, 31
	s_waitcnt vmcnt(0)
	v_and_b32_e32 v118, 0x2f80, v1
	v_bitop3_b32 v1, v3, v8, 1 bitop3:0x6c
	s_lshl_b64 s[26:27], s[68:69], 19
	v_lshlrev_b32_e32 v119, 4, v1
	v_bitop3_b32 v1, v7, v8, 2 bitop3:0x36
	s_add_u32 s30, s88, s26
	v_and_b32_e32 v2, 0xfffff800, v2
	s_movk_i32 s9, 0x70
	v_lshlrev_b32_e32 v120, 4, v1
	v_bitop3_b32 v1, v7, v8, 4 bitop3:0x36
	s_addc_u32 s31, s89, s27
	v_and_or_b32 v130, v0, s9, v2
	s_mov_b32 s9, 0x1ffffc0
	v_lshlrev_b32_e32 v121, 4, v1
	v_bitop3_b32 v1, v7, v8, 6 bitop3:0x36
	v_add_u32_e32 v8, 0x18000, v116
	v_add_u32_e32 v0, 0x20000, v130
	v_and_or_b32 v5, v5, s9, v6
	v_lshlrev_b32_e32 v122, 4, v1
	v_mov_b32_e32 v1, v131
	v_lshl_add_u64 v[64:65], s[30:31], 0, v[130:131]
	v_readfirstlane_b32 s9, v8
	v_add_u32_e32 v8, 0x1a000, v116
	s_waitcnt vmcnt(6)
	s_barrier
	v_lshl_add_u64 v[6:7], v[64:65], 0, s[78:79]
	s_mov_b32 m0, s9
	v_lshl_add_u64 v[66:67], s[30:31], 0, v[0:1]
	v_readfirstlane_b32 s15, v8
	s_mov_b32 s70, s14
	s_ashr_i32 s71, s14, 31
	global_load_lds_dwordx4 v[6:7], off
	v_lshl_add_u64 v[6:7], v[66:67], 0, s[78:79]
	s_mov_b32 m0, s15
	s_lshl_b64 s[26:27], s[70:71], 18
	v_add_u32_e32 v2, 0x40000, v130
	v_add_u32_e32 v4, 0x60000, v130
	v_lshlrev_b32_e32 v117, 7, v5
	v_mov_b32_e32 v3, v131
	v_mov_b32_e32 v5, v131
	global_load_lds_dwordx4 v[6:7], off
	v_add_u32_e32 v6, 0x1c000, v116
	s_add_u32 s54, s10, s26
	v_lshl_add_u64 v[68:69], s[30:31], 0, v[2:3]
	v_readfirstlane_b32 s26, v6
	v_lshl_add_u64 v[70:71], s[30:31], 0, v[4:5]
	v_add_u32_e32 v4, 0x1e000, v116
	s_addc_u32 s55, s11, s27
	v_lshl_add_u64 v[2:3], v[68:69], 0, s[78:79]
	s_mov_b32 m0, s26
	v_readfirstlane_b32 s27, v4
	v_add_u32_e32 v4, 0x20000, v116
	global_load_lds_dwordx4 v[2:3], off
	v_lshl_add_u64 v[2:3], v[70:71], 0, s[78:79]
	s_mov_b32 m0, s27
	v_lshl_add_u64 v[72:73], s[54:55], 0, v[130:131]
	v_readfirstlane_b32 s69, v4
	global_load_lds_dwordx4 v[2:3], off
	v_lshl_add_u64 v[2:3], v[72:73], 0, s[78:79]
	s_mov_b32 m0, s69
	v_lshl_add_u64 v[74:75], s[54:55], 0, v[0:1]
	global_load_lds_dwordx4 v[2:3], off
	v_add_u32_e32 v2, 0x22000, v116
	s_cmp_lg_u32 0, -1
	v_readfirstlane_b32 s71, v2
	v_lshl_add_u64 v[0:1], v[74:75], 0, s[78:79]
	s_mov_b32 m0, s71
	s_cselect_b32 s24, 0, 0
	s_mov_b32 s53, s52
	global_load_lds_dwordx4 v[0:1], off
	v_add_u32_e32 v0, s24, v117
	s_add_i32 s24, s24, 0x8000
	s_mov_b32 s54, s52
	s_mov_b32 s55, s52
	s_mov_b32 s56, s52
	s_mov_b32 s57, s52
	s_mov_b32 s58, s52
	s_mov_b32 s59, s52
	s_mov_b32 s60, s52
	s_mov_b32 s61, s52
	s_mov_b32 s62, s52
	s_mov_b32 s63, s52
	s_mov_b32 s64, s52
	s_mov_b32 s65, s52
	s_mov_b32 s66, s52
	s_mov_b32 s67, s52
	v_mov_b64_e32 v[32:33], s[52:53]
	v_add_u32_e32 v1, s24, v118
	v_mov_b64_e32 v[46:47], s[66:67]
	v_add_u32_e32 v76, v0, v119
	v_add_u32_e32 v77, v0, v120
	v_add_u32_e32 v78, v0, v121
	v_add_u32_e32 v79, v0, v122
	v_add_u32_e32 v80, v119, v1
	v_add_u32_e32 v81, v120, v1
	v_add_u32_e32 v82, v121, v1
	v_add_u32_e32 v83, v122, v1
	v_mov_b64_e32 v[34:35], s[54:55]
	v_mov_b64_e32 v[36:37], s[56:57]
	v_mov_b64_e32 v[38:39], s[58:59]
	v_mov_b64_e32 v[40:41], s[60:61]
	v_mov_b64_e32 v[42:43], s[62:63]
	v_mov_b64_e32 v[44:45], s[64:65]
	v_mov_b64_e32 v[62:63], v[46:47]
	v_mov_b64_e32 v[0:1], v[32:33]
	v_mov_b64_e32 v[16:17], v[32:33]
	v_mov_b64_e32 v[60:61], v[44:45]
	v_mov_b64_e32 v[58:59], v[42:43]
	v_mov_b64_e32 v[56:57], v[40:41]
	v_mov_b64_e32 v[54:55], v[38:39]
	v_mov_b64_e32 v[52:53], v[36:37]
	v_mov_b64_e32 v[50:51], v[34:35]
	v_mov_b64_e32 v[48:49], v[32:33]
	v_mov_b64_e32 v[2:3], v[34:35]
	v_mov_b64_e32 v[4:5], v[36:37]
	v_mov_b64_e32 v[6:7], v[38:39]
	v_mov_b64_e32 v[8:9], v[40:41]
	v_mov_b64_e32 v[10:11], v[42:43]
	v_mov_b64_e32 v[12:13], v[44:45]
	v_mov_b64_e32 v[14:15], v[46:47]
	v_mov_b64_e32 v[18:19], v[34:35]
	v_mov_b64_e32 v[20:21], v[36:37]
	v_mov_b64_e32 v[22:23], v[38:39]
	v_mov_b64_e32 v[24:25], v[40:41]
	v_mov_b64_e32 v[26:27], v[42:43]
	v_mov_b64_e32 v[28:29], v[44:45]
	v_mov_b64_e32 v[30:31], v[46:47]
	v_and_b32_e32 v84, 31, v129
	v_bfe_u32 v85, v129, 5, 1
	v_lshrrev_b32_e32 v86, 6, v129
	v_bfe_u32 v88, v129, 1, 3
	v_lshrrev_b32_e32 v87, 1, v86
	v_and_b32_e32 v86, 1, v86
	v_xor_b32_e32 v85, v85, v88
	v_lshl_add_u32 v87, v87, 6, v84
	v_lshl_add_u32 v86, v86, 6, v84
	v_lshlrev_b32_e32 v85, 4, v85
	v_lshlrev_b32_e32 v87, 7, v87
	v_lshlrev_b32_e32 v86, 7, v86
	v_add_u32_e32 v86, 0x8000, v86
	v_add_u32_e32 v76, v87, v85
	v_add_u32_e32 v80, v86, v85
	v_xor_b32_e32 v89, 0x20, v85
	v_add_u32_e32 v77, v87, v89
	v_add_u32_e32 v81, v86, v89
	v_xor_b32_e32 v89, 0x40, v85
	v_add_u32_e32 v78, v87, v89
	v_add_u32_e32 v82, v86, v89
	v_xor_b32_e32 v89, 0x60, v85
	v_add_u32_e32 v79, v87, v89
	v_add_u32_e32 v83, v86, v89
	v_add_u32_e32 v116, 0x18000, v76
	v_add_u32_e32 v120, 0x18000, v80
	v_add_u32_e32 v117, 0x18000, v77
	v_add_u32_e32 v121, 0x18000, v81
	v_add_u32_e32 v118, 0x18000, v78
	v_add_u32_e32 v122, 0x18000, v82
	v_add_u32_e32 v119, 0x18000, v79
	v_add_u32_e32 v123, 0x18000, v83
	v_lshlrev_b32_e32 v84, 4, v129
	s_nop 0
	v_readfirstlane_b32 s30, v84
	s_mov_b32 s25, 0
	ds_read_b128 v[84:87], v76
	ds_read_b128 v[88:91], v76 offset:4096
	ds_read_b128 v[92:95], v80
	ds_read_b128 v[96:99], v80 offset:4096
	ds_read_b128 v[100:103], v77
	ds_read_b128 v[104:107], v77 offset:4096
	ds_read_b128 v[108:111], v81
	ds_read_b128 v[112:115], v81 offset:4096
	s_waitcnt lgkmcnt(4)
	v_mfma_f32_32x32x16_bf16 v[32:47], v[84:87], v[92:95], v[32:47]
	v_mfma_f32_32x32x16_bf16 v[48:63], v[84:87], v[96:99], v[48:63]
	v_mfma_f32_32x32x16_bf16 v[0:15], v[88:91], v[92:95], v[0:15]
	v_mfma_f32_32x32x16_bf16 v[16:31], v[88:91], v[96:99], v[16:31]
	ds_read_b128 v[84:87], v78
	ds_read_b128 v[88:91], v78 offset:4096
	ds_read_b128 v[92:95], v82
	ds_read_b128 v[96:99], v82 offset:4096
	s_waitcnt lgkmcnt(4)
	v_mfma_f32_32x32x16_bf16 v[32:47], v[100:103], v[108:111], v[32:47]
	v_mfma_f32_32x32x16_bf16 v[48:63], v[100:103], v[112:115], v[48:63]
	v_mfma_f32_32x32x16_bf16 v[0:15], v[104:107], v[108:111], v[0:15]
	v_mfma_f32_32x32x16_bf16 v[16:31], v[104:107], v[112:115], v[16:31]
	ds_read_b128 v[100:103], v79
	ds_read_b128 v[104:107], v79 offset:4096
	ds_read_b128 v[108:111], v83
	ds_read_b128 v[112:115], v83 offset:4096
	s_waitcnt lgkmcnt(4)
	v_mfma_f32_32x32x16_bf16 v[32:47], v[84:87], v[92:95], v[32:47]
	v_mfma_f32_32x32x16_bf16 v[48:63], v[84:87], v[96:99], v[48:63]
	v_mfma_f32_32x32x16_bf16 v[0:15], v[88:91], v[92:95], v[0:15]
	v_mfma_f32_32x32x16_bf16 v[16:31], v[88:91], v[96:99], v[16:31]
	s_waitcnt vmcnt(6) lgkmcnt(0)
	s_barrier
;     ...
;   if (PART != 2) {
;     GEMM_ISSUE(0, 0);
;     if (nk > 1) GEMM_ISSUE(1, 1);
;   }
;   if (PART == 1) return;
;   int st = 0;
;   for (int kt = 0; kt < nk; ++kt) {
;     if (kt + 1 < nk) asm volatile("s_waitcnt vmcnt(6)" ::: "memory");
;     else asm volatile("s_waitcnt vmcnt(0)" ::: "memory");
;     __builtin_amdgcn_s_barrier();
;     asm volatile("" ::: "memory");
;     if (kt + 2 < nk) { const int st2 = (st >= 1) ? st - 1 : 2; GEMM_ISSUE(kt + 2, st2); }
;     const char* la = lds + st * STAGE_B;
;     const char* lb = la + 32768;
;     const unsigned sa_u = (unsigned)(size_t)la + arow_u, sb_u = (unsigned)(size_t)lb + brow_u;
;     const unsigned a0 = sa_u + co0, a1 = sa_u + co1, a2 = sa_u + co2, a3 = sa_u + co3;
;     const unsigned b0 = sb_u + co0, b1 = sb_u + co1, b2 = sb_u + co2, b3 = sb_u + co3;
;     {
;       bf16x8 p0, p1, q0, q1, u0, u1, w0, w1;
;       asm volatile(
;         "ds_read_b128 %4, %12\n\tds_read_b128 %5, %12 offset:4096\n\tds_read_b128 %6, %16\n\tds_read_b128 %7, %16 offset:4096\n\t"
;         "ds_read_b128 %8, %13\n\tds_read_b128 %9, %13 offset:4096\n\tds_read_b128 %10, %17\n\tds_read_b128 %11, %17 offset:4096\n\t"
;         "s_waitcnt lgkmcnt(4)\n\t"
;         "v_mfma_f32_32x32x16_bf16 %0, %4, %6, %0\n\tv_mfma_f32_32x32x16_bf16 %1, %4, %7, %1\n\tv_mfma_f32_32x32x16_bf16 %2, %5, %6, %2\n\tv_mfma_f32_32x32x16_bf16 %3, %5, %7, %3\n\t"
;         "ds_read_b128 %4, %14\n\tds_read_b128 %5, %14 offset:4096\n\tds_read_b128 %6, %18\n\tds_read_b128 %7, %18 offset:4096\n\t"
;         "s_waitcnt lgkmcnt(4)\n\t"
;         "v_mfma_f32_32x32x16_bf16 %0, %8, %10, %0\n\tv_mfma_f32_32x32x16_bf16 %1, %8, %11, %1\n\tv_mfma_f32_32x32x16_bf16 %2, %9, %10, %2\n\tv_mfma_f32_32x32x16_bf16 %3, %9, %11, %3\n\t"
;         "ds_read_b128 %8, %15\n\tds_read_b128 %9, %15 offset:4096\n\tds_read_b128 %10, %19\n\tds_read_b128 %11, %19 offset:4096\n\t"
;         "s_waitcnt lgkmcnt(4)\n\t"
;         "v_mfma_f32_32x32x16_bf16 %0, %4, %6, %0\n\tv_mfma_f32_32x32x16_bf16 %1, %4, %7, %1\n\tv_mfma_f32_32x32x16_bf16 %2, %5, %6, %2\n\tv_mfma_f32_32x32x16_bf16 %3, %5, %7, %3\n\t"
;         "s_waitcnt lgkmcnt(0)\n\t"
;         "v_mfma_f32_32x32x16_bf16 %0, %8, %10, %0\n\tv_mfma_f32_32x32x16_bf16 %1, %8, %11, %1\n\tv_mfma_f32_32x32x16_bf16 %2, %9, %10, %2\n\tv_mfma_f32_32x32x16_bf16 %3, %9, %11, %3"
	ds_read_b128 v[84:87], v76 offset:49152
	ds_read_b128 v[88:91], v76 offset:53248
	ds_read_b128 v[92:95], v80 offset:49152
	ds_read_b128 v[96:99], v80 offset:53248
	v_mfma_f32_32x32x16_bf16 v[32:47], v[100:103], v[108:111], v[32:47]
	s_mov_b32 s24, 0x180
	s_mov_b32 m0, s30
	v_lshl_add_u64 v[124:125], v[64:65], 0, s[24:25]
	global_load_lds_dwordx4 v[124:125], off
	v_mfma_f32_32x32x16_bf16 v[48:63], v[100:103], v[112:115], v[48:63]
	v_mfma_f32_32x32x16_bf16 v[0:15], v[104:107], v[108:111], v[0:15]
	s_add_u32 m0, s30, 0x2000
	v_lshl_add_u64 v[126:127], v[66:67], 0, s[24:25]
	global_load_lds_dwordx4 v[126:127], off
	v_mfma_f32_32x32x16_bf16 v[16:31], v[104:107], v[112:115], v[16:31]
	ds_read_b128 v[100:103], v77 offset:49152
	ds_read_b128 v[104:107], v77 offset:53248
	ds_read_b128 v[108:111], v81 offset:49152
	ds_read_b128 v[112:115], v81 offset:53248
	s_waitcnt lgkmcnt(4)
	v_mfma_f32_32x32x16_bf16 v[32:47], v[84:87], v[92:95], v[32:47]
	s_add_u32 m0, s30, 0x4000
	v_lshl_add_u64 v[124:125], v[68:69], 0, s[24:25]
	global_load_lds_dwordx4 v[124:125], off
	v_mfma_f32_32x32x16_bf16 v[48:63], v[84:87], v[96:99], v[48:63]
	v_mfma_f32_32x32x16_bf16 v[0:15], v[88:91], v[92:95], v[0:15]
	s_add_u32 m0, s30, 0x6000
	v_lshl_add_u64 v[126:127], v[70:71], 0, s[24:25]
	global_load_lds_dwordx4 v[126:127], off
	v_mfma_f32_32x32x16_bf16 v[16:31], v[88:91], v[96:99], v[16:31]
	ds_read_b128 v[84:87], v78 offset:49152
	ds_read_b128 v[88:91], v78 offset:53248
	ds_read_b128 v[92:95], v82 offset:49152
	ds_read_b128 v[96:99], v82 offset:53248
	s_waitcnt lgkmcnt(4)
	v_mfma_f32_32x32x16_bf16 v[32:47], v[100:103], v[108:111], v[32:47]
	s_add_u32 m0, s30, 0x8000
	v_lshl_add_u64 v[124:125], v[72:73], 0, s[24:25]
	global_load_lds_dwordx4 v[124:125], off
	v_mfma_f32_32x32x16_bf16 v[48:63], v[100:103], v[112:115], v[48:63]
	v_mfma_f32_32x32x16_bf16 v[0:15], v[104:107], v[108:111], v[0:15]
	s_add_u32 m0, s30, 0xa000
	v_lshl_add_u64 v[126:127], v[74:75], 0, s[24:25]
	global_load_lds_dwordx4 v[126:127], off
	v_mfma_f32_32x32x16_bf16 v[16:31], v[104:107], v[112:115], v[16:31]
	ds_read_b128 v[100:103], v79 offset:49152
	ds_read_b128 v[104:107], v79 offset:53248
	ds_read_b128 v[108:111], v83 offset:49152
	ds_read_b128 v[112:115], v83 offset:53248
	s_waitcnt lgkmcnt(4)
	v_mfma_f32_32x32x16_bf16 v[32:47], v[84:87], v[92:95], v[32:47]
	v_mfma_f32_32x32x16_bf16 v[48:63], v[84:87], v[96:99], v[48:63]
	v_mfma_f32_32x32x16_bf16 v[0:15], v[88:91], v[92:95], v[0:15]
	v_mfma_f32_32x32x16_bf16 v[16:31], v[88:91], v[96:99], v[16:31]
	s_waitcnt vmcnt(6) lgkmcnt(0)
	s_barrier
	ds_read_b128 v[84:87], v116
	ds_read_b128 v[88:91], v116 offset:4096
	ds_read_b128 v[92:95], v120
	ds_read_b128 v[96:99], v120 offset:4096
	v_mfma_f32_32x32x16_bf16 v[32:47], v[100:103], v[108:111], v[32:47]
	s_mov_b32 s24, 0x200
	s_add_u32 m0, s30, 0xc000
	v_lshl_add_u64 v[124:125], v[64:65], 0, s[24:25]
	global_load_lds_dwordx4 v[124:125], off
	v_mfma_f32_32x32x16_bf16 v[48:63], v[100:103], v[112:115], v[48:63]
	v_mfma_f32_32x32x16_bf16 v[0:15], v[104:107], v[108:111], v[0:15]
	s_add_u32 m0, s30, 0xe000
	v_lshl_add_u64 v[126:127], v[66:67], 0, s[24:25]
	global_load_lds_dwordx4 v[126:127], off
	v_mfma_f32_32x32x16_bf16 v[16:31], v[104:107], v[112:115], v[16:31]
	ds_read_b128 v[100:103], v117
	ds_read_b128 v[104:107], v117 offset:4096
	ds_read_b128 v[108:111], v121
	ds_read_b128 v[112:115], v121 offset:4096
	s_waitcnt lgkmcnt(4)
	v_mfma_f32_32x32x16_bf16 v[32:47], v[84:87], v[92:95], v[32:47]
	s_add_u32 m0, s30, 0x10000
	v_lshl_add_u64 v[124:125], v[68:69], 0, s[24:25]
	global_load_lds_dwordx4 v[124:125], off
	v_mfma_f32_32x32x16_bf16 v[48:63], v[84:87], v[96:99], v[48:63]
	v_mfma_f32_32x32x16_bf16 v[0:15], v[88:91], v[92:95], v[0:15]
	s_add_u32 m0, s30, 0x12000
	v_lshl_add_u64 v[126:127], v[70:71], 0, s[24:25]
	global_load_lds_dwordx4 v[126:127], off
	v_mfma_f32_32x32x16_bf16 v[16:31], v[88:91], v[96:99], v[16:31]
	ds_read_b128 v[84:87], v118
	ds_read_b128 v[88:91], v118 offset:4096
	ds_read_b128 v[92:95], v122
	ds_read_b128 v[96:99], v122 offset:4096
	s_waitcnt lgkmcnt(4)
	v_mfma_f32_32x32x16_bf16 v[32:47], v[100:103], v[108:111], v[32:47]
	s_add_u32 m0, s30, 0x14000
	v_lshl_add_u64 v[124:125], v[72:73], 0, s[24:25]
	global_load_lds_dwordx4 v[124:125], off
	v_mfma_f32_32x32x16_bf16 v[48:63], v[100:103], v[112:115], v[48:63]
	v_mfma_f32_32x32x16_bf16 v[0:15], v[104:107], v[108:111], v[0:15]
	s_add_u32 m0, s30, 0x16000
	v_lshl_add_u64 v[126:127], v[74:75], 0, s[24:25]
	global_load_lds_dwordx4 v[126:127], off
	v_mfma_f32_32x32x16_bf16 v[16:31], v[104:107], v[112:115], v[16:31]
	ds_read_b128 v[100:103], v119
	ds_read_b128 v[104:107], v119 offset:4096
	ds_read_b128 v[108:111], v123
	ds_read_b128 v[112:115], v123 offset:4096
	s_waitcnt lgkmcnt(4)
	v_mfma_f32_32x32x16_bf16 v[32:47], v[84:87], v[92:95], v[32:47]
	v_mfma_f32_32x32x16_bf16 v[48:63], v[84:87], v[96:99], v[48:63]
	v_mfma_f32_32x32x16_bf16 v[0:15], v[88:91], v[92:95], v[0:15]
	v_mfma_f32_32x32x16_bf16 v[16:31], v[88:91], v[96:99], v[16:31]
	s_waitcnt vmcnt(6) lgkmcnt(0)
	s_barrier
;     ...
;   if (PART != 2) {
;     GEMM_ISSUE(0, 0);
;     if (nk > 1) GEMM_ISSUE(1, 1);
;   }
;   if (PART == 1) return;
;   int st = 0;
;   for (int kt = 0; kt < nk; ++kt) {
;     if (kt + 1 < nk) asm volatile("s_waitcnt vmcnt(6)" ::: "memory");
;     else asm volatile("s_waitcnt vmcnt(0)" ::: "memory");
;     __builtin_amdgcn_s_barrier();
;     asm volatile("" ::: "memory");
;     if (kt + 2 < nk) { const int st2 = (st >= 1) ? st - 1 : 2; GEMM_ISSUE(kt + 2, st2); }
;     const char* la = lds + st * STAGE_B;
;     const char* lb = la + 32768;
;     const unsigned sa_u = (unsigned)(size_t)la + arow_u, sb_u = (unsigned)(size_t)lb + brow_u;
;     const unsigned a0 = sa_u + co0, a1 = sa_u + co1, a2 = sa_u + co2, a3 = sa_u + co3;
;     const unsigned b0 = sb_u + co0, b1 = sb_u + co1, b2 = sb_u + co2, b3 = sb_u + co3;
;     {
;       bf16x8 p0, p1, q0, q1, u0, u1, w0, w1;
;       asm volatile(
;         "ds_read_b128 %4, %12\n\tds_read_b128 %5, %12 offset:4096\n\tds_read_b128 %6, %16\n\tds_read_b128 %7, %16 offset:4096\n\t"
;         "ds_read_b128 %8, %13\n\tds_read_b128 %9, %13 offset:4096\n\tds_read_b128 %10, %17\n\tds_read_b128 %11, %17 offset:4096\n\t"
;         "s_waitcnt lgkmcnt(4)\n\t"
;         "v_mfma_f32_32x32x16_bf16 %0, %4, %6, %0\n\tv_mfma_f32_32x32x16_bf16 %1, %4, %7, %1\n\tv_mfma_f32_32x32x16_bf16 %2, %5, %6, %2\n\tv_mfma_f32_32x32x16_bf16 %3, %5, %7, %3\n\t"
;         "ds_read_b128 %4, %14\n\tds_read_b128 %5, %14 offset:4096\n\tds_read_b128 %6, %18\n\tds_read_b128 %7, %18 offset:4096\n\t"
;         "s_waitcnt lgkmcnt(4)\n\t"
;         "v_mfma_f32_32x32x16_bf16 %0, %8, %10, %0\n\tv_mfma_f32_32x32x16_bf16 %1, %8, %11, %1\n\tv_mfma_f32_32x32x16_bf16 %2, %9, %10, %2\n\tv_mfma_f32_32x32x16_bf16 %3, %9, %11, %3\n\t"
;         "ds_read_b128 %8, %15\n\tds_read_b128 %9, %15 offset:4096\n\tds_read_b128 %10, %19\n\tds_read_b128 %11, %19 offset:4096\n\t"
;         "s_waitcnt lgkmcnt(4)\n\t"
;         "v_mfma_f32_32x32x16_bf16 %0, %4, %6, %0\n\tv_mfma_f32_32x32x16_bf16 %1, %4, %7, %1\n\tv_mfma_f32_32x32x16_bf16 %2, %5, %6, %2\n\tv_mfma_f32_32x32x16_bf16 %3, %5, %7, %3\n\t"
;         "s_waitcnt lgkmcnt(0)\n\t"
;         "v_mfma_f32_32x32x16_bf16 %0, %8, %10, %0\n\tv_mfma_f32_32x32x16_bf16 %1, %8, %11, %1\n\tv_mfma_f32_32x32x16_bf16 %2, %9, %10, %2\n\tv_mfma_f32_32x32x16_bf16 %3, %9, %11, %3"
	ds_read_b128 v[84:87], v76
	ds_read_b128 v[88:91], v76 offset:4096
	ds_read_b128 v[92:95], v80
	ds_read_b128 v[96:99], v80 offset:4096
	v_mfma_f32_32x32x16_bf16 v[32:47], v[100:103], v[108:111], v[32:47]
	s_mov_b32 s24, 0x280
	s_add_u32 m0, s30, 0x18000
	v_lshl_add_u64 v[124:125], v[64:65], 0, s[24:25]
	global_load_lds_dwordx4 v[124:125], off
	v_mfma_f32_32x32x16_bf16 v[48:63], v[100:103], v[112:115], v[48:63]
	v_mfma_f32_32x32x16_bf16 v[0:15], v[104:107], v[108:111], v[0:15]
	s_add_u32 m0, s30, 0x1a000
	v_lshl_add_u64 v[126:127], v[66:67], 0, s[24:25]
	global_load_lds_dwordx4 v[126:127], off
	v_mfma_f32_32x32x16_bf16 v[16:31], v[104:107], v[112:115], v[16:31]
	ds_read_b128 v[100:103], v77
	ds_read_b128 v[104:107], v77 offset:4096
	ds_read_b128 v[108:111], v81
	ds_read_b128 v[112:115], v81 offset:4096
	s_waitcnt lgkmcnt(4)
	v_mfma_f32_32x32x16_bf16 v[32:47], v[84:87], v[92:95], v[32:47]
	s_add_u32 m0, s30, 0x1c000
	v_lshl_add_u64 v[124:125], v[68:69], 0, s[24:25]
	global_load_lds_dwordx4 v[124:125], off
	v_mfma_f32_32x32x16_bf16 v[48:63], v[84:87], v[96:99], v[48:63]
	v_mfma_f32_32x32x16_bf16 v[0:15], v[88:91], v[92:95], v[0:15]
	s_add_u32 m0, s30, 0x1e000
	v_lshl_add_u64 v[126:127], v[70:71], 0, s[24:25]
	global_load_lds_dwordx4 v[126:127], off
	v_mfma_f32_32x32x16_bf16 v[16:31], v[88:91], v[96:99], v[16:31]
	ds_read_b128 v[84:87], v78
	ds_read_b128 v[88:91], v78 offset:4096
	ds_read_b128 v[92:95], v82
	ds_read_b128 v[96:99], v82 offset:4096
	s_waitcnt lgkmcnt(4)
	v_mfma_f32_32x32x16_bf16 v[32:47], v[100:103], v[108:111], v[32:47]
	s_add_u32 m0, s30, 0x20000
	v_lshl_add_u64 v[124:125], v[72:73], 0, s[24:25]
	global_load_lds_dwordx4 v[124:125], off
	v_mfma_f32_32x32x16_bf16 v[48:63], v[100:103], v[112:115], v[48:63]
	v_mfma_f32_32x32x16_bf16 v[0:15], v[104:107], v[108:111], v[0:15]
	s_add_u32 m0, s30, 0x22000
	v_lshl_add_u64 v[126:127], v[74:75], 0, s[24:25]
	global_load_lds_dwordx4 v[126:127], off
	v_mfma_f32_32x32x16_bf16 v[16:31], v[104:107], v[112:115], v[16:31]
	ds_read_b128 v[100:103], v79
	ds_read_b128 v[104:107], v79 offset:4096
	ds_read_b128 v[108:111], v83
	ds_read_b128 v[112:115], v83 offset:4096
	s_waitcnt lgkmcnt(4)
	v_mfma_f32_32x32x16_bf16 v[32:47], v[84:87], v[92:95], v[32:47]
	v_mfma_f32_32x32x16_bf16 v[48:63], v[84:87], v[96:99], v[48:63]
	v_mfma_f32_32x32x16_bf16 v[0:15], v[88:91], v[92:95], v[0:15]
	v_mfma_f32_32x32x16_bf16 v[16:31], v[88:91], v[96:99], v[16:31]
	s_waitcnt vmcnt(6) lgkmcnt(0)
	s_barrier
	ds_read_b128 v[84:87], v76 offset:49152
	ds_read_b128 v[88:91], v76 offset:53248
	ds_read_b128 v[92:95], v80 offset:49152
	ds_read_b128 v[96:99], v80 offset:53248
	v_mfma_f32_32x32x16_bf16 v[32:47], v[100:103], v[108:111], v[32:47]
	s_mov_b32 s24, 0x300
	s_mov_b32 m0, s30
	v_lshl_add_u64 v[124:125], v[64:65], 0, s[24:25]
	global_load_lds_dwordx4 v[124:125], off
	v_mfma_f32_32x32x16_bf16 v[48:63], v[100:103], v[112:115], v[48:63]
	v_mfma_f32_32x32x16_bf16 v[0:15], v[104:107], v[108:111], v[0:15]
	s_add_u32 m0, s30, 0x2000
	v_lshl_add_u64 v[126:127], v[66:67], 0, s[24:25]
	global_load_lds_dwordx4 v[126:127], off
	v_mfma_f32_32x32x16_bf16 v[16:31], v[104:107], v[112:115], v[16:31]
	ds_read_b128 v[100:103], v77 offset:49152
	ds_read_b128 v[104:107], v77 offset:53248
	ds_read_b128 v[108:111], v81 offset:49152
	ds_read_b128 v[112:115], v81 offset:53248
	s_waitcnt lgkmcnt(4)
	v_mfma_f32_32x32x16_bf16 v[32:47], v[84:87], v[92:95], v[32:47]
	s_add_u32 m0, s30, 0x4000
	v_lshl_add_u64 v[124:125], v[68:69], 0, s[24:25]
	global_load_lds_dwordx4 v[124:125], off
	v_mfma_f32_32x32x16_bf16 v[48:63], v[84:87], v[96:99], v[48:63]
	v_mfma_f32_32x32x16_bf16 v[0:15], v[88:91], v[92:95], v[0:15]
	s_add_u32 m0, s30, 0x6000
	v_lshl_add_u64 v[126:127], v[70:71], 0, s[24:25]
	global_load_lds_dwordx4 v[126:127], off
	v_mfma_f32_32x32x16_bf16 v[16:31], v[88:91], v[96:99], v[16:31]
	ds_read_b128 v[84:87], v78 offset:49152
	ds_read_b128 v[88:91], v78 offset:53248
	ds_read_b128 v[92:95], v82 offset:49152
	ds_read_b128 v[96:99], v82 offset:53248
	s_waitcnt lgkmcnt(4)
	v_mfma_f32_32x32x16_bf16 v[32:47], v[100:103], v[108:111], v[32:47]
	s_add_u32 m0, s30, 0x8000
	v_lshl_add_u64 v[124:125], v[72:73], 0, s[24:25]
	global_load_lds_dwordx4 v[124:125], off
	v_mfma_f32_32x32x16_bf16 v[48:63], v[100:103], v[112:115], v[48:63]
	v_mfma_f32_32x32x16_bf16 v[0:15], v[104:107], v[108:111], v[0:15]
	s_add_u32 m0, s30, 0xa000
	v_lshl_add_u64 v[126:127], v[74:75], 0, s[24:25]
	global_load_lds_dwordx4 v[126:127], off
	v_mfma_f32_32x32x16_bf16 v[16:31], v[104:107], v[112:115], v[16:31]
	ds_read_b128 v[100:103], v79 offset:49152
	ds_read_b128 v[104:107], v79 offset:53248
	ds_read_b128 v[108:111], v83 offset:49152
	ds_read_b128 v[112:115], v83 offset:53248
	s_waitcnt lgkmcnt(4)
	v_mfma_f32_32x32x16_bf16 v[32:47], v[84:87], v[92:95], v[32:47]
	v_mfma_f32_32x32x16_bf16 v[48:63], v[84:87], v[96:99], v[48:63]
	v_mfma_f32_32x32x16_bf16 v[0:15], v[88:91], v[92:95], v[0:15]
	v_mfma_f32_32x32x16_bf16 v[16:31], v[88:91], v[96:99], v[16:31]
	s_waitcnt vmcnt(6) lgkmcnt(0)
	s_barrier
;     ...
;   if (PART != 2) {
;     GEMM_ISSUE(0, 0);
;     if (nk > 1) GEMM_ISSUE(1, 1);
;   }
;   if (PART == 1) return;
;   int st = 0;
;   for (int kt = 0; kt < nk; ++kt) {
;     if (kt + 1 < nk) asm volatile("s_waitcnt vmcnt(6)" ::: "memory");
;     else asm volatile("s_waitcnt vmcnt(0)" ::: "memory");
;     __builtin_amdgcn_s_barrier();
;     asm volatile("" ::: "memory");
;     if (kt + 2 < nk) { const int st2 = (st >= 1) ? st - 1 : 2; GEMM_ISSUE(kt + 2, st2); }
;     const char* la = lds + st * STAGE_B;
;     const char* lb = la + 32768;
;     const unsigned sa_u = (unsigned)(size_t)la + arow_u, sb_u = (unsigned)(size_t)lb + brow_u;
;     const unsigned a0 = sa_u + co0, a1 = sa_u + co1, a2 = sa_u + co2, a3 = sa_u + co3;
;     const unsigned b0 = sb_u + co0, b1 = sb_u + co1, b2 = sb_u + co2, b3 = sb_u + co3;
;     {
;       bf16x8 p0, p1, q0, q1, u0, u1, w0, w1;
;       asm volatile(
;         "ds_read_b128 %4, %12\n\tds_read_b128 %5, %12 offset:4096\n\tds_read_b128 %6, %16\n\tds_read_b128 %7, %16 offset:4096\n\t"
;         "ds_read_b128 %8, %13\n\tds_read_b128 %9, %13 offset:4096\n\tds_read_b128 %10, %17\n\tds_read_b128 %11, %17 offset:4096\n\t"
;         "s_waitcnt lgkmcnt(4)\n\t"
;         "v_mfma_f32_32x32x16_bf16 %0, %4, %6, %0\n\tv_mfma_f32_32x32x16_bf16 %1, %4, %7, %1\n\tv_mfma_f32_32x32x16_bf16 %2, %5, %6, %2\n\tv_mfma_f32_32x32x16_bf16 %3, %5, %7, %3\n\t"
;         "ds_read_b128 %4, %14\n\tds_read_b128 %5, %14 offset:4096\n\tds_read_b128 %6, %18\n\tds_read_b128 %7, %18 offset:4096\n\t"
;         "s_waitcnt lgkmcnt(4)\n\t"
;         "v_mfma_f32_32x32x16_bf16 %0, %8, %10, %0\n\tv_mfma_f32_32x32x16_bf16 %1, %8, %11, %1\n\tv_mfma_f32_32x32x16_bf16 %2, %9, %10, %2\n\tv_mfma_f32_32x32x16_bf16 %3, %9, %11, %3\n\t"
;         "ds_read_b128 %8, %15\n\tds_read_b128 %9, %15 offset:4096\n\tds_read_b128 %10, %19\n\tds_read_b128 %11, %19 offset:4096\n\t"
;         "s_waitcnt lgkmcnt(4)\n\t"
;         "v_mfma_f32_32x32x16_bf16 %0, %4, %6, %0\n\tv_mfma_f32_32x32x16_bf16 %1, %4, %7, %1\n\tv_mfma_f32_32x32x16_bf16 %2, %5, %6, %2\n\tv_mfma_f32_32x32x16_bf16 %3, %5, %7, %3\n\t"
;         "s_waitcnt lgkmcnt(0)\n\t"
;         "v_mfma_f32_32x32x16_bf16 %0, %8, %10, %0\n\tv_mfma_f32_32x32x16_bf16 %1, %8, %11, %1\n\tv_mfma_f32_32x32x16_bf16 %2, %9, %10, %2\n\tv_mfma_f32_32x32x16_bf16 %3, %9, %11, %3"
	ds_read_b128 v[84:87], v116
	ds_read_b128 v[88:91], v116 offset:4096
	ds_read_b128 v[92:95], v120
	ds_read_b128 v[96:99], v120 offset:4096
	v_mfma_f32_32x32x16_bf16 v[32:47], v[100:103], v[108:111], v[32:47]
	s_mov_b32 s24, 0x380
	s_add_u32 m0, s30, 0xc000
	v_lshl_add_u64 v[124:125], v[64:65], 0, s[24:25]
	global_load_lds_dwordx4 v[124:125], off
	v_mfma_f32_32x32x16_bf16 v[48:63], v[100:103], v[112:115], v[48:63]
	v_mfma_f32_32x32x16_bf16 v[0:15], v[104:107], v[108:111], v[0:15]
	s_add_u32 m0, s30, 0xe000
	v_lshl_add_u64 v[126:127], v[66:67], 0, s[24:25]
	global_load_lds_dwordx4 v[126:127], off
	v_mfma_f32_32x32x16_bf16 v[16:31], v[104:107], v[112:115], v[16:31]
	ds_read_b128 v[100:103], v117
	ds_read_b128 v[104:107], v117 offset:4096
	ds_read_b128 v[108:111], v121
	ds_read_b128 v[112:115], v121 offset:4096
	s_waitcnt lgkmcnt(4)
	v_mfma_f32_32x32x16_bf16 v[32:47], v[84:87], v[92:95], v[32:47]
	s_add_u32 m0, s30, 0x10000
	v_lshl_add_u64 v[124:125], v[68:69], 0, s[24:25]
	global_load_lds_dwordx4 v[124:125], off
	v_mfma_f32_32x32x16_bf16 v[48:63], v[84:87], v[96:99], v[48:63]
	v_mfma_f32_32x32x16_bf16 v[0:15], v[88:91], v[92:95], v[0:15]
	s_add_u32 m0, s30, 0x12000
	v_lshl_add_u64 v[126:127], v[70:71], 0, s[24:25]
	global_load_lds_dwordx4 v[126:127], off
	v_mfma_f32_32x32x16_bf16 v[16:31], v[88:91], v[96:99], v[16:31]
	ds_read_b128 v[84:87], v118
	ds_read_b128 v[88:91], v118 offset:4096
	ds_read_b128 v[92:95], v122
	ds_read_b128 v[96:99], v122 offset:4096
	s_waitcnt lgkmcnt(4)
	v_mfma_f32_32x32x16_bf16 v[32:47], v[100:103], v[108:111], v[32:47]
	s_add_u32 m0, s30, 0x14000
	v_lshl_add_u64 v[124:125], v[72:73], 0, s[24:25]
	global_load_lds_dwordx4 v[124:125], off
	v_mfma_f32_32x32x16_bf16 v[48:63], v[100:103], v[112:115], v[48:63]
	v_mfma_f32_32x32x16_bf16 v[0:15], v[104:107], v[108:111], v[0:15]
	s_add_u32 m0, s30, 0x16000
	v_lshl_add_u64 v[126:127], v[74:75], 0, s[24:25]
	global_load_lds_dwordx4 v[126:127], off
	v_mfma_f32_32x32x16_bf16 v[16:31], v[104:107], v[112:115], v[16:31]
	ds_read_b128 v[100:103], v119
	ds_read_b128 v[104:107], v119 offset:4096
	ds_read_b128 v[108:111], v123
	ds_read_b128 v[112:115], v123 offset:4096
	s_waitcnt lgkmcnt(4)
	v_mfma_f32_32x32x16_bf16 v[32:47], v[84:87], v[92:95], v[32:47]
	v_mfma_f32_32x32x16_bf16 v[48:63], v[84:87], v[96:99], v[48:63]
	v_mfma_f32_32x32x16_bf16 v[0:15], v[88:91], v[92:95], v[0:15]
	v_mfma_f32_32x32x16_bf16 v[16:31], v[88:91], v[96:99], v[16:31]
	s_waitcnt vmcnt(6) lgkmcnt(0)
	s_barrier
	ds_read_b128 v[84:87], v76
	ds_read_b128 v[88:91], v76 offset:4096
	ds_read_b128 v[92:95], v80
	ds_read_b128 v[96:99], v80 offset:4096
	v_mfma_f32_32x32x16_bf16 v[32:47], v[100:103], v[108:111], v[32:47]
	s_mov_b32 s24, 0x400
	s_add_u32 m0, s30, 0x18000
	v_lshl_add_u64 v[124:125], v[64:65], 0, s[24:25]
	global_load_lds_dwordx4 v[124:125], off
	v_mfma_f32_32x32x16_bf16 v[48:63], v[100:103], v[112:115], v[48:63]
	v_mfma_f32_32x32x16_bf16 v[0:15], v[104:107], v[108:111], v[0:15]
	s_add_u32 m0, s30, 0x1a000
	v_lshl_add_u64 v[126:127], v[66:67], 0, s[24:25]
	global_load_lds_dwordx4 v[126:127], off
	v_mfma_f32_32x32x16_bf16 v[16:31], v[104:107], v[112:115], v[16:31]
	ds_read_b128 v[100:103], v77
	ds_read_b128 v[104:107], v77 offset:4096
	ds_read_b128 v[108:111], v81
	ds_read_b128 v[112:115], v81 offset:4096
	s_waitcnt lgkmcnt(4)
	v_mfma_f32_32x32x16_bf16 v[32:47], v[84:87], v[92:95], v[32:47]
	s_add_u32 m0, s30, 0x1c000
	v_lshl_add_u64 v[124:125], v[68:69], 0, s[24:25]
	global_load_lds_dwordx4 v[124:125], off
	v_mfma_f32_32x32x16_bf16 v[48:63], v[84:87], v[96:99], v[48:63]
	v_mfma_f32_32x32x16_bf16 v[0:15], v[88:91], v[92:95], v[0:15]
	s_add_u32 m0, s30, 0x1e000
	v_lshl_add_u64 v[126:127], v[70:71], 0, s[24:25]
	global_load_lds_dwordx4 v[126:127], off
	v_mfma_f32_32x32x16_bf16 v[16:31], v[88:91], v[96:99], v[16:31]
	ds_read_b128 v[84:87], v78
	ds_read_b128 v[88:91], v78 offset:4096
	ds_read_b128 v[92:95], v82
	ds_read_b128 v[96:99], v82 offset:4096
	s_waitcnt lgkmcnt(4)
	v_mfma_f32_32x32x16_bf16 v[32:47], v[100:103], v[108:111], v[32:47]
	s_add_u32 m0, s30, 0x20000
	v_lshl_add_u64 v[124:125], v[72:73], 0, s[24:25]
	global_load_lds_dwordx4 v[124:125], off
	v_mfma_f32_32x32x16_bf16 v[48:63], v[100:103], v[112:115], v[48:63]
	v_mfma_f32_32x32x16_bf16 v[0:15], v[104:107], v[108:111], v[0:15]
	s_add_u32 m0, s30, 0x22000
	v_lshl_add_u64 v[126:127], v[74:75], 0, s[24:25]
	global_load_lds_dwordx4 v[126:127], off
	v_mfma_f32_32x32x16_bf16 v[16:31], v[104:107], v[112:115], v[16:31]
	ds_read_b128 v[100:103], v79
	ds_read_b128 v[104:107], v79 offset:4096
	ds_read_b128 v[108:111], v83
	ds_read_b128 v[112:115], v83 offset:4096
	s_waitcnt lgkmcnt(4)
	v_mfma_f32_32x32x16_bf16 v[32:47], v[84:87], v[92:95], v[32:47]
	v_mfma_f32_32x32x16_bf16 v[48:63], v[84:87], v[96:99], v[48:63]
	v_mfma_f32_32x32x16_bf16 v[0:15], v[88:91], v[92:95], v[0:15]
	v_mfma_f32_32x32x16_bf16 v[16:31], v[88:91], v[96:99], v[16:31]
	s_waitcnt vmcnt(6) lgkmcnt(0)
	s_barrier
;     ...
;   if (PART != 2) {
;     GEMM_ISSUE(0, 0);
;     if (nk > 1) GEMM_ISSUE(1, 1);
;   }
;   if (PART == 1) return;
;   int st = 0;
;   for (int kt = 0; kt < nk; ++kt) {
;     if (kt + 1 < nk) asm volatile("s_waitcnt vmcnt(6)" ::: "memory");
;     else asm volatile("s_waitcnt vmcnt(0)" ::: "memory");
;     __builtin_amdgcn_s_barrier();
;     asm volatile("" ::: "memory");
;     if (kt + 2 < nk) { const int st2 = (st >= 1) ? st - 1 : 2; GEMM_ISSUE(kt + 2, st2); }
;     const char* la = lds + st * STAGE_B;
;     const char* lb = la + 32768;
;     const unsigned sa_u = (unsigned)(size_t)la + arow_u, sb_u = (unsigned)(size_t)lb + brow_u;
;     const unsigned a0 = sa_u + co0, a1 = sa_u + co1, a2 = sa_u + co2, a3 = sa_u + co3;
;     const unsigned b0 = sb_u + co0, b1 = sb_u + co1, b2 = sb_u + co2, b3 = sb_u + co3;
;     {
;       bf16x8 p0, p1, q0, q1, u0, u1, w0, w1;
;       asm volatile(
;         "ds_read_b128 %4, %12\n\tds_read_b128 %5, %12 offset:4096\n\tds_read_b128 %6, %16\n\tds_read_b128 %7, %16 offset:4096\n\t"
;         "ds_read_b128 %8, %13\n\tds_read_b128 %9, %13 offset:4096\n\tds_read_b128 %10, %17\n\tds_read_b128 %11, %17 offset:4096\n\t"
;         "s_waitcnt lgkmcnt(4)\n\t"
;         "v_mfma_f32_32x32x16_bf16 %0, %4, %6, %0\n\tv_mfma_f32_32x32x16_bf16 %1, %4, %7, %1\n\tv_mfma_f32_32x32x16_bf16 %2, %5, %6, %2\n\tv_mfma_f32_32x32x16_bf16 %3, %5, %7, %3\n\t"
;         "ds_read_b128 %4, %14\n\tds_read_b128 %5, %14 offset:4096\n\tds_read_b128 %6, %18\n\tds_read_b128 %7, %18 offset:4096\n\t"
;         "s_waitcnt lgkmcnt(4)\n\t"
;         "v_mfma_f32_32x32x16_bf16 %0, %8, %10, %0\n\tv_mfma_f32_32x32x16_bf16 %1, %8, %11, %1\n\tv_mfma_f32_32x32x16_bf16 %2, %9, %10, %2\n\tv_mfma_f32_32x32x16_bf16 %3, %9, %11, %3\n\t"
;         "ds_read_b128 %8, %15\n\tds_read_b128 %9, %15 offset:4096\n\tds_read_b128 %10, %19\n\tds_read_b128 %11, %19 offset:4096\n\t"
;         "s_waitcnt lgkmcnt(4)\n\t"
;         "v_mfma_f32_32x32x16_bf16 %0, %4, %6, %0\n\tv_mfma_f32_32x32x16_bf16 %1, %4, %7, %1\n\tv_mfma_f32_32x32x16_bf16 %2, %5, %6, %2\n\tv_mfma_f32_32x32x16_bf16 %3, %5, %7, %3\n\t"
;         "s_waitcnt lgkmcnt(0)\n\t"
;         "v_mfma_f32_32x32x16_bf16 %0, %8, %10, %0\n\tv_mfma_f32_32x32x16_bf16 %1, %8, %11, %1\n\tv_mfma_f32_32x32x16_bf16 %2, %9, %10, %2\n\tv_mfma_f32_32x32x16_bf16 %3, %9, %11, %3"
	ds_read_b128 v[84:87], v76 offset:49152
	ds_read_b128 v[88:91], v76 offset:53248
	ds_read_b128 v[92:95], v80 offset:49152
	ds_read_b128 v[96:99], v80 offset:53248
	v_mfma_f32_32x32x16_bf16 v[32:47], v[100:103], v[108:111], v[32:47]
	s_mov_b32 s24, 0x480
	s_mov_b32 m0, s30
	v_lshl_add_u64 v[124:125], v[64:65], 0, s[24:25]
	global_load_lds_dwordx4 v[124:125], off
	v_mfma_f32_32x32x16_bf16 v[48:63], v[100:103], v[112:115], v[48:63]
	v_mfma_f32_32x32x16_bf16 v[0:15], v[104:107], v[108:111], v[0:15]
	s_add_u32 m0, s30, 0x2000
	v_lshl_add_u64 v[126:127], v[66:67], 0, s[24:25]
	global_load_lds_dwordx4 v[126:127], off
	v_mfma_f32_32x32x16_bf16 v[16:31], v[104:107], v[112:115], v[16:31]
	ds_read_b128 v[100:103], v77 offset:49152
	ds_read_b128 v[104:107], v77 offset:53248
	ds_read_b128 v[108:111], v81 offset:49152
	ds_read_b128 v[112:115], v81 offset:53248
	s_waitcnt lgkmcnt(4)
	v_mfma_f32_32x32x16_bf16 v[32:47], v[84:87], v[92:95], v[32:47]
	s_add_u32 m0, s30, 0x4000
	v_lshl_add_u64 v[124:125], v[68:69], 0, s[24:25]
	global_load_lds_dwordx4 v[124:125], off
	v_mfma_f32_32x32x16_bf16 v[48:63], v[84:87], v[96:99], v[48:63]
	v_mfma_f32_32x32x16_bf16 v[0:15], v[88:91], v[92:95], v[0:15]
	s_add_u32 m0, s30, 0x6000
	v_lshl_add_u64 v[126:127], v[70:71], 0, s[24:25]
	global_load_lds_dwordx4 v[126:127], off
	v_mfma_f32_32x32x16_bf16 v[16:31], v[88:91], v[96:99], v[16:31]
	ds_read_b128 v[84:87], v78 offset:49152
	ds_read_b128 v[88:91], v78 offset:53248
	ds_read_b128 v[92:95], v82 offset:49152
	ds_read_b128 v[96:99], v82 offset:53248
	s_waitcnt lgkmcnt(4)
	v_mfma_f32_32x32x16_bf16 v[32:47], v[100:103], v[108:111], v[32:47]
	s_add_u32 m0, s30, 0x8000
	v_lshl_add_u64 v[124:125], v[72:73], 0, s[24:25]
	global_load_lds_dwordx4 v[124:125], off
	v_mfma_f32_32x32x16_bf16 v[48:63], v[100:103], v[112:115], v[48:63]
	v_mfma_f32_32x32x16_bf16 v[0:15], v[104:107], v[108:111], v[0:15]
	s_add_u32 m0, s30, 0xa000
	v_lshl_add_u64 v[126:127], v[74:75], 0, s[24:25]
	global_load_lds_dwordx4 v[126:127], off
	v_mfma_f32_32x32x16_bf16 v[16:31], v[104:107], v[112:115], v[16:31]
	ds_read_b128 v[100:103], v79 offset:49152
	ds_read_b128 v[104:107], v79 offset:53248
	ds_read_b128 v[108:111], v83 offset:49152
	ds_read_b128 v[112:115], v83 offset:53248
	s_waitcnt lgkmcnt(4)
	v_mfma_f32_32x32x16_bf16 v[32:47], v[84:87], v[92:95], v[32:47]
	v_mfma_f32_32x32x16_bf16 v[48:63], v[84:87], v[96:99], v[48:63]
	v_mfma_f32_32x32x16_bf16 v[0:15], v[88:91], v[92:95], v[0:15]
	v_mfma_f32_32x32x16_bf16 v[16:31], v[88:91], v[96:99], v[16:31]
	s_waitcnt vmcnt(6) lgkmcnt(0)
	s_barrier
	ds_read_b128 v[84:87], v116
	ds_read_b128 v[88:91], v116 offset:4096
	ds_read_b128 v[92:95], v120
	ds_read_b128 v[96:99], v120 offset:4096
	v_mfma_f32_32x32x16_bf16 v[32:47], v[100:103], v[108:111], v[32:47]
	s_mov_b32 s24, 0x500
	s_add_u32 m0, s30, 0xc000
	v_lshl_add_u64 v[124:125], v[64:65], 0, s[24:25]
	global_load_lds_dwordx4 v[124:125], off
	v_mfma_f32_32x32x16_bf16 v[48:63], v[100:103], v[112:115], v[48:63]
	v_mfma_f32_32x32x16_bf16 v[0:15], v[104:107], v[108:111], v[0:15]
	s_add_u32 m0, s30, 0xe000
	v_lshl_add_u64 v[126:127], v[66:67], 0, s[24:25]
	global_load_lds_dwordx4 v[126:127], off
	v_mfma_f32_32x32x16_bf16 v[16:31], v[104:107], v[112:115], v[16:31]
	ds_read_b128 v[100:103], v117
	ds_read_b128 v[104:107], v117 offset:4096
	ds_read_b128 v[108:111], v121
	ds_read_b128 v[112:115], v121 offset:4096
	s_waitcnt lgkmcnt(4)
	v_mfma_f32_32x32x16_bf16 v[32:47], v[84:87], v[92:95], v[32:47]
	s_add_u32 m0, s30, 0x10000
	v_lshl_add_u64 v[124:125], v[68:69], 0, s[24:25]
	global_load_lds_dwordx4 v[124:125], off
	v_mfma_f32_32x32x16_bf16 v[48:63], v[84:87], v[96:99], v[48:63]
	v_mfma_f32_32x32x16_bf16 v[0:15], v[88:91], v[92:95], v[0:15]
	s_add_u32 m0, s30, 0x12000
	v_lshl_add_u64 v[126:127], v[70:71], 0, s[24:25]
	global_load_lds_dwordx4 v[126:127], off
	v_mfma_f32_32x32x16_bf16 v[16:31], v[88:91], v[96:99], v[16:31]
	ds_read_b128 v[84:87], v118
	ds_read_b128 v[88:91], v118 offset:4096
	ds_read_b128 v[92:95], v122
	ds_read_b128 v[96:99], v122 offset:4096
	s_waitcnt lgkmcnt(4)
	v_mfma_f32_32x32x16_bf16 v[32:47], v[100:103], v[108:111], v[32:47]
	s_add_u32 m0, s30, 0x14000
	v_lshl_add_u64 v[124:125], v[72:73], 0, s[24:25]
	global_load_lds_dwordx4 v[124:125], off
	v_mfma_f32_32x32x16_bf16 v[48:63], v[100:103], v[112:115], v[48:63]
	v_mfma_f32_32x32x16_bf16 v[0:15], v[104:107], v[108:111], v[0:15]
	s_add_u32 m0, s30, 0x16000
	v_lshl_add_u64 v[126:127], v[74:75], 0, s[24:25]
	global_load_lds_dwordx4 v[126:127], off
	v_mfma_f32_32x32x16_bf16 v[16:31], v[104:107], v[112:115], v[16:31]
	ds_read_b128 v[100:103], v119
	ds_read_b128 v[104:107], v119 offset:4096
	ds_read_b128 v[108:111], v123
	ds_read_b128 v[112:115], v123 offset:4096
	s_waitcnt lgkmcnt(4)
	v_mfma_f32_32x32x16_bf16 v[32:47], v[84:87], v[92:95], v[32:47]
	v_mfma_f32_32x32x16_bf16 v[48:63], v[84:87], v[96:99], v[48:63]
	v_mfma_f32_32x32x16_bf16 v[0:15], v[88:91], v[92:95], v[0:15]
	v_mfma_f32_32x32x16_bf16 v[16:31], v[88:91], v[96:99], v[16:31]
	s_waitcnt vmcnt(6) lgkmcnt(0)
	s_barrier
;     ...
;   if (PART != 2) {
;     GEMM_ISSUE(0, 0);
;     if (nk > 1) GEMM_ISSUE(1, 1);
;   }
;   if (PART == 1) return;
;   int st = 0;
;   for (int kt = 0; kt < nk; ++kt) {
;     if (kt + 1 < nk) asm volatile("s_waitcnt vmcnt(6)" ::: "memory");
;     else asm volatile("s_waitcnt vmcnt(0)" ::: "memory");
;     __builtin_amdgcn_s_barrier();
;     asm volatile("" ::: "memory");
;     if (kt + 2 < nk) { const int st2 = (st >= 1) ? st - 1 : 2; GEMM_ISSUE(kt + 2, st2); }
;     const char* la = lds + st * STAGE_B;
;     const char* lb = la + 32768;
;     const unsigned sa_u = (unsigned)(size_t)la + arow_u, sb_u = (unsigned)(size_t)lb + brow_u;
;     const unsigned a0 = sa_u + co0, a1 = sa_u + co1, a2 = sa_u + co2, a3 = sa_u + co3;
;     const unsigned b0 = sb_u + co0, b1 = sb_u + co1, b2 = sb_u + co2, b3 = sb_u + co3;
;     {
;       bf16x8 p0, p1, q0, q1, u0, u1, w0, w1;
;       asm volatile(
;         "ds_read_b128 %4, %12\n\tds_read_b128 %5, %12 offset:4096\n\tds_read_b128 %6, %16\n\tds_read_b128 %7, %16 offset:4096\n\t"
;         "ds_read_b128 %8, %13\n\tds_read_b128 %9, %13 offset:4096\n\tds_read_b128 %10, %17\n\tds_read_b128 %11, %17 offset:4096\n\t"
;         "s_waitcnt lgkmcnt(4)\n\t"
;         "v_mfma_f32_32x32x16_bf16 %0, %4, %6, %0\n\tv_mfma_f32_32x32x16_bf16 %1, %4, %7, %1\n\tv_mfma_f32_32x32x16_bf16 %2, %5, %6, %2\n\tv_mfma_f32_32x32x16_bf16 %3, %5, %7, %3\n\t"
;         "ds_read_b128 %4, %14\n\tds_read_b128 %5, %14 offset:4096\n\tds_read_b128 %6, %18\n\tds_read_b128 %7, %18 offset:4096\n\t"
;         "s_waitcnt lgkmcnt(4)\n\t"
;         "v_mfma_f32_32x32x16_bf16 %0, %8, %10, %0\n\tv_mfma_f32_32x32x16_bf16 %1, %8, %11, %1\n\tv_mfma_f32_32x32x16_bf16 %2, %9, %10, %2\n\tv_mfma_f32_32x32x16_bf16 %3, %9, %11, %3\n\t"
;         "ds_read_b128 %8, %15\n\tds_read_b128 %9, %15 offset:4096\n\tds_read_b128 %10, %19\n\tds_read_b128 %11, %19 offset:4096\n\t"
;         "s_waitcnt lgkmcnt(4)\n\t"
;         "v_mfma_f32_32x32x16_bf16 %0, %4, %6, %0\n\tv_mfma_f32_32x32x16_bf16 %1, %4, %7, %1\n\tv_mfma_f32_32x32x16_bf16 %2, %5, %6, %2\n\tv_mfma_f32_32x32x16_bf16 %3, %5, %7, %3\n\t"
;         "s_waitcnt lgkmcnt(0)\n\t"
;         "v_mfma_f32_32x32x16_bf16 %0, %8, %10, %0\n\tv_mfma_f32_32x32x16_bf16 %1, %8, %11, %1\n\tv_mfma_f32_32x32x16_bf16 %2, %9, %10, %2\n\tv_mfma_f32_32x32x16_bf16 %3, %9, %11, %3"
	ds_read_b128 v[84:87], v76
	ds_read_b128 v[88:91], v76 offset:4096
	ds_read_b128 v[92:95], v80
	ds_read_b128 v[96:99], v80 offset:4096
	v_mfma_f32_32x32x16_bf16 v[32:47], v[100:103], v[108:111], v[32:47]
	s_mov_b32 s24, 0x580
	s_add_u32 m0, s30, 0x18000
	v_lshl_add_u64 v[124:125], v[64:65], 0, s[24:25]
	global_load_lds_dwordx4 v[124:125], off
	v_mfma_f32_32x32x16_bf16 v[48:63], v[100:103], v[112:115], v[48:63]
	v_mfma_f32_32x32x16_bf16 v[0:15], v[104:107], v[108:111], v[0:15]
	s_add_u32 m0, s30, 0x1a000
	v_lshl_add_u64 v[126:127], v[66:67], 0, s[24:25]
	global_load_lds_dwordx4 v[126:127], off
	v_mfma_f32_32x32x16_bf16 v[16:31], v[104:107], v[112:115], v[16:31]
	ds_read_b128 v[100:103], v77
	ds_read_b128 v[104:107], v77 offset:4096
	ds_read_b128 v[108:111], v81
	ds_read_b128 v[112:115], v81 offset:4096
	s_waitcnt lgkmcnt(4)
	v_mfma_f32_32x32x16_bf16 v[32:47], v[84:87], v[92:95], v[32:47]
	s_add_u32 m0, s30, 0x1c000
	v_lshl_add_u64 v[124:125], v[68:69], 0, s[24:25]
	global_load_lds_dwordx4 v[124:125], off
	v_mfma_f32_32x32x16_bf16 v[48:63], v[84:87], v[96:99], v[48:63]
	v_mfma_f32_32x32x16_bf16 v[0:15], v[88:91], v[92:95], v[0:15]
	s_add_u32 m0, s30, 0x1e000
	v_lshl_add_u64 v[126:127], v[70:71], 0, s[24:25]
	global_load_lds_dwordx4 v[126:127], off
	v_mfma_f32_32x32x16_bf16 v[16:31], v[88:91], v[96:99], v[16:31]
	ds_read_b128 v[84:87], v78
	ds_read_b128 v[88:91], v78 offset:4096
	ds_read_b128 v[92:95], v82
	ds_read_b128 v[96:99], v82 offset:4096
	s_waitcnt lgkmcnt(4)
	v_mfma_f32_32x32x16_bf16 v[32:47], v[100:103], v[108:111], v[32:47]
	s_add_u32 m0, s30, 0x20000
	v_lshl_add_u64 v[124:125], v[72:73], 0, s[24:25]
	global_load_lds_dwordx4 v[124:125], off
	v_mfma_f32_32x32x16_bf16 v[48:63], v[100:103], v[112:115], v[48:63]
	v_mfma_f32_32x32x16_bf16 v[0:15], v[104:107], v[108:111], v[0:15]
	s_add_u32 m0, s30, 0x22000
	v_lshl_add_u64 v[126:127], v[74:75], 0, s[24:25]
	global_load_lds_dwordx4 v[126:127], off
	v_mfma_f32_32x32x16_bf16 v[16:31], v[104:107], v[112:115], v[16:31]
	ds_read_b128 v[100:103], v79
	ds_read_b128 v[104:107], v79 offset:4096
	ds_read_b128 v[108:111], v83
	ds_read_b128 v[112:115], v83 offset:4096
	s_waitcnt lgkmcnt(4)
	v_mfma_f32_32x32x16_bf16 v[32:47], v[84:87], v[92:95], v[32:47]
	v_mfma_f32_32x32x16_bf16 v[48:63], v[84:87], v[96:99], v[48:63]
	v_mfma_f32_32x32x16_bf16 v[0:15], v[88:91], v[92:95], v[0:15]
	v_mfma_f32_32x32x16_bf16 v[16:31], v[88:91], v[96:99], v[16:31]
	s_waitcnt vmcnt(6) lgkmcnt(0)
	s_barrier
	ds_read_b128 v[84:87], v76 offset:49152
	ds_read_b128 v[88:91], v76 offset:53248
	ds_read_b128 v[92:95], v80 offset:49152
	ds_read_b128 v[96:99], v80 offset:53248
	v_mfma_f32_32x32x16_bf16 v[32:47], v[100:103], v[108:111], v[32:47]
	s_mov_b32 s24, 0x600
	s_mov_b32 m0, s30
	v_lshl_add_u64 v[124:125], v[64:65], 0, s[24:25]
	global_load_lds_dwordx4 v[124:125], off
	v_mfma_f32_32x32x16_bf16 v[48:63], v[100:103], v[112:115], v[48:63]
	v_mfma_f32_32x32x16_bf16 v[0:15], v[104:107], v[108:111], v[0:15]
	s_add_u32 m0, s30, 0x2000
	v_lshl_add_u64 v[126:127], v[66:67], 0, s[24:25]
	global_load_lds_dwordx4 v[126:127], off
	v_mfma_f32_32x32x16_bf16 v[16:31], v[104:107], v[112:115], v[16:31]
	ds_read_b128 v[100:103], v77 offset:49152
	ds_read_b128 v[104:107], v77 offset:53248
	ds_read_b128 v[108:111], v81 offset:49152
	ds_read_b128 v[112:115], v81 offset:53248
	s_waitcnt lgkmcnt(4)
	v_mfma_f32_32x32x16_bf16 v[32:47], v[84:87], v[92:95], v[32:47]
	s_add_u32 m0, s30, 0x4000
	v_lshl_add_u64 v[124:125], v[68:69], 0, s[24:25]
	global_load_lds_dwordx4 v[124:125], off
	v_mfma_f32_32x32x16_bf16 v[48:63], v[84:87], v[96:99], v[48:63]
	v_mfma_f32_32x32x16_bf16 v[0:15], v[88:91], v[92:95], v[0:15]
	s_add_u32 m0, s30, 0x6000
	v_lshl_add_u64 v[126:127], v[70:71], 0, s[24:25]
	global_load_lds_dwordx4 v[126:127], off
	v_mfma_f32_32x32x16_bf16 v[16:31], v[88:91], v[96:99], v[16:31]
	ds_read_b128 v[84:87], v78 offset:49152
	ds_read_b128 v[88:91], v78 offset:53248
	ds_read_b128 v[92:95], v82 offset:49152
	ds_read_b128 v[96:99], v82 offset:53248
	s_waitcnt lgkmcnt(4)
	v_mfma_f32_32x32x16_bf16 v[32:47], v[100:103], v[108:111], v[32:47]
	s_add_u32 m0, s30, 0x8000
	v_lshl_add_u64 v[124:125], v[72:73], 0, s[24:25]
	global_load_lds_dwordx4 v[124:125], off
	v_mfma_f32_32x32x16_bf16 v[48:63], v[100:103], v[112:115], v[48:63]
	v_mfma_f32_32x32x16_bf16 v[0:15], v[104:107], v[108:111], v[0:15]
	s_add_u32 m0, s30, 0xa000
	v_lshl_add_u64 v[126:127], v[74:75], 0, s[24:25]
	global_load_lds_dwordx4 v[126:127], off
	v_mfma_f32_32x32x16_bf16 v[16:31], v[104:107], v[112:115], v[16:31]
	ds_read_b128 v[100:103], v79 offset:49152
	ds_read_b128 v[104:107], v79 offset:53248
	ds_read_b128 v[108:111], v83 offset:49152
	ds_read_b128 v[112:115], v83 offset:53248
	s_waitcnt lgkmcnt(4)
	v_mfma_f32_32x32x16_bf16 v[32:47], v[84:87], v[92:95], v[32:47]
	v_mfma_f32_32x32x16_bf16 v[48:63], v[84:87], v[96:99], v[48:63]
	v_mfma_f32_32x32x16_bf16 v[0:15], v[88:91], v[92:95], v[0:15]
	v_mfma_f32_32x32x16_bf16 v[16:31], v[88:91], v[96:99], v[16:31]
	s_waitcnt vmcnt(6) lgkmcnt(0)
	s_barrier
;     ...
;   if (PART != 2) {
;     GEMM_ISSUE(0, 0);
;     if (nk > 1) GEMM_ISSUE(1, 1);
;   }
;   if (PART == 1) return;
;   int st = 0;
;   for (int kt = 0; kt < nk; ++kt) {
;     if (kt + 1 < nk) asm volatile("s_waitcnt vmcnt(6)" ::: "memory");
;     else asm volatile("s_waitcnt vmcnt(0)" ::: "memory");
;     __builtin_amdgcn_s_barrier();
;     asm volatile("" ::: "memory");
;     if (kt + 2 < nk) { const int st2 = (st >= 1) ? st - 1 : 2; GEMM_ISSUE(kt + 2, st2); }
;     const char* la = lds + st * STAGE_B;
;     const char* lb = la + 32768;
;     const unsigned sa_u = (unsigned)(size_t)la + arow_u, sb_u = (unsigned)(size_t)lb + brow_u;
;     const unsigned a0 = sa_u + co0, a1 = sa_u + co1, a2 = sa_u + co2, a3 = sa_u + co3;
;     const unsigned b0 = sb_u + co0, b1 = sb_u + co1, b2 = sb_u + co2, b3 = sb_u + co3;
;     {
;       bf16x8 p0, p1, q0, q1, u0, u1, w0, w1;
;       asm volatile(
;         "ds_read_b128 %4, %12\n\tds_read_b128 %5, %12 offset:4096\n\tds_read_b128 %6, %16\n\tds_read_b128 %7, %16 offset:4096\n\t"
;         "ds_read_b128 %8, %13\n\tds_read_b128 %9, %13 offset:4096\n\tds_read_b128 %10, %17\n\tds_read_b128 %11, %17 offset:4096\n\t"
;         "s_waitcnt lgkmcnt(4)\n\t"
;         "v_mfma_f32_32x32x16_bf16 %0, %4, %6, %0\n\tv_mfma_f32_32x32x16_bf16 %1, %4, %7, %1\n\tv_mfma_f32_32x32x16_bf16 %2, %5, %6, %2\n\tv_mfma_f32_32x32x16_bf16 %3, %5, %7, %3\n\t"
;         "ds_read_b128 %4, %14\n\tds_read_b128 %5, %14 offset:4096\n\tds_read_b128 %6, %18\n\tds_read_b128 %7, %18 offset:4096\n\t"
;         "s_waitcnt lgkmcnt(4)\n\t"
;         "v_mfma_f32_32x32x16_bf16 %0, %8, %10, %0\n\tv_mfma_f32_32x32x16_bf16 %1, %8, %11, %1\n\tv_mfma_f32_32x32x16_bf16 %2, %9, %10, %2\n\tv_mfma_f32_32x32x16_bf16 %3, %9, %11, %3\n\t"
;         "ds_read_b128 %8, %15\n\tds_read_b128 %9, %15 offset:4096\n\tds_read_b128 %10, %19\n\tds_read_b128 %11, %19 offset:4096\n\t"
;         "s_waitcnt lgkmcnt(4)\n\t"
;         "v_mfma_f32_32x32x16_bf16 %0, %4, %6, %0\n\tv_mfma_f32_32x32x16_bf16 %1, %4, %7, %1\n\tv_mfma_f32_32x32x16_bf16 %2, %5, %6, %2\n\tv_mfma_f32_32x32x16_bf16 %3, %5, %7, %3\n\t"
;         "s_waitcnt lgkmcnt(0)\n\t"
;         "v_mfma_f32_32x32x16_bf16 %0, %8, %10, %0\n\tv_mfma_f32_32x32x16_bf16 %1, %8, %11, %1\n\tv_mfma_f32_32x32x16_bf16 %2, %9, %10, %2\n\tv_mfma_f32_32x32x16_bf16 %3, %9, %11, %3"
	ds_read_b128 v[84:87], v116
	ds_read_b128 v[88:91], v116 offset:4096
	ds_read_b128 v[92:95], v120
	ds_read_b128 v[96:99], v120 offset:4096
	v_mfma_f32_32x32x16_bf16 v[32:47], v[100:103], v[108:111], v[32:47]
	s_mov_b32 s24, 0x680
	s_add_u32 m0, s30, 0xc000
	v_lshl_add_u64 v[124:125], v[64:65], 0, s[24:25]
	global_load_lds_dwordx4 v[124:125], off
	v_mfma_f32_32x32x16_bf16 v[48:63], v[100:103], v[112:115], v[48:63]
	v_mfma_f32_32x32x16_bf16 v[0:15], v[104:107], v[108:111], v[0:15]
	s_add_u32 m0, s30, 0xe000
	v_lshl_add_u64 v[126:127], v[66:67], 0, s[24:25]
	global_load_lds_dwordx4 v[126:127], off
	v_mfma_f32_32x32x16_bf16 v[16:31], v[104:107], v[112:115], v[16:31]
	ds_read_b128 v[100:103], v117
	ds_read_b128 v[104:107], v117 offset:4096
	ds_read_b128 v[108:111], v121
	ds_read_b128 v[112:115], v121 offset:4096
	s_waitcnt lgkmcnt(4)
	v_mfma_f32_32x32x16_bf16 v[32:47], v[84:87], v[92:95], v[32:47]
	s_add_u32 m0, s30, 0x10000
	v_lshl_add_u64 v[124:125], v[68:69], 0, s[24:25]
	global_load_lds_dwordx4 v[124:125], off
	v_mfma_f32_32x32x16_bf16 v[48:63], v[84:87], v[96:99], v[48:63]
	v_mfma_f32_32x32x16_bf16 v[0:15], v[88:91], v[92:95], v[0:15]
	s_add_u32 m0, s30, 0x12000
	v_lshl_add_u64 v[126:127], v[70:71], 0, s[24:25]
	global_load_lds_dwordx4 v[126:127], off
	v_mfma_f32_32x32x16_bf16 v[16:31], v[88:91], v[96:99], v[16:31]
	ds_read_b128 v[84:87], v118
	ds_read_b128 v[88:91], v118 offset:4096
	ds_read_b128 v[92:95], v122
	ds_read_b128 v[96:99], v122 offset:4096
	s_waitcnt lgkmcnt(4)
	v_mfma_f32_32x32x16_bf16 v[32:47], v[100:103], v[108:111], v[32:47]
	s_add_u32 m0, s30, 0x14000
	v_lshl_add_u64 v[124:125], v[72:73], 0, s[24:25]
	global_load_lds_dwordx4 v[124:125], off
	v_mfma_f32_32x32x16_bf16 v[48:63], v[100:103], v[112:115], v[48:63]
	v_mfma_f32_32x32x16_bf16 v[0:15], v[104:107], v[108:111], v[0:15]
	s_add_u32 m0, s30, 0x16000
	v_lshl_add_u64 v[126:127], v[74:75], 0, s[24:25]
	global_load_lds_dwordx4 v[126:127], off
	v_mfma_f32_32x32x16_bf16 v[16:31], v[104:107], v[112:115], v[16:31]
	ds_read_b128 v[100:103], v119
	ds_read_b128 v[104:107], v119 offset:4096
	ds_read_b128 v[108:111], v123
	ds_read_b128 v[112:115], v123 offset:4096
	s_waitcnt lgkmcnt(4)
	v_mfma_f32_32x32x16_bf16 v[32:47], v[84:87], v[92:95], v[32:47]
	v_mfma_f32_32x32x16_bf16 v[48:63], v[84:87], v[96:99], v[48:63]
	v_mfma_f32_32x32x16_bf16 v[0:15], v[88:91], v[92:95], v[0:15]
	v_mfma_f32_32x32x16_bf16 v[16:31], v[88:91], v[96:99], v[16:31]
	s_waitcnt vmcnt(6) lgkmcnt(0)
	s_barrier
	ds_read_b128 v[84:87], v76
	ds_read_b128 v[88:91], v76 offset:4096
	ds_read_b128 v[92:95], v80
	ds_read_b128 v[96:99], v80 offset:4096
	v_mfma_f32_32x32x16_bf16 v[32:47], v[100:103], v[108:111], v[32:47]
	s_mov_b32 s24, 0x700
	s_add_u32 m0, s30, 0x18000
	v_lshl_add_u64 v[124:125], v[64:65], 0, s[24:25]
	global_load_lds_dwordx4 v[124:125], off
	v_mfma_f32_32x32x16_bf16 v[48:63], v[100:103], v[112:115], v[48:63]
	v_mfma_f32_32x32x16_bf16 v[0:15], v[104:107], v[108:111], v[0:15]
	s_add_u32 m0, s30, 0x1a000
	v_lshl_add_u64 v[126:127], v[66:67], 0, s[24:25]
	global_load_lds_dwordx4 v[126:127], off
	v_mfma_f32_32x32x16_bf16 v[16:31], v[104:107], v[112:115], v[16:31]
	ds_read_b128 v[100:103], v77
	ds_read_b128 v[104:107], v77 offset:4096
	ds_read_b128 v[108:111], v81
	ds_read_b128 v[112:115], v81 offset:4096
	s_waitcnt lgkmcnt(4)
	v_mfma_f32_32x32x16_bf16 v[32:47], v[84:87], v[92:95], v[32:47]
	s_add_u32 m0, s30, 0x1c000
	v_lshl_add_u64 v[124:125], v[68:69], 0, s[24:25]
	global_load_lds_dwordx4 v[124:125], off
	v_mfma_f32_32x32x16_bf16 v[48:63], v[84:87], v[96:99], v[48:63]
	v_mfma_f32_32x32x16_bf16 v[0:15], v[88:91], v[92:95], v[0:15]
	s_add_u32 m0, s30, 0x1e000
	v_lshl_add_u64 v[126:127], v[70:71], 0, s[24:25]
	global_load_lds_dwordx4 v[126:127], off
	v_mfma_f32_32x32x16_bf16 v[16:31], v[88:91], v[96:99], v[16:31]
	ds_read_b128 v[84:87], v78
	ds_read_b128 v[88:91], v78 offset:4096
	ds_read_b128 v[92:95], v82
	ds_read_b128 v[96:99], v82 offset:4096
	s_waitcnt lgkmcnt(4)
	v_mfma_f32_32x32x16_bf16 v[32:47], v[100:103], v[108:111], v[32:47]
	s_add_u32 m0, s30, 0x20000
	v_lshl_add_u64 v[124:125], v[72:73], 0, s[24:25]
	global_load_lds_dwordx4 v[124:125], off
	v_mfma_f32_32x32x16_bf16 v[48:63], v[100:103], v[112:115], v[48:63]
	v_mfma_f32_32x32x16_bf16 v[0:15], v[104:107], v[108:111], v[0:15]
	s_add_u32 m0, s30, 0x22000
	v_lshl_add_u64 v[126:127], v[74:75], 0, s[24:25]
	global_load_lds_dwordx4 v[126:127], off
	v_mfma_f32_32x32x16_bf16 v[16:31], v[104:107], v[112:115], v[16:31]
	ds_read_b128 v[100:103], v79
	ds_read_b128 v[104:107], v79 offset:4096
	ds_read_b128 v[108:111], v83
	ds_read_b128 v[112:115], v83 offset:4096
	s_waitcnt lgkmcnt(4)
	v_mfma_f32_32x32x16_bf16 v[32:47], v[84:87], v[92:95], v[32:47]
	v_mfma_f32_32x32x16_bf16 v[48:63], v[84:87], v[96:99], v[48:63]
	v_mfma_f32_32x32x16_bf16 v[0:15], v[88:91], v[92:95], v[0:15]
	v_mfma_f32_32x32x16_bf16 v[16:31], v[88:91], v[96:99], v[16:31]
	s_waitcnt vmcnt(6) lgkmcnt(0)
	s_barrier
;     ...
;   if (PART != 2) {
;     GEMM_ISSUE(0, 0);
;     if (nk > 1) GEMM_ISSUE(1, 1);
;   }
;   if (PART == 1) return;
;   int st = 0;
;   for (int kt = 0; kt < nk; ++kt) {
;     if (kt + 1 < nk) asm volatile("s_waitcnt vmcnt(6)" ::: "memory");
;     else asm volatile("s_waitcnt vmcnt(0)" ::: "memory");
;     __builtin_amdgcn_s_barrier();
;     asm volatile("" ::: "memory");
;     if (kt + 2 < nk) { const int st2 = (st >= 1) ? st - 1 : 2; GEMM_ISSUE(kt + 2, st2); }
;     const char* la = lds + st * STAGE_B;
;     const char* lb = la + 32768;
;     const unsigned sa_u = (unsigned)(size_t)la + arow_u, sb_u = (unsigned)(size_t)lb + brow_u;
;     const unsigned a0 = sa_u + co0, a1 = sa_u + co1, a2 = sa_u + co2, a3 = sa_u + co3;
;     const unsigned b0 = sb_u + co0, b1 = sb_u + co1, b2 = sb_u + co2, b3 = sb_u + co3;
;     {
;       bf16x8 p0, p1, q0, q1, u0, u1, w0, w1;
;       asm volatile(
;         "ds_read_b128 %4, %12\n\tds_read_b128 %5, %12 offset:4096\n\tds_read_b128 %6, %16\n\tds_read_b128 %7, %16 offset:4096\n\t"
;         "ds_read_b128 %8, %13\n\tds_read_b128 %9, %13 offset:4096\n\tds_read_b128 %10, %17\n\tds_read_b128 %11, %17 offset:4096\n\t"
;         "s_waitcnt lgkmcnt(4)\n\t"
;         "v_mfma_f32_32x32x16_bf16 %0, %4, %6, %0\n\tv_mfma_f32_32x32x16_bf16 %1, %4, %7, %1\n\tv_mfma_f32_32x32x16_bf16 %2, %5, %6, %2\n\tv_mfma_f32_32x32x16_bf16 %3, %5, %7, %3\n\t"
;         "ds_read_b128 %4, %14\n\tds_read_b128 %5, %14 offset:4096\n\tds_read_b128 %6, %18\n\tds_read_b128 %7, %18 offset:4096\n\t"
;         "s_waitcnt lgkmcnt(4)\n\t"
;         "v_mfma_f32_32x32x16_bf16 %0, %8, %10, %0\n\tv_mfma_f32_32x32x16_bf16 %1, %8, %11, %1\n\tv_mfma_f32_32x32x16_bf16 %2, %9, %10, %2\n\tv_mfma_f32_32x32x16_bf16 %3, %9, %11, %3\n\t"
;         "ds_read_b128 %8, %15\n\tds_read_b128 %9, %15 offset:4096\n\tds_read_b128 %10, %19\n\tds_read_b128 %11, %19 offset:4096\n\t"
;         "s_waitcnt lgkmcnt(4)\n\t"
;         "v_mfma_f32_32x32x16_bf16 %0, %4, %6, %0\n\tv_mfma_f32_32x32x16_bf16 %1, %4, %7, %1\n\tv_mfma_f32_32x32x16_bf16 %2, %5, %6, %2\n\tv_mfma_f32_32x32x16_bf16 %3, %5, %7, %3\n\t"
;         "s_waitcnt lgkmcnt(0)\n\t"
;         "v_mfma_f32_32x32x16_bf16 %0, %8, %10, %0\n\tv_mfma_f32_32x32x16_bf16 %1, %8, %11, %1\n\tv_mfma_f32_32x32x16_bf16 %2, %9, %10, %2\n\tv_mfma_f32_32x32x16_bf16 %3, %9, %11, %3"
	ds_read_b128 v[84:87], v76 offset:49152
	ds_read_b128 v[88:91], v76 offset:53248
	ds_read_b128 v[92:95], v80 offset:49152
	ds_read_b128 v[96:99], v80 offset:53248
	v_mfma_f32_32x32x16_bf16 v[32:47], v[100:103], v[108:111], v[32:47]
	s_mov_b32 s24, 0x780
	s_mov_b32 m0, s30
	v_lshl_add_u64 v[124:125], v[64:65], 0, s[24:25]
	global_load_lds_dwordx4 v[124:125], off
	v_mfma_f32_32x32x16_bf16 v[48:63], v[100:103], v[112:115], v[48:63]
	v_mfma_f32_32x32x16_bf16 v[0:15], v[104:107], v[108:111], v[0:15]
	s_add_u32 m0, s30, 0x2000
	v_lshl_add_u64 v[126:127], v[66:67], 0, s[24:25]
	global_load_lds_dwordx4 v[126:127], off
	v_mfma_f32_32x32x16_bf16 v[16:31], v[104:107], v[112:115], v[16:31]
	ds_read_b128 v[100:103], v77 offset:49152
	ds_read_b128 v[104:107], v77 offset:53248
	ds_read_b128 v[108:111], v81 offset:49152
	ds_read_b128 v[112:115], v81 offset:53248
	s_waitcnt lgkmcnt(4)
	v_mfma_f32_32x32x16_bf16 v[32:47], v[84:87], v[92:95], v[32:47]
	s_add_u32 m0, s30, 0x4000
	v_lshl_add_u64 v[124:125], v[68:69], 0, s[24:25]
	global_load_lds_dwordx4 v[124:125], off
	v_mfma_f32_32x32x16_bf16 v[48:63], v[84:87], v[96:99], v[48:63]
	v_mfma_f32_32x32x16_bf16 v[0:15], v[88:91], v[92:95], v[0:15]
	s_add_u32 m0, s30, 0x6000
	v_lshl_add_u64 v[126:127], v[70:71], 0, s[24:25]
	global_load_lds_dwordx4 v[126:127], off
	v_mfma_f32_32x32x16_bf16 v[16:31], v[88:91], v[96:99], v[16:31]
	ds_read_b128 v[84:87], v78 offset:49152
	ds_read_b128 v[88:91], v78 offset:53248
	ds_read_b128 v[92:95], v82 offset:49152
	ds_read_b128 v[96:99], v82 offset:53248
	s_waitcnt lgkmcnt(4)
	v_mfma_f32_32x32x16_bf16 v[32:47], v[100:103], v[108:111], v[32:47]
	s_add_u32 m0, s30, 0x8000
	v_lshl_add_u64 v[124:125], v[72:73], 0, s[24:25]
	global_load_lds_dwordx4 v[124:125], off
	v_mfma_f32_32x32x16_bf16 v[48:63], v[100:103], v[112:115], v[48:63]
	v_mfma_f32_32x32x16_bf16 v[0:15], v[104:107], v[108:111], v[0:15]
	s_add_u32 m0, s30, 0xa000
	v_lshl_add_u64 v[126:127], v[74:75], 0, s[24:25]
	global_load_lds_dwordx4 v[126:127], off
	v_mfma_f32_32x32x16_bf16 v[16:31], v[104:107], v[112:115], v[16:31]
	ds_read_b128 v[100:103], v79 offset:49152
	ds_read_b128 v[104:107], v79 offset:53248
	ds_read_b128 v[108:111], v83 offset:49152
	ds_read_b128 v[112:115], v83 offset:53248
	s_waitcnt lgkmcnt(4)
	v_mfma_f32_32x32x16_bf16 v[32:47], v[84:87], v[92:95], v[32:47]
	v_mfma_f32_32x32x16_bf16 v[48:63], v[84:87], v[96:99], v[48:63]
	v_mfma_f32_32x32x16_bf16 v[0:15], v[88:91], v[92:95], v[0:15]
	v_mfma_f32_32x32x16_bf16 v[16:31], v[88:91], v[96:99], v[16:31]
	s_waitcnt vmcnt(6) lgkmcnt(0)
	s_barrier
	ds_read_b128 v[84:87], v116
	ds_read_b128 v[88:91], v116 offset:4096
	ds_read_b128 v[92:95], v120
	ds_read_b128 v[96:99], v120 offset:4096
	v_mfma_f32_32x32x16_bf16 v[32:47], v[100:103], v[108:111], v[32:47]
	v_mfma_f32_32x32x16_bf16 v[48:63], v[100:103], v[112:115], v[48:63]
	v_mfma_f32_32x32x16_bf16 v[0:15], v[104:107], v[108:111], v[0:15]
	v_mfma_f32_32x32x16_bf16 v[16:31], v[104:107], v[112:115], v[16:31]
	ds_read_b128 v[100:103], v117
	ds_read_b128 v[104:107], v117 offset:4096
	ds_read_b128 v[108:111], v121
	ds_read_b128 v[112:115], v121 offset:4096
	s_waitcnt lgkmcnt(4)
	v_mfma_f32_32x32x16_bf16 v[32:47], v[84:87], v[92:95], v[32:47]
	v_mfma_f32_32x32x16_bf16 v[48:63], v[84:87], v[96:99], v[48:63]
	v_mfma_f32_32x32x16_bf16 v[0:15], v[88:91], v[92:95], v[0:15]
	v_mfma_f32_32x32x16_bf16 v[16:31], v[88:91], v[96:99], v[16:31]
	ds_read_b128 v[84:87], v118
	ds_read_b128 v[88:91], v118 offset:4096
	ds_read_b128 v[92:95], v122
	ds_read_b128 v[96:99], v122 offset:4096
	s_waitcnt lgkmcnt(4)
	v_mfma_f32_32x32x16_bf16 v[32:47], v[100:103], v[108:111], v[32:47]
	v_mfma_f32_32x32x16_bf16 v[48:63], v[100:103], v[112:115], v[48:63]
	v_mfma_f32_32x32x16_bf16 v[0:15], v[104:107], v[108:111], v[0:15]
	v_mfma_f32_32x32x16_bf16 v[16:31], v[104:107], v[112:115], v[16:31]
	ds_read_b128 v[100:103], v119
	ds_read_b128 v[104:107], v119 offset:4096
	ds_read_b128 v[108:111], v123
	ds_read_b128 v[112:115], v123 offset:4096
	s_waitcnt lgkmcnt(4)
	v_mfma_f32_32x32x16_bf16 v[32:47], v[84:87], v[92:95], v[32:47]
	v_mfma_f32_32x32x16_bf16 v[48:63], v[84:87], v[96:99], v[48:63]
	v_mfma_f32_32x32x16_bf16 v[0:15], v[88:91], v[92:95], v[0:15]
	v_mfma_f32_32x32x16_bf16 v[16:31], v[88:91], v[96:99], v[16:31]
	s_waitcnt vmcnt(0) lgkmcnt(0)
	s_barrier
	ds_read_b128 v[84:87], v76
	ds_read_b128 v[88:91], v76 offset:4096
	ds_read_b128 v[92:95], v80
	ds_read_b128 v[96:99], v80 offset:4096
	v_mfma_f32_32x32x16_bf16 v[32:47], v[100:103], v[108:111], v[32:47]
	v_mfma_f32_32x32x16_bf16 v[48:63], v[100:103], v[112:115], v[48:63]
	v_mfma_f32_32x32x16_bf16 v[0:15], v[104:107], v[108:111], v[0:15]
	v_mfma_f32_32x32x16_bf16 v[16:31], v[104:107], v[112:115], v[16:31]
	ds_read_b128 v[100:103], v77
	ds_read_b128 v[104:107], v77 offset:4096
	ds_read_b128 v[108:111], v81
	ds_read_b128 v[112:115], v81 offset:4096
	s_waitcnt lgkmcnt(4)
	v_mfma_f32_32x32x16_bf16 v[32:47], v[84:87], v[92:95], v[32:47]
	v_mfma_f32_32x32x16_bf16 v[48:63], v[84:87], v[96:99], v[48:63]
	v_mfma_f32_32x32x16_bf16 v[0:15], v[88:91], v[92:95], v[0:15]
	v_mfma_f32_32x32x16_bf16 v[16:31], v[88:91], v[96:99], v[16:31]
	ds_read_b128 v[84:87], v78
	ds_read_b128 v[88:91], v78 offset:4096
	ds_read_b128 v[92:95], v82
	ds_read_b128 v[96:99], v82 offset:4096
	s_waitcnt lgkmcnt(4)
	v_mfma_f32_32x32x16_bf16 v[32:47], v[100:103], v[108:111], v[32:47]
	v_mfma_f32_32x32x16_bf16 v[48:63], v[100:103], v[112:115], v[48:63]
	v_mfma_f32_32x32x16_bf16 v[0:15], v[104:107], v[108:111], v[0:15]
	v_mfma_f32_32x32x16_bf16 v[16:31], v[104:107], v[112:115], v[16:31]
	ds_read_b128 v[100:103], v79
	ds_read_b128 v[104:107], v79 offset:4096
	ds_read_b128 v[108:111], v83
	ds_read_b128 v[112:115], v83 offset:4096
	s_waitcnt lgkmcnt(4)
	v_mfma_f32_32x32x16_bf16 v[32:47], v[84:87], v[92:95], v[32:47]
	v_mfma_f32_32x32x16_bf16 v[48:63], v[84:87], v[96:99], v[48:63]
	v_mfma_f32_32x32x16_bf16 v[0:15], v[88:91], v[92:95], v[0:15]
	v_mfma_f32_32x32x16_bf16 v[16:31], v[88:91], v[96:99], v[16:31]
	s_waitcnt lgkmcnt(0)
	v_mfma_f32_32x32x16_bf16 v[32:47], v[100:103], v[108:111], v[32:47]
	v_mfma_f32_32x32x16_bf16 v[48:63], v[100:103], v[112:115], v[48:63]
	v_mfma_f32_32x32x16_bf16 v[0:15], v[104:107], v[108:111], v[0:15]
	v_mfma_f32_32x32x16_bf16 v[16:31], v[104:107], v[112:115], v[16:31]
	s_mov_b32 s53, 0x8000
	s_nop 15
	s_nop 15
	s_nop 7
	s_barrier
	s_load_dword s9, s[0:1], 0x10
	s_waitcnt lgkmcnt(0)
	s_lshr_b32 s9, s9, 16
	s_cmp_lg_u32 s9, 0
	s_cselect_b64 s[26:27], -1, 0
	s_cmp_lg_u64 s[26:27], 0
	s_addc_u32 s9, s33, 0
	s_cmp_lg_u64 s[26:27], 0
	s_addc_u32 s23, s23, s33
	s_cmpk_gt_i32 s23, 0x15ff
	s_cbranch_scc0 .LBB0_59

; #define TIDX get_tid_()
; DI int crow(int i, int h) { return (i & 3) + 8 * (i >> 2) + 4 * h; }
;   DI void pre(float (&rv)[2][2][16], int m0, int n0) const {
;     const int tid = TIDX, lane = tid & 63, wid = tid >> 6, wr = wid >> 1, wc = wid & 1, r = lane & 31, h = lane >> 5;
; #pragma unroll
;     for (int mi = 0; mi < 2; ++mi)
; #pragma unroll
;       for (int ni = 0; ni < 2; ++ni)
; #pragma unroll
;         for (int i = 0; i < 16; ++i)
;           rv[mi][ni][i] = res[(size_t)(m0 + wr * 64 + mi * 32 + crow(i, h)) * DM + n0 + wc * 64 + ni * 32 + r];
;   }
.LBB0_84:
	v_mov_b32_e32 v0, v129
	s_lshl_b32 s30, s14, 7
	s_lshl_b32 s26, s8, 8
	v_ashrrev_i32_e32 v2, 1, v0
	v_and_b32_e32 v2, 0xffffffc0, v2
	s_ashr_i32 s31, s30, 31
	v_readlane_b32 s56, v254, 26
	v_and_b32_e32 v1, 64, v0
	v_and_b32_e32 v4, 31, v0
	v_lshrrev_b32_e32 v0, 3, v0
	v_add_u32_e32 v2, s26, v2
	s_lshl_b64 s[30:31], s[30:31], 2
	v_readlane_b32 s58, v254, 28
	v_and_or_b32 v0, v0, 4, v2
	v_readlane_b32 s59, v254, 29
	s_add_u32 s68, s58, s30
	s_addc_u32 s69, s59, s31
	v_lshlrev_b32_e32 v130, 2, v1
	v_or_b32_e32 v6, 1, v0
	v_or_b32_e32 v8, 2, v0
	v_or_b32_e32 v10, 3, v0
	v_or_b32_e32 v12, 8, v0
	v_or_b32_e32 v14, 9, v0
	v_or_b32_e32 v16, 10, v0
	v_or_b32_e32 v18, 11, v0
	v_or_b32_e32 v20, 16, v0
	v_or_b32_e32 v22, 17, v0
	v_or_b32_e32 v24, 18, v0
	v_or_b32_e32 v26, 19, v0
	v_or_b32_e32 v28, 24, v0
	v_or_b32_e32 v30, 25, v0
	v_or_b32_e32 v32, 26, v0
	v_lshl_add_u64 v[2:3], s[68:69], 0, v[130:131]
	v_lshlrev_b32_e32 v130, 2, v4
	v_ashrrev_i32_e32 v1, 31, v0
	v_ashrrev_i32_e32 v7, 31, v6
	v_ashrrev_i32_e32 v9, 31, v8
	v_ashrrev_i32_e32 v11, 31, v10
	v_ashrrev_i32_e32 v13, 31, v12
	v_ashrrev_i32_e32 v15, 31, v14
	v_ashrrev_i32_e32 v17, 31, v16
	v_ashrrev_i32_e32 v19, 31, v18
	v_ashrrev_i32_e32 v21, 31, v20
	v_ashrrev_i32_e32 v23, 31, v22
	v_ashrrev_i32_e32 v25, 31, v24
	v_ashrrev_i32_e32 v27, 31, v26
	v_ashrrev_i32_e32 v29, 31, v28
	v_ashrrev_i32_e32 v31, 31, v30
	v_ashrrev_i32_e32 v33, 31, v32
	v_or_b32_e32 v34, 27, v0
	v_lshl_add_u64 v[2:3], v[2:3], 0, v[130:131]
	v_lshlrev_b64 v[4:5], 12, v[0:1]
	v_lshlrev_b64 v[6:7], 12, v[6:7]
	v_lshlrev_b64 v[8:9], 12, v[8:9]
	v_lshlrev_b64 v[10:11], 12, v[10:11]
	v_lshlrev_b64 v[12:13], 12, v[12:13]
	v_lshlrev_b64 v[14:15], 12, v[14:15]
	v_lshlrev_b64 v[16:17], 12, v[16:17]
	v_lshlrev_b64 v[18:19], 12, v[18:19]
	v_lshlrev_b64 v[20:21], 12, v[20:21]
	v_lshlrev_b64 v[22:23], 12, v[22:23]
	v_lshlrev_b64 v[24:25], 12, v[24:25]
	v_lshlrev_b64 v[26:27], 12, v[26:27]
	v_lshlrev_b64 v[28:29], 12, v[28:29]
	v_lshlrev_b64 v[30:31], 12, v[30:31]
	v_lshlrev_b64 v[32:33], 12, v[32:33]
	v_ashrrev_i32_e32 v35, 31, v34
	v_lshl_add_u64 v[4:5], v[2:3], 0, v[4:5]
	v_lshl_add_u64 v[6:7], v[2:3], 0, v[6:7]
	v_lshl_add_u64 v[8:9], v[2:3], 0, v[8:9]
	v_lshl_add_u64 v[10:11], v[2:3], 0, v[10:11]
	v_lshl_add_u64 v[12:13], v[2:3], 0, v[12:13]
	v_lshl_add_u64 v[14:15], v[2:3], 0, v[14:15]
	v_lshl_add_u64 v[16:17], v[2:3], 0, v[16:17]
	v_lshl_add_u64 v[18:19], v[2:3], 0, v[18:19]
	v_lshl_add_u64 v[20:21], v[2:3], 0, v[20:21]
	v_lshl_add_u64 v[22:23], v[2:3], 0, v[22:23]
	v_lshl_add_u64 v[24:25], v[2:3], 0, v[24:25]
	v_lshl_add_u64 v[26:27], v[2:3], 0, v[26:27]
	v_lshl_add_u64 v[28:29], v[2:3], 0, v[28:29]
	v_lshl_add_u64 v[30:31], v[2:3], 0, v[30:31]
	v_lshl_add_u64 v[32:33], v[2:3], 0, v[32:33]
	v_lshlrev_b64 v[34:35], 12, v[34:35]
	v_lshl_add_u64 v[34:35], v[2:3], 0, v[34:35]
	global_load_dword v143, v[4:5], off
	global_load_dword v141, v[6:7], off
	global_load_dword v139, v[8:9], off
	global_load_dword v136, v[10:11], off
	global_load_dword v79, v[10:11], off offset:128
	global_load_dword v83, v[8:9], off offset:128
	global_load_dword v89, v[6:7], off offset:128
	global_load_dword v95, v[4:5], off offset:128
	global_load_dword v137, v[12:13], off
	global_load_dword v133, v[14:15], off
	global_load_dword v127, v[16:17], off
	global_load_dword v124, v[18:19], off
	global_load_dword v84, v[18:19], off offset:128
	global_load_dword v90, v[16:17], off offset:128
	global_load_dword v96, v[14:15], off offset:128
	global_load_dword v101, v[12:13], off offset:128
	global_load_dword v125, v[20:21], off
	global_load_dword v121, v[22:23], off
	global_load_dword v119, v[24:25], off
	global_load_dword v116, v[26:27], off
	global_load_dword v91, v[26:27], off offset:128
	global_load_dword v97, v[24:25], off offset:128
	global_load_dword v102, v[22:23], off offset:128
	global_load_dword v105, v[20:21], off offset:128
	global_load_dword v117, v[28:29], off
	global_load_dword v113, v[30:31], off
	global_load_dword v111, v[32:33], off
	global_load_dword v109, v[34:35], off
	global_load_dword v98, v[34:35], off offset:128
	global_load_dword v103, v[32:33], off offset:128
	global_load_dword v106, v[30:31], off offset:128
	global_load_dword v107, v[28:29], off offset:128
	v_or_b32_e32 v4, 32, v0
	v_or_b32_e32 v6, 33, v0
	v_or_b32_e32 v8, 34, v0
	v_or_b32_e32 v10, 35, v0
	v_or_b32_e32 v12, 40, v0
	v_or_b32_e32 v14, 41, v0
	v_or_b32_e32 v16, 42, v0
	v_or_b32_e32 v18, 43, v0
	v_or_b32_e32 v20, 48, v0
	v_or_b32_e32 v22, 49, v0
	v_or_b32_e32 v24, 50, v0
	v_or_b32_e32 v26, 51, v0
	v_or_b32_e32 v28, 56, v0
	v_or_b32_e32 v30, 57, v0
	v_or_b32_e32 v32, 58, v0
	v_or_b32_e32 v0, 59, v0
	v_ashrrev_i32_e32 v5, 31, v4
	v_ashrrev_i32_e32 v1, 31, v0
	v_lshlrev_b64 v[4:5], 12, v[4:5]
	v_ashrrev_i32_e32 v7, 31, v6
	v_ashrrev_i32_e32 v9, 31, v8
	v_ashrrev_i32_e32 v11, 31, v10
	v_ashrrev_i32_e32 v13, 31, v12
	v_ashrrev_i32_e32 v15, 31, v14
	v_ashrrev_i32_e32 v17, 31, v16
	v_ashrrev_i32_e32 v19, 31, v18
	v_ashrrev_i32_e32 v21, 31, v20
	v_ashrrev_i32_e32 v23, 31, v22
	v_ashrrev_i32_e32 v25, 31, v24
	v_ashrrev_i32_e32 v27, 31, v26
	v_ashrrev_i32_e32 v29, 31, v28
	v_ashrrev_i32_e32 v31, 31, v30
	v_ashrrev_i32_e32 v33, 31, v32
	v_lshlrev_b64 v[0:1], 12, v[0:1]
	v_lshl_add_u64 v[4:5], v[2:3], 0, v[4:5]
	v_lshlrev_b64 v[6:7], 12, v[6:7]
	v_lshlrev_b64 v[8:9], 12, v[8:9]
	v_lshlrev_b64 v[10:11], 12, v[10:11]
	v_lshlrev_b64 v[12:13], 12, v[12:13]
	v_lshlrev_b64 v[14:15], 12, v[14:15]
	v_lshlrev_b64 v[16:17], 12, v[16:17]
	v_lshlrev_b64 v[18:19], 12, v[18:19]
	v_lshlrev_b64 v[20:21], 12, v[20:21]
	v_lshlrev_b64 v[22:23], 12, v[22:23]
	v_lshlrev_b64 v[24:25], 12, v[24:25]
; #define TIDX get_tid_()
; DI int crow(int i, int h) { return (i & 3) + 8 * (i >> 2) + 4 * h; }
; #define GEMM_ISSUE(kt_, st_) do { char* sb_ = lw + (st_) * STAGE_B; const char* ak_ = Ab + (size_t)(kt_) * 128; const char* bk_ = Bb + (size_t)(kt_) * 128; \
;     _Pragma("unroll") for (int i_ = 0; i_ < 4; ++i_) glds16(ak_ + avo[i_], sb_ + i_ * 8192); \
;     _Pragma("unroll") for (int i_ = 0; i_ < 2; ++i_) glds16(bk_ + bvo[i_], sb_ + 32768 + i_ * 8192); } while (0)
;   const int tid = TIDX, lane = tid & 63, wid = tid >> 6, wr = wid >> 1, wc = wid & 1, r = lane & 31, h = lane >> 5;
;   const int ch = (tid & 7) ^ ((tid >> 4) & 7);
;   unsigned avo[4], bvo[2];
; #pragma unroll
;   for (int i = 0; i < 4; ++i) avo[i] = (unsigned)(((tid >> 3) + 64 * i) * lda * 2 + ch * 16);
; #pragma unroll
;   for (int i = 0; i < 2; ++i) bvo[i] = (unsigned)(((tid >> 3) + 64 * i) * ldb * 2 + ch * 16);
;   const char* Ab = (const char*)A; const char* Bb = (const char*)Bt;
;   char* lw = lds + tid * 16;
;   const int nk = K >> 6;
;   const unsigned swz = (unsigned)((r >> 1) & 7);
;   const unsigned arow_u = (unsigned)((wr * 64 + r) * 128), brow_u = (unsigned)((wc * 64 + r) * 128);
;   const unsigned co0 = ((0u + h) ^ swz) << 4, co1 = ((2u + h) ^ swz) << 4, co2 = ((4u + h) ^ swz) << 4, co3 = ((6u + h) ^ swz) << 4;
;     ...
;   if (PART != 2) {
;     GEMM_ISSUE(0, 0);
;     if (nk > 1) GEMM_ISSUE(1, 1);
;   }
;   if (PART == 1) return;
;   int st = 0;
;   for (int kt = 0; kt < nk; ++kt) {
;     if (kt + 1 < nk) asm volatile("s_waitcnt vmcnt(6)" ::: "memory");
;     else asm volatile("s_waitcnt vmcnt(0)" ::: "memory");
;     __builtin_amdgcn_s_barrier();
;     asm volatile("" ::: "memory");
;     if (kt + 2 < nk) { const int st2 = (st >= 1) ? st - 1 : 2; GEMM_ISSUE(kt + 2, st2); }
;   DI void pre(float (&rv)[2][2][16], int m0, int n0) const {
;     const int tid = TIDX, lane = tid & 63, wid = tid >> 6, wr = wid >> 1, wc = wid & 1, r = lane & 31, h = lane >> 5;
; #pragma unroll
;     for (int mi = 0; mi < 2; ++mi)
; #pragma unroll
;       for (int ni = 0; ni < 2; ++ni)
; #pragma unroll
;         for (int i = 0; i < 16; ++i)
;           rv[mi][ni][i] = res[(size_t)(m0 + wr * 64 + mi * 32 + crow(i, h)) * DM + n0 + wc * 64 + ni * 32 + r];
;   }
	v_lshlrev_b64 v[26:27], 12, v[26:27]
	v_lshlrev_b64 v[28:29], 12, v[28:29]
	v_lshlrev_b64 v[30:31], 12, v[30:31]
	v_lshlrev_b64 v[32:33], 12, v[32:33]
	v_lshl_add_u64 v[0:1], v[2:3], 0, v[0:1]
	v_lshl_add_u64 v[6:7], v[2:3], 0, v[6:7]
	v_lshl_add_u64 v[8:9], v[2:3], 0, v[8:9]
	v_lshl_add_u64 v[10:11], v[2:3], 0, v[10:11]
	v_lshl_add_u64 v[12:13], v[2:3], 0, v[12:13]
	v_lshl_add_u64 v[14:15], v[2:3], 0, v[14:15]
	v_lshl_add_u64 v[16:17], v[2:3], 0, v[16:17]
	v_lshl_add_u64 v[18:19], v[2:3], 0, v[18:19]
	v_lshl_add_u64 v[20:21], v[2:3], 0, v[20:21]
	v_lshl_add_u64 v[22:23], v[2:3], 0, v[22:23]
	v_lshl_add_u64 v[24:25], v[2:3], 0, v[24:25]
	v_lshl_add_u64 v[26:27], v[2:3], 0, v[26:27]
	v_lshl_add_u64 v[28:29], v[2:3], 0, v[28:29]
	v_lshl_add_u64 v[30:31], v[2:3], 0, v[30:31]
	v_lshl_add_u64 v[32:33], v[2:3], 0, v[32:33]
	global_load_dword v142, v[4:5], off
	global_load_dword v140, v[6:7], off
	global_load_dword v138, v[8:9], off
	global_load_dword v134, v[10:11], off
	global_load_dword v76, v[10:11], off offset:128
	global_load_dword v77, v[8:9], off offset:128
	global_load_dword v80, v[6:7], off offset:128
	global_load_dword v85, v[4:5], off offset:128
	global_load_dword v135, v[12:13], off
	global_load_dword v132, v[14:15], off
	global_load_dword v126, v[16:17], off
	global_load_dword v122, v[18:19], off
	global_load_dword v78, v[18:19], off offset:128
	global_load_dword v81, v[16:17], off offset:128
	global_load_dword v86, v[14:15], off offset:128
	global_load_dword v92, v[12:13], off offset:128
	global_load_dword v123, v[20:21], off
	global_load_dword v120, v[22:23], off
	global_load_dword v118, v[24:25], off
	global_load_dword v114, v[26:27], off
	global_load_dword v82, v[26:27], off offset:128
	global_load_dword v87, v[24:25], off offset:128
	global_load_dword v93, v[22:23], off offset:128
	global_load_dword v99, v[20:21], off offset:128
	global_load_dword v115, v[28:29], off
	global_load_dword v112, v[30:31], off
	global_load_dword v110, v[32:33], off
	global_load_dword v108, v[0:1], off
	global_load_dword v88, v[0:1], off offset:128
	global_load_dword v94, v[32:33], off offset:128
	global_load_dword v100, v[30:31], off offset:128
	global_load_dword v104, v[28:29], off offset:128
	v_mov_b32_e32 v1, v129
	s_ashr_i32 s9, s8, 31
	v_lshlrev_b32_e32 v5, 4, v1
	v_lshrrev_b32_e32 v3, 5, v1
	v_xor_b32_e32 v0, v5, v1
	v_lshlrev_b32_e32 v2, 8, v1
	v_and_b32_e32 v6, 31, v1
	v_bfe_u32 v7, v1, 5, 1
	v_add_u32_e32 v151, 0, v5
	v_lshrrev_b32_e32 v5, 1, v1
	v_bfe_u32 v8, v1, 1, 3
	v_lshlrev_b32_e32 v1, 7, v1
	v_and_b32_e32 v185, 0x2f80, v1
	v_bitop3_b32 v1, v3, v8, 1 bitop3:0x6c
	s_lshl_b64 s[30:31], s[8:9], 19
	v_readlane_b32 s24, v253, 13
	v_lshlrev_b32_e32 v186, 4, v1
	v_bitop3_b32 v1, v7, v8, 2 bitop3:0x36
	v_readlane_b32 s25, v253, 14
	s_add_u32 s30, s24, s30
	v_and_b32_e32 v2, 0xfffff800, v2
	s_movk_i32 s9, 0x70
	v_lshlrev_b32_e32 v187, 4, v1
	v_bitop3_b32 v1, v7, v8, 4 bitop3:0x36
	s_addc_u32 s31, s25, s31
	v_and_or_b32 v130, v0, s9, v2
	s_mov_b32 s9, 0x1ffffc0
	v_lshlrev_b32_e32 v217, 4, v1
	v_bitop3_b32 v1, v7, v8, 6 bitop3:0x36
	v_add_u32_e32 v8, 0x18000, v151
	s_ashr_i32 s15, s14, 31
	v_add_u32_e32 v0, 0x20000, v130
	v_and_or_b32 v5, v5, s9, v6
	v_lshlrev_b32_e32 v218, 4, v1
	v_mov_b32_e32 v1, v131
	v_lshl_add_u64 v[64:65], s[30:31], 0, v[130:131]
	v_readfirstlane_b32 s9, v8
	v_add_u32_e32 v8, 0x1a000, v151
	s_lshl_b64 s[54:55], s[14:15], 18
	s_waitcnt vmcnt(63)
	s_barrier
	v_lshl_add_u64 v[6:7], v[64:65], 0, s[78:79]
	s_mov_b32 m0, s9
	v_lshl_add_u64 v[66:67], s[30:31], 0, v[0:1]
	v_readfirstlane_b32 s15, v8
	global_load_lds_dwordx4 v[6:7], off
	v_lshl_add_u64 v[6:7], v[66:67], 0, s[78:79]
	s_mov_b32 m0, s15
	v_add_u32_e32 v2, 0x40000, v130
	v_add_u32_e32 v4, 0x60000, v130
	v_lshlrev_b32_e32 v184, 7, v5
	v_mov_b32_e32 v3, v131
	v_mov_b32_e32 v5, v131
	global_load_lds_dwordx4 v[6:7], off
	v_add_u32_e32 v6, 0x1c000, v151
	s_add_u32 s54, s11, s54
	v_lshl_add_u64 v[68:69], s[30:31], 0, v[2:3]
	v_readfirstlane_b32 s27, v6
	v_lshl_add_u64 v[70:71], s[30:31], 0, v[4:5]
	v_add_u32_e32 v4, 0x1e000, v151
	s_addc_u32 s55, s23, s55
	v_lshl_add_u64 v[2:3], v[68:69], 0, s[78:79]
	s_mov_b32 m0, s27
	v_readfirstlane_b32 s70, v4
	v_add_u32_e32 v4, 0x20000, v151
	global_load_lds_dwordx4 v[2:3], off
	v_lshl_add_u64 v[2:3], v[70:71], 0, s[78:79]
	s_mov_b32 m0, s70
	v_lshl_add_u64 v[72:73], s[54:55], 0, v[130:131]
	v_readfirstlane_b32 s71, v4
	global_load_lds_dwordx4 v[2:3], off
	v_lshl_add_u64 v[2:3], v[72:73], 0, s[78:79]
	s_mov_b32 m0, s71
	v_lshl_add_u64 v[74:75], s[54:55], 0, v[0:1]
	global_load_lds_dwordx4 v[2:3], off
	v_add_u32_e32 v2, 0x22000, v151
	s_cmp_lg_u32 0, -1
	v_readfirstlane_b32 s30, v2
	v_lshl_add_u64 v[0:1], v[74:75], 0, s[78:79]
	s_mov_b32 m0, s30
	s_cselect_b32 s24, 0, 0
	v_readlane_b32 s57, v254, 27
	global_load_lds_dwordx4 v[0:1], off
	v_add_u32_e32 v0, s24, v184
	s_add_i32 s24, s24, 0x8000
	s_mov_b32 s53, s52
	v_add_u32_e32 v1, s24, v185
	s_mov_b32 s54, s52
	s_mov_b32 s55, s52
	s_mov_b32 s56, s52
	s_mov_b32 s57, s52
	s_mov_b32 s58, s52
	s_mov_b32 s59, s52
	s_mov_b32 s60, s52
	s_mov_b32 s61, s52
	s_mov_b32 s62, s52
	s_mov_b32 s63, s52
	s_mov_b32 s64, s52
	s_mov_b32 s65, s52
	s_mov_b32 s66, s52
	s_mov_b32 s67, s52
	v_mov_b64_e32 v[48:49], s[52:53]
	v_add_u32_e32 v130, v0, v186
	v_add_u32_e32 v144, v0, v187
	v_add_u32_e32 v145, v0, v217
	v_add_u32_e32 v146, v0, v218
	v_add_u32_e32 v147, v186, v1
	v_add_u32_e32 v148, v187, v1
	v_add_u32_e32 v149, v217, v1
	v_add_u32_e32 v150, v218, v1
	v_mov_b64_e32 v[50:51], s[54:55]
	v_mov_b64_e32 v[52:53], s[56:57]
	v_mov_b64_e32 v[54:55], s[58:59]
	v_mov_b64_e32 v[56:57], s[60:61]
;   const int tid = TIDX, lane = tid & 63, wid = tid >> 6, wr = wid >> 1, wc = wid & 1, r = lane & 31, h = lane >> 5;
;   const int ch = (tid & 7) ^ ((tid >> 4) & 7);
;   unsigned avo[4], bvo[2];
; #pragma unroll
;   for (int i = 0; i < 4; ++i) avo[i] = (unsigned)(((tid >> 3) + 64 * i) * lda * 2 + ch * 16);
; #pragma unroll
;   for (int i = 0; i < 2; ++i) bvo[i] = (unsigned)(((tid >> 3) + 64 * i) * ldb * 2 + ch * 16);
;   const char* Ab = (const char*)A; const char* Bb = (const char*)Bt;
;   char* lw = lds + tid * 16;
;   const int nk = K >> 6;
;   const unsigned swz = (unsigned)((r >> 1) & 7);
;   const unsigned arow_u = (unsigned)((wr * 64 + r) * 128), brow_u = (unsigned)((wc * 64 + r) * 128);
;   const unsigned co0 = ((0u + h) ^ swz) << 4, co1 = ((2u + h) ^ swz) << 4, co2 = ((4u + h) ^ swz) << 4, co3 = ((6u + h) ^ swz) << 4;
;     ...
;   if (PART != 2) {
;     GEMM_ISSUE(0, 0);
;     if (nk > 1) GEMM_ISSUE(1, 1);
;   }
;   if (PART == 1) return;
;   int st = 0;
;   for (int kt = 0; kt < nk; ++kt) {
;     if (kt + 1 < nk) asm volatile("s_waitcnt vmcnt(6)" ::: "memory");
;     else asm volatile("s_waitcnt vmcnt(0)" ::: "memory");
;     __builtin_amdgcn_s_barrier();
;     asm volatile("" ::: "memory");
;     if (kt + 2 < nk) { const int st2 = (st >= 1) ? st - 1 : 2; GEMM_ISSUE(kt + 2, st2); }
;     const char* la = lds + st * STAGE_B;
;     const char* lb = la + 32768;
;     const unsigned sa_u = (unsigned)(size_t)la + arow_u, sb_u = (unsigned)(size_t)lb + brow_u;
;     const unsigned a0 = sa_u + co0, a1 = sa_u + co1, a2 = sa_u + co2, a3 = sa_u + co3;
;     const unsigned b0 = sb_u + co0, b1 = sb_u + co1, b2 = sb_u + co2, b3 = sb_u + co3;
;     {
;       bf16x8 p0, p1, q0, q1, u0, u1, w0, w1;
;       asm volatile(
;         "ds_read_b128 %4, %12\n\tds_read_b128 %5, %12 offset:4096\n\tds_read_b128 %6, %16\n\tds_read_b128 %7, %16 offset:4096\n\t"
;         "ds_read_b128 %8, %13\n\tds_read_b128 %9, %13 offset:4096\n\tds_read_b128 %10, %17\n\tds_read_b128 %11, %17 offset:4096\n\t"
;         "s_waitcnt lgkmcnt(4)\n\t"
;         "v_mfma_f32_32x32x16_bf16 %0, %4, %6, %0\n\tv_mfma_f32_32x32x16_bf16 %1, %4, %7, %1\n\tv_mfma_f32_32x32x16_bf16 %2, %5, %6, %2\n\tv_mfma_f32_32x32x16_bf16 %3, %5, %7, %3\n\t"
;         "ds_read_b128 %4, %14\n\tds_read_b128 %5, %14 offset:4096\n\tds_read_b128 %6, %18\n\tds_read_b128 %7, %18 offset:4096\n\t"
;         "s_waitcnt lgkmcnt(4)\n\t"
	v_mov_b64_e32 v[58:59], s[62:63]
	v_mov_b64_e32 v[60:61], s[64:65]
	v_mov_b64_e32 v[62:63], s[66:67]
	v_mov_b64_e32 v[32:33], v[48:49]
	v_mov_b64_e32 v[16:17], v[48:49]
	v_mov_b64_e32 v[0:1], v[48:49]
	v_mov_b64_e32 v[34:35], v[50:51]
	v_mov_b64_e32 v[36:37], v[52:53]
	v_mov_b64_e32 v[38:39], v[54:55]
	v_mov_b64_e32 v[40:41], v[56:57]
	v_mov_b64_e32 v[42:43], v[58:59]
	v_mov_b64_e32 v[44:45], v[60:61]
	v_mov_b64_e32 v[46:47], v[62:63]
	v_mov_b64_e32 v[18:19], v[50:51]
	v_mov_b64_e32 v[20:21], v[52:53]
	v_mov_b64_e32 v[22:23], v[54:55]
	v_mov_b64_e32 v[24:25], v[56:57]
	v_mov_b64_e32 v[26:27], v[58:59]
	v_mov_b64_e32 v[28:29], v[60:61]
	v_mov_b64_e32 v[30:31], v[62:63]
	v_mov_b64_e32 v[2:3], v[50:51]
	v_mov_b64_e32 v[4:5], v[52:53]
	v_mov_b64_e32 v[6:7], v[54:55]
	v_mov_b64_e32 v[8:9], v[56:57]
	v_mov_b64_e32 v[10:11], v[58:59]
	v_mov_b64_e32 v[12:13], v[60:61]
	v_mov_b64_e32 v[14:15], v[62:63]
	v_and_b32_e32 v152, 31, v129
	v_bfe_u32 v153, v129, 5, 1
	v_lshrrev_b32_e32 v154, 6, v129
	v_bfe_u32 v156, v129, 1, 3
	v_lshrrev_b32_e32 v155, 1, v154
	v_and_b32_e32 v154, 1, v154
	v_xor_b32_e32 v153, v153, v156
	v_lshl_add_u32 v155, v155, 6, v152
	v_lshl_add_u32 v154, v154, 6, v152
	v_lshlrev_b32_e32 v153, 4, v153
	v_lshlrev_b32_e32 v155, 7, v155
	v_lshlrev_b32_e32 v154, 7, v154
	v_add_u32_e32 v154, 0x8000, v154
	v_add_u32_e32 v130, v155, v153
	v_add_u32_e32 v147, v154, v153
	v_xor_b32_e32 v157, 0x20, v153
	v_add_u32_e32 v144, v155, v157
	v_add_u32_e32 v148, v154, v157
	v_xor_b32_e32 v157, 0x40, v153
	v_add_u32_e32 v145, v155, v157
	v_add_u32_e32 v149, v154, v157
	v_xor_b32_e32 v157, 0x60, v153
	v_add_u32_e32 v146, v155, v157
	v_add_u32_e32 v150, v154, v157
	v_add_u32_e32 v184, 0x18000, v130
	v_add_u32_e32 v217, 0x18000, v147
	v_add_u32_e32 v185, 0x18000, v144
	v_add_u32_e32 v218, 0x18000, v148
	v_add_u32_e32 v186, 0x18000, v145
	v_add_u32_e32 v219, 0x18000, v149
	v_add_u32_e32 v187, 0x18000, v146
	v_add_u32_e32 v220, 0x18000, v150
	v_lshlrev_b32_e32 v152, 4, v129
	s_nop 0
	v_readfirstlane_b32 s31, v152
	s_mov_b32 s25, 0
	ds_read_b128 v[152:155], v130
	ds_read_b128 v[156:159], v130 offset:4096
	ds_read_b128 v[160:163], v147
	ds_read_b128 v[164:167], v147 offset:4096
	ds_read_b128 v[168:171], v144
	ds_read_b128 v[172:175], v144 offset:4096
	ds_read_b128 v[176:179], v148
	ds_read_b128 v[180:183], v148 offset:4096
	s_waitcnt lgkmcnt(4)
	v_mfma_f32_32x32x16_bf16 v[48:63], v[152:155], v[160:163], v[48:63]
	v_mfma_f32_32x32x16_bf16 v[32:47], v[152:155], v[164:167], v[32:47]
	v_mfma_f32_32x32x16_bf16 v[16:31], v[156:159], v[160:163], v[16:31]
	v_mfma_f32_32x32x16_bf16 v[0:15], v[156:159], v[164:167], v[0:15]
	ds_read_b128 v[152:155], v145
	ds_read_b128 v[156:159], v145 offset:4096
	ds_read_b128 v[160:163], v149
	ds_read_b128 v[164:167], v149 offset:4096
	s_waitcnt lgkmcnt(4)
	v_mfma_f32_32x32x16_bf16 v[48:63], v[168:171], v[176:179], v[48:63]
	v_mfma_f32_32x32x16_bf16 v[32:47], v[168:171], v[180:183], v[32:47]
	v_mfma_f32_32x32x16_bf16 v[16:31], v[172:175], v[176:179], v[16:31]
	v_mfma_f32_32x32x16_bf16 v[0:15], v[172:175], v[180:183], v[0:15]
	ds_read_b128 v[168:171], v146
	ds_read_b128 v[172:175], v146 offset:4096
	ds_read_b128 v[176:179], v150
	ds_read_b128 v[180:183], v150 offset:4096
	s_waitcnt lgkmcnt(4)
	v_mfma_f32_32x32x16_bf16 v[48:63], v[152:155], v[160:163], v[48:63]
	v_mfma_f32_32x32x16_bf16 v[32:47], v[152:155], v[164:167], v[32:47]
	v_mfma_f32_32x32x16_bf16 v[16:31], v[156:159], v[160:163], v[16:31]
	v_mfma_f32_32x32x16_bf16 v[0:15], v[156:159], v[164:167], v[0:15]
	s_waitcnt vmcnt(63) lgkmcnt(0)
	s_barrier
	ds_read_b128 v[152:155], v130 offset:49152
	ds_read_b128 v[156:159], v130 offset:53248
	ds_read_b128 v[160:163], v147 offset:49152
	ds_read_b128 v[164:167], v147 offset:53248
	v_mfma_f32_32x32x16_bf16 v[48:63], v[168:171], v[176:179], v[48:63]
	s_mov_b32 s24, 0x180
	s_mov_b32 m0, s31
	v_lshl_add_u64 v[222:223], v[64:65], 0, s[24:25]
	global_load_lds_dwordx4 v[222:223], off
	v_mfma_f32_32x32x16_bf16 v[32:47], v[168:171], v[180:183], v[32:47]
	v_mfma_f32_32x32x16_bf16 v[16:31], v[172:175], v[176:179], v[16:31]
	s_add_u32 m0, s31, 0x2000
	v_lshl_add_u64 v[224:225], v[66:67], 0, s[24:25]
	global_load_lds_dwordx4 v[224:225], off
	v_mfma_f32_32x32x16_bf16 v[0:15], v[172:175], v[180:183], v[0:15]
	ds_read_b128 v[168:171], v144 offset:49152
	ds_read_b128 v[172:175], v144 offset:53248
	ds_read_b128 v[176:179], v148 offset:49152
	ds_read_b128 v[180:183], v148 offset:53248
	s_waitcnt lgkmcnt(4)
	v_mfma_f32_32x32x16_bf16 v[48:63], v[152:155], v[160:163], v[48:63]
	s_add_u32 m0, s31, 0x4000
	v_lshl_add_u64 v[222:223], v[68:69], 0, s[24:25]
	global_load_lds_dwordx4 v[222:223], off
	v_mfma_f32_32x32x16_bf16 v[32:47], v[152:155], v[164:167], v[32:47]
	v_mfma_f32_32x32x16_bf16 v[16:31], v[156:159], v[160:163], v[16:31]
	s_add_u32 m0, s31, 0x6000
	v_lshl_add_u64 v[224:225], v[70:71], 0, s[24:25]
	global_load_lds_dwordx4 v[224:225], off
	v_mfma_f32_32x32x16_bf16 v[0:15], v[156:159], v[164:167], v[0:15]
	ds_read_b128 v[152:155], v145 offset:49152
	ds_read_b128 v[156:159], v145 offset:53248
	ds_read_b128 v[160:163], v149 offset:49152
	ds_read_b128 v[164:167], v149 offset:53248
	s_waitcnt lgkmcnt(4)
	v_mfma_f32_32x32x16_bf16 v[48:63], v[168:171], v[176:179], v[48:63]
	s_add_u32 m0, s31, 0x8000
	v_lshl_add_u64 v[222:223], v[72:73], 0, s[24:25]
	global_load_lds_dwordx4 v[222:223], off
	v_mfma_f32_32x32x16_bf16 v[32:47], v[168:171], v[180:183], v[32:47]
	v_mfma_f32_32x32x16_bf16 v[16:31], v[172:175], v[176:179], v[16:31]
	s_add_u32 m0, s31, 0xa000
	v_lshl_add_u64 v[224:225], v[74:75], 0, s[24:25]
	global_load_lds_dwordx4 v[224:225], off
	v_mfma_f32_32x32x16_bf16 v[0:15], v[172:175], v[180:183], v[0:15]
	ds_read_b128 v[168:171], v146 offset:49152
	ds_read_b128 v[172:175], v146 offset:53248
	ds_read_b128 v[176:179], v150 offset:49152
	ds_read_b128 v[180:183], v150 offset:53248
	s_waitcnt lgkmcnt(4)
	v_mfma_f32_32x32x16_bf16 v[48:63], v[152:155], v[160:163], v[48:63]
	v_mfma_f32_32x32x16_bf16 v[32:47], v[152:155], v[164:167], v[32:47]
	v_mfma_f32_32x32x16_bf16 v[16:31], v[156:159], v[160:163], v[16:31]
	v_mfma_f32_32x32x16_bf16 v[0:15], v[156:159], v[164:167], v[0:15]
	s_waitcnt vmcnt(6) lgkmcnt(0)
	s_barrier
;     ...
;   if (PART != 2) {
;     GEMM_ISSUE(0, 0);
;     if (nk > 1) GEMM_ISSUE(1, 1);
;   }
;   if (PART == 1) return;
;   int st = 0;
;   for (int kt = 0; kt < nk; ++kt) {
;     if (kt + 1 < nk) asm volatile("s_waitcnt vmcnt(6)" ::: "memory");
;     else asm volatile("s_waitcnt vmcnt(0)" ::: "memory");
;     __builtin_amdgcn_s_barrier();
;     asm volatile("" ::: "memory");
;     if (kt + 2 < nk) { const int st2 = (st >= 1) ? st - 1 : 2; GEMM_ISSUE(kt + 2, st2); }
;     const char* la = lds + st * STAGE_B;
;     const char* lb = la + 32768;
;     const unsigned sa_u = (unsigned)(size_t)la + arow_u, sb_u = (unsigned)(size_t)lb + brow_u;
;     const unsigned a0 = sa_u + co0, a1 = sa_u + co1, a2 = sa_u + co2, a3 = sa_u + co3;
;     const unsigned b0 = sb_u + co0, b1 = sb_u + co1, b2 = sb_u + co2, b3 = sb_u + co3;
;     {
;       bf16x8 p0, p1, q0, q1, u0, u1, w0, w1;
;       asm volatile(
;         "ds_read_b128 %4, %12\n\tds_read_b128 %5, %12 offset:4096\n\tds_read_b128 %6, %16\n\tds_read_b128 %7, %16 offset:4096\n\t"
;         "ds_read_b128 %8, %13\n\tds_read_b128 %9, %13 offset:4096\n\tds_read_b128 %10, %17\n\tds_read_b128 %11, %17 offset:4096\n\t"
;         "s_waitcnt lgkmcnt(4)\n\t"
;         "v_mfma_f32_32x32x16_bf16 %0, %4, %6, %0\n\tv_mfma_f32_32x32x16_bf16 %1, %4, %7, %1\n\tv_mfma_f32_32x32x16_bf16 %2, %5, %6, %2\n\tv_mfma_f32_32x32x16_bf16 %3, %5, %7, %3\n\t"
;         "ds_read_b128 %4, %14\n\tds_read_b128 %5, %14 offset:4096\n\tds_read_b128 %6, %18\n\tds_read_b128 %7, %18 offset:4096\n\t"
;         "s_waitcnt lgkmcnt(4)\n\t"
;         "v_mfma_f32_32x32x16_bf16 %0, %8, %10, %0\n\tv_mfma_f32_32x32x16_bf16 %1, %8, %11, %1\n\tv_mfma_f32_32x32x16_bf16 %2, %9, %10, %2\n\tv_mfma_f32_32x32x16_bf16 %3, %9, %11, %3\n\t"
;         "ds_read_b128 %8, %15\n\tds_read_b128 %9, %15 offset:4096\n\tds_read_b128 %10, %19\n\tds_read_b128 %11, %19 offset:4096\n\t"
;         "s_waitcnt lgkmcnt(4)\n\t"
;         "v_mfma_f32_32x32x16_bf16 %0, %4, %6, %0\n\tv_mfma_f32_32x32x16_bf16 %1, %4, %7, %1\n\tv_mfma_f32_32x32x16_bf16 %2, %5, %6, %2\n\tv_mfma_f32_32x32x16_bf16 %3, %5, %7, %3\n\t"
;         "s_waitcnt lgkmcnt(0)\n\t"
;         "v_mfma_f32_32x32x16_bf16 %0, %8, %10, %0\n\tv_mfma_f32_32x32x16_bf16 %1, %8, %11, %1\n\tv_mfma_f32_32x32x16_bf16 %2, %9, %10, %2\n\tv_mfma_f32_32x32x16_bf16 %3, %9, %11, %3"
	ds_read_b128 v[152:155], v184
	ds_read_b128 v[156:159], v184 offset:4096
	ds_read_b128 v[160:163], v217
	ds_read_b128 v[164:167], v217 offset:4096
	v_mfma_f32_32x32x16_bf16 v[48:63], v[168:171], v[176:179], v[48:63]
	s_mov_b32 s24, 0x200
	s_add_u32 m0, s31, 0xc000
	v_lshl_add_u64 v[222:223], v[64:65], 0, s[24:25]
	global_load_lds_dwordx4 v[222:223], off
	v_mfma_f32_32x32x16_bf16 v[32:47], v[168:171], v[180:183], v[32:47]
	v_mfma_f32_32x32x16_bf16 v[16:31], v[172:175], v[176:179], v[16:31]
	s_add_u32 m0, s31, 0xe000
	v_lshl_add_u64 v[224:225], v[66:67], 0, s[24:25]
	global_load_lds_dwordx4 v[224:225], off
	v_mfma_f32_32x32x16_bf16 v[0:15], v[172:175], v[180:183], v[0:15]
	ds_read_b128 v[168:171], v185
	ds_read_b128 v[172:175], v185 offset:4096
	ds_read_b128 v[176:179], v218
	ds_read_b128 v[180:183], v218 offset:4096
	s_waitcnt lgkmcnt(4)
	v_mfma_f32_32x32x16_bf16 v[48:63], v[152:155], v[160:163], v[48:63]
	s_add_u32 m0, s31, 0x10000
	v_lshl_add_u64 v[222:223], v[68:69], 0, s[24:25]
	global_load_lds_dwordx4 v[222:223], off
	v_mfma_f32_32x32x16_bf16 v[32:47], v[152:155], v[164:167], v[32:47]
	v_mfma_f32_32x32x16_bf16 v[16:31], v[156:159], v[160:163], v[16:31]
	s_add_u32 m0, s31, 0x12000
	v_lshl_add_u64 v[224:225], v[70:71], 0, s[24:25]
	global_load_lds_dwordx4 v[224:225], off
	v_mfma_f32_32x32x16_bf16 v[0:15], v[156:159], v[164:167], v[0:15]
	ds_read_b128 v[152:155], v186
	ds_read_b128 v[156:159], v186 offset:4096
	ds_read_b128 v[160:163], v219
	ds_read_b128 v[164:167], v219 offset:4096
	s_waitcnt lgkmcnt(4)
	v_mfma_f32_32x32x16_bf16 v[48:63], v[168:171], v[176:179], v[48:63]
	s_add_u32 m0, s31, 0x14000
	v_lshl_add_u64 v[222:223], v[72:73], 0, s[24:25]
	global_load_lds_dwordx4 v[222:223], off
	v_mfma_f32_32x32x16_bf16 v[32:47], v[168:171], v[180:183], v[32:47]
	v_mfma_f32_32x32x16_bf16 v[16:31], v[172:175], v[176:179], v[16:31]
	s_add_u32 m0, s31, 0x16000
	v_lshl_add_u64 v[224:225], v[74:75], 0, s[24:25]
	global_load_lds_dwordx4 v[224:225], off
	v_mfma_f32_32x32x16_bf16 v[0:15], v[172:175], v[180:183], v[0:15]
	ds_read_b128 v[168:171], v187
	ds_read_b128 v[172:175], v187 offset:4096
	ds_read_b128 v[176:179], v220
	ds_read_b128 v[180:183], v220 offset:4096
	s_waitcnt lgkmcnt(4)
	v_mfma_f32_32x32x16_bf16 v[48:63], v[152:155], v[160:163], v[48:63]
	v_mfma_f32_32x32x16_bf16 v[32:47], v[152:155], v[164:167], v[32:47]
	v_mfma_f32_32x32x16_bf16 v[16:31], v[156:159], v[160:163], v[16:31]
	v_mfma_f32_32x32x16_bf16 v[0:15], v[156:159], v[164:167], v[0:15]
	s_waitcnt vmcnt(6) lgkmcnt(0)
	s_barrier
	ds_read_b128 v[152:155], v130
	ds_read_b128 v[156:159], v130 offset:4096
	ds_read_b128 v[160:163], v147
	ds_read_b128 v[164:167], v147 offset:4096
	v_mfma_f32_32x32x16_bf16 v[48:63], v[168:171], v[176:179], v[48:63]
	s_mov_b32 s24, 0x280
	s_add_u32 m0, s31, 0x18000
	v_lshl_add_u64 v[222:223], v[64:65], 0, s[24:25]
	global_load_lds_dwordx4 v[222:223], off
	v_mfma_f32_32x32x16_bf16 v[32:47], v[168:171], v[180:183], v[32:47]
	v_mfma_f32_32x32x16_bf16 v[16:31], v[172:175], v[176:179], v[16:31]
	s_add_u32 m0, s31, 0x1a000
	v_lshl_add_u64 v[224:225], v[66:67], 0, s[24:25]
	global_load_lds_dwordx4 v[224:225], off
	v_mfma_f32_32x32x16_bf16 v[0:15], v[172:175], v[180:183], v[0:15]
	ds_read_b128 v[168:171], v144
	ds_read_b128 v[172:175], v144 offset:4096
	ds_read_b128 v[176:179], v148
	ds_read_b128 v[180:183], v148 offset:4096
	s_waitcnt lgkmcnt(4)
	v_mfma_f32_32x32x16_bf16 v[48:63], v[152:155], v[160:163], v[48:63]
	s_add_u32 m0, s31, 0x1c000
	v_lshl_add_u64 v[222:223], v[68:69], 0, s[24:25]
	global_load_lds_dwordx4 v[222:223], off
	v_mfma_f32_32x32x16_bf16 v[32:47], v[152:155], v[164:167], v[32:47]
	v_mfma_f32_32x32x16_bf16 v[16:31], v[156:159], v[160:163], v[16:31]
	s_add_u32 m0, s31, 0x1e000
	v_lshl_add_u64 v[224:225], v[70:71], 0, s[24:25]
	global_load_lds_dwordx4 v[224:225], off
	v_mfma_f32_32x32x16_bf16 v[0:15], v[156:159], v[164:167], v[0:15]
	ds_read_b128 v[152:155], v145
	ds_read_b128 v[156:159], v145 offset:4096
	ds_read_b128 v[160:163], v149
	ds_read_b128 v[164:167], v149 offset:4096
	s_waitcnt lgkmcnt(4)
	v_mfma_f32_32x32x16_bf16 v[48:63], v[168:171], v[176:179], v[48:63]
	s_add_u32 m0, s31, 0x20000
	v_lshl_add_u64 v[222:223], v[72:73], 0, s[24:25]
	global_load_lds_dwordx4 v[222:223], off
	v_mfma_f32_32x32x16_bf16 v[32:47], v[168:171], v[180:183], v[32:47]
	v_mfma_f32_32x32x16_bf16 v[16:31], v[172:175], v[176:179], v[16:31]
	s_add_u32 m0, s31, 0x22000
	v_lshl_add_u64 v[224:225], v[74:75], 0, s[24:25]
	global_load_lds_dwordx4 v[224:225], off
	v_mfma_f32_32x32x16_bf16 v[0:15], v[172:175], v[180:183], v[0:15]
	ds_read_b128 v[168:171], v146
	ds_read_b128 v[172:175], v146 offset:4096
	ds_read_b128 v[176:179], v150
	ds_read_b128 v[180:183], v150 offset:4096
	s_waitcnt lgkmcnt(4)
	v_mfma_f32_32x32x16_bf16 v[48:63], v[152:155], v[160:163], v[48:63]
	v_mfma_f32_32x32x16_bf16 v[32:47], v[152:155], v[164:167], v[32:47]
	v_mfma_f32_32x32x16_bf16 v[16:31], v[156:159], v[160:163], v[16:31]
	v_mfma_f32_32x32x16_bf16 v[0:15], v[156:159], v[164:167], v[0:15]
	s_waitcnt vmcnt(6) lgkmcnt(0)
	s_barrier
;     ...
;   if (PART != 2) {
;     GEMM_ISSUE(0, 0);
;     if (nk > 1) GEMM_ISSUE(1, 1);
;   }
;   if (PART == 1) return;
;   int st = 0;
;   for (int kt = 0; kt < nk; ++kt) {
;     if (kt + 1 < nk) asm volatile("s_waitcnt vmcnt(6)" ::: "memory");
;     else asm volatile("s_waitcnt vmcnt(0)" ::: "memory");
;     __builtin_amdgcn_s_barrier();
;     asm volatile("" ::: "memory");
;     if (kt + 2 < nk) { const int st2 = (st >= 1) ? st - 1 : 2; GEMM_ISSUE(kt + 2, st2); }
;     const char* la = lds + st * STAGE_B;
;     const char* lb = la + 32768;
;     const unsigned sa_u = (unsigned)(size_t)la + arow_u, sb_u = (unsigned)(size_t)lb + brow_u;
;     const unsigned a0 = sa_u + co0, a1 = sa_u + co1, a2 = sa_u + co2, a3 = sa_u + co3;
;     const unsigned b0 = sb_u + co0, b1 = sb_u + co1, b2 = sb_u + co2, b3 = sb_u + co3;
;     {
;       bf16x8 p0, p1, q0, q1, u0, u1, w0, w1;
;       asm volatile(
;         "ds_read_b128 %4, %12\n\tds_read_b128 %5, %12 offset:4096\n\tds_read_b128 %6, %16\n\tds_read_b128 %7, %16 offset:4096\n\t"
;         "ds_read_b128 %8, %13\n\tds_read_b128 %9, %13 offset:4096\n\tds_read_b128 %10, %17\n\tds_read_b128 %11, %17 offset:4096\n\t"
;         "s_waitcnt lgkmcnt(4)\n\t"
;         "v_mfma_f32_32x32x16_bf16 %0, %4, %6, %0\n\tv_mfma_f32_32x32x16_bf16 %1, %4, %7, %1\n\tv_mfma_f32_32x32x16_bf16 %2, %5, %6, %2\n\tv_mfma_f32_32x32x16_bf16 %3, %5, %7, %3\n\t"
;         "ds_read_b128 %4, %14\n\tds_read_b128 %5, %14 offset:4096\n\tds_read_b128 %6, %18\n\tds_read_b128 %7, %18 offset:4096\n\t"
;         "s_waitcnt lgkmcnt(4)\n\t"
;         "v_mfma_f32_32x32x16_bf16 %0, %8, %10, %0\n\tv_mfma_f32_32x32x16_bf16 %1, %8, %11, %1\n\tv_mfma_f32_32x32x16_bf16 %2, %9, %10, %2\n\tv_mfma_f32_32x32x16_bf16 %3, %9, %11, %3\n\t"
;         "ds_read_b128 %8, %15\n\tds_read_b128 %9, %15 offset:4096\n\tds_read_b128 %10, %19\n\tds_read_b128 %11, %19 offset:4096\n\t"
;         "s_waitcnt lgkmcnt(4)\n\t"
;         "v_mfma_f32_32x32x16_bf16 %0, %4, %6, %0\n\tv_mfma_f32_32x32x16_bf16 %1, %4, %7, %1\n\tv_mfma_f32_32x32x16_bf16 %2, %5, %6, %2\n\tv_mfma_f32_32x32x16_bf16 %3, %5, %7, %3\n\t"
;         "s_waitcnt lgkmcnt(0)\n\t"
;         "v_mfma_f32_32x32x16_bf16 %0, %8, %10, %0\n\tv_mfma_f32_32x32x16_bf16 %1, %8, %11, %1\n\tv_mfma_f32_32x32x16_bf16 %2, %9, %10, %2\n\tv_mfma_f32_32x32x16_bf16 %3, %9, %11, %3"
	ds_read_b128 v[152:155], v130 offset:49152
	ds_read_b128 v[156:159], v130 offset:53248
	ds_read_b128 v[160:163], v147 offset:49152
	ds_read_b128 v[164:167], v147 offset:53248
	v_mfma_f32_32x32x16_bf16 v[48:63], v[168:171], v[176:179], v[48:63]
	s_mov_b32 s24, 0x300
	s_mov_b32 m0, s31
	v_lshl_add_u64 v[222:223], v[64:65], 0, s[24:25]
	global_load_lds_dwordx4 v[222:223], off
	v_mfma_f32_32x32x16_bf16 v[32:47], v[168:171], v[180:183], v[32:47]
	v_mfma_f32_32x32x16_bf16 v[16:31], v[172:175], v[176:179], v[16:31]
	s_add_u32 m0, s31, 0x2000
	v_lshl_add_u64 v[224:225], v[66:67], 0, s[24:25]
	global_load_lds_dwordx4 v[224:225], off
	v_mfma_f32_32x32x16_bf16 v[0:15], v[172:175], v[180:183], v[0:15]
	ds_read_b128 v[168:171], v144 offset:49152
	ds_read_b128 v[172:175], v144 offset:53248
	ds_read_b128 v[176:179], v148 offset:49152
	ds_read_b128 v[180:183], v148 offset:53248
	s_waitcnt lgkmcnt(4)
	v_mfma_f32_32x32x16_bf16 v[48:63], v[152:155], v[160:163], v[48:63]
	s_add_u32 m0, s31, 0x4000
	v_lshl_add_u64 v[222:223], v[68:69], 0, s[24:25]
	global_load_lds_dwordx4 v[222:223], off
	v_mfma_f32_32x32x16_bf16 v[32:47], v[152:155], v[164:167], v[32:47]
	v_mfma_f32_32x32x16_bf16 v[16:31], v[156:159], v[160:163], v[16:31]
	s_add_u32 m0, s31, 0x6000
	v_lshl_add_u64 v[224:225], v[70:71], 0, s[24:25]
	global_load_lds_dwordx4 v[224:225], off
	v_mfma_f32_32x32x16_bf16 v[0:15], v[156:159], v[164:167], v[0:15]
	ds_read_b128 v[152:155], v145 offset:49152
	ds_read_b128 v[156:159], v145 offset:53248
	ds_read_b128 v[160:163], v149 offset:49152
	ds_read_b128 v[164:167], v149 offset:53248
	s_waitcnt lgkmcnt(4)
	v_mfma_f32_32x32x16_bf16 v[48:63], v[168:171], v[176:179], v[48:63]
	s_add_u32 m0, s31, 0x8000
	v_lshl_add_u64 v[222:223], v[72:73], 0, s[24:25]
	global_load_lds_dwordx4 v[222:223], off
	v_mfma_f32_32x32x16_bf16 v[32:47], v[168:171], v[180:183], v[32:47]
	v_mfma_f32_32x32x16_bf16 v[16:31], v[172:175], v[176:179], v[16:31]
	s_add_u32 m0, s31, 0xa000
	v_lshl_add_u64 v[224:225], v[74:75], 0, s[24:25]
	global_load_lds_dwordx4 v[224:225], off
	v_mfma_f32_32x32x16_bf16 v[0:15], v[172:175], v[180:183], v[0:15]
	ds_read_b128 v[168:171], v146 offset:49152
	ds_read_b128 v[172:175], v146 offset:53248
	ds_read_b128 v[176:179], v150 offset:49152
	ds_read_b128 v[180:183], v150 offset:53248
	s_waitcnt lgkmcnt(4)
	v_mfma_f32_32x32x16_bf16 v[48:63], v[152:155], v[160:163], v[48:63]
	v_mfma_f32_32x32x16_bf16 v[32:47], v[152:155], v[164:167], v[32:47]
	v_mfma_f32_32x32x16_bf16 v[16:31], v[156:159], v[160:163], v[16:31]
	v_mfma_f32_32x32x16_bf16 v[0:15], v[156:159], v[164:167], v[0:15]
	s_waitcnt vmcnt(6) lgkmcnt(0)
	s_barrier
	ds_read_b128 v[152:155], v184
	ds_read_b128 v[156:159], v184 offset:4096
	ds_read_b128 v[160:163], v217
	ds_read_b128 v[164:167], v217 offset:4096
	v_mfma_f32_32x32x16_bf16 v[48:63], v[168:171], v[176:179], v[48:63]
	s_mov_b32 s24, 0x380
	s_add_u32 m0, s31, 0xc000
	v_lshl_add_u64 v[222:223], v[64:65], 0, s[24:25]
	global_load_lds_dwordx4 v[222:223], off
	v_mfma_f32_32x32x16_bf16 v[32:47], v[168:171], v[180:183], v[32:47]
	v_mfma_f32_32x32x16_bf16 v[16:31], v[172:175], v[176:179], v[16:31]
	s_add_u32 m0, s31, 0xe000
	v_lshl_add_u64 v[224:225], v[66:67], 0, s[24:25]
	global_load_lds_dwordx4 v[224:225], off
	v_mfma_f32_32x32x16_bf16 v[0:15], v[172:175], v[180:183], v[0:15]
	ds_read_b128 v[168:171], v185
	ds_read_b128 v[172:175], v185 offset:4096
	ds_read_b128 v[176:179], v218
	ds_read_b128 v[180:183], v218 offset:4096
	s_waitcnt lgkmcnt(4)
	v_mfma_f32_32x32x16_bf16 v[48:63], v[152:155], v[160:163], v[48:63]
	s_add_u32 m0, s31, 0x10000
	v_lshl_add_u64 v[222:223], v[68:69], 0, s[24:25]
	global_load_lds_dwordx4 v[222:223], off
	v_mfma_f32_32x32x16_bf16 v[32:47], v[152:155], v[164:167], v[32:47]
	v_mfma_f32_32x32x16_bf16 v[16:31], v[156:159], v[160:163], v[16:31]
	s_add_u32 m0, s31, 0x12000
	v_lshl_add_u64 v[224:225], v[70:71], 0, s[24:25]
	global_load_lds_dwordx4 v[224:225], off
	v_mfma_f32_32x32x16_bf16 v[0:15], v[156:159], v[164:167], v[0:15]
	ds_read_b128 v[152:155], v186
	ds_read_b128 v[156:159], v186 offset:4096
	ds_read_b128 v[160:163], v219
	ds_read_b128 v[164:167], v219 offset:4096
	s_waitcnt lgkmcnt(4)
	v_mfma_f32_32x32x16_bf16 v[48:63], v[168:171], v[176:179], v[48:63]
	s_add_u32 m0, s31, 0x14000
	v_lshl_add_u64 v[222:223], v[72:73], 0, s[24:25]
	global_load_lds_dwordx4 v[222:223], off
	v_mfma_f32_32x32x16_bf16 v[32:47], v[168:171], v[180:183], v[32:47]
	v_mfma_f32_32x32x16_bf16 v[16:31], v[172:175], v[176:179], v[16:31]
	s_add_u32 m0, s31, 0x16000
	v_lshl_add_u64 v[224:225], v[74:75], 0, s[24:25]
	global_load_lds_dwordx4 v[224:225], off
	v_mfma_f32_32x32x16_bf16 v[0:15], v[172:175], v[180:183], v[0:15]
	ds_read_b128 v[168:171], v187
	ds_read_b128 v[172:175], v187 offset:4096
	ds_read_b128 v[176:179], v220
	ds_read_b128 v[180:183], v220 offset:4096
	s_waitcnt lgkmcnt(4)
	v_mfma_f32_32x32x16_bf16 v[48:63], v[152:155], v[160:163], v[48:63]
	v_mfma_f32_32x32x16_bf16 v[32:47], v[152:155], v[164:167], v[32:47]
	v_mfma_f32_32x32x16_bf16 v[16:31], v[156:159], v[160:163], v[16:31]
	v_mfma_f32_32x32x16_bf16 v[0:15], v[156:159], v[164:167], v[0:15]
	s_waitcnt vmcnt(6) lgkmcnt(0)
	s_barrier
;     ...
;   if (PART != 2) {
;     GEMM_ISSUE(0, 0);
;     if (nk > 1) GEMM_ISSUE(1, 1);
;   }
;   if (PART == 1) return;
;   int st = 0;
;   for (int kt = 0; kt < nk; ++kt) {
;     if (kt + 1 < nk) asm volatile("s_waitcnt vmcnt(6)" ::: "memory");
;     else asm volatile("s_waitcnt vmcnt(0)" ::: "memory");
;     __builtin_amdgcn_s_barrier();
;     asm volatile("" ::: "memory");
;     if (kt + 2 < nk) { const int st2 = (st >= 1) ? st - 1 : 2; GEMM_ISSUE(kt + 2, st2); }
;     const char* la = lds + st * STAGE_B;
;     const char* lb = la + 32768;
;     const unsigned sa_u = (unsigned)(size_t)la + arow_u, sb_u = (unsigned)(size_t)lb + brow_u;
;     const unsigned a0 = sa_u + co0, a1 = sa_u + co1, a2 = sa_u + co2, a3 = sa_u + co3;
;     const unsigned b0 = sb_u + co0, b1 = sb_u + co1, b2 = sb_u + co2, b3 = sb_u + co3;
;     {
;       bf16x8 p0, p1, q0, q1, u0, u1, w0, w1;
;       asm volatile(
;         "ds_read_b128 %4, %12\n\tds_read_b128 %5, %12 offset:4096\n\tds_read_b128 %6, %16\n\tds_read_b128 %7, %16 offset:4096\n\t"
;         "ds_read_b128 %8, %13\n\tds_read_b128 %9, %13 offset:4096\n\tds_read_b128 %10, %17\n\tds_read_b128 %11, %17 offset:4096\n\t"
;         "s_waitcnt lgkmcnt(4)\n\t"
;         "v_mfma_f32_32x32x16_bf16 %0, %4, %6, %0\n\tv_mfma_f32_32x32x16_bf16 %1, %4, %7, %1\n\tv_mfma_f32_32x32x16_bf16 %2, %5, %6, %2\n\tv_mfma_f32_32x32x16_bf16 %3, %5, %7, %3\n\t"
;         "ds_read_b128 %4, %14\n\tds_read_b128 %5, %14 offset:4096\n\tds_read_b128 %6, %18\n\tds_read_b128 %7, %18 offset:4096\n\t"
;         "s_waitcnt lgkmcnt(4)\n\t"
;         "v_mfma_f32_32x32x16_bf16 %0, %8, %10, %0\n\tv_mfma_f32_32x32x16_bf16 %1, %8, %11, %1\n\tv_mfma_f32_32x32x16_bf16 %2, %9, %10, %2\n\tv_mfma_f32_32x32x16_bf16 %3, %9, %11, %3\n\t"
;         "ds_read_b128 %8, %15\n\tds_read_b128 %9, %15 offset:4096\n\tds_read_b128 %10, %19\n\tds_read_b128 %11, %19 offset:4096\n\t"
;         "s_waitcnt lgkmcnt(4)\n\t"
;         "v_mfma_f32_32x32x16_bf16 %0, %4, %6, %0\n\tv_mfma_f32_32x32x16_bf16 %1, %4, %7, %1\n\tv_mfma_f32_32x32x16_bf16 %2, %5, %6, %2\n\tv_mfma_f32_32x32x16_bf16 %3, %5, %7, %3\n\t"
;         "s_waitcnt lgkmcnt(0)\n\t"
;         "v_mfma_f32_32x32x16_bf16 %0, %8, %10, %0\n\tv_mfma_f32_32x32x16_bf16 %1, %8, %11, %1\n\tv_mfma_f32_32x32x16_bf16 %2, %9, %10, %2\n\tv_mfma_f32_32x32x16_bf16 %3, %9, %11, %3"
	ds_read_b128 v[152:155], v130
	ds_read_b128 v[156:159], v130 offset:4096
	ds_read_b128 v[160:163], v147
	ds_read_b128 v[164:167], v147 offset:4096
	v_mfma_f32_32x32x16_bf16 v[48:63], v[168:171], v[176:179], v[48:63]
	s_mov_b32 s24, 0x400
	s_add_u32 m0, s31, 0x18000
	v_lshl_add_u64 v[222:223], v[64:65], 0, s[24:25]
	global_load_lds_dwordx4 v[222:223], off
	v_mfma_f32_32x32x16_bf16 v[32:47], v[168:171], v[180:183], v[32:47]
	v_mfma_f32_32x32x16_bf16 v[16:31], v[172:175], v[176:179], v[16:31]
	s_add_u32 m0, s31, 0x1a000
	v_lshl_add_u64 v[224:225], v[66:67], 0, s[24:25]
	global_load_lds_dwordx4 v[224:225], off
	v_mfma_f32_32x32x16_bf16 v[0:15], v[172:175], v[180:183], v[0:15]
	ds_read_b128 v[168:171], v144
	ds_read_b128 v[172:175], v144 offset:4096
	ds_read_b128 v[176:179], v148
	ds_read_b128 v[180:183], v148 offset:4096
	s_waitcnt lgkmcnt(4)
	v_mfma_f32_32x32x16_bf16 v[48:63], v[152:155], v[160:163], v[48:63]
	s_add_u32 m0, s31, 0x1c000
	v_lshl_add_u64 v[222:223], v[68:69], 0, s[24:25]
	global_load_lds_dwordx4 v[222:223], off
	v_mfma_f32_32x32x16_bf16 v[32:47], v[152:155], v[164:167], v[32:47]
	v_mfma_f32_32x32x16_bf16 v[16:31], v[156:159], v[160:163], v[16:31]
	s_add_u32 m0, s31, 0x1e000
	v_lshl_add_u64 v[224:225], v[70:71], 0, s[24:25]
	global_load_lds_dwordx4 v[224:225], off
	v_mfma_f32_32x32x16_bf16 v[0:15], v[156:159], v[164:167], v[0:15]
	ds_read_b128 v[152:155], v145
	ds_read_b128 v[156:159], v145 offset:4096
	ds_read_b128 v[160:163], v149
	ds_read_b128 v[164:167], v149 offset:4096
	s_waitcnt lgkmcnt(4)
	v_mfma_f32_32x32x16_bf16 v[48:63], v[168:171], v[176:179], v[48:63]
	s_add_u32 m0, s31, 0x20000
	v_lshl_add_u64 v[222:223], v[72:73], 0, s[24:25]
	global_load_lds_dwordx4 v[222:223], off
	v_mfma_f32_32x32x16_bf16 v[32:47], v[168:171], v[180:183], v[32:47]
	v_mfma_f32_32x32x16_bf16 v[16:31], v[172:175], v[176:179], v[16:31]
	s_add_u32 m0, s31, 0x22000
	v_lshl_add_u64 v[224:225], v[74:75], 0, s[24:25]
	global_load_lds_dwordx4 v[224:225], off
	v_mfma_f32_32x32x16_bf16 v[0:15], v[172:175], v[180:183], v[0:15]
	ds_read_b128 v[168:171], v146
	ds_read_b128 v[172:175], v146 offset:4096
	ds_read_b128 v[176:179], v150
	ds_read_b128 v[180:183], v150 offset:4096
	s_waitcnt lgkmcnt(4)
	v_mfma_f32_32x32x16_bf16 v[48:63], v[152:155], v[160:163], v[48:63]
	v_mfma_f32_32x32x16_bf16 v[32:47], v[152:155], v[164:167], v[32:47]
	v_mfma_f32_32x32x16_bf16 v[16:31], v[156:159], v[160:163], v[16:31]
	v_mfma_f32_32x32x16_bf16 v[0:15], v[156:159], v[164:167], v[0:15]
	s_waitcnt vmcnt(6) lgkmcnt(0)
	s_barrier
	ds_read_b128 v[152:155], v130 offset:49152
	ds_read_b128 v[156:159], v130 offset:53248
	ds_read_b128 v[160:163], v147 offset:49152
	ds_read_b128 v[164:167], v147 offset:53248
	v_mfma_f32_32x32x16_bf16 v[48:63], v[168:171], v[176:179], v[48:63]
	s_mov_b32 s24, 0x480
	s_mov_b32 m0, s31
	v_lshl_add_u64 v[222:223], v[64:65], 0, s[24:25]
	global_load_lds_dwordx4 v[222:223], off
	v_mfma_f32_32x32x16_bf16 v[32:47], v[168:171], v[180:183], v[32:47]
	v_mfma_f32_32x32x16_bf16 v[16:31], v[172:175], v[176:179], v[16:31]
	s_add_u32 m0, s31, 0x2000
	v_lshl_add_u64 v[224:225], v[66:67], 0, s[24:25]
	global_load_lds_dwordx4 v[224:225], off
	v_mfma_f32_32x32x16_bf16 v[0:15], v[172:175], v[180:183], v[0:15]
	ds_read_b128 v[168:171], v144 offset:49152
	ds_read_b128 v[172:175], v144 offset:53248
	ds_read_b128 v[176:179], v148 offset:49152
	ds_read_b128 v[180:183], v148 offset:53248
	s_waitcnt lgkmcnt(4)
	v_mfma_f32_32x32x16_bf16 v[48:63], v[152:155], v[160:163], v[48:63]
	s_add_u32 m0, s31, 0x4000
	v_lshl_add_u64 v[222:223], v[68:69], 0, s[24:25]
	global_load_lds_dwordx4 v[222:223], off
	v_mfma_f32_32x32x16_bf16 v[32:47], v[152:155], v[164:167], v[32:47]
	v_mfma_f32_32x32x16_bf16 v[16:31], v[156:159], v[160:163], v[16:31]
	s_add_u32 m0, s31, 0x6000
	v_lshl_add_u64 v[224:225], v[70:71], 0, s[24:25]
	global_load_lds_dwordx4 v[224:225], off
	v_mfma_f32_32x32x16_bf16 v[0:15], v[156:159], v[164:167], v[0:15]
	ds_read_b128 v[152:155], v145 offset:49152
	ds_read_b128 v[156:159], v145 offset:53248
	ds_read_b128 v[160:163], v149 offset:49152
	ds_read_b128 v[164:167], v149 offset:53248
	s_waitcnt lgkmcnt(4)
	v_mfma_f32_32x32x16_bf16 v[48:63], v[168:171], v[176:179], v[48:63]
	s_add_u32 m0, s31, 0x8000
	v_lshl_add_u64 v[222:223], v[72:73], 0, s[24:25]
	global_load_lds_dwordx4 v[222:223], off
	v_mfma_f32_32x32x16_bf16 v[32:47], v[168:171], v[180:183], v[32:47]
	v_mfma_f32_32x32x16_bf16 v[16:31], v[172:175], v[176:179], v[16:31]
	s_add_u32 m0, s31, 0xa000
	v_lshl_add_u64 v[224:225], v[74:75], 0, s[24:25]
	global_load_lds_dwordx4 v[224:225], off
	v_mfma_f32_32x32x16_bf16 v[0:15], v[172:175], v[180:183], v[0:15]
	ds_read_b128 v[168:171], v146 offset:49152
	ds_read_b128 v[172:175], v146 offset:53248
	ds_read_b128 v[176:179], v150 offset:49152
	ds_read_b128 v[180:183], v150 offset:53248
	s_waitcnt lgkmcnt(4)
	v_mfma_f32_32x32x16_bf16 v[48:63], v[152:155], v[160:163], v[48:63]
	v_mfma_f32_32x32x16_bf16 v[32:47], v[152:155], v[164:167], v[32:47]
	v_mfma_f32_32x32x16_bf16 v[16:31], v[156:159], v[160:163], v[16:31]
	v_mfma_f32_32x32x16_bf16 v[0:15], v[156:159], v[164:167], v[0:15]
	s_waitcnt vmcnt(6) lgkmcnt(0)
	s_barrier
;     ...
;   if (PART != 2) {
;     GEMM_ISSUE(0, 0);
;     if (nk > 1) GEMM_ISSUE(1, 1);
;   }
;   if (PART == 1) return;
;   int st = 0;
;   for (int kt = 0; kt < nk; ++kt) {
;     if (kt + 1 < nk) asm volatile("s_waitcnt vmcnt(6)" ::: "memory");
;     else asm volatile("s_waitcnt vmcnt(0)" ::: "memory");
;     __builtin_amdgcn_s_barrier();
;     asm volatile("" ::: "memory");
;     if (kt + 2 < nk) { const int st2 = (st >= 1) ? st - 1 : 2; GEMM_ISSUE(kt + 2, st2); }
;     const char* la = lds + st * STAGE_B;
;     const char* lb = la + 32768;
;     const unsigned sa_u = (unsigned)(size_t)la + arow_u, sb_u = (unsigned)(size_t)lb + brow_u;
;     const unsigned a0 = sa_u + co0, a1 = sa_u + co1, a2 = sa_u + co2, a3 = sa_u + co3;
;     const unsigned b0 = sb_u + co0, b1 = sb_u + co1, b2 = sb_u + co2, b3 = sb_u + co3;
;     {
;       bf16x8 p0, p1, q0, q1, u0, u1, w0, w1;
;       asm volatile(
;         "ds_read_b128 %4, %12\n\tds_read_b128 %5, %12 offset:4096\n\tds_read_b128 %6, %16\n\tds_read_b128 %7, %16 offset:4096\n\t"
;         "ds_read_b128 %8, %13\n\tds_read_b128 %9, %13 offset:4096\n\tds_read_b128 %10, %17\n\tds_read_b128 %11, %17 offset:4096\n\t"
;         "s_waitcnt lgkmcnt(4)\n\t"
;         "v_mfma_f32_32x32x16_bf16 %0, %4, %6, %0\n\tv_mfma_f32_32x32x16_bf16 %1, %4, %7, %1\n\tv_mfma_f32_32x32x16_bf16 %2, %5, %6, %2\n\tv_mfma_f32_32x32x16_bf16 %3, %5, %7, %3\n\t"
;         "ds_read_b128 %4, %14\n\tds_read_b128 %5, %14 offset:4096\n\tds_read_b128 %6, %18\n\tds_read_b128 %7, %18 offset:4096\n\t"
;         "s_waitcnt lgkmcnt(4)\n\t"
;         "v_mfma_f32_32x32x16_bf16 %0, %8, %10, %0\n\tv_mfma_f32_32x32x16_bf16 %1, %8, %11, %1\n\tv_mfma_f32_32x32x16_bf16 %2, %9, %10, %2\n\tv_mfma_f32_32x32x16_bf16 %3, %9, %11, %3\n\t"
;         "ds_read_b128 %8, %15\n\tds_read_b128 %9, %15 offset:4096\n\tds_read_b128 %10, %19\n\tds_read_b128 %11, %19 offset:4096\n\t"
;         "s_waitcnt lgkmcnt(4)\n\t"
;         "v_mfma_f32_32x32x16_bf16 %0, %4, %6, %0\n\tv_mfma_f32_32x32x16_bf16 %1, %4, %7, %1\n\tv_mfma_f32_32x32x16_bf16 %2, %5, %6, %2\n\tv_mfma_f32_32x32x16_bf16 %3, %5, %7, %3\n\t"
;         "s_waitcnt lgkmcnt(0)\n\t"
;         "v_mfma_f32_32x32x16_bf16 %0, %8, %10, %0\n\tv_mfma_f32_32x32x16_bf16 %1, %8, %11, %1\n\tv_mfma_f32_32x32x16_bf16 %2, %9, %10, %2\n\tv_mfma_f32_32x32x16_bf16 %3, %9, %11, %3"
	ds_read_b128 v[152:155], v184
	ds_read_b128 v[156:159], v184 offset:4096
	ds_read_b128 v[160:163], v217
	ds_read_b128 v[164:167], v217 offset:4096
	v_mfma_f32_32x32x16_bf16 v[48:63], v[168:171], v[176:179], v[48:63]
	s_mov_b32 s24, 0x500
	s_add_u32 m0, s31, 0xc000
	v_lshl_add_u64 v[222:223], v[64:65], 0, s[24:25]
	global_load_lds_dwordx4 v[222:223], off
	v_mfma_f32_32x32x16_bf16 v[32:47], v[168:171], v[180:183], v[32:47]
	v_mfma_f32_32x32x16_bf16 v[16:31], v[172:175], v[176:179], v[16:31]
	s_add_u32 m0, s31, 0xe000
	v_lshl_add_u64 v[224:225], v[66:67], 0, s[24:25]
	global_load_lds_dwordx4 v[224:225], off
	v_mfma_f32_32x32x16_bf16 v[0:15], v[172:175], v[180:183], v[0:15]
	ds_read_b128 v[168:171], v185
	ds_read_b128 v[172:175], v185 offset:4096
	ds_read_b128 v[176:179], v218
	ds_read_b128 v[180:183], v218 offset:4096
	s_waitcnt lgkmcnt(4)
	v_mfma_f32_32x32x16_bf16 v[48:63], v[152:155], v[160:163], v[48:63]
	s_add_u32 m0, s31, 0x10000
	v_lshl_add_u64 v[222:223], v[68:69], 0, s[24:25]
	global_load_lds_dwordx4 v[222:223], off
	v_mfma_f32_32x32x16_bf16 v[32:47], v[152:155], v[164:167], v[32:47]
	v_mfma_f32_32x32x16_bf16 v[16:31], v[156:159], v[160:163], v[16:31]
	s_add_u32 m0, s31, 0x12000
	v_lshl_add_u64 v[224:225], v[70:71], 0, s[24:25]
	global_load_lds_dwordx4 v[224:225], off
	v_mfma_f32_32x32x16_bf16 v[0:15], v[156:159], v[164:167], v[0:15]
	ds_read_b128 v[152:155], v186
	ds_read_b128 v[156:159], v186 offset:4096
	ds_read_b128 v[160:163], v219
	ds_read_b128 v[164:167], v219 offset:4096
	s_waitcnt lgkmcnt(4)
	v_mfma_f32_32x32x16_bf16 v[48:63], v[168:171], v[176:179], v[48:63]
	s_add_u32 m0, s31, 0x14000
	v_lshl_add_u64 v[222:223], v[72:73], 0, s[24:25]
	global_load_lds_dwordx4 v[222:223], off
	v_mfma_f32_32x32x16_bf16 v[32:47], v[168:171], v[180:183], v[32:47]
	v_mfma_f32_32x32x16_bf16 v[16:31], v[172:175], v[176:179], v[16:31]
	s_add_u32 m0, s31, 0x16000
	v_lshl_add_u64 v[224:225], v[74:75], 0, s[24:25]
	global_load_lds_dwordx4 v[224:225], off
	v_mfma_f32_32x32x16_bf16 v[0:15], v[172:175], v[180:183], v[0:15]
	ds_read_b128 v[168:171], v187
	ds_read_b128 v[172:175], v187 offset:4096
	ds_read_b128 v[176:179], v220
	ds_read_b128 v[180:183], v220 offset:4096
	s_waitcnt lgkmcnt(4)
	v_mfma_f32_32x32x16_bf16 v[48:63], v[152:155], v[160:163], v[48:63]
	v_mfma_f32_32x32x16_bf16 v[32:47], v[152:155], v[164:167], v[32:47]
	v_mfma_f32_32x32x16_bf16 v[16:31], v[156:159], v[160:163], v[16:31]
	v_mfma_f32_32x32x16_bf16 v[0:15], v[156:159], v[164:167], v[0:15]
	s_waitcnt vmcnt(6) lgkmcnt(0)
	s_barrier
	ds_read_b128 v[152:155], v130
	ds_read_b128 v[156:159], v130 offset:4096
	ds_read_b128 v[160:163], v147
	ds_read_b128 v[164:167], v147 offset:4096
	v_mfma_f32_32x32x16_bf16 v[48:63], v[168:171], v[176:179], v[48:63]
	s_mov_b32 s24, 0x580
	s_add_u32 m0, s31, 0x18000
	v_lshl_add_u64 v[222:223], v[64:65], 0, s[24:25]
	global_load_lds_dwordx4 v[222:223], off
	v_mfma_f32_32x32x16_bf16 v[32:47], v[168:171], v[180:183], v[32:47]
	v_mfma_f32_32x32x16_bf16 v[16:31], v[172:175], v[176:179], v[16:31]
	s_add_u32 m0, s31, 0x1a000
	v_lshl_add_u64 v[224:225], v[66:67], 0, s[24:25]
	global_load_lds_dwordx4 v[224:225], off
	v_mfma_f32_32x32x16_bf16 v[0:15], v[172:175], v[180:183], v[0:15]
	ds_read_b128 v[168:171], v144
	ds_read_b128 v[172:175], v144 offset:4096
	ds_read_b128 v[176:179], v148
	ds_read_b128 v[180:183], v148 offset:4096
	s_waitcnt lgkmcnt(4)
	v_mfma_f32_32x32x16_bf16 v[48:63], v[152:155], v[160:163], v[48:63]
	s_add_u32 m0, s31, 0x1c000
	v_lshl_add_u64 v[222:223], v[68:69], 0, s[24:25]
	global_load_lds_dwordx4 v[222:223], off
	v_mfma_f32_32x32x16_bf16 v[32:47], v[152:155], v[164:167], v[32:47]
	v_mfma_f32_32x32x16_bf16 v[16:31], v[156:159], v[160:163], v[16:31]
	s_add_u32 m0, s31, 0x1e000
	v_lshl_add_u64 v[224:225], v[70:71], 0, s[24:25]
	global_load_lds_dwordx4 v[224:225], off
	v_mfma_f32_32x32x16_bf16 v[0:15], v[156:159], v[164:167], v[0:15]
	ds_read_b128 v[152:155], v145
	ds_read_b128 v[156:159], v145 offset:4096
	ds_read_b128 v[160:163], v149
	ds_read_b128 v[164:167], v149 offset:4096
	s_waitcnt lgkmcnt(4)
	v_mfma_f32_32x32x16_bf16 v[48:63], v[168:171], v[176:179], v[48:63]
	s_add_u32 m0, s31, 0x20000
	v_lshl_add_u64 v[222:223], v[72:73], 0, s[24:25]
	global_load_lds_dwordx4 v[222:223], off
	v_mfma_f32_32x32x16_bf16 v[32:47], v[168:171], v[180:183], v[32:47]
	v_mfma_f32_32x32x16_bf16 v[16:31], v[172:175], v[176:179], v[16:31]
	s_add_u32 m0, s31, 0x22000
	v_lshl_add_u64 v[224:225], v[74:75], 0, s[24:25]
	global_load_lds_dwordx4 v[224:225], off
	v_mfma_f32_32x32x16_bf16 v[0:15], v[172:175], v[180:183], v[0:15]
	ds_read_b128 v[168:171], v146
	ds_read_b128 v[172:175], v146 offset:4096
	ds_read_b128 v[176:179], v150
	ds_read_b128 v[180:183], v150 offset:4096
	s_waitcnt lgkmcnt(4)
	v_mfma_f32_32x32x16_bf16 v[48:63], v[152:155], v[160:163], v[48:63]
	v_mfma_f32_32x32x16_bf16 v[32:47], v[152:155], v[164:167], v[32:47]
	v_mfma_f32_32x32x16_bf16 v[16:31], v[156:159], v[160:163], v[16:31]
	v_mfma_f32_32x32x16_bf16 v[0:15], v[156:159], v[164:167], v[0:15]
	s_waitcnt vmcnt(6) lgkmcnt(0)
	s_barrier
;     ...
;   if (PART != 2) {
;     GEMM_ISSUE(0, 0);
;     if (nk > 1) GEMM_ISSUE(1, 1);
;   }
;   if (PART == 1) return;
;   int st = 0;
;   for (int kt = 0; kt < nk; ++kt) {
;     if (kt + 1 < nk) asm volatile("s_waitcnt vmcnt(6)" ::: "memory");
;     else asm volatile("s_waitcnt vmcnt(0)" ::: "memory");
;     __builtin_amdgcn_s_barrier();
;     asm volatile("" ::: "memory");
;     if (kt + 2 < nk) { const int st2 = (st >= 1) ? st - 1 : 2; GEMM_ISSUE(kt + 2, st2); }
;     const char* la = lds + st * STAGE_B;
;     const char* lb = la + 32768;
;     const unsigned sa_u = (unsigned)(size_t)la + arow_u, sb_u = (unsigned)(size_t)lb + brow_u;
;     const unsigned a0 = sa_u + co0, a1 = sa_u + co1, a2 = sa_u + co2, a3 = sa_u + co3;
;     const unsigned b0 = sb_u + co0, b1 = sb_u + co1, b2 = sb_u + co2, b3 = sb_u + co3;
;     {
;       bf16x8 p0, p1, q0, q1, u0, u1, w0, w1;
;       asm volatile(
;         "ds_read_b128 %4, %12\n\tds_read_b128 %5, %12 offset:4096\n\tds_read_b128 %6, %16\n\tds_read_b128 %7, %16 offset:4096\n\t"
;         "ds_read_b128 %8, %13\n\tds_read_b128 %9, %13 offset:4096\n\tds_read_b128 %10, %17\n\tds_read_b128 %11, %17 offset:4096\n\t"
;         "s_waitcnt lgkmcnt(4)\n\t"
;         "v_mfma_f32_32x32x16_bf16 %0, %4, %6, %0\n\tv_mfma_f32_32x32x16_bf16 %1, %4, %7, %1\n\tv_mfma_f32_32x32x16_bf16 %2, %5, %6, %2\n\tv_mfma_f32_32x32x16_bf16 %3, %5, %7, %3\n\t"
;         "ds_read_b128 %4, %14\n\tds_read_b128 %5, %14 offset:4096\n\tds_read_b128 %6, %18\n\tds_read_b128 %7, %18 offset:4096\n\t"
;         "s_waitcnt lgkmcnt(4)\n\t"
;         "v_mfma_f32_32x32x16_bf16 %0, %8, %10, %0\n\tv_mfma_f32_32x32x16_bf16 %1, %8, %11, %1\n\tv_mfma_f32_32x32x16_bf16 %2, %9, %10, %2\n\tv_mfma_f32_32x32x16_bf16 %3, %9, %11, %3\n\t"
;         "ds_read_b128 %8, %15\n\tds_read_b128 %9, %15 offset:4096\n\tds_read_b128 %10, %19\n\tds_read_b128 %11, %19 offset:4096\n\t"
;         "s_waitcnt lgkmcnt(4)\n\t"
;         "v_mfma_f32_32x32x16_bf16 %0, %4, %6, %0\n\tv_mfma_f32_32x32x16_bf16 %1, %4, %7, %1\n\tv_mfma_f32_32x32x16_bf16 %2, %5, %6, %2\n\tv_mfma_f32_32x32x16_bf16 %3, %5, %7, %3\n\t"
;         "s_waitcnt lgkmcnt(0)\n\t"
;         "v_mfma_f32_32x32x16_bf16 %0, %8, %10, %0\n\tv_mfma_f32_32x32x16_bf16 %1, %8, %11, %1\n\tv_mfma_f32_32x32x16_bf16 %2, %9, %10, %2\n\tv_mfma_f32_32x32x16_bf16 %3, %9, %11, %3"
	ds_read_b128 v[152:155], v130 offset:49152
	ds_read_b128 v[156:159], v130 offset:53248
	ds_read_b128 v[160:163], v147 offset:49152
	ds_read_b128 v[164:167], v147 offset:53248
	v_mfma_f32_32x32x16_bf16 v[48:63], v[168:171], v[176:179], v[48:63]
	s_mov_b32 s24, 0x600
	s_mov_b32 m0, s31
	v_lshl_add_u64 v[222:223], v[64:65], 0, s[24:25]
	global_load_lds_dwordx4 v[222:223], off
	v_mfma_f32_32x32x16_bf16 v[32:47], v[168:171], v[180:183], v[32:47]
	v_mfma_f32_32x32x16_bf16 v[16:31], v[172:175], v[176:179], v[16:31]
	s_add_u32 m0, s31, 0x2000
	v_lshl_add_u64 v[224:225], v[66:67], 0, s[24:25]
	global_load_lds_dwordx4 v[224:225], off
	v_mfma_f32_32x32x16_bf16 v[0:15], v[172:175], v[180:183], v[0:15]
	ds_read_b128 v[168:171], v144 offset:49152
	ds_read_b128 v[172:175], v144 offset:53248
	ds_read_b128 v[176:179], v148 offset:49152
	ds_read_b128 v[180:183], v148 offset:53248
	s_waitcnt lgkmcnt(4)
	v_mfma_f32_32x32x16_bf16 v[48:63], v[152:155], v[160:163], v[48:63]
	s_add_u32 m0, s31, 0x4000
	v_lshl_add_u64 v[222:223], v[68:69], 0, s[24:25]
	global_load_lds_dwordx4 v[222:223], off
	v_mfma_f32_32x32x16_bf16 v[32:47], v[152:155], v[164:167], v[32:47]
	v_mfma_f32_32x32x16_bf16 v[16:31], v[156:159], v[160:163], v[16:31]
	s_add_u32 m0, s31, 0x6000
	v_lshl_add_u64 v[224:225], v[70:71], 0, s[24:25]
	global_load_lds_dwordx4 v[224:225], off
	v_mfma_f32_32x32x16_bf16 v[0:15], v[156:159], v[164:167], v[0:15]
	ds_read_b128 v[152:155], v145 offset:49152
	ds_read_b128 v[156:159], v145 offset:53248
	ds_read_b128 v[160:163], v149 offset:49152
	ds_read_b128 v[164:167], v149 offset:53248
	s_waitcnt lgkmcnt(4)
	v_mfma_f32_32x32x16_bf16 v[48:63], v[168:171], v[176:179], v[48:63]
	s_add_u32 m0, s31, 0x8000
	v_lshl_add_u64 v[222:223], v[72:73], 0, s[24:25]
	global_load_lds_dwordx4 v[222:223], off
	v_mfma_f32_32x32x16_bf16 v[32:47], v[168:171], v[180:183], v[32:47]
	v_mfma_f32_32x32x16_bf16 v[16:31], v[172:175], v[176:179], v[16:31]
	s_add_u32 m0, s31, 0xa000
	v_lshl_add_u64 v[224:225], v[74:75], 0, s[24:25]
	global_load_lds_dwordx4 v[224:225], off
	v_mfma_f32_32x32x16_bf16 v[0:15], v[172:175], v[180:183], v[0:15]
	ds_read_b128 v[168:171], v146 offset:49152
	ds_read_b128 v[172:175], v146 offset:53248
	ds_read_b128 v[176:179], v150 offset:49152
	ds_read_b128 v[180:183], v150 offset:53248
	s_waitcnt lgkmcnt(4)
	v_mfma_f32_32x32x16_bf16 v[48:63], v[152:155], v[160:163], v[48:63]
	v_mfma_f32_32x32x16_bf16 v[32:47], v[152:155], v[164:167], v[32:47]
	v_mfma_f32_32x32x16_bf16 v[16:31], v[156:159], v[160:163], v[16:31]
	v_mfma_f32_32x32x16_bf16 v[0:15], v[156:159], v[164:167], v[0:15]
	s_waitcnt vmcnt(6) lgkmcnt(0)
	s_barrier
	ds_read_b128 v[152:155], v184
	ds_read_b128 v[156:159], v184 offset:4096
	ds_read_b128 v[160:163], v217
	ds_read_b128 v[164:167], v217 offset:4096
	v_mfma_f32_32x32x16_bf16 v[48:63], v[168:171], v[176:179], v[48:63]
	s_mov_b32 s24, 0x680
	s_add_u32 m0, s31, 0xc000
	v_lshl_add_u64 v[222:223], v[64:65], 0, s[24:25]
	global_load_lds_dwordx4 v[222:223], off
	v_mfma_f32_32x32x16_bf16 v[32:47], v[168:171], v[180:183], v[32:47]
	v_mfma_f32_32x32x16_bf16 v[16:31], v[172:175], v[176:179], v[16:31]
	s_add_u32 m0, s31, 0xe000
	v_lshl_add_u64 v[224:225], v[66:67], 0, s[24:25]
	global_load_lds_dwordx4 v[224:225], off
	v_mfma_f32_32x32x16_bf16 v[0:15], v[172:175], v[180:183], v[0:15]
	ds_read_b128 v[168:171], v185
	ds_read_b128 v[172:175], v185 offset:4096
	ds_read_b128 v[176:179], v218
	ds_read_b128 v[180:183], v218 offset:4096
	s_waitcnt lgkmcnt(4)
	v_mfma_f32_32x32x16_bf16 v[48:63], v[152:155], v[160:163], v[48:63]
	s_add_u32 m0, s31, 0x10000
	v_lshl_add_u64 v[222:223], v[68:69], 0, s[24:25]
	global_load_lds_dwordx4 v[222:223], off
	v_mfma_f32_32x32x16_bf16 v[32:47], v[152:155], v[164:167], v[32:47]
	v_mfma_f32_32x32x16_bf16 v[16:31], v[156:159], v[160:163], v[16:31]
	s_add_u32 m0, s31, 0x12000
	v_lshl_add_u64 v[224:225], v[70:71], 0, s[24:25]
	global_load_lds_dwordx4 v[224:225], off
	v_mfma_f32_32x32x16_bf16 v[0:15], v[156:159], v[164:167], v[0:15]
	ds_read_b128 v[152:155], v186
	ds_read_b128 v[156:159], v186 offset:4096
	ds_read_b128 v[160:163], v219
	ds_read_b128 v[164:167], v219 offset:4096
	s_waitcnt lgkmcnt(4)
	v_mfma_f32_32x32x16_bf16 v[48:63], v[168:171], v[176:179], v[48:63]
	s_add_u32 m0, s31, 0x14000
	v_lshl_add_u64 v[222:223], v[72:73], 0, s[24:25]
	global_load_lds_dwordx4 v[222:223], off
	v_mfma_f32_32x32x16_bf16 v[32:47], v[168:171], v[180:183], v[32:47]
	v_mfma_f32_32x32x16_bf16 v[16:31], v[172:175], v[176:179], v[16:31]
	s_add_u32 m0, s31, 0x16000
	v_lshl_add_u64 v[224:225], v[74:75], 0, s[24:25]
	global_load_lds_dwordx4 v[224:225], off
	v_mfma_f32_32x32x16_bf16 v[0:15], v[172:175], v[180:183], v[0:15]
	ds_read_b128 v[168:171], v187
	ds_read_b128 v[172:175], v187 offset:4096
	ds_read_b128 v[176:179], v220
	ds_read_b128 v[180:183], v220 offset:4096
	s_waitcnt lgkmcnt(4)
	v_mfma_f32_32x32x16_bf16 v[48:63], v[152:155], v[160:163], v[48:63]
	v_mfma_f32_32x32x16_bf16 v[32:47], v[152:155], v[164:167], v[32:47]
	v_mfma_f32_32x32x16_bf16 v[16:31], v[156:159], v[160:163], v[16:31]
	v_mfma_f32_32x32x16_bf16 v[0:15], v[156:159], v[164:167], v[0:15]
	s_waitcnt vmcnt(6) lgkmcnt(0)
	s_barrier
;     ...
;   if (PART != 2) {
;     GEMM_ISSUE(0, 0);
;     if (nk > 1) GEMM_ISSUE(1, 1);
;   }
;   if (PART == 1) return;
;   int st = 0;
;   for (int kt = 0; kt < nk; ++kt) {
;     if (kt + 1 < nk) asm volatile("s_waitcnt vmcnt(6)" ::: "memory");
;     else asm volatile("s_waitcnt vmcnt(0)" ::: "memory");
;     __builtin_amdgcn_s_barrier();
;     asm volatile("" ::: "memory");
;     if (kt + 2 < nk) { const int st2 = (st >= 1) ? st - 1 : 2; GEMM_ISSUE(kt + 2, st2); }
;     const char* la = lds + st * STAGE_B;
;     const char* lb = la + 32768;
;     const unsigned sa_u = (unsigned)(size_t)la + arow_u, sb_u = (unsigned)(size_t)lb + brow_u;
;     const unsigned a0 = sa_u + co0, a1 = sa_u + co1, a2 = sa_u + co2, a3 = sa_u + co3;
;     const unsigned b0 = sb_u + co0, b1 = sb_u + co1, b2 = sb_u + co2, b3 = sb_u + co3;
;     {
;       bf16x8 p0, p1, q0, q1, u0, u1, w0, w1;
;       asm volatile(
;         "ds_read_b128 %4, %12\n\tds_read_b128 %5, %12 offset:4096\n\tds_read_b128 %6, %16\n\tds_read_b128 %7, %16 offset:4096\n\t"
;         "ds_read_b128 %8, %13\n\tds_read_b128 %9, %13 offset:4096\n\tds_read_b128 %10, %17\n\tds_read_b128 %11, %17 offset:4096\n\t"
;         "s_waitcnt lgkmcnt(4)\n\t"
;         "v_mfma_f32_32x32x16_bf16 %0, %4, %6, %0\n\tv_mfma_f32_32x32x16_bf16 %1, %4, %7, %1\n\tv_mfma_f32_32x32x16_bf16 %2, %5, %6, %2\n\tv_mfma_f32_32x32x16_bf16 %3, %5, %7, %3\n\t"
;         "ds_read_b128 %4, %14\n\tds_read_b128 %5, %14 offset:4096\n\tds_read_b128 %6, %18\n\tds_read_b128 %7, %18 offset:4096\n\t"
;         "s_waitcnt lgkmcnt(4)\n\t"
;         "v_mfma_f32_32x32x16_bf16 %0, %8, %10, %0\n\tv_mfma_f32_32x32x16_bf16 %1, %8, %11, %1\n\tv_mfma_f32_32x32x16_bf16 %2, %9, %10, %2\n\tv_mfma_f32_32x32x16_bf16 %3, %9, %11, %3\n\t"
;         "ds_read_b128 %8, %15\n\tds_read_b128 %9, %15 offset:4096\n\tds_read_b128 %10, %19\n\tds_read_b128 %11, %19 offset:4096\n\t"
;         "s_waitcnt lgkmcnt(4)\n\t"
;         "v_mfma_f32_32x32x16_bf16 %0, %4, %6, %0\n\tv_mfma_f32_32x32x16_bf16 %1, %4, %7, %1\n\tv_mfma_f32_32x32x16_bf16 %2, %5, %6, %2\n\tv_mfma_f32_32x32x16_bf16 %3, %5, %7, %3\n\t"
;         "s_waitcnt lgkmcnt(0)\n\t"
;         "v_mfma_f32_32x32x16_bf16 %0, %8, %10, %0\n\tv_mfma_f32_32x32x16_bf16 %1, %8, %11, %1\n\tv_mfma_f32_32x32x16_bf16 %2, %9, %10, %2\n\tv_mfma_f32_32x32x16_bf16 %3, %9, %11, %3"
	ds_read_b128 v[152:155], v130
	ds_read_b128 v[156:159], v130 offset:4096
	ds_read_b128 v[160:163], v147
	ds_read_b128 v[164:167], v147 offset:4096
	v_mfma_f32_32x32x16_bf16 v[48:63], v[168:171], v[176:179], v[48:63]
	s_mov_b32 s24, 0x700
	s_add_u32 m0, s31, 0x18000
	v_lshl_add_u64 v[222:223], v[64:65], 0, s[24:25]
	global_load_lds_dwordx4 v[222:223], off
	v_mfma_f32_32x32x16_bf16 v[32:47], v[168:171], v[180:183], v[32:47]
	v_mfma_f32_32x32x16_bf16 v[16:31], v[172:175], v[176:179], v[16:31]
	s_add_u32 m0, s31, 0x1a000
	v_lshl_add_u64 v[224:225], v[66:67], 0, s[24:25]
	global_load_lds_dwordx4 v[224:225], off
	v_mfma_f32_32x32x16_bf16 v[0:15], v[172:175], v[180:183], v[0:15]
	ds_read_b128 v[168:171], v144
	ds_read_b128 v[172:175], v144 offset:4096
	ds_read_b128 v[176:179], v148
	ds_read_b128 v[180:183], v148 offset:4096
	s_waitcnt lgkmcnt(4)
	v_mfma_f32_32x32x16_bf16 v[48:63], v[152:155], v[160:163], v[48:63]
	s_add_u32 m0, s31, 0x1c000
	v_lshl_add_u64 v[222:223], v[68:69], 0, s[24:25]
	global_load_lds_dwordx4 v[222:223], off
	v_mfma_f32_32x32x16_bf16 v[32:47], v[152:155], v[164:167], v[32:47]
	v_mfma_f32_32x32x16_bf16 v[16:31], v[156:159], v[160:163], v[16:31]
	s_add_u32 m0, s31, 0x1e000
	v_lshl_add_u64 v[224:225], v[70:71], 0, s[24:25]
	global_load_lds_dwordx4 v[224:225], off
	v_mfma_f32_32x32x16_bf16 v[0:15], v[156:159], v[164:167], v[0:15]
	ds_read_b128 v[152:155], v145
	ds_read_b128 v[156:159], v145 offset:4096
	ds_read_b128 v[160:163], v149
	ds_read_b128 v[164:167], v149 offset:4096
	s_waitcnt lgkmcnt(4)
	v_mfma_f32_32x32x16_bf16 v[48:63], v[168:171], v[176:179], v[48:63]
	s_add_u32 m0, s31, 0x20000
	v_lshl_add_u64 v[222:223], v[72:73], 0, s[24:25]
	global_load_lds_dwordx4 v[222:223], off
	v_mfma_f32_32x32x16_bf16 v[32:47], v[168:171], v[180:183], v[32:47]
	v_mfma_f32_32x32x16_bf16 v[16:31], v[172:175], v[176:179], v[16:31]
	s_add_u32 m0, s31, 0x22000
	v_lshl_add_u64 v[224:225], v[74:75], 0, s[24:25]
	global_load_lds_dwordx4 v[224:225], off
	v_mfma_f32_32x32x16_bf16 v[0:15], v[172:175], v[180:183], v[0:15]
	ds_read_b128 v[168:171], v146
	ds_read_b128 v[172:175], v146 offset:4096
	ds_read_b128 v[176:179], v150
	ds_read_b128 v[180:183], v150 offset:4096
	s_waitcnt lgkmcnt(4)
	v_mfma_f32_32x32x16_bf16 v[48:63], v[152:155], v[160:163], v[48:63]
	v_mfma_f32_32x32x16_bf16 v[32:47], v[152:155], v[164:167], v[32:47]
	v_mfma_f32_32x32x16_bf16 v[16:31], v[156:159], v[160:163], v[16:31]
	v_mfma_f32_32x32x16_bf16 v[0:15], v[156:159], v[164:167], v[0:15]
	s_waitcnt vmcnt(6) lgkmcnt(0)
	s_barrier
	ds_read_b128 v[152:155], v130 offset:49152
	ds_read_b128 v[156:159], v130 offset:53248
	ds_read_b128 v[160:163], v147 offset:49152
	ds_read_b128 v[164:167], v147 offset:53248
	v_mfma_f32_32x32x16_bf16 v[48:63], v[168:171], v[176:179], v[48:63]
	s_mov_b32 s24, 0x780
	s_mov_b32 m0, s31
	v_lshl_add_u64 v[222:223], v[64:65], 0, s[24:25]
	global_load_lds_dwordx4 v[222:223], off
	v_mfma_f32_32x32x16_bf16 v[32:47], v[168:171], v[180:183], v[32:47]
	v_mfma_f32_32x32x16_bf16 v[16:31], v[172:175], v[176:179], v[16:31]
	s_add_u32 m0, s31, 0x2000
	v_lshl_add_u64 v[224:225], v[66:67], 0, s[24:25]
	global_load_lds_dwordx4 v[224:225], off
	v_mfma_f32_32x32x16_bf16 v[0:15], v[172:175], v[180:183], v[0:15]
	ds_read_b128 v[168:171], v144 offset:49152
	ds_read_b128 v[172:175], v144 offset:53248
	ds_read_b128 v[176:179], v148 offset:49152
	ds_read_b128 v[180:183], v148 offset:53248
	s_waitcnt lgkmcnt(4)
	v_mfma_f32_32x32x16_bf16 v[48:63], v[152:155], v[160:163], v[48:63]
	s_add_u32 m0, s31, 0x4000
	v_lshl_add_u64 v[222:223], v[68:69], 0, s[24:25]
	global_load_lds_dwordx4 v[222:223], off
	v_mfma_f32_32x32x16_bf16 v[32:47], v[152:155], v[164:167], v[32:47]
	v_mfma_f32_32x32x16_bf16 v[16:31], v[156:159], v[160:163], v[16:31]
	s_add_u32 m0, s31, 0x6000
	v_lshl_add_u64 v[224:225], v[70:71], 0, s[24:25]
	global_load_lds_dwordx4 v[224:225], off
	v_mfma_f32_32x32x16_bf16 v[0:15], v[156:159], v[164:167], v[0:15]
	ds_read_b128 v[152:155], v145 offset:49152
	ds_read_b128 v[156:159], v145 offset:53248
	ds_read_b128 v[160:163], v149 offset:49152
	ds_read_b128 v[164:167], v149 offset:53248
	s_waitcnt lgkmcnt(4)
	v_mfma_f32_32x32x16_bf16 v[48:63], v[168:171], v[176:179], v[48:63]
	s_add_u32 m0, s31, 0x8000
	v_lshl_add_u64 v[222:223], v[72:73], 0, s[24:25]
	global_load_lds_dwordx4 v[222:223], off
	v_mfma_f32_32x32x16_bf16 v[32:47], v[168:171], v[180:183], v[32:47]
	v_mfma_f32_32x32x16_bf16 v[16:31], v[172:175], v[176:179], v[16:31]
	s_add_u32 m0, s31, 0xa000
	v_lshl_add_u64 v[224:225], v[74:75], 0, s[24:25]
	global_load_lds_dwordx4 v[224:225], off
	v_mfma_f32_32x32x16_bf16 v[0:15], v[172:175], v[180:183], v[0:15]
	ds_read_b128 v[168:171], v146 offset:49152
	ds_read_b128 v[172:175], v146 offset:53248
	ds_read_b128 v[176:179], v150 offset:49152
	ds_read_b128 v[180:183], v150 offset:53248
	s_waitcnt lgkmcnt(4)
	v_mfma_f32_32x32x16_bf16 v[48:63], v[152:155], v[160:163], v[48:63]
	v_mfma_f32_32x32x16_bf16 v[32:47], v[152:155], v[164:167], v[32:47]
	v_mfma_f32_32x32x16_bf16 v[16:31], v[156:159], v[160:163], v[16:31]
	v_mfma_f32_32x32x16_bf16 v[0:15], v[156:159], v[164:167], v[0:15]
	s_waitcnt vmcnt(6) lgkmcnt(0)
	s_barrier
;     ...
;   if (PART != 2) {
;     GEMM_ISSUE(0, 0);
;     if (nk > 1) GEMM_ISSUE(1, 1);
;   }
;   if (PART == 1) return;
;   int st = 0;
;   for (int kt = 0; kt < nk; ++kt) {
;     if (kt + 1 < nk) asm volatile("s_waitcnt vmcnt(6)" ::: "memory");
;     else asm volatile("s_waitcnt vmcnt(0)" ::: "memory");
;     __builtin_amdgcn_s_barrier();
;     asm volatile("" ::: "memory");
;     if (kt + 2 < nk) { const int st2 = (st >= 1) ? st - 1 : 2; GEMM_ISSUE(kt + 2, st2); }
;     const char* la = lds + st * STAGE_B;
;     const char* lb = la + 32768;
;     const unsigned sa_u = (unsigned)(size_t)la + arow_u, sb_u = (unsigned)(size_t)lb + brow_u;
;     const unsigned a0 = sa_u + co0, a1 = sa_u + co1, a2 = sa_u + co2, a3 = sa_u + co3;
;     const unsigned b0 = sb_u + co0, b1 = sb_u + co1, b2 = sb_u + co2, b3 = sb_u + co3;
;     {
;       bf16x8 p0, p1, q0, q1, u0, u1, w0, w1;
;       asm volatile(
;         "ds_read_b128 %4, %12\n\tds_read_b128 %5, %12 offset:4096\n\tds_read_b128 %6, %16\n\tds_read_b128 %7, %16 offset:4096\n\t"
;         "ds_read_b128 %8, %13\n\tds_read_b128 %9, %13 offset:4096\n\tds_read_b128 %10, %17\n\tds_read_b128 %11, %17 offset:4096\n\t"
;         "s_waitcnt lgkmcnt(4)\n\t"
;         "v_mfma_f32_32x32x16_bf16 %0, %4, %6, %0\n\tv_mfma_f32_32x32x16_bf16 %1, %4, %7, %1\n\tv_mfma_f32_32x32x16_bf16 %2, %5, %6, %2\n\tv_mfma_f32_32x32x16_bf16 %3, %5, %7, %3\n\t"
;         "ds_read_b128 %4, %14\n\tds_read_b128 %5, %14 offset:4096\n\tds_read_b128 %6, %18\n\tds_read_b128 %7, %18 offset:4096\n\t"
;         "s_waitcnt lgkmcnt(4)\n\t"
;         "v_mfma_f32_32x32x16_bf16 %0, %8, %10, %0\n\tv_mfma_f32_32x32x16_bf16 %1, %8, %11, %1\n\tv_mfma_f32_32x32x16_bf16 %2, %9, %10, %2\n\tv_mfma_f32_32x32x16_bf16 %3, %9, %11, %3\n\t"
;         "ds_read_b128 %8, %15\n\tds_read_b128 %9, %15 offset:4096\n\tds_read_b128 %10, %19\n\tds_read_b128 %11, %19 offset:4096\n\t"
;         "s_waitcnt lgkmcnt(4)\n\t"
;         "v_mfma_f32_32x32x16_bf16 %0, %4, %6, %0\n\tv_mfma_f32_32x32x16_bf16 %1, %4, %7, %1\n\tv_mfma_f32_32x32x16_bf16 %2, %5, %6, %2\n\tv_mfma_f32_32x32x16_bf16 %3, %5, %7, %3\n\t"
;         "s_waitcnt lgkmcnt(0)\n\t"
;         "v_mfma_f32_32x32x16_bf16 %0, %8, %10, %0\n\tv_mfma_f32_32x32x16_bf16 %1, %8, %11, %1\n\tv_mfma_f32_32x32x16_bf16 %2, %9, %10, %2\n\tv_mfma_f32_32x32x16_bf16 %3, %9, %11, %3"
	ds_read_b128 v[152:155], v184
	ds_read_b128 v[156:159], v184 offset:4096
	ds_read_b128 v[160:163], v217
	ds_read_b128 v[164:167], v217 offset:4096
	v_mfma_f32_32x32x16_bf16 v[48:63], v[168:171], v[176:179], v[48:63]
	v_mfma_f32_32x32x16_bf16 v[32:47], v[168:171], v[180:183], v[32:47]
	v_mfma_f32_32x32x16_bf16 v[16:31], v[172:175], v[176:179], v[16:31]
	v_mfma_f32_32x32x16_bf16 v[0:15], v[172:175], v[180:183], v[0:15]
	ds_read_b128 v[168:171], v185
	ds_read_b128 v[172:175], v185 offset:4096
	ds_read_b128 v[176:179], v218
	ds_read_b128 v[180:183], v218 offset:4096
	s_waitcnt lgkmcnt(4)
	v_mfma_f32_32x32x16_bf16 v[48:63], v[152:155], v[160:163], v[48:63]
	v_mfma_f32_32x32x16_bf16 v[32:47], v[152:155], v[164:167], v[32:47]
	v_mfma_f32_32x32x16_bf16 v[16:31], v[156:159], v[160:163], v[16:31]
	v_mfma_f32_32x32x16_bf16 v[0:15], v[156:159], v[164:167], v[0:15]
	ds_read_b128 v[152:155], v186
	ds_read_b128 v[156:159], v186 offset:4096
	ds_read_b128 v[160:163], v219
	ds_read_b128 v[164:167], v219 offset:4096
	s_waitcnt lgkmcnt(4)
	v_mfma_f32_32x32x16_bf16 v[48:63], v[168:171], v[176:179], v[48:63]
	v_mfma_f32_32x32x16_bf16 v[32:47], v[168:171], v[180:183], v[32:47]
	v_mfma_f32_32x32x16_bf16 v[16:31], v[172:175], v[176:179], v[16:31]
	v_mfma_f32_32x32x16_bf16 v[0:15], v[172:175], v[180:183], v[0:15]
	ds_read_b128 v[168:171], v187
	ds_read_b128 v[172:175], v187 offset:4096
	ds_read_b128 v[176:179], v220
	ds_read_b128 v[180:183], v220 offset:4096
	s_waitcnt lgkmcnt(4)
	v_mfma_f32_32x32x16_bf16 v[48:63], v[152:155], v[160:163], v[48:63]
	v_mfma_f32_32x32x16_bf16 v[32:47], v[152:155], v[164:167], v[32:47]
	v_mfma_f32_32x32x16_bf16 v[16:31], v[156:159], v[160:163], v[16:31]
	v_mfma_f32_32x32x16_bf16 v[0:15], v[156:159], v[164:167], v[0:15]
	s_waitcnt vmcnt(0) lgkmcnt(0)
	s_barrier
	ds_read_b128 v[152:155], v130
	ds_read_b128 v[156:159], v130 offset:4096
	ds_read_b128 v[160:163], v147
	ds_read_b128 v[164:167], v147 offset:4096
	v_mfma_f32_32x32x16_bf16 v[48:63], v[168:171], v[176:179], v[48:63]
	v_mfma_f32_32x32x16_bf16 v[32:47], v[168:171], v[180:183], v[32:47]
	v_mfma_f32_32x32x16_bf16 v[16:31], v[172:175], v[176:179], v[16:31]
	v_mfma_f32_32x32x16_bf16 v[0:15], v[172:175], v[180:183], v[0:15]
	ds_read_b128 v[168:171], v144
	ds_read_b128 v[172:175], v144 offset:4096
	ds_read_b128 v[176:179], v148
	ds_read_b128 v[180:183], v148 offset:4096
	s_waitcnt lgkmcnt(4)
	v_mfma_f32_32x32x16_bf16 v[48:63], v[152:155], v[160:163], v[48:63]
	v_mfma_f32_32x32x16_bf16 v[32:47], v[152:155], v[164:167], v[32:47]
	v_mfma_f32_32x32x16_bf16 v[16:31], v[156:159], v[160:163], v[16:31]
	v_mfma_f32_32x32x16_bf16 v[0:15], v[156:159], v[164:167], v[0:15]
	ds_read_b128 v[152:155], v145
	ds_read_b128 v[156:159], v145 offset:4096
	ds_read_b128 v[160:163], v149
	ds_read_b128 v[164:167], v149 offset:4096
	s_waitcnt lgkmcnt(4)
	v_mfma_f32_32x32x16_bf16 v[48:63], v[168:171], v[176:179], v[48:63]
	v_mfma_f32_32x32x16_bf16 v[32:47], v[168:171], v[180:183], v[32:47]
	v_mfma_f32_32x32x16_bf16 v[16:31], v[172:175], v[176:179], v[16:31]
	v_mfma_f32_32x32x16_bf16 v[0:15], v[172:175], v[180:183], v[0:15]
	ds_read_b128 v[168:171], v146
	ds_read_b128 v[172:175], v146 offset:4096
	ds_read_b128 v[176:179], v150
	ds_read_b128 v[180:183], v150 offset:4096
	s_waitcnt lgkmcnt(4)
	v_mfma_f32_32x32x16_bf16 v[48:63], v[152:155], v[160:163], v[48:63]
	v_mfma_f32_32x32x16_bf16 v[32:47], v[152:155], v[164:167], v[32:47]
	v_mfma_f32_32x32x16_bf16 v[16:31], v[156:159], v[160:163], v[16:31]
	v_mfma_f32_32x32x16_bf16 v[0:15], v[156:159], v[164:167], v[0:15]
	s_waitcnt lgkmcnt(0)
	v_mfma_f32_32x32x16_bf16 v[48:63], v[168:171], v[176:179], v[48:63]
	v_mfma_f32_32x32x16_bf16 v[32:47], v[168:171], v[180:183], v[32:47]
	v_mfma_f32_32x32x16_bf16 v[16:31], v[172:175], v[176:179], v[16:31]
	v_mfma_f32_32x32x16_bf16 v[0:15], v[172:175], v[180:183], v[0:15]
	s_mov_b32 s53, 0x8000
	s_nop 15
	s_nop 15
	s_nop 7
	s_barrier
	s_load_dword s9, s[0:1], 0x10
	s_waitcnt lgkmcnt(0)
	s_lshr_b32 s9, s9, 16
	s_cmp_lg_u32 s9, 0
	s_cselect_b64 s[30:31], -1, 0
	s_cmp_lg_u64 s[30:31], 0
	s_addc_u32 s9, s33, 0
	s_cmp_lg_u64 s[30:31], 0
	s_addc_u32 s10, s10, s33
	s_cmpk_gt_i32 s10, 0x3ff
	s_cbranch_scc0 .LBB0_86

;   const int tid = TIDX, lane = tid & 63, wid = tid >> 6, wr = wid >> 1, wc = wid & 1, r = lane & 31, h = lane >> 5;
;   const int ch = (tid & 7) ^ ((tid >> 4) & 7);
;   unsigned avo[4], bvo[2];
; #pragma unroll
;   for (int i = 0; i < 4; ++i) avo[i] = (unsigned)(((tid >> 3) + 64 * i) * lda * 2 + ch * 16);
; #pragma unroll
;   for (int i = 0; i < 2; ++i) bvo[i] = (unsigned)(((tid >> 3) + 64 * i) * ldb * 2 + ch * 16);
;   const char* Ab = (const char*)A; const char* Bb = (const char*)Bt;
;   char* lw = lds + tid * 16;
;   const int nk = K >> 6;
;   const unsigned swz = (unsigned)((r >> 1) & 7);
;   const unsigned arow_u = (unsigned)((wr * 64 + r) * 128), brow_u = (unsigned)((wc * 64 + r) * 128);
;   const unsigned co0 = ((0u + h) ^ swz) << 4, co1 = ((2u + h) ^ swz) << 4, co2 = ((4u + h) ^ swz) << 4, co3 = ((6u + h) ^ swz) << 4;
;     ...
;   if (PART != 2) {
;     GEMM_ISSUE(0, 0);
;     if (nk > 1) GEMM_ISSUE(1, 1);
;   }
;   if (PART == 1) return;
;   int st = 0;
;   for (int kt = 0; kt < nk; ++kt) {
;     if (kt + 1 < nk) asm volatile("s_waitcnt vmcnt(6)" ::: "memory");
;     else asm volatile("s_waitcnt vmcnt(0)" ::: "memory");
;     __builtin_amdgcn_s_barrier();
;     asm volatile("" ::: "memory");
;     if (kt + 2 < nk) { const int st2 = (st >= 1) ? st - 1 : 2; GEMM_ISSUE(kt + 2, st2); }
;     const char* la = lds + st * STAGE_B;
;     const char* lb = la + 32768;
;     const unsigned sa_u = (unsigned)(size_t)la + arow_u, sb_u = (unsigned)(size_t)lb + brow_u;
;     const unsigned a0 = sa_u + co0, a1 = sa_u + co1, a2 = sa_u + co2, a3 = sa_u + co3;
;     const unsigned b0 = sb_u + co0, b1 = sb_u + co1, b2 = sb_u + co2, b3 = sb_u + co3;
;     {
;       bf16x8 p0, p1, q0, q1, u0, u1, w0, w1;
;       asm volatile(
;         "ds_read_b128 %4, %12\n\tds_read_b128 %5, %12 offset:4096\n\tds_read_b128 %6, %16\n\tds_read_b128 %7, %16 offset:4096\n\t"
;         "ds_read_b128 %8, %13\n\tds_read_b128 %9, %13 offset:4096\n\tds_read_b128 %10, %17\n\tds_read_b128 %11, %17 offset:4096\n\t"
;         "s_waitcnt lgkmcnt(4)\n\t"
;         "v_mfma_f32_32x32x16_bf16 %0, %4, %6, %0\n\tv_mfma_f32_32x32x16_bf16 %1, %4, %7, %1\n\tv_mfma_f32_32x32x16_bf16 %2, %5, %6, %2\n\tv_mfma_f32_32x32x16_bf16 %3, %5, %7, %3\n\t"
;         "ds_read_b128 %4, %14\n\tds_read_b128 %5, %14 offset:4096\n\tds_read_b128 %6, %18\n\tds_read_b128 %7, %18 offset:4096\n\t"
;         "s_waitcnt lgkmcnt(4)\n\t"
.LBB0_220:
	v_mov_b32_e32 v1, v129
	s_ashr_i32 s9, s8, 31
	v_lshlrev_b32_e32 v5, 4, v1
	v_lshrrev_b32_e32 v3, 5, v1
	v_xor_b32_e32 v0, v5, v1
	v_lshlrev_b32_e32 v2, 8, v1
	v_and_b32_e32 v6, 31, v1
	v_bfe_u32 v7, v1, 5, 1
	v_add_u32_e32 v116, 0, v5
	v_lshrrev_b32_e32 v5, 1, v1
	v_bfe_u32 v8, v1, 1, 3
	v_lshlrev_b32_e32 v1, 7, v1
	v_and_b32_e32 v118, 0x2f80, v1
	v_bitop3_b32 v1, v3, v8, 1 bitop3:0x6c
	s_lshl_b64 s[26:27], s[8:9], 19
	v_lshlrev_b32_e32 v119, 4, v1
	v_bitop3_b32 v1, v7, v8, 2 bitop3:0x36
	s_add_u32 s26, s88, s26
	v_and_b32_e32 v2, 0xfffff800, v2
	s_movk_i32 s9, 0x70
	v_lshlrev_b32_e32 v120, 4, v1
	v_bitop3_b32 v1, v7, v8, 4 bitop3:0x36
	s_addc_u32 s27, s89, s27
	v_and_or_b32 v130, v0, s9, v2
	s_mov_b32 s9, 0x1ffffc0
	v_lshlrev_b32_e32 v121, 4, v1
	v_bitop3_b32 v1, v7, v8, 6 bitop3:0x36
	v_add_u32_e32 v8, 0x18000, v116
	v_add_u32_e32 v0, 0x20000, v130
	v_and_or_b32 v5, v5, s9, v6
	v_lshlrev_b32_e32 v122, 4, v1
	v_mov_b32_e32 v1, v131
	v_lshl_add_u64 v[64:65], s[26:27], 0, v[130:131]
	v_readfirstlane_b32 s9, v8
	v_add_u32_e32 v8, 0x1a000, v116
	s_waitcnt vmcnt(6)
	s_barrier
	v_lshl_add_u64 v[6:7], v[64:65], 0, s[78:79]
	s_mov_b32 m0, s9
	v_lshl_add_u64 v[66:67], s[26:27], 0, v[0:1]
	v_readfirstlane_b32 s11, v8
	s_ashr_i32 s15, s14, 31
	global_load_lds_dwordx4 v[6:7], off
	v_lshl_add_u64 v[6:7], v[66:67], 0, s[78:79]
	s_mov_b32 m0, s11
	s_lshl_b64 s[30:31], s[14:15], 18
	v_add_u32_e32 v2, 0x40000, v130
	v_add_u32_e32 v4, 0x60000, v130
	v_lshlrev_b32_e32 v117, 7, v5
	v_mov_b32_e32 v3, v131
	v_mov_b32_e32 v5, v131
	global_load_lds_dwordx4 v[6:7], off
	v_add_u32_e32 v6, 0x1c000, v116
	s_add_u32 s30, s70, s30
	v_lshl_add_u64 v[68:69], s[26:27], 0, v[2:3]
	v_readfirstlane_b32 s15, v6
	v_lshl_add_u64 v[70:71], s[26:27], 0, v[4:5]
	v_add_u32_e32 v4, 0x1e000, v116
	s_addc_u32 s31, s71, s31
	v_lshl_add_u64 v[2:3], v[68:69], 0, s[78:79]
	s_mov_b32 m0, s15
	v_readfirstlane_b32 s26, v4
	v_add_u32_e32 v4, 0x20000, v116
	global_load_lds_dwordx4 v[2:3], off
	v_lshl_add_u64 v[2:3], v[70:71], 0, s[78:79]
	s_mov_b32 m0, s26
	v_lshl_add_u64 v[72:73], s[30:31], 0, v[130:131]
	v_readfirstlane_b32 s27, v4
	global_load_lds_dwordx4 v[2:3], off
	v_lshl_add_u64 v[2:3], v[72:73], 0, s[78:79]
	s_mov_b32 m0, s27
	v_lshl_add_u64 v[74:75], s[30:31], 0, v[0:1]
	global_load_lds_dwordx4 v[2:3], off
	v_add_u32_e32 v2, 0x22000, v116
	s_cmp_lg_u32 0, -1
	v_readfirstlane_b32 s30, v2
	v_lshl_add_u64 v[0:1], v[74:75], 0, s[78:79]
	s_mov_b32 m0, s30
	s_cselect_b32 s31, 0, 0
	global_load_lds_dwordx4 v[0:1], off
	v_add_u32_e32 v0, s31, v117
	s_add_i32 s31, s31, 0x8000
	s_mov_b32 s53, s52
	v_add_u32_e32 v1, s31, v118
	s_mov_b32 s54, s52
	s_mov_b32 s55, s52
	s_mov_b32 s56, s52
	s_mov_b32 s57, s52
	s_mov_b32 s58, s52
	s_mov_b32 s59, s52
	s_mov_b32 s60, s52
	s_mov_b32 s61, s52
	s_mov_b32 s62, s52
	s_mov_b32 s63, s52
	s_mov_b32 s64, s52
	s_mov_b32 s65, s52
	s_mov_b32 s66, s52
	s_mov_b32 s67, s52
	v_mov_b64_e32 v[48:49], s[52:53]
	v_add_u32_e32 v76, v0, v119
	v_add_u32_e32 v77, v0, v120
	v_add_u32_e32 v78, v0, v121
	v_add_u32_e32 v79, v0, v122
	v_add_u32_e32 v80, v119, v1
	v_add_u32_e32 v81, v120, v1
	v_add_u32_e32 v82, v121, v1
	v_add_u32_e32 v83, v122, v1
	v_mov_b64_e32 v[50:51], s[54:55]
	v_mov_b64_e32 v[52:53], s[56:57]
	v_mov_b64_e32 v[54:55], s[58:59]
	v_mov_b64_e32 v[56:57], s[60:61]
	v_mov_b64_e32 v[58:59], s[62:63]
	v_mov_b64_e32 v[60:61], s[64:65]
	v_mov_b64_e32 v[62:63], s[66:67]
	v_mov_b64_e32 v[32:33], v[48:49]
	v_mov_b64_e32 v[16:17], v[48:49]
	v_mov_b64_e32 v[0:1], v[48:49]
	v_mov_b64_e32 v[34:35], v[50:51]
	v_mov_b64_e32 v[36:37], v[52:53]
	v_mov_b64_e32 v[38:39], v[54:55]
	v_mov_b64_e32 v[40:41], v[56:57]
	v_mov_b64_e32 v[42:43], v[58:59]
	v_mov_b64_e32 v[44:45], v[60:61]
	v_mov_b64_e32 v[46:47], v[62:63]
	v_mov_b64_e32 v[18:19], v[50:51]
	v_mov_b64_e32 v[20:21], v[52:53]
	v_mov_b64_e32 v[22:23], v[54:55]
	v_mov_b64_e32 v[24:25], v[56:57]
	v_mov_b64_e32 v[26:27], v[58:59]
	v_mov_b64_e32 v[28:29], v[60:61]
	v_mov_b64_e32 v[30:31], v[62:63]
	v_mov_b64_e32 v[2:3], v[50:51]
	v_mov_b64_e32 v[4:5], v[52:53]
	v_mov_b64_e32 v[6:7], v[54:55]
	v_mov_b64_e32 v[8:9], v[56:57]
	v_mov_b64_e32 v[10:11], v[58:59]
	v_mov_b64_e32 v[12:13], v[60:61]
	v_mov_b64_e32 v[14:15], v[62:63]
	v_and_b32_e32 v84, 31, v129
	v_bfe_u32 v85, v129, 5, 1
	v_lshrrev_b32_e32 v86, 6, v129
	v_bfe_u32 v88, v129, 1, 3
	v_lshrrev_b32_e32 v87, 1, v86
	v_and_b32_e32 v86, 1, v86
	v_xor_b32_e32 v85, v85, v88
	v_lshl_add_u32 v87, v87, 6, v84
	v_lshl_add_u32 v86, v86, 6, v84
	v_lshlrev_b32_e32 v85, 4, v85
	v_lshlrev_b32_e32 v87, 7, v87
	v_lshlrev_b32_e32 v86, 7, v86
	v_add_u32_e32 v86, 0x8000, v86
	v_add_u32_e32 v76, v87, v85
	v_add_u32_e32 v80, v86, v85
	v_xor_b32_e32 v89, 0x20, v85
	v_add_u32_e32 v77, v87, v89
	v_add_u32_e32 v81, v86, v89
	v_xor_b32_e32 v89, 0x40, v85
	v_add_u32_e32 v78, v87, v89
	v_add_u32_e32 v82, v86, v89
	v_xor_b32_e32 v89, 0x60, v85
	v_add_u32_e32 v79, v87, v89
	v_add_u32_e32 v83, v86, v89
	v_add_u32_e32 v116, 0x18000, v76
	v_add_u32_e32 v120, 0x18000, v80
	v_add_u32_e32 v117, 0x18000, v77
	v_add_u32_e32 v121, 0x18000, v81
	v_add_u32_e32 v118, 0x18000, v78
	v_add_u32_e32 v122, 0x18000, v82
	v_add_u32_e32 v119, 0x18000, v79
	v_add_u32_e32 v123, 0x18000, v83
	v_lshlrev_b32_e32 v84, 4, v129
	s_nop 0
	v_readfirstlane_b32 s31, v84
	s_mov_b32 s25, 0
	ds_read_b128 v[84:87], v76
	ds_read_b128 v[88:91], v76 offset:4096
	ds_read_b128 v[92:95], v80
	ds_read_b128 v[96:99], v80 offset:4096
	ds_read_b128 v[100:103], v77
	ds_read_b128 v[104:107], v77 offset:4096
	ds_read_b128 v[108:111], v81
	ds_read_b128 v[112:115], v81 offset:4096
	s_waitcnt lgkmcnt(4)
	v_mfma_f32_32x32x16_bf16 v[48:63], v[84:87], v[92:95], v[48:63]
	v_mfma_f32_32x32x16_bf16 v[32:47], v[84:87], v[96:99], v[32:47]
	v_mfma_f32_32x32x16_bf16 v[16:31], v[88:91], v[92:95], v[16:31]
	v_mfma_f32_32x32x16_bf16 v[0:15], v[88:91], v[96:99], v[0:15]
	ds_read_b128 v[84:87], v78
	ds_read_b128 v[88:91], v78 offset:4096
	ds_read_b128 v[92:95], v82
	ds_read_b128 v[96:99], v82 offset:4096
	s_waitcnt lgkmcnt(4)
	v_mfma_f32_32x32x16_bf16 v[48:63], v[100:103], v[108:111], v[48:63]
	v_mfma_f32_32x32x16_bf16 v[32:47], v[100:103], v[112:115], v[32:47]
	v_mfma_f32_32x32x16_bf16 v[16:31], v[104:107], v[108:111], v[16:31]
	v_mfma_f32_32x32x16_bf16 v[0:15], v[104:107], v[112:115], v[0:15]
	ds_read_b128 v[100:103], v79
	ds_read_b128 v[104:107], v79 offset:4096
	ds_read_b128 v[108:111], v83
	ds_read_b128 v[112:115], v83 offset:4096
	s_waitcnt lgkmcnt(4)
	v_mfma_f32_32x32x16_bf16 v[48:63], v[84:87], v[92:95], v[48:63]
	v_mfma_f32_32x32x16_bf16 v[32:47], v[84:87], v[96:99], v[32:47]
	v_mfma_f32_32x32x16_bf16 v[16:31], v[88:91], v[92:95], v[16:31]
	v_mfma_f32_32x32x16_bf16 v[0:15], v[88:91], v[96:99], v[0:15]
	s_waitcnt vmcnt(6) lgkmcnt(0)
	s_barrier
;     ...
;   if (PART != 2) {
;     GEMM_ISSUE(0, 0);
;     if (nk > 1) GEMM_ISSUE(1, 1);
;   }
;   if (PART == 1) return;
;   int st = 0;
;   for (int kt = 0; kt < nk; ++kt) {
;     if (kt + 1 < nk) asm volatile("s_waitcnt vmcnt(6)" ::: "memory");
;     else asm volatile("s_waitcnt vmcnt(0)" ::: "memory");
;     __builtin_amdgcn_s_barrier();
;     asm volatile("" ::: "memory");
;     if (kt + 2 < nk) { const int st2 = (st >= 1) ? st - 1 : 2; GEMM_ISSUE(kt + 2, st2); }
;     const char* la = lds + st * STAGE_B;
;     const char* lb = la + 32768;
;     const unsigned sa_u = (unsigned)(size_t)la + arow_u, sb_u = (unsigned)(size_t)lb + brow_u;
;     const unsigned a0 = sa_u + co0, a1 = sa_u + co1, a2 = sa_u + co2, a3 = sa_u + co3;
;     const unsigned b0 = sb_u + co0, b1 = sb_u + co1, b2 = sb_u + co2, b3 = sb_u + co3;
;     {
;       bf16x8 p0, p1, q0, q1, u0, u1, w0, w1;
;       asm volatile(
;         "ds_read_b128 %4, %12\n\tds_read_b128 %5, %12 offset:4096\n\tds_read_b128 %6, %16\n\tds_read_b128 %7, %16 offset:4096\n\t"
;         "ds_read_b128 %8, %13\n\tds_read_b128 %9, %13 offset:4096\n\tds_read_b128 %10, %17\n\tds_read_b128 %11, %17 offset:4096\n\t"
;         "s_waitcnt lgkmcnt(4)\n\t"
;         "v_mfma_f32_32x32x16_bf16 %0, %4, %6, %0\n\tv_mfma_f32_32x32x16_bf16 %1, %4, %7, %1\n\tv_mfma_f32_32x32x16_bf16 %2, %5, %6, %2\n\tv_mfma_f32_32x32x16_bf16 %3, %5, %7, %3\n\t"
;         "ds_read_b128 %4, %14\n\tds_read_b128 %5, %14 offset:4096\n\tds_read_b128 %6, %18\n\tds_read_b128 %7, %18 offset:4096\n\t"
;         "s_waitcnt lgkmcnt(4)\n\t"
;         "v_mfma_f32_32x32x16_bf16 %0, %8, %10, %0\n\tv_mfma_f32_32x32x16_bf16 %1, %8, %11, %1\n\tv_mfma_f32_32x32x16_bf16 %2, %9, %10, %2\n\tv_mfma_f32_32x32x16_bf16 %3, %9, %11, %3\n\t"
;         "ds_read_b128 %8, %15\n\tds_read_b128 %9, %15 offset:4096\n\tds_read_b128 %10, %19\n\tds_read_b128 %11, %19 offset:4096\n\t"
;         "s_waitcnt lgkmcnt(4)\n\t"
;         "v_mfma_f32_32x32x16_bf16 %0, %4, %6, %0\n\tv_mfma_f32_32x32x16_bf16 %1, %4, %7, %1\n\tv_mfma_f32_32x32x16_bf16 %2, %5, %6, %2\n\tv_mfma_f32_32x32x16_bf16 %3, %5, %7, %3\n\t"
;         "s_waitcnt lgkmcnt(0)\n\t"
;         "v_mfma_f32_32x32x16_bf16 %0, %8, %10, %0\n\tv_mfma_f32_32x32x16_bf16 %1, %8, %11, %1\n\tv_mfma_f32_32x32x16_bf16 %2, %9, %10, %2\n\tv_mfma_f32_32x32x16_bf16 %3, %9, %11, %3"
	ds_read_b128 v[84:87], v76 offset:49152
	ds_read_b128 v[88:91], v76 offset:53248
	ds_read_b128 v[92:95], v80 offset:49152
	ds_read_b128 v[96:99], v80 offset:53248
	v_mfma_f32_32x32x16_bf16 v[48:63], v[100:103], v[108:111], v[48:63]
	s_mov_b32 s24, 0x180
	s_mov_b32 m0, s31
	v_lshl_add_u64 v[124:125], v[64:65], 0, s[24:25]
	global_load_lds_dwordx4 v[124:125], off
	v_mfma_f32_32x32x16_bf16 v[32:47], v[100:103], v[112:115], v[32:47]
	v_mfma_f32_32x32x16_bf16 v[16:31], v[104:107], v[108:111], v[16:31]
	s_add_u32 m0, s31, 0x2000
	v_lshl_add_u64 v[126:127], v[66:67], 0, s[24:25]
	global_load_lds_dwordx4 v[126:127], off
	v_mfma_f32_32x32x16_bf16 v[0:15], v[104:107], v[112:115], v[0:15]
	ds_read_b128 v[100:103], v77 offset:49152
	ds_read_b128 v[104:107], v77 offset:53248
	ds_read_b128 v[108:111], v81 offset:49152
	ds_read_b128 v[112:115], v81 offset:53248
	s_waitcnt lgkmcnt(4)
	v_mfma_f32_32x32x16_bf16 v[48:63], v[84:87], v[92:95], v[48:63]
	s_add_u32 m0, s31, 0x4000
	v_lshl_add_u64 v[124:125], v[68:69], 0, s[24:25]
	global_load_lds_dwordx4 v[124:125], off
	v_mfma_f32_32x32x16_bf16 v[32:47], v[84:87], v[96:99], v[32:47]
	v_mfma_f32_32x32x16_bf16 v[16:31], v[88:91], v[92:95], v[16:31]
	s_add_u32 m0, s31, 0x6000
	v_lshl_add_u64 v[126:127], v[70:71], 0, s[24:25]
	global_load_lds_dwordx4 v[126:127], off
	v_mfma_f32_32x32x16_bf16 v[0:15], v[88:91], v[96:99], v[0:15]
	ds_read_b128 v[84:87], v78 offset:49152
	ds_read_b128 v[88:91], v78 offset:53248
	ds_read_b128 v[92:95], v82 offset:49152
	ds_read_b128 v[96:99], v82 offset:53248
	s_waitcnt lgkmcnt(4)
	v_mfma_f32_32x32x16_bf16 v[48:63], v[100:103], v[108:111], v[48:63]
	s_add_u32 m0, s31, 0x8000
	v_lshl_add_u64 v[124:125], v[72:73], 0, s[24:25]
	global_load_lds_dwordx4 v[124:125], off
	v_mfma_f32_32x32x16_bf16 v[32:47], v[100:103], v[112:115], v[32:47]
	v_mfma_f32_32x32x16_bf16 v[16:31], v[104:107], v[108:111], v[16:31]
	s_add_u32 m0, s31, 0xa000
	v_lshl_add_u64 v[126:127], v[74:75], 0, s[24:25]
	global_load_lds_dwordx4 v[126:127], off
	v_mfma_f32_32x32x16_bf16 v[0:15], v[104:107], v[112:115], v[0:15]
	ds_read_b128 v[100:103], v79 offset:49152
	ds_read_b128 v[104:107], v79 offset:53248
	ds_read_b128 v[108:111], v83 offset:49152
	ds_read_b128 v[112:115], v83 offset:53248
	s_waitcnt lgkmcnt(4)
	v_mfma_f32_32x32x16_bf16 v[48:63], v[84:87], v[92:95], v[48:63]
	v_mfma_f32_32x32x16_bf16 v[32:47], v[84:87], v[96:99], v[32:47]
	v_mfma_f32_32x32x16_bf16 v[16:31], v[88:91], v[92:95], v[16:31]
	v_mfma_f32_32x32x16_bf16 v[0:15], v[88:91], v[96:99], v[0:15]
	s_waitcnt vmcnt(6) lgkmcnt(0)
	s_barrier
	ds_read_b128 v[84:87], v116
	ds_read_b128 v[88:91], v116 offset:4096
	ds_read_b128 v[92:95], v120
	ds_read_b128 v[96:99], v120 offset:4096
	v_mfma_f32_32x32x16_bf16 v[48:63], v[100:103], v[108:111], v[48:63]
	s_mov_b32 s24, 0x200
	s_add_u32 m0, s31, 0xc000
	v_lshl_add_u64 v[124:125], v[64:65], 0, s[24:25]
	global_load_lds_dwordx4 v[124:125], off
	v_mfma_f32_32x32x16_bf16 v[32:47], v[100:103], v[112:115], v[32:47]
	v_mfma_f32_32x32x16_bf16 v[16:31], v[104:107], v[108:111], v[16:31]
	s_add_u32 m0, s31, 0xe000
	v_lshl_add_u64 v[126:127], v[66:67], 0, s[24:25]
	global_load_lds_dwordx4 v[126:127], off
	v_mfma_f32_32x32x16_bf16 v[0:15], v[104:107], v[112:115], v[0:15]
	ds_read_b128 v[100:103], v117
	ds_read_b128 v[104:107], v117 offset:4096
	ds_read_b128 v[108:111], v121
	ds_read_b128 v[112:115], v121 offset:4096
	s_waitcnt lgkmcnt(4)
	v_mfma_f32_32x32x16_bf16 v[48:63], v[84:87], v[92:95], v[48:63]
	s_add_u32 m0, s31, 0x10000
	v_lshl_add_u64 v[124:125], v[68:69], 0, s[24:25]
	global_load_lds_dwordx4 v[124:125], off
	v_mfma_f32_32x32x16_bf16 v[32:47], v[84:87], v[96:99], v[32:47]
	v_mfma_f32_32x32x16_bf16 v[16:31], v[88:91], v[92:95], v[16:31]
	s_add_u32 m0, s31, 0x12000
	v_lshl_add_u64 v[126:127], v[70:71], 0, s[24:25]
	global_load_lds_dwordx4 v[126:127], off
	v_mfma_f32_32x32x16_bf16 v[0:15], v[88:91], v[96:99], v[0:15]
	ds_read_b128 v[84:87], v118
	ds_read_b128 v[88:91], v118 offset:4096
	ds_read_b128 v[92:95], v122
	ds_read_b128 v[96:99], v122 offset:4096
	s_waitcnt lgkmcnt(4)
	v_mfma_f32_32x32x16_bf16 v[48:63], v[100:103], v[108:111], v[48:63]
	s_add_u32 m0, s31, 0x14000
	v_lshl_add_u64 v[124:125], v[72:73], 0, s[24:25]
	global_load_lds_dwordx4 v[124:125], off
	v_mfma_f32_32x32x16_bf16 v[32:47], v[100:103], v[112:115], v[32:47]
	v_mfma_f32_32x32x16_bf16 v[16:31], v[104:107], v[108:111], v[16:31]
	s_add_u32 m0, s31, 0x16000
	v_lshl_add_u64 v[126:127], v[74:75], 0, s[24:25]
	global_load_lds_dwordx4 v[126:127], off
	v_mfma_f32_32x32x16_bf16 v[0:15], v[104:107], v[112:115], v[0:15]
	ds_read_b128 v[100:103], v119
	ds_read_b128 v[104:107], v119 offset:4096
	ds_read_b128 v[108:111], v123
	ds_read_b128 v[112:115], v123 offset:4096
	s_waitcnt lgkmcnt(4)
	v_mfma_f32_32x32x16_bf16 v[48:63], v[84:87], v[92:95], v[48:63]
	v_mfma_f32_32x32x16_bf16 v[32:47], v[84:87], v[96:99], v[32:47]
	v_mfma_f32_32x32x16_bf16 v[16:31], v[88:91], v[92:95], v[16:31]
	v_mfma_f32_32x32x16_bf16 v[0:15], v[88:91], v[96:99], v[0:15]
	s_waitcnt vmcnt(6) lgkmcnt(0)
	s_barrier
;     ...
;   if (PART != 2) {
;     GEMM_ISSUE(0, 0);
;     if (nk > 1) GEMM_ISSUE(1, 1);
;   }
;   if (PART == 1) return;
;   int st = 0;
;   for (int kt = 0; kt < nk; ++kt) {
;     if (kt + 1 < nk) asm volatile("s_waitcnt vmcnt(6)" ::: "memory");
;     else asm volatile("s_waitcnt vmcnt(0)" ::: "memory");
;     __builtin_amdgcn_s_barrier();
;     asm volatile("" ::: "memory");
;     if (kt + 2 < nk) { const int st2 = (st >= 1) ? st - 1 : 2; GEMM_ISSUE(kt + 2, st2); }
;     const char* la = lds + st * STAGE_B;
;     const char* lb = la + 32768;
;     const unsigned sa_u = (unsigned)(size_t)la + arow_u, sb_u = (unsigned)(size_t)lb + brow_u;
;     const unsigned a0 = sa_u + co0, a1 = sa_u + co1, a2 = sa_u + co2, a3 = sa_u + co3;
;     const unsigned b0 = sb_u + co0, b1 = sb_u + co1, b2 = sb_u + co2, b3 = sb_u + co3;
;     {
;       bf16x8 p0, p1, q0, q1, u0, u1, w0, w1;
;       asm volatile(
;         "ds_read_b128 %4, %12\n\tds_read_b128 %5, %12 offset:4096\n\tds_read_b128 %6, %16\n\tds_read_b128 %7, %16 offset:4096\n\t"
;         "ds_read_b128 %8, %13\n\tds_read_b128 %9, %13 offset:4096\n\tds_read_b128 %10, %17\n\tds_read_b128 %11, %17 offset:4096\n\t"
;         "s_waitcnt lgkmcnt(4)\n\t"
;         "v_mfma_f32_32x32x16_bf16 %0, %4, %6, %0\n\tv_mfma_f32_32x32x16_bf16 %1, %4, %7, %1\n\tv_mfma_f32_32x32x16_bf16 %2, %5, %6, %2\n\tv_mfma_f32_32x32x16_bf16 %3, %5, %7, %3\n\t"
;         "ds_read_b128 %4, %14\n\tds_read_b128 %5, %14 offset:4096\n\tds_read_b128 %6, %18\n\tds_read_b128 %7, %18 offset:4096\n\t"
;         "s_waitcnt lgkmcnt(4)\n\t"
;         "v_mfma_f32_32x32x16_bf16 %0, %8, %10, %0\n\tv_mfma_f32_32x32x16_bf16 %1, %8, %11, %1\n\tv_mfma_f32_32x32x16_bf16 %2, %9, %10, %2\n\tv_mfma_f32_32x32x16_bf16 %3, %9, %11, %3\n\t"
;         "ds_read_b128 %8, %15\n\tds_read_b128 %9, %15 offset:4096\n\tds_read_b128 %10, %19\n\tds_read_b128 %11, %19 offset:4096\n\t"
;         "s_waitcnt lgkmcnt(4)\n\t"
;         "v_mfma_f32_32x32x16_bf16 %0, %4, %6, %0\n\tv_mfma_f32_32x32x16_bf16 %1, %4, %7, %1\n\tv_mfma_f32_32x32x16_bf16 %2, %5, %6, %2\n\tv_mfma_f32_32x32x16_bf16 %3, %5, %7, %3\n\t"
;         "s_waitcnt lgkmcnt(0)\n\t"
;         "v_mfma_f32_32x32x16_bf16 %0, %8, %10, %0\n\tv_mfma_f32_32x32x16_bf16 %1, %8, %11, %1\n\tv_mfma_f32_32x32x16_bf16 %2, %9, %10, %2\n\tv_mfma_f32_32x32x16_bf16 %3, %9, %11, %3"
	ds_read_b128 v[84:87], v76
	ds_read_b128 v[88:91], v76 offset:4096
	ds_read_b128 v[92:95], v80
	ds_read_b128 v[96:99], v80 offset:4096
	v_mfma_f32_32x32x16_bf16 v[48:63], v[100:103], v[108:111], v[48:63]
	s_mov_b32 s24, 0x280
	s_add_u32 m0, s31, 0x18000
	v_lshl_add_u64 v[124:125], v[64:65], 0, s[24:25]
	global_load_lds_dwordx4 v[124:125], off
	v_mfma_f32_32x32x16_bf16 v[32:47], v[100:103], v[112:115], v[32:47]
	v_mfma_f32_32x32x16_bf16 v[16:31], v[104:107], v[108:111], v[16:31]
	s_add_u32 m0, s31, 0x1a000
	v_lshl_add_u64 v[126:127], v[66:67], 0, s[24:25]
	global_load_lds_dwordx4 v[126:127], off
	v_mfma_f32_32x32x16_bf16 v[0:15], v[104:107], v[112:115], v[0:15]
	ds_read_b128 v[100:103], v77
	ds_read_b128 v[104:107], v77 offset:4096
	ds_read_b128 v[108:111], v81
	ds_read_b128 v[112:115], v81 offset:4096
	s_waitcnt lgkmcnt(4)
	v_mfma_f32_32x32x16_bf16 v[48:63], v[84:87], v[92:95], v[48:63]
	s_add_u32 m0, s31, 0x1c000
	v_lshl_add_u64 v[124:125], v[68:69], 0, s[24:25]
	global_load_lds_dwordx4 v[124:125], off
	v_mfma_f32_32x32x16_bf16 v[32:47], v[84:87], v[96:99], v[32:47]
	v_mfma_f32_32x32x16_bf16 v[16:31], v[88:91], v[92:95], v[16:31]
	s_add_u32 m0, s31, 0x1e000
	v_lshl_add_u64 v[126:127], v[70:71], 0, s[24:25]
	global_load_lds_dwordx4 v[126:127], off
	v_mfma_f32_32x32x16_bf16 v[0:15], v[88:91], v[96:99], v[0:15]
	ds_read_b128 v[84:87], v78
	ds_read_b128 v[88:91], v78 offset:4096
	ds_read_b128 v[92:95], v82
	ds_read_b128 v[96:99], v82 offset:4096
	s_waitcnt lgkmcnt(4)
	v_mfma_f32_32x32x16_bf16 v[48:63], v[100:103], v[108:111], v[48:63]
	s_add_u32 m0, s31, 0x20000
	v_lshl_add_u64 v[124:125], v[72:73], 0, s[24:25]
	global_load_lds_dwordx4 v[124:125], off
	v_mfma_f32_32x32x16_bf16 v[32:47], v[100:103], v[112:115], v[32:47]
	v_mfma_f32_32x32x16_bf16 v[16:31], v[104:107], v[108:111], v[16:31]
	s_add_u32 m0, s31, 0x22000
	v_lshl_add_u64 v[126:127], v[74:75], 0, s[24:25]
	global_load_lds_dwordx4 v[126:127], off
	v_mfma_f32_32x32x16_bf16 v[0:15], v[104:107], v[112:115], v[0:15]
	ds_read_b128 v[100:103], v79
	ds_read_b128 v[104:107], v79 offset:4096
	ds_read_b128 v[108:111], v83
	ds_read_b128 v[112:115], v83 offset:4096
	s_waitcnt lgkmcnt(4)
	v_mfma_f32_32x32x16_bf16 v[48:63], v[84:87], v[92:95], v[48:63]
	v_mfma_f32_32x32x16_bf16 v[32:47], v[84:87], v[96:99], v[32:47]
	v_mfma_f32_32x32x16_bf16 v[16:31], v[88:91], v[92:95], v[16:31]
	v_mfma_f32_32x32x16_bf16 v[0:15], v[88:91], v[96:99], v[0:15]
	s_waitcnt vmcnt(6) lgkmcnt(0)
	s_barrier
	ds_read_b128 v[84:87], v76 offset:49152
	ds_read_b128 v[88:91], v76 offset:53248
	ds_read_b128 v[92:95], v80 offset:49152
	ds_read_b128 v[96:99], v80 offset:53248
	v_mfma_f32_32x32x16_bf16 v[48:63], v[100:103], v[108:111], v[48:63]
	s_mov_b32 s24, 0x300
	s_mov_b32 m0, s31
	v_lshl_add_u64 v[124:125], v[64:65], 0, s[24:25]
	global_load_lds_dwordx4 v[124:125], off
	v_mfma_f32_32x32x16_bf16 v[32:47], v[100:103], v[112:115], v[32:47]
	v_mfma_f32_32x32x16_bf16 v[16:31], v[104:107], v[108:111], v[16:31]
	s_add_u32 m0, s31, 0x2000
	v_lshl_add_u64 v[126:127], v[66:67], 0, s[24:25]
	global_load_lds_dwordx4 v[126:127], off
	v_mfma_f32_32x32x16_bf16 v[0:15], v[104:107], v[112:115], v[0:15]
	ds_read_b128 v[100:103], v77 offset:49152
	ds_read_b128 v[104:107], v77 offset:53248
	ds_read_b128 v[108:111], v81 offset:49152
	ds_read_b128 v[112:115], v81 offset:53248
	s_waitcnt lgkmcnt(4)
	v_mfma_f32_32x32x16_bf16 v[48:63], v[84:87], v[92:95], v[48:63]
	s_add_u32 m0, s31, 0x4000
	v_lshl_add_u64 v[124:125], v[68:69], 0, s[24:25]
	global_load_lds_dwordx4 v[124:125], off
	v_mfma_f32_32x32x16_bf16 v[32:47], v[84:87], v[96:99], v[32:47]
	v_mfma_f32_32x32x16_bf16 v[16:31], v[88:91], v[92:95], v[16:31]
	s_add_u32 m0, s31, 0x6000
	v_lshl_add_u64 v[126:127], v[70:71], 0, s[24:25]
	global_load_lds_dwordx4 v[126:127], off
	v_mfma_f32_32x32x16_bf16 v[0:15], v[88:91], v[96:99], v[0:15]
	ds_read_b128 v[84:87], v78 offset:49152
	ds_read_b128 v[88:91], v78 offset:53248
	ds_read_b128 v[92:95], v82 offset:49152
	ds_read_b128 v[96:99], v82 offset:53248
	s_waitcnt lgkmcnt(4)
	v_mfma_f32_32x32x16_bf16 v[48:63], v[100:103], v[108:111], v[48:63]
	s_add_u32 m0, s31, 0x8000
	v_lshl_add_u64 v[124:125], v[72:73], 0, s[24:25]
	global_load_lds_dwordx4 v[124:125], off
	v_mfma_f32_32x32x16_bf16 v[32:47], v[100:103], v[112:115], v[32:47]
	v_mfma_f32_32x32x16_bf16 v[16:31], v[104:107], v[108:111], v[16:31]
	s_add_u32 m0, s31, 0xa000
	v_lshl_add_u64 v[126:127], v[74:75], 0, s[24:25]
	global_load_lds_dwordx4 v[126:127], off
	v_mfma_f32_32x32x16_bf16 v[0:15], v[104:107], v[112:115], v[0:15]
	ds_read_b128 v[100:103], v79 offset:49152
	ds_read_b128 v[104:107], v79 offset:53248
	ds_read_b128 v[108:111], v83 offset:49152
	ds_read_b128 v[112:115], v83 offset:53248
	s_waitcnt lgkmcnt(4)
	v_mfma_f32_32x32x16_bf16 v[48:63], v[84:87], v[92:95], v[48:63]
	v_mfma_f32_32x32x16_bf16 v[32:47], v[84:87], v[96:99], v[32:47]
	v_mfma_f32_32x32x16_bf16 v[16:31], v[88:91], v[92:95], v[16:31]
	v_mfma_f32_32x32x16_bf16 v[0:15], v[88:91], v[96:99], v[0:15]
	s_waitcnt vmcnt(6) lgkmcnt(0)
	s_barrier
;     ...
;   if (PART != 2) {
;     GEMM_ISSUE(0, 0);
;     if (nk > 1) GEMM_ISSUE(1, 1);
;   }
;   if (PART == 1) return;
;   int st = 0;
;   for (int kt = 0; kt < nk; ++kt) {
;     if (kt + 1 < nk) asm volatile("s_waitcnt vmcnt(6)" ::: "memory");
;     else asm volatile("s_waitcnt vmcnt(0)" ::: "memory");
;     __builtin_amdgcn_s_barrier();
;     asm volatile("" ::: "memory");
;     if (kt + 2 < nk) { const int st2 = (st >= 1) ? st - 1 : 2; GEMM_ISSUE(kt + 2, st2); }
;     const char* la = lds + st * STAGE_B;
;     const char* lb = la + 32768;
;     const unsigned sa_u = (unsigned)(size_t)la + arow_u, sb_u = (unsigned)(size_t)lb + brow_u;
;     const unsigned a0 = sa_u + co0, a1 = sa_u + co1, a2 = sa_u + co2, a3 = sa_u + co3;
;     const unsigned b0 = sb_u + co0, b1 = sb_u + co1, b2 = sb_u + co2, b3 = sb_u + co3;
;     {
;       bf16x8 p0, p1, q0, q1, u0, u1, w0, w1;
;       asm volatile(
;         "ds_read_b128 %4, %12\n\tds_read_b128 %5, %12 offset:4096\n\tds_read_b128 %6, %16\n\tds_read_b128 %7, %16 offset:4096\n\t"
;         "ds_read_b128 %8, %13\n\tds_read_b128 %9, %13 offset:4096\n\tds_read_b128 %10, %17\n\tds_read_b128 %11, %17 offset:4096\n\t"
;         "s_waitcnt lgkmcnt(4)\n\t"
;         "v_mfma_f32_32x32x16_bf16 %0, %4, %6, %0\n\tv_mfma_f32_32x32x16_bf16 %1, %4, %7, %1\n\tv_mfma_f32_32x32x16_bf16 %2, %5, %6, %2\n\tv_mfma_f32_32x32x16_bf16 %3, %5, %7, %3\n\t"
;         "ds_read_b128 %4, %14\n\tds_read_b128 %5, %14 offset:4096\n\tds_read_b128 %6, %18\n\tds_read_b128 %7, %18 offset:4096\n\t"
;         "s_waitcnt lgkmcnt(4)\n\t"
;         "v_mfma_f32_32x32x16_bf16 %0, %8, %10, %0\n\tv_mfma_f32_32x32x16_bf16 %1, %8, %11, %1\n\tv_mfma_f32_32x32x16_bf16 %2, %9, %10, %2\n\tv_mfma_f32_32x32x16_bf16 %3, %9, %11, %3\n\t"
;         "ds_read_b128 %8, %15\n\tds_read_b128 %9, %15 offset:4096\n\tds_read_b128 %10, %19\n\tds_read_b128 %11, %19 offset:4096\n\t"
;         "s_waitcnt lgkmcnt(4)\n\t"
;         "v_mfma_f32_32x32x16_bf16 %0, %4, %6, %0\n\tv_mfma_f32_32x32x16_bf16 %1, %4, %7, %1\n\tv_mfma_f32_32x32x16_bf16 %2, %5, %6, %2\n\tv_mfma_f32_32x32x16_bf16 %3, %5, %7, %3\n\t"
;         "s_waitcnt lgkmcnt(0)\n\t"
;         "v_mfma_f32_32x32x16_bf16 %0, %8, %10, %0\n\tv_mfma_f32_32x32x16_bf16 %1, %8, %11, %1\n\tv_mfma_f32_32x32x16_bf16 %2, %9, %10, %2\n\tv_mfma_f32_32x32x16_bf16 %3, %9, %11, %3"
	ds_read_b128 v[84:87], v116
	ds_read_b128 v[88:91], v116 offset:4096
	ds_read_b128 v[92:95], v120
	ds_read_b128 v[96:99], v120 offset:4096
	v_mfma_f32_32x32x16_bf16 v[48:63], v[100:103], v[108:111], v[48:63]
	s_mov_b32 s24, 0x380
	s_add_u32 m0, s31, 0xc000
	v_lshl_add_u64 v[124:125], v[64:65], 0, s[24:25]
	global_load_lds_dwordx4 v[124:125], off
	v_mfma_f32_32x32x16_bf16 v[32:47], v[100:103], v[112:115], v[32:47]
	v_mfma_f32_32x32x16_bf16 v[16:31], v[104:107], v[108:111], v[16:31]
	s_add_u32 m0, s31, 0xe000
	v_lshl_add_u64 v[126:127], v[66:67], 0, s[24:25]
	global_load_lds_dwordx4 v[126:127], off
	v_mfma_f32_32x32x16_bf16 v[0:15], v[104:107], v[112:115], v[0:15]
	ds_read_b128 v[100:103], v117
	ds_read_b128 v[104:107], v117 offset:4096
	ds_read_b128 v[108:111], v121
	ds_read_b128 v[112:115], v121 offset:4096
	s_waitcnt lgkmcnt(4)
	v_mfma_f32_32x32x16_bf16 v[48:63], v[84:87], v[92:95], v[48:63]
	s_add_u32 m0, s31, 0x10000
	v_lshl_add_u64 v[124:125], v[68:69], 0, s[24:25]
	global_load_lds_dwordx4 v[124:125], off
	v_mfma_f32_32x32x16_bf16 v[32:47], v[84:87], v[96:99], v[32:47]
	v_mfma_f32_32x32x16_bf16 v[16:31], v[88:91], v[92:95], v[16:31]
	s_add_u32 m0, s31, 0x12000
	v_lshl_add_u64 v[126:127], v[70:71], 0, s[24:25]
	global_load_lds_dwordx4 v[126:127], off
	v_mfma_f32_32x32x16_bf16 v[0:15], v[88:91], v[96:99], v[0:15]
	ds_read_b128 v[84:87], v118
	ds_read_b128 v[88:91], v118 offset:4096
	ds_read_b128 v[92:95], v122
	ds_read_b128 v[96:99], v122 offset:4096
	s_waitcnt lgkmcnt(4)
	v_mfma_f32_32x32x16_bf16 v[48:63], v[100:103], v[108:111], v[48:63]
	s_add_u32 m0, s31, 0x14000
	v_lshl_add_u64 v[124:125], v[72:73], 0, s[24:25]
	global_load_lds_dwordx4 v[124:125], off
	v_mfma_f32_32x32x16_bf16 v[32:47], v[100:103], v[112:115], v[32:47]
	v_mfma_f32_32x32x16_bf16 v[16:31], v[104:107], v[108:111], v[16:31]
	s_add_u32 m0, s31, 0x16000
	v_lshl_add_u64 v[126:127], v[74:75], 0, s[24:25]
	global_load_lds_dwordx4 v[126:127], off
	v_mfma_f32_32x32x16_bf16 v[0:15], v[104:107], v[112:115], v[0:15]
	ds_read_b128 v[100:103], v119
	ds_read_b128 v[104:107], v119 offset:4096
	ds_read_b128 v[108:111], v123
	ds_read_b128 v[112:115], v123 offset:4096
	s_waitcnt lgkmcnt(4)
	v_mfma_f32_32x32x16_bf16 v[48:63], v[84:87], v[92:95], v[48:63]
	v_mfma_f32_32x32x16_bf16 v[32:47], v[84:87], v[96:99], v[32:47]
	v_mfma_f32_32x32x16_bf16 v[16:31], v[88:91], v[92:95], v[16:31]
	v_mfma_f32_32x32x16_bf16 v[0:15], v[88:91], v[96:99], v[0:15]
	s_waitcnt vmcnt(6) lgkmcnt(0)
	s_barrier
	ds_read_b128 v[84:87], v76
	ds_read_b128 v[88:91], v76 offset:4096
	ds_read_b128 v[92:95], v80
	ds_read_b128 v[96:99], v80 offset:4096
	v_mfma_f32_32x32x16_bf16 v[48:63], v[100:103], v[108:111], v[48:63]
	s_mov_b32 s24, 0x400
	s_add_u32 m0, s31, 0x18000
	v_lshl_add_u64 v[124:125], v[64:65], 0, s[24:25]
	global_load_lds_dwordx4 v[124:125], off
	v_mfma_f32_32x32x16_bf16 v[32:47], v[100:103], v[112:115], v[32:47]
	v_mfma_f32_32x32x16_bf16 v[16:31], v[104:107], v[108:111], v[16:31]
	s_add_u32 m0, s31, 0x1a000
	v_lshl_add_u64 v[126:127], v[66:67], 0, s[24:25]
	global_load_lds_dwordx4 v[126:127], off
	v_mfma_f32_32x32x16_bf16 v[0:15], v[104:107], v[112:115], v[0:15]
	ds_read_b128 v[100:103], v77
	ds_read_b128 v[104:107], v77 offset:4096
	ds_read_b128 v[108:111], v81
	ds_read_b128 v[112:115], v81 offset:4096
	s_waitcnt lgkmcnt(4)
	v_mfma_f32_32x32x16_bf16 v[48:63], v[84:87], v[92:95], v[48:63]
	s_add_u32 m0, s31, 0x1c000
	v_lshl_add_u64 v[124:125], v[68:69], 0, s[24:25]
	global_load_lds_dwordx4 v[124:125], off
	v_mfma_f32_32x32x16_bf16 v[32:47], v[84:87], v[96:99], v[32:47]
	v_mfma_f32_32x32x16_bf16 v[16:31], v[88:91], v[92:95], v[16:31]
	s_add_u32 m0, s31, 0x1e000
	v_lshl_add_u64 v[126:127], v[70:71], 0, s[24:25]
	global_load_lds_dwordx4 v[126:127], off
	v_mfma_f32_32x32x16_bf16 v[0:15], v[88:91], v[96:99], v[0:15]
	ds_read_b128 v[84:87], v78
	ds_read_b128 v[88:91], v78 offset:4096
	ds_read_b128 v[92:95], v82
	ds_read_b128 v[96:99], v82 offset:4096
	s_waitcnt lgkmcnt(4)
	v_mfma_f32_32x32x16_bf16 v[48:63], v[100:103], v[108:111], v[48:63]
	s_add_u32 m0, s31, 0x20000
	v_lshl_add_u64 v[124:125], v[72:73], 0, s[24:25]
	global_load_lds_dwordx4 v[124:125], off
	v_mfma_f32_32x32x16_bf16 v[32:47], v[100:103], v[112:115], v[32:47]
	v_mfma_f32_32x32x16_bf16 v[16:31], v[104:107], v[108:111], v[16:31]
	s_add_u32 m0, s31, 0x22000
	v_lshl_add_u64 v[126:127], v[74:75], 0, s[24:25]
	global_load_lds_dwordx4 v[126:127], off
	v_mfma_f32_32x32x16_bf16 v[0:15], v[104:107], v[112:115], v[0:15]
	ds_read_b128 v[100:103], v79
	ds_read_b128 v[104:107], v79 offset:4096
	ds_read_b128 v[108:111], v83
	ds_read_b128 v[112:115], v83 offset:4096
	s_waitcnt lgkmcnt(4)
	v_mfma_f32_32x32x16_bf16 v[48:63], v[84:87], v[92:95], v[48:63]
	v_mfma_f32_32x32x16_bf16 v[32:47], v[84:87], v[96:99], v[32:47]
	v_mfma_f32_32x32x16_bf16 v[16:31], v[88:91], v[92:95], v[16:31]
	v_mfma_f32_32x32x16_bf16 v[0:15], v[88:91], v[96:99], v[0:15]
	s_waitcnt vmcnt(6) lgkmcnt(0)
	s_barrier
;     ...
;   if (PART != 2) {
;     GEMM_ISSUE(0, 0);
;     if (nk > 1) GEMM_ISSUE(1, 1);
;   }
;   if (PART == 1) return;
;   int st = 0;
;   for (int kt = 0; kt < nk; ++kt) {
;     if (kt + 1 < nk) asm volatile("s_waitcnt vmcnt(6)" ::: "memory");
;     else asm volatile("s_waitcnt vmcnt(0)" ::: "memory");
;     __builtin_amdgcn_s_barrier();
;     asm volatile("" ::: "memory");
;     if (kt + 2 < nk) { const int st2 = (st >= 1) ? st - 1 : 2; GEMM_ISSUE(kt + 2, st2); }
;     const char* la = lds + st * STAGE_B;
;     const char* lb = la + 32768;
;     const unsigned sa_u = (unsigned)(size_t)la + arow_u, sb_u = (unsigned)(size_t)lb + brow_u;
;     const unsigned a0 = sa_u + co0, a1 = sa_u + co1, a2 = sa_u + co2, a3 = sa_u + co3;
;     const unsigned b0 = sb_u + co0, b1 = sb_u + co1, b2 = sb_u + co2, b3 = sb_u + co3;
;     {
;       bf16x8 p0, p1, q0, q1, u0, u1, w0, w1;
;       asm volatile(
;         "ds_read_b128 %4, %12\n\tds_read_b128 %5, %12 offset:4096\n\tds_read_b128 %6, %16\n\tds_read_b128 %7, %16 offset:4096\n\t"
;         "ds_read_b128 %8, %13\n\tds_read_b128 %9, %13 offset:4096\n\tds_read_b128 %10, %17\n\tds_read_b128 %11, %17 offset:4096\n\t"
;         "s_waitcnt lgkmcnt(4)\n\t"
;         "v_mfma_f32_32x32x16_bf16 %0, %4, %6, %0\n\tv_mfma_f32_32x32x16_bf16 %1, %4, %7, %1\n\tv_mfma_f32_32x32x16_bf16 %2, %5, %6, %2\n\tv_mfma_f32_32x32x16_bf16 %3, %5, %7, %3\n\t"
;         "ds_read_b128 %4, %14\n\tds_read_b128 %5, %14 offset:4096\n\tds_read_b128 %6, %18\n\tds_read_b128 %7, %18 offset:4096\n\t"
;         "s_waitcnt lgkmcnt(4)\n\t"
;         "v_mfma_f32_32x32x16_bf16 %0, %8, %10, %0\n\tv_mfma_f32_32x32x16_bf16 %1, %8, %11, %1\n\tv_mfma_f32_32x32x16_bf16 %2, %9, %10, %2\n\tv_mfma_f32_32x32x16_bf16 %3, %9, %11, %3\n\t"
;         "ds_read_b128 %8, %15\n\tds_read_b128 %9, %15 offset:4096\n\tds_read_b128 %10, %19\n\tds_read_b128 %11, %19 offset:4096\n\t"
;         "s_waitcnt lgkmcnt(4)\n\t"
;         "v_mfma_f32_32x32x16_bf16 %0, %4, %6, %0\n\tv_mfma_f32_32x32x16_bf16 %1, %4, %7, %1\n\tv_mfma_f32_32x32x16_bf16 %2, %5, %6, %2\n\tv_mfma_f32_32x32x16_bf16 %3, %5, %7, %3\n\t"
;         "s_waitcnt lgkmcnt(0)\n\t"
;         "v_mfma_f32_32x32x16_bf16 %0, %8, %10, %0\n\tv_mfma_f32_32x32x16_bf16 %1, %8, %11, %1\n\tv_mfma_f32_32x32x16_bf16 %2, %9, %10, %2\n\tv_mfma_f32_32x32x16_bf16 %3, %9, %11, %3"
	ds_read_b128 v[84:87], v76 offset:49152
	ds_read_b128 v[88:91], v76 offset:53248
	ds_read_b128 v[92:95], v80 offset:49152
	ds_read_b128 v[96:99], v80 offset:53248
	v_mfma_f32_32x32x16_bf16 v[48:63], v[100:103], v[108:111], v[48:63]
	s_mov_b32 s24, 0x480
	s_mov_b32 m0, s31
	v_lshl_add_u64 v[124:125], v[64:65], 0, s[24:25]
	global_load_lds_dwordx4 v[124:125], off
	v_mfma_f32_32x32x16_bf16 v[32:47], v[100:103], v[112:115], v[32:47]
	v_mfma_f32_32x32x16_bf16 v[16:31], v[104:107], v[108:111], v[16:31]
	s_add_u32 m0, s31, 0x2000
	v_lshl_add_u64 v[126:127], v[66:67], 0, s[24:25]
	global_load_lds_dwordx4 v[126:127], off
	v_mfma_f32_32x32x16_bf16 v[0:15], v[104:107], v[112:115], v[0:15]
	ds_read_b128 v[100:103], v77 offset:49152
	ds_read_b128 v[104:107], v77 offset:53248
	ds_read_b128 v[108:111], v81 offset:49152
	ds_read_b128 v[112:115], v81 offset:53248
	s_waitcnt lgkmcnt(4)
	v_mfma_f32_32x32x16_bf16 v[48:63], v[84:87], v[92:95], v[48:63]
	s_add_u32 m0, s31, 0x4000
	v_lshl_add_u64 v[124:125], v[68:69], 0, s[24:25]
	global_load_lds_dwordx4 v[124:125], off
	v_mfma_f32_32x32x16_bf16 v[32:47], v[84:87], v[96:99], v[32:47]
	v_mfma_f32_32x32x16_bf16 v[16:31], v[88:91], v[92:95], v[16:31]
	s_add_u32 m0, s31, 0x6000
	v_lshl_add_u64 v[126:127], v[70:71], 0, s[24:25]
	global_load_lds_dwordx4 v[126:127], off
	v_mfma_f32_32x32x16_bf16 v[0:15], v[88:91], v[96:99], v[0:15]
	ds_read_b128 v[84:87], v78 offset:49152
	ds_read_b128 v[88:91], v78 offset:53248
	ds_read_b128 v[92:95], v82 offset:49152
	ds_read_b128 v[96:99], v82 offset:53248
	s_waitcnt lgkmcnt(4)
	v_mfma_f32_32x32x16_bf16 v[48:63], v[100:103], v[108:111], v[48:63]
	s_add_u32 m0, s31, 0x8000
	v_lshl_add_u64 v[124:125], v[72:73], 0, s[24:25]
	global_load_lds_dwordx4 v[124:125], off
	v_mfma_f32_32x32x16_bf16 v[32:47], v[100:103], v[112:115], v[32:47]
	v_mfma_f32_32x32x16_bf16 v[16:31], v[104:107], v[108:111], v[16:31]
	s_add_u32 m0, s31, 0xa000
	v_lshl_add_u64 v[126:127], v[74:75], 0, s[24:25]
	global_load_lds_dwordx4 v[126:127], off
	v_mfma_f32_32x32x16_bf16 v[0:15], v[104:107], v[112:115], v[0:15]
	ds_read_b128 v[100:103], v79 offset:49152
	ds_read_b128 v[104:107], v79 offset:53248
	ds_read_b128 v[108:111], v83 offset:49152
	ds_read_b128 v[112:115], v83 offset:53248
	s_waitcnt lgkmcnt(4)
	v_mfma_f32_32x32x16_bf16 v[48:63], v[84:87], v[92:95], v[48:63]
	v_mfma_f32_32x32x16_bf16 v[32:47], v[84:87], v[96:99], v[32:47]
	v_mfma_f32_32x32x16_bf16 v[16:31], v[88:91], v[92:95], v[16:31]
	v_mfma_f32_32x32x16_bf16 v[0:15], v[88:91], v[96:99], v[0:15]
	s_waitcnt vmcnt(6) lgkmcnt(0)
	s_barrier
	ds_read_b128 v[84:87], v116
	ds_read_b128 v[88:91], v116 offset:4096
	ds_read_b128 v[92:95], v120
	ds_read_b128 v[96:99], v120 offset:4096
	v_mfma_f32_32x32x16_bf16 v[48:63], v[100:103], v[108:111], v[48:63]
	s_mov_b32 s24, 0x500
	s_add_u32 m0, s31, 0xc000
	v_lshl_add_u64 v[124:125], v[64:65], 0, s[24:25]
	global_load_lds_dwordx4 v[124:125], off
	v_mfma_f32_32x32x16_bf16 v[32:47], v[100:103], v[112:115], v[32:47]
	v_mfma_f32_32x32x16_bf16 v[16:31], v[104:107], v[108:111], v[16:31]
	s_add_u32 m0, s31, 0xe000
	v_lshl_add_u64 v[126:127], v[66:67], 0, s[24:25]
	global_load_lds_dwordx4 v[126:127], off
	v_mfma_f32_32x32x16_bf16 v[0:15], v[104:107], v[112:115], v[0:15]
	ds_read_b128 v[100:103], v117
	ds_read_b128 v[104:107], v117 offset:4096
	ds_read_b128 v[108:111], v121
	ds_read_b128 v[112:115], v121 offset:4096
	s_waitcnt lgkmcnt(4)
	v_mfma_f32_32x32x16_bf16 v[48:63], v[84:87], v[92:95], v[48:63]
	s_add_u32 m0, s31, 0x10000
	v_lshl_add_u64 v[124:125], v[68:69], 0, s[24:25]
	global_load_lds_dwordx4 v[124:125], off
	v_mfma_f32_32x32x16_bf16 v[32:47], v[84:87], v[96:99], v[32:47]
	v_mfma_f32_32x32x16_bf16 v[16:31], v[88:91], v[92:95], v[16:31]
	s_add_u32 m0, s31, 0x12000
	v_lshl_add_u64 v[126:127], v[70:71], 0, s[24:25]
	global_load_lds_dwordx4 v[126:127], off
	v_mfma_f32_32x32x16_bf16 v[0:15], v[88:91], v[96:99], v[0:15]
	ds_read_b128 v[84:87], v118
	ds_read_b128 v[88:91], v118 offset:4096
	ds_read_b128 v[92:95], v122
	ds_read_b128 v[96:99], v122 offset:4096
	s_waitcnt lgkmcnt(4)
	v_mfma_f32_32x32x16_bf16 v[48:63], v[100:103], v[108:111], v[48:63]
	s_add_u32 m0, s31, 0x14000
	v_lshl_add_u64 v[124:125], v[72:73], 0, s[24:25]
	global_load_lds_dwordx4 v[124:125], off
	v_mfma_f32_32x32x16_bf16 v[32:47], v[100:103], v[112:115], v[32:47]
	v_mfma_f32_32x32x16_bf16 v[16:31], v[104:107], v[108:111], v[16:31]
	s_add_u32 m0, s31, 0x16000
	v_lshl_add_u64 v[126:127], v[74:75], 0, s[24:25]
	global_load_lds_dwordx4 v[126:127], off
	v_mfma_f32_32x32x16_bf16 v[0:15], v[104:107], v[112:115], v[0:15]
	ds_read_b128 v[100:103], v119
	ds_read_b128 v[104:107], v119 offset:4096
	ds_read_b128 v[108:111], v123
	ds_read_b128 v[112:115], v123 offset:4096
	s_waitcnt lgkmcnt(4)
	v_mfma_f32_32x32x16_bf16 v[48:63], v[84:87], v[92:95], v[48:63]
	v_mfma_f32_32x32x16_bf16 v[32:47], v[84:87], v[96:99], v[32:47]
	v_mfma_f32_32x32x16_bf16 v[16:31], v[88:91], v[92:95], v[16:31]
	v_mfma_f32_32x32x16_bf16 v[0:15], v[88:91], v[96:99], v[0:15]
	s_waitcnt vmcnt(6) lgkmcnt(0)
	s_barrier
;     ...
;   for (int kt = 0; kt < nk; ++kt) {
;     if (kt + 1 < nk) asm volatile("s_waitcnt vmcnt(6)" ::: "memory");
;     else asm volatile("s_waitcnt vmcnt(0)" ::: "memory");
;     __builtin_amdgcn_s_barrier();
;     asm volatile("" ::: "memory");
;     if (kt + 2 < nk) { const int st2 = (st >= 1) ? st - 1 : 2; GEMM_ISSUE(kt + 2, st2); }
;     const char* la = lds + st * STAGE_B;
;     const char* lb = la + 32768;
;     const unsigned sa_u = (unsigned)(size_t)la + arow_u, sb_u = (unsigned)(size_t)lb + brow_u;
;     const unsigned a0 = sa_u + co0, a1 = sa_u + co1, a2 = sa_u + co2, a3 = sa_u + co3;
;     const unsigned b0 = sb_u + co0, b1 = sb_u + co1, b2 = sb_u + co2, b3 = sb_u + co3;
;     {
;       bf16x8 p0, p1, q0, q1, u0, u1, w0, w1;
;       asm volatile(
;         "ds_read_b128 %4, %12\n\tds_read_b128 %5, %12 offset:4096\n\tds_read_b128 %6, %16\n\tds_read_b128 %7, %16 offset:4096\n\t"
;         "ds_read_b128 %8, %13\n\tds_read_b128 %9, %13 offset:4096\n\tds_read_b128 %10, %17\n\tds_read_b128 %11, %17 offset:4096\n\t"
;         "s_waitcnt lgkmcnt(4)\n\t"
;         "v_mfma_f32_32x32x16_bf16 %0, %4, %6, %0\n\tv_mfma_f32_32x32x16_bf16 %1, %4, %7, %1\n\tv_mfma_f32_32x32x16_bf16 %2, %5, %6, %2\n\tv_mfma_f32_32x32x16_bf16 %3, %5, %7, %3\n\t"
;         "ds_read_b128 %4, %14\n\tds_read_b128 %5, %14 offset:4096\n\tds_read_b128 %6, %18\n\tds_read_b128 %7, %18 offset:4096\n\t"
;         "s_waitcnt lgkmcnt(4)\n\t"
;         "v_mfma_f32_32x32x16_bf16 %0, %8, %10, %0\n\tv_mfma_f32_32x32x16_bf16 %1, %8, %11, %1\n\tv_mfma_f32_32x32x16_bf16 %2, %9, %10, %2\n\tv_mfma_f32_32x32x16_bf16 %3, %9, %11, %3\n\t"
;         "ds_read_b128 %8, %15\n\tds_read_b128 %9, %15 offset:4096\n\tds_read_b128 %10, %19\n\tds_read_b128 %11, %19 offset:4096\n\t"
;         "s_waitcnt lgkmcnt(4)\n\t"
;         "v_mfma_f32_32x32x16_bf16 %0, %4, %6, %0\n\tv_mfma_f32_32x32x16_bf16 %1, %4, %7, %1\n\tv_mfma_f32_32x32x16_bf16 %2, %5, %6, %2\n\tv_mfma_f32_32x32x16_bf16 %3, %5, %7, %3\n\t"
;         "s_waitcnt lgkmcnt(0)\n\t"
;         "v_mfma_f32_32x32x16_bf16 %0, %8, %10, %0\n\tv_mfma_f32_32x32x16_bf16 %1, %8, %11, %1\n\tv_mfma_f32_32x32x16_bf16 %2, %9, %10, %2\n\tv_mfma_f32_32x32x16_bf16 %3, %9, %11, %3"
;         : "+v"(acc[0][0]), "+v"(acc[0][1]), "+v"(acc[1][0]), "+v"(acc[1][1]),
;           "=&v"(p0), "=&v"(p1), "=&v"(q0), "=&v"(q1), "=&v"(u0), "=&v"(u1), "=&v"(w0), "=&v"(w1)
	ds_read_b128 v[84:87], v76
	ds_read_b128 v[88:91], v76 offset:4096
	ds_read_b128 v[92:95], v80
	ds_read_b128 v[96:99], v80 offset:4096
	v_mfma_f32_32x32x16_bf16 v[48:63], v[100:103], v[108:111], v[48:63]
	s_mov_b32 s24, 0x580
	s_add_u32 m0, s31, 0x18000
	v_lshl_add_u64 v[124:125], v[64:65], 0, s[24:25]
	global_load_lds_dwordx4 v[124:125], off
	v_mfma_f32_32x32x16_bf16 v[32:47], v[100:103], v[112:115], v[32:47]
	v_mfma_f32_32x32x16_bf16 v[16:31], v[104:107], v[108:111], v[16:31]
	s_add_u32 m0, s31, 0x1a000
	v_lshl_add_u64 v[126:127], v[66:67], 0, s[24:25]
	global_load_lds_dwordx4 v[126:127], off
	v_mfma_f32_32x32x16_bf16 v[0:15], v[104:107], v[112:115], v[0:15]
	ds_read_b128 v[100:103], v77
	ds_read_b128 v[104:107], v77 offset:4096
	ds_read_b128 v[108:111], v81
	ds_read_b128 v[112:115], v81 offset:4096
	s_waitcnt lgkmcnt(4)
	v_mfma_f32_32x32x16_bf16 v[48:63], v[84:87], v[92:95], v[48:63]
	s_add_u32 m0, s31, 0x1c000
	v_lshl_add_u64 v[124:125], v[68:69], 0, s[24:25]
	global_load_lds_dwordx4 v[124:125], off
	v_mfma_f32_32x32x16_bf16 v[32:47], v[84:87], v[96:99], v[32:47]
	v_mfma_f32_32x32x16_bf16 v[16:31], v[88:91], v[92:95], v[16:31]
	s_add_u32 m0, s31, 0x1e000
	v_lshl_add_u64 v[126:127], v[70:71], 0, s[24:25]
	global_load_lds_dwordx4 v[126:127], off
	v_mfma_f32_32x32x16_bf16 v[0:15], v[88:91], v[96:99], v[0:15]
	ds_read_b128 v[84:87], v78
	ds_read_b128 v[88:91], v78 offset:4096
	ds_read_b128 v[92:95], v82
	ds_read_b128 v[96:99], v82 offset:4096
	s_waitcnt lgkmcnt(4)
	v_mfma_f32_32x32x16_bf16 v[48:63], v[100:103], v[108:111], v[48:63]
	s_add_u32 m0, s31, 0x20000
	v_lshl_add_u64 v[124:125], v[72:73], 0, s[24:25]
	global_load_lds_dwordx4 v[124:125], off
	v_mfma_f32_32x32x16_bf16 v[32:47], v[100:103], v[112:115], v[32:47]
	v_mfma_f32_32x32x16_bf16 v[16:31], v[104:107], v[108:111], v[16:31]
	s_add_u32 m0, s31, 0x22000
	v_lshl_add_u64 v[126:127], v[74:75], 0, s[24:25]
	global_load_lds_dwordx4 v[126:127], off
	v_mfma_f32_32x32x16_bf16 v[0:15], v[104:107], v[112:115], v[0:15]
	ds_read_b128 v[100:103], v79
	ds_read_b128 v[104:107], v79 offset:4096
	ds_read_b128 v[108:111], v83
	ds_read_b128 v[112:115], v83 offset:4096
	s_waitcnt lgkmcnt(4)
	v_mfma_f32_32x32x16_bf16 v[48:63], v[84:87], v[92:95], v[48:63]
	v_mfma_f32_32x32x16_bf16 v[32:47], v[84:87], v[96:99], v[32:47]
	v_mfma_f32_32x32x16_bf16 v[16:31], v[88:91], v[92:95], v[16:31]
	v_mfma_f32_32x32x16_bf16 v[0:15], v[88:91], v[96:99], v[0:15]
	s_waitcnt vmcnt(6) lgkmcnt(0)
	s_barrier
	ds_read_b128 v[84:87], v76 offset:49152
	ds_read_b128 v[88:91], v76 offset:53248
	ds_read_b128 v[92:95], v80 offset:49152
	ds_read_b128 v[96:99], v80 offset:53248
	v_mfma_f32_32x32x16_bf16 v[48:63], v[100:103], v[108:111], v[48:63]
	s_mov_b32 s24, 0x600
	s_mov_b32 m0, s31
	v_lshl_add_u64 v[124:125], v[64:65], 0, s[24:25]
	global_load_lds_dwordx4 v[124:125], off
	v_mfma_f32_32x32x16_bf16 v[32:47], v[100:103], v[112:115], v[32:47]
	v_mfma_f32_32x32x16_bf16 v[16:31], v[104:107], v[108:111], v[16:31]
	s_add_u32 m0, s31, 0x2000
	v_lshl_add_u64 v[126:127], v[66:67], 0, s[24:25]
	global_load_lds_dwordx4 v[126:127], off
	v_mfma_f32_32x32x16_bf16 v[0:15], v[104:107], v[112:115], v[0:15]
	ds_read_b128 v[100:103], v77 offset:49152
	ds_read_b128 v[104:107], v77 offset:53248
	ds_read_b128 v[108:111], v81 offset:49152
	ds_read_b128 v[112:115], v81 offset:53248
	s_waitcnt lgkmcnt(4)
	v_mfma_f32_32x32x16_bf16 v[48:63], v[84:87], v[92:95], v[48:63]
	s_add_u32 m0, s31, 0x4000
	v_lshl_add_u64 v[124:125], v[68:69], 0, s[24:25]
	global_load_lds_dwordx4 v[124:125], off
	v_mfma_f32_32x32x16_bf16 v[32:47], v[84:87], v[96:99], v[32:47]
	v_mfma_f32_32x32x16_bf16 v[16:31], v[88:91], v[92:95], v[16:31]
	s_add_u32 m0, s31, 0x6000
	v_lshl_add_u64 v[126:127], v[70:71], 0, s[24:25]
	global_load_lds_dwordx4 v[126:127], off
	v_mfma_f32_32x32x16_bf16 v[0:15], v[88:91], v[96:99], v[0:15]
	ds_read_b128 v[84:87], v78 offset:49152
	ds_read_b128 v[88:91], v78 offset:53248
	ds_read_b128 v[92:95], v82 offset:49152
	ds_read_b128 v[96:99], v82 offset:53248
	s_waitcnt lgkmcnt(4)
	v_mfma_f32_32x32x16_bf16 v[48:63], v[100:103], v[108:111], v[48:63]
	s_add_u32 m0, s31, 0x8000
	v_lshl_add_u64 v[124:125], v[72:73], 0, s[24:25]
	global_load_lds_dwordx4 v[124:125], off
	v_mfma_f32_32x32x16_bf16 v[32:47], v[100:103], v[112:115], v[32:47]
	v_mfma_f32_32x32x16_bf16 v[16:31], v[104:107], v[108:111], v[16:31]
	s_add_u32 m0, s31, 0xa000
	v_lshl_add_u64 v[126:127], v[74:75], 0, s[24:25]
	global_load_lds_dwordx4 v[126:127], off
	v_mfma_f32_32x32x16_bf16 v[0:15], v[104:107], v[112:115], v[0:15]
	ds_read_b128 v[100:103], v79 offset:49152
	ds_read_b128 v[104:107], v79 offset:53248
	ds_read_b128 v[108:111], v83 offset:49152
	ds_read_b128 v[112:115], v83 offset:53248
	s_waitcnt lgkmcnt(4)
	v_mfma_f32_32x32x16_bf16 v[48:63], v[84:87], v[92:95], v[48:63]
	v_mfma_f32_32x32x16_bf16 v[32:47], v[84:87], v[96:99], v[32:47]
	v_mfma_f32_32x32x16_bf16 v[16:31], v[88:91], v[92:95], v[16:31]
	v_mfma_f32_32x32x16_bf16 v[0:15], v[88:91], v[96:99], v[0:15]
	s_waitcnt vmcnt(6) lgkmcnt(0)
	s_barrier
;     ...
;   for (int kt = 0; kt < nk; ++kt) {
;     if (kt + 1 < nk) asm volatile("s_waitcnt vmcnt(6)" ::: "memory");
;     else asm volatile("s_waitcnt vmcnt(0)" ::: "memory");
;     __builtin_amdgcn_s_barrier();
;     asm volatile("" ::: "memory");
;     if (kt + 2 < nk) { const int st2 = (st >= 1) ? st - 1 : 2; GEMM_ISSUE(kt + 2, st2); }
;     const char* la = lds + st * STAGE_B;
;     const char* lb = la + 32768;
;     const unsigned sa_u = (unsigned)(size_t)la + arow_u, sb_u = (unsigned)(size_t)lb + brow_u;
;     const unsigned a0 = sa_u + co0, a1 = sa_u + co1, a2 = sa_u + co2, a3 = sa_u + co3;
;     const unsigned b0 = sb_u + co0, b1 = sb_u + co1, b2 = sb_u + co2, b3 = sb_u + co3;
;     {
;       bf16x8 p0, p1, q0, q1, u0, u1, w0, w1;
;       asm volatile(
;         "ds_read_b128 %4, %12\n\tds_read_b128 %5, %12 offset:4096\n\tds_read_b128 %6, %16\n\tds_read_b128 %7, %16 offset:4096\n\t"
;         "ds_read_b128 %8, %13\n\tds_read_b128 %9, %13 offset:4096\n\tds_read_b128 %10, %17\n\tds_read_b128 %11, %17 offset:4096\n\t"
;         "s_waitcnt lgkmcnt(4)\n\t"
;         "v_mfma_f32_32x32x16_bf16 %0, %4, %6, %0\n\tv_mfma_f32_32x32x16_bf16 %1, %4, %7, %1\n\tv_mfma_f32_32x32x16_bf16 %2, %5, %6, %2\n\tv_mfma_f32_32x32x16_bf16 %3, %5, %7, %3\n\t"
;         "ds_read_b128 %4, %14\n\tds_read_b128 %5, %14 offset:4096\n\tds_read_b128 %6, %18\n\tds_read_b128 %7, %18 offset:4096\n\t"
;         "s_waitcnt lgkmcnt(4)\n\t"
;         "v_mfma_f32_32x32x16_bf16 %0, %8, %10, %0\n\tv_mfma_f32_32x32x16_bf16 %1, %8, %11, %1\n\tv_mfma_f32_32x32x16_bf16 %2, %9, %10, %2\n\tv_mfma_f32_32x32x16_bf16 %3, %9, %11, %3\n\t"
;         "ds_read_b128 %8, %15\n\tds_read_b128 %9, %15 offset:4096\n\tds_read_b128 %10, %19\n\tds_read_b128 %11, %19 offset:4096\n\t"
;         "s_waitcnt lgkmcnt(4)\n\t"
;         "v_mfma_f32_32x32x16_bf16 %0, %4, %6, %0\n\tv_mfma_f32_32x32x16_bf16 %1, %4, %7, %1\n\tv_mfma_f32_32x32x16_bf16 %2, %5, %6, %2\n\tv_mfma_f32_32x32x16_bf16 %3, %5, %7, %3\n\t"
;         "s_waitcnt lgkmcnt(0)\n\t"
;         "v_mfma_f32_32x32x16_bf16 %0, %8, %10, %0\n\tv_mfma_f32_32x32x16_bf16 %1, %8, %11, %1\n\tv_mfma_f32_32x32x16_bf16 %2, %9, %10, %2\n\tv_mfma_f32_32x32x16_bf16 %3, %9, %11, %3"
;         : "+v"(acc[0][0]), "+v"(acc[0][1]), "+v"(acc[1][0]), "+v"(acc[1][1]),
;           "=&v"(p0), "=&v"(p1), "=&v"(q0), "=&v"(q1), "=&v"(u0), "=&v"(u1), "=&v"(w0), "=&v"(w1)
	ds_read_b128 v[84:87], v116
	ds_read_b128 v[88:91], v116 offset:4096
	ds_read_b128 v[92:95], v120
	ds_read_b128 v[96:99], v120 offset:4096
	v_mfma_f32_32x32x16_bf16 v[48:63], v[100:103], v[108:111], v[48:63]
	s_mov_b32 s24, 0x680
	s_add_u32 m0, s31, 0xc000
	v_lshl_add_u64 v[124:125], v[64:65], 0, s[24:25]
	global_load_lds_dwordx4 v[124:125], off
	v_mfma_f32_32x32x16_bf16 v[32:47], v[100:103], v[112:115], v[32:47]
	v_mfma_f32_32x32x16_bf16 v[16:31], v[104:107], v[108:111], v[16:31]
	s_add_u32 m0, s31, 0xe000
	v_lshl_add_u64 v[126:127], v[66:67], 0, s[24:25]
	global_load_lds_dwordx4 v[126:127], off
	v_mfma_f32_32x32x16_bf16 v[0:15], v[104:107], v[112:115], v[0:15]
	ds_read_b128 v[100:103], v117
	ds_read_b128 v[104:107], v117 offset:4096
	ds_read_b128 v[108:111], v121
	ds_read_b128 v[112:115], v121 offset:4096
	s_waitcnt lgkmcnt(4)
	v_mfma_f32_32x32x16_bf16 v[48:63], v[84:87], v[92:95], v[48:63]
	s_add_u32 m0, s31, 0x10000
	v_lshl_add_u64 v[124:125], v[68:69], 0, s[24:25]
	global_load_lds_dwordx4 v[124:125], off
	v_mfma_f32_32x32x16_bf16 v[32:47], v[84:87], v[96:99], v[32:47]
	v_mfma_f32_32x32x16_bf16 v[16:31], v[88:91], v[92:95], v[16:31]
	s_add_u32 m0, s31, 0x12000
	v_lshl_add_u64 v[126:127], v[70:71], 0, s[24:25]
	global_load_lds_dwordx4 v[126:127], off
	v_mfma_f32_32x32x16_bf16 v[0:15], v[88:91], v[96:99], v[0:15]
	ds_read_b128 v[84:87], v118
	ds_read_b128 v[88:91], v118 offset:4096
	ds_read_b128 v[92:95], v122
	ds_read_b128 v[96:99], v122 offset:4096
	s_waitcnt lgkmcnt(4)
	v_mfma_f32_32x32x16_bf16 v[48:63], v[100:103], v[108:111], v[48:63]
	s_add_u32 m0, s31, 0x14000
	v_lshl_add_u64 v[124:125], v[72:73], 0, s[24:25]
	global_load_lds_dwordx4 v[124:125], off
	v_mfma_f32_32x32x16_bf16 v[32:47], v[100:103], v[112:115], v[32:47]
	v_mfma_f32_32x32x16_bf16 v[16:31], v[104:107], v[108:111], v[16:31]
	s_add_u32 m0, s31, 0x16000
	v_lshl_add_u64 v[126:127], v[74:75], 0, s[24:25]
	global_load_lds_dwordx4 v[126:127], off
	v_mfma_f32_32x32x16_bf16 v[0:15], v[104:107], v[112:115], v[0:15]
	ds_read_b128 v[100:103], v119
	ds_read_b128 v[104:107], v119 offset:4096
	ds_read_b128 v[108:111], v123
	ds_read_b128 v[112:115], v123 offset:4096
	s_waitcnt lgkmcnt(4)
	v_mfma_f32_32x32x16_bf16 v[48:63], v[84:87], v[92:95], v[48:63]
	v_mfma_f32_32x32x16_bf16 v[32:47], v[84:87], v[96:99], v[32:47]
	v_mfma_f32_32x32x16_bf16 v[16:31], v[88:91], v[92:95], v[16:31]
	v_mfma_f32_32x32x16_bf16 v[0:15], v[88:91], v[96:99], v[0:15]
	s_waitcnt vmcnt(6) lgkmcnt(0)
	s_barrier
	ds_read_b128 v[84:87], v76
	ds_read_b128 v[88:91], v76 offset:4096
	ds_read_b128 v[92:95], v80
	ds_read_b128 v[96:99], v80 offset:4096
	v_mfma_f32_32x32x16_bf16 v[48:63], v[100:103], v[108:111], v[48:63]
	s_mov_b32 s24, 0x700
	s_add_u32 m0, s31, 0x18000
	v_lshl_add_u64 v[124:125], v[64:65], 0, s[24:25]
	global_load_lds_dwordx4 v[124:125], off
	v_mfma_f32_32x32x16_bf16 v[32:47], v[100:103], v[112:115], v[32:47]
	v_mfma_f32_32x32x16_bf16 v[16:31], v[104:107], v[108:111], v[16:31]
	s_add_u32 m0, s31, 0x1a000
	v_lshl_add_u64 v[126:127], v[66:67], 0, s[24:25]
	global_load_lds_dwordx4 v[126:127], off
	v_mfma_f32_32x32x16_bf16 v[0:15], v[104:107], v[112:115], v[0:15]
	ds_read_b128 v[100:103], v77
	ds_read_b128 v[104:107], v77 offset:4096
	ds_read_b128 v[108:111], v81
	ds_read_b128 v[112:115], v81 offset:4096
	s_waitcnt lgkmcnt(4)
	v_mfma_f32_32x32x16_bf16 v[48:63], v[84:87], v[92:95], v[48:63]
	s_add_u32 m0, s31, 0x1c000
	v_lshl_add_u64 v[124:125], v[68:69], 0, s[24:25]
	global_load_lds_dwordx4 v[124:125], off
	v_mfma_f32_32x32x16_bf16 v[32:47], v[84:87], v[96:99], v[32:47]
	v_mfma_f32_32x32x16_bf16 v[16:31], v[88:91], v[92:95], v[16:31]
	s_add_u32 m0, s31, 0x1e000
	v_lshl_add_u64 v[126:127], v[70:71], 0, s[24:25]
	global_load_lds_dwordx4 v[126:127], off
	v_mfma_f32_32x32x16_bf16 v[0:15], v[88:91], v[96:99], v[0:15]
	ds_read_b128 v[84:87], v78
	ds_read_b128 v[88:91], v78 offset:4096
	ds_read_b128 v[92:95], v82
	ds_read_b128 v[96:99], v82 offset:4096
	s_waitcnt lgkmcnt(4)
	v_mfma_f32_32x32x16_bf16 v[48:63], v[100:103], v[108:111], v[48:63]
	s_add_u32 m0, s31, 0x20000
	v_lshl_add_u64 v[124:125], v[72:73], 0, s[24:25]
	global_load_lds_dwordx4 v[124:125], off
	v_mfma_f32_32x32x16_bf16 v[32:47], v[100:103], v[112:115], v[32:47]
	v_mfma_f32_32x32x16_bf16 v[16:31], v[104:107], v[108:111], v[16:31]
	s_add_u32 m0, s31, 0x22000
	v_lshl_add_u64 v[126:127], v[74:75], 0, s[24:25]
	global_load_lds_dwordx4 v[126:127], off
	v_mfma_f32_32x32x16_bf16 v[0:15], v[104:107], v[112:115], v[0:15]
	ds_read_b128 v[100:103], v79
	ds_read_b128 v[104:107], v79 offset:4096
	ds_read_b128 v[108:111], v83
	ds_read_b128 v[112:115], v83 offset:4096
	s_waitcnt lgkmcnt(4)
	v_mfma_f32_32x32x16_bf16 v[48:63], v[84:87], v[92:95], v[48:63]
	v_mfma_f32_32x32x16_bf16 v[32:47], v[84:87], v[96:99], v[32:47]
	v_mfma_f32_32x32x16_bf16 v[16:31], v[88:91], v[92:95], v[16:31]
	v_mfma_f32_32x32x16_bf16 v[0:15], v[88:91], v[96:99], v[0:15]
	s_waitcnt vmcnt(6) lgkmcnt(0)
	s_barrier
;     ...
;   for (int kt = 0; kt < nk; ++kt) {
;     if (kt + 1 < nk) asm volatile("s_waitcnt vmcnt(6)" ::: "memory");
;     else asm volatile("s_waitcnt vmcnt(0)" ::: "memory");
;     __builtin_amdgcn_s_barrier();
;     asm volatile("" ::: "memory");
;     if (kt + 2 < nk) { const int st2 = (st >= 1) ? st - 1 : 2; GEMM_ISSUE(kt + 2, st2); }
;     const char* la = lds + st * STAGE_B;
;     const char* lb = la + 32768;
;     const unsigned sa_u = (unsigned)(size_t)la + arow_u, sb_u = (unsigned)(size_t)lb + brow_u;
;     const unsigned a0 = sa_u + co0, a1 = sa_u + co1, a2 = sa_u + co2, a3 = sa_u + co3;
;     const unsigned b0 = sb_u + co0, b1 = sb_u + co1, b2 = sb_u + co2, b3 = sb_u + co3;
;     {
;       bf16x8 p0, p1, q0, q1, u0, u1, w0, w1;
;       asm volatile(
;         "ds_read_b128 %4, %12\n\tds_read_b128 %5, %12 offset:4096\n\tds_read_b128 %6, %16\n\tds_read_b128 %7, %16 offset:4096\n\t"
;         "ds_read_b128 %8, %13\n\tds_read_b128 %9, %13 offset:4096\n\tds_read_b128 %10, %17\n\tds_read_b128 %11, %17 offset:4096\n\t"
;         "s_waitcnt lgkmcnt(4)\n\t"
;         "v_mfma_f32_32x32x16_bf16 %0, %4, %6, %0\n\tv_mfma_f32_32x32x16_bf16 %1, %4, %7, %1\n\tv_mfma_f32_32x32x16_bf16 %2, %5, %6, %2\n\tv_mfma_f32_32x32x16_bf16 %3, %5, %7, %3\n\t"
;         "ds_read_b128 %4, %14\n\tds_read_b128 %5, %14 offset:4096\n\tds_read_b128 %6, %18\n\tds_read_b128 %7, %18 offset:4096\n\t"
;         "s_waitcnt lgkmcnt(4)\n\t"
;         "v_mfma_f32_32x32x16_bf16 %0, %8, %10, %0\n\tv_mfma_f32_32x32x16_bf16 %1, %8, %11, %1\n\tv_mfma_f32_32x32x16_bf16 %2, %9, %10, %2\n\tv_mfma_f32_32x32x16_bf16 %3, %9, %11, %3\n\t"
;         "ds_read_b128 %8, %15\n\tds_read_b128 %9, %15 offset:4096\n\tds_read_b128 %10, %19\n\tds_read_b128 %11, %19 offset:4096\n\t"
;         "s_waitcnt lgkmcnt(4)\n\t"
;         "v_mfma_f32_32x32x16_bf16 %0, %4, %6, %0\n\tv_mfma_f32_32x32x16_bf16 %1, %4, %7, %1\n\tv_mfma_f32_32x32x16_bf16 %2, %5, %6, %2\n\tv_mfma_f32_32x32x16_bf16 %3, %5, %7, %3\n\t"
;         "s_waitcnt lgkmcnt(0)\n\t"
;         "v_mfma_f32_32x32x16_bf16 %0, %8, %10, %0\n\tv_mfma_f32_32x32x16_bf16 %1, %8, %11, %1\n\tv_mfma_f32_32x32x16_bf16 %2, %9, %10, %2\n\tv_mfma_f32_32x32x16_bf16 %3, %9, %11, %3"
;         : "+v"(acc[0][0]), "+v"(acc[0][1]), "+v"(acc[1][0]), "+v"(acc[1][1]),
;           "=&v"(p0), "=&v"(p1), "=&v"(q0), "=&v"(q1), "=&v"(u0), "=&v"(u1), "=&v"(w0), "=&v"(w1)
	ds_read_b128 v[84:87], v76 offset:49152
	ds_read_b128 v[88:91], v76 offset:53248
	ds_read_b128 v[92:95], v80 offset:49152
	ds_read_b128 v[96:99], v80 offset:53248
	v_mfma_f32_32x32x16_bf16 v[48:63], v[100:103], v[108:111], v[48:63]
	s_mov_b32 s24, 0x780
	s_mov_b32 m0, s31
	v_lshl_add_u64 v[124:125], v[64:65], 0, s[24:25]
	global_load_lds_dwordx4 v[124:125], off
	v_mfma_f32_32x32x16_bf16 v[32:47], v[100:103], v[112:115], v[32:47]
	v_mfma_f32_32x32x16_bf16 v[16:31], v[104:107], v[108:111], v[16:31]
	s_add_u32 m0, s31, 0x2000
	v_lshl_add_u64 v[126:127], v[66:67], 0, s[24:25]
	global_load_lds_dwordx4 v[126:127], off
	v_mfma_f32_32x32x16_bf16 v[0:15], v[104:107], v[112:115], v[0:15]
	ds_read_b128 v[100:103], v77 offset:49152
	ds_read_b128 v[104:107], v77 offset:53248
	ds_read_b128 v[108:111], v81 offset:49152
	ds_read_b128 v[112:115], v81 offset:53248
	s_waitcnt lgkmcnt(4)
	v_mfma_f32_32x32x16_bf16 v[48:63], v[84:87], v[92:95], v[48:63]
	s_add_u32 m0, s31, 0x4000
	v_lshl_add_u64 v[124:125], v[68:69], 0, s[24:25]
	global_load_lds_dwordx4 v[124:125], off
	v_mfma_f32_32x32x16_bf16 v[32:47], v[84:87], v[96:99], v[32:47]
	v_mfma_f32_32x32x16_bf16 v[16:31], v[88:91], v[92:95], v[16:31]
	s_add_u32 m0, s31, 0x6000
	v_lshl_add_u64 v[126:127], v[70:71], 0, s[24:25]
	global_load_lds_dwordx4 v[126:127], off
	v_mfma_f32_32x32x16_bf16 v[0:15], v[88:91], v[96:99], v[0:15]
	ds_read_b128 v[84:87], v78 offset:49152
	ds_read_b128 v[88:91], v78 offset:53248
	ds_read_b128 v[92:95], v82 offset:49152
	ds_read_b128 v[96:99], v82 offset:53248
	s_waitcnt lgkmcnt(4)
	v_mfma_f32_32x32x16_bf16 v[48:63], v[100:103], v[108:111], v[48:63]
	s_add_u32 m0, s31, 0x8000
	v_lshl_add_u64 v[124:125], v[72:73], 0, s[24:25]
	global_load_lds_dwordx4 v[124:125], off
	v_mfma_f32_32x32x16_bf16 v[32:47], v[100:103], v[112:115], v[32:47]
	v_mfma_f32_32x32x16_bf16 v[16:31], v[104:107], v[108:111], v[16:31]
	s_add_u32 m0, s31, 0xa000
	v_lshl_add_u64 v[126:127], v[74:75], 0, s[24:25]
	global_load_lds_dwordx4 v[126:127], off
	v_mfma_f32_32x32x16_bf16 v[0:15], v[104:107], v[112:115], v[0:15]
	ds_read_b128 v[100:103], v79 offset:49152
	ds_read_b128 v[104:107], v79 offset:53248
	ds_read_b128 v[108:111], v83 offset:49152
	ds_read_b128 v[112:115], v83 offset:53248
	s_waitcnt lgkmcnt(4)
	v_mfma_f32_32x32x16_bf16 v[48:63], v[84:87], v[92:95], v[48:63]
	v_mfma_f32_32x32x16_bf16 v[32:47], v[84:87], v[96:99], v[32:47]
	v_mfma_f32_32x32x16_bf16 v[16:31], v[88:91], v[92:95], v[16:31]
	v_mfma_f32_32x32x16_bf16 v[0:15], v[88:91], v[96:99], v[0:15]
	s_waitcnt vmcnt(6) lgkmcnt(0)
	s_barrier
	ds_read_b128 v[84:87], v116
	ds_read_b128 v[88:91], v116 offset:4096
	ds_read_b128 v[92:95], v120
	ds_read_b128 v[96:99], v120 offset:4096
	v_mfma_f32_32x32x16_bf16 v[48:63], v[100:103], v[108:111], v[48:63]
	v_mfma_f32_32x32x16_bf16 v[32:47], v[100:103], v[112:115], v[32:47]
	v_mfma_f32_32x32x16_bf16 v[16:31], v[104:107], v[108:111], v[16:31]
	v_mfma_f32_32x32x16_bf16 v[0:15], v[104:107], v[112:115], v[0:15]
	ds_read_b128 v[100:103], v117
	ds_read_b128 v[104:107], v117 offset:4096
	ds_read_b128 v[108:111], v121
	ds_read_b128 v[112:115], v121 offset:4096
	s_waitcnt lgkmcnt(4)
	v_mfma_f32_32x32x16_bf16 v[48:63], v[84:87], v[92:95], v[48:63]
	v_mfma_f32_32x32x16_bf16 v[32:47], v[84:87], v[96:99], v[32:47]
	v_mfma_f32_32x32x16_bf16 v[16:31], v[88:91], v[92:95], v[16:31]
	v_mfma_f32_32x32x16_bf16 v[0:15], v[88:91], v[96:99], v[0:15]
	ds_read_b128 v[84:87], v118
	ds_read_b128 v[88:91], v118 offset:4096
	ds_read_b128 v[92:95], v122
	ds_read_b128 v[96:99], v122 offset:4096
	s_waitcnt lgkmcnt(4)
	v_mfma_f32_32x32x16_bf16 v[48:63], v[100:103], v[108:111], v[48:63]
	v_mfma_f32_32x32x16_bf16 v[32:47], v[100:103], v[112:115], v[32:47]
	v_mfma_f32_32x32x16_bf16 v[16:31], v[104:107], v[108:111], v[16:31]
	v_mfma_f32_32x32x16_bf16 v[0:15], v[104:107], v[112:115], v[0:15]
	ds_read_b128 v[100:103], v119
	ds_read_b128 v[104:107], v119 offset:4096
	ds_read_b128 v[108:111], v123
	ds_read_b128 v[112:115], v123 offset:4096
	s_waitcnt lgkmcnt(4)
	v_mfma_f32_32x32x16_bf16 v[48:63], v[84:87], v[92:95], v[48:63]
	v_mfma_f32_32x32x16_bf16 v[32:47], v[84:87], v[96:99], v[32:47]
	v_mfma_f32_32x32x16_bf16 v[16:31], v[88:91], v[92:95], v[16:31]
	v_mfma_f32_32x32x16_bf16 v[0:15], v[88:91], v[96:99], v[0:15]
	s_waitcnt vmcnt(0) lgkmcnt(0)
	s_barrier
	ds_read_b128 v[84:87], v76
	ds_read_b128 v[88:91], v76 offset:4096
	ds_read_b128 v[92:95], v80
	ds_read_b128 v[96:99], v80 offset:4096
	v_mfma_f32_32x32x16_bf16 v[48:63], v[100:103], v[108:111], v[48:63]
	v_mfma_f32_32x32x16_bf16 v[32:47], v[100:103], v[112:115], v[32:47]
	v_mfma_f32_32x32x16_bf16 v[16:31], v[104:107], v[108:111], v[16:31]
	v_mfma_f32_32x32x16_bf16 v[0:15], v[104:107], v[112:115], v[0:15]
	ds_read_b128 v[100:103], v77
	ds_read_b128 v[104:107], v77 offset:4096
	ds_read_b128 v[108:111], v81
	ds_read_b128 v[112:115], v81 offset:4096
	s_waitcnt lgkmcnt(4)
	v_mfma_f32_32x32x16_bf16 v[48:63], v[84:87], v[92:95], v[48:63]
	v_mfma_f32_32x32x16_bf16 v[32:47], v[84:87], v[96:99], v[32:47]
	v_mfma_f32_32x32x16_bf16 v[16:31], v[88:91], v[92:95], v[16:31]
	v_mfma_f32_32x32x16_bf16 v[0:15], v[88:91], v[96:99], v[0:15]
	ds_read_b128 v[84:87], v78
	ds_read_b128 v[88:91], v78 offset:4096
	ds_read_b128 v[92:95], v82
	ds_read_b128 v[96:99], v82 offset:4096
	s_waitcnt lgkmcnt(4)
	v_mfma_f32_32x32x16_bf16 v[48:63], v[100:103], v[108:111], v[48:63]
	v_mfma_f32_32x32x16_bf16 v[32:47], v[100:103], v[112:115], v[32:47]
	v_mfma_f32_32x32x16_bf16 v[16:31], v[104:107], v[108:111], v[16:31]
	v_mfma_f32_32x32x16_bf16 v[0:15], v[104:107], v[112:115], v[0:15]
	ds_read_b128 v[100:103], v79
	ds_read_b128 v[104:107], v79 offset:4096
	ds_read_b128 v[108:111], v83
	ds_read_b128 v[112:115], v83 offset:4096
	s_waitcnt lgkmcnt(4)
	v_mfma_f32_32x32x16_bf16 v[48:63], v[84:87], v[92:95], v[48:63]
	v_mfma_f32_32x32x16_bf16 v[32:47], v[84:87], v[96:99], v[32:47]
	v_mfma_f32_32x32x16_bf16 v[16:31], v[88:91], v[92:95], v[16:31]
	v_mfma_f32_32x32x16_bf16 v[0:15], v[88:91], v[96:99], v[0:15]
	s_waitcnt lgkmcnt(0)
	v_mfma_f32_32x32x16_bf16 v[48:63], v[100:103], v[108:111], v[48:63]
	v_mfma_f32_32x32x16_bf16 v[32:47], v[100:103], v[112:115], v[32:47]
	v_mfma_f32_32x32x16_bf16 v[16:31], v[104:107], v[108:111], v[16:31]
	v_mfma_f32_32x32x16_bf16 v[0:15], v[104:107], v[112:115], v[0:15]
	s_add_i32 s23, s33, s23
	s_mov_b32 s53, 0x8000
	s_nop 15
	s_nop 15
	s_nop 7
	s_barrier
	s_cmpk_gt_i32 s23, 0xc7f
	s_cbranch_scc0 .LBB0_222

;   const int tid = TIDX, lane = tid & 63, wid = tid >> 6, wr = wid >> 1, wc = wid & 1, r = lane & 31, h = lane >> 5;
;   const int ch = (tid & 7) ^ ((tid >> 4) & 7);
;   unsigned avo[4], bvo[2];
; #pragma unroll
;   for (int i = 0; i < 4; ++i) avo[i] = (unsigned)(((tid >> 3) + 64 * i) * lda * 2 + ch * 16);
; #pragma unroll
;   for (int i = 0; i < 2; ++i) bvo[i] = (unsigned)(((tid >> 3) + 64 * i) * ldb * 2 + ch * 16);
;   const char* Ab = (const char*)A; const char* Bb = (const char*)Bt;
;   char* lw = lds + tid * 16;
;   const int nk = K >> 6;
;   const unsigned swz = (unsigned)((r >> 1) & 7);
;   const unsigned arow_u = (unsigned)((wr * 64 + r) * 128), brow_u = (unsigned)((wc * 64 + r) * 128);
;   const unsigned co0 = ((0u + h) ^ swz) << 4, co1 = ((2u + h) ^ swz) << 4, co2 = ((4u + h) ^ swz) << 4, co3 = ((6u + h) ^ swz) << 4;
;     ...
;   if (PART != 2) {
;     GEMM_ISSUE(0, 0);
;     if (nk > 1) GEMM_ISSUE(1, 1);
;   }
;   if (PART == 1) return;
;   int st = 0;
;   for (int kt = 0; kt < nk; ++kt) {
;     if (kt + 1 < nk) asm volatile("s_waitcnt vmcnt(6)" ::: "memory");
;     else asm volatile("s_waitcnt vmcnt(0)" ::: "memory");
;     __builtin_amdgcn_s_barrier();
;     asm volatile("" ::: "memory");
;     if (kt + 2 < nk) { const int st2 = (st >= 1) ? st - 1 : 2; GEMM_ISSUE(kt + 2, st2); }
;     const char* la = lds + st * STAGE_B;
;     const char* lb = la + 32768;
;     const unsigned sa_u = (unsigned)(size_t)la + arow_u, sb_u = (unsigned)(size_t)lb + brow_u;
;     const unsigned a0 = sa_u + co0, a1 = sa_u + co1, a2 = sa_u + co2, a3 = sa_u + co3;
;     const unsigned b0 = sb_u + co0, b1 = sb_u + co1, b2 = sb_u + co2, b3 = sb_u + co3;
;     {
;       bf16x8 p0, p1, q0, q1, u0, u1, w0, w1;
;       asm volatile(
;         "ds_read_b128 %4, %12\n\tds_read_b128 %5, %12 offset:4096\n\tds_read_b128 %6, %16\n\tds_read_b128 %7, %16 offset:4096\n\t"
;         "ds_read_b128 %8, %13\n\tds_read_b128 %9, %13 offset:4096\n\tds_read_b128 %10, %17\n\tds_read_b128 %11, %17 offset:4096\n\t"
;         "s_waitcnt lgkmcnt(4)\n\t"
;         "v_mfma_f32_32x32x16_bf16 %0, %4, %6, %0\n\tv_mfma_f32_32x32x16_bf16 %1, %4, %7, %1\n\tv_mfma_f32_32x32x16_bf16 %2, %5, %6, %2\n\tv_mfma_f32_32x32x16_bf16 %3, %5, %7, %3\n\t"
;         "ds_read_b128 %4, %14\n\tds_read_b128 %5, %14 offset:4096\n\tds_read_b128 %6, %18\n\tds_read_b128 %7, %18 offset:4096\n\t"
;         "s_waitcnt lgkmcnt(4)\n\t"
.LBB0_723:
	v_and_b32_e32 v164, 31, v129
	v_bfe_u32 v165, v129, 5, 1
	v_lshrrev_b32_e32 v166, 6, v129
	v_bfe_u32 v168, v129, 1, 3
	v_lshrrev_b32_e32 v167, 1, v166
	v_and_b32_e32 v166, 1, v166
	v_xor_b32_e32 v165, v165, v168
	v_lshl_add_u32 v167, v167, 6, v164
	v_lshl_add_u32 v166, v166, 6, v164
	v_lshlrev_b32_e32 v165, 4, v165
	v_lshlrev_b32_e32 v167, 7, v167
	v_lshlrev_b32_e32 v166, 7, v166
	v_add_u32_e32 v166, 0x8000, v166
	v_add_u32_e32 v76, v167, v165
	v_add_u32_e32 v80, v166, v165
	v_xor_b32_e32 v169, 0x20, v165
	v_add_u32_e32 v77, v167, v169
	v_add_u32_e32 v81, v166, v169
	v_xor_b32_e32 v169, 0x40, v165
	v_add_u32_e32 v78, v167, v169
	v_add_u32_e32 v82, v166, v169
	v_xor_b32_e32 v169, 0x60, v165
	v_add_u32_e32 v79, v167, v169
	v_add_u32_e32 v83, v166, v169
	v_add_u32_e32 v84, 0x18000, v76
	v_add_u32_e32 v156, 0x18000, v80
	v_add_u32_e32 v85, 0x18000, v77
	v_add_u32_e32 v157, 0x18000, v81
	v_add_u32_e32 v86, 0x18000, v78
	v_add_u32_e32 v158, 0x18000, v82
	v_add_u32_e32 v87, 0x18000, v79
	v_add_u32_e32 v159, 0x18000, v83
	v_lshlrev_b32_e32 v164, 4, v129
	s_nop 0
	v_readfirstlane_b32 s26, v164
	s_mov_b32 s11, 0
	s_waitcnt vmcnt(63)
	s_barrier
	ds_read_b128 v[164:167], v76
	ds_read_b128 v[168:171], v76 offset:4096
	ds_read_b128 v[172:175], v80
	ds_read_b128 v[176:179], v80 offset:4096
	s_mov_b32 s10, 0xa5c2100
	s_add_u32 m0, s26, 0x18000
	v_lshl_add_u64 v[160:161], v[74:75], 0, s[10:11]
	global_load_lds_dwordx4 v[160:161], off
	s_add_u32 m0, s26, 0x1a000
	v_lshl_add_u64 v[162:163], v[72:73], 0, s[10:11]
	global_load_lds_dwordx4 v[162:163], off
	ds_read_b128 v[180:183], v77
	ds_read_b128 v[184:187], v77 offset:4096
	ds_read_b128 v[218:221], v81
	ds_read_b128 v[222:225], v81 offset:4096
	s_waitcnt lgkmcnt(4)
	v_mfma_f32_32x32x16_bf16 v[48:63], v[164:167], v[172:175], v[48:63]
	s_add_u32 m0, s26, 0x1c000
	v_lshl_add_u64 v[160:161], v[70:71], 0, s[10:11]
	global_load_lds_dwordx4 v[160:161], off
	v_mfma_f32_32x32x16_bf16 v[32:47], v[164:167], v[176:179], v[32:47]
	v_mfma_f32_32x32x16_bf16 v[16:31], v[168:171], v[172:175], v[16:31]
	s_add_u32 m0, s26, 0x1e000
	v_lshl_add_u64 v[162:163], v[68:69], 0, s[10:11]
	global_load_lds_dwordx4 v[162:163], off
	v_mfma_f32_32x32x16_bf16 v[0:15], v[168:171], v[176:179], v[0:15]
	ds_read_b128 v[164:167], v78
	ds_read_b128 v[168:171], v78 offset:4096
	ds_read_b128 v[172:175], v82
	ds_read_b128 v[176:179], v82 offset:4096
	s_waitcnt lgkmcnt(4)
	v_mfma_f32_32x32x16_bf16 v[48:63], v[180:183], v[218:221], v[48:63]
	s_mov_b32 s10, 0xb00100
	s_add_u32 m0, s26, 0x20000
	v_lshl_add_u64 v[160:161], v[66:67], 0, s[10:11]
	global_load_lds_dwordx4 v[160:161], off
	v_mfma_f32_32x32x16_bf16 v[32:47], v[180:183], v[222:225], v[32:47]
	v_mfma_f32_32x32x16_bf16 v[16:31], v[184:187], v[218:221], v[16:31]
	s_add_u32 m0, s26, 0x22000
	v_lshl_add_u64 v[162:163], v[64:65], 0, s[10:11]
	global_load_lds_dwordx4 v[162:163], off
	v_mfma_f32_32x32x16_bf16 v[0:15], v[184:187], v[222:225], v[0:15]
	ds_read_b128 v[180:183], v79
	ds_read_b128 v[184:187], v79 offset:4096
	ds_read_b128 v[218:221], v83
	ds_read_b128 v[222:225], v83 offset:4096
	s_waitcnt lgkmcnt(4)
	v_mfma_f32_32x32x16_bf16 v[48:63], v[164:167], v[172:175], v[48:63]
	v_mfma_f32_32x32x16_bf16 v[32:47], v[164:167], v[176:179], v[32:47]
	v_mfma_f32_32x32x16_bf16 v[16:31], v[168:171], v[172:175], v[16:31]
	v_mfma_f32_32x32x16_bf16 v[0:15], v[168:171], v[176:179], v[0:15]
	s_waitcnt vmcnt(63) lgkmcnt(0)
	s_barrier
	ds_read_b128 v[164:167], v76 offset:49152
	ds_read_b128 v[168:171], v76 offset:53248
	ds_read_b128 v[172:175], v80 offset:49152
	ds_read_b128 v[176:179], v80 offset:53248
	v_mfma_f32_32x32x16_bf16 v[48:63], v[180:183], v[218:221], v[48:63]
	s_mov_b32 s10, 0xa5c2180
	s_mov_b32 m0, s26
	v_lshl_add_u64 v[160:161], v[74:75], 0, s[10:11]
	global_load_lds_dwordx4 v[160:161], off
	v_mfma_f32_32x32x16_bf16 v[32:47], v[180:183], v[222:225], v[32:47]
	v_mfma_f32_32x32x16_bf16 v[16:31], v[184:187], v[218:221], v[16:31]
	s_add_u32 m0, s26, 0x2000
	v_lshl_add_u64 v[162:163], v[72:73], 0, s[10:11]
	global_load_lds_dwordx4 v[162:163], off
	v_mfma_f32_32x32x16_bf16 v[0:15], v[184:187], v[222:225], v[0:15]
	ds_read_b128 v[180:183], v77 offset:49152
	ds_read_b128 v[184:187], v77 offset:53248
	ds_read_b128 v[218:221], v81 offset:49152
	ds_read_b128 v[222:225], v81 offset:53248
	s_waitcnt lgkmcnt(4)
	v_mfma_f32_32x32x16_bf16 v[48:63], v[164:167], v[172:175], v[48:63]
	s_add_u32 m0, s26, 0x4000
	v_lshl_add_u64 v[160:161], v[70:71], 0, s[10:11]
	global_load_lds_dwordx4 v[160:161], off
	v_mfma_f32_32x32x16_bf16 v[32:47], v[164:167], v[176:179], v[32:47]
	v_mfma_f32_32x32x16_bf16 v[16:31], v[168:171], v[172:175], v[16:31]
	s_add_u32 m0, s26, 0x6000
	v_lshl_add_u64 v[162:163], v[68:69], 0, s[10:11]
	global_load_lds_dwordx4 v[162:163], off
	v_mfma_f32_32x32x16_bf16 v[0:15], v[168:171], v[176:179], v[0:15]
	ds_read_b128 v[164:167], v78 offset:49152
	ds_read_b128 v[168:171], v78 offset:53248
	ds_read_b128 v[172:175], v82 offset:49152
	ds_read_b128 v[176:179], v82 offset:53248
	s_waitcnt lgkmcnt(4)
	v_mfma_f32_32x32x16_bf16 v[48:63], v[180:183], v[218:221], v[48:63]
	s_mov_b32 s10, 0xb00180
	s_add_u32 m0, s26, 0x8000
	v_lshl_add_u64 v[160:161], v[66:67], 0, s[10:11]
	global_load_lds_dwordx4 v[160:161], off
	v_mfma_f32_32x32x16_bf16 v[32:47], v[180:183], v[222:225], v[32:47]
	v_mfma_f32_32x32x16_bf16 v[16:31], v[184:187], v[218:221], v[16:31]
	s_add_u32 m0, s26, 0xa000
	v_lshl_add_u64 v[162:163], v[64:65], 0, s[10:11]
	global_load_lds_dwordx4 v[162:163], off
	v_mfma_f32_32x32x16_bf16 v[0:15], v[184:187], v[222:225], v[0:15]
	ds_read_b128 v[180:183], v79 offset:49152
	ds_read_b128 v[184:187], v79 offset:53248
	ds_read_b128 v[218:221], v83 offset:49152
	ds_read_b128 v[222:225], v83 offset:53248
	s_waitcnt lgkmcnt(4)
	v_mfma_f32_32x32x16_bf16 v[48:63], v[164:167], v[172:175], v[48:63]
	v_mfma_f32_32x32x16_bf16 v[32:47], v[164:167], v[176:179], v[32:47]
	v_mfma_f32_32x32x16_bf16 v[16:31], v[168:171], v[172:175], v[16:31]
	v_mfma_f32_32x32x16_bf16 v[0:15], v[168:171], v[176:179], v[0:15]
	s_waitcnt vmcnt(6) lgkmcnt(0)
	s_barrier
;     ...
;   for (int kt = 0; kt < nk; ++kt) {
;     if (kt + 1 < nk) asm volatile("s_waitcnt vmcnt(6)" ::: "memory");
;     else asm volatile("s_waitcnt vmcnt(0)" ::: "memory");
;     __builtin_amdgcn_s_barrier();
;     asm volatile("" ::: "memory");
;     if (kt + 2 < nk) { const int st2 = (st >= 1) ? st - 1 : 2; GEMM_ISSUE(kt + 2, st2); }
;     const char* la = lds + st * STAGE_B;
;     const char* lb = la + 32768;
;     const unsigned sa_u = (unsigned)(size_t)la + arow_u, sb_u = (unsigned)(size_t)lb + brow_u;
;     const unsigned a0 = sa_u + co0, a1 = sa_u + co1, a2 = sa_u + co2, a3 = sa_u + co3;
;     const unsigned b0 = sb_u + co0, b1 = sb_u + co1, b2 = sb_u + co2, b3 = sb_u + co3;
;     {
;       bf16x8 p0, p1, q0, q1, u0, u1, w0, w1;
;       asm volatile(
;         "ds_read_b128 %4, %12\n\tds_read_b128 %5, %12 offset:4096\n\tds_read_b128 %6, %16\n\tds_read_b128 %7, %16 offset:4096\n\t"
;         "ds_read_b128 %8, %13\n\tds_read_b128 %9, %13 offset:4096\n\tds_read_b128 %10, %17\n\tds_read_b128 %11, %17 offset:4096\n\t"
;         "s_waitcnt lgkmcnt(4)\n\t"
;         "v_mfma_f32_32x32x16_bf16 %0, %4, %6, %0\n\tv_mfma_f32_32x32x16_bf16 %1, %4, %7, %1\n\tv_mfma_f32_32x32x16_bf16 %2, %5, %6, %2\n\tv_mfma_f32_32x32x16_bf16 %3, %5, %7, %3\n\t"
;         "ds_read_b128 %4, %14\n\tds_read_b128 %5, %14 offset:4096\n\tds_read_b128 %6, %18\n\tds_read_b128 %7, %18 offset:4096\n\t"
;         "s_waitcnt lgkmcnt(4)\n\t"
;         "v_mfma_f32_32x32x16_bf16 %0, %8, %10, %0\n\tv_mfma_f32_32x32x16_bf16 %1, %8, %11, %1\n\tv_mfma_f32_32x32x16_bf16 %2, %9, %10, %2\n\tv_mfma_f32_32x32x16_bf16 %3, %9, %11, %3\n\t"
;         "ds_read_b128 %8, %15\n\tds_read_b128 %9, %15 offset:4096\n\tds_read_b128 %10, %19\n\tds_read_b128 %11, %19 offset:4096\n\t"
;         "s_waitcnt lgkmcnt(4)\n\t"
;         "v_mfma_f32_32x32x16_bf16 %0, %4, %6, %0\n\tv_mfma_f32_32x32x16_bf16 %1, %4, %7, %1\n\tv_mfma_f32_32x32x16_bf16 %2, %5, %6, %2\n\tv_mfma_f32_32x32x16_bf16 %3, %5, %7, %3\n\t"
;         "s_waitcnt lgkmcnt(0)\n\t"
;         "v_mfma_f32_32x32x16_bf16 %0, %8, %10, %0\n\tv_mfma_f32_32x32x16_bf16 %1, %8, %11, %1\n\tv_mfma_f32_32x32x16_bf16 %2, %9, %10, %2\n\tv_mfma_f32_32x32x16_bf16 %3, %9, %11, %3"
;         : "+v"(acc[0][0]), "+v"(acc[0][1]), "+v"(acc[1][0]), "+v"(acc[1][1]),
;           "=&v"(p0), "=&v"(p1), "=&v"(q0), "=&v"(q1), "=&v"(u0), "=&v"(u1), "=&v"(w0), "=&v"(w1)
	ds_read_b128 v[164:167], v84
	ds_read_b128 v[168:171], v84 offset:4096
	ds_read_b128 v[172:175], v156
	ds_read_b128 v[176:179], v156 offset:4096
	v_mfma_f32_32x32x16_bf16 v[48:63], v[180:183], v[218:221], v[48:63]
	s_mov_b32 s10, 0xa5c2200
	s_add_u32 m0, s26, 0xc000
	v_lshl_add_u64 v[160:161], v[74:75], 0, s[10:11]
	global_load_lds_dwordx4 v[160:161], off
	v_mfma_f32_32x32x16_bf16 v[32:47], v[180:183], v[222:225], v[32:47]
	v_mfma_f32_32x32x16_bf16 v[16:31], v[184:187], v[218:221], v[16:31]
	s_add_u32 m0, s26, 0xe000
	v_lshl_add_u64 v[162:163], v[72:73], 0, s[10:11]
	global_load_lds_dwordx4 v[162:163], off
	v_mfma_f32_32x32x16_bf16 v[0:15], v[184:187], v[222:225], v[0:15]
	ds_read_b128 v[180:183], v85
	ds_read_b128 v[184:187], v85 offset:4096
	ds_read_b128 v[218:221], v157
	ds_read_b128 v[222:225], v157 offset:4096
	s_waitcnt lgkmcnt(4)
	v_mfma_f32_32x32x16_bf16 v[48:63], v[164:167], v[172:175], v[48:63]
	s_add_u32 m0, s26, 0x10000
	v_lshl_add_u64 v[160:161], v[70:71], 0, s[10:11]
	global_load_lds_dwordx4 v[160:161], off
	v_mfma_f32_32x32x16_bf16 v[32:47], v[164:167], v[176:179], v[32:47]
	v_mfma_f32_32x32x16_bf16 v[16:31], v[168:171], v[172:175], v[16:31]
	s_add_u32 m0, s26, 0x12000
	v_lshl_add_u64 v[162:163], v[68:69], 0, s[10:11]
	global_load_lds_dwordx4 v[162:163], off
	v_mfma_f32_32x32x16_bf16 v[0:15], v[168:171], v[176:179], v[0:15]
	ds_read_b128 v[164:167], v86
	ds_read_b128 v[168:171], v86 offset:4096
	ds_read_b128 v[172:175], v158
	ds_read_b128 v[176:179], v158 offset:4096
	s_waitcnt lgkmcnt(4)
	v_mfma_f32_32x32x16_bf16 v[48:63], v[180:183], v[218:221], v[48:63]
	s_mov_b32 s10, 0xb00200
	s_add_u32 m0, s26, 0x14000
	v_lshl_add_u64 v[160:161], v[66:67], 0, s[10:11]
	global_load_lds_dwordx4 v[160:161], off
	v_mfma_f32_32x32x16_bf16 v[32:47], v[180:183], v[222:225], v[32:47]
	v_mfma_f32_32x32x16_bf16 v[16:31], v[184:187], v[218:221], v[16:31]
	s_add_u32 m0, s26, 0x16000
	v_lshl_add_u64 v[162:163], v[64:65], 0, s[10:11]
	global_load_lds_dwordx4 v[162:163], off
	v_mfma_f32_32x32x16_bf16 v[0:15], v[184:187], v[222:225], v[0:15]
	ds_read_b128 v[180:183], v87
	ds_read_b128 v[184:187], v87 offset:4096
	ds_read_b128 v[218:221], v159
	ds_read_b128 v[222:225], v159 offset:4096
	s_waitcnt lgkmcnt(4)
	v_mfma_f32_32x32x16_bf16 v[48:63], v[164:167], v[172:175], v[48:63]
	v_mfma_f32_32x32x16_bf16 v[32:47], v[164:167], v[176:179], v[32:47]
	v_mfma_f32_32x32x16_bf16 v[16:31], v[168:171], v[172:175], v[16:31]
	v_mfma_f32_32x32x16_bf16 v[0:15], v[168:171], v[176:179], v[0:15]
	s_waitcnt vmcnt(6) lgkmcnt(0)
	s_barrier
	ds_read_b128 v[164:167], v76
	ds_read_b128 v[168:171], v76 offset:4096
	ds_read_b128 v[172:175], v80
	ds_read_b128 v[176:179], v80 offset:4096
	v_mfma_f32_32x32x16_bf16 v[48:63], v[180:183], v[218:221], v[48:63]
	s_mov_b32 s10, 0xa5c2280
	s_add_u32 m0, s26, 0x18000
	v_lshl_add_u64 v[160:161], v[74:75], 0, s[10:11]
	global_load_lds_dwordx4 v[160:161], off
	v_mfma_f32_32x32x16_bf16 v[32:47], v[180:183], v[222:225], v[32:47]
	v_mfma_f32_32x32x16_bf16 v[16:31], v[184:187], v[218:221], v[16:31]
	s_add_u32 m0, s26, 0x1a000
	v_lshl_add_u64 v[162:163], v[72:73], 0, s[10:11]
	global_load_lds_dwordx4 v[162:163], off
	v_mfma_f32_32x32x16_bf16 v[0:15], v[184:187], v[222:225], v[0:15]
	ds_read_b128 v[180:183], v77
	ds_read_b128 v[184:187], v77 offset:4096
	ds_read_b128 v[218:221], v81
	ds_read_b128 v[222:225], v81 offset:4096
	s_waitcnt lgkmcnt(4)
	v_mfma_f32_32x32x16_bf16 v[48:63], v[164:167], v[172:175], v[48:63]
	s_add_u32 m0, s26, 0x1c000
	v_lshl_add_u64 v[160:161], v[70:71], 0, s[10:11]
	global_load_lds_dwordx4 v[160:161], off
	v_mfma_f32_32x32x16_bf16 v[32:47], v[164:167], v[176:179], v[32:47]
	v_mfma_f32_32x32x16_bf16 v[16:31], v[168:171], v[172:175], v[16:31]
	s_add_u32 m0, s26, 0x1e000
	v_lshl_add_u64 v[162:163], v[68:69], 0, s[10:11]
	global_load_lds_dwordx4 v[162:163], off
	v_mfma_f32_32x32x16_bf16 v[0:15], v[168:171], v[176:179], v[0:15]
	ds_read_b128 v[164:167], v78
	ds_read_b128 v[168:171], v78 offset:4096
	ds_read_b128 v[172:175], v82
	ds_read_b128 v[176:179], v82 offset:4096
	s_waitcnt lgkmcnt(4)
	v_mfma_f32_32x32x16_bf16 v[48:63], v[180:183], v[218:221], v[48:63]
	s_mov_b32 s10, 0xb00280
	s_add_u32 m0, s26, 0x20000
	v_lshl_add_u64 v[160:161], v[66:67], 0, s[10:11]
	global_load_lds_dwordx4 v[160:161], off
	v_mfma_f32_32x32x16_bf16 v[32:47], v[180:183], v[222:225], v[32:47]
	v_mfma_f32_32x32x16_bf16 v[16:31], v[184:187], v[218:221], v[16:31]
	s_add_u32 m0, s26, 0x22000
	v_lshl_add_u64 v[162:163], v[64:65], 0, s[10:11]
	global_load_lds_dwordx4 v[162:163], off
	v_mfma_f32_32x32x16_bf16 v[0:15], v[184:187], v[222:225], v[0:15]
	ds_read_b128 v[180:183], v79
	ds_read_b128 v[184:187], v79 offset:4096
	ds_read_b128 v[218:221], v83
	ds_read_b128 v[222:225], v83 offset:4096
	s_waitcnt lgkmcnt(4)
	v_mfma_f32_32x32x16_bf16 v[48:63], v[164:167], v[172:175], v[48:63]
	v_mfma_f32_32x32x16_bf16 v[32:47], v[164:167], v[176:179], v[32:47]
	v_mfma_f32_32x32x16_bf16 v[16:31], v[168:171], v[172:175], v[16:31]
	v_mfma_f32_32x32x16_bf16 v[0:15], v[168:171], v[176:179], v[0:15]
	s_waitcnt vmcnt(6) lgkmcnt(0)
	s_barrier
;     ...
;   for (int kt = 0; kt < nk; ++kt) {
;     if (kt + 1 < nk) asm volatile("s_waitcnt vmcnt(6)" ::: "memory");
;     else asm volatile("s_waitcnt vmcnt(0)" ::: "memory");
;     __builtin_amdgcn_s_barrier();
;     asm volatile("" ::: "memory");
;     if (kt + 2 < nk) { const int st2 = (st >= 1) ? st - 1 : 2; GEMM_ISSUE(kt + 2, st2); }
;     const char* la = lds + st * STAGE_B;
;     const char* lb = la + 32768;
;     const unsigned sa_u = (unsigned)(size_t)la + arow_u, sb_u = (unsigned)(size_t)lb + brow_u;
;     const unsigned a0 = sa_u + co0, a1 = sa_u + co1, a2 = sa_u + co2, a3 = sa_u + co3;
;     const unsigned b0 = sb_u + co0, b1 = sb_u + co1, b2 = sb_u + co2, b3 = sb_u + co3;
;     {
;       bf16x8 p0, p1, q0, q1, u0, u1, w0, w1;
;       asm volatile(
;         "ds_read_b128 %4, %12\n\tds_read_b128 %5, %12 offset:4096\n\tds_read_b128 %6, %16\n\tds_read_b128 %7, %16 offset:4096\n\t"
;         "ds_read_b128 %8, %13\n\tds_read_b128 %9, %13 offset:4096\n\tds_read_b128 %10, %17\n\tds_read_b128 %11, %17 offset:4096\n\t"
;         "s_waitcnt lgkmcnt(4)\n\t"
;         "v_mfma_f32_32x32x16_bf16 %0, %4, %6, %0\n\tv_mfma_f32_32x32x16_bf16 %1, %4, %7, %1\n\tv_mfma_f32_32x32x16_bf16 %2, %5, %6, %2\n\tv_mfma_f32_32x32x16_bf16 %3, %5, %7, %3\n\t"
;         "ds_read_b128 %4, %14\n\tds_read_b128 %5, %14 offset:4096\n\tds_read_b128 %6, %18\n\tds_read_b128 %7, %18 offset:4096\n\t"
;         "s_waitcnt lgkmcnt(4)\n\t"
;         "v_mfma_f32_32x32x16_bf16 %0, %8, %10, %0\n\tv_mfma_f32_32x32x16_bf16 %1, %8, %11, %1\n\tv_mfma_f32_32x32x16_bf16 %2, %9, %10, %2\n\tv_mfma_f32_32x32x16_bf16 %3, %9, %11, %3\n\t"
;         "ds_read_b128 %8, %15\n\tds_read_b128 %9, %15 offset:4096\n\tds_read_b128 %10, %19\n\tds_read_b128 %11, %19 offset:4096\n\t"
;         "s_waitcnt lgkmcnt(4)\n\t"
;         "v_mfma_f32_32x32x16_bf16 %0, %4, %6, %0\n\tv_mfma_f32_32x32x16_bf16 %1, %4, %7, %1\n\tv_mfma_f32_32x32x16_bf16 %2, %5, %6, %2\n\tv_mfma_f32_32x32x16_bf16 %3, %5, %7, %3\n\t"
;         "s_waitcnt lgkmcnt(0)\n\t"
;         "v_mfma_f32_32x32x16_bf16 %0, %8, %10, %0\n\tv_mfma_f32_32x32x16_bf16 %1, %8, %11, %1\n\tv_mfma_f32_32x32x16_bf16 %2, %9, %10, %2\n\tv_mfma_f32_32x32x16_bf16 %3, %9, %11, %3"
;         : "+v"(acc[0][0]), "+v"(acc[0][1]), "+v"(acc[1][0]), "+v"(acc[1][1]),
;           "=&v"(p0), "=&v"(p1), "=&v"(q0), "=&v"(q1), "=&v"(u0), "=&v"(u1), "=&v"(w0), "=&v"(w1)
	ds_read_b128 v[164:167], v76 offset:49152
	ds_read_b128 v[168:171], v76 offset:53248
	ds_read_b128 v[172:175], v80 offset:49152
	ds_read_b128 v[176:179], v80 offset:53248
	v_mfma_f32_32x32x16_bf16 v[48:63], v[180:183], v[218:221], v[48:63]
	s_mov_b32 s10, 0xa5c2300
	s_mov_b32 m0, s26
	v_lshl_add_u64 v[160:161], v[74:75], 0, s[10:11]
	global_load_lds_dwordx4 v[160:161], off
	v_mfma_f32_32x32x16_bf16 v[32:47], v[180:183], v[222:225], v[32:47]
	v_mfma_f32_32x32x16_bf16 v[16:31], v[184:187], v[218:221], v[16:31]
	s_add_u32 m0, s26, 0x2000
	v_lshl_add_u64 v[162:163], v[72:73], 0, s[10:11]
	global_load_lds_dwordx4 v[162:163], off
	v_mfma_f32_32x32x16_bf16 v[0:15], v[184:187], v[222:225], v[0:15]
	ds_read_b128 v[180:183], v77 offset:49152
	ds_read_b128 v[184:187], v77 offset:53248
	ds_read_b128 v[218:221], v81 offset:49152
	ds_read_b128 v[222:225], v81 offset:53248
	s_waitcnt lgkmcnt(4)
	v_mfma_f32_32x32x16_bf16 v[48:63], v[164:167], v[172:175], v[48:63]
	s_add_u32 m0, s26, 0x4000
	v_lshl_add_u64 v[160:161], v[70:71], 0, s[10:11]
	global_load_lds_dwordx4 v[160:161], off
	v_mfma_f32_32x32x16_bf16 v[32:47], v[164:167], v[176:179], v[32:47]
	v_mfma_f32_32x32x16_bf16 v[16:31], v[168:171], v[172:175], v[16:31]
	s_add_u32 m0, s26, 0x6000
	v_lshl_add_u64 v[162:163], v[68:69], 0, s[10:11]
	global_load_lds_dwordx4 v[162:163], off
	v_mfma_f32_32x32x16_bf16 v[0:15], v[168:171], v[176:179], v[0:15]
	ds_read_b128 v[164:167], v78 offset:49152
	ds_read_b128 v[168:171], v78 offset:53248
	ds_read_b128 v[172:175], v82 offset:49152
	ds_read_b128 v[176:179], v82 offset:53248
	s_waitcnt lgkmcnt(4)
	v_mfma_f32_32x32x16_bf16 v[48:63], v[180:183], v[218:221], v[48:63]
	s_mov_b32 s10, 0xb00300
	s_add_u32 m0, s26, 0x8000
	v_lshl_add_u64 v[160:161], v[66:67], 0, s[10:11]
	global_load_lds_dwordx4 v[160:161], off
	v_mfma_f32_32x32x16_bf16 v[32:47], v[180:183], v[222:225], v[32:47]
	v_mfma_f32_32x32x16_bf16 v[16:31], v[184:187], v[218:221], v[16:31]
	s_add_u32 m0, s26, 0xa000
	v_lshl_add_u64 v[162:163], v[64:65], 0, s[10:11]
	global_load_lds_dwordx4 v[162:163], off
	v_mfma_f32_32x32x16_bf16 v[0:15], v[184:187], v[222:225], v[0:15]
	ds_read_b128 v[180:183], v79 offset:49152
	ds_read_b128 v[184:187], v79 offset:53248
	ds_read_b128 v[218:221], v83 offset:49152
	ds_read_b128 v[222:225], v83 offset:53248
	s_waitcnt lgkmcnt(4)
	v_mfma_f32_32x32x16_bf16 v[48:63], v[164:167], v[172:175], v[48:63]
	v_mfma_f32_32x32x16_bf16 v[32:47], v[164:167], v[176:179], v[32:47]
	v_mfma_f32_32x32x16_bf16 v[16:31], v[168:171], v[172:175], v[16:31]
	v_mfma_f32_32x32x16_bf16 v[0:15], v[168:171], v[176:179], v[0:15]
	s_waitcnt vmcnt(6) lgkmcnt(0)
	s_barrier
	ds_read_b128 v[164:167], v84
	ds_read_b128 v[168:171], v84 offset:4096
	ds_read_b128 v[172:175], v156
	ds_read_b128 v[176:179], v156 offset:4096
	v_mfma_f32_32x32x16_bf16 v[48:63], v[180:183], v[218:221], v[48:63]
	s_mov_b32 s10, 0xa5c2380
	s_add_u32 m0, s26, 0xc000
	v_lshl_add_u64 v[160:161], v[74:75], 0, s[10:11]
	global_load_lds_dwordx4 v[160:161], off
	v_mfma_f32_32x32x16_bf16 v[32:47], v[180:183], v[222:225], v[32:47]
	v_mfma_f32_32x32x16_bf16 v[16:31], v[184:187], v[218:221], v[16:31]
	s_add_u32 m0, s26, 0xe000
	v_lshl_add_u64 v[162:163], v[72:73], 0, s[10:11]
	global_load_lds_dwordx4 v[162:163], off
	v_mfma_f32_32x32x16_bf16 v[0:15], v[184:187], v[222:225], v[0:15]
	ds_read_b128 v[180:183], v85
	ds_read_b128 v[184:187], v85 offset:4096
	ds_read_b128 v[218:221], v157
	ds_read_b128 v[222:225], v157 offset:4096
	s_waitcnt lgkmcnt(4)
	v_mfma_f32_32x32x16_bf16 v[48:63], v[164:167], v[172:175], v[48:63]
	s_add_u32 m0, s26, 0x10000
	v_lshl_add_u64 v[160:161], v[70:71], 0, s[10:11]
	global_load_lds_dwordx4 v[160:161], off
	v_mfma_f32_32x32x16_bf16 v[32:47], v[164:167], v[176:179], v[32:47]
	v_mfma_f32_32x32x16_bf16 v[16:31], v[168:171], v[172:175], v[16:31]
	s_add_u32 m0, s26, 0x12000
	v_lshl_add_u64 v[162:163], v[68:69], 0, s[10:11]
	global_load_lds_dwordx4 v[162:163], off
	v_mfma_f32_32x32x16_bf16 v[0:15], v[168:171], v[176:179], v[0:15]
	ds_read_b128 v[164:167], v86
	ds_read_b128 v[168:171], v86 offset:4096
	ds_read_b128 v[172:175], v158
	ds_read_b128 v[176:179], v158 offset:4096
	s_waitcnt lgkmcnt(4)
	v_mfma_f32_32x32x16_bf16 v[48:63], v[180:183], v[218:221], v[48:63]
	s_mov_b32 s10, 0xb00380
	s_add_u32 m0, s26, 0x14000
	v_lshl_add_u64 v[160:161], v[66:67], 0, s[10:11]
	global_load_lds_dwordx4 v[160:161], off
	v_mfma_f32_32x32x16_bf16 v[32:47], v[180:183], v[222:225], v[32:47]
	v_mfma_f32_32x32x16_bf16 v[16:31], v[184:187], v[218:221], v[16:31]
	s_add_u32 m0, s26, 0x16000
	v_lshl_add_u64 v[162:163], v[64:65], 0, s[10:11]
	global_load_lds_dwordx4 v[162:163], off
	v_mfma_f32_32x32x16_bf16 v[0:15], v[184:187], v[222:225], v[0:15]
	ds_read_b128 v[180:183], v87
	ds_read_b128 v[184:187], v87 offset:4096
	ds_read_b128 v[218:221], v159
	ds_read_b128 v[222:225], v159 offset:4096
	s_waitcnt lgkmcnt(4)
	v_mfma_f32_32x32x16_bf16 v[48:63], v[164:167], v[172:175], v[48:63]
	v_mfma_f32_32x32x16_bf16 v[32:47], v[164:167], v[176:179], v[32:47]
	v_mfma_f32_32x32x16_bf16 v[16:31], v[168:171], v[172:175], v[16:31]
	v_mfma_f32_32x32x16_bf16 v[0:15], v[168:171], v[176:179], v[0:15]
	s_waitcnt vmcnt(6) lgkmcnt(0)
	s_barrier
;     ...
;   for (int kt = 0; kt < nk; ++kt) {
;     if (kt + 1 < nk) asm volatile("s_waitcnt vmcnt(6)" ::: "memory");
;     else asm volatile("s_waitcnt vmcnt(0)" ::: "memory");
;     __builtin_amdgcn_s_barrier();
;     asm volatile("" ::: "memory");
;     if (kt + 2 < nk) { const int st2 = (st >= 1) ? st - 1 : 2; GEMM_ISSUE(kt + 2, st2); }
;     const char* la = lds + st * STAGE_B;
;     const char* lb = la + 32768;
;     const unsigned sa_u = (unsigned)(size_t)la + arow_u, sb_u = (unsigned)(size_t)lb + brow_u;
;     const unsigned a0 = sa_u + co0, a1 = sa_u + co1, a2 = sa_u + co2, a3 = sa_u + co3;
;     const unsigned b0 = sb_u + co0, b1 = sb_u + co1, b2 = sb_u + co2, b3 = sb_u + co3;
;     {
;       bf16x8 p0, p1, q0, q1, u0, u1, w0, w1;
;       asm volatile(
;         "ds_read_b128 %4, %12\n\tds_read_b128 %5, %12 offset:4096\n\tds_read_b128 %6, %16\n\tds_read_b128 %7, %16 offset:4096\n\t"
;         "ds_read_b128 %8, %13\n\tds_read_b128 %9, %13 offset:4096\n\tds_read_b128 %10, %17\n\tds_read_b128 %11, %17 offset:4096\n\t"
;         "s_waitcnt lgkmcnt(4)\n\t"
;         "v_mfma_f32_32x32x16_bf16 %0, %4, %6, %0\n\tv_mfma_f32_32x32x16_bf16 %1, %4, %7, %1\n\tv_mfma_f32_32x32x16_bf16 %2, %5, %6, %2\n\tv_mfma_f32_32x32x16_bf16 %3, %5, %7, %3\n\t"
;         "ds_read_b128 %4, %14\n\tds_read_b128 %5, %14 offset:4096\n\tds_read_b128 %6, %18\n\tds_read_b128 %7, %18 offset:4096\n\t"
;         "s_waitcnt lgkmcnt(4)\n\t"
;         "v_mfma_f32_32x32x16_bf16 %0, %8, %10, %0\n\tv_mfma_f32_32x32x16_bf16 %1, %8, %11, %1\n\tv_mfma_f32_32x32x16_bf16 %2, %9, %10, %2\n\tv_mfma_f32_32x32x16_bf16 %3, %9, %11, %3\n\t"
;         "ds_read_b128 %8, %15\n\tds_read_b128 %9, %15 offset:4096\n\tds_read_b128 %10, %19\n\tds_read_b128 %11, %19 offset:4096\n\t"
;         "s_waitcnt lgkmcnt(4)\n\t"
;         "v_mfma_f32_32x32x16_bf16 %0, %4, %6, %0\n\tv_mfma_f32_32x32x16_bf16 %1, %4, %7, %1\n\tv_mfma_f32_32x32x16_bf16 %2, %5, %6, %2\n\tv_mfma_f32_32x32x16_bf16 %3, %5, %7, %3\n\t"
;         "s_waitcnt lgkmcnt(0)\n\t"
;         "v_mfma_f32_32x32x16_bf16 %0, %8, %10, %0\n\tv_mfma_f32_32x32x16_bf16 %1, %8, %11, %1\n\tv_mfma_f32_32x32x16_bf16 %2, %9, %10, %2\n\tv_mfma_f32_32x32x16_bf16 %3, %9, %11, %3"
;         : "+v"(acc[0][0]), "+v"(acc[0][1]), "+v"(acc[1][0]), "+v"(acc[1][1]),
;           "=&v"(p0), "=&v"(p1), "=&v"(q0), "=&v"(q1), "=&v"(u0), "=&v"(u1), "=&v"(w0), "=&v"(w1)
	ds_read_b128 v[164:167], v76
	ds_read_b128 v[168:171], v76 offset:4096
	ds_read_b128 v[172:175], v80
	ds_read_b128 v[176:179], v80 offset:4096
	v_mfma_f32_32x32x16_bf16 v[48:63], v[180:183], v[218:221], v[48:63]
	s_mov_b32 s10, 0xa5c2400
	s_add_u32 m0, s26, 0x18000
	v_lshl_add_u64 v[160:161], v[74:75], 0, s[10:11]
	global_load_lds_dwordx4 v[160:161], off
	v_mfma_f32_32x32x16_bf16 v[32:47], v[180:183], v[222:225], v[32:47]
	v_mfma_f32_32x32x16_bf16 v[16:31], v[184:187], v[218:221], v[16:31]
	s_add_u32 m0, s26, 0x1a000
	v_lshl_add_u64 v[162:163], v[72:73], 0, s[10:11]
	global_load_lds_dwordx4 v[162:163], off
	v_mfma_f32_32x32x16_bf16 v[0:15], v[184:187], v[222:225], v[0:15]
	ds_read_b128 v[180:183], v77
	ds_read_b128 v[184:187], v77 offset:4096
	ds_read_b128 v[218:221], v81
	ds_read_b128 v[222:225], v81 offset:4096
	s_waitcnt lgkmcnt(4)
	v_mfma_f32_32x32x16_bf16 v[48:63], v[164:167], v[172:175], v[48:63]
	s_add_u32 m0, s26, 0x1c000
	v_lshl_add_u64 v[160:161], v[70:71], 0, s[10:11]
	global_load_lds_dwordx4 v[160:161], off
	v_mfma_f32_32x32x16_bf16 v[32:47], v[164:167], v[176:179], v[32:47]
	v_mfma_f32_32x32x16_bf16 v[16:31], v[168:171], v[172:175], v[16:31]
	s_add_u32 m0, s26, 0x1e000
	v_lshl_add_u64 v[162:163], v[68:69], 0, s[10:11]
	global_load_lds_dwordx4 v[162:163], off
	v_mfma_f32_32x32x16_bf16 v[0:15], v[168:171], v[176:179], v[0:15]
	ds_read_b128 v[164:167], v78
	ds_read_b128 v[168:171], v78 offset:4096
	ds_read_b128 v[172:175], v82
	ds_read_b128 v[176:179], v82 offset:4096
	s_waitcnt lgkmcnt(4)
	v_mfma_f32_32x32x16_bf16 v[48:63], v[180:183], v[218:221], v[48:63]
	s_mov_b32 s10, 0xb00400
	s_add_u32 m0, s26, 0x20000
	v_lshl_add_u64 v[160:161], v[66:67], 0, s[10:11]
	global_load_lds_dwordx4 v[160:161], off
	v_mfma_f32_32x32x16_bf16 v[32:47], v[180:183], v[222:225], v[32:47]
	v_mfma_f32_32x32x16_bf16 v[16:31], v[184:187], v[218:221], v[16:31]
	s_add_u32 m0, s26, 0x22000
	v_lshl_add_u64 v[162:163], v[64:65], 0, s[10:11]
	global_load_lds_dwordx4 v[162:163], off
	v_mfma_f32_32x32x16_bf16 v[0:15], v[184:187], v[222:225], v[0:15]
	ds_read_b128 v[180:183], v79
	ds_read_b128 v[184:187], v79 offset:4096
	ds_read_b128 v[218:221], v83
	ds_read_b128 v[222:225], v83 offset:4096
	s_waitcnt lgkmcnt(4)
	v_mfma_f32_32x32x16_bf16 v[48:63], v[164:167], v[172:175], v[48:63]
	v_mfma_f32_32x32x16_bf16 v[32:47], v[164:167], v[176:179], v[32:47]
	v_mfma_f32_32x32x16_bf16 v[16:31], v[168:171], v[172:175], v[16:31]
	v_mfma_f32_32x32x16_bf16 v[0:15], v[168:171], v[176:179], v[0:15]
	s_waitcnt vmcnt(6) lgkmcnt(0)
	s_barrier
	ds_read_b128 v[164:167], v76 offset:49152
	ds_read_b128 v[168:171], v76 offset:53248
	ds_read_b128 v[172:175], v80 offset:49152
	ds_read_b128 v[176:179], v80 offset:53248
	v_mfma_f32_32x32x16_bf16 v[48:63], v[180:183], v[218:221], v[48:63]
	s_mov_b32 s10, 0xa5c2480
	s_mov_b32 m0, s26
	v_lshl_add_u64 v[160:161], v[74:75], 0, s[10:11]
	global_load_lds_dwordx4 v[160:161], off
	v_mfma_f32_32x32x16_bf16 v[32:47], v[180:183], v[222:225], v[32:47]
	v_mfma_f32_32x32x16_bf16 v[16:31], v[184:187], v[218:221], v[16:31]
	s_add_u32 m0, s26, 0x2000
	v_lshl_add_u64 v[162:163], v[72:73], 0, s[10:11]
	global_load_lds_dwordx4 v[162:163], off
	v_mfma_f32_32x32x16_bf16 v[0:15], v[184:187], v[222:225], v[0:15]
	ds_read_b128 v[180:183], v77 offset:49152
	ds_read_b128 v[184:187], v77 offset:53248
	ds_read_b128 v[218:221], v81 offset:49152
	ds_read_b128 v[222:225], v81 offset:53248
	s_waitcnt lgkmcnt(4)
	v_mfma_f32_32x32x16_bf16 v[48:63], v[164:167], v[172:175], v[48:63]
	s_add_u32 m0, s26, 0x4000
	v_lshl_add_u64 v[160:161], v[70:71], 0, s[10:11]
	global_load_lds_dwordx4 v[160:161], off
	v_mfma_f32_32x32x16_bf16 v[32:47], v[164:167], v[176:179], v[32:47]
	v_mfma_f32_32x32x16_bf16 v[16:31], v[168:171], v[172:175], v[16:31]
	s_add_u32 m0, s26, 0x6000
	v_lshl_add_u64 v[162:163], v[68:69], 0, s[10:11]
	global_load_lds_dwordx4 v[162:163], off
	v_mfma_f32_32x32x16_bf16 v[0:15], v[168:171], v[176:179], v[0:15]
	ds_read_b128 v[164:167], v78 offset:49152
	ds_read_b128 v[168:171], v78 offset:53248
	ds_read_b128 v[172:175], v82 offset:49152
	ds_read_b128 v[176:179], v82 offset:53248
	s_waitcnt lgkmcnt(4)
	v_mfma_f32_32x32x16_bf16 v[48:63], v[180:183], v[218:221], v[48:63]
	s_mov_b32 s10, 0xb00480
	s_add_u32 m0, s26, 0x8000
	v_lshl_add_u64 v[160:161], v[66:67], 0, s[10:11]
	global_load_lds_dwordx4 v[160:161], off
	v_mfma_f32_32x32x16_bf16 v[32:47], v[180:183], v[222:225], v[32:47]
	v_mfma_f32_32x32x16_bf16 v[16:31], v[184:187], v[218:221], v[16:31]
	s_add_u32 m0, s26, 0xa000
	v_lshl_add_u64 v[162:163], v[64:65], 0, s[10:11]
	global_load_lds_dwordx4 v[162:163], off
	v_mfma_f32_32x32x16_bf16 v[0:15], v[184:187], v[222:225], v[0:15]
	ds_read_b128 v[180:183], v79 offset:49152
	ds_read_b128 v[184:187], v79 offset:53248
	ds_read_b128 v[218:221], v83 offset:49152
	ds_read_b128 v[222:225], v83 offset:53248
	s_waitcnt lgkmcnt(4)
	v_mfma_f32_32x32x16_bf16 v[48:63], v[164:167], v[172:175], v[48:63]
	v_mfma_f32_32x32x16_bf16 v[32:47], v[164:167], v[176:179], v[32:47]
	v_mfma_f32_32x32x16_bf16 v[16:31], v[168:171], v[172:175], v[16:31]
	v_mfma_f32_32x32x16_bf16 v[0:15], v[168:171], v[176:179], v[0:15]
	s_waitcnt vmcnt(6) lgkmcnt(0)
	s_barrier
;     ...
;   for (int kt = 0; kt < nk; ++kt) {
;     if (kt + 1 < nk) asm volatile("s_waitcnt vmcnt(6)" ::: "memory");
;     else asm volatile("s_waitcnt vmcnt(0)" ::: "memory");
;     __builtin_amdgcn_s_barrier();
;     asm volatile("" ::: "memory");
;     if (kt + 2 < nk) { const int st2 = (st >= 1) ? st - 1 : 2; GEMM_ISSUE(kt + 2, st2); }
;     const char* la = lds + st * STAGE_B;
;     const char* lb = la + 32768;
;     const unsigned sa_u = (unsigned)(size_t)la + arow_u, sb_u = (unsigned)(size_t)lb + brow_u;
;     const unsigned a0 = sa_u + co0, a1 = sa_u + co1, a2 = sa_u + co2, a3 = sa_u + co3;
;     const unsigned b0 = sb_u + co0, b1 = sb_u + co1, b2 = sb_u + co2, b3 = sb_u + co3;
;     {
;       bf16x8 p0, p1, q0, q1, u0, u1, w0, w1;
;       asm volatile(
;         "ds_read_b128 %4, %12\n\tds_read_b128 %5, %12 offset:4096\n\tds_read_b128 %6, %16\n\tds_read_b128 %7, %16 offset:4096\n\t"
;         "ds_read_b128 %8, %13\n\tds_read_b128 %9, %13 offset:4096\n\tds_read_b128 %10, %17\n\tds_read_b128 %11, %17 offset:4096\n\t"
;         "s_waitcnt lgkmcnt(4)\n\t"
;         "v_mfma_f32_32x32x16_bf16 %0, %4, %6, %0\n\tv_mfma_f32_32x32x16_bf16 %1, %4, %7, %1\n\tv_mfma_f32_32x32x16_bf16 %2, %5, %6, %2\n\tv_mfma_f32_32x32x16_bf16 %3, %5, %7, %3\n\t"
;         "ds_read_b128 %4, %14\n\tds_read_b128 %5, %14 offset:4096\n\tds_read_b128 %6, %18\n\tds_read_b128 %7, %18 offset:4096\n\t"
;         "s_waitcnt lgkmcnt(4)\n\t"
;         "v_mfma_f32_32x32x16_bf16 %0, %8, %10, %0\n\tv_mfma_f32_32x32x16_bf16 %1, %8, %11, %1\n\tv_mfma_f32_32x32x16_bf16 %2, %9, %10, %2\n\tv_mfma_f32_32x32x16_bf16 %3, %9, %11, %3\n\t"
;         "ds_read_b128 %8, %15\n\tds_read_b128 %9, %15 offset:4096\n\tds_read_b128 %10, %19\n\tds_read_b128 %11, %19 offset:4096\n\t"
;         "s_waitcnt lgkmcnt(4)\n\t"
;         "v_mfma_f32_32x32x16_bf16 %0, %4, %6, %0\n\tv_mfma_f32_32x32x16_bf16 %1, %4, %7, %1\n\tv_mfma_f32_32x32x16_bf16 %2, %5, %6, %2\n\tv_mfma_f32_32x32x16_bf16 %3, %5, %7, %3\n\t"
;         "s_waitcnt lgkmcnt(0)\n\t"
;         "v_mfma_f32_32x32x16_bf16 %0, %8, %10, %0\n\tv_mfma_f32_32x32x16_bf16 %1, %8, %11, %1\n\tv_mfma_f32_32x32x16_bf16 %2, %9, %10, %2\n\tv_mfma_f32_32x32x16_bf16 %3, %9, %11, %3"
;         : "+v"(acc[0][0]), "+v"(acc[0][1]), "+v"(acc[1][0]), "+v"(acc[1][1]),
;           "=&v"(p0), "=&v"(p1), "=&v"(q0), "=&v"(q1), "=&v"(u0), "=&v"(u1), "=&v"(w0), "=&v"(w1)
	ds_read_b128 v[164:167], v84
	ds_read_b128 v[168:171], v84 offset:4096
	ds_read_b128 v[172:175], v156
	ds_read_b128 v[176:179], v156 offset:4096
	v_mfma_f32_32x32x16_bf16 v[48:63], v[180:183], v[218:221], v[48:63]
	s_mov_b32 s10, 0xa5c2500
	s_add_u32 m0, s26, 0xc000
	v_lshl_add_u64 v[160:161], v[74:75], 0, s[10:11]
	global_load_lds_dwordx4 v[160:161], off
	v_mfma_f32_32x32x16_bf16 v[32:47], v[180:183], v[222:225], v[32:47]
	v_mfma_f32_32x32x16_bf16 v[16:31], v[184:187], v[218:221], v[16:31]
	s_add_u32 m0, s26, 0xe000
	v_lshl_add_u64 v[162:163], v[72:73], 0, s[10:11]
	global_load_lds_dwordx4 v[162:163], off
	v_mfma_f32_32x32x16_bf16 v[0:15], v[184:187], v[222:225], v[0:15]
	ds_read_b128 v[180:183], v85
	ds_read_b128 v[184:187], v85 offset:4096
	ds_read_b128 v[218:221], v157
	ds_read_b128 v[222:225], v157 offset:4096
	s_waitcnt lgkmcnt(4)
	v_mfma_f32_32x32x16_bf16 v[48:63], v[164:167], v[172:175], v[48:63]
	s_add_u32 m0, s26, 0x10000
	v_lshl_add_u64 v[160:161], v[70:71], 0, s[10:11]
	global_load_lds_dwordx4 v[160:161], off
	v_mfma_f32_32x32x16_bf16 v[32:47], v[164:167], v[176:179], v[32:47]
	v_mfma_f32_32x32x16_bf16 v[16:31], v[168:171], v[172:175], v[16:31]
	s_add_u32 m0, s26, 0x12000
	v_lshl_add_u64 v[162:163], v[68:69], 0, s[10:11]
	global_load_lds_dwordx4 v[162:163], off
	v_mfma_f32_32x32x16_bf16 v[0:15], v[168:171], v[176:179], v[0:15]
	ds_read_b128 v[164:167], v86
	ds_read_b128 v[168:171], v86 offset:4096
	ds_read_b128 v[172:175], v158
	ds_read_b128 v[176:179], v158 offset:4096
	s_waitcnt lgkmcnt(4)
	v_mfma_f32_32x32x16_bf16 v[48:63], v[180:183], v[218:221], v[48:63]
	s_mov_b32 s10, 0xb00500
	s_add_u32 m0, s26, 0x14000
	v_lshl_add_u64 v[160:161], v[66:67], 0, s[10:11]
	global_load_lds_dwordx4 v[160:161], off
	v_mfma_f32_32x32x16_bf16 v[32:47], v[180:183], v[222:225], v[32:47]
	v_mfma_f32_32x32x16_bf16 v[16:31], v[184:187], v[218:221], v[16:31]
	s_add_u32 m0, s26, 0x16000
	v_lshl_add_u64 v[162:163], v[64:65], 0, s[10:11]
	global_load_lds_dwordx4 v[162:163], off
	v_mfma_f32_32x32x16_bf16 v[0:15], v[184:187], v[222:225], v[0:15]
	ds_read_b128 v[180:183], v87
	ds_read_b128 v[184:187], v87 offset:4096
	ds_read_b128 v[218:221], v159
	ds_read_b128 v[222:225], v159 offset:4096
	s_waitcnt lgkmcnt(4)
	v_mfma_f32_32x32x16_bf16 v[48:63], v[164:167], v[172:175], v[48:63]
	v_mfma_f32_32x32x16_bf16 v[32:47], v[164:167], v[176:179], v[32:47]
	v_mfma_f32_32x32x16_bf16 v[16:31], v[168:171], v[172:175], v[16:31]
	v_mfma_f32_32x32x16_bf16 v[0:15], v[168:171], v[176:179], v[0:15]
	s_waitcnt vmcnt(6) lgkmcnt(0)
	s_barrier
	ds_read_b128 v[164:167], v76
	ds_read_b128 v[168:171], v76 offset:4096
	ds_read_b128 v[172:175], v80
	ds_read_b128 v[176:179], v80 offset:4096
	v_mfma_f32_32x32x16_bf16 v[48:63], v[180:183], v[218:221], v[48:63]
	s_mov_b32 s10, 0xa5c2580
	s_add_u32 m0, s26, 0x18000
	v_lshl_add_u64 v[160:161], v[74:75], 0, s[10:11]
	global_load_lds_dwordx4 v[160:161], off
	v_mfma_f32_32x32x16_bf16 v[32:47], v[180:183], v[222:225], v[32:47]
	v_mfma_f32_32x32x16_bf16 v[16:31], v[184:187], v[218:221], v[16:31]
	s_add_u32 m0, s26, 0x1a000
	v_lshl_add_u64 v[162:163], v[72:73], 0, s[10:11]
	global_load_lds_dwordx4 v[162:163], off
	v_mfma_f32_32x32x16_bf16 v[0:15], v[184:187], v[222:225], v[0:15]
	ds_read_b128 v[180:183], v77
	ds_read_b128 v[184:187], v77 offset:4096
	ds_read_b128 v[218:221], v81
	ds_read_b128 v[222:225], v81 offset:4096
	s_waitcnt lgkmcnt(4)
	v_mfma_f32_32x32x16_bf16 v[48:63], v[164:167], v[172:175], v[48:63]
	s_add_u32 m0, s26, 0x1c000
	v_lshl_add_u64 v[160:161], v[70:71], 0, s[10:11]
	global_load_lds_dwordx4 v[160:161], off
	v_mfma_f32_32x32x16_bf16 v[32:47], v[164:167], v[176:179], v[32:47]
	v_mfma_f32_32x32x16_bf16 v[16:31], v[168:171], v[172:175], v[16:31]
	s_add_u32 m0, s26, 0x1e000
	v_lshl_add_u64 v[162:163], v[68:69], 0, s[10:11]
	global_load_lds_dwordx4 v[162:163], off
	v_mfma_f32_32x32x16_bf16 v[0:15], v[168:171], v[176:179], v[0:15]
	ds_read_b128 v[164:167], v78
	ds_read_b128 v[168:171], v78 offset:4096
	ds_read_b128 v[172:175], v82
	ds_read_b128 v[176:179], v82 offset:4096
	s_waitcnt lgkmcnt(4)
	v_mfma_f32_32x32x16_bf16 v[48:63], v[180:183], v[218:221], v[48:63]
	s_mov_b32 s10, 0xb00580
	s_add_u32 m0, s26, 0x20000
	v_lshl_add_u64 v[160:161], v[66:67], 0, s[10:11]
	global_load_lds_dwordx4 v[160:161], off
	v_mfma_f32_32x32x16_bf16 v[32:47], v[180:183], v[222:225], v[32:47]
	v_mfma_f32_32x32x16_bf16 v[16:31], v[184:187], v[218:221], v[16:31]
	s_add_u32 m0, s26, 0x22000
	v_lshl_add_u64 v[162:163], v[64:65], 0, s[10:11]
	global_load_lds_dwordx4 v[162:163], off
	v_mfma_f32_32x32x16_bf16 v[0:15], v[184:187], v[222:225], v[0:15]
	ds_read_b128 v[180:183], v79
	ds_read_b128 v[184:187], v79 offset:4096
	ds_read_b128 v[218:221], v83
	ds_read_b128 v[222:225], v83 offset:4096
	s_waitcnt lgkmcnt(4)
	v_mfma_f32_32x32x16_bf16 v[48:63], v[164:167], v[172:175], v[48:63]
	v_mfma_f32_32x32x16_bf16 v[32:47], v[164:167], v[176:179], v[32:47]
	v_mfma_f32_32x32x16_bf16 v[16:31], v[168:171], v[172:175], v[16:31]
	v_mfma_f32_32x32x16_bf16 v[0:15], v[168:171], v[176:179], v[0:15]
	s_waitcnt vmcnt(6) lgkmcnt(0)
	s_barrier
;     ...
;   for (int kt = 0; kt < nk; ++kt) {
;     if (kt + 1 < nk) asm volatile("s_waitcnt vmcnt(6)" ::: "memory");
;     else asm volatile("s_waitcnt vmcnt(0)" ::: "memory");
;     __builtin_amdgcn_s_barrier();
;     asm volatile("" ::: "memory");
;     if (kt + 2 < nk) { const int st2 = (st >= 1) ? st - 1 : 2; GEMM_ISSUE(kt + 2, st2); }
;     const char* la = lds + st * STAGE_B;
;     const char* lb = la + 32768;
;     const unsigned sa_u = (unsigned)(size_t)la + arow_u, sb_u = (unsigned)(size_t)lb + brow_u;
;     const unsigned a0 = sa_u + co0, a1 = sa_u + co1, a2 = sa_u + co2, a3 = sa_u + co3;
;     const unsigned b0 = sb_u + co0, b1 = sb_u + co1, b2 = sb_u + co2, b3 = sb_u + co3;
;     {
;       bf16x8 p0, p1, q0, q1, u0, u1, w0, w1;
;       asm volatile(
;         "ds_read_b128 %4, %12\n\tds_read_b128 %5, %12 offset:4096\n\tds_read_b128 %6, %16\n\tds_read_b128 %7, %16 offset:4096\n\t"
;         "ds_read_b128 %8, %13\n\tds_read_b128 %9, %13 offset:4096\n\tds_read_b128 %10, %17\n\tds_read_b128 %11, %17 offset:4096\n\t"
;         "s_waitcnt lgkmcnt(4)\n\t"
;         "v_mfma_f32_32x32x16_bf16 %0, %4, %6, %0\n\tv_mfma_f32_32x32x16_bf16 %1, %4, %7, %1\n\tv_mfma_f32_32x32x16_bf16 %2, %5, %6, %2\n\tv_mfma_f32_32x32x16_bf16 %3, %5, %7, %3\n\t"
;         "ds_read_b128 %4, %14\n\tds_read_b128 %5, %14 offset:4096\n\tds_read_b128 %6, %18\n\tds_read_b128 %7, %18 offset:4096\n\t"
;         "s_waitcnt lgkmcnt(4)\n\t"
;         "v_mfma_f32_32x32x16_bf16 %0, %8, %10, %0\n\tv_mfma_f32_32x32x16_bf16 %1, %8, %11, %1\n\tv_mfma_f32_32x32x16_bf16 %2, %9, %10, %2\n\tv_mfma_f32_32x32x16_bf16 %3, %9, %11, %3\n\t"
;         "ds_read_b128 %8, %15\n\tds_read_b128 %9, %15 offset:4096\n\tds_read_b128 %10, %19\n\tds_read_b128 %11, %19 offset:4096\n\t"
;         "s_waitcnt lgkmcnt(4)\n\t"
;         "v_mfma_f32_32x32x16_bf16 %0, %4, %6, %0\n\tv_mfma_f32_32x32x16_bf16 %1, %4, %7, %1\n\tv_mfma_f32_32x32x16_bf16 %2, %5, %6, %2\n\tv_mfma_f32_32x32x16_bf16 %3, %5, %7, %3\n\t"
;         "s_waitcnt lgkmcnt(0)\n\t"
;         "v_mfma_f32_32x32x16_bf16 %0, %8, %10, %0\n\tv_mfma_f32_32x32x16_bf16 %1, %8, %11, %1\n\tv_mfma_f32_32x32x16_bf16 %2, %9, %10, %2\n\tv_mfma_f32_32x32x16_bf16 %3, %9, %11, %3"
;         : "+v"(acc[0][0]), "+v"(acc[0][1]), "+v"(acc[1][0]), "+v"(acc[1][1]),
;           "=&v"(p0), "=&v"(p1), "=&v"(q0), "=&v"(q1), "=&v"(u0), "=&v"(u1), "=&v"(w0), "=&v"(w1)
	ds_read_b128 v[164:167], v76 offset:49152
	ds_read_b128 v[168:171], v76 offset:53248
	ds_read_b128 v[172:175], v80 offset:49152
	ds_read_b128 v[176:179], v80 offset:53248
	v_mfma_f32_32x32x16_bf16 v[48:63], v[180:183], v[218:221], v[48:63]
	s_mov_b32 s10, 0xa5c2600
	s_mov_b32 m0, s26
	v_lshl_add_u64 v[160:161], v[74:75], 0, s[10:11]
	global_load_lds_dwordx4 v[160:161], off
	v_mfma_f32_32x32x16_bf16 v[32:47], v[180:183], v[222:225], v[32:47]
	v_mfma_f32_32x32x16_bf16 v[16:31], v[184:187], v[218:221], v[16:31]
	s_add_u32 m0, s26, 0x2000
	v_lshl_add_u64 v[162:163], v[72:73], 0, s[10:11]
	global_load_lds_dwordx4 v[162:163], off
	v_mfma_f32_32x32x16_bf16 v[0:15], v[184:187], v[222:225], v[0:15]
	ds_read_b128 v[180:183], v77 offset:49152
	ds_read_b128 v[184:187], v77 offset:53248
	ds_read_b128 v[218:221], v81 offset:49152
	ds_read_b128 v[222:225], v81 offset:53248
	s_waitcnt lgkmcnt(4)
	v_mfma_f32_32x32x16_bf16 v[48:63], v[164:167], v[172:175], v[48:63]
	s_add_u32 m0, s26, 0x4000
	v_lshl_add_u64 v[160:161], v[70:71], 0, s[10:11]
	global_load_lds_dwordx4 v[160:161], off
	v_mfma_f32_32x32x16_bf16 v[32:47], v[164:167], v[176:179], v[32:47]
	v_mfma_f32_32x32x16_bf16 v[16:31], v[168:171], v[172:175], v[16:31]
	s_add_u32 m0, s26, 0x6000
	v_lshl_add_u64 v[162:163], v[68:69], 0, s[10:11]
	global_load_lds_dwordx4 v[162:163], off
	v_mfma_f32_32x32x16_bf16 v[0:15], v[168:171], v[176:179], v[0:15]
	ds_read_b128 v[164:167], v78 offset:49152
	ds_read_b128 v[168:171], v78 offset:53248
	ds_read_b128 v[172:175], v82 offset:49152
	ds_read_b128 v[176:179], v82 offset:53248
	s_waitcnt lgkmcnt(4)
	v_mfma_f32_32x32x16_bf16 v[48:63], v[180:183], v[218:221], v[48:63]
	s_mov_b32 s10, 0xb00600
	s_add_u32 m0, s26, 0x8000
	v_lshl_add_u64 v[160:161], v[66:67], 0, s[10:11]
	global_load_lds_dwordx4 v[160:161], off
	v_mfma_f32_32x32x16_bf16 v[32:47], v[180:183], v[222:225], v[32:47]
	v_mfma_f32_32x32x16_bf16 v[16:31], v[184:187], v[218:221], v[16:31]
	s_add_u32 m0, s26, 0xa000
	v_lshl_add_u64 v[162:163], v[64:65], 0, s[10:11]
	global_load_lds_dwordx4 v[162:163], off
	v_mfma_f32_32x32x16_bf16 v[0:15], v[184:187], v[222:225], v[0:15]
	ds_read_b128 v[180:183], v79 offset:49152
	ds_read_b128 v[184:187], v79 offset:53248
	ds_read_b128 v[218:221], v83 offset:49152
	ds_read_b128 v[222:225], v83 offset:53248
	s_waitcnt lgkmcnt(4)
	v_mfma_f32_32x32x16_bf16 v[48:63], v[164:167], v[172:175], v[48:63]
	v_mfma_f32_32x32x16_bf16 v[32:47], v[164:167], v[176:179], v[32:47]
	v_mfma_f32_32x32x16_bf16 v[16:31], v[168:171], v[172:175], v[16:31]
	v_mfma_f32_32x32x16_bf16 v[0:15], v[168:171], v[176:179], v[0:15]
	s_waitcnt vmcnt(6) lgkmcnt(0)
	s_barrier
	ds_read_b128 v[164:167], v84
	ds_read_b128 v[168:171], v84 offset:4096
	ds_read_b128 v[172:175], v156
	ds_read_b128 v[176:179], v156 offset:4096
	v_mfma_f32_32x32x16_bf16 v[48:63], v[180:183], v[218:221], v[48:63]
	s_mov_b32 s10, 0xa5c2680
	s_add_u32 m0, s26, 0xc000
	v_lshl_add_u64 v[160:161], v[74:75], 0, s[10:11]
	global_load_lds_dwordx4 v[160:161], off
	v_mfma_f32_32x32x16_bf16 v[32:47], v[180:183], v[222:225], v[32:47]
	v_mfma_f32_32x32x16_bf16 v[16:31], v[184:187], v[218:221], v[16:31]
	s_add_u32 m0, s26, 0xe000
	v_lshl_add_u64 v[162:163], v[72:73], 0, s[10:11]
	global_load_lds_dwordx4 v[162:163], off
	v_mfma_f32_32x32x16_bf16 v[0:15], v[184:187], v[222:225], v[0:15]
	ds_read_b128 v[180:183], v85
	ds_read_b128 v[184:187], v85 offset:4096
	ds_read_b128 v[218:221], v157
	ds_read_b128 v[222:225], v157 offset:4096
	s_waitcnt lgkmcnt(4)
	v_mfma_f32_32x32x16_bf16 v[48:63], v[164:167], v[172:175], v[48:63]
	s_add_u32 m0, s26, 0x10000
	v_lshl_add_u64 v[160:161], v[70:71], 0, s[10:11]
	global_load_lds_dwordx4 v[160:161], off
	v_mfma_f32_32x32x16_bf16 v[32:47], v[164:167], v[176:179], v[32:47]
	v_mfma_f32_32x32x16_bf16 v[16:31], v[168:171], v[172:175], v[16:31]
	s_add_u32 m0, s26, 0x12000
	v_lshl_add_u64 v[162:163], v[68:69], 0, s[10:11]
	global_load_lds_dwordx4 v[162:163], off
	v_mfma_f32_32x32x16_bf16 v[0:15], v[168:171], v[176:179], v[0:15]
	ds_read_b128 v[164:167], v86
	ds_read_b128 v[168:171], v86 offset:4096
	ds_read_b128 v[172:175], v158
	ds_read_b128 v[176:179], v158 offset:4096
	s_waitcnt lgkmcnt(4)
	v_mfma_f32_32x32x16_bf16 v[48:63], v[180:183], v[218:221], v[48:63]
	s_mov_b32 s10, 0xb00680
	s_add_u32 m0, s26, 0x14000
	v_lshl_add_u64 v[160:161], v[66:67], 0, s[10:11]
	global_load_lds_dwordx4 v[160:161], off
	v_mfma_f32_32x32x16_bf16 v[32:47], v[180:183], v[222:225], v[32:47]
	v_mfma_f32_32x32x16_bf16 v[16:31], v[184:187], v[218:221], v[16:31]
	s_add_u32 m0, s26, 0x16000
	v_lshl_add_u64 v[162:163], v[64:65], 0, s[10:11]
	global_load_lds_dwordx4 v[162:163], off
	v_mfma_f32_32x32x16_bf16 v[0:15], v[184:187], v[222:225], v[0:15]
	ds_read_b128 v[180:183], v87
	ds_read_b128 v[184:187], v87 offset:4096
	ds_read_b128 v[218:221], v159
	ds_read_b128 v[222:225], v159 offset:4096
	s_waitcnt lgkmcnt(4)
	v_mfma_f32_32x32x16_bf16 v[48:63], v[164:167], v[172:175], v[48:63]
	v_mfma_f32_32x32x16_bf16 v[32:47], v[164:167], v[176:179], v[32:47]
	v_mfma_f32_32x32x16_bf16 v[16:31], v[168:171], v[172:175], v[16:31]
	v_mfma_f32_32x32x16_bf16 v[0:15], v[168:171], v[176:179], v[0:15]
	s_waitcnt vmcnt(6) lgkmcnt(0)
	s_barrier
;     ...
;   for (int kt = 0; kt < nk; ++kt) {
;     if (kt + 1 < nk) asm volatile("s_waitcnt vmcnt(6)" ::: "memory");
;     else asm volatile("s_waitcnt vmcnt(0)" ::: "memory");
;     __builtin_amdgcn_s_barrier();
;     asm volatile("" ::: "memory");
;     if (kt + 2 < nk) { const int st2 = (st >= 1) ? st - 1 : 2; GEMM_ISSUE(kt + 2, st2); }
;     const char* la = lds + st * STAGE_B;
;     const char* lb = la + 32768;
;     const unsigned sa_u = (unsigned)(size_t)la + arow_u, sb_u = (unsigned)(size_t)lb + brow_u;
;     const unsigned a0 = sa_u + co0, a1 = sa_u + co1, a2 = sa_u + co2, a3 = sa_u + co3;
;     const unsigned b0 = sb_u + co0, b1 = sb_u + co1, b2 = sb_u + co2, b3 = sb_u + co3;
;     {
;       bf16x8 p0, p1, q0, q1, u0, u1, w0, w1;
;       asm volatile(
;         "ds_read_b128 %4, %12\n\tds_read_b128 %5, %12 offset:4096\n\tds_read_b128 %6, %16\n\tds_read_b128 %7, %16 offset:4096\n\t"
;         "ds_read_b128 %8, %13\n\tds_read_b128 %9, %13 offset:4096\n\tds_read_b128 %10, %17\n\tds_read_b128 %11, %17 offset:4096\n\t"
;         "s_waitcnt lgkmcnt(4)\n\t"
;         "v_mfma_f32_32x32x16_bf16 %0, %4, %6, %0\n\tv_mfma_f32_32x32x16_bf16 %1, %4, %7, %1\n\tv_mfma_f32_32x32x16_bf16 %2, %5, %6, %2\n\tv_mfma_f32_32x32x16_bf16 %3, %5, %7, %3\n\t"
;         "ds_read_b128 %4, %14\n\tds_read_b128 %5, %14 offset:4096\n\tds_read_b128 %6, %18\n\tds_read_b128 %7, %18 offset:4096\n\t"
;         "s_waitcnt lgkmcnt(4)\n\t"
;         "v_mfma_f32_32x32x16_bf16 %0, %8, %10, %0\n\tv_mfma_f32_32x32x16_bf16 %1, %8, %11, %1\n\tv_mfma_f32_32x32x16_bf16 %2, %9, %10, %2\n\tv_mfma_f32_32x32x16_bf16 %3, %9, %11, %3\n\t"
;         "ds_read_b128 %8, %15\n\tds_read_b128 %9, %15 offset:4096\n\tds_read_b128 %10, %19\n\tds_read_b128 %11, %19 offset:4096\n\t"
;         "s_waitcnt lgkmcnt(4)\n\t"
;         "v_mfma_f32_32x32x16_bf16 %0, %4, %6, %0\n\tv_mfma_f32_32x32x16_bf16 %1, %4, %7, %1\n\tv_mfma_f32_32x32x16_bf16 %2, %5, %6, %2\n\tv_mfma_f32_32x32x16_bf16 %3, %5, %7, %3\n\t"
;         "s_waitcnt lgkmcnt(0)\n\t"
;         "v_mfma_f32_32x32x16_bf16 %0, %8, %10, %0\n\tv_mfma_f32_32x32x16_bf16 %1, %8, %11, %1\n\tv_mfma_f32_32x32x16_bf16 %2, %9, %10, %2\n\tv_mfma_f32_32x32x16_bf16 %3, %9, %11, %3"
;         : "+v"(acc[0][0]), "+v"(acc[0][1]), "+v"(acc[1][0]), "+v"(acc[1][1]),
;           "=&v"(p0), "=&v"(p1), "=&v"(q0), "=&v"(q1), "=&v"(u0), "=&v"(u1), "=&v"(w0), "=&v"(w1)
	ds_read_b128 v[164:167], v76
	ds_read_b128 v[168:171], v76 offset:4096
	ds_read_b128 v[172:175], v80
	ds_read_b128 v[176:179], v80 offset:4096
	v_mfma_f32_32x32x16_bf16 v[48:63], v[180:183], v[218:221], v[48:63]
	s_mov_b32 s10, 0xa5c2700
	s_add_u32 m0, s26, 0x18000
	v_lshl_add_u64 v[160:161], v[74:75], 0, s[10:11]
	global_load_lds_dwordx4 v[160:161], off
	v_mfma_f32_32x32x16_bf16 v[32:47], v[180:183], v[222:225], v[32:47]
	v_mfma_f32_32x32x16_bf16 v[16:31], v[184:187], v[218:221], v[16:31]
	s_add_u32 m0, s26, 0x1a000
	v_lshl_add_u64 v[162:163], v[72:73], 0, s[10:11]
	global_load_lds_dwordx4 v[162:163], off
	v_mfma_f32_32x32x16_bf16 v[0:15], v[184:187], v[222:225], v[0:15]
	ds_read_b128 v[180:183], v77
	ds_read_b128 v[184:187], v77 offset:4096
	ds_read_b128 v[218:221], v81
	ds_read_b128 v[222:225], v81 offset:4096
	s_waitcnt lgkmcnt(4)
	v_mfma_f32_32x32x16_bf16 v[48:63], v[164:167], v[172:175], v[48:63]
	s_add_u32 m0, s26, 0x1c000
	v_lshl_add_u64 v[160:161], v[70:71], 0, s[10:11]
	global_load_lds_dwordx4 v[160:161], off
	v_mfma_f32_32x32x16_bf16 v[32:47], v[164:167], v[176:179], v[32:47]
	v_mfma_f32_32x32x16_bf16 v[16:31], v[168:171], v[172:175], v[16:31]
	s_add_u32 m0, s26, 0x1e000
	v_lshl_add_u64 v[162:163], v[68:69], 0, s[10:11]
	global_load_lds_dwordx4 v[162:163], off
	v_mfma_f32_32x32x16_bf16 v[0:15], v[168:171], v[176:179], v[0:15]
	ds_read_b128 v[164:167], v78
	ds_read_b128 v[168:171], v78 offset:4096
	ds_read_b128 v[172:175], v82
	ds_read_b128 v[176:179], v82 offset:4096
	s_waitcnt lgkmcnt(4)
	v_mfma_f32_32x32x16_bf16 v[48:63], v[180:183], v[218:221], v[48:63]
	s_mov_b32 s10, 0xb00700
	s_add_u32 m0, s26, 0x20000
	v_lshl_add_u64 v[160:161], v[66:67], 0, s[10:11]
	global_load_lds_dwordx4 v[160:161], off
	v_mfma_f32_32x32x16_bf16 v[32:47], v[180:183], v[222:225], v[32:47]
	v_mfma_f32_32x32x16_bf16 v[16:31], v[184:187], v[218:221], v[16:31]
	s_add_u32 m0, s26, 0x22000
	v_lshl_add_u64 v[162:163], v[64:65], 0, s[10:11]
	global_load_lds_dwordx4 v[162:163], off
	v_mfma_f32_32x32x16_bf16 v[0:15], v[184:187], v[222:225], v[0:15]
	ds_read_b128 v[180:183], v79
	ds_read_b128 v[184:187], v79 offset:4096
	ds_read_b128 v[218:221], v83
	ds_read_b128 v[222:225], v83 offset:4096
	s_waitcnt lgkmcnt(4)
	v_mfma_f32_32x32x16_bf16 v[48:63], v[164:167], v[172:175], v[48:63]
	v_mfma_f32_32x32x16_bf16 v[32:47], v[164:167], v[176:179], v[32:47]
	v_mfma_f32_32x32x16_bf16 v[16:31], v[168:171], v[172:175], v[16:31]
	v_mfma_f32_32x32x16_bf16 v[0:15], v[168:171], v[176:179], v[0:15]
	s_waitcnt vmcnt(6) lgkmcnt(0)
	s_barrier
	ds_read_b128 v[164:167], v76 offset:49152
	ds_read_b128 v[168:171], v76 offset:53248
	ds_read_b128 v[172:175], v80 offset:49152
	ds_read_b128 v[176:179], v80 offset:53248
	v_mfma_f32_32x32x16_bf16 v[48:63], v[180:183], v[218:221], v[48:63]
	s_mov_b32 s10, 0xa5c2780
	s_mov_b32 m0, s26
	v_lshl_add_u64 v[160:161], v[74:75], 0, s[10:11]
	global_load_lds_dwordx4 v[160:161], off
	v_mfma_f32_32x32x16_bf16 v[32:47], v[180:183], v[222:225], v[32:47]
	v_mfma_f32_32x32x16_bf16 v[16:31], v[184:187], v[218:221], v[16:31]
	s_add_u32 m0, s26, 0x2000
	v_lshl_add_u64 v[162:163], v[72:73], 0, s[10:11]
	global_load_lds_dwordx4 v[162:163], off
	v_mfma_f32_32x32x16_bf16 v[0:15], v[184:187], v[222:225], v[0:15]
	ds_read_b128 v[180:183], v77 offset:49152
	ds_read_b128 v[184:187], v77 offset:53248
	ds_read_b128 v[218:221], v81 offset:49152
	ds_read_b128 v[222:225], v81 offset:53248
	s_waitcnt lgkmcnt(4)
	v_mfma_f32_32x32x16_bf16 v[48:63], v[164:167], v[172:175], v[48:63]
	s_add_u32 m0, s26, 0x4000
	v_lshl_add_u64 v[160:161], v[70:71], 0, s[10:11]
	global_load_lds_dwordx4 v[160:161], off
	v_mfma_f32_32x32x16_bf16 v[32:47], v[164:167], v[176:179], v[32:47]
	v_mfma_f32_32x32x16_bf16 v[16:31], v[168:171], v[172:175], v[16:31]
	s_add_u32 m0, s26, 0x6000
	v_lshl_add_u64 v[162:163], v[68:69], 0, s[10:11]
	global_load_lds_dwordx4 v[162:163], off
	v_mfma_f32_32x32x16_bf16 v[0:15], v[168:171], v[176:179], v[0:15]
	ds_read_b128 v[164:167], v78 offset:49152
	ds_read_b128 v[168:171], v78 offset:53248
	ds_read_b128 v[172:175], v82 offset:49152
	ds_read_b128 v[176:179], v82 offset:53248
	s_waitcnt lgkmcnt(4)
	v_mfma_f32_32x32x16_bf16 v[48:63], v[180:183], v[218:221], v[48:63]
	s_mov_b32 s10, 0xb00780
	s_add_u32 m0, s26, 0x8000
	v_lshl_add_u64 v[160:161], v[66:67], 0, s[10:11]
	global_load_lds_dwordx4 v[160:161], off
	v_mfma_f32_32x32x16_bf16 v[32:47], v[180:183], v[222:225], v[32:47]
	v_mfma_f32_32x32x16_bf16 v[16:31], v[184:187], v[218:221], v[16:31]
	s_add_u32 m0, s26, 0xa000
	v_lshl_add_u64 v[162:163], v[64:65], 0, s[10:11]
	global_load_lds_dwordx4 v[162:163], off
	v_mfma_f32_32x32x16_bf16 v[0:15], v[184:187], v[222:225], v[0:15]
	ds_read_b128 v[180:183], v79 offset:49152
	ds_read_b128 v[184:187], v79 offset:53248
	ds_read_b128 v[218:221], v83 offset:49152
	ds_read_b128 v[222:225], v83 offset:53248
	s_waitcnt lgkmcnt(4)
	v_mfma_f32_32x32x16_bf16 v[48:63], v[164:167], v[172:175], v[48:63]
	v_mfma_f32_32x32x16_bf16 v[32:47], v[164:167], v[176:179], v[32:47]
	v_mfma_f32_32x32x16_bf16 v[16:31], v[168:171], v[172:175], v[16:31]
	v_mfma_f32_32x32x16_bf16 v[0:15], v[168:171], v[176:179], v[0:15]
	s_waitcnt vmcnt(6) lgkmcnt(0)
	s_barrier
;     ...
;   for (int kt = 0; kt < nk; ++kt) {
;     if (kt + 1 < nk) asm volatile("s_waitcnt vmcnt(6)" ::: "memory");
;     else asm volatile("s_waitcnt vmcnt(0)" ::: "memory");
;     __builtin_amdgcn_s_barrier();
;     asm volatile("" ::: "memory");
;     if (kt + 2 < nk) { const int st2 = (st >= 1) ? st - 1 : 2; GEMM_ISSUE(kt + 2, st2); }
;     const char* la = lds + st * STAGE_B;
;     const char* lb = la + 32768;
;     const unsigned sa_u = (unsigned)(size_t)la + arow_u, sb_u = (unsigned)(size_t)lb + brow_u;
;     const unsigned a0 = sa_u + co0, a1 = sa_u + co1, a2 = sa_u + co2, a3 = sa_u + co3;
;     const unsigned b0 = sb_u + co0, b1 = sb_u + co1, b2 = sb_u + co2, b3 = sb_u + co3;
;     {
;       bf16x8 p0, p1, q0, q1, u0, u1, w0, w1;
;       asm volatile(
;         "ds_read_b128 %4, %12\n\tds_read_b128 %5, %12 offset:4096\n\tds_read_b128 %6, %16\n\tds_read_b128 %7, %16 offset:4096\n\t"
;         "ds_read_b128 %8, %13\n\tds_read_b128 %9, %13 offset:4096\n\tds_read_b128 %10, %17\n\tds_read_b128 %11, %17 offset:4096\n\t"
;         "s_waitcnt lgkmcnt(4)\n\t"
;         "v_mfma_f32_32x32x16_bf16 %0, %4, %6, %0\n\tv_mfma_f32_32x32x16_bf16 %1, %4, %7, %1\n\tv_mfma_f32_32x32x16_bf16 %2, %5, %6, %2\n\tv_mfma_f32_32x32x16_bf16 %3, %5, %7, %3\n\t"
;         "ds_read_b128 %4, %14\n\tds_read_b128 %5, %14 offset:4096\n\tds_read_b128 %6, %18\n\tds_read_b128 %7, %18 offset:4096\n\t"
;         "s_waitcnt lgkmcnt(4)\n\t"
;         "v_mfma_f32_32x32x16_bf16 %0, %8, %10, %0\n\tv_mfma_f32_32x32x16_bf16 %1, %8, %11, %1\n\tv_mfma_f32_32x32x16_bf16 %2, %9, %10, %2\n\tv_mfma_f32_32x32x16_bf16 %3, %9, %11, %3\n\t"
;         "ds_read_b128 %8, %15\n\tds_read_b128 %9, %15 offset:4096\n\tds_read_b128 %10, %19\n\tds_read_b128 %11, %19 offset:4096\n\t"
;         "s_waitcnt lgkmcnt(4)\n\t"
;         "v_mfma_f32_32x32x16_bf16 %0, %4, %6, %0\n\tv_mfma_f32_32x32x16_bf16 %1, %4, %7, %1\n\tv_mfma_f32_32x32x16_bf16 %2, %5, %6, %2\n\tv_mfma_f32_32x32x16_bf16 %3, %5, %7, %3\n\t"
;         "s_waitcnt lgkmcnt(0)\n\t"
;         "v_mfma_f32_32x32x16_bf16 %0, %8, %10, %0\n\tv_mfma_f32_32x32x16_bf16 %1, %8, %11, %1\n\tv_mfma_f32_32x32x16_bf16 %2, %9, %10, %2\n\tv_mfma_f32_32x32x16_bf16 %3, %9, %11, %3"
;         : "+v"(acc[0][0]), "+v"(acc[0][1]), "+v"(acc[1][0]), "+v"(acc[1][1]),
;           "=&v"(p0), "=&v"(p1), "=&v"(q0), "=&v"(q1), "=&v"(u0), "=&v"(u1), "=&v"(w0), "=&v"(w1)
	ds_read_b128 v[164:167], v84
	ds_read_b128 v[168:171], v84 offset:4096
	ds_read_b128 v[172:175], v156
	ds_read_b128 v[176:179], v156 offset:4096
	v_mfma_f32_32x32x16_bf16 v[48:63], v[180:183], v[218:221], v[48:63]
	s_mov_b32 s10, 0xa5c2800
	s_add_u32 m0, s26, 0xc000
	v_lshl_add_u64 v[160:161], v[74:75], 0, s[10:11]
	global_load_lds_dwordx4 v[160:161], off
	v_mfma_f32_32x32x16_bf16 v[32:47], v[180:183], v[222:225], v[32:47]
	v_mfma_f32_32x32x16_bf16 v[16:31], v[184:187], v[218:221], v[16:31]
	s_add_u32 m0, s26, 0xe000
	v_lshl_add_u64 v[162:163], v[72:73], 0, s[10:11]
	global_load_lds_dwordx4 v[162:163], off
	v_mfma_f32_32x32x16_bf16 v[0:15], v[184:187], v[222:225], v[0:15]
	ds_read_b128 v[180:183], v85
	ds_read_b128 v[184:187], v85 offset:4096
	ds_read_b128 v[218:221], v157
	ds_read_b128 v[222:225], v157 offset:4096
	s_waitcnt lgkmcnt(4)
	v_mfma_f32_32x32x16_bf16 v[48:63], v[164:167], v[172:175], v[48:63]
	s_add_u32 m0, s26, 0x10000
	v_lshl_add_u64 v[160:161], v[70:71], 0, s[10:11]
	global_load_lds_dwordx4 v[160:161], off
	v_mfma_f32_32x32x16_bf16 v[32:47], v[164:167], v[176:179], v[32:47]
	v_mfma_f32_32x32x16_bf16 v[16:31], v[168:171], v[172:175], v[16:31]
	s_add_u32 m0, s26, 0x12000
	v_lshl_add_u64 v[162:163], v[68:69], 0, s[10:11]
	global_load_lds_dwordx4 v[162:163], off
	v_mfma_f32_32x32x16_bf16 v[0:15], v[168:171], v[176:179], v[0:15]
	ds_read_b128 v[164:167], v86
	ds_read_b128 v[168:171], v86 offset:4096
	ds_read_b128 v[172:175], v158
	ds_read_b128 v[176:179], v158 offset:4096
	s_waitcnt lgkmcnt(4)
	v_mfma_f32_32x32x16_bf16 v[48:63], v[180:183], v[218:221], v[48:63]
	s_mov_b32 s10, 0xb00800
	s_add_u32 m0, s26, 0x14000
	v_lshl_add_u64 v[160:161], v[66:67], 0, s[10:11]
	global_load_lds_dwordx4 v[160:161], off
	v_mfma_f32_32x32x16_bf16 v[32:47], v[180:183], v[222:225], v[32:47]
	v_mfma_f32_32x32x16_bf16 v[16:31], v[184:187], v[218:221], v[16:31]
	s_add_u32 m0, s26, 0x16000
	v_lshl_add_u64 v[162:163], v[64:65], 0, s[10:11]
	global_load_lds_dwordx4 v[162:163], off
	v_mfma_f32_32x32x16_bf16 v[0:15], v[184:187], v[222:225], v[0:15]
	ds_read_b128 v[180:183], v87
	ds_read_b128 v[184:187], v87 offset:4096
	ds_read_b128 v[218:221], v159
	ds_read_b128 v[222:225], v159 offset:4096
	s_waitcnt lgkmcnt(4)
	v_mfma_f32_32x32x16_bf16 v[48:63], v[164:167], v[172:175], v[48:63]
	v_mfma_f32_32x32x16_bf16 v[32:47], v[164:167], v[176:179], v[32:47]
	v_mfma_f32_32x32x16_bf16 v[16:31], v[168:171], v[172:175], v[16:31]
	v_mfma_f32_32x32x16_bf16 v[0:15], v[168:171], v[176:179], v[0:15]
	s_waitcnt vmcnt(6) lgkmcnt(0)
	s_barrier
	ds_read_b128 v[164:167], v76
	ds_read_b128 v[168:171], v76 offset:4096
	ds_read_b128 v[172:175], v80
	ds_read_b128 v[176:179], v80 offset:4096
	v_mfma_f32_32x32x16_bf16 v[48:63], v[180:183], v[218:221], v[48:63]
	s_mov_b32 s10, 0xa5c2880
	s_add_u32 m0, s26, 0x18000
	v_lshl_add_u64 v[160:161], v[74:75], 0, s[10:11]
	global_load_lds_dwordx4 v[160:161], off
	v_mfma_f32_32x32x16_bf16 v[32:47], v[180:183], v[222:225], v[32:47]
	v_mfma_f32_32x32x16_bf16 v[16:31], v[184:187], v[218:221], v[16:31]
	s_add_u32 m0, s26, 0x1a000
	v_lshl_add_u64 v[162:163], v[72:73], 0, s[10:11]
	global_load_lds_dwordx4 v[162:163], off
	v_mfma_f32_32x32x16_bf16 v[0:15], v[184:187], v[222:225], v[0:15]
	ds_read_b128 v[180:183], v77
	ds_read_b128 v[184:187], v77 offset:4096
	ds_read_b128 v[218:221], v81
	ds_read_b128 v[222:225], v81 offset:4096
	s_waitcnt lgkmcnt(4)
	v_mfma_f32_32x32x16_bf16 v[48:63], v[164:167], v[172:175], v[48:63]
	s_add_u32 m0, s26, 0x1c000
	v_lshl_add_u64 v[160:161], v[70:71], 0, s[10:11]
	global_load_lds_dwordx4 v[160:161], off
	v_mfma_f32_32x32x16_bf16 v[32:47], v[164:167], v[176:179], v[32:47]
	v_mfma_f32_32x32x16_bf16 v[16:31], v[168:171], v[172:175], v[16:31]
	s_add_u32 m0, s26, 0x1e000
	v_lshl_add_u64 v[162:163], v[68:69], 0, s[10:11]
	global_load_lds_dwordx4 v[162:163], off
	v_mfma_f32_32x32x16_bf16 v[0:15], v[168:171], v[176:179], v[0:15]
	ds_read_b128 v[164:167], v78
	ds_read_b128 v[168:171], v78 offset:4096
	ds_read_b128 v[172:175], v82
	ds_read_b128 v[176:179], v82 offset:4096
	s_waitcnt lgkmcnt(4)
	v_mfma_f32_32x32x16_bf16 v[48:63], v[180:183], v[218:221], v[48:63]
	s_mov_b32 s10, 0xb00880
	s_add_u32 m0, s26, 0x20000
	v_lshl_add_u64 v[160:161], v[66:67], 0, s[10:11]
	global_load_lds_dwordx4 v[160:161], off
	v_mfma_f32_32x32x16_bf16 v[32:47], v[180:183], v[222:225], v[32:47]
	v_mfma_f32_32x32x16_bf16 v[16:31], v[184:187], v[218:221], v[16:31]
	s_add_u32 m0, s26, 0x22000
	v_lshl_add_u64 v[162:163], v[64:65], 0, s[10:11]
	global_load_lds_dwordx4 v[162:163], off
	v_mfma_f32_32x32x16_bf16 v[0:15], v[184:187], v[222:225], v[0:15]
	ds_read_b128 v[180:183], v79
	ds_read_b128 v[184:187], v79 offset:4096
	ds_read_b128 v[218:221], v83
	ds_read_b128 v[222:225], v83 offset:4096
	s_waitcnt lgkmcnt(4)
	v_mfma_f32_32x32x16_bf16 v[48:63], v[164:167], v[172:175], v[48:63]
	v_mfma_f32_32x32x16_bf16 v[32:47], v[164:167], v[176:179], v[32:47]
	v_mfma_f32_32x32x16_bf16 v[16:31], v[168:171], v[172:175], v[16:31]
	v_mfma_f32_32x32x16_bf16 v[0:15], v[168:171], v[176:179], v[0:15]
	s_waitcnt vmcnt(6) lgkmcnt(0)
	s_barrier
;     ...
;   for (int kt = 0; kt < nk; ++kt) {
;     if (kt + 1 < nk) asm volatile("s_waitcnt vmcnt(6)" ::: "memory");
;     else asm volatile("s_waitcnt vmcnt(0)" ::: "memory");
;     __builtin_amdgcn_s_barrier();
;     asm volatile("" ::: "memory");
;     if (kt + 2 < nk) { const int st2 = (st >= 1) ? st - 1 : 2; GEMM_ISSUE(kt + 2, st2); }
;     const char* la = lds + st * STAGE_B;
;     const char* lb = la + 32768;
;     const unsigned sa_u = (unsigned)(size_t)la + arow_u, sb_u = (unsigned)(size_t)lb + brow_u;
;     const unsigned a0 = sa_u + co0, a1 = sa_u + co1, a2 = sa_u + co2, a3 = sa_u + co3;
;     const unsigned b0 = sb_u + co0, b1 = sb_u + co1, b2 = sb_u + co2, b3 = sb_u + co3;
;     {
;       bf16x8 p0, p1, q0, q1, u0, u1, w0, w1;
;       asm volatile(
;         "ds_read_b128 %4, %12\n\tds_read_b128 %5, %12 offset:4096\n\tds_read_b128 %6, %16\n\tds_read_b128 %7, %16 offset:4096\n\t"
;         "ds_read_b128 %8, %13\n\tds_read_b128 %9, %13 offset:4096\n\tds_read_b128 %10, %17\n\tds_read_b128 %11, %17 offset:4096\n\t"
;         "s_waitcnt lgkmcnt(4)\n\t"
;         "v_mfma_f32_32x32x16_bf16 %0, %4, %6, %0\n\tv_mfma_f32_32x32x16_bf16 %1, %4, %7, %1\n\tv_mfma_f32_32x32x16_bf16 %2, %5, %6, %2\n\tv_mfma_f32_32x32x16_bf16 %3, %5, %7, %3\n\t"
;         "ds_read_b128 %4, %14\n\tds_read_b128 %5, %14 offset:4096\n\tds_read_b128 %6, %18\n\tds_read_b128 %7, %18 offset:4096\n\t"
;         "s_waitcnt lgkmcnt(4)\n\t"
;         "v_mfma_f32_32x32x16_bf16 %0, %8, %10, %0\n\tv_mfma_f32_32x32x16_bf16 %1, %8, %11, %1\n\tv_mfma_f32_32x32x16_bf16 %2, %9, %10, %2\n\tv_mfma_f32_32x32x16_bf16 %3, %9, %11, %3\n\t"
;         "ds_read_b128 %8, %15\n\tds_read_b128 %9, %15 offset:4096\n\tds_read_b128 %10, %19\n\tds_read_b128 %11, %19 offset:4096\n\t"
;         "s_waitcnt lgkmcnt(4)\n\t"
;         "v_mfma_f32_32x32x16_bf16 %0, %4, %6, %0\n\tv_mfma_f32_32x32x16_bf16 %1, %4, %7, %1\n\tv_mfma_f32_32x32x16_bf16 %2, %5, %6, %2\n\tv_mfma_f32_32x32x16_bf16 %3, %5, %7, %3\n\t"
;         "s_waitcnt lgkmcnt(0)\n\t"
;         "v_mfma_f32_32x32x16_bf16 %0, %8, %10, %0\n\tv_mfma_f32_32x32x16_bf16 %1, %8, %11, %1\n\tv_mfma_f32_32x32x16_bf16 %2, %9, %10, %2\n\tv_mfma_f32_32x32x16_bf16 %3, %9, %11, %3"
;         : "+v"(acc[0][0]), "+v"(acc[0][1]), "+v"(acc[1][0]), "+v"(acc[1][1]),
;           "=&v"(p0), "=&v"(p1), "=&v"(q0), "=&v"(q1), "=&v"(u0), "=&v"(u1), "=&v"(w0), "=&v"(w1)
	ds_read_b128 v[164:167], v76 offset:49152
	ds_read_b128 v[168:171], v76 offset:53248
	ds_read_b128 v[172:175], v80 offset:49152
	ds_read_b128 v[176:179], v80 offset:53248
	v_mfma_f32_32x32x16_bf16 v[48:63], v[180:183], v[218:221], v[48:63]
	s_mov_b32 s10, 0xa5c2900
	s_mov_b32 m0, s26
	v_lshl_add_u64 v[160:161], v[74:75], 0, s[10:11]
	global_load_lds_dwordx4 v[160:161], off
	v_mfma_f32_32x32x16_bf16 v[32:47], v[180:183], v[222:225], v[32:47]
	v_mfma_f32_32x32x16_bf16 v[16:31], v[184:187], v[218:221], v[16:31]
	s_add_u32 m0, s26, 0x2000
	v_lshl_add_u64 v[162:163], v[72:73], 0, s[10:11]
	global_load_lds_dwordx4 v[162:163], off
	v_mfma_f32_32x32x16_bf16 v[0:15], v[184:187], v[222:225], v[0:15]
	ds_read_b128 v[180:183], v77 offset:49152
	ds_read_b128 v[184:187], v77 offset:53248
	ds_read_b128 v[218:221], v81 offset:49152
	ds_read_b128 v[222:225], v81 offset:53248
	s_waitcnt lgkmcnt(4)
	v_mfma_f32_32x32x16_bf16 v[48:63], v[164:167], v[172:175], v[48:63]
	s_add_u32 m0, s26, 0x4000
	v_lshl_add_u64 v[160:161], v[70:71], 0, s[10:11]
	global_load_lds_dwordx4 v[160:161], off
	v_mfma_f32_32x32x16_bf16 v[32:47], v[164:167], v[176:179], v[32:47]
	v_mfma_f32_32x32x16_bf16 v[16:31], v[168:171], v[172:175], v[16:31]
	s_add_u32 m0, s26, 0x6000
	v_lshl_add_u64 v[162:163], v[68:69], 0, s[10:11]
	global_load_lds_dwordx4 v[162:163], off
	v_mfma_f32_32x32x16_bf16 v[0:15], v[168:171], v[176:179], v[0:15]
	ds_read_b128 v[164:167], v78 offset:49152
	ds_read_b128 v[168:171], v78 offset:53248
	ds_read_b128 v[172:175], v82 offset:49152
	ds_read_b128 v[176:179], v82 offset:53248
	s_waitcnt lgkmcnt(4)
	v_mfma_f32_32x32x16_bf16 v[48:63], v[180:183], v[218:221], v[48:63]
	s_mov_b32 s10, 0xb00900
	s_add_u32 m0, s26, 0x8000
	v_lshl_add_u64 v[160:161], v[66:67], 0, s[10:11]
	global_load_lds_dwordx4 v[160:161], off
	v_mfma_f32_32x32x16_bf16 v[32:47], v[180:183], v[222:225], v[32:47]
	v_mfma_f32_32x32x16_bf16 v[16:31], v[184:187], v[218:221], v[16:31]
	s_add_u32 m0, s26, 0xa000
	v_lshl_add_u64 v[162:163], v[64:65], 0, s[10:11]
	global_load_lds_dwordx4 v[162:163], off
	v_mfma_f32_32x32x16_bf16 v[0:15], v[184:187], v[222:225], v[0:15]
	ds_read_b128 v[180:183], v79 offset:49152
	ds_read_b128 v[184:187], v79 offset:53248
	ds_read_b128 v[218:221], v83 offset:49152
	ds_read_b128 v[222:225], v83 offset:53248
	s_waitcnt lgkmcnt(4)
	v_mfma_f32_32x32x16_bf16 v[48:63], v[164:167], v[172:175], v[48:63]
	v_mfma_f32_32x32x16_bf16 v[32:47], v[164:167], v[176:179], v[32:47]
	v_mfma_f32_32x32x16_bf16 v[16:31], v[168:171], v[172:175], v[16:31]
	v_mfma_f32_32x32x16_bf16 v[0:15], v[168:171], v[176:179], v[0:15]
	s_waitcnt vmcnt(6) lgkmcnt(0)
	s_barrier
	ds_read_b128 v[164:167], v84
	ds_read_b128 v[168:171], v84 offset:4096
	ds_read_b128 v[172:175], v156
	ds_read_b128 v[176:179], v156 offset:4096
	v_mfma_f32_32x32x16_bf16 v[48:63], v[180:183], v[218:221], v[48:63]
	s_mov_b32 s10, 0xa5c2980
	s_add_u32 m0, s26, 0xc000
	v_lshl_add_u64 v[160:161], v[74:75], 0, s[10:11]
	global_load_lds_dwordx4 v[160:161], off
	v_mfma_f32_32x32x16_bf16 v[32:47], v[180:183], v[222:225], v[32:47]
	v_mfma_f32_32x32x16_bf16 v[16:31], v[184:187], v[218:221], v[16:31]
	s_add_u32 m0, s26, 0xe000
	v_lshl_add_u64 v[162:163], v[72:73], 0, s[10:11]
	global_load_lds_dwordx4 v[162:163], off
	v_mfma_f32_32x32x16_bf16 v[0:15], v[184:187], v[222:225], v[0:15]
	ds_read_b128 v[180:183], v85
	ds_read_b128 v[184:187], v85 offset:4096
	ds_read_b128 v[218:221], v157
	ds_read_b128 v[222:225], v157 offset:4096
	s_waitcnt lgkmcnt(4)
	v_mfma_f32_32x32x16_bf16 v[48:63], v[164:167], v[172:175], v[48:63]
	s_add_u32 m0, s26, 0x10000
	v_lshl_add_u64 v[160:161], v[70:71], 0, s[10:11]
	global_load_lds_dwordx4 v[160:161], off
	v_mfma_f32_32x32x16_bf16 v[32:47], v[164:167], v[176:179], v[32:47]
	v_mfma_f32_32x32x16_bf16 v[16:31], v[168:171], v[172:175], v[16:31]
	s_add_u32 m0, s26, 0x12000
	v_lshl_add_u64 v[162:163], v[68:69], 0, s[10:11]
	global_load_lds_dwordx4 v[162:163], off
	v_mfma_f32_32x32x16_bf16 v[0:15], v[168:171], v[176:179], v[0:15]
	ds_read_b128 v[164:167], v86
	ds_read_b128 v[168:171], v86 offset:4096
	ds_read_b128 v[172:175], v158
	ds_read_b128 v[176:179], v158 offset:4096
	s_waitcnt lgkmcnt(4)
	v_mfma_f32_32x32x16_bf16 v[48:63], v[180:183], v[218:221], v[48:63]
	s_mov_b32 s10, 0xb00980
	s_add_u32 m0, s26, 0x14000
	v_lshl_add_u64 v[160:161], v[66:67], 0, s[10:11]
	global_load_lds_dwordx4 v[160:161], off
	v_mfma_f32_32x32x16_bf16 v[32:47], v[180:183], v[222:225], v[32:47]
	v_mfma_f32_32x32x16_bf16 v[16:31], v[184:187], v[218:221], v[16:31]
	s_add_u32 m0, s26, 0x16000
	v_lshl_add_u64 v[162:163], v[64:65], 0, s[10:11]
	global_load_lds_dwordx4 v[162:163], off
	v_mfma_f32_32x32x16_bf16 v[0:15], v[184:187], v[222:225], v[0:15]
	ds_read_b128 v[180:183], v87
	ds_read_b128 v[184:187], v87 offset:4096
	ds_read_b128 v[218:221], v159
	ds_read_b128 v[222:225], v159 offset:4096
	s_waitcnt lgkmcnt(4)
	v_mfma_f32_32x32x16_bf16 v[48:63], v[164:167], v[172:175], v[48:63]
	v_mfma_f32_32x32x16_bf16 v[32:47], v[164:167], v[176:179], v[32:47]
	v_mfma_f32_32x32x16_bf16 v[16:31], v[168:171], v[172:175], v[16:31]
	v_mfma_f32_32x32x16_bf16 v[0:15], v[168:171], v[176:179], v[0:15]
	s_waitcnt vmcnt(6) lgkmcnt(0)
	s_barrier
;     ...
;   for (int kt = 0; kt < nk; ++kt) {
;     if (kt + 1 < nk) asm volatile("s_waitcnt vmcnt(6)" ::: "memory");
;     else asm volatile("s_waitcnt vmcnt(0)" ::: "memory");
;     __builtin_amdgcn_s_barrier();
;     asm volatile("" ::: "memory");
;     if (kt + 2 < nk) { const int st2 = (st >= 1) ? st - 1 : 2; GEMM_ISSUE(kt + 2, st2); }
;     const char* la = lds + st * STAGE_B;
;     const char* lb = la + 32768;
;     const unsigned sa_u = (unsigned)(size_t)la + arow_u, sb_u = (unsigned)(size_t)lb + brow_u;
;     const unsigned a0 = sa_u + co0, a1 = sa_u + co1, a2 = sa_u + co2, a3 = sa_u + co3;
;     const unsigned b0 = sb_u + co0, b1 = sb_u + co1, b2 = sb_u + co2, b3 = sb_u + co3;
;     {
;       bf16x8 p0, p1, q0, q1, u0, u1, w0, w1;
;       asm volatile(
;         "ds_read_b128 %4, %12\n\tds_read_b128 %5, %12 offset:4096\n\tds_read_b128 %6, %16\n\tds_read_b128 %7, %16 offset:4096\n\t"
;         "ds_read_b128 %8, %13\n\tds_read_b128 %9, %13 offset:4096\n\tds_read_b128 %10, %17\n\tds_read_b128 %11, %17 offset:4096\n\t"
;         "s_waitcnt lgkmcnt(4)\n\t"
;         "v_mfma_f32_32x32x16_bf16 %0, %4, %6, %0\n\tv_mfma_f32_32x32x16_bf16 %1, %4, %7, %1\n\tv_mfma_f32_32x32x16_bf16 %2, %5, %6, %2\n\tv_mfma_f32_32x32x16_bf16 %3, %5, %7, %3\n\t"
;         "ds_read_b128 %4, %14\n\tds_read_b128 %5, %14 offset:4096\n\tds_read_b128 %6, %18\n\tds_read_b128 %7, %18 offset:4096\n\t"
;         "s_waitcnt lgkmcnt(4)\n\t"
;         "v_mfma_f32_32x32x16_bf16 %0, %8, %10, %0\n\tv_mfma_f32_32x32x16_bf16 %1, %8, %11, %1\n\tv_mfma_f32_32x32x16_bf16 %2, %9, %10, %2\n\tv_mfma_f32_32x32x16_bf16 %3, %9, %11, %3\n\t"
;         "ds_read_b128 %8, %15\n\tds_read_b128 %9, %15 offset:4096\n\tds_read_b128 %10, %19\n\tds_read_b128 %11, %19 offset:4096\n\t"
;         "s_waitcnt lgkmcnt(4)\n\t"
;         "v_mfma_f32_32x32x16_bf16 %0, %4, %6, %0\n\tv_mfma_f32_32x32x16_bf16 %1, %4, %7, %1\n\tv_mfma_f32_32x32x16_bf16 %2, %5, %6, %2\n\tv_mfma_f32_32x32x16_bf16 %3, %5, %7, %3\n\t"
;         "s_waitcnt lgkmcnt(0)\n\t"
;         "v_mfma_f32_32x32x16_bf16 %0, %8, %10, %0\n\tv_mfma_f32_32x32x16_bf16 %1, %8, %11, %1\n\tv_mfma_f32_32x32x16_bf16 %2, %9, %10, %2\n\tv_mfma_f32_32x32x16_bf16 %3, %9, %11, %3"
;         : "+v"(acc[0][0]), "+v"(acc[0][1]), "+v"(acc[1][0]), "+v"(acc[1][1]),
;           "=&v"(p0), "=&v"(p1), "=&v"(q0), "=&v"(q1), "=&v"(u0), "=&v"(u1), "=&v"(w0), "=&v"(w1)
	ds_read_b128 v[164:167], v76
	ds_read_b128 v[168:171], v76 offset:4096
	ds_read_b128 v[172:175], v80
	ds_read_b128 v[176:179], v80 offset:4096
	v_mfma_f32_32x32x16_bf16 v[48:63], v[180:183], v[218:221], v[48:63]
	s_mov_b32 s10, 0xa5c2a00
	s_add_u32 m0, s26, 0x18000
	v_lshl_add_u64 v[160:161], v[74:75], 0, s[10:11]
	global_load_lds_dwordx4 v[160:161], off
	v_mfma_f32_32x32x16_bf16 v[32:47], v[180:183], v[222:225], v[32:47]
	v_mfma_f32_32x32x16_bf16 v[16:31], v[184:187], v[218:221], v[16:31]
	s_add_u32 m0, s26, 0x1a000
	v_lshl_add_u64 v[162:163], v[72:73], 0, s[10:11]
	global_load_lds_dwordx4 v[162:163], off
	v_mfma_f32_32x32x16_bf16 v[0:15], v[184:187], v[222:225], v[0:15]
	ds_read_b128 v[180:183], v77
	ds_read_b128 v[184:187], v77 offset:4096
	ds_read_b128 v[218:221], v81
	ds_read_b128 v[222:225], v81 offset:4096
	s_waitcnt lgkmcnt(4)
	v_mfma_f32_32x32x16_bf16 v[48:63], v[164:167], v[172:175], v[48:63]
	s_add_u32 m0, s26, 0x1c000
	v_lshl_add_u64 v[160:161], v[70:71], 0, s[10:11]
	global_load_lds_dwordx4 v[160:161], off
	v_mfma_f32_32x32x16_bf16 v[32:47], v[164:167], v[176:179], v[32:47]
	v_mfma_f32_32x32x16_bf16 v[16:31], v[168:171], v[172:175], v[16:31]
	s_add_u32 m0, s26, 0x1e000
	v_lshl_add_u64 v[162:163], v[68:69], 0, s[10:11]
	global_load_lds_dwordx4 v[162:163], off
	v_mfma_f32_32x32x16_bf16 v[0:15], v[168:171], v[176:179], v[0:15]
	ds_read_b128 v[164:167], v78
	ds_read_b128 v[168:171], v78 offset:4096
	ds_read_b128 v[172:175], v82
	ds_read_b128 v[176:179], v82 offset:4096
	s_waitcnt lgkmcnt(4)
	v_mfma_f32_32x32x16_bf16 v[48:63], v[180:183], v[218:221], v[48:63]
	s_mov_b32 s10, 0xb00a00
	s_add_u32 m0, s26, 0x20000
	v_lshl_add_u64 v[160:161], v[66:67], 0, s[10:11]
	global_load_lds_dwordx4 v[160:161], off
	v_mfma_f32_32x32x16_bf16 v[32:47], v[180:183], v[222:225], v[32:47]
	v_mfma_f32_32x32x16_bf16 v[16:31], v[184:187], v[218:221], v[16:31]
	s_add_u32 m0, s26, 0x22000
	v_lshl_add_u64 v[162:163], v[64:65], 0, s[10:11]
	global_load_lds_dwordx4 v[162:163], off
	v_mfma_f32_32x32x16_bf16 v[0:15], v[184:187], v[222:225], v[0:15]
	ds_read_b128 v[180:183], v79
	ds_read_b128 v[184:187], v79 offset:4096
	ds_read_b128 v[218:221], v83
	ds_read_b128 v[222:225], v83 offset:4096
	s_waitcnt lgkmcnt(4)
	v_mfma_f32_32x32x16_bf16 v[48:63], v[164:167], v[172:175], v[48:63]
	v_mfma_f32_32x32x16_bf16 v[32:47], v[164:167], v[176:179], v[32:47]
	v_mfma_f32_32x32x16_bf16 v[16:31], v[168:171], v[172:175], v[16:31]
	v_mfma_f32_32x32x16_bf16 v[0:15], v[168:171], v[176:179], v[0:15]
	s_waitcnt vmcnt(6) lgkmcnt(0)
	s_barrier
	ds_read_b128 v[164:167], v76 offset:49152
	ds_read_b128 v[168:171], v76 offset:53248
	ds_read_b128 v[172:175], v80 offset:49152
	ds_read_b128 v[176:179], v80 offset:53248
	v_mfma_f32_32x32x16_bf16 v[48:63], v[180:183], v[218:221], v[48:63]
	s_mov_b32 s10, 0xa5c2a80
	s_mov_b32 m0, s26
	v_lshl_add_u64 v[160:161], v[74:75], 0, s[10:11]
	global_load_lds_dwordx4 v[160:161], off
	v_mfma_f32_32x32x16_bf16 v[32:47], v[180:183], v[222:225], v[32:47]
	v_mfma_f32_32x32x16_bf16 v[16:31], v[184:187], v[218:221], v[16:31]
	s_add_u32 m0, s26, 0x2000
	v_lshl_add_u64 v[162:163], v[72:73], 0, s[10:11]
	global_load_lds_dwordx4 v[162:163], off
	v_mfma_f32_32x32x16_bf16 v[0:15], v[184:187], v[222:225], v[0:15]
	ds_read_b128 v[180:183], v77 offset:49152
	ds_read_b128 v[184:187], v77 offset:53248
	ds_read_b128 v[218:221], v81 offset:49152
	ds_read_b128 v[222:225], v81 offset:53248
	s_waitcnt lgkmcnt(4)
	v_mfma_f32_32x32x16_bf16 v[48:63], v[164:167], v[172:175], v[48:63]
	s_add_u32 m0, s26, 0x4000
	v_lshl_add_u64 v[160:161], v[70:71], 0, s[10:11]
	global_load_lds_dwordx4 v[160:161], off
	v_mfma_f32_32x32x16_bf16 v[32:47], v[164:167], v[176:179], v[32:47]
	v_mfma_f32_32x32x16_bf16 v[16:31], v[168:171], v[172:175], v[16:31]
	s_add_u32 m0, s26, 0x6000
	v_lshl_add_u64 v[162:163], v[68:69], 0, s[10:11]
	global_load_lds_dwordx4 v[162:163], off
	v_mfma_f32_32x32x16_bf16 v[0:15], v[168:171], v[176:179], v[0:15]
	ds_read_b128 v[164:167], v78 offset:49152
	ds_read_b128 v[168:171], v78 offset:53248
	ds_read_b128 v[172:175], v82 offset:49152
	ds_read_b128 v[176:179], v82 offset:53248
	s_waitcnt lgkmcnt(4)
	v_mfma_f32_32x32x16_bf16 v[48:63], v[180:183], v[218:221], v[48:63]
	s_mov_b32 s10, 0xb00a80
	s_add_u32 m0, s26, 0x8000
	v_lshl_add_u64 v[160:161], v[66:67], 0, s[10:11]
	global_load_lds_dwordx4 v[160:161], off
	v_mfma_f32_32x32x16_bf16 v[32:47], v[180:183], v[222:225], v[32:47]
	v_mfma_f32_32x32x16_bf16 v[16:31], v[184:187], v[218:221], v[16:31]
	s_add_u32 m0, s26, 0xa000
	v_lshl_add_u64 v[162:163], v[64:65], 0, s[10:11]
	global_load_lds_dwordx4 v[162:163], off
	v_mfma_f32_32x32x16_bf16 v[0:15], v[184:187], v[222:225], v[0:15]
	ds_read_b128 v[180:183], v79 offset:49152
	ds_read_b128 v[184:187], v79 offset:53248
	ds_read_b128 v[218:221], v83 offset:49152
	ds_read_b128 v[222:225], v83 offset:53248
	s_waitcnt lgkmcnt(4)
	v_mfma_f32_32x32x16_bf16 v[48:63], v[164:167], v[172:175], v[48:63]
	v_mfma_f32_32x32x16_bf16 v[32:47], v[164:167], v[176:179], v[32:47]
	v_mfma_f32_32x32x16_bf16 v[16:31], v[168:171], v[172:175], v[16:31]
	v_mfma_f32_32x32x16_bf16 v[0:15], v[168:171], v[176:179], v[0:15]
	s_waitcnt vmcnt(6) lgkmcnt(0)
	s_barrier
;     ...
;   for (int kt = 0; kt < nk; ++kt) {
;     if (kt + 1 < nk) asm volatile("s_waitcnt vmcnt(6)" ::: "memory");
;     else asm volatile("s_waitcnt vmcnt(0)" ::: "memory");
;     __builtin_amdgcn_s_barrier();
;     asm volatile("" ::: "memory");
;     if (kt + 2 < nk) { const int st2 = (st >= 1) ? st - 1 : 2; GEMM_ISSUE(kt + 2, st2); }
;     const char* la = lds + st * STAGE_B;
;     const char* lb = la + 32768;
;     const unsigned sa_u = (unsigned)(size_t)la + arow_u, sb_u = (unsigned)(size_t)lb + brow_u;
;     const unsigned a0 = sa_u + co0, a1 = sa_u + co1, a2 = sa_u + co2, a3 = sa_u + co3;
;     const unsigned b0 = sb_u + co0, b1 = sb_u + co1, b2 = sb_u + co2, b3 = sb_u + co3;
;     {
;       bf16x8 p0, p1, q0, q1, u0, u1, w0, w1;
;       asm volatile(
;         "ds_read_b128 %4, %12\n\tds_read_b128 %5, %12 offset:4096\n\tds_read_b128 %6, %16\n\tds_read_b128 %7, %16 offset:4096\n\t"
;         "ds_read_b128 %8, %13\n\tds_read_b128 %9, %13 offset:4096\n\tds_read_b128 %10, %17\n\tds_read_b128 %11, %17 offset:4096\n\t"
;         "s_waitcnt lgkmcnt(4)\n\t"
;         "v_mfma_f32_32x32x16_bf16 %0, %4, %6, %0\n\tv_mfma_f32_32x32x16_bf16 %1, %4, %7, %1\n\tv_mfma_f32_32x32x16_bf16 %2, %5, %6, %2\n\tv_mfma_f32_32x32x16_bf16 %3, %5, %7, %3\n\t"
;         "ds_read_b128 %4, %14\n\tds_read_b128 %5, %14 offset:4096\n\tds_read_b128 %6, %18\n\tds_read_b128 %7, %18 offset:4096\n\t"
;         "s_waitcnt lgkmcnt(4)\n\t"
;         "v_mfma_f32_32x32x16_bf16 %0, %8, %10, %0\n\tv_mfma_f32_32x32x16_bf16 %1, %8, %11, %1\n\tv_mfma_f32_32x32x16_bf16 %2, %9, %10, %2\n\tv_mfma_f32_32x32x16_bf16 %3, %9, %11, %3\n\t"
;         "ds_read_b128 %8, %15\n\tds_read_b128 %9, %15 offset:4096\n\tds_read_b128 %10, %19\n\tds_read_b128 %11, %19 offset:4096\n\t"
;         "s_waitcnt lgkmcnt(4)\n\t"
;         "v_mfma_f32_32x32x16_bf16 %0, %4, %6, %0\n\tv_mfma_f32_32x32x16_bf16 %1, %4, %7, %1\n\tv_mfma_f32_32x32x16_bf16 %2, %5, %6, %2\n\tv_mfma_f32_32x32x16_bf16 %3, %5, %7, %3\n\t"
;         "s_waitcnt lgkmcnt(0)\n\t"
;         "v_mfma_f32_32x32x16_bf16 %0, %8, %10, %0\n\tv_mfma_f32_32x32x16_bf16 %1, %8, %11, %1\n\tv_mfma_f32_32x32x16_bf16 %2, %9, %10, %2\n\tv_mfma_f32_32x32x16_bf16 %3, %9, %11, %3"
;         : "+v"(acc[0][0]), "+v"(acc[0][1]), "+v"(acc[1][0]), "+v"(acc[1][1]),
;           "=&v"(p0), "=&v"(p1), "=&v"(q0), "=&v"(q1), "=&v"(u0), "=&v"(u1), "=&v"(w0), "=&v"(w1)
	ds_read_b128 v[164:167], v84
	ds_read_b128 v[168:171], v84 offset:4096
	ds_read_b128 v[172:175], v156
	ds_read_b128 v[176:179], v156 offset:4096
	v_mfma_f32_32x32x16_bf16 v[48:63], v[180:183], v[218:221], v[48:63]
	s_mov_b32 s10, 0xa5c2b00
	s_add_u32 m0, s26, 0xc000
	v_lshl_add_u64 v[160:161], v[74:75], 0, s[10:11]
	global_load_lds_dwordx4 v[160:161], off
	v_mfma_f32_32x32x16_bf16 v[32:47], v[180:183], v[222:225], v[32:47]
	v_mfma_f32_32x32x16_bf16 v[16:31], v[184:187], v[218:221], v[16:31]
	s_add_u32 m0, s26, 0xe000
	v_lshl_add_u64 v[162:163], v[72:73], 0, s[10:11]
	global_load_lds_dwordx4 v[162:163], off
	v_mfma_f32_32x32x16_bf16 v[0:15], v[184:187], v[222:225], v[0:15]
	ds_read_b128 v[180:183], v85
	ds_read_b128 v[184:187], v85 offset:4096
	ds_read_b128 v[218:221], v157
	ds_read_b128 v[222:225], v157 offset:4096
	s_waitcnt lgkmcnt(4)
	v_mfma_f32_32x32x16_bf16 v[48:63], v[164:167], v[172:175], v[48:63]
	s_add_u32 m0, s26, 0x10000
	v_lshl_add_u64 v[160:161], v[70:71], 0, s[10:11]
	global_load_lds_dwordx4 v[160:161], off
	v_mfma_f32_32x32x16_bf16 v[32:47], v[164:167], v[176:179], v[32:47]
	v_mfma_f32_32x32x16_bf16 v[16:31], v[168:171], v[172:175], v[16:31]
	s_add_u32 m0, s26, 0x12000
	v_lshl_add_u64 v[162:163], v[68:69], 0, s[10:11]
	global_load_lds_dwordx4 v[162:163], off
	v_mfma_f32_32x32x16_bf16 v[0:15], v[168:171], v[176:179], v[0:15]
	ds_read_b128 v[164:167], v86
	ds_read_b128 v[168:171], v86 offset:4096
	ds_read_b128 v[172:175], v158
	ds_read_b128 v[176:179], v158 offset:4096
	s_waitcnt lgkmcnt(4)
	v_mfma_f32_32x32x16_bf16 v[48:63], v[180:183], v[218:221], v[48:63]
	s_mov_b32 s10, 0xb00b00
	s_add_u32 m0, s26, 0x14000
	v_lshl_add_u64 v[160:161], v[66:67], 0, s[10:11]
	global_load_lds_dwordx4 v[160:161], off
	v_mfma_f32_32x32x16_bf16 v[32:47], v[180:183], v[222:225], v[32:47]
	v_mfma_f32_32x32x16_bf16 v[16:31], v[184:187], v[218:221], v[16:31]
	s_add_u32 m0, s26, 0x16000
	v_lshl_add_u64 v[162:163], v[64:65], 0, s[10:11]
	global_load_lds_dwordx4 v[162:163], off
	v_mfma_f32_32x32x16_bf16 v[0:15], v[184:187], v[222:225], v[0:15]
	ds_read_b128 v[180:183], v87
	ds_read_b128 v[184:187], v87 offset:4096
	ds_read_b128 v[218:221], v159
	ds_read_b128 v[222:225], v159 offset:4096
	s_waitcnt lgkmcnt(4)
	v_mfma_f32_32x32x16_bf16 v[48:63], v[164:167], v[172:175], v[48:63]
	v_mfma_f32_32x32x16_bf16 v[32:47], v[164:167], v[176:179], v[32:47]
	v_mfma_f32_32x32x16_bf16 v[16:31], v[168:171], v[172:175], v[16:31]
	v_mfma_f32_32x32x16_bf16 v[0:15], v[168:171], v[176:179], v[0:15]
	s_waitcnt vmcnt(6) lgkmcnt(0)
	s_barrier
	ds_read_b128 v[164:167], v76
	ds_read_b128 v[168:171], v76 offset:4096
	ds_read_b128 v[172:175], v80
	ds_read_b128 v[176:179], v80 offset:4096
	v_mfma_f32_32x32x16_bf16 v[48:63], v[180:183], v[218:221], v[48:63]
	s_mov_b32 s10, 0xa5c2b80
	s_add_u32 m0, s26, 0x18000
	v_lshl_add_u64 v[160:161], v[74:75], 0, s[10:11]
	global_load_lds_dwordx4 v[160:161], off
	v_mfma_f32_32x32x16_bf16 v[32:47], v[180:183], v[222:225], v[32:47]
	v_mfma_f32_32x32x16_bf16 v[16:31], v[184:187], v[218:221], v[16:31]
	s_add_u32 m0, s26, 0x1a000
	v_lshl_add_u64 v[162:163], v[72:73], 0, s[10:11]
	global_load_lds_dwordx4 v[162:163], off
	v_mfma_f32_32x32x16_bf16 v[0:15], v[184:187], v[222:225], v[0:15]
	ds_read_b128 v[180:183], v77
	ds_read_b128 v[184:187], v77 offset:4096
	ds_read_b128 v[218:221], v81
	ds_read_b128 v[222:225], v81 offset:4096
	s_waitcnt lgkmcnt(4)
	v_mfma_f32_32x32x16_bf16 v[48:63], v[164:167], v[172:175], v[48:63]
	s_add_u32 m0, s26, 0x1c000
	v_lshl_add_u64 v[160:161], v[70:71], 0, s[10:11]
	global_load_lds_dwordx4 v[160:161], off
	v_mfma_f32_32x32x16_bf16 v[32:47], v[164:167], v[176:179], v[32:47]
	v_mfma_f32_32x32x16_bf16 v[16:31], v[168:171], v[172:175], v[16:31]
	s_add_u32 m0, s26, 0x1e000
	v_lshl_add_u64 v[162:163], v[68:69], 0, s[10:11]
	global_load_lds_dwordx4 v[162:163], off
	v_mfma_f32_32x32x16_bf16 v[0:15], v[168:171], v[176:179], v[0:15]
	ds_read_b128 v[164:167], v78
	ds_read_b128 v[168:171], v78 offset:4096
	ds_read_b128 v[172:175], v82
	ds_read_b128 v[176:179], v82 offset:4096
	s_waitcnt lgkmcnt(4)
	v_mfma_f32_32x32x16_bf16 v[48:63], v[180:183], v[218:221], v[48:63]
	s_mov_b32 s10, 0xb00b80
	s_add_u32 m0, s26, 0x20000
	v_lshl_add_u64 v[160:161], v[66:67], 0, s[10:11]
	global_load_lds_dwordx4 v[160:161], off
	v_mfma_f32_32x32x16_bf16 v[32:47], v[180:183], v[222:225], v[32:47]
	v_mfma_f32_32x32x16_bf16 v[16:31], v[184:187], v[218:221], v[16:31]
	s_add_u32 m0, s26, 0x22000
	v_lshl_add_u64 v[162:163], v[64:65], 0, s[10:11]
	global_load_lds_dwordx4 v[162:163], off
	v_mfma_f32_32x32x16_bf16 v[0:15], v[184:187], v[222:225], v[0:15]
	ds_read_b128 v[180:183], v79
	ds_read_b128 v[184:187], v79 offset:4096
	ds_read_b128 v[218:221], v83
	ds_read_b128 v[222:225], v83 offset:4096
	s_waitcnt lgkmcnt(4)
	v_mfma_f32_32x32x16_bf16 v[48:63], v[164:167], v[172:175], v[48:63]
	v_mfma_f32_32x32x16_bf16 v[32:47], v[164:167], v[176:179], v[32:47]
	v_mfma_f32_32x32x16_bf16 v[16:31], v[168:171], v[172:175], v[16:31]
	v_mfma_f32_32x32x16_bf16 v[0:15], v[168:171], v[176:179], v[0:15]
	s_waitcnt vmcnt(6) lgkmcnt(0)
	s_barrier
;     ...
;   for (int kt = 0; kt < nk; ++kt) {
;     if (kt + 1 < nk) asm volatile("s_waitcnt vmcnt(6)" ::: "memory");
;     else asm volatile("s_waitcnt vmcnt(0)" ::: "memory");
;     __builtin_amdgcn_s_barrier();
;     asm volatile("" ::: "memory");
;     if (kt + 2 < nk) { const int st2 = (st >= 1) ? st - 1 : 2; GEMM_ISSUE(kt + 2, st2); }
;     const char* la = lds + st * STAGE_B;
;     const char* lb = la + 32768;
;     const unsigned sa_u = (unsigned)(size_t)la + arow_u, sb_u = (unsigned)(size_t)lb + brow_u;
;     const unsigned a0 = sa_u + co0, a1 = sa_u + co1, a2 = sa_u + co2, a3 = sa_u + co3;
;     const unsigned b0 = sb_u + co0, b1 = sb_u + co1, b2 = sb_u + co2, b3 = sb_u + co3;
;     {
;       bf16x8 p0, p1, q0, q1, u0, u1, w0, w1;
;       asm volatile(
;         "ds_read_b128 %4, %12\n\tds_read_b128 %5, %12 offset:4096\n\tds_read_b128 %6, %16\n\tds_read_b128 %7, %16 offset:4096\n\t"
;         "ds_read_b128 %8, %13\n\tds_read_b128 %9, %13 offset:4096\n\tds_read_b128 %10, %17\n\tds_read_b128 %11, %17 offset:4096\n\t"
;         "s_waitcnt lgkmcnt(4)\n\t"
;         "v_mfma_f32_32x32x16_bf16 %0, %4, %6, %0\n\tv_mfma_f32_32x32x16_bf16 %1, %4, %7, %1\n\tv_mfma_f32_32x32x16_bf16 %2, %5, %6, %2\n\tv_mfma_f32_32x32x16_bf16 %3, %5, %7, %3\n\t"
;         "ds_read_b128 %4, %14\n\tds_read_b128 %5, %14 offset:4096\n\tds_read_b128 %6, %18\n\tds_read_b128 %7, %18 offset:4096\n\t"
;         "s_waitcnt lgkmcnt(4)\n\t"
;         "v_mfma_f32_32x32x16_bf16 %0, %8, %10, %0\n\tv_mfma_f32_32x32x16_bf16 %1, %8, %11, %1\n\tv_mfma_f32_32x32x16_bf16 %2, %9, %10, %2\n\tv_mfma_f32_32x32x16_bf16 %3, %9, %11, %3\n\t"
;         "ds_read_b128 %8, %15\n\tds_read_b128 %9, %15 offset:4096\n\tds_read_b128 %10, %19\n\tds_read_b128 %11, %19 offset:4096\n\t"
;         "s_waitcnt lgkmcnt(4)\n\t"
;         "v_mfma_f32_32x32x16_bf16 %0, %4, %6, %0\n\tv_mfma_f32_32x32x16_bf16 %1, %4, %7, %1\n\tv_mfma_f32_32x32x16_bf16 %2, %5, %6, %2\n\tv_mfma_f32_32x32x16_bf16 %3, %5, %7, %3\n\t"
;         "s_waitcnt lgkmcnt(0)\n\t"
;         "v_mfma_f32_32x32x16_bf16 %0, %8, %10, %0\n\tv_mfma_f32_32x32x16_bf16 %1, %8, %11, %1\n\tv_mfma_f32_32x32x16_bf16 %2, %9, %10, %2\n\tv_mfma_f32_32x32x16_bf16 %3, %9, %11, %3"
;         : "+v"(acc[0][0]), "+v"(acc[0][1]), "+v"(acc[1][0]), "+v"(acc[1][1]),
;           "=&v"(p0), "=&v"(p1), "=&v"(q0), "=&v"(q1), "=&v"(u0), "=&v"(u1), "=&v"(w0), "=&v"(w1)
	ds_read_b128 v[164:167], v76 offset:49152
	ds_read_b128 v[168:171], v76 offset:53248
	ds_read_b128 v[172:175], v80 offset:49152
	ds_read_b128 v[176:179], v80 offset:53248
	v_mfma_f32_32x32x16_bf16 v[48:63], v[180:183], v[218:221], v[48:63]
	s_mov_b32 s10, 0xa5c2c00
	s_mov_b32 m0, s26
	v_lshl_add_u64 v[160:161], v[74:75], 0, s[10:11]
	global_load_lds_dwordx4 v[160:161], off
	v_mfma_f32_32x32x16_bf16 v[32:47], v[180:183], v[222:225], v[32:47]
	v_mfma_f32_32x32x16_bf16 v[16:31], v[184:187], v[218:221], v[16:31]
	s_add_u32 m0, s26, 0x2000
	v_lshl_add_u64 v[162:163], v[72:73], 0, s[10:11]
	global_load_lds_dwordx4 v[162:163], off
	v_mfma_f32_32x32x16_bf16 v[0:15], v[184:187], v[222:225], v[0:15]
	ds_read_b128 v[180:183], v77 offset:49152
	ds_read_b128 v[184:187], v77 offset:53248
	ds_read_b128 v[218:221], v81 offset:49152
	ds_read_b128 v[222:225], v81 offset:53248
	s_waitcnt lgkmcnt(4)
	v_mfma_f32_32x32x16_bf16 v[48:63], v[164:167], v[172:175], v[48:63]
	s_add_u32 m0, s26, 0x4000
	v_lshl_add_u64 v[160:161], v[70:71], 0, s[10:11]
	global_load_lds_dwordx4 v[160:161], off
	v_mfma_f32_32x32x16_bf16 v[32:47], v[164:167], v[176:179], v[32:47]
	v_mfma_f32_32x32x16_bf16 v[16:31], v[168:171], v[172:175], v[16:31]
	s_add_u32 m0, s26, 0x6000
	v_lshl_add_u64 v[162:163], v[68:69], 0, s[10:11]
	global_load_lds_dwordx4 v[162:163], off
	v_mfma_f32_32x32x16_bf16 v[0:15], v[168:171], v[176:179], v[0:15]
	ds_read_b128 v[164:167], v78 offset:49152
	ds_read_b128 v[168:171], v78 offset:53248
	ds_read_b128 v[172:175], v82 offset:49152
	ds_read_b128 v[176:179], v82 offset:53248
	s_waitcnt lgkmcnt(4)
	v_mfma_f32_32x32x16_bf16 v[48:63], v[180:183], v[218:221], v[48:63]
	s_mov_b32 s10, 0xb00c00
	s_add_u32 m0, s26, 0x8000
	v_lshl_add_u64 v[160:161], v[66:67], 0, s[10:11]
	global_load_lds_dwordx4 v[160:161], off
	v_mfma_f32_32x32x16_bf16 v[32:47], v[180:183], v[222:225], v[32:47]
	v_mfma_f32_32x32x16_bf16 v[16:31], v[184:187], v[218:221], v[16:31]
	s_add_u32 m0, s26, 0xa000
	v_lshl_add_u64 v[162:163], v[64:65], 0, s[10:11]
	global_load_lds_dwordx4 v[162:163], off
	v_mfma_f32_32x32x16_bf16 v[0:15], v[184:187], v[222:225], v[0:15]
	ds_read_b128 v[180:183], v79 offset:49152
	ds_read_b128 v[184:187], v79 offset:53248
	ds_read_b128 v[218:221], v83 offset:49152
	ds_read_b128 v[222:225], v83 offset:53248
	s_waitcnt lgkmcnt(4)
	v_mfma_f32_32x32x16_bf16 v[48:63], v[164:167], v[172:175], v[48:63]
	v_mfma_f32_32x32x16_bf16 v[32:47], v[164:167], v[176:179], v[32:47]
	v_mfma_f32_32x32x16_bf16 v[16:31], v[168:171], v[172:175], v[16:31]
	v_mfma_f32_32x32x16_bf16 v[0:15], v[168:171], v[176:179], v[0:15]
	s_waitcnt vmcnt(6) lgkmcnt(0)
	s_barrier
	ds_read_b128 v[164:167], v84
	ds_read_b128 v[168:171], v84 offset:4096
	ds_read_b128 v[172:175], v156
	ds_read_b128 v[176:179], v156 offset:4096
	v_mfma_f32_32x32x16_bf16 v[48:63], v[180:183], v[218:221], v[48:63]
	s_mov_b32 s10, 0xa5c2c80
	s_add_u32 m0, s26, 0xc000
	v_lshl_add_u64 v[160:161], v[74:75], 0, s[10:11]
	global_load_lds_dwordx4 v[160:161], off
	v_mfma_f32_32x32x16_bf16 v[32:47], v[180:183], v[222:225], v[32:47]
	v_mfma_f32_32x32x16_bf16 v[16:31], v[184:187], v[218:221], v[16:31]
	s_add_u32 m0, s26, 0xe000
	v_lshl_add_u64 v[162:163], v[72:73], 0, s[10:11]
	global_load_lds_dwordx4 v[162:163], off
	v_mfma_f32_32x32x16_bf16 v[0:15], v[184:187], v[222:225], v[0:15]
	ds_read_b128 v[180:183], v85
	ds_read_b128 v[184:187], v85 offset:4096
	ds_read_b128 v[218:221], v157
	ds_read_b128 v[222:225], v157 offset:4096
	s_waitcnt lgkmcnt(4)
	v_mfma_f32_32x32x16_bf16 v[48:63], v[164:167], v[172:175], v[48:63]
	s_add_u32 m0, s26, 0x10000
	v_lshl_add_u64 v[160:161], v[70:71], 0, s[10:11]
	global_load_lds_dwordx4 v[160:161], off
	v_mfma_f32_32x32x16_bf16 v[32:47], v[164:167], v[176:179], v[32:47]
	v_mfma_f32_32x32x16_bf16 v[16:31], v[168:171], v[172:175], v[16:31]
	s_add_u32 m0, s26, 0x12000
	v_lshl_add_u64 v[162:163], v[68:69], 0, s[10:11]
	global_load_lds_dwordx4 v[162:163], off
	v_mfma_f32_32x32x16_bf16 v[0:15], v[168:171], v[176:179], v[0:15]
	ds_read_b128 v[164:167], v86
	ds_read_b128 v[168:171], v86 offset:4096
	ds_read_b128 v[172:175], v158
	ds_read_b128 v[176:179], v158 offset:4096
	s_waitcnt lgkmcnt(4)
	v_mfma_f32_32x32x16_bf16 v[48:63], v[180:183], v[218:221], v[48:63]
	s_mov_b32 s10, 0xb00c80
	s_add_u32 m0, s26, 0x14000
	v_lshl_add_u64 v[160:161], v[66:67], 0, s[10:11]
	global_load_lds_dwordx4 v[160:161], off
	v_mfma_f32_32x32x16_bf16 v[32:47], v[180:183], v[222:225], v[32:47]
	v_mfma_f32_32x32x16_bf16 v[16:31], v[184:187], v[218:221], v[16:31]
	s_add_u32 m0, s26, 0x16000
	v_lshl_add_u64 v[162:163], v[64:65], 0, s[10:11]
	global_load_lds_dwordx4 v[162:163], off
	v_mfma_f32_32x32x16_bf16 v[0:15], v[184:187], v[222:225], v[0:15]
	ds_read_b128 v[180:183], v87
	ds_read_b128 v[184:187], v87 offset:4096
	ds_read_b128 v[218:221], v159
	ds_read_b128 v[222:225], v159 offset:4096
	s_waitcnt lgkmcnt(4)
	v_mfma_f32_32x32x16_bf16 v[48:63], v[164:167], v[172:175], v[48:63]
	v_mfma_f32_32x32x16_bf16 v[32:47], v[164:167], v[176:179], v[32:47]
	v_mfma_f32_32x32x16_bf16 v[16:31], v[168:171], v[172:175], v[16:31]
	v_mfma_f32_32x32x16_bf16 v[0:15], v[168:171], v[176:179], v[0:15]
	s_waitcnt vmcnt(6) lgkmcnt(0)
	s_barrier
;     ...
;   for (int kt = 0; kt < nk; ++kt) {
;     if (kt + 1 < nk) asm volatile("s_waitcnt vmcnt(6)" ::: "memory");
;     else asm volatile("s_waitcnt vmcnt(0)" ::: "memory");
;     __builtin_amdgcn_s_barrier();
;     asm volatile("" ::: "memory");
;     if (kt + 2 < nk) { const int st2 = (st >= 1) ? st - 1 : 2; GEMM_ISSUE(kt + 2, st2); }
;     const char* la = lds + st * STAGE_B;
;     const char* lb = la + 32768;
;     const unsigned sa_u = (unsigned)(size_t)la + arow_u, sb_u = (unsigned)(size_t)lb + brow_u;
;     const unsigned a0 = sa_u + co0, a1 = sa_u + co1, a2 = sa_u + co2, a3 = sa_u + co3;
;     const unsigned b0 = sb_u + co0, b1 = sb_u + co1, b2 = sb_u + co2, b3 = sb_u + co3;
;     {
;       bf16x8 p0, p1, q0, q1, u0, u1, w0, w1;
;       asm volatile(
;         "ds_read_b128 %4, %12\n\tds_read_b128 %5, %12 offset:4096\n\tds_read_b128 %6, %16\n\tds_read_b128 %7, %16 offset:4096\n\t"
;         "ds_read_b128 %8, %13\n\tds_read_b128 %9, %13 offset:4096\n\tds_read_b128 %10, %17\n\tds_read_b128 %11, %17 offset:4096\n\t"
;         "s_waitcnt lgkmcnt(4)\n\t"
;         "v_mfma_f32_32x32x16_bf16 %0, %4, %6, %0\n\tv_mfma_f32_32x32x16_bf16 %1, %4, %7, %1\n\tv_mfma_f32_32x32x16_bf16 %2, %5, %6, %2\n\tv_mfma_f32_32x32x16_bf16 %3, %5, %7, %3\n\t"
;         "ds_read_b128 %4, %14\n\tds_read_b128 %5, %14 offset:4096\n\tds_read_b128 %6, %18\n\tds_read_b128 %7, %18 offset:4096\n\t"
;         "s_waitcnt lgkmcnt(4)\n\t"
;         "v_mfma_f32_32x32x16_bf16 %0, %8, %10, %0\n\tv_mfma_f32_32x32x16_bf16 %1, %8, %11, %1\n\tv_mfma_f32_32x32x16_bf16 %2, %9, %10, %2\n\tv_mfma_f32_32x32x16_bf16 %3, %9, %11, %3\n\t"
;         "ds_read_b128 %8, %15\n\tds_read_b128 %9, %15 offset:4096\n\tds_read_b128 %10, %19\n\tds_read_b128 %11, %19 offset:4096\n\t"
;         "s_waitcnt lgkmcnt(4)\n\t"
;         "v_mfma_f32_32x32x16_bf16 %0, %4, %6, %0\n\tv_mfma_f32_32x32x16_bf16 %1, %4, %7, %1\n\tv_mfma_f32_32x32x16_bf16 %2, %5, %6, %2\n\tv_mfma_f32_32x32x16_bf16 %3, %5, %7, %3\n\t"
;         "s_waitcnt lgkmcnt(0)\n\t"
;         "v_mfma_f32_32x32x16_bf16 %0, %8, %10, %0\n\tv_mfma_f32_32x32x16_bf16 %1, %8, %11, %1\n\tv_mfma_f32_32x32x16_bf16 %2, %9, %10, %2\n\tv_mfma_f32_32x32x16_bf16 %3, %9, %11, %3"
;         : "+v"(acc[0][0]), "+v"(acc[0][1]), "+v"(acc[1][0]), "+v"(acc[1][1]),
;           "=&v"(p0), "=&v"(p1), "=&v"(q0), "=&v"(q1), "=&v"(u0), "=&v"(u1), "=&v"(w0), "=&v"(w1)
	ds_read_b128 v[164:167], v76
	ds_read_b128 v[168:171], v76 offset:4096
	ds_read_b128 v[172:175], v80
	ds_read_b128 v[176:179], v80 offset:4096
	v_mfma_f32_32x32x16_bf16 v[48:63], v[180:183], v[218:221], v[48:63]
	s_mov_b32 s10, 0xa5c2d00
	s_add_u32 m0, s26, 0x18000
	v_lshl_add_u64 v[160:161], v[74:75], 0, s[10:11]
	global_load_lds_dwordx4 v[160:161], off
	v_mfma_f32_32x32x16_bf16 v[32:47], v[180:183], v[222:225], v[32:47]
	v_mfma_f32_32x32x16_bf16 v[16:31], v[184:187], v[218:221], v[16:31]
	s_add_u32 m0, s26, 0x1a000
	v_lshl_add_u64 v[162:163], v[72:73], 0, s[10:11]
	global_load_lds_dwordx4 v[162:163], off
	v_mfma_f32_32x32x16_bf16 v[0:15], v[184:187], v[222:225], v[0:15]
	ds_read_b128 v[180:183], v77
	ds_read_b128 v[184:187], v77 offset:4096
	ds_read_b128 v[218:221], v81
	ds_read_b128 v[222:225], v81 offset:4096
	s_waitcnt lgkmcnt(4)
	v_mfma_f32_32x32x16_bf16 v[48:63], v[164:167], v[172:175], v[48:63]
	s_add_u32 m0, s26, 0x1c000
	v_lshl_add_u64 v[160:161], v[70:71], 0, s[10:11]
	global_load_lds_dwordx4 v[160:161], off
	v_mfma_f32_32x32x16_bf16 v[32:47], v[164:167], v[176:179], v[32:47]
	v_mfma_f32_32x32x16_bf16 v[16:31], v[168:171], v[172:175], v[16:31]
	s_add_u32 m0, s26, 0x1e000
	v_lshl_add_u64 v[162:163], v[68:69], 0, s[10:11]
	global_load_lds_dwordx4 v[162:163], off
	v_mfma_f32_32x32x16_bf16 v[0:15], v[168:171], v[176:179], v[0:15]
	ds_read_b128 v[164:167], v78
	ds_read_b128 v[168:171], v78 offset:4096
	ds_read_b128 v[172:175], v82
	ds_read_b128 v[176:179], v82 offset:4096
	s_waitcnt lgkmcnt(4)
	v_mfma_f32_32x32x16_bf16 v[48:63], v[180:183], v[218:221], v[48:63]
	s_mov_b32 s10, 0xb00d00
	s_add_u32 m0, s26, 0x20000
	v_lshl_add_u64 v[160:161], v[66:67], 0, s[10:11]
	global_load_lds_dwordx4 v[160:161], off
	v_mfma_f32_32x32x16_bf16 v[32:47], v[180:183], v[222:225], v[32:47]
	v_mfma_f32_32x32x16_bf16 v[16:31], v[184:187], v[218:221], v[16:31]
	s_add_u32 m0, s26, 0x22000
	v_lshl_add_u64 v[162:163], v[64:65], 0, s[10:11]
	global_load_lds_dwordx4 v[162:163], off
	v_mfma_f32_32x32x16_bf16 v[0:15], v[184:187], v[222:225], v[0:15]
	ds_read_b128 v[180:183], v79
	ds_read_b128 v[184:187], v79 offset:4096
	ds_read_b128 v[218:221], v83
	ds_read_b128 v[222:225], v83 offset:4096
	s_waitcnt lgkmcnt(4)
	v_mfma_f32_32x32x16_bf16 v[48:63], v[164:167], v[172:175], v[48:63]
	v_mfma_f32_32x32x16_bf16 v[32:47], v[164:167], v[176:179], v[32:47]
	v_mfma_f32_32x32x16_bf16 v[16:31], v[168:171], v[172:175], v[16:31]
	v_mfma_f32_32x32x16_bf16 v[0:15], v[168:171], v[176:179], v[0:15]
	s_waitcnt vmcnt(6) lgkmcnt(0)
	s_barrier
	ds_read_b128 v[164:167], v76 offset:49152
	ds_read_b128 v[168:171], v76 offset:53248
	ds_read_b128 v[172:175], v80 offset:49152
	ds_read_b128 v[176:179], v80 offset:53248
	v_mfma_f32_32x32x16_bf16 v[48:63], v[180:183], v[218:221], v[48:63]
	s_mov_b32 s10, 0xa5c2d80
	s_mov_b32 m0, s26
	v_lshl_add_u64 v[160:161], v[74:75], 0, s[10:11]
	global_load_lds_dwordx4 v[160:161], off
	v_mfma_f32_32x32x16_bf16 v[32:47], v[180:183], v[222:225], v[32:47]
	v_mfma_f32_32x32x16_bf16 v[16:31], v[184:187], v[218:221], v[16:31]
	s_add_u32 m0, s26, 0x2000
	v_lshl_add_u64 v[162:163], v[72:73], 0, s[10:11]
	global_load_lds_dwordx4 v[162:163], off
	v_mfma_f32_32x32x16_bf16 v[0:15], v[184:187], v[222:225], v[0:15]
	ds_read_b128 v[180:183], v77 offset:49152
	ds_read_b128 v[184:187], v77 offset:53248
	ds_read_b128 v[218:221], v81 offset:49152
	ds_read_b128 v[222:225], v81 offset:53248
	s_waitcnt lgkmcnt(4)
	v_mfma_f32_32x32x16_bf16 v[48:63], v[164:167], v[172:175], v[48:63]
	s_add_u32 m0, s26, 0x4000
	v_lshl_add_u64 v[160:161], v[70:71], 0, s[10:11]
	global_load_lds_dwordx4 v[160:161], off
	v_mfma_f32_32x32x16_bf16 v[32:47], v[164:167], v[176:179], v[32:47]
	v_mfma_f32_32x32x16_bf16 v[16:31], v[168:171], v[172:175], v[16:31]
	s_add_u32 m0, s26, 0x6000
	v_lshl_add_u64 v[162:163], v[68:69], 0, s[10:11]
	global_load_lds_dwordx4 v[162:163], off
	v_mfma_f32_32x32x16_bf16 v[0:15], v[168:171], v[176:179], v[0:15]
	ds_read_b128 v[164:167], v78 offset:49152
	ds_read_b128 v[168:171], v78 offset:53248
	ds_read_b128 v[172:175], v82 offset:49152
	ds_read_b128 v[176:179], v82 offset:53248
	s_waitcnt lgkmcnt(4)
	v_mfma_f32_32x32x16_bf16 v[48:63], v[180:183], v[218:221], v[48:63]
	s_mov_b32 s10, 0xb00d80
	s_add_u32 m0, s26, 0x8000
	v_lshl_add_u64 v[160:161], v[66:67], 0, s[10:11]
	global_load_lds_dwordx4 v[160:161], off
	v_mfma_f32_32x32x16_bf16 v[32:47], v[180:183], v[222:225], v[32:47]
	v_mfma_f32_32x32x16_bf16 v[16:31], v[184:187], v[218:221], v[16:31]
	s_add_u32 m0, s26, 0xa000
	v_lshl_add_u64 v[162:163], v[64:65], 0, s[10:11]
	global_load_lds_dwordx4 v[162:163], off
	v_mfma_f32_32x32x16_bf16 v[0:15], v[184:187], v[222:225], v[0:15]
	ds_read_b128 v[180:183], v79 offset:49152
	ds_read_b128 v[184:187], v79 offset:53248
	ds_read_b128 v[218:221], v83 offset:49152
	ds_read_b128 v[222:225], v83 offset:53248
	s_waitcnt lgkmcnt(4)
	v_mfma_f32_32x32x16_bf16 v[48:63], v[164:167], v[172:175], v[48:63]
	v_mfma_f32_32x32x16_bf16 v[32:47], v[164:167], v[176:179], v[32:47]
	v_mfma_f32_32x32x16_bf16 v[16:31], v[168:171], v[172:175], v[16:31]
	v_mfma_f32_32x32x16_bf16 v[0:15], v[168:171], v[176:179], v[0:15]
	s_waitcnt vmcnt(6) lgkmcnt(0)
	s_barrier
;     ...
;   for (int kt = 0; kt < nk; ++kt) {
;     if (kt + 1 < nk) asm volatile("s_waitcnt vmcnt(6)" ::: "memory");
;     else asm volatile("s_waitcnt vmcnt(0)" ::: "memory");
;     __builtin_amdgcn_s_barrier();
;     asm volatile("" ::: "memory");
;     if (kt + 2 < nk) { const int st2 = (st >= 1) ? st - 1 : 2; GEMM_ISSUE(kt + 2, st2); }
;     const char* la = lds + st * STAGE_B;
;     const char* lb = la + 32768;
;     const unsigned sa_u = (unsigned)(size_t)la + arow_u, sb_u = (unsigned)(size_t)lb + brow_u;
;     const unsigned a0 = sa_u + co0, a1 = sa_u + co1, a2 = sa_u + co2, a3 = sa_u + co3;
;     const unsigned b0 = sb_u + co0, b1 = sb_u + co1, b2 = sb_u + co2, b3 = sb_u + co3;
;     {
;       bf16x8 p0, p1, q0, q1, u0, u1, w0, w1;
;       asm volatile(
;         "ds_read_b128 %4, %12\n\tds_read_b128 %5, %12 offset:4096\n\tds_read_b128 %6, %16\n\tds_read_b128 %7, %16 offset:4096\n\t"
;         "ds_read_b128 %8, %13\n\tds_read_b128 %9, %13 offset:4096\n\tds_read_b128 %10, %17\n\tds_read_b128 %11, %17 offset:4096\n\t"
;         "s_waitcnt lgkmcnt(4)\n\t"
;         "v_mfma_f32_32x32x16_bf16 %0, %4, %6, %0\n\tv_mfma_f32_32x32x16_bf16 %1, %4, %7, %1\n\tv_mfma_f32_32x32x16_bf16 %2, %5, %6, %2\n\tv_mfma_f32_32x32x16_bf16 %3, %5, %7, %3\n\t"
;         "ds_read_b128 %4, %14\n\tds_read_b128 %5, %14 offset:4096\n\tds_read_b128 %6, %18\n\tds_read_b128 %7, %18 offset:4096\n\t"
;         "s_waitcnt lgkmcnt(4)\n\t"
;         "v_mfma_f32_32x32x16_bf16 %0, %8, %10, %0\n\tv_mfma_f32_32x32x16_bf16 %1, %8, %11, %1\n\tv_mfma_f32_32x32x16_bf16 %2, %9, %10, %2\n\tv_mfma_f32_32x32x16_bf16 %3, %9, %11, %3\n\t"
;         "ds_read_b128 %8, %15\n\tds_read_b128 %9, %15 offset:4096\n\tds_read_b128 %10, %19\n\tds_read_b128 %11, %19 offset:4096\n\t"
;         "s_waitcnt lgkmcnt(4)\n\t"
;         "v_mfma_f32_32x32x16_bf16 %0, %4, %6, %0\n\tv_mfma_f32_32x32x16_bf16 %1, %4, %7, %1\n\tv_mfma_f32_32x32x16_bf16 %2, %5, %6, %2\n\tv_mfma_f32_32x32x16_bf16 %3, %5, %7, %3\n\t"
;         "s_waitcnt lgkmcnt(0)\n\t"
;         "v_mfma_f32_32x32x16_bf16 %0, %8, %10, %0\n\tv_mfma_f32_32x32x16_bf16 %1, %8, %11, %1\n\tv_mfma_f32_32x32x16_bf16 %2, %9, %10, %2\n\tv_mfma_f32_32x32x16_bf16 %3, %9, %11, %3"
;         : "+v"(acc[0][0]), "+v"(acc[0][1]), "+v"(acc[1][0]), "+v"(acc[1][1]),
;           "=&v"(p0), "=&v"(p1), "=&v"(q0), "=&v"(q1), "=&v"(u0), "=&v"(u1), "=&v"(w0), "=&v"(w1)
	ds_read_b128 v[164:167], v84
	ds_read_b128 v[168:171], v84 offset:4096
	ds_read_b128 v[172:175], v156
	ds_read_b128 v[176:179], v156 offset:4096
	v_mfma_f32_32x32x16_bf16 v[48:63], v[180:183], v[218:221], v[48:63]
	s_mov_b32 s10, 0xa5c2e00
	s_add_u32 m0, s26, 0xc000
	v_lshl_add_u64 v[160:161], v[74:75], 0, s[10:11]
	global_load_lds_dwordx4 v[160:161], off
	v_mfma_f32_32x32x16_bf16 v[32:47], v[180:183], v[222:225], v[32:47]
	v_mfma_f32_32x32x16_bf16 v[16:31], v[184:187], v[218:221], v[16:31]
	s_add_u32 m0, s26, 0xe000
	v_lshl_add_u64 v[162:163], v[72:73], 0, s[10:11]
	global_load_lds_dwordx4 v[162:163], off
	v_mfma_f32_32x32x16_bf16 v[0:15], v[184:187], v[222:225], v[0:15]
	ds_read_b128 v[180:183], v85
	ds_read_b128 v[184:187], v85 offset:4096
	ds_read_b128 v[218:221], v157
	ds_read_b128 v[222:225], v157 offset:4096
	s_waitcnt lgkmcnt(4)
	v_mfma_f32_32x32x16_bf16 v[48:63], v[164:167], v[172:175], v[48:63]
	s_add_u32 m0, s26, 0x10000
	v_lshl_add_u64 v[160:161], v[70:71], 0, s[10:11]
	global_load_lds_dwordx4 v[160:161], off
	v_mfma_f32_32x32x16_bf16 v[32:47], v[164:167], v[176:179], v[32:47]
	v_mfma_f32_32x32x16_bf16 v[16:31], v[168:171], v[172:175], v[16:31]
	s_add_u32 m0, s26, 0x12000
	v_lshl_add_u64 v[162:163], v[68:69], 0, s[10:11]
	global_load_lds_dwordx4 v[162:163], off
	v_mfma_f32_32x32x16_bf16 v[0:15], v[168:171], v[176:179], v[0:15]
	ds_read_b128 v[164:167], v86
	ds_read_b128 v[168:171], v86 offset:4096
	ds_read_b128 v[172:175], v158
	ds_read_b128 v[176:179], v158 offset:4096
	s_waitcnt lgkmcnt(4)
	v_mfma_f32_32x32x16_bf16 v[48:63], v[180:183], v[218:221], v[48:63]
	s_mov_b32 s10, 0xb00e00
	s_add_u32 m0, s26, 0x14000
	v_lshl_add_u64 v[160:161], v[66:67], 0, s[10:11]
	global_load_lds_dwordx4 v[160:161], off
	v_mfma_f32_32x32x16_bf16 v[32:47], v[180:183], v[222:225], v[32:47]
	v_mfma_f32_32x32x16_bf16 v[16:31], v[184:187], v[218:221], v[16:31]
	s_add_u32 m0, s26, 0x16000
	v_lshl_add_u64 v[162:163], v[64:65], 0, s[10:11]
	global_load_lds_dwordx4 v[162:163], off
	v_mfma_f32_32x32x16_bf16 v[0:15], v[184:187], v[222:225], v[0:15]
	ds_read_b128 v[180:183], v87
	ds_read_b128 v[184:187], v87 offset:4096
	ds_read_b128 v[218:221], v159
	ds_read_b128 v[222:225], v159 offset:4096
	s_waitcnt lgkmcnt(4)
	v_mfma_f32_32x32x16_bf16 v[48:63], v[164:167], v[172:175], v[48:63]
	v_mfma_f32_32x32x16_bf16 v[32:47], v[164:167], v[176:179], v[32:47]
	v_mfma_f32_32x32x16_bf16 v[16:31], v[168:171], v[172:175], v[16:31]
	v_mfma_f32_32x32x16_bf16 v[0:15], v[168:171], v[176:179], v[0:15]
	s_waitcnt vmcnt(6) lgkmcnt(0)
	s_barrier
	ds_read_b128 v[164:167], v76
	ds_read_b128 v[168:171], v76 offset:4096
	ds_read_b128 v[172:175], v80
	ds_read_b128 v[176:179], v80 offset:4096
	v_mfma_f32_32x32x16_bf16 v[48:63], v[180:183], v[218:221], v[48:63]
	s_mov_b32 s10, 0xa5c2e80
	s_add_u32 m0, s26, 0x18000
	v_lshl_add_u64 v[160:161], v[74:75], 0, s[10:11]
	global_load_lds_dwordx4 v[160:161], off
	v_mfma_f32_32x32x16_bf16 v[32:47], v[180:183], v[222:225], v[32:47]
	v_mfma_f32_32x32x16_bf16 v[16:31], v[184:187], v[218:221], v[16:31]
	s_add_u32 m0, s26, 0x1a000
	v_lshl_add_u64 v[162:163], v[72:73], 0, s[10:11]
	global_load_lds_dwordx4 v[162:163], off
	v_mfma_f32_32x32x16_bf16 v[0:15], v[184:187], v[222:225], v[0:15]
	ds_read_b128 v[180:183], v77
	ds_read_b128 v[184:187], v77 offset:4096
	ds_read_b128 v[218:221], v81
	ds_read_b128 v[222:225], v81 offset:4096
	s_waitcnt lgkmcnt(4)
	v_mfma_f32_32x32x16_bf16 v[48:63], v[164:167], v[172:175], v[48:63]
	s_add_u32 m0, s26, 0x1c000
	v_lshl_add_u64 v[160:161], v[70:71], 0, s[10:11]
	global_load_lds_dwordx4 v[160:161], off
	v_mfma_f32_32x32x16_bf16 v[32:47], v[164:167], v[176:179], v[32:47]
	v_mfma_f32_32x32x16_bf16 v[16:31], v[168:171], v[172:175], v[16:31]
	s_add_u32 m0, s26, 0x1e000
	v_lshl_add_u64 v[162:163], v[68:69], 0, s[10:11]
	global_load_lds_dwordx4 v[162:163], off
	v_mfma_f32_32x32x16_bf16 v[0:15], v[168:171], v[176:179], v[0:15]
	ds_read_b128 v[164:167], v78
	ds_read_b128 v[168:171], v78 offset:4096
	ds_read_b128 v[172:175], v82
	ds_read_b128 v[176:179], v82 offset:4096
	s_waitcnt lgkmcnt(4)
	v_mfma_f32_32x32x16_bf16 v[48:63], v[180:183], v[218:221], v[48:63]
	s_mov_b32 s10, 0xb00e80
	s_add_u32 m0, s26, 0x20000
	v_lshl_add_u64 v[160:161], v[66:67], 0, s[10:11]
	global_load_lds_dwordx4 v[160:161], off
	v_mfma_f32_32x32x16_bf16 v[32:47], v[180:183], v[222:225], v[32:47]
	v_mfma_f32_32x32x16_bf16 v[16:31], v[184:187], v[218:221], v[16:31]
	s_add_u32 m0, s26, 0x22000
	v_lshl_add_u64 v[162:163], v[64:65], 0, s[10:11]
	global_load_lds_dwordx4 v[162:163], off
	v_mfma_f32_32x32x16_bf16 v[0:15], v[184:187], v[222:225], v[0:15]
	ds_read_b128 v[180:183], v79
	ds_read_b128 v[184:187], v79 offset:4096
	ds_read_b128 v[218:221], v83
	ds_read_b128 v[222:225], v83 offset:4096
	s_waitcnt lgkmcnt(4)
	v_mfma_f32_32x32x16_bf16 v[48:63], v[164:167], v[172:175], v[48:63]
	v_mfma_f32_32x32x16_bf16 v[32:47], v[164:167], v[176:179], v[32:47]
	v_mfma_f32_32x32x16_bf16 v[16:31], v[168:171], v[172:175], v[16:31]
	v_mfma_f32_32x32x16_bf16 v[0:15], v[168:171], v[176:179], v[0:15]
	s_waitcnt vmcnt(6) lgkmcnt(0)
	s_barrier
;     ...
;   for (int kt = 0; kt < nk; ++kt) {
;     if (kt + 1 < nk) asm volatile("s_waitcnt vmcnt(6)" ::: "memory");
;     else asm volatile("s_waitcnt vmcnt(0)" ::: "memory");
;     __builtin_amdgcn_s_barrier();
;     asm volatile("" ::: "memory");
;     if (kt + 2 < nk) { const int st2 = (st >= 1) ? st - 1 : 2; GEMM_ISSUE(kt + 2, st2); }
;     const char* la = lds + st * STAGE_B;
;     const char* lb = la + 32768;
;     const unsigned sa_u = (unsigned)(size_t)la + arow_u, sb_u = (unsigned)(size_t)lb + brow_u;
;     const unsigned a0 = sa_u + co0, a1 = sa_u + co1, a2 = sa_u + co2, a3 = sa_u + co3;
;     const unsigned b0 = sb_u + co0, b1 = sb_u + co1, b2 = sb_u + co2, b3 = sb_u + co3;
;     {
;       bf16x8 p0, p1, q0, q1, u0, u1, w0, w1;
;       asm volatile(
;         "ds_read_b128 %4, %12\n\tds_read_b128 %5, %12 offset:4096\n\tds_read_b128 %6, %16\n\tds_read_b128 %7, %16 offset:4096\n\t"
;         "ds_read_b128 %8, %13\n\tds_read_b128 %9, %13 offset:4096\n\tds_read_b128 %10, %17\n\tds_read_b128 %11, %17 offset:4096\n\t"
;         "s_waitcnt lgkmcnt(4)\n\t"
;         "v_mfma_f32_32x32x16_bf16 %0, %4, %6, %0\n\tv_mfma_f32_32x32x16_bf16 %1, %4, %7, %1\n\tv_mfma_f32_32x32x16_bf16 %2, %5, %6, %2\n\tv_mfma_f32_32x32x16_bf16 %3, %5, %7, %3\n\t"
;         "ds_read_b128 %4, %14\n\tds_read_b128 %5, %14 offset:4096\n\tds_read_b128 %6, %18\n\tds_read_b128 %7, %18 offset:4096\n\t"
;         "s_waitcnt lgkmcnt(4)\n\t"
;         "v_mfma_f32_32x32x16_bf16 %0, %8, %10, %0\n\tv_mfma_f32_32x32x16_bf16 %1, %8, %11, %1\n\tv_mfma_f32_32x32x16_bf16 %2, %9, %10, %2\n\tv_mfma_f32_32x32x16_bf16 %3, %9, %11, %3\n\t"
;         "ds_read_b128 %8, %15\n\tds_read_b128 %9, %15 offset:4096\n\tds_read_b128 %10, %19\n\tds_read_b128 %11, %19 offset:4096\n\t"
;         "s_waitcnt lgkmcnt(4)\n\t"
;         "v_mfma_f32_32x32x16_bf16 %0, %4, %6, %0\n\tv_mfma_f32_32x32x16_bf16 %1, %4, %7, %1\n\tv_mfma_f32_32x32x16_bf16 %2, %5, %6, %2\n\tv_mfma_f32_32x32x16_bf16 %3, %5, %7, %3\n\t"
;         "s_waitcnt lgkmcnt(0)\n\t"
;         "v_mfma_f32_32x32x16_bf16 %0, %8, %10, %0\n\tv_mfma_f32_32x32x16_bf16 %1, %8, %11, %1\n\tv_mfma_f32_32x32x16_bf16 %2, %9, %10, %2\n\tv_mfma_f32_32x32x16_bf16 %3, %9, %11, %3"
;         : "+v"(acc[0][0]), "+v"(acc[0][1]), "+v"(acc[1][0]), "+v"(acc[1][1]),
;           "=&v"(p0), "=&v"(p1), "=&v"(q0), "=&v"(q1), "=&v"(u0), "=&v"(u1), "=&v"(w0), "=&v"(w1)
	ds_read_b128 v[164:167], v76 offset:49152
	ds_read_b128 v[168:171], v76 offset:53248
	ds_read_b128 v[172:175], v80 offset:49152
	ds_read_b128 v[176:179], v80 offset:53248
	v_mfma_f32_32x32x16_bf16 v[48:63], v[180:183], v[218:221], v[48:63]
	s_mov_b32 s10, 0xa5c2f00
	s_mov_b32 m0, s26
	v_lshl_add_u64 v[160:161], v[74:75], 0, s[10:11]
	global_load_lds_dwordx4 v[160:161], off
	v_mfma_f32_32x32x16_bf16 v[32:47], v[180:183], v[222:225], v[32:47]
	v_mfma_f32_32x32x16_bf16 v[16:31], v[184:187], v[218:221], v[16:31]
	s_add_u32 m0, s26, 0x2000
	v_lshl_add_u64 v[162:163], v[72:73], 0, s[10:11]
	global_load_lds_dwordx4 v[162:163], off
	v_mfma_f32_32x32x16_bf16 v[0:15], v[184:187], v[222:225], v[0:15]
	ds_read_b128 v[180:183], v77 offset:49152
	ds_read_b128 v[184:187], v77 offset:53248
	ds_read_b128 v[218:221], v81 offset:49152
	ds_read_b128 v[222:225], v81 offset:53248
	s_waitcnt lgkmcnt(4)
	v_mfma_f32_32x32x16_bf16 v[48:63], v[164:167], v[172:175], v[48:63]
	s_add_u32 m0, s26, 0x4000
	v_lshl_add_u64 v[160:161], v[70:71], 0, s[10:11]
	global_load_lds_dwordx4 v[160:161], off
	v_mfma_f32_32x32x16_bf16 v[32:47], v[164:167], v[176:179], v[32:47]
	v_mfma_f32_32x32x16_bf16 v[16:31], v[168:171], v[172:175], v[16:31]
	s_add_u32 m0, s26, 0x6000
	v_lshl_add_u64 v[162:163], v[68:69], 0, s[10:11]
	global_load_lds_dwordx4 v[162:163], off
	v_mfma_f32_32x32x16_bf16 v[0:15], v[168:171], v[176:179], v[0:15]
	ds_read_b128 v[164:167], v78 offset:49152
	ds_read_b128 v[168:171], v78 offset:53248
	ds_read_b128 v[172:175], v82 offset:49152
	ds_read_b128 v[176:179], v82 offset:53248
	s_waitcnt lgkmcnt(4)
	v_mfma_f32_32x32x16_bf16 v[48:63], v[180:183], v[218:221], v[48:63]
	s_mov_b32 s10, 0xb00f00
	s_add_u32 m0, s26, 0x8000
	v_lshl_add_u64 v[160:161], v[66:67], 0, s[10:11]
	global_load_lds_dwordx4 v[160:161], off
	v_mfma_f32_32x32x16_bf16 v[32:47], v[180:183], v[222:225], v[32:47]
	v_mfma_f32_32x32x16_bf16 v[16:31], v[184:187], v[218:221], v[16:31]
	s_add_u32 m0, s26, 0xa000
	v_lshl_add_u64 v[162:163], v[64:65], 0, s[10:11]
	global_load_lds_dwordx4 v[162:163], off
	v_mfma_f32_32x32x16_bf16 v[0:15], v[184:187], v[222:225], v[0:15]
	ds_read_b128 v[180:183], v79 offset:49152
	ds_read_b128 v[184:187], v79 offset:53248
	ds_read_b128 v[218:221], v83 offset:49152
	ds_read_b128 v[222:225], v83 offset:53248
	s_waitcnt lgkmcnt(4)
	v_mfma_f32_32x32x16_bf16 v[48:63], v[164:167], v[172:175], v[48:63]
	v_mfma_f32_32x32x16_bf16 v[32:47], v[164:167], v[176:179], v[32:47]
	v_mfma_f32_32x32x16_bf16 v[16:31], v[168:171], v[172:175], v[16:31]
	v_mfma_f32_32x32x16_bf16 v[0:15], v[168:171], v[176:179], v[0:15]
	s_waitcnt vmcnt(6) lgkmcnt(0)
	s_barrier
	ds_read_b128 v[164:167], v84
	ds_read_b128 v[168:171], v84 offset:4096
	ds_read_b128 v[172:175], v156
	ds_read_b128 v[176:179], v156 offset:4096
	v_mfma_f32_32x32x16_bf16 v[48:63], v[180:183], v[218:221], v[48:63]
	s_mov_b32 s10, 0xa5c2f80
	s_add_u32 m0, s26, 0xc000
	v_lshl_add_u64 v[160:161], v[74:75], 0, s[10:11]
	global_load_lds_dwordx4 v[160:161], off
	v_mfma_f32_32x32x16_bf16 v[32:47], v[180:183], v[222:225], v[32:47]
	v_mfma_f32_32x32x16_bf16 v[16:31], v[184:187], v[218:221], v[16:31]
	s_add_u32 m0, s26, 0xe000
	v_lshl_add_u64 v[162:163], v[72:73], 0, s[10:11]
	global_load_lds_dwordx4 v[162:163], off
	v_mfma_f32_32x32x16_bf16 v[0:15], v[184:187], v[222:225], v[0:15]
	ds_read_b128 v[180:183], v85
	ds_read_b128 v[184:187], v85 offset:4096
	ds_read_b128 v[218:221], v157
	ds_read_b128 v[222:225], v157 offset:4096
	s_waitcnt lgkmcnt(4)
	v_mfma_f32_32x32x16_bf16 v[48:63], v[164:167], v[172:175], v[48:63]
	s_add_u32 m0, s26, 0x10000
	v_lshl_add_u64 v[160:161], v[70:71], 0, s[10:11]
	global_load_lds_dwordx4 v[160:161], off
	v_mfma_f32_32x32x16_bf16 v[32:47], v[164:167], v[176:179], v[32:47]
	v_mfma_f32_32x32x16_bf16 v[16:31], v[168:171], v[172:175], v[16:31]
	s_add_u32 m0, s26, 0x12000
	v_lshl_add_u64 v[162:163], v[68:69], 0, s[10:11]
	global_load_lds_dwordx4 v[162:163], off
	v_mfma_f32_32x32x16_bf16 v[0:15], v[168:171], v[176:179], v[0:15]
	ds_read_b128 v[164:167], v86
	ds_read_b128 v[168:171], v86 offset:4096
	ds_read_b128 v[172:175], v158
	ds_read_b128 v[176:179], v158 offset:4096
	s_waitcnt lgkmcnt(4)
	v_mfma_f32_32x32x16_bf16 v[48:63], v[180:183], v[218:221], v[48:63]
	s_mov_b32 s10, 0xb00f80
	s_add_u32 m0, s26, 0x14000
	v_lshl_add_u64 v[160:161], v[66:67], 0, s[10:11]
	global_load_lds_dwordx4 v[160:161], off
	v_mfma_f32_32x32x16_bf16 v[32:47], v[180:183], v[222:225], v[32:47]
	v_mfma_f32_32x32x16_bf16 v[16:31], v[184:187], v[218:221], v[16:31]
	s_add_u32 m0, s26, 0x16000
	v_lshl_add_u64 v[162:163], v[64:65], 0, s[10:11]
	global_load_lds_dwordx4 v[162:163], off
	v_mfma_f32_32x32x16_bf16 v[0:15], v[184:187], v[222:225], v[0:15]
	ds_read_b128 v[180:183], v87
	ds_read_b128 v[184:187], v87 offset:4096
	ds_read_b128 v[218:221], v159
	ds_read_b128 v[222:225], v159 offset:4096
	s_waitcnt lgkmcnt(4)
	v_mfma_f32_32x32x16_bf16 v[48:63], v[164:167], v[172:175], v[48:63]
	v_mfma_f32_32x32x16_bf16 v[32:47], v[164:167], v[176:179], v[32:47]
	v_mfma_f32_32x32x16_bf16 v[16:31], v[168:171], v[172:175], v[16:31]
	v_mfma_f32_32x32x16_bf16 v[0:15], v[168:171], v[176:179], v[0:15]
	s_waitcnt vmcnt(6) lgkmcnt(0)
	s_barrier
;     ...
;   for (int kt = 0; kt < nk; ++kt) {
;     if (kt + 1 < nk) asm volatile("s_waitcnt vmcnt(6)" ::: "memory");
;     else asm volatile("s_waitcnt vmcnt(0)" ::: "memory");
;     __builtin_amdgcn_s_barrier();
;     asm volatile("" ::: "memory");
;     if (kt + 2 < nk) { const int st2 = (st >= 1) ? st - 1 : 2; GEMM_ISSUE(kt + 2, st2); }
;     const char* la = lds + st * STAGE_B;
;     const char* lb = la + 32768;
;     const unsigned sa_u = (unsigned)(size_t)la + arow_u, sb_u = (unsigned)(size_t)lb + brow_u;
;     const unsigned a0 = sa_u + co0, a1 = sa_u + co1, a2 = sa_u + co2, a3 = sa_u + co3;
;     const unsigned b0 = sb_u + co0, b1 = sb_u + co1, b2 = sb_u + co2, b3 = sb_u + co3;
;     {
;       bf16x8 p0, p1, q0, q1, u0, u1, w0, w1;
;       asm volatile(
;         "ds_read_b128 %4, %12\n\tds_read_b128 %5, %12 offset:4096\n\tds_read_b128 %6, %16\n\tds_read_b128 %7, %16 offset:4096\n\t"
;         "ds_read_b128 %8, %13\n\tds_read_b128 %9, %13 offset:4096\n\tds_read_b128 %10, %17\n\tds_read_b128 %11, %17 offset:4096\n\t"
;         "s_waitcnt lgkmcnt(4)\n\t"
;         "v_mfma_f32_32x32x16_bf16 %0, %4, %6, %0\n\tv_mfma_f32_32x32x16_bf16 %1, %4, %7, %1\n\tv_mfma_f32_32x32x16_bf16 %2, %5, %6, %2\n\tv_mfma_f32_32x32x16_bf16 %3, %5, %7, %3\n\t"
;         "ds_read_b128 %4, %14\n\tds_read_b128 %5, %14 offset:4096\n\tds_read_b128 %6, %18\n\tds_read_b128 %7, %18 offset:4096\n\t"
;         "s_waitcnt lgkmcnt(4)\n\t"
;         "v_mfma_f32_32x32x16_bf16 %0, %8, %10, %0\n\tv_mfma_f32_32x32x16_bf16 %1, %8, %11, %1\n\tv_mfma_f32_32x32x16_bf16 %2, %9, %10, %2\n\tv_mfma_f32_32x32x16_bf16 %3, %9, %11, %3\n\t"
;         "ds_read_b128 %8, %15\n\tds_read_b128 %9, %15 offset:4096\n\tds_read_b128 %10, %19\n\tds_read_b128 %11, %19 offset:4096\n\t"
;         "s_waitcnt lgkmcnt(4)\n\t"
;         "v_mfma_f32_32x32x16_bf16 %0, %4, %6, %0\n\tv_mfma_f32_32x32x16_bf16 %1, %4, %7, %1\n\tv_mfma_f32_32x32x16_bf16 %2, %5, %6, %2\n\tv_mfma_f32_32x32x16_bf16 %3, %5, %7, %3\n\t"
;         "s_waitcnt lgkmcnt(0)\n\t"
;         "v_mfma_f32_32x32x16_bf16 %0, %8, %10, %0\n\tv_mfma_f32_32x32x16_bf16 %1, %8, %11, %1\n\tv_mfma_f32_32x32x16_bf16 %2, %9, %10, %2\n\tv_mfma_f32_32x32x16_bf16 %3, %9, %11, %3"
;         : "+v"(acc[0][0]), "+v"(acc[0][1]), "+v"(acc[1][0]), "+v"(acc[1][1]),
;           "=&v"(p0), "=&v"(p1), "=&v"(q0), "=&v"(q1), "=&v"(u0), "=&v"(u1), "=&v"(w0), "=&v"(w1)
	ds_read_b128 v[164:167], v76
	ds_read_b128 v[168:171], v76 offset:4096
	ds_read_b128 v[172:175], v80
	ds_read_b128 v[176:179], v80 offset:4096
	v_mfma_f32_32x32x16_bf16 v[48:63], v[180:183], v[218:221], v[48:63]
	s_mov_b32 s10, 0xa5c3000
	s_add_u32 m0, s26, 0x18000
	v_lshl_add_u64 v[160:161], v[74:75], 0, s[10:11]
	global_load_lds_dwordx4 v[160:161], off
	v_mfma_f32_32x32x16_bf16 v[32:47], v[180:183], v[222:225], v[32:47]
	v_mfma_f32_32x32x16_bf16 v[16:31], v[184:187], v[218:221], v[16:31]
	s_add_u32 m0, s26, 0x1a000
	v_lshl_add_u64 v[162:163], v[72:73], 0, s[10:11]
	global_load_lds_dwordx4 v[162:163], off
	v_mfma_f32_32x32x16_bf16 v[0:15], v[184:187], v[222:225], v[0:15]
	ds_read_b128 v[180:183], v77
	ds_read_b128 v[184:187], v77 offset:4096
	ds_read_b128 v[218:221], v81
	ds_read_b128 v[222:225], v81 offset:4096
	s_waitcnt lgkmcnt(4)
	v_mfma_f32_32x32x16_bf16 v[48:63], v[164:167], v[172:175], v[48:63]
	s_add_u32 m0, s26, 0x1c000
	v_lshl_add_u64 v[160:161], v[70:71], 0, s[10:11]
	global_load_lds_dwordx4 v[160:161], off
	v_mfma_f32_32x32x16_bf16 v[32:47], v[164:167], v[176:179], v[32:47]
	v_mfma_f32_32x32x16_bf16 v[16:31], v[168:171], v[172:175], v[16:31]
	s_add_u32 m0, s26, 0x1e000
	v_lshl_add_u64 v[162:163], v[68:69], 0, s[10:11]
	global_load_lds_dwordx4 v[162:163], off
	v_mfma_f32_32x32x16_bf16 v[0:15], v[168:171], v[176:179], v[0:15]
	ds_read_b128 v[164:167], v78
	ds_read_b128 v[168:171], v78 offset:4096
	ds_read_b128 v[172:175], v82
	ds_read_b128 v[176:179], v82 offset:4096
	s_waitcnt lgkmcnt(4)
	v_mfma_f32_32x32x16_bf16 v[48:63], v[180:183], v[218:221], v[48:63]
	s_mov_b32 s10, 0xb01000
	s_add_u32 m0, s26, 0x20000
	v_lshl_add_u64 v[160:161], v[66:67], 0, s[10:11]
	global_load_lds_dwordx4 v[160:161], off
	v_mfma_f32_32x32x16_bf16 v[32:47], v[180:183], v[222:225], v[32:47]
	v_mfma_f32_32x32x16_bf16 v[16:31], v[184:187], v[218:221], v[16:31]
	s_add_u32 m0, s26, 0x22000
	v_lshl_add_u64 v[162:163], v[64:65], 0, s[10:11]
	global_load_lds_dwordx4 v[162:163], off
	v_mfma_f32_32x32x16_bf16 v[0:15], v[184:187], v[222:225], v[0:15]
	ds_read_b128 v[180:183], v79
	ds_read_b128 v[184:187], v79 offset:4096
	ds_read_b128 v[218:221], v83
	ds_read_b128 v[222:225], v83 offset:4096
	s_waitcnt lgkmcnt(4)
	v_mfma_f32_32x32x16_bf16 v[48:63], v[164:167], v[172:175], v[48:63]
	v_mfma_f32_32x32x16_bf16 v[32:47], v[164:167], v[176:179], v[32:47]
	v_mfma_f32_32x32x16_bf16 v[16:31], v[168:171], v[172:175], v[16:31]
	v_mfma_f32_32x32x16_bf16 v[0:15], v[168:171], v[176:179], v[0:15]
	s_waitcnt vmcnt(6) lgkmcnt(0)
	s_barrier
	ds_read_b128 v[164:167], v76 offset:49152
	ds_read_b128 v[168:171], v76 offset:53248
	ds_read_b128 v[172:175], v80 offset:49152
	ds_read_b128 v[176:179], v80 offset:53248
	v_mfma_f32_32x32x16_bf16 v[48:63], v[180:183], v[218:221], v[48:63]
	s_mov_b32 s10, 0xa5c3080
	s_mov_b32 m0, s26
	v_lshl_add_u64 v[160:161], v[74:75], 0, s[10:11]
	global_load_lds_dwordx4 v[160:161], off
	v_mfma_f32_32x32x16_bf16 v[32:47], v[180:183], v[222:225], v[32:47]
	v_mfma_f32_32x32x16_bf16 v[16:31], v[184:187], v[218:221], v[16:31]
	s_add_u32 m0, s26, 0x2000
	v_lshl_add_u64 v[162:163], v[72:73], 0, s[10:11]
	global_load_lds_dwordx4 v[162:163], off
	v_mfma_f32_32x32x16_bf16 v[0:15], v[184:187], v[222:225], v[0:15]
	ds_read_b128 v[180:183], v77 offset:49152
	ds_read_b128 v[184:187], v77 offset:53248
	ds_read_b128 v[218:221], v81 offset:49152
	ds_read_b128 v[222:225], v81 offset:53248
	s_waitcnt lgkmcnt(4)
	v_mfma_f32_32x32x16_bf16 v[48:63], v[164:167], v[172:175], v[48:63]
	s_add_u32 m0, s26, 0x4000
	v_lshl_add_u64 v[160:161], v[70:71], 0, s[10:11]
	global_load_lds_dwordx4 v[160:161], off
	v_mfma_f32_32x32x16_bf16 v[32:47], v[164:167], v[176:179], v[32:47]
	v_mfma_f32_32x32x16_bf16 v[16:31], v[168:171], v[172:175], v[16:31]
	s_add_u32 m0, s26, 0x6000
	v_lshl_add_u64 v[162:163], v[68:69], 0, s[10:11]
	global_load_lds_dwordx4 v[162:163], off
	v_mfma_f32_32x32x16_bf16 v[0:15], v[168:171], v[176:179], v[0:15]
	ds_read_b128 v[164:167], v78 offset:49152
	ds_read_b128 v[168:171], v78 offset:53248
	ds_read_b128 v[172:175], v82 offset:49152
	ds_read_b128 v[176:179], v82 offset:53248
	s_waitcnt lgkmcnt(4)
	v_mfma_f32_32x32x16_bf16 v[48:63], v[180:183], v[218:221], v[48:63]
	s_mov_b32 s10, 0xb01080
	s_add_u32 m0, s26, 0x8000
	v_lshl_add_u64 v[160:161], v[66:67], 0, s[10:11]
	global_load_lds_dwordx4 v[160:161], off
	v_mfma_f32_32x32x16_bf16 v[32:47], v[180:183], v[222:225], v[32:47]
	v_mfma_f32_32x32x16_bf16 v[16:31], v[184:187], v[218:221], v[16:31]
	s_add_u32 m0, s26, 0xa000
	v_lshl_add_u64 v[162:163], v[64:65], 0, s[10:11]
	global_load_lds_dwordx4 v[162:163], off
	v_mfma_f32_32x32x16_bf16 v[0:15], v[184:187], v[222:225], v[0:15]
	ds_read_b128 v[180:183], v79 offset:49152
	ds_read_b128 v[184:187], v79 offset:53248
	ds_read_b128 v[218:221], v83 offset:49152
	ds_read_b128 v[222:225], v83 offset:53248
	s_waitcnt lgkmcnt(4)
	v_mfma_f32_32x32x16_bf16 v[48:63], v[164:167], v[172:175], v[48:63]
	v_mfma_f32_32x32x16_bf16 v[32:47], v[164:167], v[176:179], v[32:47]
	v_mfma_f32_32x32x16_bf16 v[16:31], v[168:171], v[172:175], v[16:31]
	v_mfma_f32_32x32x16_bf16 v[0:15], v[168:171], v[176:179], v[0:15]
	s_waitcnt vmcnt(6) lgkmcnt(0)
	s_barrier
;     ...
;   for (int kt = 0; kt < nk; ++kt) {
;     if (kt + 1 < nk) asm volatile("s_waitcnt vmcnt(6)" ::: "memory");
;     else asm volatile("s_waitcnt vmcnt(0)" ::: "memory");
;     __builtin_amdgcn_s_barrier();
;     asm volatile("" ::: "memory");
;     if (kt + 2 < nk) { const int st2 = (st >= 1) ? st - 1 : 2; GEMM_ISSUE(kt + 2, st2); }
;     const char* la = lds + st * STAGE_B;
;     const char* lb = la + 32768;
;     const unsigned sa_u = (unsigned)(size_t)la + arow_u, sb_u = (unsigned)(size_t)lb + brow_u;
;     const unsigned a0 = sa_u + co0, a1 = sa_u + co1, a2 = sa_u + co2, a3 = sa_u + co3;
;     const unsigned b0 = sb_u + co0, b1 = sb_u + co1, b2 = sb_u + co2, b3 = sb_u + co3;
;     {
;       bf16x8 p0, p1, q0, q1, u0, u1, w0, w1;
;       asm volatile(
;         "ds_read_b128 %4, %12\n\tds_read_b128 %5, %12 offset:4096\n\tds_read_b128 %6, %16\n\tds_read_b128 %7, %16 offset:4096\n\t"
;         "ds_read_b128 %8, %13\n\tds_read_b128 %9, %13 offset:4096\n\tds_read_b128 %10, %17\n\tds_read_b128 %11, %17 offset:4096\n\t"
;         "s_waitcnt lgkmcnt(4)\n\t"
;         "v_mfma_f32_32x32x16_bf16 %0, %4, %6, %0\n\tv_mfma_f32_32x32x16_bf16 %1, %4, %7, %1\n\tv_mfma_f32_32x32x16_bf16 %2, %5, %6, %2\n\tv_mfma_f32_32x32x16_bf16 %3, %5, %7, %3\n\t"
;         "ds_read_b128 %4, %14\n\tds_read_b128 %5, %14 offset:4096\n\tds_read_b128 %6, %18\n\tds_read_b128 %7, %18 offset:4096\n\t"
;         "s_waitcnt lgkmcnt(4)\n\t"
;         "v_mfma_f32_32x32x16_bf16 %0, %8, %10, %0\n\tv_mfma_f32_32x32x16_bf16 %1, %8, %11, %1\n\tv_mfma_f32_32x32x16_bf16 %2, %9, %10, %2\n\tv_mfma_f32_32x32x16_bf16 %3, %9, %11, %3\n\t"
;         "ds_read_b128 %8, %15\n\tds_read_b128 %9, %15 offset:4096\n\tds_read_b128 %10, %19\n\tds_read_b128 %11, %19 offset:4096\n\t"
;         "s_waitcnt lgkmcnt(4)\n\t"
;         "v_mfma_f32_32x32x16_bf16 %0, %4, %6, %0\n\tv_mfma_f32_32x32x16_bf16 %1, %4, %7, %1\n\tv_mfma_f32_32x32x16_bf16 %2, %5, %6, %2\n\tv_mfma_f32_32x32x16_bf16 %3, %5, %7, %3\n\t"
;         "s_waitcnt lgkmcnt(0)\n\t"
;         "v_mfma_f32_32x32x16_bf16 %0, %8, %10, %0\n\tv_mfma_f32_32x32x16_bf16 %1, %8, %11, %1\n\tv_mfma_f32_32x32x16_bf16 %2, %9, %10, %2\n\tv_mfma_f32_32x32x16_bf16 %3, %9, %11, %3"
;         : "+v"(acc[0][0]), "+v"(acc[0][1]), "+v"(acc[1][0]), "+v"(acc[1][1]),
;           "=&v"(p0), "=&v"(p1), "=&v"(q0), "=&v"(q1), "=&v"(u0), "=&v"(u1), "=&v"(w0), "=&v"(w1)
	ds_read_b128 v[164:167], v84
	ds_read_b128 v[168:171], v84 offset:4096
	ds_read_b128 v[172:175], v156
	ds_read_b128 v[176:179], v156 offset:4096
	v_mfma_f32_32x32x16_bf16 v[48:63], v[180:183], v[218:221], v[48:63]
	s_mov_b32 s10, 0xa5c3100
	s_add_u32 m0, s26, 0xc000
	v_lshl_add_u64 v[160:161], v[74:75], 0, s[10:11]
	global_load_lds_dwordx4 v[160:161], off
	v_mfma_f32_32x32x16_bf16 v[32:47], v[180:183], v[222:225], v[32:47]
	v_mfma_f32_32x32x16_bf16 v[16:31], v[184:187], v[218:221], v[16:31]
	s_add_u32 m0, s26, 0xe000
	v_lshl_add_u64 v[162:163], v[72:73], 0, s[10:11]
	global_load_lds_dwordx4 v[162:163], off
	v_mfma_f32_32x32x16_bf16 v[0:15], v[184:187], v[222:225], v[0:15]
	ds_read_b128 v[180:183], v85
	ds_read_b128 v[184:187], v85 offset:4096
	ds_read_b128 v[218:221], v157
	ds_read_b128 v[222:225], v157 offset:4096
	s_waitcnt lgkmcnt(4)
	v_mfma_f32_32x32x16_bf16 v[48:63], v[164:167], v[172:175], v[48:63]
	s_add_u32 m0, s26, 0x10000
	v_lshl_add_u64 v[160:161], v[70:71], 0, s[10:11]
	global_load_lds_dwordx4 v[160:161], off
	v_mfma_f32_32x32x16_bf16 v[32:47], v[164:167], v[176:179], v[32:47]
	v_mfma_f32_32x32x16_bf16 v[16:31], v[168:171], v[172:175], v[16:31]
	s_add_u32 m0, s26, 0x12000
	v_lshl_add_u64 v[162:163], v[68:69], 0, s[10:11]
	global_load_lds_dwordx4 v[162:163], off
	v_mfma_f32_32x32x16_bf16 v[0:15], v[168:171], v[176:179], v[0:15]
	ds_read_b128 v[164:167], v86
	ds_read_b128 v[168:171], v86 offset:4096
	ds_read_b128 v[172:175], v158
	ds_read_b128 v[176:179], v158 offset:4096
	s_waitcnt lgkmcnt(4)
	v_mfma_f32_32x32x16_bf16 v[48:63], v[180:183], v[218:221], v[48:63]
	s_mov_b32 s10, 0xb01100
	s_add_u32 m0, s26, 0x14000
	v_lshl_add_u64 v[160:161], v[66:67], 0, s[10:11]
	global_load_lds_dwordx4 v[160:161], off
	v_mfma_f32_32x32x16_bf16 v[32:47], v[180:183], v[222:225], v[32:47]
	v_mfma_f32_32x32x16_bf16 v[16:31], v[184:187], v[218:221], v[16:31]
	s_add_u32 m0, s26, 0x16000
	v_lshl_add_u64 v[162:163], v[64:65], 0, s[10:11]
	global_load_lds_dwordx4 v[162:163], off
	v_mfma_f32_32x32x16_bf16 v[0:15], v[184:187], v[222:225], v[0:15]
	ds_read_b128 v[180:183], v87
	ds_read_b128 v[184:187], v87 offset:4096
	ds_read_b128 v[218:221], v159
	ds_read_b128 v[222:225], v159 offset:4096
	s_waitcnt lgkmcnt(4)
	v_mfma_f32_32x32x16_bf16 v[48:63], v[164:167], v[172:175], v[48:63]
	v_mfma_f32_32x32x16_bf16 v[32:47], v[164:167], v[176:179], v[32:47]
	v_mfma_f32_32x32x16_bf16 v[16:31], v[168:171], v[172:175], v[16:31]
	v_mfma_f32_32x32x16_bf16 v[0:15], v[168:171], v[176:179], v[0:15]
	s_waitcnt vmcnt(6) lgkmcnt(0)
	s_barrier
	ds_read_b128 v[164:167], v76
	ds_read_b128 v[168:171], v76 offset:4096
	ds_read_b128 v[172:175], v80
	ds_read_b128 v[176:179], v80 offset:4096
	v_mfma_f32_32x32x16_bf16 v[48:63], v[180:183], v[218:221], v[48:63]
	s_mov_b32 s10, 0xa5c3180
	s_add_u32 m0, s26, 0x18000
	v_lshl_add_u64 v[160:161], v[74:75], 0, s[10:11]
	global_load_lds_dwordx4 v[160:161], off
	v_mfma_f32_32x32x16_bf16 v[32:47], v[180:183], v[222:225], v[32:47]
	v_mfma_f32_32x32x16_bf16 v[16:31], v[184:187], v[218:221], v[16:31]
	s_add_u32 m0, s26, 0x1a000
	v_lshl_add_u64 v[162:163], v[72:73], 0, s[10:11]
	global_load_lds_dwordx4 v[162:163], off
	v_mfma_f32_32x32x16_bf16 v[0:15], v[184:187], v[222:225], v[0:15]
	ds_read_b128 v[180:183], v77
	ds_read_b128 v[184:187], v77 offset:4096
	ds_read_b128 v[218:221], v81
	ds_read_b128 v[222:225], v81 offset:4096
	s_waitcnt lgkmcnt(4)
	v_mfma_f32_32x32x16_bf16 v[48:63], v[164:167], v[172:175], v[48:63]
	s_add_u32 m0, s26, 0x1c000
	v_lshl_add_u64 v[160:161], v[70:71], 0, s[10:11]
	global_load_lds_dwordx4 v[160:161], off
	v_mfma_f32_32x32x16_bf16 v[32:47], v[164:167], v[176:179], v[32:47]
	v_mfma_f32_32x32x16_bf16 v[16:31], v[168:171], v[172:175], v[16:31]
	s_add_u32 m0, s26, 0x1e000
	v_lshl_add_u64 v[162:163], v[68:69], 0, s[10:11]
	global_load_lds_dwordx4 v[162:163], off
	v_mfma_f32_32x32x16_bf16 v[0:15], v[168:171], v[176:179], v[0:15]
	ds_read_b128 v[164:167], v78
	ds_read_b128 v[168:171], v78 offset:4096
	ds_read_b128 v[172:175], v82
	ds_read_b128 v[176:179], v82 offset:4096
	s_waitcnt lgkmcnt(4)
	v_mfma_f32_32x32x16_bf16 v[48:63], v[180:183], v[218:221], v[48:63]
	s_mov_b32 s10, 0xb01180
	s_add_u32 m0, s26, 0x20000
	v_lshl_add_u64 v[160:161], v[66:67], 0, s[10:11]
	global_load_lds_dwordx4 v[160:161], off
	v_mfma_f32_32x32x16_bf16 v[32:47], v[180:183], v[222:225], v[32:47]
	v_mfma_f32_32x32x16_bf16 v[16:31], v[184:187], v[218:221], v[16:31]
	s_add_u32 m0, s26, 0x22000
	v_lshl_add_u64 v[162:163], v[64:65], 0, s[10:11]
	global_load_lds_dwordx4 v[162:163], off
	v_mfma_f32_32x32x16_bf16 v[0:15], v[184:187], v[222:225], v[0:15]
	ds_read_b128 v[180:183], v79
	ds_read_b128 v[184:187], v79 offset:4096
	ds_read_b128 v[218:221], v83
	ds_read_b128 v[222:225], v83 offset:4096
	s_waitcnt lgkmcnt(4)
	v_mfma_f32_32x32x16_bf16 v[48:63], v[164:167], v[172:175], v[48:63]
	v_mfma_f32_32x32x16_bf16 v[32:47], v[164:167], v[176:179], v[32:47]
	v_mfma_f32_32x32x16_bf16 v[16:31], v[168:171], v[172:175], v[16:31]
	v_mfma_f32_32x32x16_bf16 v[0:15], v[168:171], v[176:179], v[0:15]
	s_waitcnt vmcnt(6) lgkmcnt(0)
	s_barrier
;     ...
;   for (int kt = 0; kt < nk; ++kt) {
;     if (kt + 1 < nk) asm volatile("s_waitcnt vmcnt(6)" ::: "memory");
;     else asm volatile("s_waitcnt vmcnt(0)" ::: "memory");
;     __builtin_amdgcn_s_barrier();
;     asm volatile("" ::: "memory");
;     if (kt + 2 < nk) { const int st2 = (st >= 1) ? st - 1 : 2; GEMM_ISSUE(kt + 2, st2); }
;     const char* la = lds + st * STAGE_B;
;     const char* lb = la + 32768;
;     const unsigned sa_u = (unsigned)(size_t)la + arow_u, sb_u = (unsigned)(size_t)lb + brow_u;
;     const unsigned a0 = sa_u + co0, a1 = sa_u + co1, a2 = sa_u + co2, a3 = sa_u + co3;
;     const unsigned b0 = sb_u + co0, b1 = sb_u + co1, b2 = sb_u + co2, b3 = sb_u + co3;
;     {
;       bf16x8 p0, p1, q0, q1, u0, u1, w0, w1;
;       asm volatile(
;         "ds_read_b128 %4, %12\n\tds_read_b128 %5, %12 offset:4096\n\tds_read_b128 %6, %16\n\tds_read_b128 %7, %16 offset:4096\n\t"
;         "ds_read_b128 %8, %13\n\tds_read_b128 %9, %13 offset:4096\n\tds_read_b128 %10, %17\n\tds_read_b128 %11, %17 offset:4096\n\t"
;         "s_waitcnt lgkmcnt(4)\n\t"
;         "v_mfma_f32_32x32x16_bf16 %0, %4, %6, %0\n\tv_mfma_f32_32x32x16_bf16 %1, %4, %7, %1\n\tv_mfma_f32_32x32x16_bf16 %2, %5, %6, %2\n\tv_mfma_f32_32x32x16_bf16 %3, %5, %7, %3\n\t"
;         "ds_read_b128 %4, %14\n\tds_read_b128 %5, %14 offset:4096\n\tds_read_b128 %6, %18\n\tds_read_b128 %7, %18 offset:4096\n\t"
;         "s_waitcnt lgkmcnt(4)\n\t"
;         "v_mfma_f32_32x32x16_bf16 %0, %8, %10, %0\n\tv_mfma_f32_32x32x16_bf16 %1, %8, %11, %1\n\tv_mfma_f32_32x32x16_bf16 %2, %9, %10, %2\n\tv_mfma_f32_32x32x16_bf16 %3, %9, %11, %3\n\t"
;         "ds_read_b128 %8, %15\n\tds_read_b128 %9, %15 offset:4096\n\tds_read_b128 %10, %19\n\tds_read_b128 %11, %19 offset:4096\n\t"
;         "s_waitcnt lgkmcnt(4)\n\t"
;         "v_mfma_f32_32x32x16_bf16 %0, %4, %6, %0\n\tv_mfma_f32_32x32x16_bf16 %1, %4, %7, %1\n\tv_mfma_f32_32x32x16_bf16 %2, %5, %6, %2\n\tv_mfma_f32_32x32x16_bf16 %3, %5, %7, %3\n\t"
;         "s_waitcnt lgkmcnt(0)\n\t"
;         "v_mfma_f32_32x32x16_bf16 %0, %8, %10, %0\n\tv_mfma_f32_32x32x16_bf16 %1, %8, %11, %1\n\tv_mfma_f32_32x32x16_bf16 %2, %9, %10, %2\n\tv_mfma_f32_32x32x16_bf16 %3, %9, %11, %3"
;         : "+v"(acc[0][0]), "+v"(acc[0][1]), "+v"(acc[1][0]), "+v"(acc[1][1]),
;           "=&v"(p0), "=&v"(p1), "=&v"(q0), "=&v"(q1), "=&v"(u0), "=&v"(u1), "=&v"(w0), "=&v"(w1)
	ds_read_b128 v[164:167], v76 offset:49152
	ds_read_b128 v[168:171], v76 offset:53248
	ds_read_b128 v[172:175], v80 offset:49152
	ds_read_b128 v[176:179], v80 offset:53248
	v_mfma_f32_32x32x16_bf16 v[48:63], v[180:183], v[218:221], v[48:63]
	s_mov_b32 s10, 0xa5c3200
	s_mov_b32 m0, s26
	v_lshl_add_u64 v[160:161], v[74:75], 0, s[10:11]
	global_load_lds_dwordx4 v[160:161], off
	v_mfma_f32_32x32x16_bf16 v[32:47], v[180:183], v[222:225], v[32:47]
	v_mfma_f32_32x32x16_bf16 v[16:31], v[184:187], v[218:221], v[16:31]
	s_add_u32 m0, s26, 0x2000
	v_lshl_add_u64 v[162:163], v[72:73], 0, s[10:11]
	global_load_lds_dwordx4 v[162:163], off
	v_mfma_f32_32x32x16_bf16 v[0:15], v[184:187], v[222:225], v[0:15]
	ds_read_b128 v[180:183], v77 offset:49152
	ds_read_b128 v[184:187], v77 offset:53248
	ds_read_b128 v[218:221], v81 offset:49152
	ds_read_b128 v[222:225], v81 offset:53248
	s_waitcnt lgkmcnt(4)
	v_mfma_f32_32x32x16_bf16 v[48:63], v[164:167], v[172:175], v[48:63]
	s_add_u32 m0, s26, 0x4000
	v_lshl_add_u64 v[160:161], v[70:71], 0, s[10:11]
	global_load_lds_dwordx4 v[160:161], off
	v_mfma_f32_32x32x16_bf16 v[32:47], v[164:167], v[176:179], v[32:47]
	v_mfma_f32_32x32x16_bf16 v[16:31], v[168:171], v[172:175], v[16:31]
	s_add_u32 m0, s26, 0x6000
	v_lshl_add_u64 v[162:163], v[68:69], 0, s[10:11]
	global_load_lds_dwordx4 v[162:163], off
	v_mfma_f32_32x32x16_bf16 v[0:15], v[168:171], v[176:179], v[0:15]
	ds_read_b128 v[164:167], v78 offset:49152
	ds_read_b128 v[168:171], v78 offset:53248
	ds_read_b128 v[172:175], v82 offset:49152
	ds_read_b128 v[176:179], v82 offset:53248
	s_waitcnt lgkmcnt(4)
	v_mfma_f32_32x32x16_bf16 v[48:63], v[180:183], v[218:221], v[48:63]
	s_mov_b32 s10, 0xb01200
	s_add_u32 m0, s26, 0x8000
	v_lshl_add_u64 v[160:161], v[66:67], 0, s[10:11]
	global_load_lds_dwordx4 v[160:161], off
	v_mfma_f32_32x32x16_bf16 v[32:47], v[180:183], v[222:225], v[32:47]
	v_mfma_f32_32x32x16_bf16 v[16:31], v[184:187], v[218:221], v[16:31]
	s_add_u32 m0, s26, 0xa000
	v_lshl_add_u64 v[162:163], v[64:65], 0, s[10:11]
	global_load_lds_dwordx4 v[162:163], off
	v_mfma_f32_32x32x16_bf16 v[0:15], v[184:187], v[222:225], v[0:15]
	ds_read_b128 v[180:183], v79 offset:49152
	ds_read_b128 v[184:187], v79 offset:53248
	ds_read_b128 v[218:221], v83 offset:49152
	ds_read_b128 v[222:225], v83 offset:53248
	s_waitcnt lgkmcnt(4)
	v_mfma_f32_32x32x16_bf16 v[48:63], v[164:167], v[172:175], v[48:63]
	v_mfma_f32_32x32x16_bf16 v[32:47], v[164:167], v[176:179], v[32:47]
	v_mfma_f32_32x32x16_bf16 v[16:31], v[168:171], v[172:175], v[16:31]
	v_mfma_f32_32x32x16_bf16 v[0:15], v[168:171], v[176:179], v[0:15]
	s_waitcnt vmcnt(6) lgkmcnt(0)
	s_barrier
	ds_read_b128 v[164:167], v84
	ds_read_b128 v[168:171], v84 offset:4096
	ds_read_b128 v[172:175], v156
	ds_read_b128 v[176:179], v156 offset:4096
	v_mfma_f32_32x32x16_bf16 v[48:63], v[180:183], v[218:221], v[48:63]
	s_mov_b32 s10, 0xa5c3280
	s_add_u32 m0, s26, 0xc000
	v_lshl_add_u64 v[160:161], v[74:75], 0, s[10:11]
	global_load_lds_dwordx4 v[160:161], off
	v_mfma_f32_32x32x16_bf16 v[32:47], v[180:183], v[222:225], v[32:47]
	v_mfma_f32_32x32x16_bf16 v[16:31], v[184:187], v[218:221], v[16:31]
	s_add_u32 m0, s26, 0xe000
	v_lshl_add_u64 v[162:163], v[72:73], 0, s[10:11]
	global_load_lds_dwordx4 v[162:163], off
	v_mfma_f32_32x32x16_bf16 v[0:15], v[184:187], v[222:225], v[0:15]
	ds_read_b128 v[180:183], v85
	ds_read_b128 v[184:187], v85 offset:4096
	ds_read_b128 v[218:221], v157
	ds_read_b128 v[222:225], v157 offset:4096
	s_waitcnt lgkmcnt(4)
	v_mfma_f32_32x32x16_bf16 v[48:63], v[164:167], v[172:175], v[48:63]
	s_add_u32 m0, s26, 0x10000
	v_lshl_add_u64 v[160:161], v[70:71], 0, s[10:11]
	global_load_lds_dwordx4 v[160:161], off
	v_mfma_f32_32x32x16_bf16 v[32:47], v[164:167], v[176:179], v[32:47]
	v_mfma_f32_32x32x16_bf16 v[16:31], v[168:171], v[172:175], v[16:31]
	s_add_u32 m0, s26, 0x12000
	v_lshl_add_u64 v[162:163], v[68:69], 0, s[10:11]
	global_load_lds_dwordx4 v[162:163], off
	v_mfma_f32_32x32x16_bf16 v[0:15], v[168:171], v[176:179], v[0:15]
	ds_read_b128 v[164:167], v86
	ds_read_b128 v[168:171], v86 offset:4096
	ds_read_b128 v[172:175], v158
	ds_read_b128 v[176:179], v158 offset:4096
	s_waitcnt lgkmcnt(4)
	v_mfma_f32_32x32x16_bf16 v[48:63], v[180:183], v[218:221], v[48:63]
	s_mov_b32 s10, 0xb01280
	s_add_u32 m0, s26, 0x14000
	v_lshl_add_u64 v[160:161], v[66:67], 0, s[10:11]
	global_load_lds_dwordx4 v[160:161], off
	v_mfma_f32_32x32x16_bf16 v[32:47], v[180:183], v[222:225], v[32:47]
	v_mfma_f32_32x32x16_bf16 v[16:31], v[184:187], v[218:221], v[16:31]
	s_add_u32 m0, s26, 0x16000
	v_lshl_add_u64 v[162:163], v[64:65], 0, s[10:11]
	global_load_lds_dwordx4 v[162:163], off
	v_mfma_f32_32x32x16_bf16 v[0:15], v[184:187], v[222:225], v[0:15]
	ds_read_b128 v[180:183], v87
	ds_read_b128 v[184:187], v87 offset:4096
	ds_read_b128 v[218:221], v159
	ds_read_b128 v[222:225], v159 offset:4096
	s_waitcnt lgkmcnt(4)
	v_mfma_f32_32x32x16_bf16 v[48:63], v[164:167], v[172:175], v[48:63]
	v_mfma_f32_32x32x16_bf16 v[32:47], v[164:167], v[176:179], v[32:47]
	v_mfma_f32_32x32x16_bf16 v[16:31], v[168:171], v[172:175], v[16:31]
	v_mfma_f32_32x32x16_bf16 v[0:15], v[168:171], v[176:179], v[0:15]
	s_waitcnt vmcnt(6) lgkmcnt(0)
	s_barrier
;     ...
;   for (int kt = 0; kt < nk; ++kt) {
;     if (kt + 1 < nk) asm volatile("s_waitcnt vmcnt(6)" ::: "memory");
;     else asm volatile("s_waitcnt vmcnt(0)" ::: "memory");
;     __builtin_amdgcn_s_barrier();
;     asm volatile("" ::: "memory");
;     if (kt + 2 < nk) { const int st2 = (st >= 1) ? st - 1 : 2; GEMM_ISSUE(kt + 2, st2); }
;     const char* la = lds + st * STAGE_B;
;     const char* lb = la + 32768;
;     const unsigned sa_u = (unsigned)(size_t)la + arow_u, sb_u = (unsigned)(size_t)lb + brow_u;
;     const unsigned a0 = sa_u + co0, a1 = sa_u + co1, a2 = sa_u + co2, a3 = sa_u + co3;
;     const unsigned b0 = sb_u + co0, b1 = sb_u + co1, b2 = sb_u + co2, b3 = sb_u + co3;
;     {
;       bf16x8 p0, p1, q0, q1, u0, u1, w0, w1;
;       asm volatile(
;         "ds_read_b128 %4, %12\n\tds_read_b128 %5, %12 offset:4096\n\tds_read_b128 %6, %16\n\tds_read_b128 %7, %16 offset:4096\n\t"
;         "ds_read_b128 %8, %13\n\tds_read_b128 %9, %13 offset:4096\n\tds_read_b128 %10, %17\n\tds_read_b128 %11, %17 offset:4096\n\t"
;         "s_waitcnt lgkmcnt(4)\n\t"
;         "v_mfma_f32_32x32x16_bf16 %0, %4, %6, %0\n\tv_mfma_f32_32x32x16_bf16 %1, %4, %7, %1\n\tv_mfma_f32_32x32x16_bf16 %2, %5, %6, %2\n\tv_mfma_f32_32x32x16_bf16 %3, %5, %7, %3\n\t"
;         "ds_read_b128 %4, %14\n\tds_read_b128 %5, %14 offset:4096\n\tds_read_b128 %6, %18\n\tds_read_b128 %7, %18 offset:4096\n\t"
;         "s_waitcnt lgkmcnt(4)\n\t"
;         "v_mfma_f32_32x32x16_bf16 %0, %8, %10, %0\n\tv_mfma_f32_32x32x16_bf16 %1, %8, %11, %1\n\tv_mfma_f32_32x32x16_bf16 %2, %9, %10, %2\n\tv_mfma_f32_32x32x16_bf16 %3, %9, %11, %3\n\t"
;         "ds_read_b128 %8, %15\n\tds_read_b128 %9, %15 offset:4096\n\tds_read_b128 %10, %19\n\tds_read_b128 %11, %19 offset:4096\n\t"
;         "s_waitcnt lgkmcnt(4)\n\t"
;         "v_mfma_f32_32x32x16_bf16 %0, %4, %6, %0\n\tv_mfma_f32_32x32x16_bf16 %1, %4, %7, %1\n\tv_mfma_f32_32x32x16_bf16 %2, %5, %6, %2\n\tv_mfma_f32_32x32x16_bf16 %3, %5, %7, %3\n\t"
;         "s_waitcnt lgkmcnt(0)\n\t"
;         "v_mfma_f32_32x32x16_bf16 %0, %8, %10, %0\n\tv_mfma_f32_32x32x16_bf16 %1, %8, %11, %1\n\tv_mfma_f32_32x32x16_bf16 %2, %9, %10, %2\n\tv_mfma_f32_32x32x16_bf16 %3, %9, %11, %3"
;         : "+v"(acc[0][0]), "+v"(acc[0][1]), "+v"(acc[1][0]), "+v"(acc[1][1]),
;           "=&v"(p0), "=&v"(p1), "=&v"(q0), "=&v"(q1), "=&v"(u0), "=&v"(u1), "=&v"(w0), "=&v"(w1)
	ds_read_b128 v[164:167], v76
	ds_read_b128 v[168:171], v76 offset:4096
	ds_read_b128 v[172:175], v80
	ds_read_b128 v[176:179], v80 offset:4096
	v_mfma_f32_32x32x16_bf16 v[48:63], v[180:183], v[218:221], v[48:63]
	s_mov_b32 s10, 0xa5c3300
	s_add_u32 m0, s26, 0x18000
	v_lshl_add_u64 v[160:161], v[74:75], 0, s[10:11]
	global_load_lds_dwordx4 v[160:161], off
	v_mfma_f32_32x32x16_bf16 v[32:47], v[180:183], v[222:225], v[32:47]
	v_mfma_f32_32x32x16_bf16 v[16:31], v[184:187], v[218:221], v[16:31]
	s_add_u32 m0, s26, 0x1a000
	v_lshl_add_u64 v[162:163], v[72:73], 0, s[10:11]
	global_load_lds_dwordx4 v[162:163], off
	v_mfma_f32_32x32x16_bf16 v[0:15], v[184:187], v[222:225], v[0:15]
	ds_read_b128 v[180:183], v77
	ds_read_b128 v[184:187], v77 offset:4096
	ds_read_b128 v[218:221], v81
	ds_read_b128 v[222:225], v81 offset:4096
	s_waitcnt lgkmcnt(4)
	v_mfma_f32_32x32x16_bf16 v[48:63], v[164:167], v[172:175], v[48:63]
	s_add_u32 m0, s26, 0x1c000
	v_lshl_add_u64 v[160:161], v[70:71], 0, s[10:11]
	global_load_lds_dwordx4 v[160:161], off
	v_mfma_f32_32x32x16_bf16 v[32:47], v[164:167], v[176:179], v[32:47]
	v_mfma_f32_32x32x16_bf16 v[16:31], v[168:171], v[172:175], v[16:31]
	s_add_u32 m0, s26, 0x1e000
	v_lshl_add_u64 v[162:163], v[68:69], 0, s[10:11]
	global_load_lds_dwordx4 v[162:163], off
	v_mfma_f32_32x32x16_bf16 v[0:15], v[168:171], v[176:179], v[0:15]
	ds_read_b128 v[164:167], v78
	ds_read_b128 v[168:171], v78 offset:4096
	ds_read_b128 v[172:175], v82
	ds_read_b128 v[176:179], v82 offset:4096
	s_waitcnt lgkmcnt(4)
	v_mfma_f32_32x32x16_bf16 v[48:63], v[180:183], v[218:221], v[48:63]
	s_mov_b32 s10, 0xb01300
	s_add_u32 m0, s26, 0x20000
	v_lshl_add_u64 v[160:161], v[66:67], 0, s[10:11]
	global_load_lds_dwordx4 v[160:161], off
	v_mfma_f32_32x32x16_bf16 v[32:47], v[180:183], v[222:225], v[32:47]
	v_mfma_f32_32x32x16_bf16 v[16:31], v[184:187], v[218:221], v[16:31]
	s_add_u32 m0, s26, 0x22000
	v_lshl_add_u64 v[162:163], v[64:65], 0, s[10:11]
	global_load_lds_dwordx4 v[162:163], off
	v_mfma_f32_32x32x16_bf16 v[0:15], v[184:187], v[222:225], v[0:15]
	ds_read_b128 v[180:183], v79
	ds_read_b128 v[184:187], v79 offset:4096
	ds_read_b128 v[218:221], v83
	ds_read_b128 v[222:225], v83 offset:4096
	s_waitcnt lgkmcnt(4)
	v_mfma_f32_32x32x16_bf16 v[48:63], v[164:167], v[172:175], v[48:63]
	v_mfma_f32_32x32x16_bf16 v[32:47], v[164:167], v[176:179], v[32:47]
	v_mfma_f32_32x32x16_bf16 v[16:31], v[168:171], v[172:175], v[16:31]
	v_mfma_f32_32x32x16_bf16 v[0:15], v[168:171], v[176:179], v[0:15]
	s_waitcnt vmcnt(6) lgkmcnt(0)
	s_barrier
	ds_read_b128 v[164:167], v76 offset:49152
	ds_read_b128 v[168:171], v76 offset:53248
	ds_read_b128 v[172:175], v80 offset:49152
	ds_read_b128 v[176:179], v80 offset:53248
	v_mfma_f32_32x32x16_bf16 v[48:63], v[180:183], v[218:221], v[48:63]
	s_mov_b32 s10, 0xa5c3380
	s_mov_b32 m0, s26
	v_lshl_add_u64 v[160:161], v[74:75], 0, s[10:11]
	global_load_lds_dwordx4 v[160:161], off
	v_mfma_f32_32x32x16_bf16 v[32:47], v[180:183], v[222:225], v[32:47]
	v_mfma_f32_32x32x16_bf16 v[16:31], v[184:187], v[218:221], v[16:31]
	s_add_u32 m0, s26, 0x2000
	v_lshl_add_u64 v[162:163], v[72:73], 0, s[10:11]
	global_load_lds_dwordx4 v[162:163], off
	v_mfma_f32_32x32x16_bf16 v[0:15], v[184:187], v[222:225], v[0:15]
	ds_read_b128 v[180:183], v77 offset:49152
	ds_read_b128 v[184:187], v77 offset:53248
	ds_read_b128 v[218:221], v81 offset:49152
	ds_read_b128 v[222:225], v81 offset:53248
	s_waitcnt lgkmcnt(4)
	v_mfma_f32_32x32x16_bf16 v[48:63], v[164:167], v[172:175], v[48:63]
	s_add_u32 m0, s26, 0x4000
	v_lshl_add_u64 v[160:161], v[70:71], 0, s[10:11]
	global_load_lds_dwordx4 v[160:161], off
	v_mfma_f32_32x32x16_bf16 v[32:47], v[164:167], v[176:179], v[32:47]
	v_mfma_f32_32x32x16_bf16 v[16:31], v[168:171], v[172:175], v[16:31]
	s_add_u32 m0, s26, 0x6000
	v_lshl_add_u64 v[162:163], v[68:69], 0, s[10:11]
	global_load_lds_dwordx4 v[162:163], off
	v_mfma_f32_32x32x16_bf16 v[0:15], v[168:171], v[176:179], v[0:15]
	ds_read_b128 v[164:167], v78 offset:49152
	ds_read_b128 v[168:171], v78 offset:53248
	ds_read_b128 v[172:175], v82 offset:49152
	ds_read_b128 v[176:179], v82 offset:53248
	s_waitcnt lgkmcnt(4)
	v_mfma_f32_32x32x16_bf16 v[48:63], v[180:183], v[218:221], v[48:63]
	s_mov_b32 s10, 0xb01380
	s_add_u32 m0, s26, 0x8000
	v_lshl_add_u64 v[160:161], v[66:67], 0, s[10:11]
	global_load_lds_dwordx4 v[160:161], off
	v_mfma_f32_32x32x16_bf16 v[32:47], v[180:183], v[222:225], v[32:47]
	v_mfma_f32_32x32x16_bf16 v[16:31], v[184:187], v[218:221], v[16:31]
	s_add_u32 m0, s26, 0xa000
	v_lshl_add_u64 v[162:163], v[64:65], 0, s[10:11]
	global_load_lds_dwordx4 v[162:163], off
	v_mfma_f32_32x32x16_bf16 v[0:15], v[184:187], v[222:225], v[0:15]
	ds_read_b128 v[180:183], v79 offset:49152
	ds_read_b128 v[184:187], v79 offset:53248
	ds_read_b128 v[218:221], v83 offset:49152
	ds_read_b128 v[222:225], v83 offset:53248
	s_waitcnt lgkmcnt(4)
	v_mfma_f32_32x32x16_bf16 v[48:63], v[164:167], v[172:175], v[48:63]
	v_mfma_f32_32x32x16_bf16 v[32:47], v[164:167], v[176:179], v[32:47]
	v_mfma_f32_32x32x16_bf16 v[16:31], v[168:171], v[172:175], v[16:31]
	v_mfma_f32_32x32x16_bf16 v[0:15], v[168:171], v[176:179], v[0:15]
	s_waitcnt vmcnt(6) lgkmcnt(0)
	s_barrier
;     ...
;   if (PART != 2) {
;     GEMM_ISSUE(0, 0);
;     if (nk > 1) GEMM_ISSUE(1, 1);
;   }
;   if (PART == 1) return;
;   int st = 0;
;   for (int kt = 0; kt < nk; ++kt) {
;     if (kt + 1 < nk) asm volatile("s_waitcnt vmcnt(6)" ::: "memory");
;     else asm volatile("s_waitcnt vmcnt(0)" ::: "memory");
;     __builtin_amdgcn_s_barrier();
;     asm volatile("" ::: "memory");
;     if (kt + 2 < nk) { const int st2 = (st >= 1) ? st - 1 : 2; GEMM_ISSUE(kt + 2, st2); }
;     const char* la = lds + st * STAGE_B;
;     const char* lb = la + 32768;
;     const unsigned sa_u = (unsigned)(size_t)la + arow_u, sb_u = (unsigned)(size_t)lb + brow_u;
;     const unsigned a0 = sa_u + co0, a1 = sa_u + co1, a2 = sa_u + co2, a3 = sa_u + co3;
;     const unsigned b0 = sb_u + co0, b1 = sb_u + co1, b2 = sb_u + co2, b3 = sb_u + co3;
;     {
;       bf16x8 p0, p1, q0, q1, u0, u1, w0, w1;
;       asm volatile(
;         "ds_read_b128 %4, %12\n\tds_read_b128 %5, %12 offset:4096\n\tds_read_b128 %6, %16\n\tds_read_b128 %7, %16 offset:4096\n\t"
;         "ds_read_b128 %8, %13\n\tds_read_b128 %9, %13 offset:4096\n\tds_read_b128 %10, %17\n\tds_read_b128 %11, %17 offset:4096\n\t"
;         "s_waitcnt lgkmcnt(4)\n\t"
;         "v_mfma_f32_32x32x16_bf16 %0, %4, %6, %0\n\tv_mfma_f32_32x32x16_bf16 %1, %4, %7, %1\n\tv_mfma_f32_32x32x16_bf16 %2, %5, %6, %2\n\tv_mfma_f32_32x32x16_bf16 %3, %5, %7, %3\n\t"
;         "ds_read_b128 %4, %14\n\tds_read_b128 %5, %14 offset:4096\n\tds_read_b128 %6, %18\n\tds_read_b128 %7, %18 offset:4096\n\t"
;         "s_waitcnt lgkmcnt(4)\n\t"
;         "v_mfma_f32_32x32x16_bf16 %0, %8, %10, %0\n\tv_mfma_f32_32x32x16_bf16 %1, %8, %11, %1\n\tv_mfma_f32_32x32x16_bf16 %2, %9, %10, %2\n\tv_mfma_f32_32x32x16_bf16 %3, %9, %11, %3\n\t"
;         "ds_read_b128 %8, %15\n\tds_read_b128 %9, %15 offset:4096\n\tds_read_b128 %10, %19\n\tds_read_b128 %11, %19 offset:4096\n\t"
;         "s_waitcnt lgkmcnt(4)\n\t"
;         "v_mfma_f32_32x32x16_bf16 %0, %4, %6, %0\n\tv_mfma_f32_32x32x16_bf16 %1, %4, %7, %1\n\tv_mfma_f32_32x32x16_bf16 %2, %5, %6, %2\n\tv_mfma_f32_32x32x16_bf16 %3, %5, %7, %3\n\t"
;         "s_waitcnt lgkmcnt(0)\n\t"
;         "v_mfma_f32_32x32x16_bf16 %0, %8, %10, %0\n\tv_mfma_f32_32x32x16_bf16 %1, %8, %11, %1\n\tv_mfma_f32_32x32x16_bf16 %2, %9, %10, %2\n\tv_mfma_f32_32x32x16_bf16 %3, %9, %11, %3"
	ds_read_b128 v[164:167], v84
	ds_read_b128 v[168:171], v84 offset:4096
	ds_read_b128 v[172:175], v156
	ds_read_b128 v[176:179], v156 offset:4096
	v_mfma_f32_32x32x16_bf16 v[48:63], v[180:183], v[218:221], v[48:63]
	s_mov_b32 s10, 0xa5c3400
	s_add_u32 m0, s26, 0xc000
	v_lshl_add_u64 v[160:161], v[74:75], 0, s[10:11]
	global_load_lds_dwordx4 v[160:161], off
	v_mfma_f32_32x32x16_bf16 v[32:47], v[180:183], v[222:225], v[32:47]
	v_mfma_f32_32x32x16_bf16 v[16:31], v[184:187], v[218:221], v[16:31]
	s_add_u32 m0, s26, 0xe000
	v_lshl_add_u64 v[162:163], v[72:73], 0, s[10:11]
	global_load_lds_dwordx4 v[162:163], off
	v_mfma_f32_32x32x16_bf16 v[0:15], v[184:187], v[222:225], v[0:15]
	ds_read_b128 v[180:183], v85
	ds_read_b128 v[184:187], v85 offset:4096
	ds_read_b128 v[218:221], v157
	ds_read_b128 v[222:225], v157 offset:4096
	s_waitcnt lgkmcnt(4)
	v_mfma_f32_32x32x16_bf16 v[48:63], v[164:167], v[172:175], v[48:63]
	s_add_u32 m0, s26, 0x10000
	v_lshl_add_u64 v[160:161], v[70:71], 0, s[10:11]
	global_load_lds_dwordx4 v[160:161], off
	v_mfma_f32_32x32x16_bf16 v[32:47], v[164:167], v[176:179], v[32:47]
	v_mfma_f32_32x32x16_bf16 v[16:31], v[168:171], v[172:175], v[16:31]
	s_add_u32 m0, s26, 0x12000
	v_lshl_add_u64 v[162:163], v[68:69], 0, s[10:11]
	global_load_lds_dwordx4 v[162:163], off
	v_mfma_f32_32x32x16_bf16 v[0:15], v[168:171], v[176:179], v[0:15]
	ds_read_b128 v[164:167], v86
	ds_read_b128 v[168:171], v86 offset:4096
	ds_read_b128 v[172:175], v158
	ds_read_b128 v[176:179], v158 offset:4096
	s_waitcnt lgkmcnt(4)
	v_mfma_f32_32x32x16_bf16 v[48:63], v[180:183], v[218:221], v[48:63]
	s_mov_b32 s10, 0xb01400
	s_add_u32 m0, s26, 0x14000
	v_lshl_add_u64 v[160:161], v[66:67], 0, s[10:11]
	global_load_lds_dwordx4 v[160:161], off
	v_mfma_f32_32x32x16_bf16 v[32:47], v[180:183], v[222:225], v[32:47]
	v_mfma_f32_32x32x16_bf16 v[16:31], v[184:187], v[218:221], v[16:31]
	s_add_u32 m0, s26, 0x16000
	v_lshl_add_u64 v[162:163], v[64:65], 0, s[10:11]
	global_load_lds_dwordx4 v[162:163], off
	v_mfma_f32_32x32x16_bf16 v[0:15], v[184:187], v[222:225], v[0:15]
	ds_read_b128 v[180:183], v87
	ds_read_b128 v[184:187], v87 offset:4096
	ds_read_b128 v[218:221], v159
	ds_read_b128 v[222:225], v159 offset:4096
	s_waitcnt lgkmcnt(4)
	v_mfma_f32_32x32x16_bf16 v[48:63], v[164:167], v[172:175], v[48:63]
	v_mfma_f32_32x32x16_bf16 v[32:47], v[164:167], v[176:179], v[32:47]
	v_mfma_f32_32x32x16_bf16 v[16:31], v[168:171], v[172:175], v[16:31]
	v_mfma_f32_32x32x16_bf16 v[0:15], v[168:171], v[176:179], v[0:15]
	s_waitcnt vmcnt(6) lgkmcnt(0)
	s_barrier
	ds_read_b128 v[164:167], v76
	ds_read_b128 v[168:171], v76 offset:4096
	ds_read_b128 v[172:175], v80
	ds_read_b128 v[176:179], v80 offset:4096
	v_mfma_f32_32x32x16_bf16 v[48:63], v[180:183], v[218:221], v[48:63]
	s_mov_b32 s10, 0xa5c3480
	s_add_u32 m0, s26, 0x18000
	v_lshl_add_u64 v[160:161], v[74:75], 0, s[10:11]
	global_load_lds_dwordx4 v[160:161], off
	v_mfma_f32_32x32x16_bf16 v[32:47], v[180:183], v[222:225], v[32:47]
	v_mfma_f32_32x32x16_bf16 v[16:31], v[184:187], v[218:221], v[16:31]
	s_add_u32 m0, s26, 0x1a000
	v_lshl_add_u64 v[162:163], v[72:73], 0, s[10:11]
	global_load_lds_dwordx4 v[162:163], off
	v_mfma_f32_32x32x16_bf16 v[0:15], v[184:187], v[222:225], v[0:15]
	ds_read_b128 v[180:183], v77
	ds_read_b128 v[184:187], v77 offset:4096
	ds_read_b128 v[218:221], v81
	ds_read_b128 v[222:225], v81 offset:4096
	s_waitcnt lgkmcnt(4)
	v_mfma_f32_32x32x16_bf16 v[48:63], v[164:167], v[172:175], v[48:63]
	s_add_u32 m0, s26, 0x1c000
	v_lshl_add_u64 v[160:161], v[70:71], 0, s[10:11]
	global_load_lds_dwordx4 v[160:161], off
	v_mfma_f32_32x32x16_bf16 v[32:47], v[164:167], v[176:179], v[32:47]
	v_mfma_f32_32x32x16_bf16 v[16:31], v[168:171], v[172:175], v[16:31]
	s_add_u32 m0, s26, 0x1e000
	v_lshl_add_u64 v[162:163], v[68:69], 0, s[10:11]
	global_load_lds_dwordx4 v[162:163], off
	v_mfma_f32_32x32x16_bf16 v[0:15], v[168:171], v[176:179], v[0:15]
	ds_read_b128 v[164:167], v78
	ds_read_b128 v[168:171], v78 offset:4096
	ds_read_b128 v[172:175], v82
	ds_read_b128 v[176:179], v82 offset:4096
	s_waitcnt lgkmcnt(4)
	v_mfma_f32_32x32x16_bf16 v[48:63], v[180:183], v[218:221], v[48:63]
	s_mov_b32 s10, 0xb01480
	s_add_u32 m0, s26, 0x20000
	v_lshl_add_u64 v[160:161], v[66:67], 0, s[10:11]
	global_load_lds_dwordx4 v[160:161], off
	v_mfma_f32_32x32x16_bf16 v[32:47], v[180:183], v[222:225], v[32:47]
	v_mfma_f32_32x32x16_bf16 v[16:31], v[184:187], v[218:221], v[16:31]
	s_add_u32 m0, s26, 0x22000
	v_lshl_add_u64 v[162:163], v[64:65], 0, s[10:11]
	global_load_lds_dwordx4 v[162:163], off
	v_mfma_f32_32x32x16_bf16 v[0:15], v[184:187], v[222:225], v[0:15]
	ds_read_b128 v[180:183], v79
	ds_read_b128 v[184:187], v79 offset:4096
	ds_read_b128 v[218:221], v83
	ds_read_b128 v[222:225], v83 offset:4096
	s_waitcnt lgkmcnt(4)
	v_mfma_f32_32x32x16_bf16 v[48:63], v[164:167], v[172:175], v[48:63]
	v_mfma_f32_32x32x16_bf16 v[32:47], v[164:167], v[176:179], v[32:47]
	v_mfma_f32_32x32x16_bf16 v[16:31], v[168:171], v[172:175], v[16:31]
	v_mfma_f32_32x32x16_bf16 v[0:15], v[168:171], v[176:179], v[0:15]
	s_waitcnt vmcnt(6) lgkmcnt(0)
	s_barrier
;     ...
;   if (PART != 2) {
;     GEMM_ISSUE(0, 0);
;     if (nk > 1) GEMM_ISSUE(1, 1);
;   }
;   if (PART == 1) return;
;   int st = 0;
;   for (int kt = 0; kt < nk; ++kt) {
;     if (kt + 1 < nk) asm volatile("s_waitcnt vmcnt(6)" ::: "memory");
;     else asm volatile("s_waitcnt vmcnt(0)" ::: "memory");
;     __builtin_amdgcn_s_barrier();
;     asm volatile("" ::: "memory");
;     if (kt + 2 < nk) { const int st2 = (st >= 1) ? st - 1 : 2; GEMM_ISSUE(kt + 2, st2); }
;     const char* la = lds + st * STAGE_B;
;     const char* lb = la + 32768;
;     const unsigned sa_u = (unsigned)(size_t)la + arow_u, sb_u = (unsigned)(size_t)lb + brow_u;
;     const unsigned a0 = sa_u + co0, a1 = sa_u + co1, a2 = sa_u + co2, a3 = sa_u + co3;
;     const unsigned b0 = sb_u + co0, b1 = sb_u + co1, b2 = sb_u + co2, b3 = sb_u + co3;
;     {
;       bf16x8 p0, p1, q0, q1, u0, u1, w0, w1;
;       asm volatile(
;         "ds_read_b128 %4, %12\n\tds_read_b128 %5, %12 offset:4096\n\tds_read_b128 %6, %16\n\tds_read_b128 %7, %16 offset:4096\n\t"
;         "ds_read_b128 %8, %13\n\tds_read_b128 %9, %13 offset:4096\n\tds_read_b128 %10, %17\n\tds_read_b128 %11, %17 offset:4096\n\t"
;         "s_waitcnt lgkmcnt(4)\n\t"
;         "v_mfma_f32_32x32x16_bf16 %0, %4, %6, %0\n\tv_mfma_f32_32x32x16_bf16 %1, %4, %7, %1\n\tv_mfma_f32_32x32x16_bf16 %2, %5, %6, %2\n\tv_mfma_f32_32x32x16_bf16 %3, %5, %7, %3\n\t"
;         "ds_read_b128 %4, %14\n\tds_read_b128 %5, %14 offset:4096\n\tds_read_b128 %6, %18\n\tds_read_b128 %7, %18 offset:4096\n\t"
;         "s_waitcnt lgkmcnt(4)\n\t"
;         "v_mfma_f32_32x32x16_bf16 %0, %8, %10, %0\n\tv_mfma_f32_32x32x16_bf16 %1, %8, %11, %1\n\tv_mfma_f32_32x32x16_bf16 %2, %9, %10, %2\n\tv_mfma_f32_32x32x16_bf16 %3, %9, %11, %3\n\t"
;         "ds_read_b128 %8, %15\n\tds_read_b128 %9, %15 offset:4096\n\tds_read_b128 %10, %19\n\tds_read_b128 %11, %19 offset:4096\n\t"
;         "s_waitcnt lgkmcnt(4)\n\t"
;         "v_mfma_f32_32x32x16_bf16 %0, %4, %6, %0\n\tv_mfma_f32_32x32x16_bf16 %1, %4, %7, %1\n\tv_mfma_f32_32x32x16_bf16 %2, %5, %6, %2\n\tv_mfma_f32_32x32x16_bf16 %3, %5, %7, %3\n\t"
;         "s_waitcnt lgkmcnt(0)\n\t"
;         "v_mfma_f32_32x32x16_bf16 %0, %8, %10, %0\n\tv_mfma_f32_32x32x16_bf16 %1, %8, %11, %1\n\tv_mfma_f32_32x32x16_bf16 %2, %9, %10, %2\n\tv_mfma_f32_32x32x16_bf16 %3, %9, %11, %3"
	ds_read_b128 v[164:167], v76 offset:49152
	ds_read_b128 v[168:171], v76 offset:53248
	ds_read_b128 v[172:175], v80 offset:49152
	ds_read_b128 v[176:179], v80 offset:53248
	v_mfma_f32_32x32x16_bf16 v[48:63], v[180:183], v[218:221], v[48:63]
	s_mov_b32 s10, 0xa5c3500
	s_mov_b32 m0, s26
	v_lshl_add_u64 v[160:161], v[74:75], 0, s[10:11]
	global_load_lds_dwordx4 v[160:161], off
	v_mfma_f32_32x32x16_bf16 v[32:47], v[180:183], v[222:225], v[32:47]
	v_mfma_f32_32x32x16_bf16 v[16:31], v[184:187], v[218:221], v[16:31]
	s_add_u32 m0, s26, 0x2000
	v_lshl_add_u64 v[162:163], v[72:73], 0, s[10:11]
	global_load_lds_dwordx4 v[162:163], off
	v_mfma_f32_32x32x16_bf16 v[0:15], v[184:187], v[222:225], v[0:15]
	ds_read_b128 v[180:183], v77 offset:49152
	ds_read_b128 v[184:187], v77 offset:53248
	ds_read_b128 v[218:221], v81 offset:49152
	ds_read_b128 v[222:225], v81 offset:53248
	s_waitcnt lgkmcnt(4)
	v_mfma_f32_32x32x16_bf16 v[48:63], v[164:167], v[172:175], v[48:63]
	s_add_u32 m0, s26, 0x4000
	v_lshl_add_u64 v[160:161], v[70:71], 0, s[10:11]
	global_load_lds_dwordx4 v[160:161], off
	v_mfma_f32_32x32x16_bf16 v[32:47], v[164:167], v[176:179], v[32:47]
	v_mfma_f32_32x32x16_bf16 v[16:31], v[168:171], v[172:175], v[16:31]
	s_add_u32 m0, s26, 0x6000
	v_lshl_add_u64 v[162:163], v[68:69], 0, s[10:11]
	global_load_lds_dwordx4 v[162:163], off
	v_mfma_f32_32x32x16_bf16 v[0:15], v[168:171], v[176:179], v[0:15]
	ds_read_b128 v[164:167], v78 offset:49152
	ds_read_b128 v[168:171], v78 offset:53248
	ds_read_b128 v[172:175], v82 offset:49152
	ds_read_b128 v[176:179], v82 offset:53248
	s_waitcnt lgkmcnt(4)
	v_mfma_f32_32x32x16_bf16 v[48:63], v[180:183], v[218:221], v[48:63]
	s_mov_b32 s10, 0xb01500
	s_add_u32 m0, s26, 0x8000
	v_lshl_add_u64 v[160:161], v[66:67], 0, s[10:11]
	global_load_lds_dwordx4 v[160:161], off
	v_mfma_f32_32x32x16_bf16 v[32:47], v[180:183], v[222:225], v[32:47]
	v_mfma_f32_32x32x16_bf16 v[16:31], v[184:187], v[218:221], v[16:31]
	s_add_u32 m0, s26, 0xa000
	v_lshl_add_u64 v[162:163], v[64:65], 0, s[10:11]
	global_load_lds_dwordx4 v[162:163], off
	v_mfma_f32_32x32x16_bf16 v[0:15], v[184:187], v[222:225], v[0:15]
	ds_read_b128 v[180:183], v79 offset:49152
	ds_read_b128 v[184:187], v79 offset:53248
	ds_read_b128 v[218:221], v83 offset:49152
	ds_read_b128 v[222:225], v83 offset:53248
	s_waitcnt lgkmcnt(4)
	v_mfma_f32_32x32x16_bf16 v[48:63], v[164:167], v[172:175], v[48:63]
	v_mfma_f32_32x32x16_bf16 v[32:47], v[164:167], v[176:179], v[32:47]
	v_mfma_f32_32x32x16_bf16 v[16:31], v[168:171], v[172:175], v[16:31]
	v_mfma_f32_32x32x16_bf16 v[0:15], v[168:171], v[176:179], v[0:15]
	s_waitcnt vmcnt(6) lgkmcnt(0)
	s_barrier
	ds_read_b128 v[164:167], v84
	ds_read_b128 v[168:171], v84 offset:4096
	ds_read_b128 v[172:175], v156
	ds_read_b128 v[176:179], v156 offset:4096
	v_mfma_f32_32x32x16_bf16 v[48:63], v[180:183], v[218:221], v[48:63]
	s_mov_b32 s10, 0xa5c3580
	s_add_u32 m0, s26, 0xc000
	v_lshl_add_u64 v[160:161], v[74:75], 0, s[10:11]
	global_load_lds_dwordx4 v[160:161], off
	v_mfma_f32_32x32x16_bf16 v[32:47], v[180:183], v[222:225], v[32:47]
	v_mfma_f32_32x32x16_bf16 v[16:31], v[184:187], v[218:221], v[16:31]
	s_add_u32 m0, s26, 0xe000
	v_lshl_add_u64 v[162:163], v[72:73], 0, s[10:11]
	global_load_lds_dwordx4 v[162:163], off
	v_mfma_f32_32x32x16_bf16 v[0:15], v[184:187], v[222:225], v[0:15]
	ds_read_b128 v[180:183], v85
	ds_read_b128 v[184:187], v85 offset:4096
	ds_read_b128 v[218:221], v157
	ds_read_b128 v[222:225], v157 offset:4096
	s_waitcnt lgkmcnt(4)
	v_mfma_f32_32x32x16_bf16 v[48:63], v[164:167], v[172:175], v[48:63]
	s_add_u32 m0, s26, 0x10000
	v_lshl_add_u64 v[160:161], v[70:71], 0, s[10:11]
	global_load_lds_dwordx4 v[160:161], off
	v_mfma_f32_32x32x16_bf16 v[32:47], v[164:167], v[176:179], v[32:47]
	v_mfma_f32_32x32x16_bf16 v[16:31], v[168:171], v[172:175], v[16:31]
	s_add_u32 m0, s26, 0x12000
	v_lshl_add_u64 v[162:163], v[68:69], 0, s[10:11]
	global_load_lds_dwordx4 v[162:163], off
	v_mfma_f32_32x32x16_bf16 v[0:15], v[168:171], v[176:179], v[0:15]
	ds_read_b128 v[164:167], v86
	ds_read_b128 v[168:171], v86 offset:4096
	ds_read_b128 v[172:175], v158
	ds_read_b128 v[176:179], v158 offset:4096
	s_waitcnt lgkmcnt(4)
	v_mfma_f32_32x32x16_bf16 v[48:63], v[180:183], v[218:221], v[48:63]
	s_mov_b32 s10, 0xb01580
	s_add_u32 m0, s26, 0x14000
	v_lshl_add_u64 v[160:161], v[66:67], 0, s[10:11]
	global_load_lds_dwordx4 v[160:161], off
	v_mfma_f32_32x32x16_bf16 v[32:47], v[180:183], v[222:225], v[32:47]
	v_mfma_f32_32x32x16_bf16 v[16:31], v[184:187], v[218:221], v[16:31]
	s_add_u32 m0, s26, 0x16000
	v_lshl_add_u64 v[162:163], v[64:65], 0, s[10:11]
	global_load_lds_dwordx4 v[162:163], off
	v_mfma_f32_32x32x16_bf16 v[0:15], v[184:187], v[222:225], v[0:15]
	ds_read_b128 v[180:183], v87
	ds_read_b128 v[184:187], v87 offset:4096
	ds_read_b128 v[218:221], v159
	ds_read_b128 v[222:225], v159 offset:4096
	s_waitcnt lgkmcnt(4)
	v_mfma_f32_32x32x16_bf16 v[48:63], v[164:167], v[172:175], v[48:63]
	v_mfma_f32_32x32x16_bf16 v[32:47], v[164:167], v[176:179], v[32:47]
	v_mfma_f32_32x32x16_bf16 v[16:31], v[168:171], v[172:175], v[16:31]
	v_mfma_f32_32x32x16_bf16 v[0:15], v[168:171], v[176:179], v[0:15]
	s_waitcnt vmcnt(6) lgkmcnt(0)
	s_barrier
;     ...
;   for (int kt = 0; kt < nk; ++kt) {
;     if (kt + 1 < nk) asm volatile("s_waitcnt vmcnt(6)" ::: "memory");
;     else asm volatile("s_waitcnt vmcnt(0)" ::: "memory");
;     __builtin_amdgcn_s_barrier();
;     asm volatile("" ::: "memory");
;     if (kt + 2 < nk) { const int st2 = (st >= 1) ? st - 1 : 2; GEMM_ISSUE(kt + 2, st2); }
;     const char* la = lds + st * STAGE_B;
;     const char* lb = la + 32768;
;     const unsigned sa_u = (unsigned)(size_t)la + arow_u, sb_u = (unsigned)(size_t)lb + brow_u;
;     const unsigned a0 = sa_u + co0, a1 = sa_u + co1, a2 = sa_u + co2, a3 = sa_u + co3;
;     const unsigned b0 = sb_u + co0, b1 = sb_u + co1, b2 = sb_u + co2, b3 = sb_u + co3;
;     {
;       bf16x8 p0, p1, q0, q1, u0, u1, w0, w1;
;       asm volatile(
;         "ds_read_b128 %4, %12\n\tds_read_b128 %5, %12 offset:4096\n\tds_read_b128 %6, %16\n\tds_read_b128 %7, %16 offset:4096\n\t"
;         "ds_read_b128 %8, %13\n\tds_read_b128 %9, %13 offset:4096\n\tds_read_b128 %10, %17\n\tds_read_b128 %11, %17 offset:4096\n\t"
;         "s_waitcnt lgkmcnt(4)\n\t"
;         "v_mfma_f32_32x32x16_bf16 %0, %4, %6, %0\n\tv_mfma_f32_32x32x16_bf16 %1, %4, %7, %1\n\tv_mfma_f32_32x32x16_bf16 %2, %5, %6, %2\n\tv_mfma_f32_32x32x16_bf16 %3, %5, %7, %3\n\t"
;         "ds_read_b128 %4, %14\n\tds_read_b128 %5, %14 offset:4096\n\tds_read_b128 %6, %18\n\tds_read_b128 %7, %18 offset:4096\n\t"
;         "s_waitcnt lgkmcnt(4)\n\t"
;         "v_mfma_f32_32x32x16_bf16 %0, %8, %10, %0\n\tv_mfma_f32_32x32x16_bf16 %1, %8, %11, %1\n\tv_mfma_f32_32x32x16_bf16 %2, %9, %10, %2\n\tv_mfma_f32_32x32x16_bf16 %3, %9, %11, %3\n\t"
;         "ds_read_b128 %8, %15\n\tds_read_b128 %9, %15 offset:4096\n\tds_read_b128 %10, %19\n\tds_read_b128 %11, %19 offset:4096\n\t"
;         "s_waitcnt lgkmcnt(4)\n\t"
;         "v_mfma_f32_32x32x16_bf16 %0, %4, %6, %0\n\tv_mfma_f32_32x32x16_bf16 %1, %4, %7, %1\n\tv_mfma_f32_32x32x16_bf16 %2, %5, %6, %2\n\tv_mfma_f32_32x32x16_bf16 %3, %5, %7, %3\n\t"
;         "s_waitcnt lgkmcnt(0)\n\t"
;         "v_mfma_f32_32x32x16_bf16 %0, %8, %10, %0\n\tv_mfma_f32_32x32x16_bf16 %1, %8, %11, %1\n\tv_mfma_f32_32x32x16_bf16 %2, %9, %10, %2\n\tv_mfma_f32_32x32x16_bf16 %3, %9, %11, %3"
;         : "+v"(acc[0][0]), "+v"(acc[0][1]), "+v"(acc[1][0]), "+v"(acc[1][1]),
;           "=&v"(p0), "=&v"(p1), "=&v"(q0), "=&v"(q1), "=&v"(u0), "=&v"(u1), "=&v"(w0), "=&v"(w1)
	ds_read_b128 v[164:167], v76
	ds_read_b128 v[168:171], v76 offset:4096
	ds_read_b128 v[172:175], v80
	ds_read_b128 v[176:179], v80 offset:4096
	v_mfma_f32_32x32x16_bf16 v[48:63], v[180:183], v[218:221], v[48:63]
	v_mfma_f32_32x32x16_bf16 v[32:47], v[180:183], v[222:225], v[32:47]
	v_mfma_f32_32x32x16_bf16 v[16:31], v[184:187], v[218:221], v[16:31]
	v_mfma_f32_32x32x16_bf16 v[0:15], v[184:187], v[222:225], v[0:15]
	ds_read_b128 v[180:183], v77
	ds_read_b128 v[184:187], v77 offset:4096
	ds_read_b128 v[218:221], v81
	ds_read_b128 v[222:225], v81 offset:4096
	s_waitcnt lgkmcnt(4)
	v_mfma_f32_32x32x16_bf16 v[48:63], v[164:167], v[172:175], v[48:63]
	v_mfma_f32_32x32x16_bf16 v[32:47], v[164:167], v[176:179], v[32:47]
	v_mfma_f32_32x32x16_bf16 v[16:31], v[168:171], v[172:175], v[16:31]
	v_mfma_f32_32x32x16_bf16 v[0:15], v[168:171], v[176:179], v[0:15]
	ds_read_b128 v[164:167], v78
	ds_read_b128 v[168:171], v78 offset:4096
	ds_read_b128 v[172:175], v82
	ds_read_b128 v[176:179], v82 offset:4096
	s_waitcnt lgkmcnt(4)
	v_mfma_f32_32x32x16_bf16 v[48:63], v[180:183], v[218:221], v[48:63]
	v_mfma_f32_32x32x16_bf16 v[32:47], v[180:183], v[222:225], v[32:47]
	v_mfma_f32_32x32x16_bf16 v[16:31], v[184:187], v[218:221], v[16:31]
	v_mfma_f32_32x32x16_bf16 v[0:15], v[184:187], v[222:225], v[0:15]
	ds_read_b128 v[180:183], v79
	ds_read_b128 v[184:187], v79 offset:4096
	ds_read_b128 v[218:221], v83
	ds_read_b128 v[222:225], v83 offset:4096
	s_waitcnt lgkmcnt(4)
	v_mfma_f32_32x32x16_bf16 v[48:63], v[164:167], v[172:175], v[48:63]
	v_mfma_f32_32x32x16_bf16 v[32:47], v[164:167], v[176:179], v[32:47]
	v_mfma_f32_32x32x16_bf16 v[16:31], v[168:171], v[172:175], v[16:31]
	v_mfma_f32_32x32x16_bf16 v[0:15], v[168:171], v[176:179], v[0:15]
	s_waitcnt vmcnt(0) lgkmcnt(0)
	s_barrier
	ds_read_b128 v[164:167], v76 offset:49152
	ds_read_b128 v[168:171], v76 offset:53248
	ds_read_b128 v[172:175], v80 offset:49152
	ds_read_b128 v[176:179], v80 offset:53248
	v_mfma_f32_32x32x16_bf16 v[48:63], v[180:183], v[218:221], v[48:63]
	v_mfma_f32_32x32x16_bf16 v[32:47], v[180:183], v[222:225], v[32:47]
	v_mfma_f32_32x32x16_bf16 v[16:31], v[184:187], v[218:221], v[16:31]
	v_mfma_f32_32x32x16_bf16 v[0:15], v[184:187], v[222:225], v[0:15]
	ds_read_b128 v[180:183], v77 offset:49152
	ds_read_b128 v[184:187], v77 offset:53248
	ds_read_b128 v[218:221], v81 offset:49152
	ds_read_b128 v[222:225], v81 offset:53248
	s_waitcnt lgkmcnt(4)
	v_mfma_f32_32x32x16_bf16 v[48:63], v[164:167], v[172:175], v[48:63]
	v_mfma_f32_32x32x16_bf16 v[32:47], v[164:167], v[176:179], v[32:47]
	v_mfma_f32_32x32x16_bf16 v[16:31], v[168:171], v[172:175], v[16:31]
	v_mfma_f32_32x32x16_bf16 v[0:15], v[168:171], v[176:179], v[0:15]
	ds_read_b128 v[164:167], v78 offset:49152
	ds_read_b128 v[168:171], v78 offset:53248
	ds_read_b128 v[172:175], v82 offset:49152
	ds_read_b128 v[176:179], v82 offset:53248
	s_waitcnt lgkmcnt(4)
	v_mfma_f32_32x32x16_bf16 v[48:63], v[180:183], v[218:221], v[48:63]
	v_mfma_f32_32x32x16_bf16 v[32:47], v[180:183], v[222:225], v[32:47]
	v_mfma_f32_32x32x16_bf16 v[16:31], v[184:187], v[218:221], v[16:31]
	v_mfma_f32_32x32x16_bf16 v[0:15], v[184:187], v[222:225], v[0:15]
	ds_read_b128 v[180:183], v79 offset:49152
	ds_read_b128 v[184:187], v79 offset:53248
	ds_read_b128 v[218:221], v83 offset:49152
	ds_read_b128 v[222:225], v83 offset:53248
	s_waitcnt lgkmcnt(4)
	v_mfma_f32_32x32x16_bf16 v[48:63], v[164:167], v[172:175], v[48:63]
	v_mfma_f32_32x32x16_bf16 v[32:47], v[164:167], v[176:179], v[32:47]
	v_mfma_f32_32x32x16_bf16 v[16:31], v[168:171], v[172:175], v[16:31]
	v_mfma_f32_32x32x16_bf16 v[0:15], v[168:171], v[176:179], v[0:15]
	s_waitcnt lgkmcnt(0)
	v_mfma_f32_32x32x16_bf16 v[48:63], v[180:183], v[218:221], v[48:63]
	v_mfma_f32_32x32x16_bf16 v[32:47], v[180:183], v[222:225], v[32:47]
	v_mfma_f32_32x32x16_bf16 v[16:31], v[184:187], v[218:221], v[16:31]
	v_mfma_f32_32x32x16_bf16 v[0:15], v[184:187], v[222:225], v[0:15]
	s_nop 15
	s_nop 15
	s_nop 7
	s_barrier
	s_load_dword s10, s[0:1], 0x10
	s_waitcnt lgkmcnt(0)
	s_lshr_b32 s10, s10, 16
	s_cmp_lg_u32 s10, 0
	s_cselect_b64 s[10:11], -1, 0
	s_cmp_lg_u64 s[10:11], 0
	s_addc_u32 s26, s33, 0

;   const int tid = TIDX, lane = tid & 63, wid = tid >> 6, wr = wid >> 1, wc = wid & 1, r = lane & 31, h = lane >> 5;
;   const int ch = (tid & 7) ^ ((tid >> 4) & 7);
;   unsigned avo[4], bvo[2];
; #pragma unroll
;   for (int i = 0; i < 4; ++i) avo[i] = (unsigned)(((tid >> 3) + 64 * i) * lda * 2 + ch * 16);
; #pragma unroll
;   for (int i = 0; i < 2; ++i) bvo[i] = (unsigned)(((tid >> 3) + 64 * i) * ldb * 2 + ch * 16);
;   const char* Ab = (const char*)A; const char* Bb = (const char*)Bt;
;   char* lw = lds + tid * 16;
;   const int nk = K >> 6;
;   const unsigned swz = (unsigned)((r >> 1) & 7);
;   const unsigned arow_u = (unsigned)((wr * 64 + r) * 128), brow_u = (unsigned)((wc * 64 + r) * 128);
;   const unsigned co0 = ((0u + h) ^ swz) << 4, co1 = ((2u + h) ^ swz) << 4, co2 = ((4u + h) ^ swz) << 4, co3 = ((6u + h) ^ swz) << 4;
;     ...
;   if (PART != 2) {
;     GEMM_ISSUE(0, 0);
;     if (nk > 1) GEMM_ISSUE(1, 1);
;   }
;   if (PART == 1) return;
;   int st = 0;
;   for (int kt = 0; kt < nk; ++kt) {
;     if (kt + 1 < nk) asm volatile("s_waitcnt vmcnt(6)" ::: "memory");
;     else asm volatile("s_waitcnt vmcnt(0)" ::: "memory");
;     __builtin_amdgcn_s_barrier();
;     asm volatile("" ::: "memory");
;     if (kt + 2 < nk) { const int st2 = (st >= 1) ? st - 1 : 2; GEMM_ISSUE(kt + 2, st2); }
;     const char* la = lds + st * STAGE_B;
;     const char* lb = la + 32768;
;     const unsigned sa_u = (unsigned)(size_t)la + arow_u, sb_u = (unsigned)(size_t)lb + brow_u;
;     const unsigned a0 = sa_u + co0, a1 = sa_u + co1, a2 = sa_u + co2, a3 = sa_u + co3;
;     const unsigned b0 = sb_u + co0, b1 = sb_u + co1, b2 = sb_u + co2, b3 = sb_u + co3;
;     {
;       bf16x8 p0, p1, q0, q1, u0, u1, w0, w1;
;       asm volatile(
;         "ds_read_b128 %4, %12\n\tds_read_b128 %5, %12 offset:4096\n\tds_read_b128 %6, %16\n\tds_read_b128 %7, %16 offset:4096\n\t"
;         "ds_read_b128 %8, %13\n\tds_read_b128 %9, %13 offset:4096\n\tds_read_b128 %10, %17\n\tds_read_b128 %11, %17 offset:4096\n\t"
;         "s_waitcnt lgkmcnt(4)\n\t"
;         "v_mfma_f32_32x32x16_bf16 %0, %4, %6, %0\n\tv_mfma_f32_32x32x16_bf16 %1, %4, %7, %1\n\tv_mfma_f32_32x32x16_bf16 %2, %5, %6, %2\n\tv_mfma_f32_32x32x16_bf16 %3, %5, %7, %3\n\t"
;         "ds_read_b128 %4, %14\n\tds_read_b128 %5, %14 offset:4096\n\tds_read_b128 %6, %18\n\tds_read_b128 %7, %18 offset:4096\n\t"
;         "s_waitcnt lgkmcnt(4)\n\t"
.LBB0_758:
	v_mov_b32_e32 v1, v129
	s_mov_b32 s68, s8
	v_lshlrev_b32_e32 v5, 4, v1
	v_lshrrev_b32_e32 v3, 5, v1
	v_xor_b32_e32 v0, v5, v1
	v_lshlrev_b32_e32 v2, 8, v1
	v_and_b32_e32 v6, 31, v1
	v_bfe_u32 v7, v1, 5, 1
	v_add_u32_e32 v116, 0, v5
	v_lshrrev_b32_e32 v5, 1, v1
	v_bfe_u32 v8, v1, 1, 3
	v_lshlrev_b32_e32 v1, 7, v1
	s_ashr_i32 s69, s8, 31
	v_and_b32_e32 v118, 0x2f80, v1
	v_bitop3_b32 v1, v3, v8, 1 bitop3:0x6c
	s_lshl_b64 s[14:15], s[68:69], 19
	v_lshlrev_b32_e32 v119, 4, v1
	v_bitop3_b32 v1, v7, v8, 2 bitop3:0x36
	s_add_u32 s26, s88, s14
	v_and_b32_e32 v2, 0xfffff800, v2
	s_movk_i32 s9, 0x70
	v_lshlrev_b32_e32 v120, 4, v1
	v_bitop3_b32 v1, v7, v8, 4 bitop3:0x36
	s_addc_u32 s27, s89, s15
	v_and_or_b32 v130, v0, s9, v2
	s_mov_b32 s9, 0x1ffffc0
	v_lshlrev_b32_e32 v121, 4, v1
	v_bitop3_b32 v1, v7, v8, 6 bitop3:0x36
	v_add_u32_e32 v8, 0x18000, v116
	v_add_u32_e32 v0, 0x20000, v130
	v_and_or_b32 v5, v5, s9, v6
	v_lshlrev_b32_e32 v122, 4, v1
	v_mov_b32_e32 v1, v131
	v_lshl_add_u64 v[64:65], s[26:27], 0, v[130:131]
	v_readfirstlane_b32 s9, v8
	v_add_u32_e32 v8, 0x1a000, v116
	s_waitcnt vmcnt(6)
	s_barrier
	v_lshl_add_u64 v[6:7], v[64:65], 0, s[78:79]
	s_mov_b32 m0, s9
	v_lshl_add_u64 v[66:67], s[26:27], 0, v[0:1]
	v_readfirstlane_b32 s11, v8
	s_mov_b32 s70, s10
	s_ashr_i32 s71, s10, 31
	global_load_lds_dwordx4 v[6:7], off
	v_lshl_add_u64 v[6:7], v[66:67], 0, s[78:79]
	s_mov_b32 m0, s11
	s_lshl_b64 s[14:15], s[70:71], 18
	v_add_u32_e32 v2, 0x40000, v130
	v_add_u32_e32 v4, 0x60000, v130
	v_lshlrev_b32_e32 v117, 7, v5
	v_mov_b32_e32 v3, v131
	v_mov_b32_e32 v5, v131
	global_load_lds_dwordx4 v[6:7], off
	v_add_u32_e32 v6, 0x1c000, v116
	s_add_u32 s30, s4, s14
	v_lshl_add_u64 v[68:69], s[26:27], 0, v[2:3]
	v_readfirstlane_b32 s14, v6
	v_lshl_add_u64 v[70:71], s[26:27], 0, v[4:5]
	v_add_u32_e32 v4, 0x1e000, v116
	s_addc_u32 s31, s22, s15
	v_lshl_add_u64 v[2:3], v[68:69], 0, s[78:79]
	s_mov_b32 m0, s14
	v_readfirstlane_b32 s15, v4
	v_add_u32_e32 v4, 0x20000, v116
	global_load_lds_dwordx4 v[2:3], off
	v_lshl_add_u64 v[2:3], v[70:71], 0, s[78:79]
	s_mov_b32 m0, s15
	v_lshl_add_u64 v[72:73], s[30:31], 0, v[130:131]
	v_readfirstlane_b32 s26, v4
	global_load_lds_dwordx4 v[2:3], off
	v_lshl_add_u64 v[2:3], v[72:73], 0, s[78:79]
	s_mov_b32 m0, s26
	v_lshl_add_u64 v[74:75], s[30:31], 0, v[0:1]
	global_load_lds_dwordx4 v[2:3], off
	v_add_u32_e32 v2, 0x22000, v116
	s_cmp_lg_u32 0, -1
	v_readfirstlane_b32 s27, v2
	v_lshl_add_u64 v[0:1], v[74:75], 0, s[78:79]
	s_mov_b32 m0, s27
	s_cselect_b32 s30, 0, 0
	s_mov_b32 s53, s52
	global_load_lds_dwordx4 v[0:1], off
	v_add_u32_e32 v0, s30, v117
	s_add_i32 s30, s30, 0x8000
	s_mov_b32 s54, s52
	s_mov_b32 s55, s52
	s_mov_b32 s56, s52
	s_mov_b32 s57, s52
	s_mov_b32 s58, s52
	s_mov_b32 s59, s52
	s_mov_b32 s60, s52
	s_mov_b32 s61, s52
	s_mov_b32 s62, s52
	s_mov_b32 s63, s52
	s_mov_b32 s64, s52
	s_mov_b32 s65, s52
	s_mov_b32 s66, s52
	s_mov_b32 s67, s52
	v_mov_b64_e32 v[32:33], s[52:53]
	v_add_u32_e32 v1, s30, v118
	v_mov_b64_e32 v[46:47], s[66:67]
	v_add_u32_e32 v76, v0, v119
	v_add_u32_e32 v77, v0, v120
	v_add_u32_e32 v78, v0, v121
	v_add_u32_e32 v79, v0, v122
	v_add_u32_e32 v80, v119, v1
	v_add_u32_e32 v81, v120, v1
	v_add_u32_e32 v82, v121, v1
	v_add_u32_e32 v83, v122, v1
	v_mov_b64_e32 v[34:35], s[54:55]
	v_mov_b64_e32 v[36:37], s[56:57]
	v_mov_b64_e32 v[38:39], s[58:59]
	v_mov_b64_e32 v[40:41], s[60:61]
	v_mov_b64_e32 v[42:43], s[62:63]
	v_mov_b64_e32 v[44:45], s[64:65]
	v_mov_b64_e32 v[62:63], v[46:47]
	v_mov_b64_e32 v[0:1], v[32:33]
	v_mov_b64_e32 v[16:17], v[32:33]
	v_mov_b64_e32 v[60:61], v[44:45]
	v_mov_b64_e32 v[58:59], v[42:43]
	v_mov_b64_e32 v[56:57], v[40:41]
	v_mov_b64_e32 v[54:55], v[38:39]
	v_mov_b64_e32 v[52:53], v[36:37]
	v_mov_b64_e32 v[50:51], v[34:35]
	v_mov_b64_e32 v[48:49], v[32:33]
	v_mov_b64_e32 v[2:3], v[34:35]
	v_mov_b64_e32 v[4:5], v[36:37]
	v_mov_b64_e32 v[6:7], v[38:39]
	v_mov_b64_e32 v[8:9], v[40:41]
	v_mov_b64_e32 v[10:11], v[42:43]
	v_mov_b64_e32 v[12:13], v[44:45]
	v_mov_b64_e32 v[14:15], v[46:47]
	v_mov_b64_e32 v[18:19], v[34:35]
	v_mov_b64_e32 v[20:21], v[36:37]
	v_mov_b64_e32 v[22:23], v[38:39]
	v_mov_b64_e32 v[24:25], v[40:41]
	v_mov_b64_e32 v[26:27], v[42:43]
	v_mov_b64_e32 v[28:29], v[44:45]
	v_mov_b64_e32 v[30:31], v[46:47]
	v_and_b32_e32 v84, 31, v129
	v_bfe_u32 v85, v129, 5, 1
	v_lshrrev_b32_e32 v86, 6, v129
	v_bfe_u32 v88, v129, 1, 3
	v_lshrrev_b32_e32 v87, 1, v86
	v_and_b32_e32 v86, 1, v86
	v_xor_b32_e32 v85, v85, v88
	v_lshl_add_u32 v87, v87, 6, v84
	v_lshl_add_u32 v86, v86, 6, v84
	v_lshlrev_b32_e32 v85, 4, v85
	v_lshlrev_b32_e32 v87, 7, v87
	v_lshlrev_b32_e32 v86, 7, v86
	v_add_u32_e32 v86, 0x8000, v86
	v_add_u32_e32 v76, v87, v85
	v_add_u32_e32 v80, v86, v85
	v_xor_b32_e32 v89, 0x20, v85
	v_add_u32_e32 v77, v87, v89
	v_add_u32_e32 v81, v86, v89
	v_xor_b32_e32 v89, 0x40, v85
	v_add_u32_e32 v78, v87, v89
	v_add_u32_e32 v82, v86, v89
	v_xor_b32_e32 v89, 0x60, v85
	v_add_u32_e32 v79, v87, v89
	v_add_u32_e32 v83, v86, v89
	v_add_u32_e32 v116, 0x18000, v76
	v_add_u32_e32 v120, 0x18000, v80
	v_add_u32_e32 v117, 0x18000, v77
	v_add_u32_e32 v121, 0x18000, v81
	v_add_u32_e32 v118, 0x18000, v78
	v_add_u32_e32 v122, 0x18000, v82
	v_add_u32_e32 v119, 0x18000, v79
	v_add_u32_e32 v123, 0x18000, v83
	v_lshlrev_b32_e32 v84, 4, v129
	s_nop 0
	v_readfirstlane_b32 s30, v84
	s_mov_b32 s25, 0
	ds_read_b128 v[84:87], v76
	ds_read_b128 v[88:91], v76 offset:4096
	ds_read_b128 v[92:95], v80
	ds_read_b128 v[96:99], v80 offset:4096
	ds_read_b128 v[100:103], v77
	ds_read_b128 v[104:107], v77 offset:4096
	ds_read_b128 v[108:111], v81
	ds_read_b128 v[112:115], v81 offset:4096
	s_waitcnt lgkmcnt(4)
	v_mfma_f32_32x32x16_bf16 v[32:47], v[84:87], v[92:95], v[32:47]
	v_mfma_f32_32x32x16_bf16 v[48:63], v[84:87], v[96:99], v[48:63]
	v_mfma_f32_32x32x16_bf16 v[0:15], v[88:91], v[92:95], v[0:15]
	v_mfma_f32_32x32x16_bf16 v[16:31], v[88:91], v[96:99], v[16:31]
	ds_read_b128 v[84:87], v78
	ds_read_b128 v[88:91], v78 offset:4096
	ds_read_b128 v[92:95], v82
	ds_read_b128 v[96:99], v82 offset:4096
	s_waitcnt lgkmcnt(4)
	v_mfma_f32_32x32x16_bf16 v[32:47], v[100:103], v[108:111], v[32:47]
	v_mfma_f32_32x32x16_bf16 v[48:63], v[100:103], v[112:115], v[48:63]
	v_mfma_f32_32x32x16_bf16 v[0:15], v[104:107], v[108:111], v[0:15]
	v_mfma_f32_32x32x16_bf16 v[16:31], v[104:107], v[112:115], v[16:31]
	ds_read_b128 v[100:103], v79
	ds_read_b128 v[104:107], v79 offset:4096
	ds_read_b128 v[108:111], v83
	ds_read_b128 v[112:115], v83 offset:4096
	s_waitcnt lgkmcnt(4)
	v_mfma_f32_32x32x16_bf16 v[32:47], v[84:87], v[92:95], v[32:47]
	v_mfma_f32_32x32x16_bf16 v[48:63], v[84:87], v[96:99], v[48:63]
	v_mfma_f32_32x32x16_bf16 v[0:15], v[88:91], v[92:95], v[0:15]
	v_mfma_f32_32x32x16_bf16 v[16:31], v[88:91], v[96:99], v[16:31]
	s_waitcnt vmcnt(6) lgkmcnt(0)
	s_barrier
;     ...
;   if (PART != 2) {
;     GEMM_ISSUE(0, 0);
;     if (nk > 1) GEMM_ISSUE(1, 1);
;   }
;   if (PART == 1) return;
;   int st = 0;
;   for (int kt = 0; kt < nk; ++kt) {
;     if (kt + 1 < nk) asm volatile("s_waitcnt vmcnt(6)" ::: "memory");
;     else asm volatile("s_waitcnt vmcnt(0)" ::: "memory");
;     __builtin_amdgcn_s_barrier();
;     asm volatile("" ::: "memory");
;     if (kt + 2 < nk) { const int st2 = (st >= 1) ? st - 1 : 2; GEMM_ISSUE(kt + 2, st2); }
;     const char* la = lds + st * STAGE_B;
;     const char* lb = la + 32768;
;     const unsigned sa_u = (unsigned)(size_t)la + arow_u, sb_u = (unsigned)(size_t)lb + brow_u;
;     const unsigned a0 = sa_u + co0, a1 = sa_u + co1, a2 = sa_u + co2, a3 = sa_u + co3;
;     const unsigned b0 = sb_u + co0, b1 = sb_u + co1, b2 = sb_u + co2, b3 = sb_u + co3;
;     {
;       bf16x8 p0, p1, q0, q1, u0, u1, w0, w1;
;       asm volatile(
;         "ds_read_b128 %4, %12\n\tds_read_b128 %5, %12 offset:4096\n\tds_read_b128 %6, %16\n\tds_read_b128 %7, %16 offset:4096\n\t"
;         "ds_read_b128 %8, %13\n\tds_read_b128 %9, %13 offset:4096\n\tds_read_b128 %10, %17\n\tds_read_b128 %11, %17 offset:4096\n\t"
;         "s_waitcnt lgkmcnt(4)\n\t"
;         "v_mfma_f32_32x32x16_bf16 %0, %4, %6, %0\n\tv_mfma_f32_32x32x16_bf16 %1, %4, %7, %1\n\tv_mfma_f32_32x32x16_bf16 %2, %5, %6, %2\n\tv_mfma_f32_32x32x16_bf16 %3, %5, %7, %3\n\t"
;         "ds_read_b128 %4, %14\n\tds_read_b128 %5, %14 offset:4096\n\tds_read_b128 %6, %18\n\tds_read_b128 %7, %18 offset:4096\n\t"
;         "s_waitcnt lgkmcnt(4)\n\t"
;         "v_mfma_f32_32x32x16_bf16 %0, %8, %10, %0\n\tv_mfma_f32_32x32x16_bf16 %1, %8, %11, %1\n\tv_mfma_f32_32x32x16_bf16 %2, %9, %10, %2\n\tv_mfma_f32_32x32x16_bf16 %3, %9, %11, %3\n\t"
;         "ds_read_b128 %8, %15\n\tds_read_b128 %9, %15 offset:4096\n\tds_read_b128 %10, %19\n\tds_read_b128 %11, %19 offset:4096\n\t"
;         "s_waitcnt lgkmcnt(4)\n\t"
;         "v_mfma_f32_32x32x16_bf16 %0, %4, %6, %0\n\tv_mfma_f32_32x32x16_bf16 %1, %4, %7, %1\n\tv_mfma_f32_32x32x16_bf16 %2, %5, %6, %2\n\tv_mfma_f32_32x32x16_bf16 %3, %5, %7, %3\n\t"
;         "s_waitcnt lgkmcnt(0)\n\t"
;         "v_mfma_f32_32x32x16_bf16 %0, %8, %10, %0\n\tv_mfma_f32_32x32x16_bf16 %1, %8, %11, %1\n\tv_mfma_f32_32x32x16_bf16 %2, %9, %10, %2\n\tv_mfma_f32_32x32x16_bf16 %3, %9, %11, %3"
	ds_read_b128 v[84:87], v76 offset:49152
	ds_read_b128 v[88:91], v76 offset:53248
	ds_read_b128 v[92:95], v80 offset:49152
	ds_read_b128 v[96:99], v80 offset:53248
	v_mfma_f32_32x32x16_bf16 v[32:47], v[100:103], v[108:111], v[32:47]
	s_mov_b32 s24, 0x180
	s_mov_b32 m0, s30
	v_lshl_add_u64 v[124:125], v[64:65], 0, s[24:25]
	global_load_lds_dwordx4 v[124:125], off
	v_mfma_f32_32x32x16_bf16 v[48:63], v[100:103], v[112:115], v[48:63]
	v_mfma_f32_32x32x16_bf16 v[0:15], v[104:107], v[108:111], v[0:15]
	s_add_u32 m0, s30, 0x2000
	v_lshl_add_u64 v[126:127], v[66:67], 0, s[24:25]
	global_load_lds_dwordx4 v[126:127], off
	v_mfma_f32_32x32x16_bf16 v[16:31], v[104:107], v[112:115], v[16:31]
	ds_read_b128 v[100:103], v77 offset:49152
	ds_read_b128 v[104:107], v77 offset:53248
	ds_read_b128 v[108:111], v81 offset:49152
	ds_read_b128 v[112:115], v81 offset:53248
	s_waitcnt lgkmcnt(4)
	v_mfma_f32_32x32x16_bf16 v[32:47], v[84:87], v[92:95], v[32:47]
	s_add_u32 m0, s30, 0x4000
	v_lshl_add_u64 v[124:125], v[68:69], 0, s[24:25]
	global_load_lds_dwordx4 v[124:125], off
	v_mfma_f32_32x32x16_bf16 v[48:63], v[84:87], v[96:99], v[48:63]
	v_mfma_f32_32x32x16_bf16 v[0:15], v[88:91], v[92:95], v[0:15]
	s_add_u32 m0, s30, 0x6000
	v_lshl_add_u64 v[126:127], v[70:71], 0, s[24:25]
	global_load_lds_dwordx4 v[126:127], off
	v_mfma_f32_32x32x16_bf16 v[16:31], v[88:91], v[96:99], v[16:31]
	ds_read_b128 v[84:87], v78 offset:49152
	ds_read_b128 v[88:91], v78 offset:53248
	ds_read_b128 v[92:95], v82 offset:49152
	ds_read_b128 v[96:99], v82 offset:53248
	s_waitcnt lgkmcnt(4)
	v_mfma_f32_32x32x16_bf16 v[32:47], v[100:103], v[108:111], v[32:47]
	s_add_u32 m0, s30, 0x8000
	v_lshl_add_u64 v[124:125], v[72:73], 0, s[24:25]
	global_load_lds_dwordx4 v[124:125], off
	v_mfma_f32_32x32x16_bf16 v[48:63], v[100:103], v[112:115], v[48:63]
	v_mfma_f32_32x32x16_bf16 v[0:15], v[104:107], v[108:111], v[0:15]
	s_add_u32 m0, s30, 0xa000
	v_lshl_add_u64 v[126:127], v[74:75], 0, s[24:25]
	global_load_lds_dwordx4 v[126:127], off
	v_mfma_f32_32x32x16_bf16 v[16:31], v[104:107], v[112:115], v[16:31]
	ds_read_b128 v[100:103], v79 offset:49152
	ds_read_b128 v[104:107], v79 offset:53248
	ds_read_b128 v[108:111], v83 offset:49152
	ds_read_b128 v[112:115], v83 offset:53248
	s_waitcnt lgkmcnt(4)
	v_mfma_f32_32x32x16_bf16 v[32:47], v[84:87], v[92:95], v[32:47]
	v_mfma_f32_32x32x16_bf16 v[48:63], v[84:87], v[96:99], v[48:63]
	v_mfma_f32_32x32x16_bf16 v[0:15], v[88:91], v[92:95], v[0:15]
	v_mfma_f32_32x32x16_bf16 v[16:31], v[88:91], v[96:99], v[16:31]
	s_waitcnt vmcnt(6) lgkmcnt(0)
	s_barrier
	ds_read_b128 v[84:87], v116
	ds_read_b128 v[88:91], v116 offset:4096
	ds_read_b128 v[92:95], v120
	ds_read_b128 v[96:99], v120 offset:4096
	v_mfma_f32_32x32x16_bf16 v[32:47], v[100:103], v[108:111], v[32:47]
	s_mov_b32 s24, 0x200
	s_add_u32 m0, s30, 0xc000
	v_lshl_add_u64 v[124:125], v[64:65], 0, s[24:25]
	global_load_lds_dwordx4 v[124:125], off
	v_mfma_f32_32x32x16_bf16 v[48:63], v[100:103], v[112:115], v[48:63]
	v_mfma_f32_32x32x16_bf16 v[0:15], v[104:107], v[108:111], v[0:15]
	s_add_u32 m0, s30, 0xe000
	v_lshl_add_u64 v[126:127], v[66:67], 0, s[24:25]
	global_load_lds_dwordx4 v[126:127], off
	v_mfma_f32_32x32x16_bf16 v[16:31], v[104:107], v[112:115], v[16:31]
	ds_read_b128 v[100:103], v117
	ds_read_b128 v[104:107], v117 offset:4096
	ds_read_b128 v[108:111], v121
	ds_read_b128 v[112:115], v121 offset:4096
	s_waitcnt lgkmcnt(4)
	v_mfma_f32_32x32x16_bf16 v[32:47], v[84:87], v[92:95], v[32:47]
	s_add_u32 m0, s30, 0x10000
	v_lshl_add_u64 v[124:125], v[68:69], 0, s[24:25]
	global_load_lds_dwordx4 v[124:125], off
	v_mfma_f32_32x32x16_bf16 v[48:63], v[84:87], v[96:99], v[48:63]
	v_mfma_f32_32x32x16_bf16 v[0:15], v[88:91], v[92:95], v[0:15]
	s_add_u32 m0, s30, 0x12000
	v_lshl_add_u64 v[126:127], v[70:71], 0, s[24:25]
	global_load_lds_dwordx4 v[126:127], off
	v_mfma_f32_32x32x16_bf16 v[16:31], v[88:91], v[96:99], v[16:31]
	ds_read_b128 v[84:87], v118
	ds_read_b128 v[88:91], v118 offset:4096
	ds_read_b128 v[92:95], v122
	ds_read_b128 v[96:99], v122 offset:4096
	s_waitcnt lgkmcnt(4)
	v_mfma_f32_32x32x16_bf16 v[32:47], v[100:103], v[108:111], v[32:47]
	s_add_u32 m0, s30, 0x14000
	v_lshl_add_u64 v[124:125], v[72:73], 0, s[24:25]
	global_load_lds_dwordx4 v[124:125], off
	v_mfma_f32_32x32x16_bf16 v[48:63], v[100:103], v[112:115], v[48:63]
	v_mfma_f32_32x32x16_bf16 v[0:15], v[104:107], v[108:111], v[0:15]
	s_add_u32 m0, s30, 0x16000
	v_lshl_add_u64 v[126:127], v[74:75], 0, s[24:25]
	global_load_lds_dwordx4 v[126:127], off
	v_mfma_f32_32x32x16_bf16 v[16:31], v[104:107], v[112:115], v[16:31]
	ds_read_b128 v[100:103], v119
	ds_read_b128 v[104:107], v119 offset:4096
	ds_read_b128 v[108:111], v123
	ds_read_b128 v[112:115], v123 offset:4096
	s_waitcnt lgkmcnt(4)
	v_mfma_f32_32x32x16_bf16 v[32:47], v[84:87], v[92:95], v[32:47]
	v_mfma_f32_32x32x16_bf16 v[48:63], v[84:87], v[96:99], v[48:63]
	v_mfma_f32_32x32x16_bf16 v[0:15], v[88:91], v[92:95], v[0:15]
	v_mfma_f32_32x32x16_bf16 v[16:31], v[88:91], v[96:99], v[16:31]
	s_waitcnt vmcnt(6) lgkmcnt(0)
	s_barrier
;     ...
;   if (PART != 2) {
;     GEMM_ISSUE(0, 0);
;     if (nk > 1) GEMM_ISSUE(1, 1);
;   }
;   if (PART == 1) return;
;   int st = 0;
;   for (int kt = 0; kt < nk; ++kt) {
;     if (kt + 1 < nk) asm volatile("s_waitcnt vmcnt(6)" ::: "memory");
;     else asm volatile("s_waitcnt vmcnt(0)" ::: "memory");
;     __builtin_amdgcn_s_barrier();
;     asm volatile("" ::: "memory");
;     if (kt + 2 < nk) { const int st2 = (st >= 1) ? st - 1 : 2; GEMM_ISSUE(kt + 2, st2); }
;     const char* la = lds + st * STAGE_B;
;     const char* lb = la + 32768;
;     const unsigned sa_u = (unsigned)(size_t)la + arow_u, sb_u = (unsigned)(size_t)lb + brow_u;
;     const unsigned a0 = sa_u + co0, a1 = sa_u + co1, a2 = sa_u + co2, a3 = sa_u + co3;
;     const unsigned b0 = sb_u + co0, b1 = sb_u + co1, b2 = sb_u + co2, b3 = sb_u + co3;
;     {
;       bf16x8 p0, p1, q0, q1, u0, u1, w0, w1;
;       asm volatile(
;         "ds_read_b128 %4, %12\n\tds_read_b128 %5, %12 offset:4096\n\tds_read_b128 %6, %16\n\tds_read_b128 %7, %16 offset:4096\n\t"
;         "ds_read_b128 %8, %13\n\tds_read_b128 %9, %13 offset:4096\n\tds_read_b128 %10, %17\n\tds_read_b128 %11, %17 offset:4096\n\t"
;         "s_waitcnt lgkmcnt(4)\n\t"
;         "v_mfma_f32_32x32x16_bf16 %0, %4, %6, %0\n\tv_mfma_f32_32x32x16_bf16 %1, %4, %7, %1\n\tv_mfma_f32_32x32x16_bf16 %2, %5, %6, %2\n\tv_mfma_f32_32x32x16_bf16 %3, %5, %7, %3\n\t"
;         "ds_read_b128 %4, %14\n\tds_read_b128 %5, %14 offset:4096\n\tds_read_b128 %6, %18\n\tds_read_b128 %7, %18 offset:4096\n\t"
;         "s_waitcnt lgkmcnt(4)\n\t"
;         "v_mfma_f32_32x32x16_bf16 %0, %8, %10, %0\n\tv_mfma_f32_32x32x16_bf16 %1, %8, %11, %1\n\tv_mfma_f32_32x32x16_bf16 %2, %9, %10, %2\n\tv_mfma_f32_32x32x16_bf16 %3, %9, %11, %3\n\t"
;         "ds_read_b128 %8, %15\n\tds_read_b128 %9, %15 offset:4096\n\tds_read_b128 %10, %19\n\tds_read_b128 %11, %19 offset:4096\n\t"
;         "s_waitcnt lgkmcnt(4)\n\t"
;         "v_mfma_f32_32x32x16_bf16 %0, %4, %6, %0\n\tv_mfma_f32_32x32x16_bf16 %1, %4, %7, %1\n\tv_mfma_f32_32x32x16_bf16 %2, %5, %6, %2\n\tv_mfma_f32_32x32x16_bf16 %3, %5, %7, %3\n\t"
;         "s_waitcnt lgkmcnt(0)\n\t"
;         "v_mfma_f32_32x32x16_bf16 %0, %8, %10, %0\n\tv_mfma_f32_32x32x16_bf16 %1, %8, %11, %1\n\tv_mfma_f32_32x32x16_bf16 %2, %9, %10, %2\n\tv_mfma_f32_32x32x16_bf16 %3, %9, %11, %3"
	ds_read_b128 v[84:87], v76
	ds_read_b128 v[88:91], v76 offset:4096
	ds_read_b128 v[92:95], v80
	ds_read_b128 v[96:99], v80 offset:4096
	v_mfma_f32_32x32x16_bf16 v[32:47], v[100:103], v[108:111], v[32:47]
	s_mov_b32 s24, 0x280
	s_add_u32 m0, s30, 0x18000
	v_lshl_add_u64 v[124:125], v[64:65], 0, s[24:25]
	global_load_lds_dwordx4 v[124:125], off
	v_mfma_f32_32x32x16_bf16 v[48:63], v[100:103], v[112:115], v[48:63]
	v_mfma_f32_32x32x16_bf16 v[0:15], v[104:107], v[108:111], v[0:15]
	s_add_u32 m0, s30, 0x1a000
	v_lshl_add_u64 v[126:127], v[66:67], 0, s[24:25]
	global_load_lds_dwordx4 v[126:127], off
	v_mfma_f32_32x32x16_bf16 v[16:31], v[104:107], v[112:115], v[16:31]
	ds_read_b128 v[100:103], v77
	ds_read_b128 v[104:107], v77 offset:4096
	ds_read_b128 v[108:111], v81
	ds_read_b128 v[112:115], v81 offset:4096
	s_waitcnt lgkmcnt(4)
	v_mfma_f32_32x32x16_bf16 v[32:47], v[84:87], v[92:95], v[32:47]
	s_add_u32 m0, s30, 0x1c000
	v_lshl_add_u64 v[124:125], v[68:69], 0, s[24:25]
	global_load_lds_dwordx4 v[124:125], off
	v_mfma_f32_32x32x16_bf16 v[48:63], v[84:87], v[96:99], v[48:63]
	v_mfma_f32_32x32x16_bf16 v[0:15], v[88:91], v[92:95], v[0:15]
	s_add_u32 m0, s30, 0x1e000
	v_lshl_add_u64 v[126:127], v[70:71], 0, s[24:25]
	global_load_lds_dwordx4 v[126:127], off
	v_mfma_f32_32x32x16_bf16 v[16:31], v[88:91], v[96:99], v[16:31]
	ds_read_b128 v[84:87], v78
	ds_read_b128 v[88:91], v78 offset:4096
	ds_read_b128 v[92:95], v82
	ds_read_b128 v[96:99], v82 offset:4096
	s_waitcnt lgkmcnt(4)
	v_mfma_f32_32x32x16_bf16 v[32:47], v[100:103], v[108:111], v[32:47]
	s_add_u32 m0, s30, 0x20000
	v_lshl_add_u64 v[124:125], v[72:73], 0, s[24:25]
	global_load_lds_dwordx4 v[124:125], off
	v_mfma_f32_32x32x16_bf16 v[48:63], v[100:103], v[112:115], v[48:63]
	v_mfma_f32_32x32x16_bf16 v[0:15], v[104:107], v[108:111], v[0:15]
	s_add_u32 m0, s30, 0x22000
	v_lshl_add_u64 v[126:127], v[74:75], 0, s[24:25]
	global_load_lds_dwordx4 v[126:127], off
	v_mfma_f32_32x32x16_bf16 v[16:31], v[104:107], v[112:115], v[16:31]
	ds_read_b128 v[100:103], v79
	ds_read_b128 v[104:107], v79 offset:4096
	ds_read_b128 v[108:111], v83
	ds_read_b128 v[112:115], v83 offset:4096
	s_waitcnt lgkmcnt(4)
	v_mfma_f32_32x32x16_bf16 v[32:47], v[84:87], v[92:95], v[32:47]
	v_mfma_f32_32x32x16_bf16 v[48:63], v[84:87], v[96:99], v[48:63]
	v_mfma_f32_32x32x16_bf16 v[0:15], v[88:91], v[92:95], v[0:15]
	v_mfma_f32_32x32x16_bf16 v[16:31], v[88:91], v[96:99], v[16:31]
	s_waitcnt vmcnt(6) lgkmcnt(0)
	s_barrier
	ds_read_b128 v[84:87], v76 offset:49152
	ds_read_b128 v[88:91], v76 offset:53248
	ds_read_b128 v[92:95], v80 offset:49152
	ds_read_b128 v[96:99], v80 offset:53248
	v_mfma_f32_32x32x16_bf16 v[32:47], v[100:103], v[108:111], v[32:47]
	s_mov_b32 s24, 0x300
	s_mov_b32 m0, s30
	v_lshl_add_u64 v[124:125], v[64:65], 0, s[24:25]
	global_load_lds_dwordx4 v[124:125], off
	v_mfma_f32_32x32x16_bf16 v[48:63], v[100:103], v[112:115], v[48:63]
	v_mfma_f32_32x32x16_bf16 v[0:15], v[104:107], v[108:111], v[0:15]
	s_add_u32 m0, s30, 0x2000
	v_lshl_add_u64 v[126:127], v[66:67], 0, s[24:25]
	global_load_lds_dwordx4 v[126:127], off
	v_mfma_f32_32x32x16_bf16 v[16:31], v[104:107], v[112:115], v[16:31]
	ds_read_b128 v[100:103], v77 offset:49152
	ds_read_b128 v[104:107], v77 offset:53248
	ds_read_b128 v[108:111], v81 offset:49152
	ds_read_b128 v[112:115], v81 offset:53248
	s_waitcnt lgkmcnt(4)
	v_mfma_f32_32x32x16_bf16 v[32:47], v[84:87], v[92:95], v[32:47]
	s_add_u32 m0, s30, 0x4000
	v_lshl_add_u64 v[124:125], v[68:69], 0, s[24:25]
	global_load_lds_dwordx4 v[124:125], off
	v_mfma_f32_32x32x16_bf16 v[48:63], v[84:87], v[96:99], v[48:63]
	v_mfma_f32_32x32x16_bf16 v[0:15], v[88:91], v[92:95], v[0:15]
	s_add_u32 m0, s30, 0x6000
	v_lshl_add_u64 v[126:127], v[70:71], 0, s[24:25]
	global_load_lds_dwordx4 v[126:127], off
	v_mfma_f32_32x32x16_bf16 v[16:31], v[88:91], v[96:99], v[16:31]
	ds_read_b128 v[84:87], v78 offset:49152
	ds_read_b128 v[88:91], v78 offset:53248
	ds_read_b128 v[92:95], v82 offset:49152
	ds_read_b128 v[96:99], v82 offset:53248
	s_waitcnt lgkmcnt(4)
	v_mfma_f32_32x32x16_bf16 v[32:47], v[100:103], v[108:111], v[32:47]
	s_add_u32 m0, s30, 0x8000
	v_lshl_add_u64 v[124:125], v[72:73], 0, s[24:25]
	global_load_lds_dwordx4 v[124:125], off
	v_mfma_f32_32x32x16_bf16 v[48:63], v[100:103], v[112:115], v[48:63]
	v_mfma_f32_32x32x16_bf16 v[0:15], v[104:107], v[108:111], v[0:15]
	s_add_u32 m0, s30, 0xa000
	v_lshl_add_u64 v[126:127], v[74:75], 0, s[24:25]
	global_load_lds_dwordx4 v[126:127], off
	v_mfma_f32_32x32x16_bf16 v[16:31], v[104:107], v[112:115], v[16:31]
	ds_read_b128 v[100:103], v79 offset:49152
	ds_read_b128 v[104:107], v79 offset:53248
	ds_read_b128 v[108:111], v83 offset:49152
	ds_read_b128 v[112:115], v83 offset:53248
	s_waitcnt lgkmcnt(4)
	v_mfma_f32_32x32x16_bf16 v[32:47], v[84:87], v[92:95], v[32:47]
	v_mfma_f32_32x32x16_bf16 v[48:63], v[84:87], v[96:99], v[48:63]
	v_mfma_f32_32x32x16_bf16 v[0:15], v[88:91], v[92:95], v[0:15]
	v_mfma_f32_32x32x16_bf16 v[16:31], v[88:91], v[96:99], v[16:31]
	s_waitcnt vmcnt(6) lgkmcnt(0)
	s_barrier
;     ...
;   if (PART != 2) {
;     GEMM_ISSUE(0, 0);
;     if (nk > 1) GEMM_ISSUE(1, 1);
;   }
;   if (PART == 1) return;
;   int st = 0;
;   for (int kt = 0; kt < nk; ++kt) {
;     if (kt + 1 < nk) asm volatile("s_waitcnt vmcnt(6)" ::: "memory");
;     else asm volatile("s_waitcnt vmcnt(0)" ::: "memory");
;     __builtin_amdgcn_s_barrier();
;     asm volatile("" ::: "memory");
;     if (kt + 2 < nk) { const int st2 = (st >= 1) ? st - 1 : 2; GEMM_ISSUE(kt + 2, st2); }
;     const char* la = lds + st * STAGE_B;
;     const char* lb = la + 32768;
;     const unsigned sa_u = (unsigned)(size_t)la + arow_u, sb_u = (unsigned)(size_t)lb + brow_u;
;     const unsigned a0 = sa_u + co0, a1 = sa_u + co1, a2 = sa_u + co2, a3 = sa_u + co3;
;     const unsigned b0 = sb_u + co0, b1 = sb_u + co1, b2 = sb_u + co2, b3 = sb_u + co3;
;     {
;       bf16x8 p0, p1, q0, q1, u0, u1, w0, w1;
;       asm volatile(
;         "ds_read_b128 %4, %12\n\tds_read_b128 %5, %12 offset:4096\n\tds_read_b128 %6, %16\n\tds_read_b128 %7, %16 offset:4096\n\t"
;         "ds_read_b128 %8, %13\n\tds_read_b128 %9, %13 offset:4096\n\tds_read_b128 %10, %17\n\tds_read_b128 %11, %17 offset:4096\n\t"
;         "s_waitcnt lgkmcnt(4)\n\t"
;         "v_mfma_f32_32x32x16_bf16 %0, %4, %6, %0\n\tv_mfma_f32_32x32x16_bf16 %1, %4, %7, %1\n\tv_mfma_f32_32x32x16_bf16 %2, %5, %6, %2\n\tv_mfma_f32_32x32x16_bf16 %3, %5, %7, %3\n\t"
;         "ds_read_b128 %4, %14\n\tds_read_b128 %5, %14 offset:4096\n\tds_read_b128 %6, %18\n\tds_read_b128 %7, %18 offset:4096\n\t"
;         "s_waitcnt lgkmcnt(4)\n\t"
;         "v_mfma_f32_32x32x16_bf16 %0, %8, %10, %0\n\tv_mfma_f32_32x32x16_bf16 %1, %8, %11, %1\n\tv_mfma_f32_32x32x16_bf16 %2, %9, %10, %2\n\tv_mfma_f32_32x32x16_bf16 %3, %9, %11, %3\n\t"
;         "ds_read_b128 %8, %15\n\tds_read_b128 %9, %15 offset:4096\n\tds_read_b128 %10, %19\n\tds_read_b128 %11, %19 offset:4096\n\t"
;         "s_waitcnt lgkmcnt(4)\n\t"
;         "v_mfma_f32_32x32x16_bf16 %0, %4, %6, %0\n\tv_mfma_f32_32x32x16_bf16 %1, %4, %7, %1\n\tv_mfma_f32_32x32x16_bf16 %2, %5, %6, %2\n\tv_mfma_f32_32x32x16_bf16 %3, %5, %7, %3\n\t"
;         "s_waitcnt lgkmcnt(0)\n\t"
;         "v_mfma_f32_32x32x16_bf16 %0, %8, %10, %0\n\tv_mfma_f32_32x32x16_bf16 %1, %8, %11, %1\n\tv_mfma_f32_32x32x16_bf16 %2, %9, %10, %2\n\tv_mfma_f32_32x32x16_bf16 %3, %9, %11, %3"
	ds_read_b128 v[84:87], v116
	ds_read_b128 v[88:91], v116 offset:4096
	ds_read_b128 v[92:95], v120
	ds_read_b128 v[96:99], v120 offset:4096
	v_mfma_f32_32x32x16_bf16 v[32:47], v[100:103], v[108:111], v[32:47]
	s_mov_b32 s24, 0x380
	s_add_u32 m0, s30, 0xc000
	v_lshl_add_u64 v[124:125], v[64:65], 0, s[24:25]
	global_load_lds_dwordx4 v[124:125], off
	v_mfma_f32_32x32x16_bf16 v[48:63], v[100:103], v[112:115], v[48:63]
	v_mfma_f32_32x32x16_bf16 v[0:15], v[104:107], v[108:111], v[0:15]
	s_add_u32 m0, s30, 0xe000
	v_lshl_add_u64 v[126:127], v[66:67], 0, s[24:25]
	global_load_lds_dwordx4 v[126:127], off
	v_mfma_f32_32x32x16_bf16 v[16:31], v[104:107], v[112:115], v[16:31]
	ds_read_b128 v[100:103], v117
	ds_read_b128 v[104:107], v117 offset:4096
	ds_read_b128 v[108:111], v121
	ds_read_b128 v[112:115], v121 offset:4096
	s_waitcnt lgkmcnt(4)
	v_mfma_f32_32x32x16_bf16 v[32:47], v[84:87], v[92:95], v[32:47]
	s_add_u32 m0, s30, 0x10000
	v_lshl_add_u64 v[124:125], v[68:69], 0, s[24:25]
	global_load_lds_dwordx4 v[124:125], off
	v_mfma_f32_32x32x16_bf16 v[48:63], v[84:87], v[96:99], v[48:63]
	v_mfma_f32_32x32x16_bf16 v[0:15], v[88:91], v[92:95], v[0:15]
	s_add_u32 m0, s30, 0x12000
	v_lshl_add_u64 v[126:127], v[70:71], 0, s[24:25]
	global_load_lds_dwordx4 v[126:127], off
	v_mfma_f32_32x32x16_bf16 v[16:31], v[88:91], v[96:99], v[16:31]
	ds_read_b128 v[84:87], v118
	ds_read_b128 v[88:91], v118 offset:4096
	ds_read_b128 v[92:95], v122
	ds_read_b128 v[96:99], v122 offset:4096
	s_waitcnt lgkmcnt(4)
	v_mfma_f32_32x32x16_bf16 v[32:47], v[100:103], v[108:111], v[32:47]
	s_add_u32 m0, s30, 0x14000
	v_lshl_add_u64 v[124:125], v[72:73], 0, s[24:25]
	global_load_lds_dwordx4 v[124:125], off
	v_mfma_f32_32x32x16_bf16 v[48:63], v[100:103], v[112:115], v[48:63]
	v_mfma_f32_32x32x16_bf16 v[0:15], v[104:107], v[108:111], v[0:15]
	s_add_u32 m0, s30, 0x16000
	v_lshl_add_u64 v[126:127], v[74:75], 0, s[24:25]
	global_load_lds_dwordx4 v[126:127], off
	v_mfma_f32_32x32x16_bf16 v[16:31], v[104:107], v[112:115], v[16:31]
	ds_read_b128 v[100:103], v119
	ds_read_b128 v[104:107], v119 offset:4096
	ds_read_b128 v[108:111], v123
	ds_read_b128 v[112:115], v123 offset:4096
	s_waitcnt lgkmcnt(4)
	v_mfma_f32_32x32x16_bf16 v[32:47], v[84:87], v[92:95], v[32:47]
	v_mfma_f32_32x32x16_bf16 v[48:63], v[84:87], v[96:99], v[48:63]
	v_mfma_f32_32x32x16_bf16 v[0:15], v[88:91], v[92:95], v[0:15]
	v_mfma_f32_32x32x16_bf16 v[16:31], v[88:91], v[96:99], v[16:31]
	s_waitcnt vmcnt(6) lgkmcnt(0)
	s_barrier
	ds_read_b128 v[84:87], v76
	ds_read_b128 v[88:91], v76 offset:4096
	ds_read_b128 v[92:95], v80
	ds_read_b128 v[96:99], v80 offset:4096
	v_mfma_f32_32x32x16_bf16 v[32:47], v[100:103], v[108:111], v[32:47]
	s_mov_b32 s24, 0x400
	s_add_u32 m0, s30, 0x18000
	v_lshl_add_u64 v[124:125], v[64:65], 0, s[24:25]
	global_load_lds_dwordx4 v[124:125], off
	v_mfma_f32_32x32x16_bf16 v[48:63], v[100:103], v[112:115], v[48:63]
	v_mfma_f32_32x32x16_bf16 v[0:15], v[104:107], v[108:111], v[0:15]
	s_add_u32 m0, s30, 0x1a000
	v_lshl_add_u64 v[126:127], v[66:67], 0, s[24:25]
	global_load_lds_dwordx4 v[126:127], off
	v_mfma_f32_32x32x16_bf16 v[16:31], v[104:107], v[112:115], v[16:31]
	ds_read_b128 v[100:103], v77
	ds_read_b128 v[104:107], v77 offset:4096
	ds_read_b128 v[108:111], v81
	ds_read_b128 v[112:115], v81 offset:4096
	s_waitcnt lgkmcnt(4)
	v_mfma_f32_32x32x16_bf16 v[32:47], v[84:87], v[92:95], v[32:47]
	s_add_u32 m0, s30, 0x1c000
	v_lshl_add_u64 v[124:125], v[68:69], 0, s[24:25]
	global_load_lds_dwordx4 v[124:125], off
	v_mfma_f32_32x32x16_bf16 v[48:63], v[84:87], v[96:99], v[48:63]
	v_mfma_f32_32x32x16_bf16 v[0:15], v[88:91], v[92:95], v[0:15]
	s_add_u32 m0, s30, 0x1e000
	v_lshl_add_u64 v[126:127], v[70:71], 0, s[24:25]
	global_load_lds_dwordx4 v[126:127], off
	v_mfma_f32_32x32x16_bf16 v[16:31], v[88:91], v[96:99], v[16:31]
	ds_read_b128 v[84:87], v78
	ds_read_b128 v[88:91], v78 offset:4096
	ds_read_b128 v[92:95], v82
	ds_read_b128 v[96:99], v82 offset:4096
	s_waitcnt lgkmcnt(4)
	v_mfma_f32_32x32x16_bf16 v[32:47], v[100:103], v[108:111], v[32:47]
	s_add_u32 m0, s30, 0x20000
	v_lshl_add_u64 v[124:125], v[72:73], 0, s[24:25]
	global_load_lds_dwordx4 v[124:125], off
	v_mfma_f32_32x32x16_bf16 v[48:63], v[100:103], v[112:115], v[48:63]
	v_mfma_f32_32x32x16_bf16 v[0:15], v[104:107], v[108:111], v[0:15]
	s_add_u32 m0, s30, 0x22000
	v_lshl_add_u64 v[126:127], v[74:75], 0, s[24:25]
	global_load_lds_dwordx4 v[126:127], off
	v_mfma_f32_32x32x16_bf16 v[16:31], v[104:107], v[112:115], v[16:31]
	ds_read_b128 v[100:103], v79
	ds_read_b128 v[104:107], v79 offset:4096
	ds_read_b128 v[108:111], v83
	ds_read_b128 v[112:115], v83 offset:4096
	s_waitcnt lgkmcnt(4)
	v_mfma_f32_32x32x16_bf16 v[32:47], v[84:87], v[92:95], v[32:47]
	v_mfma_f32_32x32x16_bf16 v[48:63], v[84:87], v[96:99], v[48:63]
	v_mfma_f32_32x32x16_bf16 v[0:15], v[88:91], v[92:95], v[0:15]
	v_mfma_f32_32x32x16_bf16 v[16:31], v[88:91], v[96:99], v[16:31]
	s_waitcnt vmcnt(6) lgkmcnt(0)
	s_barrier
;     ...
;   if (PART != 2) {
;     GEMM_ISSUE(0, 0);
;     if (nk > 1) GEMM_ISSUE(1, 1);
;   }
;   if (PART == 1) return;
;   int st = 0;
;   for (int kt = 0; kt < nk; ++kt) {
;     if (kt + 1 < nk) asm volatile("s_waitcnt vmcnt(6)" ::: "memory");
;     else asm volatile("s_waitcnt vmcnt(0)" ::: "memory");
;     __builtin_amdgcn_s_barrier();
;     asm volatile("" ::: "memory");
;     if (kt + 2 < nk) { const int st2 = (st >= 1) ? st - 1 : 2; GEMM_ISSUE(kt + 2, st2); }
;     const char* la = lds + st * STAGE_B;
;     const char* lb = la + 32768;
;     const unsigned sa_u = (unsigned)(size_t)la + arow_u, sb_u = (unsigned)(size_t)lb + brow_u;
;     const unsigned a0 = sa_u + co0, a1 = sa_u + co1, a2 = sa_u + co2, a3 = sa_u + co3;
;     const unsigned b0 = sb_u + co0, b1 = sb_u + co1, b2 = sb_u + co2, b3 = sb_u + co3;
;     {
;       bf16x8 p0, p1, q0, q1, u0, u1, w0, w1;
;       asm volatile(
;         "ds_read_b128 %4, %12\n\tds_read_b128 %5, %12 offset:4096\n\tds_read_b128 %6, %16\n\tds_read_b128 %7, %16 offset:4096\n\t"
;         "ds_read_b128 %8, %13\n\tds_read_b128 %9, %13 offset:4096\n\tds_read_b128 %10, %17\n\tds_read_b128 %11, %17 offset:4096\n\t"
;         "s_waitcnt lgkmcnt(4)\n\t"
;         "v_mfma_f32_32x32x16_bf16 %0, %4, %6, %0\n\tv_mfma_f32_32x32x16_bf16 %1, %4, %7, %1\n\tv_mfma_f32_32x32x16_bf16 %2, %5, %6, %2\n\tv_mfma_f32_32x32x16_bf16 %3, %5, %7, %3\n\t"
;         "ds_read_b128 %4, %14\n\tds_read_b128 %5, %14 offset:4096\n\tds_read_b128 %6, %18\n\tds_read_b128 %7, %18 offset:4096\n\t"
;         "s_waitcnt lgkmcnt(4)\n\t"
;         "v_mfma_f32_32x32x16_bf16 %0, %8, %10, %0\n\tv_mfma_f32_32x32x16_bf16 %1, %8, %11, %1\n\tv_mfma_f32_32x32x16_bf16 %2, %9, %10, %2\n\tv_mfma_f32_32x32x16_bf16 %3, %9, %11, %3\n\t"
;         "ds_read_b128 %8, %15\n\tds_read_b128 %9, %15 offset:4096\n\tds_read_b128 %10, %19\n\tds_read_b128 %11, %19 offset:4096\n\t"
;         "s_waitcnt lgkmcnt(4)\n\t"
;         "v_mfma_f32_32x32x16_bf16 %0, %4, %6, %0\n\tv_mfma_f32_32x32x16_bf16 %1, %4, %7, %1\n\tv_mfma_f32_32x32x16_bf16 %2, %5, %6, %2\n\tv_mfma_f32_32x32x16_bf16 %3, %5, %7, %3\n\t"
;         "s_waitcnt lgkmcnt(0)\n\t"
;         "v_mfma_f32_32x32x16_bf16 %0, %8, %10, %0\n\tv_mfma_f32_32x32x16_bf16 %1, %8, %11, %1\n\tv_mfma_f32_32x32x16_bf16 %2, %9, %10, %2\n\tv_mfma_f32_32x32x16_bf16 %3, %9, %11, %3"
	ds_read_b128 v[84:87], v76 offset:49152
	ds_read_b128 v[88:91], v76 offset:53248
	ds_read_b128 v[92:95], v80 offset:49152
	ds_read_b128 v[96:99], v80 offset:53248
	v_mfma_f32_32x32x16_bf16 v[32:47], v[100:103], v[108:111], v[32:47]
	s_mov_b32 s24, 0x480
	s_mov_b32 m0, s30
	v_lshl_add_u64 v[124:125], v[64:65], 0, s[24:25]
	global_load_lds_dwordx4 v[124:125], off
	v_mfma_f32_32x32x16_bf16 v[48:63], v[100:103], v[112:115], v[48:63]
	v_mfma_f32_32x32x16_bf16 v[0:15], v[104:107], v[108:111], v[0:15]
	s_add_u32 m0, s30, 0x2000
	v_lshl_add_u64 v[126:127], v[66:67], 0, s[24:25]
	global_load_lds_dwordx4 v[126:127], off
	v_mfma_f32_32x32x16_bf16 v[16:31], v[104:107], v[112:115], v[16:31]
	ds_read_b128 v[100:103], v77 offset:49152
	ds_read_b128 v[104:107], v77 offset:53248
	ds_read_b128 v[108:111], v81 offset:49152
	ds_read_b128 v[112:115], v81 offset:53248
	s_waitcnt lgkmcnt(4)
	v_mfma_f32_32x32x16_bf16 v[32:47], v[84:87], v[92:95], v[32:47]
	s_add_u32 m0, s30, 0x4000
	v_lshl_add_u64 v[124:125], v[68:69], 0, s[24:25]
	global_load_lds_dwordx4 v[124:125], off
	v_mfma_f32_32x32x16_bf16 v[48:63], v[84:87], v[96:99], v[48:63]
	v_mfma_f32_32x32x16_bf16 v[0:15], v[88:91], v[92:95], v[0:15]
	s_add_u32 m0, s30, 0x6000
	v_lshl_add_u64 v[126:127], v[70:71], 0, s[24:25]
	global_load_lds_dwordx4 v[126:127], off
	v_mfma_f32_32x32x16_bf16 v[16:31], v[88:91], v[96:99], v[16:31]
	ds_read_b128 v[84:87], v78 offset:49152
	ds_read_b128 v[88:91], v78 offset:53248
	ds_read_b128 v[92:95], v82 offset:49152
	ds_read_b128 v[96:99], v82 offset:53248
	s_waitcnt lgkmcnt(4)
	v_mfma_f32_32x32x16_bf16 v[32:47], v[100:103], v[108:111], v[32:47]
	s_add_u32 m0, s30, 0x8000
	v_lshl_add_u64 v[124:125], v[72:73], 0, s[24:25]
	global_load_lds_dwordx4 v[124:125], off
	v_mfma_f32_32x32x16_bf16 v[48:63], v[100:103], v[112:115], v[48:63]
	v_mfma_f32_32x32x16_bf16 v[0:15], v[104:107], v[108:111], v[0:15]
	s_add_u32 m0, s30, 0xa000
	v_lshl_add_u64 v[126:127], v[74:75], 0, s[24:25]
	global_load_lds_dwordx4 v[126:127], off
	v_mfma_f32_32x32x16_bf16 v[16:31], v[104:107], v[112:115], v[16:31]
	ds_read_b128 v[100:103], v79 offset:49152
	ds_read_b128 v[104:107], v79 offset:53248
	ds_read_b128 v[108:111], v83 offset:49152
	ds_read_b128 v[112:115], v83 offset:53248
	s_waitcnt lgkmcnt(4)
	v_mfma_f32_32x32x16_bf16 v[32:47], v[84:87], v[92:95], v[32:47]
	v_mfma_f32_32x32x16_bf16 v[48:63], v[84:87], v[96:99], v[48:63]
	v_mfma_f32_32x32x16_bf16 v[0:15], v[88:91], v[92:95], v[0:15]
	v_mfma_f32_32x32x16_bf16 v[16:31], v[88:91], v[96:99], v[16:31]
	s_waitcnt vmcnt(6) lgkmcnt(0)
	s_barrier
	ds_read_b128 v[84:87], v116
	ds_read_b128 v[88:91], v116 offset:4096
	ds_read_b128 v[92:95], v120
	ds_read_b128 v[96:99], v120 offset:4096
	v_mfma_f32_32x32x16_bf16 v[32:47], v[100:103], v[108:111], v[32:47]
	s_mov_b32 s24, 0x500
	s_add_u32 m0, s30, 0xc000
	v_lshl_add_u64 v[124:125], v[64:65], 0, s[24:25]
	global_load_lds_dwordx4 v[124:125], off
	v_mfma_f32_32x32x16_bf16 v[48:63], v[100:103], v[112:115], v[48:63]
	v_mfma_f32_32x32x16_bf16 v[0:15], v[104:107], v[108:111], v[0:15]
	s_add_u32 m0, s30, 0xe000
	v_lshl_add_u64 v[126:127], v[66:67], 0, s[24:25]
	global_load_lds_dwordx4 v[126:127], off
	v_mfma_f32_32x32x16_bf16 v[16:31], v[104:107], v[112:115], v[16:31]
	ds_read_b128 v[100:103], v117
	ds_read_b128 v[104:107], v117 offset:4096
	ds_read_b128 v[108:111], v121
	ds_read_b128 v[112:115], v121 offset:4096
	s_waitcnt lgkmcnt(4)
	v_mfma_f32_32x32x16_bf16 v[32:47], v[84:87], v[92:95], v[32:47]
	s_add_u32 m0, s30, 0x10000
	v_lshl_add_u64 v[124:125], v[68:69], 0, s[24:25]
	global_load_lds_dwordx4 v[124:125], off
	v_mfma_f32_32x32x16_bf16 v[48:63], v[84:87], v[96:99], v[48:63]
	v_mfma_f32_32x32x16_bf16 v[0:15], v[88:91], v[92:95], v[0:15]
	s_add_u32 m0, s30, 0x12000
	v_lshl_add_u64 v[126:127], v[70:71], 0, s[24:25]
	global_load_lds_dwordx4 v[126:127], off
	v_mfma_f32_32x32x16_bf16 v[16:31], v[88:91], v[96:99], v[16:31]
	ds_read_b128 v[84:87], v118
	ds_read_b128 v[88:91], v118 offset:4096
	ds_read_b128 v[92:95], v122
	ds_read_b128 v[96:99], v122 offset:4096
	s_waitcnt lgkmcnt(4)
	v_mfma_f32_32x32x16_bf16 v[32:47], v[100:103], v[108:111], v[32:47]
	s_add_u32 m0, s30, 0x14000
	v_lshl_add_u64 v[124:125], v[72:73], 0, s[24:25]
	global_load_lds_dwordx4 v[124:125], off
	v_mfma_f32_32x32x16_bf16 v[48:63], v[100:103], v[112:115], v[48:63]
	v_mfma_f32_32x32x16_bf16 v[0:15], v[104:107], v[108:111], v[0:15]
	s_add_u32 m0, s30, 0x16000
	v_lshl_add_u64 v[126:127], v[74:75], 0, s[24:25]
	global_load_lds_dwordx4 v[126:127], off
	v_mfma_f32_32x32x16_bf16 v[16:31], v[104:107], v[112:115], v[16:31]
	ds_read_b128 v[100:103], v119
	ds_read_b128 v[104:107], v119 offset:4096
	ds_read_b128 v[108:111], v123
	ds_read_b128 v[112:115], v123 offset:4096
	s_waitcnt lgkmcnt(4)
	v_mfma_f32_32x32x16_bf16 v[32:47], v[84:87], v[92:95], v[32:47]
	v_mfma_f32_32x32x16_bf16 v[48:63], v[84:87], v[96:99], v[48:63]
	v_mfma_f32_32x32x16_bf16 v[0:15], v[88:91], v[92:95], v[0:15]
	v_mfma_f32_32x32x16_bf16 v[16:31], v[88:91], v[96:99], v[16:31]
	s_waitcnt vmcnt(6) lgkmcnt(0)
	s_barrier
;     ...
;   if (PART != 2) {
;     GEMM_ISSUE(0, 0);
;     if (nk > 1) GEMM_ISSUE(1, 1);
;   }
;   if (PART == 1) return;
;   int st = 0;
;   for (int kt = 0; kt < nk; ++kt) {
;     if (kt + 1 < nk) asm volatile("s_waitcnt vmcnt(6)" ::: "memory");
;     else asm volatile("s_waitcnt vmcnt(0)" ::: "memory");
;     __builtin_amdgcn_s_barrier();
;     asm volatile("" ::: "memory");
;     if (kt + 2 < nk) { const int st2 = (st >= 1) ? st - 1 : 2; GEMM_ISSUE(kt + 2, st2); }
;     const char* la = lds + st * STAGE_B;
;     const char* lb = la + 32768;
;     const unsigned sa_u = (unsigned)(size_t)la + arow_u, sb_u = (unsigned)(size_t)lb + brow_u;
;     const unsigned a0 = sa_u + co0, a1 = sa_u + co1, a2 = sa_u + co2, a3 = sa_u + co3;
;     const unsigned b0 = sb_u + co0, b1 = sb_u + co1, b2 = sb_u + co2, b3 = sb_u + co3;
;     {
;       bf16x8 p0, p1, q0, q1, u0, u1, w0, w1;
;       asm volatile(
;         "ds_read_b128 %4, %12\n\tds_read_b128 %5, %12 offset:4096\n\tds_read_b128 %6, %16\n\tds_read_b128 %7, %16 offset:4096\n\t"
;         "ds_read_b128 %8, %13\n\tds_read_b128 %9, %13 offset:4096\n\tds_read_b128 %10, %17\n\tds_read_b128 %11, %17 offset:4096\n\t"
;         "s_waitcnt lgkmcnt(4)\n\t"
;         "v_mfma_f32_32x32x16_bf16 %0, %4, %6, %0\n\tv_mfma_f32_32x32x16_bf16 %1, %4, %7, %1\n\tv_mfma_f32_32x32x16_bf16 %2, %5, %6, %2\n\tv_mfma_f32_32x32x16_bf16 %3, %5, %7, %3\n\t"
;         "ds_read_b128 %4, %14\n\tds_read_b128 %5, %14 offset:4096\n\tds_read_b128 %6, %18\n\tds_read_b128 %7, %18 offset:4096\n\t"
;         "s_waitcnt lgkmcnt(4)\n\t"
;         "v_mfma_f32_32x32x16_bf16 %0, %8, %10, %0\n\tv_mfma_f32_32x32x16_bf16 %1, %8, %11, %1\n\tv_mfma_f32_32x32x16_bf16 %2, %9, %10, %2\n\tv_mfma_f32_32x32x16_bf16 %3, %9, %11, %3\n\t"
;         "ds_read_b128 %8, %15\n\tds_read_b128 %9, %15 offset:4096\n\tds_read_b128 %10, %19\n\tds_read_b128 %11, %19 offset:4096\n\t"
;         "s_waitcnt lgkmcnt(4)\n\t"
;         "v_mfma_f32_32x32x16_bf16 %0, %4, %6, %0\n\tv_mfma_f32_32x32x16_bf16 %1, %4, %7, %1\n\tv_mfma_f32_32x32x16_bf16 %2, %5, %6, %2\n\tv_mfma_f32_32x32x16_bf16 %3, %5, %7, %3\n\t"
;         "s_waitcnt lgkmcnt(0)\n\t"
;         "v_mfma_f32_32x32x16_bf16 %0, %8, %10, %0\n\tv_mfma_f32_32x32x16_bf16 %1, %8, %11, %1\n\tv_mfma_f32_32x32x16_bf16 %2, %9, %10, %2\n\tv_mfma_f32_32x32x16_bf16 %3, %9, %11, %3"
	ds_read_b128 v[84:87], v76
	ds_read_b128 v[88:91], v76 offset:4096
	ds_read_b128 v[92:95], v80
	ds_read_b128 v[96:99], v80 offset:4096
	v_mfma_f32_32x32x16_bf16 v[32:47], v[100:103], v[108:111], v[32:47]
	s_mov_b32 s24, 0x580
	s_add_u32 m0, s30, 0x18000
	v_lshl_add_u64 v[124:125], v[64:65], 0, s[24:25]
	global_load_lds_dwordx4 v[124:125], off
	v_mfma_f32_32x32x16_bf16 v[48:63], v[100:103], v[112:115], v[48:63]
	v_mfma_f32_32x32x16_bf16 v[0:15], v[104:107], v[108:111], v[0:15]
	s_add_u32 m0, s30, 0x1a000
	v_lshl_add_u64 v[126:127], v[66:67], 0, s[24:25]
	global_load_lds_dwordx4 v[126:127], off
	v_mfma_f32_32x32x16_bf16 v[16:31], v[104:107], v[112:115], v[16:31]
	ds_read_b128 v[100:103], v77
	ds_read_b128 v[104:107], v77 offset:4096
	ds_read_b128 v[108:111], v81
	ds_read_b128 v[112:115], v81 offset:4096
	s_waitcnt lgkmcnt(4)
	v_mfma_f32_32x32x16_bf16 v[32:47], v[84:87], v[92:95], v[32:47]
	s_add_u32 m0, s30, 0x1c000
	v_lshl_add_u64 v[124:125], v[68:69], 0, s[24:25]
	global_load_lds_dwordx4 v[124:125], off
	v_mfma_f32_32x32x16_bf16 v[48:63], v[84:87], v[96:99], v[48:63]
	v_mfma_f32_32x32x16_bf16 v[0:15], v[88:91], v[92:95], v[0:15]
	s_add_u32 m0, s30, 0x1e000
	v_lshl_add_u64 v[126:127], v[70:71], 0, s[24:25]
	global_load_lds_dwordx4 v[126:127], off
	v_mfma_f32_32x32x16_bf16 v[16:31], v[88:91], v[96:99], v[16:31]
	ds_read_b128 v[84:87], v78
	ds_read_b128 v[88:91], v78 offset:4096
	ds_read_b128 v[92:95], v82
	ds_read_b128 v[96:99], v82 offset:4096
	s_waitcnt lgkmcnt(4)
	v_mfma_f32_32x32x16_bf16 v[32:47], v[100:103], v[108:111], v[32:47]
	s_add_u32 m0, s30, 0x20000
	v_lshl_add_u64 v[124:125], v[72:73], 0, s[24:25]
	global_load_lds_dwordx4 v[124:125], off
	v_mfma_f32_32x32x16_bf16 v[48:63], v[100:103], v[112:115], v[48:63]
	v_mfma_f32_32x32x16_bf16 v[0:15], v[104:107], v[108:111], v[0:15]
	s_add_u32 m0, s30, 0x22000
	v_lshl_add_u64 v[126:127], v[74:75], 0, s[24:25]
	global_load_lds_dwordx4 v[126:127], off
	v_mfma_f32_32x32x16_bf16 v[16:31], v[104:107], v[112:115], v[16:31]
	ds_read_b128 v[100:103], v79
	ds_read_b128 v[104:107], v79 offset:4096
	ds_read_b128 v[108:111], v83
	ds_read_b128 v[112:115], v83 offset:4096
	s_waitcnt lgkmcnt(4)
	v_mfma_f32_32x32x16_bf16 v[32:47], v[84:87], v[92:95], v[32:47]
	v_mfma_f32_32x32x16_bf16 v[48:63], v[84:87], v[96:99], v[48:63]
	v_mfma_f32_32x32x16_bf16 v[0:15], v[88:91], v[92:95], v[0:15]
	v_mfma_f32_32x32x16_bf16 v[16:31], v[88:91], v[96:99], v[16:31]
	s_waitcnt vmcnt(6) lgkmcnt(0)
	s_barrier
	ds_read_b128 v[84:87], v76 offset:49152
	ds_read_b128 v[88:91], v76 offset:53248
	ds_read_b128 v[92:95], v80 offset:49152
	ds_read_b128 v[96:99], v80 offset:53248
	v_mfma_f32_32x32x16_bf16 v[32:47], v[100:103], v[108:111], v[32:47]
	s_mov_b32 s24, 0x600
	s_mov_b32 m0, s30
	v_lshl_add_u64 v[124:125], v[64:65], 0, s[24:25]
	global_load_lds_dwordx4 v[124:125], off
	v_mfma_f32_32x32x16_bf16 v[48:63], v[100:103], v[112:115], v[48:63]
	v_mfma_f32_32x32x16_bf16 v[0:15], v[104:107], v[108:111], v[0:15]
	s_add_u32 m0, s30, 0x2000
	v_lshl_add_u64 v[126:127], v[66:67], 0, s[24:25]
	global_load_lds_dwordx4 v[126:127], off
	v_mfma_f32_32x32x16_bf16 v[16:31], v[104:107], v[112:115], v[16:31]
	ds_read_b128 v[100:103], v77 offset:49152
	ds_read_b128 v[104:107], v77 offset:53248
	ds_read_b128 v[108:111], v81 offset:49152
	ds_read_b128 v[112:115], v81 offset:53248
	s_waitcnt lgkmcnt(4)
	v_mfma_f32_32x32x16_bf16 v[32:47], v[84:87], v[92:95], v[32:47]
	s_add_u32 m0, s30, 0x4000
	v_lshl_add_u64 v[124:125], v[68:69], 0, s[24:25]
	global_load_lds_dwordx4 v[124:125], off
	v_mfma_f32_32x32x16_bf16 v[48:63], v[84:87], v[96:99], v[48:63]
	v_mfma_f32_32x32x16_bf16 v[0:15], v[88:91], v[92:95], v[0:15]
	s_add_u32 m0, s30, 0x6000
	v_lshl_add_u64 v[126:127], v[70:71], 0, s[24:25]
	global_load_lds_dwordx4 v[126:127], off
	v_mfma_f32_32x32x16_bf16 v[16:31], v[88:91], v[96:99], v[16:31]
	ds_read_b128 v[84:87], v78 offset:49152
	ds_read_b128 v[88:91], v78 offset:53248
	ds_read_b128 v[92:95], v82 offset:49152
	ds_read_b128 v[96:99], v82 offset:53248
	s_waitcnt lgkmcnt(4)
	v_mfma_f32_32x32x16_bf16 v[32:47], v[100:103], v[108:111], v[32:47]
	s_add_u32 m0, s30, 0x8000
	v_lshl_add_u64 v[124:125], v[72:73], 0, s[24:25]
	global_load_lds_dwordx4 v[124:125], off
	v_mfma_f32_32x32x16_bf16 v[48:63], v[100:103], v[112:115], v[48:63]
	v_mfma_f32_32x32x16_bf16 v[0:15], v[104:107], v[108:111], v[0:15]
	s_add_u32 m0, s30, 0xa000
	v_lshl_add_u64 v[126:127], v[74:75], 0, s[24:25]
	global_load_lds_dwordx4 v[126:127], off
	v_mfma_f32_32x32x16_bf16 v[16:31], v[104:107], v[112:115], v[16:31]
	ds_read_b128 v[100:103], v79 offset:49152
	ds_read_b128 v[104:107], v79 offset:53248
	ds_read_b128 v[108:111], v83 offset:49152
	ds_read_b128 v[112:115], v83 offset:53248
	s_waitcnt lgkmcnt(4)
	v_mfma_f32_32x32x16_bf16 v[32:47], v[84:87], v[92:95], v[32:47]
	v_mfma_f32_32x32x16_bf16 v[48:63], v[84:87], v[96:99], v[48:63]
	v_mfma_f32_32x32x16_bf16 v[0:15], v[88:91], v[92:95], v[0:15]
	v_mfma_f32_32x32x16_bf16 v[16:31], v[88:91], v[96:99], v[16:31]
	s_waitcnt vmcnt(6) lgkmcnt(0)
	s_barrier
;     ...
;   if (PART != 2) {
;     GEMM_ISSUE(0, 0);
;     if (nk > 1) GEMM_ISSUE(1, 1);
;   }
;   if (PART == 1) return;
;   int st = 0;
;   for (int kt = 0; kt < nk; ++kt) {
;     if (kt + 1 < nk) asm volatile("s_waitcnt vmcnt(6)" ::: "memory");
;     else asm volatile("s_waitcnt vmcnt(0)" ::: "memory");
;     __builtin_amdgcn_s_barrier();
;     asm volatile("" ::: "memory");
;     if (kt + 2 < nk) { const int st2 = (st >= 1) ? st - 1 : 2; GEMM_ISSUE(kt + 2, st2); }
;     const char* la = lds + st * STAGE_B;
;     const char* lb = la + 32768;
;     const unsigned sa_u = (unsigned)(size_t)la + arow_u, sb_u = (unsigned)(size_t)lb + brow_u;
;     const unsigned a0 = sa_u + co0, a1 = sa_u + co1, a2 = sa_u + co2, a3 = sa_u + co3;
;     const unsigned b0 = sb_u + co0, b1 = sb_u + co1, b2 = sb_u + co2, b3 = sb_u + co3;
;     {
;       bf16x8 p0, p1, q0, q1, u0, u1, w0, w1;
;       asm volatile(
;         "ds_read_b128 %4, %12\n\tds_read_b128 %5, %12 offset:4096\n\tds_read_b128 %6, %16\n\tds_read_b128 %7, %16 offset:4096\n\t"
;         "ds_read_b128 %8, %13\n\tds_read_b128 %9, %13 offset:4096\n\tds_read_b128 %10, %17\n\tds_read_b128 %11, %17 offset:4096\n\t"
;         "s_waitcnt lgkmcnt(4)\n\t"
;         "v_mfma_f32_32x32x16_bf16 %0, %4, %6, %0\n\tv_mfma_f32_32x32x16_bf16 %1, %4, %7, %1\n\tv_mfma_f32_32x32x16_bf16 %2, %5, %6, %2\n\tv_mfma_f32_32x32x16_bf16 %3, %5, %7, %3\n\t"
;         "ds_read_b128 %4, %14\n\tds_read_b128 %5, %14 offset:4096\n\tds_read_b128 %6, %18\n\tds_read_b128 %7, %18 offset:4096\n\t"
;         "s_waitcnt lgkmcnt(4)\n\t"
;         "v_mfma_f32_32x32x16_bf16 %0, %8, %10, %0\n\tv_mfma_f32_32x32x16_bf16 %1, %8, %11, %1\n\tv_mfma_f32_32x32x16_bf16 %2, %9, %10, %2\n\tv_mfma_f32_32x32x16_bf16 %3, %9, %11, %3\n\t"
;         "ds_read_b128 %8, %15\n\tds_read_b128 %9, %15 offset:4096\n\tds_read_b128 %10, %19\n\tds_read_b128 %11, %19 offset:4096\n\t"
;         "s_waitcnt lgkmcnt(4)\n\t"
;         "v_mfma_f32_32x32x16_bf16 %0, %4, %6, %0\n\tv_mfma_f32_32x32x16_bf16 %1, %4, %7, %1\n\tv_mfma_f32_32x32x16_bf16 %2, %5, %6, %2\n\tv_mfma_f32_32x32x16_bf16 %3, %5, %7, %3\n\t"
;         "s_waitcnt lgkmcnt(0)\n\t"
;         "v_mfma_f32_32x32x16_bf16 %0, %8, %10, %0\n\tv_mfma_f32_32x32x16_bf16 %1, %8, %11, %1\n\tv_mfma_f32_32x32x16_bf16 %2, %9, %10, %2\n\tv_mfma_f32_32x32x16_bf16 %3, %9, %11, %3"
	ds_read_b128 v[84:87], v116
	ds_read_b128 v[88:91], v116 offset:4096
	ds_read_b128 v[92:95], v120
	ds_read_b128 v[96:99], v120 offset:4096
	v_mfma_f32_32x32x16_bf16 v[32:47], v[100:103], v[108:111], v[32:47]
	s_mov_b32 s24, 0x680
	s_add_u32 m0, s30, 0xc000
	v_lshl_add_u64 v[124:125], v[64:65], 0, s[24:25]
	global_load_lds_dwordx4 v[124:125], off
	v_mfma_f32_32x32x16_bf16 v[48:63], v[100:103], v[112:115], v[48:63]
	v_mfma_f32_32x32x16_bf16 v[0:15], v[104:107], v[108:111], v[0:15]
	s_add_u32 m0, s30, 0xe000
	v_lshl_add_u64 v[126:127], v[66:67], 0, s[24:25]
	global_load_lds_dwordx4 v[126:127], off
	v_mfma_f32_32x32x16_bf16 v[16:31], v[104:107], v[112:115], v[16:31]
	ds_read_b128 v[100:103], v117
	ds_read_b128 v[104:107], v117 offset:4096
	ds_read_b128 v[108:111], v121
	ds_read_b128 v[112:115], v121 offset:4096
	s_waitcnt lgkmcnt(4)
	v_mfma_f32_32x32x16_bf16 v[32:47], v[84:87], v[92:95], v[32:47]
	s_add_u32 m0, s30, 0x10000
	v_lshl_add_u64 v[124:125], v[68:69], 0, s[24:25]
	global_load_lds_dwordx4 v[124:125], off
	v_mfma_f32_32x32x16_bf16 v[48:63], v[84:87], v[96:99], v[48:63]
	v_mfma_f32_32x32x16_bf16 v[0:15], v[88:91], v[92:95], v[0:15]
	s_add_u32 m0, s30, 0x12000
	v_lshl_add_u64 v[126:127], v[70:71], 0, s[24:25]
	global_load_lds_dwordx4 v[126:127], off
	v_mfma_f32_32x32x16_bf16 v[16:31], v[88:91], v[96:99], v[16:31]
	ds_read_b128 v[84:87], v118
	ds_read_b128 v[88:91], v118 offset:4096
	ds_read_b128 v[92:95], v122
	ds_read_b128 v[96:99], v122 offset:4096
	s_waitcnt lgkmcnt(4)
	v_mfma_f32_32x32x16_bf16 v[32:47], v[100:103], v[108:111], v[32:47]
	s_add_u32 m0, s30, 0x14000
	v_lshl_add_u64 v[124:125], v[72:73], 0, s[24:25]
	global_load_lds_dwordx4 v[124:125], off
	v_mfma_f32_32x32x16_bf16 v[48:63], v[100:103], v[112:115], v[48:63]
	v_mfma_f32_32x32x16_bf16 v[0:15], v[104:107], v[108:111], v[0:15]
	s_add_u32 m0, s30, 0x16000
	v_lshl_add_u64 v[126:127], v[74:75], 0, s[24:25]
	global_load_lds_dwordx4 v[126:127], off
	v_mfma_f32_32x32x16_bf16 v[16:31], v[104:107], v[112:115], v[16:31]
	ds_read_b128 v[100:103], v119
	ds_read_b128 v[104:107], v119 offset:4096
	ds_read_b128 v[108:111], v123
	ds_read_b128 v[112:115], v123 offset:4096
	s_waitcnt lgkmcnt(4)
	v_mfma_f32_32x32x16_bf16 v[32:47], v[84:87], v[92:95], v[32:47]
	v_mfma_f32_32x32x16_bf16 v[48:63], v[84:87], v[96:99], v[48:63]
	v_mfma_f32_32x32x16_bf16 v[0:15], v[88:91], v[92:95], v[0:15]
	v_mfma_f32_32x32x16_bf16 v[16:31], v[88:91], v[96:99], v[16:31]
	s_waitcnt vmcnt(6) lgkmcnt(0)
	s_barrier
	ds_read_b128 v[84:87], v76
	ds_read_b128 v[88:91], v76 offset:4096
	ds_read_b128 v[92:95], v80
	ds_read_b128 v[96:99], v80 offset:4096
	v_mfma_f32_32x32x16_bf16 v[32:47], v[100:103], v[108:111], v[32:47]
	s_mov_b32 s24, 0x700
	s_add_u32 m0, s30, 0x18000
	v_lshl_add_u64 v[124:125], v[64:65], 0, s[24:25]
	global_load_lds_dwordx4 v[124:125], off
	v_mfma_f32_32x32x16_bf16 v[48:63], v[100:103], v[112:115], v[48:63]
	v_mfma_f32_32x32x16_bf16 v[0:15], v[104:107], v[108:111], v[0:15]
	s_add_u32 m0, s30, 0x1a000
	v_lshl_add_u64 v[126:127], v[66:67], 0, s[24:25]
	global_load_lds_dwordx4 v[126:127], off
	v_mfma_f32_32x32x16_bf16 v[16:31], v[104:107], v[112:115], v[16:31]
	ds_read_b128 v[100:103], v77
	ds_read_b128 v[104:107], v77 offset:4096
	ds_read_b128 v[108:111], v81
	ds_read_b128 v[112:115], v81 offset:4096
	s_waitcnt lgkmcnt(4)
	v_mfma_f32_32x32x16_bf16 v[32:47], v[84:87], v[92:95], v[32:47]
	s_add_u32 m0, s30, 0x1c000
	v_lshl_add_u64 v[124:125], v[68:69], 0, s[24:25]
	global_load_lds_dwordx4 v[124:125], off
	v_mfma_f32_32x32x16_bf16 v[48:63], v[84:87], v[96:99], v[48:63]
	v_mfma_f32_32x32x16_bf16 v[0:15], v[88:91], v[92:95], v[0:15]
	s_add_u32 m0, s30, 0x1e000
	v_lshl_add_u64 v[126:127], v[70:71], 0, s[24:25]
	global_load_lds_dwordx4 v[126:127], off
	v_mfma_f32_32x32x16_bf16 v[16:31], v[88:91], v[96:99], v[16:31]
	ds_read_b128 v[84:87], v78
	ds_read_b128 v[88:91], v78 offset:4096
	ds_read_b128 v[92:95], v82
	ds_read_b128 v[96:99], v82 offset:4096
	s_waitcnt lgkmcnt(4)
	v_mfma_f32_32x32x16_bf16 v[32:47], v[100:103], v[108:111], v[32:47]
	s_add_u32 m0, s30, 0x20000
	v_lshl_add_u64 v[124:125], v[72:73], 0, s[24:25]
	global_load_lds_dwordx4 v[124:125], off
	v_mfma_f32_32x32x16_bf16 v[48:63], v[100:103], v[112:115], v[48:63]
	v_mfma_f32_32x32x16_bf16 v[0:15], v[104:107], v[108:111], v[0:15]
	s_add_u32 m0, s30, 0x22000
	v_lshl_add_u64 v[126:127], v[74:75], 0, s[24:25]
	global_load_lds_dwordx4 v[126:127], off
	v_mfma_f32_32x32x16_bf16 v[16:31], v[104:107], v[112:115], v[16:31]
	ds_read_b128 v[100:103], v79
	ds_read_b128 v[104:107], v79 offset:4096
	ds_read_b128 v[108:111], v83
	ds_read_b128 v[112:115], v83 offset:4096
	s_waitcnt lgkmcnt(4)
	v_mfma_f32_32x32x16_bf16 v[32:47], v[84:87], v[92:95], v[32:47]
	v_mfma_f32_32x32x16_bf16 v[48:63], v[84:87], v[96:99], v[48:63]
	v_mfma_f32_32x32x16_bf16 v[0:15], v[88:91], v[92:95], v[0:15]
	v_mfma_f32_32x32x16_bf16 v[16:31], v[88:91], v[96:99], v[16:31]
	s_waitcnt vmcnt(6) lgkmcnt(0)
	s_barrier
;     ...
;   if (PART != 2) {
;     GEMM_ISSUE(0, 0);
;     if (nk > 1) GEMM_ISSUE(1, 1);
;   }
;   if (PART == 1) return;
;   int st = 0;
;   for (int kt = 0; kt < nk; ++kt) {
;     if (kt + 1 < nk) asm volatile("s_waitcnt vmcnt(6)" ::: "memory");
;     else asm volatile("s_waitcnt vmcnt(0)" ::: "memory");
;     __builtin_amdgcn_s_barrier();
;     asm volatile("" ::: "memory");
;     if (kt + 2 < nk) { const int st2 = (st >= 1) ? st - 1 : 2; GEMM_ISSUE(kt + 2, st2); }
;     const char* la = lds + st * STAGE_B;
;     const char* lb = la + 32768;
;     const unsigned sa_u = (unsigned)(size_t)la + arow_u, sb_u = (unsigned)(size_t)lb + brow_u;
;     const unsigned a0 = sa_u + co0, a1 = sa_u + co1, a2 = sa_u + co2, a3 = sa_u + co3;
;     const unsigned b0 = sb_u + co0, b1 = sb_u + co1, b2 = sb_u + co2, b3 = sb_u + co3;
;     {
;       bf16x8 p0, p1, q0, q1, u0, u1, w0, w1;
;       asm volatile(
;         "ds_read_b128 %4, %12\n\tds_read_b128 %5, %12 offset:4096\n\tds_read_b128 %6, %16\n\tds_read_b128 %7, %16 offset:4096\n\t"
;         "ds_read_b128 %8, %13\n\tds_read_b128 %9, %13 offset:4096\n\tds_read_b128 %10, %17\n\tds_read_b128 %11, %17 offset:4096\n\t"
;         "s_waitcnt lgkmcnt(4)\n\t"
;         "v_mfma_f32_32x32x16_bf16 %0, %4, %6, %0\n\tv_mfma_f32_32x32x16_bf16 %1, %4, %7, %1\n\tv_mfma_f32_32x32x16_bf16 %2, %5, %6, %2\n\tv_mfma_f32_32x32x16_bf16 %3, %5, %7, %3\n\t"
;         "ds_read_b128 %4, %14\n\tds_read_b128 %5, %14 offset:4096\n\tds_read_b128 %6, %18\n\tds_read_b128 %7, %18 offset:4096\n\t"
;         "s_waitcnt lgkmcnt(4)\n\t"
;         "v_mfma_f32_32x32x16_bf16 %0, %8, %10, %0\n\tv_mfma_f32_32x32x16_bf16 %1, %8, %11, %1\n\tv_mfma_f32_32x32x16_bf16 %2, %9, %10, %2\n\tv_mfma_f32_32x32x16_bf16 %3, %9, %11, %3\n\t"
;         "ds_read_b128 %8, %15\n\tds_read_b128 %9, %15 offset:4096\n\tds_read_b128 %10, %19\n\tds_read_b128 %11, %19 offset:4096\n\t"
;         "s_waitcnt lgkmcnt(4)\n\t"
;         "v_mfma_f32_32x32x16_bf16 %0, %4, %6, %0\n\tv_mfma_f32_32x32x16_bf16 %1, %4, %7, %1\n\tv_mfma_f32_32x32x16_bf16 %2, %5, %6, %2\n\tv_mfma_f32_32x32x16_bf16 %3, %5, %7, %3\n\t"
;         "s_waitcnt lgkmcnt(0)\n\t"
;         "v_mfma_f32_32x32x16_bf16 %0, %8, %10, %0\n\tv_mfma_f32_32x32x16_bf16 %1, %8, %11, %1\n\tv_mfma_f32_32x32x16_bf16 %2, %9, %10, %2\n\tv_mfma_f32_32x32x16_bf16 %3, %9, %11, %3"
	ds_read_b128 v[84:87], v76 offset:49152
	ds_read_b128 v[88:91], v76 offset:53248
	ds_read_b128 v[92:95], v80 offset:49152
	ds_read_b128 v[96:99], v80 offset:53248
	v_mfma_f32_32x32x16_bf16 v[32:47], v[100:103], v[108:111], v[32:47]
	s_mov_b32 s24, 0x780
	s_mov_b32 m0, s30
	v_lshl_add_u64 v[124:125], v[64:65], 0, s[24:25]
	global_load_lds_dwordx4 v[124:125], off
	v_mfma_f32_32x32x16_bf16 v[48:63], v[100:103], v[112:115], v[48:63]
	v_mfma_f32_32x32x16_bf16 v[0:15], v[104:107], v[108:111], v[0:15]
	s_add_u32 m0, s30, 0x2000
	v_lshl_add_u64 v[126:127], v[66:67], 0, s[24:25]
	global_load_lds_dwordx4 v[126:127], off
	v_mfma_f32_32x32x16_bf16 v[16:31], v[104:107], v[112:115], v[16:31]
	ds_read_b128 v[100:103], v77 offset:49152
	ds_read_b128 v[104:107], v77 offset:53248
	ds_read_b128 v[108:111], v81 offset:49152
	ds_read_b128 v[112:115], v81 offset:53248
	s_waitcnt lgkmcnt(4)
	v_mfma_f32_32x32x16_bf16 v[32:47], v[84:87], v[92:95], v[32:47]
	s_add_u32 m0, s30, 0x4000
	v_lshl_add_u64 v[124:125], v[68:69], 0, s[24:25]
	global_load_lds_dwordx4 v[124:125], off
	v_mfma_f32_32x32x16_bf16 v[48:63], v[84:87], v[96:99], v[48:63]
	v_mfma_f32_32x32x16_bf16 v[0:15], v[88:91], v[92:95], v[0:15]
	s_add_u32 m0, s30, 0x6000
	v_lshl_add_u64 v[126:127], v[70:71], 0, s[24:25]
	global_load_lds_dwordx4 v[126:127], off
	v_mfma_f32_32x32x16_bf16 v[16:31], v[88:91], v[96:99], v[16:31]
	ds_read_b128 v[84:87], v78 offset:49152
	ds_read_b128 v[88:91], v78 offset:53248
	ds_read_b128 v[92:95], v82 offset:49152
	ds_read_b128 v[96:99], v82 offset:53248
	s_waitcnt lgkmcnt(4)
	v_mfma_f32_32x32x16_bf16 v[32:47], v[100:103], v[108:111], v[32:47]
	s_add_u32 m0, s30, 0x8000
	v_lshl_add_u64 v[124:125], v[72:73], 0, s[24:25]
	global_load_lds_dwordx4 v[124:125], off
	v_mfma_f32_32x32x16_bf16 v[48:63], v[100:103], v[112:115], v[48:63]
	v_mfma_f32_32x32x16_bf16 v[0:15], v[104:107], v[108:111], v[0:15]
	s_add_u32 m0, s30, 0xa000
	v_lshl_add_u64 v[126:127], v[74:75], 0, s[24:25]
	global_load_lds_dwordx4 v[126:127], off
	v_mfma_f32_32x32x16_bf16 v[16:31], v[104:107], v[112:115], v[16:31]
	ds_read_b128 v[100:103], v79 offset:49152
	ds_read_b128 v[104:107], v79 offset:53248
	ds_read_b128 v[108:111], v83 offset:49152
	ds_read_b128 v[112:115], v83 offset:53248
	s_waitcnt lgkmcnt(4)
	v_mfma_f32_32x32x16_bf16 v[32:47], v[84:87], v[92:95], v[32:47]
	v_mfma_f32_32x32x16_bf16 v[48:63], v[84:87], v[96:99], v[48:63]
	v_mfma_f32_32x32x16_bf16 v[0:15], v[88:91], v[92:95], v[0:15]
	v_mfma_f32_32x32x16_bf16 v[16:31], v[88:91], v[96:99], v[16:31]
	s_waitcnt vmcnt(6) lgkmcnt(0)
	s_barrier
	ds_read_b128 v[84:87], v116
	ds_read_b128 v[88:91], v116 offset:4096
	ds_read_b128 v[92:95], v120
	ds_read_b128 v[96:99], v120 offset:4096
	v_mfma_f32_32x32x16_bf16 v[32:47], v[100:103], v[108:111], v[32:47]
	v_mfma_f32_32x32x16_bf16 v[48:63], v[100:103], v[112:115], v[48:63]
	v_mfma_f32_32x32x16_bf16 v[0:15], v[104:107], v[108:111], v[0:15]
	v_mfma_f32_32x32x16_bf16 v[16:31], v[104:107], v[112:115], v[16:31]
	ds_read_b128 v[100:103], v117
	ds_read_b128 v[104:107], v117 offset:4096
	ds_read_b128 v[108:111], v121
	ds_read_b128 v[112:115], v121 offset:4096
	s_waitcnt lgkmcnt(4)
	v_mfma_f32_32x32x16_bf16 v[32:47], v[84:87], v[92:95], v[32:47]
	v_mfma_f32_32x32x16_bf16 v[48:63], v[84:87], v[96:99], v[48:63]
	v_mfma_f32_32x32x16_bf16 v[0:15], v[88:91], v[92:95], v[0:15]
	v_mfma_f32_32x32x16_bf16 v[16:31], v[88:91], v[96:99], v[16:31]
	ds_read_b128 v[84:87], v118
	ds_read_b128 v[88:91], v118 offset:4096
	ds_read_b128 v[92:95], v122
	ds_read_b128 v[96:99], v122 offset:4096
	s_waitcnt lgkmcnt(4)
	v_mfma_f32_32x32x16_bf16 v[32:47], v[100:103], v[108:111], v[32:47]
	v_mfma_f32_32x32x16_bf16 v[48:63], v[100:103], v[112:115], v[48:63]
	v_mfma_f32_32x32x16_bf16 v[0:15], v[104:107], v[108:111], v[0:15]
	v_mfma_f32_32x32x16_bf16 v[16:31], v[104:107], v[112:115], v[16:31]
	ds_read_b128 v[100:103], v119
	ds_read_b128 v[104:107], v119 offset:4096
	ds_read_b128 v[108:111], v123
	ds_read_b128 v[112:115], v123 offset:4096
	s_waitcnt lgkmcnt(4)
	v_mfma_f32_32x32x16_bf16 v[32:47], v[84:87], v[92:95], v[32:47]
	v_mfma_f32_32x32x16_bf16 v[48:63], v[84:87], v[96:99], v[48:63]
	v_mfma_f32_32x32x16_bf16 v[0:15], v[88:91], v[92:95], v[0:15]
	v_mfma_f32_32x32x16_bf16 v[16:31], v[88:91], v[96:99], v[16:31]
	s_waitcnt vmcnt(0) lgkmcnt(0)
	s_barrier
	ds_read_b128 v[84:87], v76
	ds_read_b128 v[88:91], v76 offset:4096
	ds_read_b128 v[92:95], v80
	ds_read_b128 v[96:99], v80 offset:4096
	v_mfma_f32_32x32x16_bf16 v[32:47], v[100:103], v[108:111], v[32:47]
	v_mfma_f32_32x32x16_bf16 v[48:63], v[100:103], v[112:115], v[48:63]
	v_mfma_f32_32x32x16_bf16 v[0:15], v[104:107], v[108:111], v[0:15]
	v_mfma_f32_32x32x16_bf16 v[16:31], v[104:107], v[112:115], v[16:31]
	ds_read_b128 v[100:103], v77
	ds_read_b128 v[104:107], v77 offset:4096
	ds_read_b128 v[108:111], v81
	ds_read_b128 v[112:115], v81 offset:4096
	s_waitcnt lgkmcnt(4)
	v_mfma_f32_32x32x16_bf16 v[32:47], v[84:87], v[92:95], v[32:47]
	v_mfma_f32_32x32x16_bf16 v[48:63], v[84:87], v[96:99], v[48:63]
	v_mfma_f32_32x32x16_bf16 v[0:15], v[88:91], v[92:95], v[0:15]
	v_mfma_f32_32x32x16_bf16 v[16:31], v[88:91], v[96:99], v[16:31]
	ds_read_b128 v[84:87], v78
	ds_read_b128 v[88:91], v78 offset:4096
	ds_read_b128 v[92:95], v82
	ds_read_b128 v[96:99], v82 offset:4096
	s_waitcnt lgkmcnt(4)
	v_mfma_f32_32x32x16_bf16 v[32:47], v[100:103], v[108:111], v[32:47]
	v_mfma_f32_32x32x16_bf16 v[48:63], v[100:103], v[112:115], v[48:63]
	v_mfma_f32_32x32x16_bf16 v[0:15], v[104:107], v[108:111], v[0:15]
	v_mfma_f32_32x32x16_bf16 v[16:31], v[104:107], v[112:115], v[16:31]
	ds_read_b128 v[100:103], v79
	ds_read_b128 v[104:107], v79 offset:4096
	ds_read_b128 v[108:111], v83
	ds_read_b128 v[112:115], v83 offset:4096
	s_waitcnt lgkmcnt(4)
	v_mfma_f32_32x32x16_bf16 v[32:47], v[84:87], v[92:95], v[32:47]
	v_mfma_f32_32x32x16_bf16 v[48:63], v[84:87], v[96:99], v[48:63]
	v_mfma_f32_32x32x16_bf16 v[0:15], v[88:91], v[92:95], v[0:15]
	v_mfma_f32_32x32x16_bf16 v[16:31], v[88:91], v[96:99], v[16:31]
	s_waitcnt lgkmcnt(0)
	v_mfma_f32_32x32x16_bf16 v[32:47], v[100:103], v[108:111], v[32:47]
	v_mfma_f32_32x32x16_bf16 v[48:63], v[100:103], v[112:115], v[48:63]
	v_mfma_f32_32x32x16_bf16 v[0:15], v[104:107], v[108:111], v[0:15]
	v_mfma_f32_32x32x16_bf16 v[16:31], v[104:107], v[112:115], v[16:31]
	s_nop 15
	s_nop 15
	s_nop 7
	s_barrier
	s_load_dword s9, s[0:1], 0x10
	s_waitcnt lgkmcnt(0)
	s_lshr_b32 s9, s9, 16
	s_cmp_lg_u32 s9, 0
	s_cselect_b64 s[14:15], -1, 0
	s_cmp_lg_u64 s[14:15], 0
	s_addc_u32 s9, s33, 0
	s_cmp_lg_u64 s[14:15], 0
	s_addc_u32 s23, s23, s33
	s_cmpk_gt_i32 s23, 0x15ff
	s_cbranch_scc0 .LBB0_760
